# GEMM MFMA issue order: k0 then k1 per group of four accumulators (accumulator reuse distance 4 instead of 8)
# baseline (speedup 1.0000x reference)
; #define PG8_STAGE(bufoff, gbase, voff) do { _Pragma("unroll") for (int _i = 0; _i < 2; ++_i) \
;         __builtin_amdgcn_global_load_lds((const unsigned*)((const char*)(gbase) + (voff)[_i]), (PG8_LAS unsigned*)(lds + (bufoff) + ldsw + _i * 8192), 16, 0, 0); } while (0)
; #define PG8_LDA(dst, b, h) do { _Pragma("unroll") for (int m = 0; m < 4; ++m) _Pragma("unroll") for (int k = 0; k < 2; ++k) dst[m][k] = *(const PG8_LAS bf16x8*)(lds + PG8_SA(b, h) + aoff + m * 2048 + k * 1024); } while (0)
; #define PG8_LDB(dst, b, h) do { _Pragma("unroll") for (int n = 0; n < 2; ++n) _Pragma("unroll") for (int k = 0; k < 2; ++k) dst[n][k] = *(const PG8_LAS bf16x8*)(lds + PG8_SB(b, h) + boff + n * 2048 + k * 1024); } while (0)
; #define PG8_WAIT_V(n) asm volatile("s_waitcnt vmcnt(" #n ")" ::: "memory")
; #define PG8_WAIT_L(n) asm volatile("s_waitcnt lgkmcnt(" #n ")" ::: "memory")
; #define PG8_BAR __builtin_amdgcn_s_barrier()
; #define PG8_SCHED __builtin_amdgcn_sched_barrier(0)
; template <class Epi, class Sched, bool ALIGN_EPI = false, bool SP2 = false>
; __device__ __forceinline__ void gemm_phase(PG8_LAS unsigned char* lds, const Gemm g, const Sched& S, const Epi& E) {
;     ...
;         const bool has_next = S.next(ui + 1, nxt);
;         const char* nA = has_next ? (const char*)g.A + (size_t)nxt.pm * tstep : cA; const char* nB = has_next ? (const char*)g.Bt + (size_t)nxt.pn * tstep : cB;
;         for (int t = 0; t < nt; t += 2) {
;             const bool last = (t == nt - 2);
;             const char* a1 = cA + (size_t)(t + 1) * kstep;
;             const char* a2 = last ? nA : cA + (size_t)(t + 2) * kstep; const char* b2 = last ? nB : cB + (size_t)(t + 2) * kstep;
;             const char* a3 = a2 + kstep; const char* b3 = b2 + kstep;
;             if (last && has_next) S.a_ready(nxt);
;             if constexpr (SP2) {
;             PG8_LDB(B0, 0, 0); PG8_LDB(B1, 0, 1); PG8_SCHED; PG8_LDA(At, 0, 0); PG8_STAGE(PG8_SA(1, 1), a1 + hstep, voffA);
;             PG8_WAIT_V(8); PG8_WAIT_L(0); PG8_BAR; PG8_MMA(0, 0, At, B0); PG8_MMA(0, 1, At, B1); PG8_BAR; PG8_SCHED;
;             PG8_LDA(At, 0, 1); PG8_STAGE(PG8_SB(0, 0), b2, voffB); PG8_STAGE(PG8_SB(0, 1), b2 + hstep, voffB); PG8_STAGE(PG8_SA(0, 0), a2, voffA);
;             PG8_WAIT_V(8); PG8_WAIT_L(0); PG8_BAR; PG8_MMA(1, 0, At, B0); PG8_MMA(1, 1, At, B1); PG8_BAR; PG8_SCHED;
.LBB0_190:
	s_ashr_i32 s27, s26, 31
	s_lshl_b64 s[14:15], s[26:27], 19
	s_add_u32 s28, s22, s14
	s_addc_u32 s29, s23, s15
	s_and_b64 s[14:15], s[0:1], exec
	s_cselect_b32 s27, s29, s49
	s_cselect_b32 s67, s28, s48
	s_ashr_i32 s25, s24, 31
	s_lshl_b64 s[14:15], s[24:25], 19
	s_add_u32 s40, s94, s14
	s_addc_u32 s41, s96, s15
	s_and_b64 s[14:15], s[0:1], exec
	s_cselect_b32 s25, s41, s51
	s_cselect_b32 s86, s40, s50
	s_add_u32 s48, s48, 0x40080
	s_addc_u32 s49, s49, 0
	s_add_u32 s87, s50, 0x100
	s_addc_u32 s88, s51, 0
	s_mov_b32 s89, -2
	ds_read_b128 v[144:147], v155
	ds_read_b128 v[148:151], v155 offset:1024
	ds_read_b128 v[160:163], v155 offset:2048
	ds_read_b128 v[168:171], v155 offset:3072
	ds_read_b128 v[172:175], v156
	ds_read_b128 v[176:179], v156 offset:1024
	ds_read_b128 v[182:185], v156 offset:2048
	ds_read_b128 v[186:189], v156 offset:3072
	s_add_u32 s3, s48, 0xfffc0080
	s_addc_u32 s14, s49, -1
	s_cmp_eq_u32 s89, 12
	s_cselect_b32 s55, s27, s14
	s_cselect_b32 s54, s67, s3
	s_cselect_b32 s51, s25, s88
	s_cselect_b32 s50, s86, s87
	v_lshl_add_u64 v[164:165], s[48:49], 0, v[136:137]
	s_add_i32 m0, s45, 0xc000
	ds_read_b128 v[190:193], v157
	ds_read_b128 v[194:197], v157 offset:1024
	ds_read_b128 v[198:201], v157 offset:2048
	ds_read_b128 v[208:211], v157 offset:3072
	ds_read_b128 v[212:215], v157 offset:4096
	ds_read_b128 v[216:219], v157 offset:5120
	ds_read_b128 v[220:223], v157 offset:6144
	ds_read_b128 v[224:227], v157 offset:7168
	global_load_lds_dwordx4 v[164:165], off
	v_lshl_add_u64 v[164:165], s[48:49], 0, v[138:139]
	s_add_i32 m0, s45, 0xe000
	s_nop 0
	global_load_lds_dwordx4 v[164:165], off
	s_waitcnt vmcnt(8)
	s_waitcnt lgkmcnt(0)
	s_barrier
	s_setprio 1
	s_waitcnt lgkmcnt(0)
	v_mfma_f32_16x16x32_bf16 v[124:127], v[144:147], v[190:193], 0
	v_mfma_f32_16x16x32_bf16 v[120:123], v[160:163], v[190:193], 0
	v_mfma_f32_16x16x32_bf16 v[108:111], v[144:147], v[198:201], 0
	v_mfma_f32_16x16x32_bf16 v[104:107], v[160:163], v[198:201], 0
	v_mfma_f32_16x16x32_bf16 v[124:127], v[148:151], v[194:197], v[124:127]
	v_mfma_f32_16x16x32_bf16 v[120:123], v[168:171], v[194:197], v[120:123]
	v_mfma_f32_16x16x32_bf16 v[108:111], v[148:151], v[208:211], v[108:111]
	v_mfma_f32_16x16x32_bf16 v[104:107], v[168:171], v[208:211], v[104:107]
	v_mfma_f32_16x16x32_bf16 v[92:95], v[144:147], v[212:215], 0
	v_mfma_f32_16x16x32_bf16 v[88:91], v[160:163], v[212:215], 0
	v_mfma_f32_16x16x32_bf16 v[76:79], v[144:147], v[220:223], 0
	v_mfma_f32_16x16x32_bf16 v[72:75], v[160:163], v[220:223], 0
	v_mfma_f32_16x16x32_bf16 v[92:95], v[148:151], v[216:219], v[92:95]
	v_mfma_f32_16x16x32_bf16 v[88:91], v[168:171], v[216:219], v[88:91]
	v_mfma_f32_16x16x32_bf16 v[76:79], v[148:151], v[224:227], v[76:79]
	v_mfma_f32_16x16x32_bf16 v[72:75], v[168:171], v[224:227], v[72:75]
	s_setprio 0
	s_setprio 1
	v_mfma_f32_16x16x32_bf16 v[116:119], v[172:175], v[190:193], 0
	v_mfma_f32_16x16x32_bf16 v[112:115], v[182:185], v[190:193], 0
	v_mfma_f32_16x16x32_bf16 v[100:103], v[172:175], v[198:201], 0
	v_mfma_f32_16x16x32_bf16 v[96:99], v[182:185], v[198:201], 0
	v_mfma_f32_16x16x32_bf16 v[116:119], v[176:179], v[194:197], v[116:119]
	v_mfma_f32_16x16x32_bf16 v[112:115], v[186:189], v[194:197], v[112:115]
	v_mfma_f32_16x16x32_bf16 v[100:103], v[176:179], v[208:211], v[100:103]
	v_mfma_f32_16x16x32_bf16 v[96:99], v[186:189], v[208:211], v[96:99]
	v_mfma_f32_16x16x32_bf16 v[84:87], v[172:175], v[212:215], 0
	v_mfma_f32_16x16x32_bf16 v[80:83], v[182:185], v[212:215], 0
	v_mfma_f32_16x16x32_bf16 v[68:71], v[172:175], v[220:223], 0
	v_mfma_f32_16x16x32_bf16 v[64:67], v[182:185], v[220:223], 0
	v_mfma_f32_16x16x32_bf16 v[84:87], v[176:179], v[216:219], v[84:87]
	v_mfma_f32_16x16x32_bf16 v[80:83], v[186:189], v[216:219], v[80:83]
	v_mfma_f32_16x16x32_bf16 v[68:71], v[176:179], v[224:227], v[68:71]
	v_mfma_f32_16x16x32_bf16 v[64:67], v[186:189], v[224:227], v[64:67]
	s_setprio 0
	s_barrier
	s_add_i32 s3, s63, s43
	v_lshl_add_u64 v[164:165], s[50:51], 0, v[132:133]
	s_mov_b32 m0, s3
	ds_read_b128 v[190:193], v157 offset:16384
	ds_read_b128 v[194:197], v157 offset:17408
	ds_read_b128 v[198:201], v157 offset:18432
	ds_read_b128 v[208:211], v157 offset:19456
	ds_read_b128 v[212:215], v157 offset:20480
	ds_read_b128 v[216:219], v157 offset:21504
	ds_read_b128 v[220:223], v157 offset:22528
	ds_read_b128 v[224:227], v157 offset:23552
	global_load_lds_dwordx4 v[164:165], off
	s_add_i32 m0, s3, 0x2000
	s_add_u32 s14, s50, 0x40000
	v_lshl_add_u64 v[202:203], s[50:51], 0, v[128:129]
	s_addc_u32 s15, s51, 0
	s_add_i32 s3, s64, s43
	global_load_lds_dwordx4 v[202:203], off
	v_lshl_add_u64 v[228:229], s[14:15], 0, v[132:133]
	s_mov_b32 m0, s3
	global_load_lds_dwordx4 v[228:229], off
	v_lshl_add_u64 v[228:229], s[14:15], 0, v[128:129]
	s_add_i32 m0, s3, 0x2000
	s_nop 0
	global_load_lds_dwordx4 v[228:229], off
	s_waitcnt vmcnt(6)
	s_waitcnt lgkmcnt(0)
	s_barrier
; #define PG8_STAGE(bufoff, gbase, voff) do { _Pragma("unroll") for (int _i = 0; _i < 2; ++_i) \
;         __builtin_amdgcn_global_load_lds((const unsigned*)((const char*)(gbase) + (voff)[_i]), (PG8_LAS unsigned*)(lds + (bufoff) + ldsw + _i * 8192), 16, 0, 0); } while (0)
; #define PG8_LDA(dst, b, h) do { _Pragma("unroll") for (int m = 0; m < 4; ++m) _Pragma("unroll") for (int k = 0; k < 2; ++k) dst[m][k] = *(const PG8_LAS bf16x8*)(lds + PG8_SA(b, h) + aoff + m * 2048 + k * 1024); } while (0)
; #define PG8_LDB(dst, b, h) do { _Pragma("unroll") for (int n = 0; n < 2; ++n) _Pragma("unroll") for (int k = 0; k < 2; ++k) dst[n][k] = *(const PG8_LAS bf16x8*)(lds + PG8_SB(b, h) + boff + n * 2048 + k * 1024); } while (0)
; #define PG8_MMA(ai, bj, At, Bt) do { __builtin_amdgcn_s_setprio(1); _Pragma("unroll") for (int m = 0; m < 4; ++m) _Pragma("unroll") for (int n = 0; n < 2; ++n) _Pragma("unroll") for (int k = 0; k < 2; ++k) \
;         acc[ai][bj][m][n] = __builtin_amdgcn_mfma_f32_16x16x32_bf16(Bt[n][k], At[m][k], acc[ai][bj][m][n], 0, 0, 0); __builtin_amdgcn_s_setprio(0); } while (0)
; #define PG8_WAIT_V(n) asm volatile("s_waitcnt vmcnt(" #n ")" ::: "memory")
; #define PG8_WAIT_L(n) asm volatile("s_waitcnt lgkmcnt(" #n ")" ::: "memory")
; #define PG8_BAR __builtin_amdgcn_s_barrier()
; #define PG8_SCHED __builtin_amdgcn_sched_barrier(0)
; template <class Epi, class Sched, bool ALIGN_EPI = false, bool SP2 = false>
; __device__ __forceinline__ void gemm_phase(PG8_LAS unsigned char* lds, const Gemm g, const Sched& S, const Epi& E) {
;     ...
;             PG8_WAIT_V(8); PG8_WAIT_L(0); PG8_BAR; PG8_MMA(0, 0, At, B0); PG8_MMA(0, 1, At, B1); PG8_BAR; PG8_SCHED;
;             PG8_LDA(At, 0, 1); PG8_STAGE(PG8_SB(0, 0), b2, voffB); PG8_STAGE(PG8_SB(0, 1), b2 + hstep, voffB); PG8_STAGE(PG8_SA(0, 0), a2, voffA);
;             PG8_WAIT_V(8); PG8_WAIT_L(0); PG8_BAR; PG8_MMA(1, 0, At, B0); PG8_MMA(1, 1, At, B1); PG8_BAR; PG8_SCHED;
;             PG8_LDB(B0, 1, 0); PG8_LDB(B1, 1, 1); PG8_SCHED; PG8_LDA(At, 1, 0); PG8_STAGE(PG8_SA(0, 1), a2 + hstep, voffA);
;             PG8_WAIT_V(8); PG8_WAIT_L(0); PG8_BAR; PG8_MMA(0, 0, At, B0); PG8_MMA(0, 1, At, B1); PG8_BAR; PG8_SCHED;
	s_setprio 1
	s_waitcnt lgkmcnt(0)
	v_mfma_f32_16x16x32_bf16 v[60:63], v[144:147], v[190:193], 0
	v_mfma_f32_16x16x32_bf16 v[56:59], v[160:163], v[190:193], 0
	v_mfma_f32_16x16x32_bf16 v[44:47], v[144:147], v[198:201], 0
	v_mfma_f32_16x16x32_bf16 v[40:43], v[160:163], v[198:201], 0
	v_mfma_f32_16x16x32_bf16 v[60:63], v[148:151], v[194:197], v[60:63]
	v_mfma_f32_16x16x32_bf16 v[56:59], v[168:171], v[194:197], v[56:59]
	v_mfma_f32_16x16x32_bf16 v[44:47], v[148:151], v[208:211], v[44:47]
	v_mfma_f32_16x16x32_bf16 v[40:43], v[168:171], v[208:211], v[40:43]
	v_mfma_f32_16x16x32_bf16 v[28:31], v[144:147], v[212:215], 0
	v_mfma_f32_16x16x32_bf16 v[24:27], v[160:163], v[212:215], 0
	v_mfma_f32_16x16x32_bf16 v[12:15], v[144:147], v[220:223], 0
	v_mfma_f32_16x16x32_bf16 v[8:11], v[160:163], v[220:223], 0
	v_mfma_f32_16x16x32_bf16 v[28:31], v[148:151], v[216:219], v[28:31]
	v_mfma_f32_16x16x32_bf16 v[24:27], v[168:171], v[216:219], v[24:27]
	v_lshl_add_u64 v[228:229], s[54:55], 0, v[134:135]
	s_mov_b32 m0, s45
	s_nop 0
	global_load_lds_dwordx4 v[228:229], off
	v_mfma_f32_16x16x32_bf16 v[12:15], v[148:151], v[224:227], v[12:15]
	v_mfma_f32_16x16x32_bf16 v[8:11], v[168:171], v[224:227], v[8:11]
	s_setprio 0
	s_setprio 1
	v_mfma_f32_16x16x32_bf16 v[52:55], v[172:175], v[190:193], 0
	v_mfma_f32_16x16x32_bf16 v[48:51], v[182:185], v[190:193], 0
	v_mfma_f32_16x16x32_bf16 v[36:39], v[172:175], v[198:201], 0
	v_mfma_f32_16x16x32_bf16 v[32:35], v[182:185], v[198:201], 0
	v_mfma_f32_16x16x32_bf16 v[52:55], v[176:179], v[194:197], v[52:55]
	v_mfma_f32_16x16x32_bf16 v[48:51], v[186:189], v[194:197], v[48:51]
	v_mfma_f32_16x16x32_bf16 v[36:39], v[176:179], v[208:211], v[36:39]
	v_mfma_f32_16x16x32_bf16 v[32:35], v[186:189], v[208:211], v[32:35]
	v_mfma_f32_16x16x32_bf16 v[20:23], v[172:175], v[212:215], 0
	v_mfma_f32_16x16x32_bf16 v[16:19], v[182:185], v[212:215], 0
	v_mfma_f32_16x16x32_bf16 v[4:7], v[172:175], v[220:223], 0
	v_mfma_f32_16x16x32_bf16 v[0:3], v[182:185], v[220:223], 0
	v_mfma_f32_16x16x32_bf16 v[20:23], v[176:179], v[216:219], v[20:23]
	v_mfma_f32_16x16x32_bf16 v[16:19], v[186:189], v[216:219], v[16:19]
	v_lshl_add_u64 v[230:231], s[54:55], 0, v[130:131]
	s_mov_b32 m0, s57
	s_nop 0
	global_load_lds_dwordx4 v[230:231], off
	v_mfma_f32_16x16x32_bf16 v[4:7], v[176:179], v[224:227], v[4:7]
	v_mfma_f32_16x16x32_bf16 v[0:3], v[186:189], v[224:227], v[0:3]
	s_setprio 0
	s_barrier
	s_add_i32 s3, 0, 0x18000
	v_add_u32_e32 v159, s3, v153
	s_add_i32 s33, 0, 0x1c000
	ds_read_b128 v[144:147], v159
	ds_read_b128 v[148:151], v159 offset:1024
	ds_read_b128 v[160:163], v159 offset:2048
	ds_read_b128 v[168:171], v159 offset:3072
	v_add_u32_e32 v159, s33, v153
	ds_read_b128 v[172:175], v159
	ds_read_b128 v[176:179], v159 offset:1024
	ds_read_b128 v[182:185], v159 offset:2048
	ds_read_b128 v[186:189], v159 offset:3072
	s_add_u32 s14, s54, 0x40000
	s_addc_u32 s15, s55, 0
	s_mov_b32 m0, s58
	v_lshl_add_u64 v[232:233], s[14:15], 0, v[134:135]
	ds_read_b128 v[190:193], v157 offset:32768
	ds_read_b128 v[194:197], v157 offset:33792
	ds_read_b128 v[198:201], v157 offset:34816
	ds_read_b128 v[208:211], v157 offset:35840
	ds_read_b128 v[212:215], v157 offset:36864
	ds_read_b128 v[216:219], v157 offset:37888
	ds_read_b128 v[220:223], v157 offset:38912
	ds_read_b128 v[224:227], v157 offset:39936
	global_load_lds_dwordx4 v[232:233], off
	v_lshl_add_u64 v[232:233], s[14:15], 0, v[130:131]
	s_mov_b32 m0, s59
	s_nop 0
	global_load_lds_dwordx4 v[232:233], off
	s_waitcnt vmcnt(8)
	s_waitcnt lgkmcnt(0)
	s_barrier
	s_setprio 1
	s_waitcnt lgkmcnt(0)
	v_mfma_f32_16x16x32_bf16 v[124:127], v[144:147], v[190:193], v[124:127]
	v_mfma_f32_16x16x32_bf16 v[120:123], v[160:163], v[190:193], v[120:123]
	v_mfma_f32_16x16x32_bf16 v[108:111], v[144:147], v[198:201], v[108:111]
	v_mfma_f32_16x16x32_bf16 v[104:107], v[160:163], v[198:201], v[104:107]
	v_mfma_f32_16x16x32_bf16 v[124:127], v[148:151], v[194:197], v[124:127]
	v_mfma_f32_16x16x32_bf16 v[120:123], v[168:171], v[194:197], v[120:123]
	v_mfma_f32_16x16x32_bf16 v[108:111], v[148:151], v[208:211], v[108:111]
	v_mfma_f32_16x16x32_bf16 v[104:107], v[168:171], v[208:211], v[104:107]
	v_mfma_f32_16x16x32_bf16 v[92:95], v[144:147], v[212:215], v[92:95]
	v_mfma_f32_16x16x32_bf16 v[88:91], v[160:163], v[212:215], v[88:91]
	v_mfma_f32_16x16x32_bf16 v[76:79], v[144:147], v[220:223], v[76:79]
	v_mfma_f32_16x16x32_bf16 v[72:75], v[160:163], v[220:223], v[72:75]
	v_mfma_f32_16x16x32_bf16 v[92:95], v[148:151], v[216:219], v[92:95]
	v_mfma_f32_16x16x32_bf16 v[88:91], v[168:171], v[216:219], v[88:91]
	v_mfma_f32_16x16x32_bf16 v[76:79], v[148:151], v[224:227], v[76:79]
	v_mfma_f32_16x16x32_bf16 v[72:75], v[168:171], v[224:227], v[72:75]
	s_setprio 0
	s_setprio 1
	v_mfma_f32_16x16x32_bf16 v[116:119], v[172:175], v[190:193], v[116:119]
	v_mfma_f32_16x16x32_bf16 v[112:115], v[182:185], v[190:193], v[112:115]
	v_mfma_f32_16x16x32_bf16 v[100:103], v[172:175], v[198:201], v[100:103]
	v_mfma_f32_16x16x32_bf16 v[96:99], v[182:185], v[198:201], v[96:99]
	v_mfma_f32_16x16x32_bf16 v[116:119], v[176:179], v[194:197], v[116:119]
	v_mfma_f32_16x16x32_bf16 v[112:115], v[186:189], v[194:197], v[112:115]
	v_mfma_f32_16x16x32_bf16 v[100:103], v[176:179], v[208:211], v[100:103]
	v_mfma_f32_16x16x32_bf16 v[96:99], v[186:189], v[208:211], v[96:99]
	v_mfma_f32_16x16x32_bf16 v[84:87], v[172:175], v[212:215], v[84:87]
	v_mfma_f32_16x16x32_bf16 v[80:83], v[182:185], v[212:215], v[80:83]
	v_mfma_f32_16x16x32_bf16 v[68:71], v[172:175], v[220:223], v[68:71]
	v_mfma_f32_16x16x32_bf16 v[64:67], v[182:185], v[220:223], v[64:67]
	v_mfma_f32_16x16x32_bf16 v[84:87], v[176:179], v[216:219], v[84:87]
	v_mfma_f32_16x16x32_bf16 v[80:83], v[186:189], v[216:219], v[80:83]
	v_mfma_f32_16x16x32_bf16 v[68:71], v[176:179], v[224:227], v[68:71]
	v_mfma_f32_16x16x32_bf16 v[64:67], v[186:189], v[224:227], v[64:67]
	s_setprio 0
	s_barrier
; #define PG8_STAGE(bufoff, gbase, voff) do { _Pragma("unroll") for (int _i = 0; _i < 2; ++_i) \
;         __builtin_amdgcn_global_load_lds((const unsigned*)((const char*)(gbase) + (voff)[_i]), (PG8_LAS unsigned*)(lds + (bufoff) + ldsw + _i * 8192), 16, 0, 0); } while (0)
; #define PG8_LDA(dst, b, h) do { _Pragma("unroll") for (int m = 0; m < 4; ++m) _Pragma("unroll") for (int k = 0; k < 2; ++k) dst[m][k] = *(const PG8_LAS bf16x8*)(lds + PG8_SA(b, h) + aoff + m * 2048 + k * 1024); } while (0)
; #define PG8_LDB(dst, b, h) do { _Pragma("unroll") for (int n = 0; n < 2; ++n) _Pragma("unroll") for (int k = 0; k < 2; ++k) dst[n][k] = *(const PG8_LAS bf16x8*)(lds + PG8_SB(b, h) + boff + n * 2048 + k * 1024); } while (0)
; template <class Epi, class Sched, bool ALIGN_EPI = false, bool SP2 = false>
; __device__ __forceinline__ void gemm_phase(PG8_LAS unsigned char* lds, const Gemm g, const Sched& S, const Epi& E) {
;     ...
;         for (int t = 0; t < nt; t += 2) {
;             const bool last = (t == nt - 2);
;             const char* a1 = cA + (size_t)(t + 1) * kstep;
;             const char* a2 = last ? nA : cA + (size_t)(t + 2) * kstep; const char* b2 = last ? nB : cB + (size_t)(t + 2) * kstep;
;             const char* a3 = a2 + kstep; const char* b3 = b2 + kstep;
;             if (last && has_next) S.a_ready(nxt);
;             if constexpr (SP2) {
;             PG8_LDB(B0, 0, 0); PG8_LDB(B1, 0, 1); PG8_SCHED; PG8_LDA(At, 0, 0); PG8_STAGE(PG8_SA(1, 1), a1 + hstep, voffA);
;             PG8_WAIT_V(8); PG8_WAIT_L(0); PG8_BAR; PG8_MMA(0, 0, At, B0); PG8_MMA(0, 1, At, B1); PG8_BAR; PG8_SCHED;
;             PG8_LDA(At, 0, 1); PG8_STAGE(PG8_SB(0, 0), b2, voffB); PG8_STAGE(PG8_SB(0, 1), b2 + hstep, voffB); PG8_STAGE(PG8_SA(0, 0), a2, voffA);
;             PG8_WAIT_V(8); PG8_WAIT_L(0); PG8_BAR; PG8_MMA(1, 0, At, B0); PG8_MMA(1, 1, At, B1); PG8_BAR; PG8_SCHED;
;             PG8_LDB(B0, 1, 0); PG8_LDB(B1, 1, 1); PG8_SCHED; PG8_LDA(At, 1, 0); PG8_STAGE(PG8_SA(0, 1), a2 + hstep, voffA);
;             PG8_WAIT_V(8); PG8_WAIT_L(0); PG8_BAR; PG8_MMA(0, 0, At, B0); PG8_MMA(0, 1, At, B1); PG8_BAR; PG8_SCHED;
;             PG8_LDA(At, 1, 1); PG8_STAGE(PG8_SB(1, 0), b3, voffB); PG8_STAGE(PG8_SB(1, 1), b3 + hstep, voffB); PG8_STAGE(PG8_SA(1, 0), a3, voffA);
;             PG8_WAIT_V(8); PG8_WAIT_L(0); PG8_BAR; PG8_MMA(1, 0, At, B0); PG8_MMA(1, 1, At, B1); PG8_BAR; PG8_SCHED;
	s_add_i32 s3, s3, s43
	v_lshl_add_u64 v[164:165], v[164:165], 0, s[10:11]
	s_mov_b32 m0, s3
	ds_read_b128 v[190:193], v157 offset:49152
	ds_read_b128 v[194:197], v157 offset:50176
	ds_read_b128 v[198:201], v157 offset:51200
	ds_read_b128 v[208:211], v157 offset:52224
	ds_read_b128 v[212:215], v157 offset:53248
	ds_read_b128 v[216:219], v157 offset:54272
	ds_read_b128 v[220:223], v157 offset:55296
	ds_read_b128 v[224:227], v157 offset:56320
	global_load_lds_dwordx4 v[164:165], off
	s_add_i32 m0, s3, 0x2000
	s_add_u32 s14, s50, 0x40080
	v_lshl_add_u64 v[164:165], v[202:203], 0, s[10:11]
	s_addc_u32 s15, s51, 0
	s_add_i32 s3, s33, s43
	global_load_lds_dwordx4 v[164:165], off
	v_lshl_add_u64 v[164:165], s[14:15], 0, v[132:133]
	s_mov_b32 m0, s3
	s_nop 0
	global_load_lds_dwordx4 v[164:165], off
	v_lshl_add_u64 v[164:165], s[14:15], 0, v[128:129]
	s_add_i32 m0, s3, 0x2000
	s_nop 0
	global_load_lds_dwordx4 v[164:165], off
	s_waitcnt vmcnt(6)
	s_waitcnt lgkmcnt(0)
	s_barrier
	s_setprio 1
	s_waitcnt lgkmcnt(0)
	v_mfma_f32_16x16x32_bf16 v[60:63], v[144:147], v[190:193], v[60:63]
	v_mfma_f32_16x16x32_bf16 v[56:59], v[160:163], v[190:193], v[56:59]
	v_mfma_f32_16x16x32_bf16 v[44:47], v[144:147], v[198:201], v[44:47]
	v_mfma_f32_16x16x32_bf16 v[40:43], v[160:163], v[198:201], v[40:43]
	v_mfma_f32_16x16x32_bf16 v[60:63], v[148:151], v[194:197], v[60:63]
	v_mfma_f32_16x16x32_bf16 v[56:59], v[168:171], v[194:197], v[56:59]
	v_mfma_f32_16x16x32_bf16 v[44:47], v[148:151], v[208:211], v[44:47]
	v_mfma_f32_16x16x32_bf16 v[40:43], v[168:171], v[208:211], v[40:43]
	v_mfma_f32_16x16x32_bf16 v[28:31], v[144:147], v[212:215], v[28:31]
	v_mfma_f32_16x16x32_bf16 v[24:27], v[160:163], v[212:215], v[24:27]
	v_mfma_f32_16x16x32_bf16 v[12:15], v[144:147], v[220:223], v[12:15]
	v_mfma_f32_16x16x32_bf16 v[8:11], v[160:163], v[220:223], v[8:11]
	v_mfma_f32_16x16x32_bf16 v[28:31], v[148:151], v[216:219], v[28:31]
	v_mfma_f32_16x16x32_bf16 v[24:27], v[168:171], v[216:219], v[24:27]
	v_lshl_add_u64 v[164:165], v[228:229], 0, s[10:11]
	s_mov_b32 m0, s61
	s_nop 0
	global_load_lds_dwordx4 v[164:165], off
	v_mfma_f32_16x16x32_bf16 v[12:15], v[148:151], v[224:227], v[12:15]
	v_mfma_f32_16x16x32_bf16 v[8:11], v[168:171], v[224:227], v[8:11]
	s_setprio 0
	s_setprio 1
	v_mfma_f32_16x16x32_bf16 v[52:55], v[172:175], v[190:193], v[52:55]
	v_mfma_f32_16x16x32_bf16 v[48:51], v[182:185], v[190:193], v[48:51]
	v_mfma_f32_16x16x32_bf16 v[36:39], v[172:175], v[198:201], v[36:39]
	v_mfma_f32_16x16x32_bf16 v[32:35], v[182:185], v[198:201], v[32:35]
	v_mfma_f32_16x16x32_bf16 v[52:55], v[176:179], v[194:197], v[52:55]
	v_mfma_f32_16x16x32_bf16 v[48:51], v[186:189], v[194:197], v[48:51]
	v_mfma_f32_16x16x32_bf16 v[36:39], v[176:179], v[208:211], v[36:39]
	v_mfma_f32_16x16x32_bf16 v[32:35], v[186:189], v[208:211], v[32:35]
	v_mfma_f32_16x16x32_bf16 v[20:23], v[172:175], v[212:215], v[20:23]
	v_mfma_f32_16x16x32_bf16 v[16:19], v[182:185], v[212:215], v[16:19]
	v_mfma_f32_16x16x32_bf16 v[4:7], v[172:175], v[220:223], v[4:7]
	v_mfma_f32_16x16x32_bf16 v[0:3], v[182:185], v[220:223], v[0:3]
	v_mfma_f32_16x16x32_bf16 v[20:23], v[176:179], v[216:219], v[20:23]
	v_mfma_f32_16x16x32_bf16 v[16:19], v[186:189], v[216:219], v[16:19]
	v_lshl_add_u64 v[164:165], v[230:231], 0, s[10:11]
	s_mov_b32 m0, s62
	s_nop 0
	global_load_lds_dwordx4 v[164:165], off
	v_mfma_f32_16x16x32_bf16 v[4:7], v[176:179], v[224:227], v[4:7]
	v_mfma_f32_16x16x32_bf16 v[0:3], v[186:189], v[224:227], v[0:3]
	s_setprio 0
	s_barrier
	s_add_i32 s89, s89, 2
	s_add_u32 s48, s48, 0x100
	s_addc_u32 s49, s49, 0
	s_add_u32 s87, s87, 0x100
	s_addc_u32 s88, s88, 0
.LBB0_191:
	ds_read_b128 v[144:147], v155
	ds_read_b128 v[148:151], v155 offset:1024
	ds_read_b128 v[160:163], v155 offset:2048
	ds_read_b128 v[168:171], v155 offset:3072
	ds_read_b128 v[172:175], v156
	ds_read_b128 v[176:179], v156 offset:1024
	ds_read_b128 v[182:185], v156 offset:2048
	ds_read_b128 v[186:189], v156 offset:3072
	s_add_u32 s3, s48, 0xfffc0080
	s_addc_u32 s14, s49, -1
	s_cmp_eq_u32 s89, 12
	s_cselect_b32 s55, s27, s14
	s_cselect_b32 s54, s67, s3
	s_cselect_b32 s51, s25, s88
	s_cselect_b32 s50, s86, s87
	v_lshl_add_u64 v[164:165], s[48:49], 0, v[136:137]
	s_add_i32 m0, s45, 0xc000
	ds_read_b128 v[190:193], v157
	ds_read_b128 v[194:197], v157 offset:1024
	ds_read_b128 v[198:201], v157 offset:2048
	ds_read_b128 v[208:211], v157 offset:3072
	ds_read_b128 v[212:215], v157 offset:4096
	ds_read_b128 v[216:219], v157 offset:5120
	ds_read_b128 v[220:223], v157 offset:6144
	ds_read_b128 v[224:227], v157 offset:7168
	global_load_lds_dwordx4 v[164:165], off
	v_lshl_add_u64 v[164:165], s[48:49], 0, v[138:139]
	s_add_i32 m0, s45, 0xe000
	s_nop 0
	global_load_lds_dwordx4 v[164:165], off
	s_waitcnt vmcnt(8)
	s_waitcnt lgkmcnt(0)
	s_barrier
; #define PG8_STAGE(bufoff, gbase, voff) do { _Pragma("unroll") for (int _i = 0; _i < 2; ++_i) \
;         __builtin_amdgcn_global_load_lds((const unsigned*)((const char*)(gbase) + (voff)[_i]), (PG8_LAS unsigned*)(lds + (bufoff) + ldsw + _i * 8192), 16, 0, 0); } while (0)
; #define PG8_LDA(dst, b, h) do { _Pragma("unroll") for (int m = 0; m < 4; ++m) _Pragma("unroll") for (int k = 0; k < 2; ++k) dst[m][k] = *(const PG8_LAS bf16x8*)(lds + PG8_SA(b, h) + aoff + m * 2048 + k * 1024); } while (0)
; #define PG8_LDB(dst, b, h) do { _Pragma("unroll") for (int n = 0; n < 2; ++n) _Pragma("unroll") for (int k = 0; k < 2; ++k) dst[n][k] = *(const PG8_LAS bf16x8*)(lds + PG8_SB(b, h) + boff + n * 2048 + k * 1024); } while (0)
; #define PG8_MMA(ai, bj, At, Bt) do { __builtin_amdgcn_s_setprio(1); _Pragma("unroll") for (int m = 0; m < 4; ++m) _Pragma("unroll") for (int n = 0; n < 2; ++n) _Pragma("unroll") for (int k = 0; k < 2; ++k) \
;         acc[ai][bj][m][n] = __builtin_amdgcn_mfma_f32_16x16x32_bf16(Bt[n][k], At[m][k], acc[ai][bj][m][n], 0, 0, 0); __builtin_amdgcn_s_setprio(0); } while (0)
; #define PG8_WAIT_V(n) asm volatile("s_waitcnt vmcnt(" #n ")" ::: "memory")
; #define PG8_WAIT_L(n) asm volatile("s_waitcnt lgkmcnt(" #n ")" ::: "memory")
; #define PG8_BAR __builtin_amdgcn_s_barrier()
; #define PG8_SCHED __builtin_amdgcn_sched_barrier(0)
; template <class Epi, class Sched, bool ALIGN_EPI = false, bool SP2 = false>
; __device__ __forceinline__ void gemm_phase(PG8_LAS unsigned char* lds, const Gemm g, const Sched& S, const Epi& E) {
;     ...
;             PG8_LDB(B0, 0, 0); PG8_LDB(B1, 0, 1); PG8_SCHED; PG8_LDA(At, 0, 0); PG8_STAGE(PG8_SA(1, 1), a1 + hstep, voffA);
;             PG8_WAIT_V(8); PG8_WAIT_L(0); PG8_BAR; PG8_MMA(0, 0, At, B0); PG8_MMA(0, 1, At, B1); PG8_BAR; PG8_SCHED;
;             PG8_LDA(At, 0, 1); PG8_STAGE(PG8_SB(0, 0), b2, voffB); PG8_STAGE(PG8_SB(0, 1), b2 + hstep, voffB); PG8_STAGE(PG8_SA(0, 0), a2, voffA);
;             PG8_WAIT_V(8); PG8_WAIT_L(0); PG8_BAR; PG8_MMA(1, 0, At, B0); PG8_MMA(1, 1, At, B1); PG8_BAR; PG8_SCHED;
	s_setprio 1
	s_waitcnt lgkmcnt(0)
	v_mfma_f32_16x16x32_bf16 v[124:127], v[144:147], v[190:193], v[124:127]
	v_mfma_f32_16x16x32_bf16 v[120:123], v[160:163], v[190:193], v[120:123]
	v_mfma_f32_16x16x32_bf16 v[108:111], v[144:147], v[198:201], v[108:111]
	v_mfma_f32_16x16x32_bf16 v[104:107], v[160:163], v[198:201], v[104:107]
	v_mfma_f32_16x16x32_bf16 v[124:127], v[148:151], v[194:197], v[124:127]
	v_mfma_f32_16x16x32_bf16 v[120:123], v[168:171], v[194:197], v[120:123]
	v_mfma_f32_16x16x32_bf16 v[108:111], v[148:151], v[208:211], v[108:111]
	v_mfma_f32_16x16x32_bf16 v[104:107], v[168:171], v[208:211], v[104:107]
	v_mfma_f32_16x16x32_bf16 v[92:95], v[144:147], v[212:215], v[92:95]
	v_mfma_f32_16x16x32_bf16 v[88:91], v[160:163], v[212:215], v[88:91]
	v_mfma_f32_16x16x32_bf16 v[76:79], v[144:147], v[220:223], v[76:79]
	v_mfma_f32_16x16x32_bf16 v[72:75], v[160:163], v[220:223], v[72:75]
	v_mfma_f32_16x16x32_bf16 v[92:95], v[148:151], v[216:219], v[92:95]
	v_mfma_f32_16x16x32_bf16 v[88:91], v[168:171], v[216:219], v[88:91]
	v_mfma_f32_16x16x32_bf16 v[76:79], v[148:151], v[224:227], v[76:79]
	v_mfma_f32_16x16x32_bf16 v[72:75], v[168:171], v[224:227], v[72:75]
	s_setprio 0
	s_setprio 1
	v_mfma_f32_16x16x32_bf16 v[116:119], v[172:175], v[190:193], v[116:119]
	v_mfma_f32_16x16x32_bf16 v[112:115], v[182:185], v[190:193], v[112:115]
	v_mfma_f32_16x16x32_bf16 v[100:103], v[172:175], v[198:201], v[100:103]
	v_mfma_f32_16x16x32_bf16 v[96:99], v[182:185], v[198:201], v[96:99]
	v_mfma_f32_16x16x32_bf16 v[116:119], v[176:179], v[194:197], v[116:119]
	v_mfma_f32_16x16x32_bf16 v[112:115], v[186:189], v[194:197], v[112:115]
	v_mfma_f32_16x16x32_bf16 v[100:103], v[176:179], v[208:211], v[100:103]
	v_mfma_f32_16x16x32_bf16 v[96:99], v[186:189], v[208:211], v[96:99]
	v_mfma_f32_16x16x32_bf16 v[84:87], v[172:175], v[212:215], v[84:87]
	v_mfma_f32_16x16x32_bf16 v[80:83], v[182:185], v[212:215], v[80:83]
	v_mfma_f32_16x16x32_bf16 v[68:71], v[172:175], v[220:223], v[68:71]
	v_mfma_f32_16x16x32_bf16 v[64:67], v[182:185], v[220:223], v[64:67]
	v_mfma_f32_16x16x32_bf16 v[84:87], v[176:179], v[216:219], v[84:87]
	v_mfma_f32_16x16x32_bf16 v[80:83], v[186:189], v[216:219], v[80:83]
	v_mfma_f32_16x16x32_bf16 v[68:71], v[176:179], v[224:227], v[68:71]
	v_mfma_f32_16x16x32_bf16 v[64:67], v[186:189], v[224:227], v[64:67]
	s_setprio 0
	s_barrier
	s_add_i32 s3, s63, s43
	v_lshl_add_u64 v[164:165], s[50:51], 0, v[132:133]
	s_mov_b32 m0, s3
	ds_read_b128 v[190:193], v157 offset:16384
	ds_read_b128 v[194:197], v157 offset:17408
	ds_read_b128 v[198:201], v157 offset:18432
	ds_read_b128 v[208:211], v157 offset:19456
	ds_read_b128 v[212:215], v157 offset:20480
	ds_read_b128 v[216:219], v157 offset:21504
	ds_read_b128 v[220:223], v157 offset:22528
	ds_read_b128 v[224:227], v157 offset:23552
	global_load_lds_dwordx4 v[164:165], off
	s_add_i32 m0, s3, 0x2000
	s_add_u32 s14, s50, 0x40000
	v_lshl_add_u64 v[202:203], s[50:51], 0, v[128:129]
	s_addc_u32 s15, s51, 0
	s_add_i32 s3, s64, s43
	global_load_lds_dwordx4 v[202:203], off
	v_lshl_add_u64 v[228:229], s[14:15], 0, v[132:133]
	s_mov_b32 m0, s3
	global_load_lds_dwordx4 v[228:229], off
	v_lshl_add_u64 v[228:229], s[14:15], 0, v[128:129]
	s_add_i32 m0, s3, 0x2000
	s_nop 0
	global_load_lds_dwordx4 v[228:229], off
	s_waitcnt vmcnt(6)
	s_waitcnt lgkmcnt(0)
	s_barrier
	s_setprio 1
	s_waitcnt lgkmcnt(0)
	v_mfma_f32_16x16x32_bf16 v[60:63], v[144:147], v[190:193], v[60:63]
	v_mfma_f32_16x16x32_bf16 v[56:59], v[160:163], v[190:193], v[56:59]
	v_mfma_f32_16x16x32_bf16 v[44:47], v[144:147], v[198:201], v[44:47]
	v_mfma_f32_16x16x32_bf16 v[40:43], v[160:163], v[198:201], v[40:43]
	v_mfma_f32_16x16x32_bf16 v[60:63], v[148:151], v[194:197], v[60:63]
	v_mfma_f32_16x16x32_bf16 v[56:59], v[168:171], v[194:197], v[56:59]
	v_mfma_f32_16x16x32_bf16 v[44:47], v[148:151], v[208:211], v[44:47]
	v_mfma_f32_16x16x32_bf16 v[40:43], v[168:171], v[208:211], v[40:43]
	v_mfma_f32_16x16x32_bf16 v[28:31], v[144:147], v[212:215], v[28:31]
	v_mfma_f32_16x16x32_bf16 v[24:27], v[160:163], v[212:215], v[24:27]
	v_mfma_f32_16x16x32_bf16 v[12:15], v[144:147], v[220:223], v[12:15]
	v_mfma_f32_16x16x32_bf16 v[8:11], v[160:163], v[220:223], v[8:11]
	v_mfma_f32_16x16x32_bf16 v[28:31], v[148:151], v[216:219], v[28:31]
	v_mfma_f32_16x16x32_bf16 v[24:27], v[168:171], v[216:219], v[24:27]
	v_lshl_add_u64 v[228:229], s[54:55], 0, v[134:135]
	s_mov_b32 m0, s45
	s_nop 0
	global_load_lds_dwordx4 v[228:229], off
	v_mfma_f32_16x16x32_bf16 v[12:15], v[148:151], v[224:227], v[12:15]
	v_mfma_f32_16x16x32_bf16 v[8:11], v[168:171], v[224:227], v[8:11]
	s_setprio 0
	s_setprio 1
	v_mfma_f32_16x16x32_bf16 v[52:55], v[172:175], v[190:193], v[52:55]
	v_mfma_f32_16x16x32_bf16 v[48:51], v[182:185], v[190:193], v[48:51]
	v_mfma_f32_16x16x32_bf16 v[36:39], v[172:175], v[198:201], v[36:39]
	v_mfma_f32_16x16x32_bf16 v[32:35], v[182:185], v[198:201], v[32:35]
	v_mfma_f32_16x16x32_bf16 v[52:55], v[176:179], v[194:197], v[52:55]
	v_mfma_f32_16x16x32_bf16 v[48:51], v[186:189], v[194:197], v[48:51]
	v_mfma_f32_16x16x32_bf16 v[36:39], v[176:179], v[208:211], v[36:39]
	v_mfma_f32_16x16x32_bf16 v[32:35], v[186:189], v[208:211], v[32:35]
	v_mfma_f32_16x16x32_bf16 v[20:23], v[172:175], v[212:215], v[20:23]
	v_mfma_f32_16x16x32_bf16 v[16:19], v[182:185], v[212:215], v[16:19]
	v_mfma_f32_16x16x32_bf16 v[4:7], v[172:175], v[220:223], v[4:7]
	v_mfma_f32_16x16x32_bf16 v[0:3], v[182:185], v[220:223], v[0:3]
	v_mfma_f32_16x16x32_bf16 v[20:23], v[176:179], v[216:219], v[20:23]
	v_mfma_f32_16x16x32_bf16 v[16:19], v[186:189], v[216:219], v[16:19]
	v_lshl_add_u64 v[230:231], s[54:55], 0, v[130:131]
	s_mov_b32 m0, s57
	s_nop 0
	global_load_lds_dwordx4 v[230:231], off
	v_mfma_f32_16x16x32_bf16 v[4:7], v[176:179], v[224:227], v[4:7]
	v_mfma_f32_16x16x32_bf16 v[0:3], v[186:189], v[224:227], v[0:3]
	s_setprio 0
	s_barrier
; #define PG8_STAGE(bufoff, gbase, voff) do { _Pragma("unroll") for (int _i = 0; _i < 2; ++_i) \
;         __builtin_amdgcn_global_load_lds((const unsigned*)((const char*)(gbase) + (voff)[_i]), (PG8_LAS unsigned*)(lds + (bufoff) + ldsw + _i * 8192), 16, 0, 0); } while (0)
; #define PG8_LDA(dst, b, h) do { _Pragma("unroll") for (int m = 0; m < 4; ++m) _Pragma("unroll") for (int k = 0; k < 2; ++k) dst[m][k] = *(const PG8_LAS bf16x8*)(lds + PG8_SA(b, h) + aoff + m * 2048 + k * 1024); } while (0)
; #define PG8_LDB(dst, b, h) do { _Pragma("unroll") for (int n = 0; n < 2; ++n) _Pragma("unroll") for (int k = 0; k < 2; ++k) dst[n][k] = *(const PG8_LAS bf16x8*)(lds + PG8_SB(b, h) + boff + n * 2048 + k * 1024); } while (0)
; #define PG8_MMA(ai, bj, At, Bt) do { __builtin_amdgcn_s_setprio(1); _Pragma("unroll") for (int m = 0; m < 4; ++m) _Pragma("unroll") for (int n = 0; n < 2; ++n) _Pragma("unroll") for (int k = 0; k < 2; ++k) \
;         acc[ai][bj][m][n] = __builtin_amdgcn_mfma_f32_16x16x32_bf16(Bt[n][k], At[m][k], acc[ai][bj][m][n], 0, 0, 0); __builtin_amdgcn_s_setprio(0); } while (0)
; #define PG8_WAIT_V(n) asm volatile("s_waitcnt vmcnt(" #n ")" ::: "memory")
; #define PG8_WAIT_L(n) asm volatile("s_waitcnt lgkmcnt(" #n ")" ::: "memory")
; #define PG8_BAR __builtin_amdgcn_s_barrier()
; #define PG8_SCHED __builtin_amdgcn_sched_barrier(0)
; template <class Epi, class Sched, bool ALIGN_EPI = false, bool SP2 = false>
; __device__ __forceinline__ void gemm_phase(PG8_LAS unsigned char* lds, const Gemm g, const Sched& S, const Epi& E) {
;     ...
;             PG8_LDB(B0, 1, 0); PG8_LDB(B1, 1, 1); PG8_SCHED; PG8_LDA(At, 1, 0); PG8_STAGE(PG8_SA(0, 1), a2 + hstep, voffA);
;             PG8_WAIT_V(8); PG8_WAIT_L(0); PG8_BAR; PG8_MMA(0, 0, At, B0); PG8_MMA(0, 1, At, B1); PG8_BAR; PG8_SCHED;
	s_add_i32 s3, 0, 0x18000
	v_add_u32_e32 v159, s3, v153
	s_add_i32 s33, 0, 0x1c000
	ds_read_b128 v[144:147], v159
	ds_read_b128 v[148:151], v159 offset:1024
	ds_read_b128 v[160:163], v159 offset:2048
	ds_read_b128 v[168:171], v159 offset:3072
	v_add_u32_e32 v159, s33, v153
	ds_read_b128 v[172:175], v159
	ds_read_b128 v[176:179], v159 offset:1024
	ds_read_b128 v[182:185], v159 offset:2048
	ds_read_b128 v[186:189], v159 offset:3072
	s_add_u32 s14, s54, 0x40000
	s_addc_u32 s15, s55, 0
	s_mov_b32 m0, s58
	v_lshl_add_u64 v[232:233], s[14:15], 0, v[134:135]
	ds_read_b128 v[190:193], v157 offset:32768
	ds_read_b128 v[194:197], v157 offset:33792
	ds_read_b128 v[198:201], v157 offset:34816
	ds_read_b128 v[208:211], v157 offset:35840
	ds_read_b128 v[212:215], v157 offset:36864
	ds_read_b128 v[216:219], v157 offset:37888
	ds_read_b128 v[220:223], v157 offset:38912
	ds_read_b128 v[224:227], v157 offset:39936
	global_load_lds_dwordx4 v[232:233], off
	v_lshl_add_u64 v[232:233], s[14:15], 0, v[130:131]
	s_mov_b32 m0, s59
	s_nop 0
	global_load_lds_dwordx4 v[232:233], off
	s_waitcnt vmcnt(8)
	s_waitcnt lgkmcnt(0)
	s_barrier
	s_setprio 1
	s_waitcnt lgkmcnt(0)
	v_mfma_f32_16x16x32_bf16 v[124:127], v[144:147], v[190:193], v[124:127]
	v_mfma_f32_16x16x32_bf16 v[120:123], v[160:163], v[190:193], v[120:123]
	v_mfma_f32_16x16x32_bf16 v[108:111], v[144:147], v[198:201], v[108:111]
	v_mfma_f32_16x16x32_bf16 v[104:107], v[160:163], v[198:201], v[104:107]
	v_mfma_f32_16x16x32_bf16 v[124:127], v[148:151], v[194:197], v[124:127]
	v_mfma_f32_16x16x32_bf16 v[120:123], v[168:171], v[194:197], v[120:123]
	v_mfma_f32_16x16x32_bf16 v[108:111], v[148:151], v[208:211], v[108:111]
	v_mfma_f32_16x16x32_bf16 v[104:107], v[168:171], v[208:211], v[104:107]
	v_mfma_f32_16x16x32_bf16 v[92:95], v[144:147], v[212:215], v[92:95]
	v_mfma_f32_16x16x32_bf16 v[88:91], v[160:163], v[212:215], v[88:91]
	v_mfma_f32_16x16x32_bf16 v[76:79], v[144:147], v[220:223], v[76:79]
	v_mfma_f32_16x16x32_bf16 v[72:75], v[160:163], v[220:223], v[72:75]
	v_mfma_f32_16x16x32_bf16 v[92:95], v[148:151], v[216:219], v[92:95]
	v_mfma_f32_16x16x32_bf16 v[88:91], v[168:171], v[216:219], v[88:91]
	v_mfma_f32_16x16x32_bf16 v[76:79], v[148:151], v[224:227], v[76:79]
	v_mfma_f32_16x16x32_bf16 v[72:75], v[168:171], v[224:227], v[72:75]
	s_setprio 0
	s_setprio 1
	v_mfma_f32_16x16x32_bf16 v[116:119], v[172:175], v[190:193], v[116:119]
	v_mfma_f32_16x16x32_bf16 v[112:115], v[182:185], v[190:193], v[112:115]
	v_mfma_f32_16x16x32_bf16 v[100:103], v[172:175], v[198:201], v[100:103]
	v_mfma_f32_16x16x32_bf16 v[96:99], v[182:185], v[198:201], v[96:99]
	v_mfma_f32_16x16x32_bf16 v[116:119], v[176:179], v[194:197], v[116:119]
	v_mfma_f32_16x16x32_bf16 v[112:115], v[186:189], v[194:197], v[112:115]
	v_mfma_f32_16x16x32_bf16 v[100:103], v[176:179], v[208:211], v[100:103]
	v_mfma_f32_16x16x32_bf16 v[96:99], v[186:189], v[208:211], v[96:99]
	v_mfma_f32_16x16x32_bf16 v[84:87], v[172:175], v[212:215], v[84:87]
	v_mfma_f32_16x16x32_bf16 v[80:83], v[182:185], v[212:215], v[80:83]
	v_mfma_f32_16x16x32_bf16 v[68:71], v[172:175], v[220:223], v[68:71]
	v_mfma_f32_16x16x32_bf16 v[64:67], v[182:185], v[220:223], v[64:67]
	v_mfma_f32_16x16x32_bf16 v[84:87], v[176:179], v[216:219], v[84:87]
	v_mfma_f32_16x16x32_bf16 v[80:83], v[186:189], v[216:219], v[80:83]
	v_mfma_f32_16x16x32_bf16 v[68:71], v[176:179], v[224:227], v[68:71]
	v_mfma_f32_16x16x32_bf16 v[64:67], v[186:189], v[224:227], v[64:67]
	s_setprio 0
	s_barrier
; #define PG8_STAGE(bufoff, gbase, voff) do { _Pragma("unroll") for (int _i = 0; _i < 2; ++_i) \
;         __builtin_amdgcn_global_load_lds((const unsigned*)((const char*)(gbase) + (voff)[_i]), (PG8_LAS unsigned*)(lds + (bufoff) + ldsw + _i * 8192), 16, 0, 0); } while (0)
; #define PG8_LDA(dst, b, h) do { _Pragma("unroll") for (int m = 0; m < 4; ++m) _Pragma("unroll") for (int k = 0; k < 2; ++k) dst[m][k] = *(const PG8_LAS bf16x8*)(lds + PG8_SA(b, h) + aoff + m * 2048 + k * 1024); } while (0)
; #define PG8_MMA(ai, bj, At, Bt) do { __builtin_amdgcn_s_setprio(1); _Pragma("unroll") for (int m = 0; m < 4; ++m) _Pragma("unroll") for (int n = 0; n < 2; ++n) _Pragma("unroll") for (int k = 0; k < 2; ++k) \
;         acc[ai][bj][m][n] = __builtin_amdgcn_mfma_f32_16x16x32_bf16(Bt[n][k], At[m][k], acc[ai][bj][m][n], 0, 0, 0); __builtin_amdgcn_s_setprio(0); } while (0)
; #define PG8_WAIT_V(n) asm volatile("s_waitcnt vmcnt(" #n ")" ::: "memory")
; #define PG8_WAIT_L(n) asm volatile("s_waitcnt lgkmcnt(" #n ")" ::: "memory")
; #define PG8_BAR __builtin_amdgcn_s_barrier()
; #define PG8_SCHED __builtin_amdgcn_sched_barrier(0)
; template <class Epi, class Sched, bool ALIGN_EPI = false, bool SP2 = false>
; __device__ __forceinline__ void gemm_phase(PG8_LAS unsigned char* lds, const Gemm g, const Sched& S, const Epi& E) {
;     ...
;             PG8_LDA(At, 1, 1); PG8_STAGE(PG8_SB(1, 0), b3, voffB); PG8_STAGE(PG8_SB(1, 1), b3 + hstep, voffB); PG8_STAGE(PG8_SA(1, 0), a3, voffA);
;             PG8_WAIT_V(8); PG8_WAIT_L(0); PG8_BAR; PG8_MMA(1, 0, At, B0); PG8_MMA(1, 1, At, B1); PG8_BAR; PG8_SCHED;
;     ...
;         if constexpr (ALIGN_EPI) { if (wr == 0) PG8_BAR; }
;         if constexpr (!Epi::AFTER_DRAIN) { E(acc, cur, wr, wc, fr, fq); S.done(cur); }
	s_add_i32 s3, s3, s43
	v_lshl_add_u64 v[164:165], v[164:165], 0, s[10:11]
	s_mov_b32 m0, s3
	ds_read_b128 v[190:193], v157 offset:49152
	ds_read_b128 v[194:197], v157 offset:50176
	ds_read_b128 v[198:201], v157 offset:51200
	ds_read_b128 v[208:211], v157 offset:52224
	ds_read_b128 v[212:215], v157 offset:53248
	ds_read_b128 v[216:219], v157 offset:54272
	ds_read_b128 v[220:223], v157 offset:55296
	ds_read_b128 v[224:227], v157 offset:56320
	global_load_lds_dwordx4 v[164:165], off
	s_add_i32 m0, s3, 0x2000
	s_add_u32 s14, s50, 0x40080
	v_lshl_add_u64 v[164:165], v[202:203], 0, s[10:11]
	s_addc_u32 s15, s51, 0
	s_add_i32 s3, s33, s43
	global_load_lds_dwordx4 v[164:165], off
	v_lshl_add_u64 v[164:165], s[14:15], 0, v[132:133]
	s_mov_b32 m0, s3
	s_nop 0
	global_load_lds_dwordx4 v[164:165], off
	v_lshl_add_u64 v[164:165], s[14:15], 0, v[128:129]
	s_add_i32 m0, s3, 0x2000
	s_nop 0
	global_load_lds_dwordx4 v[164:165], off
	s_waitcnt vmcnt(6)
	s_waitcnt lgkmcnt(0)
	s_barrier
	s_setprio 1
	s_waitcnt lgkmcnt(0)
	v_mfma_f32_16x16x32_bf16 v[60:63], v[144:147], v[190:193], v[60:63]
	v_mfma_f32_16x16x32_bf16 v[56:59], v[160:163], v[190:193], v[56:59]
	v_mfma_f32_16x16x32_bf16 v[44:47], v[144:147], v[198:201], v[44:47]
	v_mfma_f32_16x16x32_bf16 v[40:43], v[160:163], v[198:201], v[40:43]
	v_mfma_f32_16x16x32_bf16 v[60:63], v[148:151], v[194:197], v[60:63]
	v_mfma_f32_16x16x32_bf16 v[56:59], v[168:171], v[194:197], v[56:59]
	v_mfma_f32_16x16x32_bf16 v[44:47], v[148:151], v[208:211], v[44:47]
	v_mfma_f32_16x16x32_bf16 v[40:43], v[168:171], v[208:211], v[40:43]
	v_mfma_f32_16x16x32_bf16 v[28:31], v[144:147], v[212:215], v[28:31]
	v_mfma_f32_16x16x32_bf16 v[24:27], v[160:163], v[212:215], v[24:27]
	v_mfma_f32_16x16x32_bf16 v[12:15], v[144:147], v[220:223], v[12:15]
	v_mfma_f32_16x16x32_bf16 v[8:11], v[160:163], v[220:223], v[8:11]
	v_mfma_f32_16x16x32_bf16 v[28:31], v[148:151], v[216:219], v[28:31]
	v_mfma_f32_16x16x32_bf16 v[24:27], v[168:171], v[216:219], v[24:27]
	v_lshl_add_u64 v[164:165], v[228:229], 0, s[10:11]
	s_mov_b32 m0, s61
	s_nop 0
	global_load_lds_dwordx4 v[164:165], off
	v_mfma_f32_16x16x32_bf16 v[12:15], v[148:151], v[224:227], v[12:15]
	v_mfma_f32_16x16x32_bf16 v[8:11], v[168:171], v[224:227], v[8:11]
	s_setprio 0
	s_setprio 1
	v_mfma_f32_16x16x32_bf16 v[52:55], v[172:175], v[190:193], v[52:55]
	v_mfma_f32_16x16x32_bf16 v[48:51], v[182:185], v[190:193], v[48:51]
	v_mfma_f32_16x16x32_bf16 v[36:39], v[172:175], v[198:201], v[36:39]
	v_mfma_f32_16x16x32_bf16 v[32:35], v[182:185], v[198:201], v[32:35]
	v_mfma_f32_16x16x32_bf16 v[52:55], v[176:179], v[194:197], v[52:55]
	v_mfma_f32_16x16x32_bf16 v[48:51], v[186:189], v[194:197], v[48:51]
	v_mfma_f32_16x16x32_bf16 v[36:39], v[176:179], v[208:211], v[36:39]
	v_mfma_f32_16x16x32_bf16 v[32:35], v[186:189], v[208:211], v[32:35]
	v_mfma_f32_16x16x32_bf16 v[20:23], v[172:175], v[212:215], v[20:23]
	v_mfma_f32_16x16x32_bf16 v[16:19], v[182:185], v[212:215], v[16:19]
	v_mfma_f32_16x16x32_bf16 v[4:7], v[172:175], v[220:223], v[4:7]
	v_mfma_f32_16x16x32_bf16 v[0:3], v[182:185], v[220:223], v[0:3]
	v_mfma_f32_16x16x32_bf16 v[20:23], v[176:179], v[216:219], v[20:23]
	v_mfma_f32_16x16x32_bf16 v[16:19], v[186:189], v[216:219], v[16:19]
	v_lshl_add_u64 v[164:165], v[230:231], 0, s[10:11]
	s_mov_b32 m0, s62
	s_nop 0
	global_load_lds_dwordx4 v[164:165], off
	v_mfma_f32_16x16x32_bf16 v[4:7], v[176:179], v[224:227], v[4:7]
	v_mfma_f32_16x16x32_bf16 v[0:3], v[186:189], v[224:227], v[0:3]
	s_setprio 0
	s_barrier
	s_add_i32 s89, s89, 2
	s_add_u32 s48, s48, 0x100
	s_addc_u32 s49, s49, 0
	s_add_u32 s87, s87, 0x100
	s_addc_u32 s88, s88, 0
	s_cmp_gt_u32 s89, 13
	s_cbranch_scc0 .LBB0_191
	v_lshl_add_u32 v144, s44, 8, v152
	v_ashrrev_i32_e32 v145, 31, v144
	v_lshl_add_u64 v[150:151], v[144:145], 3, s[6:7]
	global_load_dwordx2 v[182:183], v[150:151], off
	global_load_dwordx2 v[184:185], v[150:151], off offset:128
	global_load_dwordx2 v[186:187], v[150:151], off offset:256
	global_load_dwordx2 v[188:189], v[150:151], off offset:384
	global_load_dwordx2 v[190:191], v[150:151], off offset:1024
	global_load_dwordx2 v[192:193], v[150:151], off offset:1152
	global_load_dwordx2 v[194:195], v[150:151], off offset:1280
	global_load_dwordx2 v[196:197], v[150:151], off offset:1408
	s_and_b64 vcc, exec, s[16:17]
	s_cbranch_vccz .LBB0_194
	s_barrier

; #define PG8_STAGE(bufoff, gbase, voff) do { _Pragma("unroll") for (int _i = 0; _i < 2; ++_i) \
;         __builtin_amdgcn_global_load_lds((const unsigned*)((const char*)(gbase) + (voff)[_i]), (PG8_LAS unsigned*)(lds + (bufoff) + ldsw + _i * 8192), 16, 0, 0); } while (0)
; #define PG8_LDA(dst, b, h) do { _Pragma("unroll") for (int m = 0; m < 4; ++m) _Pragma("unroll") for (int k = 0; k < 2; ++k) dst[m][k] = *(const PG8_LAS bf16x8*)(lds + PG8_SA(b, h) + aoff + m * 2048 + k * 1024); } while (0)
; #define PG8_LDB(dst, b, h) do { _Pragma("unroll") for (int n = 0; n < 2; ++n) _Pragma("unroll") for (int k = 0; k < 2; ++k) dst[n][k] = *(const PG8_LAS bf16x8*)(lds + PG8_SB(b, h) + boff + n * 2048 + k * 1024); } while (0)
; #define PG8_WAIT_V(n) asm volatile("s_waitcnt vmcnt(" #n ")" ::: "memory")
; #define PG8_WAIT_L(n) asm volatile("s_waitcnt lgkmcnt(" #n ")" ::: "memory")
; #define PG8_BAR __builtin_amdgcn_s_barrier()
; #define PG8_SCHED __builtin_amdgcn_sched_barrier(0)
; template <class Epi, class Sched, bool ALIGN_EPI = false, bool SP2 = false>
; __device__ __forceinline__ void gemm_phase(PG8_LAS unsigned char* lds, const Gemm g, const Sched& S, const Epi& E) {
;     ...
;         const bool has_next = S.next(ui + 1, nxt);
;         const char* nA = has_next ? (const char*)g.A + (size_t)nxt.pm * tstep : cA; const char* nB = has_next ? (const char*)g.Bt + (size_t)nxt.pn * tstep : cB;
;         for (int t = 0; t < nt; t += 2) {
;             const bool last = (t == nt - 2);
;             const char* a1 = cA + (size_t)(t + 1) * kstep;
;             const char* a2 = last ? nA : cA + (size_t)(t + 2) * kstep; const char* b2 = last ? nB : cB + (size_t)(t + 2) * kstep;
;             const char* a3 = a2 + kstep; const char* b3 = b2 + kstep;
;             if (last && has_next) S.a_ready(nxt);
;             if constexpr (SP2) {
;             PG8_LDB(B0, 0, 0); PG8_LDB(B1, 0, 1); PG8_SCHED; PG8_LDA(At, 0, 0); PG8_STAGE(PG8_SA(1, 1), a1 + hstep, voffA);
;             PG8_WAIT_V(8); PG8_WAIT_L(0); PG8_BAR; PG8_MMA(0, 0, At, B0); PG8_MMA(0, 1, At, B1); PG8_BAR; PG8_SCHED;
;             PG8_LDA(At, 0, 1); PG8_STAGE(PG8_SB(0, 0), b2, voffB); PG8_STAGE(PG8_SB(0, 1), b2 + hstep, voffB); PG8_STAGE(PG8_SA(0, 0), a2, voffA);
;             PG8_WAIT_V(8); PG8_WAIT_L(0); PG8_BAR; PG8_MMA(1, 0, At, B0); PG8_MMA(1, 1, At, B1); PG8_BAR; PG8_SCHED;
.LBB0_268:
	s_add_u32 s91, s50, 0x100
	s_addc_u32 s92, s51, 0
	s_mov_b32 s93, -2
	s_waitcnt lgkmcnt(0)
	ds_read_b128 v[128:131], v165
	ds_read_b128 v[132:135], v165 offset:1024
	ds_read_b128 v[152:155], v165 offset:2048
	ds_read_b128 v[156:159], v165 offset:3072
	ds_read_b128 v[172:175], v168
	ds_read_b128 v[176:179], v168 offset:1024
	ds_read_b128 v[182:185], v168 offset:2048
	ds_read_b128 v[186:189], v168 offset:3072
	s_add_u32 s50, s10, 0x100
	s_addc_u32 s51, s11, 0
	s_cmp_eq_u32 s93, 40
	s_cselect_b32 s57, s1, s51
	s_cselect_b32 s56, s0, s50
	s_cselect_b32 s55, s49, s92
	s_cselect_b32 s54, s48, s91
	v_lshl_add_u64 v[160:161], s[10:11], 0, v[144:145]
	s_add_i32 m0, s58, 0xc000
	ds_read_b128 v[190:193], v169
	ds_read_b128 v[194:197], v169 offset:1024
	ds_read_b128 v[198:201], v169 offset:2048
	ds_read_b128 v[208:211], v169 offset:3072
	ds_read_b128 v[212:215], v169 offset:4096
	ds_read_b128 v[216:219], v169 offset:5120
	ds_read_b128 v[220:223], v169 offset:6144
	ds_read_b128 v[224:227], v169 offset:7168
	global_load_lds_dwordx4 v[160:161], off
	v_lshl_add_u64 v[160:161], s[10:11], 0, v[146:147]
	s_add_i32 m0, s58, 0xe000
	s_nop 0
	global_load_lds_dwordx4 v[160:161], off
	s_waitcnt vmcnt(8)
	s_waitcnt lgkmcnt(0)
	s_barrier
	s_setprio 1
	s_waitcnt lgkmcnt(0)
	v_mfma_f32_16x16x32_bf16 v[124:127], v[128:131], v[190:193], 0
	v_mfma_f32_16x16x32_bf16 v[120:123], v[152:155], v[190:193], 0
	v_mfma_f32_16x16x32_bf16 v[108:111], v[128:131], v[198:201], 0
	v_mfma_f32_16x16x32_bf16 v[104:107], v[152:155], v[198:201], 0
	v_mfma_f32_16x16x32_bf16 v[124:127], v[132:135], v[194:197], v[124:127]
	v_mfma_f32_16x16x32_bf16 v[120:123], v[156:159], v[194:197], v[120:123]
	v_mfma_f32_16x16x32_bf16 v[108:111], v[132:135], v[208:211], v[108:111]
	v_mfma_f32_16x16x32_bf16 v[104:107], v[156:159], v[208:211], v[104:107]
	v_mfma_f32_16x16x32_bf16 v[92:95], v[128:131], v[212:215], 0
	v_mfma_f32_16x16x32_bf16 v[88:91], v[152:155], v[212:215], 0
	v_mfma_f32_16x16x32_bf16 v[76:79], v[128:131], v[220:223], 0
	v_mfma_f32_16x16x32_bf16 v[72:75], v[152:155], v[220:223], 0
	v_mfma_f32_16x16x32_bf16 v[92:95], v[132:135], v[216:219], v[92:95]
	v_mfma_f32_16x16x32_bf16 v[88:91], v[156:159], v[216:219], v[88:91]
	v_mfma_f32_16x16x32_bf16 v[76:79], v[132:135], v[224:227], v[76:79]
	v_mfma_f32_16x16x32_bf16 v[72:75], v[156:159], v[224:227], v[72:75]
	s_setprio 0
	s_setprio 1
	v_mfma_f32_16x16x32_bf16 v[116:119], v[172:175], v[190:193], 0
	v_mfma_f32_16x16x32_bf16 v[112:115], v[182:185], v[190:193], 0
	v_mfma_f32_16x16x32_bf16 v[100:103], v[172:175], v[198:201], 0
	v_mfma_f32_16x16x32_bf16 v[96:99], v[182:185], v[198:201], 0
	v_mfma_f32_16x16x32_bf16 v[116:119], v[176:179], v[194:197], v[116:119]
	v_mfma_f32_16x16x32_bf16 v[112:115], v[186:189], v[194:197], v[112:115]
	v_mfma_f32_16x16x32_bf16 v[100:103], v[176:179], v[208:211], v[100:103]
	v_mfma_f32_16x16x32_bf16 v[96:99], v[186:189], v[208:211], v[96:99]
	v_mfma_f32_16x16x32_bf16 v[84:87], v[172:175], v[212:215], 0
	v_mfma_f32_16x16x32_bf16 v[80:83], v[182:185], v[212:215], 0
	v_mfma_f32_16x16x32_bf16 v[68:71], v[172:175], v[220:223], 0
	v_mfma_f32_16x16x32_bf16 v[64:67], v[182:185], v[220:223], 0
	v_mfma_f32_16x16x32_bf16 v[84:87], v[176:179], v[216:219], v[84:87]
	v_mfma_f32_16x16x32_bf16 v[80:83], v[186:189], v[216:219], v[80:83]
	v_mfma_f32_16x16x32_bf16 v[68:71], v[176:179], v[224:227], v[68:71]
	v_mfma_f32_16x16x32_bf16 v[64:67], v[186:189], v[224:227], v[64:67]
	s_setprio 0
	s_barrier
	s_add_i32 s3, s65, s43
	v_lshl_add_u64 v[160:161], s[54:55], 0, v[138:139]
	s_mov_b32 m0, s3
	ds_read_b128 v[190:193], v169 offset:16384
	ds_read_b128 v[194:197], v169 offset:17408
	ds_read_b128 v[198:201], v169 offset:18432
	ds_read_b128 v[208:211], v169 offset:19456
	ds_read_b128 v[212:215], v169 offset:20480
	ds_read_b128 v[216:219], v169 offset:21504
	ds_read_b128 v[220:223], v169 offset:22528
	ds_read_b128 v[224:227], v169 offset:23552
	global_load_lds_dwordx4 v[160:161], off
	s_add_i32 m0, s3, 0x2000
	s_add_u32 s10, s54, 0xb0000
	v_lshl_add_u64 v[202:203], s[54:55], 0, v[142:143]
	s_addc_u32 s11, s55, 0
	s_add_i32 s3, s66, s43
	global_load_lds_dwordx4 v[202:203], off
	v_lshl_add_u64 v[228:229], s[10:11], 0, v[138:139]
	s_mov_b32 m0, s3
	global_load_lds_dwordx4 v[228:229], off
	v_lshl_add_u64 v[228:229], s[10:11], 0, v[142:143]
	s_add_i32 m0, s3, 0x2000
	s_nop 0
	global_load_lds_dwordx4 v[228:229], off
	s_waitcnt vmcnt(6)
	s_waitcnt lgkmcnt(0)
	s_barrier
; #define PG8_STAGE(bufoff, gbase, voff) do { _Pragma("unroll") for (int _i = 0; _i < 2; ++_i) \
;         __builtin_amdgcn_global_load_lds((const unsigned*)((const char*)(gbase) + (voff)[_i]), (PG8_LAS unsigned*)(lds + (bufoff) + ldsw + _i * 8192), 16, 0, 0); } while (0)
; #define PG8_LDA(dst, b, h) do { _Pragma("unroll") for (int m = 0; m < 4; ++m) _Pragma("unroll") for (int k = 0; k < 2; ++k) dst[m][k] = *(const PG8_LAS bf16x8*)(lds + PG8_SA(b, h) + aoff + m * 2048 + k * 1024); } while (0)
; #define PG8_LDB(dst, b, h) do { _Pragma("unroll") for (int n = 0; n < 2; ++n) _Pragma("unroll") for (int k = 0; k < 2; ++k) dst[n][k] = *(const PG8_LAS bf16x8*)(lds + PG8_SB(b, h) + boff + n * 2048 + k * 1024); } while (0)
; #define PG8_MMA(ai, bj, At, Bt) do { __builtin_amdgcn_s_setprio(1); _Pragma("unroll") for (int m = 0; m < 4; ++m) _Pragma("unroll") for (int n = 0; n < 2; ++n) _Pragma("unroll") for (int k = 0; k < 2; ++k) \
;         acc[ai][bj][m][n] = __builtin_amdgcn_mfma_f32_16x16x32_bf16(Bt[n][k], At[m][k], acc[ai][bj][m][n], 0, 0, 0); __builtin_amdgcn_s_setprio(0); } while (0)
; #define PG8_WAIT_V(n) asm volatile("s_waitcnt vmcnt(" #n ")" ::: "memory")
; #define PG8_WAIT_L(n) asm volatile("s_waitcnt lgkmcnt(" #n ")" ::: "memory")
; #define PG8_BAR __builtin_amdgcn_s_barrier()
; #define PG8_SCHED __builtin_amdgcn_sched_barrier(0)
; template <class Epi, class Sched, bool ALIGN_EPI = false, bool SP2 = false>
; __device__ __forceinline__ void gemm_phase(PG8_LAS unsigned char* lds, const Gemm g, const Sched& S, const Epi& E) {
;     ...
;             PG8_WAIT_V(8); PG8_WAIT_L(0); PG8_BAR; PG8_MMA(0, 0, At, B0); PG8_MMA(0, 1, At, B1); PG8_BAR; PG8_SCHED;
;             PG8_LDA(At, 0, 1); PG8_STAGE(PG8_SB(0, 0), b2, voffB); PG8_STAGE(PG8_SB(0, 1), b2 + hstep, voffB); PG8_STAGE(PG8_SA(0, 0), a2, voffA);
;             PG8_WAIT_V(8); PG8_WAIT_L(0); PG8_BAR; PG8_MMA(1, 0, At, B0); PG8_MMA(1, 1, At, B1); PG8_BAR; PG8_SCHED;
;             PG8_LDB(B0, 1, 0); PG8_LDB(B1, 1, 1); PG8_SCHED; PG8_LDA(At, 1, 0); PG8_STAGE(PG8_SA(0, 1), a2 + hstep, voffA);
;             PG8_WAIT_V(8); PG8_WAIT_L(0); PG8_BAR; PG8_MMA(0, 0, At, B0); PG8_MMA(0, 1, At, B1); PG8_BAR; PG8_SCHED;
	s_setprio 1
	s_waitcnt lgkmcnt(0)
	v_mfma_f32_16x16x32_bf16 v[60:63], v[128:131], v[190:193], 0
	v_mfma_f32_16x16x32_bf16 v[56:59], v[152:155], v[190:193], 0
	v_mfma_f32_16x16x32_bf16 v[44:47], v[128:131], v[198:201], 0
	v_mfma_f32_16x16x32_bf16 v[40:43], v[152:155], v[198:201], 0
	v_mfma_f32_16x16x32_bf16 v[60:63], v[132:135], v[194:197], v[60:63]
	v_mfma_f32_16x16x32_bf16 v[56:59], v[156:159], v[194:197], v[56:59]
	v_mfma_f32_16x16x32_bf16 v[44:47], v[132:135], v[208:211], v[44:47]
	v_mfma_f32_16x16x32_bf16 v[40:43], v[156:159], v[208:211], v[40:43]
	v_mfma_f32_16x16x32_bf16 v[28:31], v[128:131], v[212:215], 0
	v_mfma_f32_16x16x32_bf16 v[24:27], v[152:155], v[212:215], 0
	v_mfma_f32_16x16x32_bf16 v[12:15], v[128:131], v[220:223], 0
	v_mfma_f32_16x16x32_bf16 v[8:11], v[152:155], v[220:223], 0
	v_mfma_f32_16x16x32_bf16 v[28:31], v[132:135], v[216:219], v[28:31]
	v_mfma_f32_16x16x32_bf16 v[24:27], v[156:159], v[216:219], v[24:27]
	v_lshl_add_u64 v[228:229], s[56:57], 0, v[136:137]
	s_mov_b32 m0, s58
	s_nop 0
	global_load_lds_dwordx4 v[228:229], off
	v_mfma_f32_16x16x32_bf16 v[12:15], v[132:135], v[224:227], v[12:15]
	v_mfma_f32_16x16x32_bf16 v[8:11], v[156:159], v[224:227], v[8:11]
	s_setprio 0
	s_setprio 1
	v_mfma_f32_16x16x32_bf16 v[52:55], v[172:175], v[190:193], 0
	v_mfma_f32_16x16x32_bf16 v[48:51], v[182:185], v[190:193], 0
	v_mfma_f32_16x16x32_bf16 v[36:39], v[172:175], v[198:201], 0
	v_mfma_f32_16x16x32_bf16 v[32:35], v[182:185], v[198:201], 0
	v_mfma_f32_16x16x32_bf16 v[52:55], v[176:179], v[194:197], v[52:55]
	v_mfma_f32_16x16x32_bf16 v[48:51], v[186:189], v[194:197], v[48:51]
	v_mfma_f32_16x16x32_bf16 v[36:39], v[176:179], v[208:211], v[36:39]
	v_mfma_f32_16x16x32_bf16 v[32:35], v[186:189], v[208:211], v[32:35]
	v_mfma_f32_16x16x32_bf16 v[20:23], v[172:175], v[212:215], 0
	v_mfma_f32_16x16x32_bf16 v[16:19], v[182:185], v[212:215], 0
	v_mfma_f32_16x16x32_bf16 v[4:7], v[172:175], v[220:223], 0
	v_mfma_f32_16x16x32_bf16 v[0:3], v[182:185], v[220:223], 0
	v_mfma_f32_16x16x32_bf16 v[20:23], v[176:179], v[216:219], v[20:23]
	v_mfma_f32_16x16x32_bf16 v[16:19], v[186:189], v[216:219], v[16:19]
	v_lshl_add_u64 v[230:231], s[56:57], 0, v[140:141]
	s_mov_b32 m0, s59
	s_nop 0
	global_load_lds_dwordx4 v[230:231], off
	v_mfma_f32_16x16x32_bf16 v[4:7], v[176:179], v[224:227], v[4:7]
	v_mfma_f32_16x16x32_bf16 v[0:3], v[186:189], v[224:227], v[0:3]
	s_setprio 0
	s_barrier
	s_add_i32 s3, 0, 0x18000
	s_add_i32 s14, 0, 0x1c000
	v_add_u32_e32 v156, s3, v163
	v_add_u32_e32 v171, s14, v163
	ds_read_b128 v[128:131], v156
	ds_read_b128 v[132:135], v156 offset:1024
	ds_read_b128 v[152:155], v156 offset:2048
	ds_read_b128 v[156:159], v156 offset:3072
	ds_read_b128 v[172:175], v171
	ds_read_b128 v[176:179], v171 offset:1024
	ds_read_b128 v[182:185], v171 offset:2048
	ds_read_b128 v[186:189], v171 offset:3072
	s_add_u32 s10, s56, 0xb0000
	s_addc_u32 s11, s57, 0
	s_mov_b32 m0, s60
	v_lshl_add_u64 v[232:233], s[10:11], 0, v[136:137]
	ds_read_b128 v[190:193], v169 offset:32768
	ds_read_b128 v[194:197], v169 offset:33792
	ds_read_b128 v[198:201], v169 offset:34816
	ds_read_b128 v[208:211], v169 offset:35840
	ds_read_b128 v[212:215], v169 offset:36864
	ds_read_b128 v[216:219], v169 offset:37888
	ds_read_b128 v[220:223], v169 offset:38912
	ds_read_b128 v[224:227], v169 offset:39936
	global_load_lds_dwordx4 v[232:233], off
	v_lshl_add_u64 v[232:233], s[10:11], 0, v[140:141]
	s_mov_b32 m0, s61
	s_nop 0
	global_load_lds_dwordx4 v[232:233], off
	s_waitcnt vmcnt(8)
	s_waitcnt lgkmcnt(0)
	s_barrier
	s_setprio 1
	s_waitcnt lgkmcnt(0)
	v_mfma_f32_16x16x32_bf16 v[124:127], v[128:131], v[190:193], v[124:127]
	v_mfma_f32_16x16x32_bf16 v[120:123], v[152:155], v[190:193], v[120:123]
	v_mfma_f32_16x16x32_bf16 v[108:111], v[128:131], v[198:201], v[108:111]
	v_mfma_f32_16x16x32_bf16 v[104:107], v[152:155], v[198:201], v[104:107]
	v_mfma_f32_16x16x32_bf16 v[124:127], v[132:135], v[194:197], v[124:127]
	v_mfma_f32_16x16x32_bf16 v[120:123], v[156:159], v[194:197], v[120:123]
	v_mfma_f32_16x16x32_bf16 v[108:111], v[132:135], v[208:211], v[108:111]
	v_mfma_f32_16x16x32_bf16 v[104:107], v[156:159], v[208:211], v[104:107]
	v_mfma_f32_16x16x32_bf16 v[92:95], v[128:131], v[212:215], v[92:95]
	v_mfma_f32_16x16x32_bf16 v[88:91], v[152:155], v[212:215], v[88:91]
	v_mfma_f32_16x16x32_bf16 v[76:79], v[128:131], v[220:223], v[76:79]
	v_mfma_f32_16x16x32_bf16 v[72:75], v[152:155], v[220:223], v[72:75]
	v_mfma_f32_16x16x32_bf16 v[92:95], v[132:135], v[216:219], v[92:95]
	v_mfma_f32_16x16x32_bf16 v[88:91], v[156:159], v[216:219], v[88:91]
	v_mfma_f32_16x16x32_bf16 v[76:79], v[132:135], v[224:227], v[76:79]
	v_mfma_f32_16x16x32_bf16 v[72:75], v[156:159], v[224:227], v[72:75]
	s_setprio 0
	s_setprio 1
	v_mfma_f32_16x16x32_bf16 v[116:119], v[172:175], v[190:193], v[116:119]
	v_mfma_f32_16x16x32_bf16 v[112:115], v[182:185], v[190:193], v[112:115]
	v_mfma_f32_16x16x32_bf16 v[100:103], v[172:175], v[198:201], v[100:103]
	v_mfma_f32_16x16x32_bf16 v[96:99], v[182:185], v[198:201], v[96:99]
	v_mfma_f32_16x16x32_bf16 v[116:119], v[176:179], v[194:197], v[116:119]
	v_mfma_f32_16x16x32_bf16 v[112:115], v[186:189], v[194:197], v[112:115]
	v_mfma_f32_16x16x32_bf16 v[100:103], v[176:179], v[208:211], v[100:103]
	v_mfma_f32_16x16x32_bf16 v[96:99], v[186:189], v[208:211], v[96:99]
	v_mfma_f32_16x16x32_bf16 v[84:87], v[172:175], v[212:215], v[84:87]
	v_mfma_f32_16x16x32_bf16 v[80:83], v[182:185], v[212:215], v[80:83]
	v_mfma_f32_16x16x32_bf16 v[68:71], v[172:175], v[220:223], v[68:71]
	v_mfma_f32_16x16x32_bf16 v[64:67], v[182:185], v[220:223], v[64:67]
	v_mfma_f32_16x16x32_bf16 v[84:87], v[176:179], v[216:219], v[84:87]
	v_mfma_f32_16x16x32_bf16 v[80:83], v[186:189], v[216:219], v[80:83]
	v_mfma_f32_16x16x32_bf16 v[68:71], v[176:179], v[224:227], v[68:71]
	v_mfma_f32_16x16x32_bf16 v[64:67], v[186:189], v[224:227], v[64:67]
	s_setprio 0
	s_barrier
; #define PG8_STAGE(bufoff, gbase, voff) do { _Pragma("unroll") for (int _i = 0; _i < 2; ++_i) \
;         __builtin_amdgcn_global_load_lds((const unsigned*)((const char*)(gbase) + (voff)[_i]), (PG8_LAS unsigned*)(lds + (bufoff) + ldsw + _i * 8192), 16, 0, 0); } while (0)
; #define PG8_LDA(dst, b, h) do { _Pragma("unroll") for (int m = 0; m < 4; ++m) _Pragma("unroll") for (int k = 0; k < 2; ++k) dst[m][k] = *(const PG8_LAS bf16x8*)(lds + PG8_SA(b, h) + aoff + m * 2048 + k * 1024); } while (0)
; #define PG8_LDB(dst, b, h) do { _Pragma("unroll") for (int n = 0; n < 2; ++n) _Pragma("unroll") for (int k = 0; k < 2; ++k) dst[n][k] = *(const PG8_LAS bf16x8*)(lds + PG8_SB(b, h) + boff + n * 2048 + k * 1024); } while (0)
; template <class Epi, class Sched, bool ALIGN_EPI = false, bool SP2 = false>
; __device__ __forceinline__ void gemm_phase(PG8_LAS unsigned char* lds, const Gemm g, const Sched& S, const Epi& E) {
;     ...
;         for (int t = 0; t < nt; t += 2) {
;             const bool last = (t == nt - 2);
;             const char* a1 = cA + (size_t)(t + 1) * kstep;
;             const char* a2 = last ? nA : cA + (size_t)(t + 2) * kstep; const char* b2 = last ? nB : cB + (size_t)(t + 2) * kstep;
;             const char* a3 = a2 + kstep; const char* b3 = b2 + kstep;
;             if (last && has_next) S.a_ready(nxt);
;             if constexpr (SP2) {
;             PG8_LDB(B0, 0, 0); PG8_LDB(B1, 0, 1); PG8_SCHED; PG8_LDA(At, 0, 0); PG8_STAGE(PG8_SA(1, 1), a1 + hstep, voffA);
;             PG8_WAIT_V(8); PG8_WAIT_L(0); PG8_BAR; PG8_MMA(0, 0, At, B0); PG8_MMA(0, 1, At, B1); PG8_BAR; PG8_SCHED;
;             PG8_LDA(At, 0, 1); PG8_STAGE(PG8_SB(0, 0), b2, voffB); PG8_STAGE(PG8_SB(0, 1), b2 + hstep, voffB); PG8_STAGE(PG8_SA(0, 0), a2, voffA);
;             PG8_WAIT_V(8); PG8_WAIT_L(0); PG8_BAR; PG8_MMA(1, 0, At, B0); PG8_MMA(1, 1, At, B1); PG8_BAR; PG8_SCHED;
;             PG8_LDB(B0, 1, 0); PG8_LDB(B1, 1, 1); PG8_SCHED; PG8_LDA(At, 1, 0); PG8_STAGE(PG8_SA(0, 1), a2 + hstep, voffA);
;             PG8_WAIT_V(8); PG8_WAIT_L(0); PG8_BAR; PG8_MMA(0, 0, At, B0); PG8_MMA(0, 1, At, B1); PG8_BAR; PG8_SCHED;
;             PG8_LDA(At, 1, 1); PG8_STAGE(PG8_SB(1, 0), b3, voffB); PG8_STAGE(PG8_SB(1, 1), b3 + hstep, voffB); PG8_STAGE(PG8_SA(1, 0), a3, voffA);
;             PG8_WAIT_V(8); PG8_WAIT_L(0); PG8_BAR; PG8_MMA(1, 0, At, B0); PG8_MMA(1, 1, At, B1); PG8_BAR; PG8_SCHED;
	s_add_i32 s3, s3, s43
	v_lshl_add_u64 v[160:161], v[160:161], 0, s[40:41]
	s_mov_b32 m0, s3
	ds_read_b128 v[190:193], v169 offset:49152
	ds_read_b128 v[194:197], v169 offset:50176
	ds_read_b128 v[198:201], v169 offset:51200
	ds_read_b128 v[208:211], v169 offset:52224
	ds_read_b128 v[212:215], v169 offset:53248
	ds_read_b128 v[216:219], v169 offset:54272
	ds_read_b128 v[220:223], v169 offset:55296
	ds_read_b128 v[224:227], v169 offset:56320
	global_load_lds_dwordx4 v[160:161], off
	s_add_i32 m0, s3, 0x2000
	s_add_u32 s10, s54, 0xb0080
	v_lshl_add_u64 v[160:161], v[202:203], 0, s[40:41]
	s_addc_u32 s11, s55, 0
	s_add_i32 s3, s14, s43
	global_load_lds_dwordx4 v[160:161], off
	v_lshl_add_u64 v[160:161], s[10:11], 0, v[138:139]
	s_mov_b32 m0, s3
	s_nop 0
	global_load_lds_dwordx4 v[160:161], off
	v_lshl_add_u64 v[160:161], s[10:11], 0, v[142:143]
	s_add_i32 m0, s3, 0x2000
	s_nop 0
	global_load_lds_dwordx4 v[160:161], off
	s_waitcnt vmcnt(6)
	s_waitcnt lgkmcnt(0)
	s_barrier
	s_setprio 1
	s_waitcnt lgkmcnt(0)
	v_mfma_f32_16x16x32_bf16 v[60:63], v[128:131], v[190:193], v[60:63]
	v_mfma_f32_16x16x32_bf16 v[56:59], v[152:155], v[190:193], v[56:59]
	v_mfma_f32_16x16x32_bf16 v[44:47], v[128:131], v[198:201], v[44:47]
	v_mfma_f32_16x16x32_bf16 v[40:43], v[152:155], v[198:201], v[40:43]
	v_mfma_f32_16x16x32_bf16 v[60:63], v[132:135], v[194:197], v[60:63]
	v_mfma_f32_16x16x32_bf16 v[56:59], v[156:159], v[194:197], v[56:59]
	v_mfma_f32_16x16x32_bf16 v[44:47], v[132:135], v[208:211], v[44:47]
	v_mfma_f32_16x16x32_bf16 v[40:43], v[156:159], v[208:211], v[40:43]
	v_mfma_f32_16x16x32_bf16 v[28:31], v[128:131], v[212:215], v[28:31]
	v_mfma_f32_16x16x32_bf16 v[24:27], v[152:155], v[212:215], v[24:27]
	v_mfma_f32_16x16x32_bf16 v[12:15], v[128:131], v[220:223], v[12:15]
	v_mfma_f32_16x16x32_bf16 v[8:11], v[152:155], v[220:223], v[8:11]
	v_mfma_f32_16x16x32_bf16 v[28:31], v[132:135], v[216:219], v[28:31]
	v_mfma_f32_16x16x32_bf16 v[24:27], v[156:159], v[216:219], v[24:27]
	v_lshl_add_u64 v[160:161], v[228:229], 0, s[40:41]
	s_mov_b32 m0, s63
	s_nop 0
	global_load_lds_dwordx4 v[160:161], off
	v_mfma_f32_16x16x32_bf16 v[12:15], v[132:135], v[224:227], v[12:15]
	v_mfma_f32_16x16x32_bf16 v[8:11], v[156:159], v[224:227], v[8:11]
	s_setprio 0
	s_setprio 1
	v_mfma_f32_16x16x32_bf16 v[52:55], v[172:175], v[190:193], v[52:55]
	v_mfma_f32_16x16x32_bf16 v[48:51], v[182:185], v[190:193], v[48:51]
	v_mfma_f32_16x16x32_bf16 v[36:39], v[172:175], v[198:201], v[36:39]
	v_mfma_f32_16x16x32_bf16 v[32:35], v[182:185], v[198:201], v[32:35]
	v_mfma_f32_16x16x32_bf16 v[52:55], v[176:179], v[194:197], v[52:55]
	v_mfma_f32_16x16x32_bf16 v[48:51], v[186:189], v[194:197], v[48:51]
	v_mfma_f32_16x16x32_bf16 v[36:39], v[176:179], v[208:211], v[36:39]
	v_mfma_f32_16x16x32_bf16 v[32:35], v[186:189], v[208:211], v[32:35]
	v_mfma_f32_16x16x32_bf16 v[20:23], v[172:175], v[212:215], v[20:23]
	v_mfma_f32_16x16x32_bf16 v[16:19], v[182:185], v[212:215], v[16:19]
	v_mfma_f32_16x16x32_bf16 v[4:7], v[172:175], v[220:223], v[4:7]
	v_mfma_f32_16x16x32_bf16 v[0:3], v[182:185], v[220:223], v[0:3]
	v_mfma_f32_16x16x32_bf16 v[20:23], v[176:179], v[216:219], v[20:23]
	v_mfma_f32_16x16x32_bf16 v[16:19], v[186:189], v[216:219], v[16:19]
	v_lshl_add_u64 v[160:161], v[230:231], 0, s[40:41]
	s_mov_b32 m0, s64
	s_nop 0
	global_load_lds_dwordx4 v[160:161], off
	v_mfma_f32_16x16x32_bf16 v[4:7], v[176:179], v[224:227], v[4:7]
	v_mfma_f32_16x16x32_bf16 v[0:3], v[186:189], v[224:227], v[0:3]
	s_setprio 0
	s_barrier
	s_add_i32 s93, s93, 2
	s_add_u32 s91, s91, 0x100
	s_addc_u32 s92, s92, 0
	s_mov_b64 s[10:11], s[50:51]
.LBB0_269:
	ds_read_b128 v[128:131], v165
	ds_read_b128 v[132:135], v165 offset:1024
	ds_read_b128 v[152:155], v165 offset:2048
	ds_read_b128 v[156:159], v165 offset:3072
	ds_read_b128 v[172:175], v168
	ds_read_b128 v[176:179], v168 offset:1024
	ds_read_b128 v[182:185], v168 offset:2048
	ds_read_b128 v[186:189], v168 offset:3072
	s_add_u32 s50, s10, 0x100
	s_addc_u32 s51, s11, 0
	s_cmp_eq_u32 s93, 40
	s_cselect_b32 s57, s1, s51
	s_cselect_b32 s56, s0, s50
	s_cselect_b32 s55, s49, s92
	s_cselect_b32 s54, s48, s91
	v_lshl_add_u64 v[160:161], s[10:11], 0, v[144:145]
	s_add_i32 m0, s58, 0xc000
	ds_read_b128 v[190:193], v169
	ds_read_b128 v[194:197], v169 offset:1024
	ds_read_b128 v[198:201], v169 offset:2048
	ds_read_b128 v[208:211], v169 offset:3072
	ds_read_b128 v[212:215], v169 offset:4096
	ds_read_b128 v[216:219], v169 offset:5120
	ds_read_b128 v[220:223], v169 offset:6144
	ds_read_b128 v[224:227], v169 offset:7168
	global_load_lds_dwordx4 v[160:161], off
	v_lshl_add_u64 v[160:161], s[10:11], 0, v[146:147]
	s_add_i32 m0, s58, 0xe000
	s_nop 0
	global_load_lds_dwordx4 v[160:161], off
	s_waitcnt vmcnt(8)
	s_waitcnt lgkmcnt(0)
	s_barrier
; #define PG8_STAGE(bufoff, gbase, voff) do { _Pragma("unroll") for (int _i = 0; _i < 2; ++_i) \
;         __builtin_amdgcn_global_load_lds((const unsigned*)((const char*)(gbase) + (voff)[_i]), (PG8_LAS unsigned*)(lds + (bufoff) + ldsw + _i * 8192), 16, 0, 0); } while (0)
; #define PG8_LDA(dst, b, h) do { _Pragma("unroll") for (int m = 0; m < 4; ++m) _Pragma("unroll") for (int k = 0; k < 2; ++k) dst[m][k] = *(const PG8_LAS bf16x8*)(lds + PG8_SA(b, h) + aoff + m * 2048 + k * 1024); } while (0)
; #define PG8_LDB(dst, b, h) do { _Pragma("unroll") for (int n = 0; n < 2; ++n) _Pragma("unroll") for (int k = 0; k < 2; ++k) dst[n][k] = *(const PG8_LAS bf16x8*)(lds + PG8_SB(b, h) + boff + n * 2048 + k * 1024); } while (0)
; #define PG8_MMA(ai, bj, At, Bt) do { __builtin_amdgcn_s_setprio(1); _Pragma("unroll") for (int m = 0; m < 4; ++m) _Pragma("unroll") for (int n = 0; n < 2; ++n) _Pragma("unroll") for (int k = 0; k < 2; ++k) \
;         acc[ai][bj][m][n] = __builtin_amdgcn_mfma_f32_16x16x32_bf16(Bt[n][k], At[m][k], acc[ai][bj][m][n], 0, 0, 0); __builtin_amdgcn_s_setprio(0); } while (0)
; #define PG8_WAIT_V(n) asm volatile("s_waitcnt vmcnt(" #n ")" ::: "memory")
; #define PG8_WAIT_L(n) asm volatile("s_waitcnt lgkmcnt(" #n ")" ::: "memory")
; #define PG8_BAR __builtin_amdgcn_s_barrier()
; #define PG8_SCHED __builtin_amdgcn_sched_barrier(0)
; template <class Epi, class Sched, bool ALIGN_EPI = false, bool SP2 = false>
; __device__ __forceinline__ void gemm_phase(PG8_LAS unsigned char* lds, const Gemm g, const Sched& S, const Epi& E) {
;     ...
;             PG8_LDB(B0, 0, 0); PG8_LDB(B1, 0, 1); PG8_SCHED; PG8_LDA(At, 0, 0); PG8_STAGE(PG8_SA(1, 1), a1 + hstep, voffA);
;             PG8_WAIT_V(8); PG8_WAIT_L(0); PG8_BAR; PG8_MMA(0, 0, At, B0); PG8_MMA(0, 1, At, B1); PG8_BAR; PG8_SCHED;
;             PG8_LDA(At, 0, 1); PG8_STAGE(PG8_SB(0, 0), b2, voffB); PG8_STAGE(PG8_SB(0, 1), b2 + hstep, voffB); PG8_STAGE(PG8_SA(0, 0), a2, voffA);
;             PG8_WAIT_V(8); PG8_WAIT_L(0); PG8_BAR; PG8_MMA(1, 0, At, B0); PG8_MMA(1, 1, At, B1); PG8_BAR; PG8_SCHED;
	s_setprio 1
	s_waitcnt lgkmcnt(0)
	v_mfma_f32_16x16x32_bf16 v[124:127], v[128:131], v[190:193], v[124:127]
	v_mfma_f32_16x16x32_bf16 v[120:123], v[152:155], v[190:193], v[120:123]
	v_mfma_f32_16x16x32_bf16 v[108:111], v[128:131], v[198:201], v[108:111]
	v_mfma_f32_16x16x32_bf16 v[104:107], v[152:155], v[198:201], v[104:107]
	v_mfma_f32_16x16x32_bf16 v[124:127], v[132:135], v[194:197], v[124:127]
	v_mfma_f32_16x16x32_bf16 v[120:123], v[156:159], v[194:197], v[120:123]
	v_mfma_f32_16x16x32_bf16 v[108:111], v[132:135], v[208:211], v[108:111]
	v_mfma_f32_16x16x32_bf16 v[104:107], v[156:159], v[208:211], v[104:107]
	v_mfma_f32_16x16x32_bf16 v[92:95], v[128:131], v[212:215], v[92:95]
	v_mfma_f32_16x16x32_bf16 v[88:91], v[152:155], v[212:215], v[88:91]
	v_mfma_f32_16x16x32_bf16 v[76:79], v[128:131], v[220:223], v[76:79]
	v_mfma_f32_16x16x32_bf16 v[72:75], v[152:155], v[220:223], v[72:75]
	v_mfma_f32_16x16x32_bf16 v[92:95], v[132:135], v[216:219], v[92:95]
	v_mfma_f32_16x16x32_bf16 v[88:91], v[156:159], v[216:219], v[88:91]
	v_mfma_f32_16x16x32_bf16 v[76:79], v[132:135], v[224:227], v[76:79]
	v_mfma_f32_16x16x32_bf16 v[72:75], v[156:159], v[224:227], v[72:75]
	s_setprio 0
	s_setprio 1
	v_mfma_f32_16x16x32_bf16 v[116:119], v[172:175], v[190:193], v[116:119]
	v_mfma_f32_16x16x32_bf16 v[112:115], v[182:185], v[190:193], v[112:115]
	v_mfma_f32_16x16x32_bf16 v[100:103], v[172:175], v[198:201], v[100:103]
	v_mfma_f32_16x16x32_bf16 v[96:99], v[182:185], v[198:201], v[96:99]
	v_mfma_f32_16x16x32_bf16 v[116:119], v[176:179], v[194:197], v[116:119]
	v_mfma_f32_16x16x32_bf16 v[112:115], v[186:189], v[194:197], v[112:115]
	v_mfma_f32_16x16x32_bf16 v[100:103], v[176:179], v[208:211], v[100:103]
	v_mfma_f32_16x16x32_bf16 v[96:99], v[186:189], v[208:211], v[96:99]
	v_mfma_f32_16x16x32_bf16 v[84:87], v[172:175], v[212:215], v[84:87]
	v_mfma_f32_16x16x32_bf16 v[80:83], v[182:185], v[212:215], v[80:83]
	v_mfma_f32_16x16x32_bf16 v[68:71], v[172:175], v[220:223], v[68:71]
	v_mfma_f32_16x16x32_bf16 v[64:67], v[182:185], v[220:223], v[64:67]
	v_mfma_f32_16x16x32_bf16 v[84:87], v[176:179], v[216:219], v[84:87]
	v_mfma_f32_16x16x32_bf16 v[80:83], v[186:189], v[216:219], v[80:83]
	v_mfma_f32_16x16x32_bf16 v[68:71], v[176:179], v[224:227], v[68:71]
	v_mfma_f32_16x16x32_bf16 v[64:67], v[186:189], v[224:227], v[64:67]
	s_setprio 0
	s_barrier
	s_add_i32 s3, s65, s43
	v_lshl_add_u64 v[160:161], s[54:55], 0, v[138:139]
	s_mov_b32 m0, s3
	ds_read_b128 v[190:193], v169 offset:16384
	ds_read_b128 v[194:197], v169 offset:17408
	ds_read_b128 v[198:201], v169 offset:18432
	ds_read_b128 v[208:211], v169 offset:19456
	ds_read_b128 v[212:215], v169 offset:20480
	ds_read_b128 v[216:219], v169 offset:21504
	ds_read_b128 v[220:223], v169 offset:22528
	ds_read_b128 v[224:227], v169 offset:23552
	global_load_lds_dwordx4 v[160:161], off
	s_add_i32 m0, s3, 0x2000
	s_add_u32 s10, s54, 0xb0000
	v_lshl_add_u64 v[202:203], s[54:55], 0, v[142:143]
	s_addc_u32 s11, s55, 0
	s_add_i32 s3, s66, s43
	global_load_lds_dwordx4 v[202:203], off
	v_lshl_add_u64 v[228:229], s[10:11], 0, v[138:139]
	s_mov_b32 m0, s3
	global_load_lds_dwordx4 v[228:229], off
	v_lshl_add_u64 v[228:229], s[10:11], 0, v[142:143]
	s_add_i32 m0, s3, 0x2000
	s_nop 0
	global_load_lds_dwordx4 v[228:229], off
	s_waitcnt vmcnt(6)
	s_waitcnt lgkmcnt(0)
	s_barrier
	s_setprio 1
	s_waitcnt lgkmcnt(0)
	v_mfma_f32_16x16x32_bf16 v[60:63], v[128:131], v[190:193], v[60:63]
	v_mfma_f32_16x16x32_bf16 v[56:59], v[152:155], v[190:193], v[56:59]
	v_mfma_f32_16x16x32_bf16 v[44:47], v[128:131], v[198:201], v[44:47]
	v_mfma_f32_16x16x32_bf16 v[40:43], v[152:155], v[198:201], v[40:43]
	v_mfma_f32_16x16x32_bf16 v[60:63], v[132:135], v[194:197], v[60:63]
	v_mfma_f32_16x16x32_bf16 v[56:59], v[156:159], v[194:197], v[56:59]
	v_mfma_f32_16x16x32_bf16 v[44:47], v[132:135], v[208:211], v[44:47]
	v_mfma_f32_16x16x32_bf16 v[40:43], v[156:159], v[208:211], v[40:43]
	v_mfma_f32_16x16x32_bf16 v[28:31], v[128:131], v[212:215], v[28:31]
	v_mfma_f32_16x16x32_bf16 v[24:27], v[152:155], v[212:215], v[24:27]
	v_mfma_f32_16x16x32_bf16 v[12:15], v[128:131], v[220:223], v[12:15]
	v_mfma_f32_16x16x32_bf16 v[8:11], v[152:155], v[220:223], v[8:11]
	v_mfma_f32_16x16x32_bf16 v[28:31], v[132:135], v[216:219], v[28:31]
	v_mfma_f32_16x16x32_bf16 v[24:27], v[156:159], v[216:219], v[24:27]
	v_lshl_add_u64 v[228:229], s[56:57], 0, v[136:137]
	s_mov_b32 m0, s58
	s_nop 0
	global_load_lds_dwordx4 v[228:229], off
	v_mfma_f32_16x16x32_bf16 v[12:15], v[132:135], v[224:227], v[12:15]
	v_mfma_f32_16x16x32_bf16 v[8:11], v[156:159], v[224:227], v[8:11]
	s_setprio 0
	s_setprio 1
	v_mfma_f32_16x16x32_bf16 v[52:55], v[172:175], v[190:193], v[52:55]
	v_mfma_f32_16x16x32_bf16 v[48:51], v[182:185], v[190:193], v[48:51]
	v_mfma_f32_16x16x32_bf16 v[36:39], v[172:175], v[198:201], v[36:39]
	v_mfma_f32_16x16x32_bf16 v[32:35], v[182:185], v[198:201], v[32:35]
	v_mfma_f32_16x16x32_bf16 v[52:55], v[176:179], v[194:197], v[52:55]
	v_mfma_f32_16x16x32_bf16 v[48:51], v[186:189], v[194:197], v[48:51]
	v_mfma_f32_16x16x32_bf16 v[36:39], v[176:179], v[208:211], v[36:39]
	v_mfma_f32_16x16x32_bf16 v[32:35], v[186:189], v[208:211], v[32:35]
	v_mfma_f32_16x16x32_bf16 v[20:23], v[172:175], v[212:215], v[20:23]
	v_mfma_f32_16x16x32_bf16 v[16:19], v[182:185], v[212:215], v[16:19]
	v_mfma_f32_16x16x32_bf16 v[4:7], v[172:175], v[220:223], v[4:7]
	v_mfma_f32_16x16x32_bf16 v[0:3], v[182:185], v[220:223], v[0:3]
	v_mfma_f32_16x16x32_bf16 v[20:23], v[176:179], v[216:219], v[20:23]
	v_mfma_f32_16x16x32_bf16 v[16:19], v[186:189], v[216:219], v[16:19]
	v_lshl_add_u64 v[230:231], s[56:57], 0, v[140:141]
	s_mov_b32 m0, s59
	s_nop 0
	global_load_lds_dwordx4 v[230:231], off
	v_mfma_f32_16x16x32_bf16 v[4:7], v[176:179], v[224:227], v[4:7]
	v_mfma_f32_16x16x32_bf16 v[0:3], v[186:189], v[224:227], v[0:3]
	s_setprio 0
	s_barrier
; #define PG8_STAGE(bufoff, gbase, voff) do { _Pragma("unroll") for (int _i = 0; _i < 2; ++_i) \
;         __builtin_amdgcn_global_load_lds((const unsigned*)((const char*)(gbase) + (voff)[_i]), (PG8_LAS unsigned*)(lds + (bufoff) + ldsw + _i * 8192), 16, 0, 0); } while (0)
; #define PG8_LDA(dst, b, h) do { _Pragma("unroll") for (int m = 0; m < 4; ++m) _Pragma("unroll") for (int k = 0; k < 2; ++k) dst[m][k] = *(const PG8_LAS bf16x8*)(lds + PG8_SA(b, h) + aoff + m * 2048 + k * 1024); } while (0)
; #define PG8_LDB(dst, b, h) do { _Pragma("unroll") for (int n = 0; n < 2; ++n) _Pragma("unroll") for (int k = 0; k < 2; ++k) dst[n][k] = *(const PG8_LAS bf16x8*)(lds + PG8_SB(b, h) + boff + n * 2048 + k * 1024); } while (0)
; #define PG8_MMA(ai, bj, At, Bt) do { __builtin_amdgcn_s_setprio(1); _Pragma("unroll") for (int m = 0; m < 4; ++m) _Pragma("unroll") for (int n = 0; n < 2; ++n) _Pragma("unroll") for (int k = 0; k < 2; ++k) \
;         acc[ai][bj][m][n] = __builtin_amdgcn_mfma_f32_16x16x32_bf16(Bt[n][k], At[m][k], acc[ai][bj][m][n], 0, 0, 0); __builtin_amdgcn_s_setprio(0); } while (0)
; #define PG8_WAIT_V(n) asm volatile("s_waitcnt vmcnt(" #n ")" ::: "memory")
; #define PG8_WAIT_L(n) asm volatile("s_waitcnt lgkmcnt(" #n ")" ::: "memory")
; #define PG8_BAR __builtin_amdgcn_s_barrier()
; #define PG8_SCHED __builtin_amdgcn_sched_barrier(0)
; template <class Epi, class Sched, bool ALIGN_EPI = false, bool SP2 = false>
; __device__ __forceinline__ void gemm_phase(PG8_LAS unsigned char* lds, const Gemm g, const Sched& S, const Epi& E) {
;     ...
;             PG8_LDB(B0, 1, 0); PG8_LDB(B1, 1, 1); PG8_SCHED; PG8_LDA(At, 1, 0); PG8_STAGE(PG8_SA(0, 1), a2 + hstep, voffA);
;             PG8_WAIT_V(8); PG8_WAIT_L(0); PG8_BAR; PG8_MMA(0, 0, At, B0); PG8_MMA(0, 1, At, B1); PG8_BAR; PG8_SCHED;
	s_add_i32 s3, 0, 0x18000
	s_add_i32 s14, 0, 0x1c000
	v_add_u32_e32 v156, s3, v163
	v_add_u32_e32 v171, s14, v163
	ds_read_b128 v[128:131], v156
	ds_read_b128 v[132:135], v156 offset:1024
	ds_read_b128 v[152:155], v156 offset:2048
	ds_read_b128 v[156:159], v156 offset:3072
	ds_read_b128 v[172:175], v171
	ds_read_b128 v[176:179], v171 offset:1024
	ds_read_b128 v[182:185], v171 offset:2048
	ds_read_b128 v[186:189], v171 offset:3072
	s_add_u32 s10, s56, 0xb0000
	s_addc_u32 s11, s57, 0
	s_mov_b32 m0, s60
	v_lshl_add_u64 v[232:233], s[10:11], 0, v[136:137]
	ds_read_b128 v[190:193], v169 offset:32768
	ds_read_b128 v[194:197], v169 offset:33792
	ds_read_b128 v[198:201], v169 offset:34816
	ds_read_b128 v[208:211], v169 offset:35840
	ds_read_b128 v[212:215], v169 offset:36864
	ds_read_b128 v[216:219], v169 offset:37888
	ds_read_b128 v[220:223], v169 offset:38912
	ds_read_b128 v[224:227], v169 offset:39936
	global_load_lds_dwordx4 v[232:233], off
	v_lshl_add_u64 v[232:233], s[10:11], 0, v[140:141]
	s_mov_b32 m0, s61
	s_nop 0
	global_load_lds_dwordx4 v[232:233], off
	s_waitcnt vmcnt(8)
	s_waitcnt lgkmcnt(0)
	s_barrier
	s_setprio 1
	s_waitcnt lgkmcnt(0)
	v_mfma_f32_16x16x32_bf16 v[124:127], v[128:131], v[190:193], v[124:127]
	v_mfma_f32_16x16x32_bf16 v[120:123], v[152:155], v[190:193], v[120:123]
	v_mfma_f32_16x16x32_bf16 v[108:111], v[128:131], v[198:201], v[108:111]
	v_mfma_f32_16x16x32_bf16 v[104:107], v[152:155], v[198:201], v[104:107]
	v_mfma_f32_16x16x32_bf16 v[124:127], v[132:135], v[194:197], v[124:127]
	v_mfma_f32_16x16x32_bf16 v[120:123], v[156:159], v[194:197], v[120:123]
	v_mfma_f32_16x16x32_bf16 v[108:111], v[132:135], v[208:211], v[108:111]
	v_mfma_f32_16x16x32_bf16 v[104:107], v[156:159], v[208:211], v[104:107]
	v_mfma_f32_16x16x32_bf16 v[92:95], v[128:131], v[212:215], v[92:95]
	v_mfma_f32_16x16x32_bf16 v[88:91], v[152:155], v[212:215], v[88:91]
	v_mfma_f32_16x16x32_bf16 v[76:79], v[128:131], v[220:223], v[76:79]
	v_mfma_f32_16x16x32_bf16 v[72:75], v[152:155], v[220:223], v[72:75]
	v_mfma_f32_16x16x32_bf16 v[92:95], v[132:135], v[216:219], v[92:95]
	v_mfma_f32_16x16x32_bf16 v[88:91], v[156:159], v[216:219], v[88:91]
	v_mfma_f32_16x16x32_bf16 v[76:79], v[132:135], v[224:227], v[76:79]
	v_mfma_f32_16x16x32_bf16 v[72:75], v[156:159], v[224:227], v[72:75]
	s_setprio 0
	s_setprio 1
	v_mfma_f32_16x16x32_bf16 v[116:119], v[172:175], v[190:193], v[116:119]
	v_mfma_f32_16x16x32_bf16 v[112:115], v[182:185], v[190:193], v[112:115]
	v_mfma_f32_16x16x32_bf16 v[100:103], v[172:175], v[198:201], v[100:103]
	v_mfma_f32_16x16x32_bf16 v[96:99], v[182:185], v[198:201], v[96:99]
	v_mfma_f32_16x16x32_bf16 v[116:119], v[176:179], v[194:197], v[116:119]
	v_mfma_f32_16x16x32_bf16 v[112:115], v[186:189], v[194:197], v[112:115]
	v_mfma_f32_16x16x32_bf16 v[100:103], v[176:179], v[208:211], v[100:103]
	v_mfma_f32_16x16x32_bf16 v[96:99], v[186:189], v[208:211], v[96:99]
	v_mfma_f32_16x16x32_bf16 v[84:87], v[172:175], v[212:215], v[84:87]
	v_mfma_f32_16x16x32_bf16 v[80:83], v[182:185], v[212:215], v[80:83]
	v_mfma_f32_16x16x32_bf16 v[68:71], v[172:175], v[220:223], v[68:71]
	v_mfma_f32_16x16x32_bf16 v[64:67], v[182:185], v[220:223], v[64:67]
	v_mfma_f32_16x16x32_bf16 v[84:87], v[176:179], v[216:219], v[84:87]
	v_mfma_f32_16x16x32_bf16 v[80:83], v[186:189], v[216:219], v[80:83]
	v_mfma_f32_16x16x32_bf16 v[68:71], v[176:179], v[224:227], v[68:71]
	v_mfma_f32_16x16x32_bf16 v[64:67], v[186:189], v[224:227], v[64:67]
	s_setprio 0
	s_barrier
; #define PG8_STAGE(bufoff, gbase, voff) do { _Pragma("unroll") for (int _i = 0; _i < 2; ++_i) \
;         __builtin_amdgcn_global_load_lds((const unsigned*)((const char*)(gbase) + (voff)[_i]), (PG8_LAS unsigned*)(lds + (bufoff) + ldsw + _i * 8192), 16, 0, 0); } while (0)
; #define PG8_WAIT_V(n) asm volatile("s_waitcnt vmcnt(" #n ")" ::: "memory")
; #define PG8_WAIT_L(n) asm volatile("s_waitcnt lgkmcnt(" #n ")" ::: "memory")
; template <class Epi, class Sched, bool ALIGN_EPI = false, bool SP2 = false>
; __device__ __forceinline__ void gemm_phase(PG8_LAS unsigned char* lds, const Gemm g, const Sched& S, const Epi& E) {
;     ...
;             PG8_LDA(At, 1, 1); PG8_STAGE(PG8_SB(1, 0), b3, voffB); PG8_STAGE(PG8_SB(1, 1), b3 + hstep, voffB); PG8_STAGE(PG8_SA(1, 0), a3, voffA);
;             PG8_WAIT_V(8); PG8_WAIT_L(0); PG8_BAR; PG8_MMA(1, 0, At, B0); PG8_MMA(1, 1, At, B1); PG8_BAR; PG8_SCHED;
;             } else {
;             PG8_LDB(B0, 0, 0); PG8_SCHED; PG8_LDA(At, 0, 0); PG8_STAGE(PG8_SA(1, 1), a1 + hstep, voffA);
;             PG8_WAIT_L(8); PG8_BAR; PG8_WAIT_L(0); PG8_MMA(0, 0, At, B0); PG8_BAR; PG8_SCHED;
;             PG8_LDB(B1, 0, 1); PG8_STAGE(PG8_SB(0, 0), b2, voffB);
;             PG8_BAR; PG8_WAIT_L(0); PG8_MMA(0, 1, At, B1); PG8_BAR;
;             PG8_LDA(At, 0, 1); PG8_STAGE(PG8_SA(0, 0), a2, voffA);
;             PG8_BAR; PG8_WAIT_L(0); PG8_MMA(1, 0, At, B0); PG8_BAR; PG8_SCHED;
;             PG8_STAGE(PG8_SB(0, 1), b2 + hstep, voffB);
;             PG8_WAIT_V(6); PG8_BAR; PG8_MMA(1, 1, At, B1); PG8_BAR;
;             PG8_LDB(B0, 1, 0); PG8_SCHED; PG8_LDA(At, 1, 0); PG8_STAGE(PG8_SA(0, 1), a2 + hstep, voffA);
;             PG8_WAIT_L(8); PG8_BAR; PG8_WAIT_L(0); PG8_MMA(0, 0, At, B0); PG8_BAR; PG8_SCHED;
;             PG8_LDB(B1, 1, 1); PG8_STAGE(PG8_SB(1, 0), b3, voffB);
;             PG8_BAR; PG8_WAIT_L(0); PG8_MMA(0, 1, At, B1); PG8_BAR;
;             PG8_LDA(At, 1, 1); PG8_STAGE(PG8_SA(1, 0), a3, voffA);
;             PG8_BAR; PG8_WAIT_L(0); PG8_MMA(1, 0, At, B0); PG8_BAR; PG8_SCHED;
;             PG8_STAGE(PG8_SB(1, 1), b3 + hstep, voffB);
;             PG8_WAIT_V(6); PG8_BAR; PG8_MMA(1, 1, At, B1); PG8_BAR;
;             }
;         }
;         if constexpr (ALIGN_EPI) { if (wr == 0) PG8_BAR; }
;         if constexpr (!Epi::AFTER_DRAIN) { E(acc, cur, wr, wc, fr, fq); S.done(cur); }
;         if (!has_next) break;
	s_add_i32 s3, s3, s43
	v_lshl_add_u64 v[160:161], v[160:161], 0, s[40:41]
	s_mov_b32 m0, s3
	ds_read_b128 v[190:193], v169 offset:49152
	ds_read_b128 v[194:197], v169 offset:50176
	ds_read_b128 v[198:201], v169 offset:51200
	ds_read_b128 v[208:211], v169 offset:52224
	ds_read_b128 v[212:215], v169 offset:53248
	ds_read_b128 v[216:219], v169 offset:54272
	ds_read_b128 v[220:223], v169 offset:55296
	ds_read_b128 v[224:227], v169 offset:56320
	global_load_lds_dwordx4 v[160:161], off
	s_add_i32 m0, s3, 0x2000
	s_add_u32 s10, s54, 0xb0080
	v_lshl_add_u64 v[160:161], v[202:203], 0, s[40:41]
	s_addc_u32 s11, s55, 0
	s_add_i32 s3, s14, s43
	global_load_lds_dwordx4 v[160:161], off
	v_lshl_add_u64 v[160:161], s[10:11], 0, v[138:139]
	s_mov_b32 m0, s3
	s_nop 0
	global_load_lds_dwordx4 v[160:161], off
	v_lshl_add_u64 v[160:161], s[10:11], 0, v[142:143]
	s_add_i32 m0, s3, 0x2000
	s_nop 0
	global_load_lds_dwordx4 v[160:161], off
	s_waitcnt vmcnt(6)
	s_waitcnt lgkmcnt(0)
	s_barrier
	s_setprio 1
	s_waitcnt lgkmcnt(0)
	v_mfma_f32_16x16x32_bf16 v[60:63], v[128:131], v[190:193], v[60:63]
	v_mfma_f32_16x16x32_bf16 v[56:59], v[152:155], v[190:193], v[56:59]
	v_mfma_f32_16x16x32_bf16 v[44:47], v[128:131], v[198:201], v[44:47]
	v_mfma_f32_16x16x32_bf16 v[40:43], v[152:155], v[198:201], v[40:43]
	v_mfma_f32_16x16x32_bf16 v[60:63], v[132:135], v[194:197], v[60:63]
	v_mfma_f32_16x16x32_bf16 v[56:59], v[156:159], v[194:197], v[56:59]
	v_mfma_f32_16x16x32_bf16 v[44:47], v[132:135], v[208:211], v[44:47]
	v_mfma_f32_16x16x32_bf16 v[40:43], v[156:159], v[208:211], v[40:43]
	v_mfma_f32_16x16x32_bf16 v[28:31], v[128:131], v[212:215], v[28:31]
	v_mfma_f32_16x16x32_bf16 v[24:27], v[152:155], v[212:215], v[24:27]
	v_mfma_f32_16x16x32_bf16 v[12:15], v[128:131], v[220:223], v[12:15]
	v_mfma_f32_16x16x32_bf16 v[8:11], v[152:155], v[220:223], v[8:11]
	v_mfma_f32_16x16x32_bf16 v[28:31], v[132:135], v[216:219], v[28:31]
	v_mfma_f32_16x16x32_bf16 v[24:27], v[156:159], v[216:219], v[24:27]
	v_lshl_add_u64 v[160:161], v[228:229], 0, s[40:41]
	s_mov_b32 m0, s63
	s_nop 0
	global_load_lds_dwordx4 v[160:161], off
	v_mfma_f32_16x16x32_bf16 v[12:15], v[132:135], v[224:227], v[12:15]
	v_mfma_f32_16x16x32_bf16 v[8:11], v[156:159], v[224:227], v[8:11]
	s_setprio 0
	s_setprio 1
	v_mfma_f32_16x16x32_bf16 v[52:55], v[172:175], v[190:193], v[52:55]
	v_mfma_f32_16x16x32_bf16 v[48:51], v[182:185], v[190:193], v[48:51]
	v_mfma_f32_16x16x32_bf16 v[36:39], v[172:175], v[198:201], v[36:39]
	v_mfma_f32_16x16x32_bf16 v[32:35], v[182:185], v[198:201], v[32:35]
	v_mfma_f32_16x16x32_bf16 v[52:55], v[176:179], v[194:197], v[52:55]
	v_mfma_f32_16x16x32_bf16 v[48:51], v[186:189], v[194:197], v[48:51]
	v_mfma_f32_16x16x32_bf16 v[36:39], v[176:179], v[208:211], v[36:39]
	v_mfma_f32_16x16x32_bf16 v[32:35], v[186:189], v[208:211], v[32:35]
	v_mfma_f32_16x16x32_bf16 v[20:23], v[172:175], v[212:215], v[20:23]
	v_mfma_f32_16x16x32_bf16 v[16:19], v[182:185], v[212:215], v[16:19]
	v_mfma_f32_16x16x32_bf16 v[4:7], v[172:175], v[220:223], v[4:7]
	v_mfma_f32_16x16x32_bf16 v[0:3], v[182:185], v[220:223], v[0:3]
	v_mfma_f32_16x16x32_bf16 v[20:23], v[176:179], v[216:219], v[20:23]
	v_mfma_f32_16x16x32_bf16 v[16:19], v[186:189], v[216:219], v[16:19]
	v_lshl_add_u64 v[160:161], v[230:231], 0, s[40:41]
	s_mov_b32 m0, s64
	s_nop 0
	global_load_lds_dwordx4 v[160:161], off
	v_mfma_f32_16x16x32_bf16 v[4:7], v[176:179], v[224:227], v[4:7]
	v_mfma_f32_16x16x32_bf16 v[0:3], v[186:189], v[224:227], v[0:3]
	s_setprio 0
	s_barrier
	s_add_i32 s93, s93, 2
	s_add_u32 s91, s91, 0x100
	s_addc_u32 s92, s92, 0
	s_cmp_gt_u32 s93, 41
	s_mov_b64 s[10:11], s[50:51]
	s_cbranch_scc0 .LBB0_269
	s_and_b64 vcc, exec, s[44:45]
	s_cbranch_vccz .LBB0_272
	s_barrier

; #define PG8_STAGE(bufoff, gbase, voff) do { _Pragma("unroll") for (int _i = 0; _i < 2; ++_i) \
;         __builtin_amdgcn_global_load_lds((const unsigned*)((const char*)(gbase) + (voff)[_i]), (PG8_LAS unsigned*)(lds + (bufoff) + ldsw + _i * 8192), 16, 0, 0); } while (0)
; #define PG8_LDA(dst, b, h) do { _Pragma("unroll") for (int m = 0; m < 4; ++m) _Pragma("unroll") for (int k = 0; k < 2; ++k) dst[m][k] = *(const PG8_LAS bf16x8*)(lds + PG8_SA(b, h) + aoff + m * 2048 + k * 1024); } while (0)
; #define PG8_LDB(dst, b, h) do { _Pragma("unroll") for (int n = 0; n < 2; ++n) _Pragma("unroll") for (int k = 0; k < 2; ++k) dst[n][k] = *(const PG8_LAS bf16x8*)(lds + PG8_SB(b, h) + boff + n * 2048 + k * 1024); } while (0)
; #define PG8_WAIT_V(n) asm volatile("s_waitcnt vmcnt(" #n ")" ::: "memory")
; #define PG8_WAIT_L(n) asm volatile("s_waitcnt lgkmcnt(" #n ")" ::: "memory")
; #define PG8_BAR __builtin_amdgcn_s_barrier()
; #define PG8_SCHED __builtin_amdgcn_sched_barrier(0)
; template <class Epi, class Sched, bool ALIGN_EPI = false, bool SP2 = false>
; __device__ __forceinline__ void gemm_phase(PG8_LAS unsigned char* lds, const Gemm g, const Sched& S, const Epi& E) {
;     ...
;         const bool has_next = S.next(ui + 1, nxt);
;         const char* nA = has_next ? (const char*)g.A + (size_t)nxt.pm * tstep : cA; const char* nB = has_next ? (const char*)g.Bt + (size_t)nxt.pn * tstep : cB;
;         for (int t = 0; t < nt; t += 2) {
;             const bool last = (t == nt - 2);
;             const char* a1 = cA + (size_t)(t + 1) * kstep;
;             const char* a2 = last ? nA : cA + (size_t)(t + 2) * kstep; const char* b2 = last ? nB : cB + (size_t)(t + 2) * kstep;
;             const char* a3 = a2 + kstep; const char* b3 = b2 + kstep;
;             if (last && has_next) S.a_ready(nxt);
;             if constexpr (SP2) {
;             PG8_LDB(B0, 0, 0); PG8_LDB(B1, 0, 1); PG8_SCHED; PG8_LDA(At, 0, 0); PG8_STAGE(PG8_SA(1, 1), a1 + hstep, voffA);
;             PG8_WAIT_V(8); PG8_WAIT_L(0); PG8_BAR; PG8_MMA(0, 0, At, B0); PG8_MMA(0, 1, At, B1); PG8_BAR; PG8_SCHED;
;             PG8_LDA(At, 0, 1); PG8_STAGE(PG8_SB(0, 0), b2, voffB); PG8_STAGE(PG8_SB(0, 1), b2 + hstep, voffB); PG8_STAGE(PG8_SA(0, 0), a2, voffA);
;             PG8_WAIT_V(8); PG8_WAIT_L(0); PG8_BAR; PG8_MMA(1, 0, At, B0); PG8_MMA(1, 1, At, B1); PG8_BAR; PG8_SCHED;
.LBB0_416:
	s_ashr_i32 s45, s44, 31
	s_lshl_b64 s[14:15], s[44:45], 19
	s_add_u32 s48, s22, s14
	s_addc_u32 s49, s23, s15
	s_and_b64 s[14:15], s[6:7], exec
	s_cselect_b32 s45, s49, s55
	s_cselect_b32 s89, s48, s54
	s_ashr_i32 s41, s40, 31
	s_lshl_b64 s[14:15], s[40:41], 19
	s_add_u32 s50, s84, s14
	s_addc_u32 s51, s85, s15
	s_and_b64 s[14:15], s[6:7], exec
	s_cselect_b32 s41, s51, s57
	s_cselect_b32 s90, s50, s56
	s_add_u32 s54, s54, 0x40080
	s_addc_u32 s55, s55, 0
	s_add_u32 s91, s56, 0x100
	s_addc_u32 s92, s57, 0
	s_mov_b32 s93, -2
	ds_read_b128 v[154:157], v169
	ds_read_b128 v[158:161], v169 offset:1024
	ds_read_b128 v[162:165], v169 offset:2048
	ds_read_b128 v[174:177], v169 offset:3072
	ds_read_b128 v[182:185], v170
	ds_read_b128 v[186:189], v170 offset:1024
	ds_read_b128 v[190:193], v170 offset:2048
	ds_read_b128 v[194:197], v170 offset:3072
	s_add_u32 s3, s54, 0xfffc0080
	s_addc_u32 s14, s55, -1
	s_cmp_eq_u32 s93, 12
	s_cselect_b32 s59, s45, s14
	s_cselect_b32 s58, s89, s3
	s_cselect_b32 s57, s41, s92
	s_cselect_b32 s56, s90, s91
	v_lshl_add_u64 v[178:179], s[54:55], 0, v[146:147]
	s_add_i32 m0, s60, 0xc000
	ds_read_b128 v[198:201], v171
	ds_read_b128 v[208:211], v171 offset:1024
	ds_read_b128 v[212:215], v171 offset:2048
	ds_read_b128 v[216:219], v171 offset:3072
	ds_read_b128 v[220:223], v171 offset:4096
	ds_read_b128 v[224:227], v171 offset:5120
	ds_read_b128 v[228:231], v171 offset:6144
	ds_read_b128 v[232:235], v171 offset:7168
	global_load_lds_dwordx4 v[178:179], off
	v_lshl_add_u64 v[178:179], s[54:55], 0, v[148:149]
	s_add_i32 m0, s60, 0xe000
	s_nop 0
	global_load_lds_dwordx4 v[178:179], off
	s_waitcnt vmcnt(8)
	s_waitcnt lgkmcnt(0)
	s_barrier
	s_setprio 1
	s_waitcnt lgkmcnt(0)
	v_mfma_f32_16x16x32_bf16 v[124:127], v[154:157], v[198:201], 0
	v_mfma_f32_16x16x32_bf16 v[120:123], v[162:165], v[198:201], 0
	v_mfma_f32_16x16x32_bf16 v[116:119], v[154:157], v[212:215], 0
	v_mfma_f32_16x16x32_bf16 v[112:115], v[162:165], v[212:215], 0
	v_mfma_f32_16x16x32_bf16 v[124:127], v[158:161], v[208:211], v[124:127]
	v_mfma_f32_16x16x32_bf16 v[120:123], v[174:177], v[208:211], v[120:123]
	v_mfma_f32_16x16x32_bf16 v[116:119], v[158:161], v[216:219], v[116:119]
	v_mfma_f32_16x16x32_bf16 v[112:115], v[174:177], v[216:219], v[112:115]
	v_mfma_f32_16x16x32_bf16 v[108:111], v[154:157], v[220:223], 0
	v_mfma_f32_16x16x32_bf16 v[104:107], v[162:165], v[220:223], 0
	v_mfma_f32_16x16x32_bf16 v[100:103], v[154:157], v[228:231], 0
	v_mfma_f32_16x16x32_bf16 v[96:99], v[162:165], v[228:231], 0
	v_mfma_f32_16x16x32_bf16 v[108:111], v[158:161], v[224:227], v[108:111]
	v_mfma_f32_16x16x32_bf16 v[104:107], v[174:177], v[224:227], v[104:107]
	v_mfma_f32_16x16x32_bf16 v[100:103], v[158:161], v[232:235], v[100:103]
	v_mfma_f32_16x16x32_bf16 v[96:99], v[174:177], v[232:235], v[96:99]
	s_setprio 0
	s_setprio 1
	v_mfma_f32_16x16x32_bf16 v[68:71], v[182:185], v[198:201], 0
	v_mfma_f32_16x16x32_bf16 v[64:67], v[190:193], v[198:201], 0
	v_mfma_f32_16x16x32_bf16 v[52:55], v[182:185], v[212:215], 0
	v_mfma_f32_16x16x32_bf16 v[48:51], v[190:193], v[212:215], 0
	v_mfma_f32_16x16x32_bf16 v[68:71], v[186:189], v[208:211], v[68:71]
	v_mfma_f32_16x16x32_bf16 v[64:67], v[194:197], v[208:211], v[64:67]
	v_mfma_f32_16x16x32_bf16 v[52:55], v[186:189], v[216:219], v[52:55]
	v_mfma_f32_16x16x32_bf16 v[48:51], v[194:197], v[216:219], v[48:51]
	v_mfma_f32_16x16x32_bf16 v[44:47], v[182:185], v[220:223], 0
	v_mfma_f32_16x16x32_bf16 v[40:43], v[190:193], v[220:223], 0
	v_mfma_f32_16x16x32_bf16 v[36:39], v[182:185], v[228:231], 0
	v_mfma_f32_16x16x32_bf16 v[32:35], v[190:193], v[228:231], 0
	v_mfma_f32_16x16x32_bf16 v[44:47], v[186:189], v[224:227], v[44:47]
	v_mfma_f32_16x16x32_bf16 v[40:43], v[194:197], v[224:227], v[40:43]
	v_mfma_f32_16x16x32_bf16 v[36:39], v[186:189], v[232:235], v[36:39]
	v_mfma_f32_16x16x32_bf16 v[32:35], v[194:197], v[232:235], v[32:35]
	s_setprio 0
	s_barrier
	s_add_i32 s3, s86, s34
	v_lshl_add_u64 v[178:179], s[56:57], 0, v[132:133]
	s_mov_b32 m0, s3
	ds_read_b128 v[198:201], v171 offset:16384
	ds_read_b128 v[208:211], v171 offset:17408
	ds_read_b128 v[212:215], v171 offset:18432
	ds_read_b128 v[216:219], v171 offset:19456
	ds_read_b128 v[220:223], v171 offset:20480
	ds_read_b128 v[224:227], v171 offset:21504
	ds_read_b128 v[228:231], v171 offset:22528
	ds_read_b128 v[232:235], v171 offset:23552
	global_load_lds_dwordx4 v[178:179], off
	s_add_i32 m0, s3, 0x2000
	s_add_u32 s14, s56, 0x40000
	v_lshl_add_u64 v[202:203], s[56:57], 0, v[128:129]
	s_addc_u32 s15, s57, 0
	s_add_i32 s3, s87, s34
	global_load_lds_dwordx4 v[202:203], off
	v_lshl_add_u64 v[236:237], s[14:15], 0, v[132:133]
	s_mov_b32 m0, s3
	global_load_lds_dwordx4 v[236:237], off
	v_lshl_add_u64 v[236:237], s[14:15], 0, v[128:129]
	s_add_i32 m0, s3, 0x2000
	s_nop 0
	global_load_lds_dwordx4 v[236:237], off
	s_waitcnt vmcnt(6)
	s_waitcnt lgkmcnt(0)
	s_barrier
; #define PG8_STAGE(bufoff, gbase, voff) do { _Pragma("unroll") for (int _i = 0; _i < 2; ++_i) \
;         __builtin_amdgcn_global_load_lds((const unsigned*)((const char*)(gbase) + (voff)[_i]), (PG8_LAS unsigned*)(lds + (bufoff) + ldsw + _i * 8192), 16, 0, 0); } while (0)
; #define PG8_LDA(dst, b, h) do { _Pragma("unroll") for (int m = 0; m < 4; ++m) _Pragma("unroll") for (int k = 0; k < 2; ++k) dst[m][k] = *(const PG8_LAS bf16x8*)(lds + PG8_SA(b, h) + aoff + m * 2048 + k * 1024); } while (0)
; #define PG8_LDB(dst, b, h) do { _Pragma("unroll") for (int n = 0; n < 2; ++n) _Pragma("unroll") for (int k = 0; k < 2; ++k) dst[n][k] = *(const PG8_LAS bf16x8*)(lds + PG8_SB(b, h) + boff + n * 2048 + k * 1024); } while (0)
; #define PG8_MMA(ai, bj, At, Bt) do { __builtin_amdgcn_s_setprio(1); _Pragma("unroll") for (int m = 0; m < 4; ++m) _Pragma("unroll") for (int n = 0; n < 2; ++n) _Pragma("unroll") for (int k = 0; k < 2; ++k) \
;         acc[ai][bj][m][n] = __builtin_amdgcn_mfma_f32_16x16x32_bf16(Bt[n][k], At[m][k], acc[ai][bj][m][n], 0, 0, 0); __builtin_amdgcn_s_setprio(0); } while (0)
; #define PG8_WAIT_V(n) asm volatile("s_waitcnt vmcnt(" #n ")" ::: "memory")
; #define PG8_WAIT_L(n) asm volatile("s_waitcnt lgkmcnt(" #n ")" ::: "memory")
; #define PG8_BAR __builtin_amdgcn_s_barrier()
; #define PG8_SCHED __builtin_amdgcn_sched_barrier(0)
; template <class Epi, class Sched, bool ALIGN_EPI = false, bool SP2 = false>
; __device__ __forceinline__ void gemm_phase(PG8_LAS unsigned char* lds, const Gemm g, const Sched& S, const Epi& E) {
;     ...
;             PG8_WAIT_V(8); PG8_WAIT_L(0); PG8_BAR; PG8_MMA(0, 0, At, B0); PG8_MMA(0, 1, At, B1); PG8_BAR; PG8_SCHED;
;             PG8_LDA(At, 0, 1); PG8_STAGE(PG8_SB(0, 0), b2, voffB); PG8_STAGE(PG8_SB(0, 1), b2 + hstep, voffB); PG8_STAGE(PG8_SA(0, 0), a2, voffA);
;             PG8_WAIT_V(8); PG8_WAIT_L(0); PG8_BAR; PG8_MMA(1, 0, At, B0); PG8_MMA(1, 1, At, B1); PG8_BAR; PG8_SCHED;
;             PG8_LDB(B0, 1, 0); PG8_LDB(B1, 1, 1); PG8_SCHED; PG8_LDA(At, 1, 0); PG8_STAGE(PG8_SA(0, 1), a2 + hstep, voffA);
;             PG8_WAIT_V(8); PG8_WAIT_L(0); PG8_BAR; PG8_MMA(0, 0, At, B0); PG8_MMA(0, 1, At, B1); PG8_BAR; PG8_SCHED;
	s_setprio 1
	s_waitcnt lgkmcnt(0)
	v_mfma_f32_16x16x32_bf16 v[92:95], v[154:157], v[198:201], 0
	v_mfma_f32_16x16x32_bf16 v[88:91], v[162:165], v[198:201], 0
	v_mfma_f32_16x16x32_bf16 v[84:87], v[154:157], v[212:215], 0
	v_mfma_f32_16x16x32_bf16 v[80:83], v[162:165], v[212:215], 0
	v_mfma_f32_16x16x32_bf16 v[92:95], v[158:161], v[208:211], v[92:95]
	v_mfma_f32_16x16x32_bf16 v[88:91], v[174:177], v[208:211], v[88:91]
	v_mfma_f32_16x16x32_bf16 v[84:87], v[158:161], v[216:219], v[84:87]
	v_mfma_f32_16x16x32_bf16 v[80:83], v[174:177], v[216:219], v[80:83]
	v_mfma_f32_16x16x32_bf16 v[76:79], v[154:157], v[220:223], 0
	v_mfma_f32_16x16x32_bf16 v[72:75], v[162:165], v[220:223], 0
	v_mfma_f32_16x16x32_bf16 v[60:63], v[154:157], v[228:231], 0
	v_mfma_f32_16x16x32_bf16 v[56:59], v[162:165], v[228:231], 0
	v_mfma_f32_16x16x32_bf16 v[76:79], v[158:161], v[224:227], v[76:79]
	v_mfma_f32_16x16x32_bf16 v[72:75], v[174:177], v[224:227], v[72:75]
	v_lshl_add_u64 v[236:237], s[58:59], 0, v[134:135]
	s_mov_b32 m0, s60
	s_nop 0
	global_load_lds_dwordx4 v[236:237], off
	v_mfma_f32_16x16x32_bf16 v[60:63], v[158:161], v[232:235], v[60:63]
	v_mfma_f32_16x16x32_bf16 v[56:59], v[174:177], v[232:235], v[56:59]
	s_setprio 0
	s_setprio 1
	v_mfma_f32_16x16x32_bf16 v[28:31], v[182:185], v[198:201], 0
	v_mfma_f32_16x16x32_bf16 v[24:27], v[190:193], v[198:201], 0
	v_mfma_f32_16x16x32_bf16 v[20:23], v[182:185], v[212:215], 0
	v_mfma_f32_16x16x32_bf16 v[16:19], v[190:193], v[212:215], 0
	v_mfma_f32_16x16x32_bf16 v[28:31], v[186:189], v[208:211], v[28:31]
	v_mfma_f32_16x16x32_bf16 v[24:27], v[194:197], v[208:211], v[24:27]
	v_mfma_f32_16x16x32_bf16 v[20:23], v[186:189], v[216:219], v[20:23]
	v_mfma_f32_16x16x32_bf16 v[16:19], v[194:197], v[216:219], v[16:19]
	v_mfma_f32_16x16x32_bf16 v[12:15], v[182:185], v[220:223], 0
	v_mfma_f32_16x16x32_bf16 v[8:11], v[190:193], v[220:223], 0
	v_mfma_f32_16x16x32_bf16 v[4:7], v[182:185], v[228:231], 0
	v_mfma_f32_16x16x32_bf16 v[0:3], v[190:193], v[228:231], 0
	v_mfma_f32_16x16x32_bf16 v[12:15], v[186:189], v[224:227], v[12:15]
	v_mfma_f32_16x16x32_bf16 v[8:11], v[194:197], v[224:227], v[8:11]
	v_lshl_add_u64 v[238:239], s[58:59], 0, v[130:131]
	s_mov_b32 m0, s61
	s_nop 0
	global_load_lds_dwordx4 v[238:239], off
	v_mfma_f32_16x16x32_bf16 v[4:7], v[186:189], v[232:235], v[4:7]
	v_mfma_f32_16x16x32_bf16 v[0:3], v[194:197], v[232:235], v[0:3]
	s_setprio 0
	s_barrier
	s_add_i32 s3, 0, 0x18000
	v_add_u32_e32 v136, s3, v143
	s_add_i32 s33, 0, 0x1c000
	ds_read_b128 v[154:157], v136
	ds_read_b128 v[158:161], v136 offset:1024
	ds_read_b128 v[162:165], v136 offset:2048
	ds_read_b128 v[174:177], v136 offset:3072
	v_add_u32_e32 v136, s33, v143
	ds_read_b128 v[182:185], v136
	ds_read_b128 v[186:189], v136 offset:1024
	ds_read_b128 v[190:193], v136 offset:2048
	ds_read_b128 v[194:197], v136 offset:3072
	s_add_u32 s14, s58, 0x40000
	s_addc_u32 s15, s59, 0
	s_mov_b32 m0, s62
	v_lshl_add_u64 v[240:241], s[14:15], 0, v[134:135]
	ds_read_b128 v[198:201], v171 offset:32768
	ds_read_b128 v[208:211], v171 offset:33792
	ds_read_b128 v[212:215], v171 offset:34816
	ds_read_b128 v[216:219], v171 offset:35840
	ds_read_b128 v[220:223], v171 offset:36864
	ds_read_b128 v[224:227], v171 offset:37888
	ds_read_b128 v[228:231], v171 offset:38912
	ds_read_b128 v[232:235], v171 offset:39936
	global_load_lds_dwordx4 v[240:241], off
	v_lshl_add_u64 v[240:241], s[14:15], 0, v[130:131]
	s_mov_b32 m0, s63
	s_nop 0
	global_load_lds_dwordx4 v[240:241], off
	s_waitcnt vmcnt(8)
	s_waitcnt lgkmcnt(0)
	s_barrier
	s_setprio 1
	s_waitcnt lgkmcnt(0)
	v_mfma_f32_16x16x32_bf16 v[124:127], v[154:157], v[198:201], v[124:127]
	v_mfma_f32_16x16x32_bf16 v[120:123], v[162:165], v[198:201], v[120:123]
	v_mfma_f32_16x16x32_bf16 v[116:119], v[154:157], v[212:215], v[116:119]
	v_mfma_f32_16x16x32_bf16 v[112:115], v[162:165], v[212:215], v[112:115]
	v_mfma_f32_16x16x32_bf16 v[124:127], v[158:161], v[208:211], v[124:127]
	v_mfma_f32_16x16x32_bf16 v[120:123], v[174:177], v[208:211], v[120:123]
	v_mfma_f32_16x16x32_bf16 v[116:119], v[158:161], v[216:219], v[116:119]
	v_mfma_f32_16x16x32_bf16 v[112:115], v[174:177], v[216:219], v[112:115]
	v_mfma_f32_16x16x32_bf16 v[108:111], v[154:157], v[220:223], v[108:111]
	v_mfma_f32_16x16x32_bf16 v[104:107], v[162:165], v[220:223], v[104:107]
	v_mfma_f32_16x16x32_bf16 v[100:103], v[154:157], v[228:231], v[100:103]
	v_mfma_f32_16x16x32_bf16 v[96:99], v[162:165], v[228:231], v[96:99]
	v_mfma_f32_16x16x32_bf16 v[108:111], v[158:161], v[224:227], v[108:111]
	v_mfma_f32_16x16x32_bf16 v[104:107], v[174:177], v[224:227], v[104:107]
	v_mfma_f32_16x16x32_bf16 v[100:103], v[158:161], v[232:235], v[100:103]
	v_mfma_f32_16x16x32_bf16 v[96:99], v[174:177], v[232:235], v[96:99]
	s_setprio 0
	s_setprio 1
	v_mfma_f32_16x16x32_bf16 v[68:71], v[182:185], v[198:201], v[68:71]
	v_mfma_f32_16x16x32_bf16 v[64:67], v[190:193], v[198:201], v[64:67]
	v_mfma_f32_16x16x32_bf16 v[52:55], v[182:185], v[212:215], v[52:55]
	v_mfma_f32_16x16x32_bf16 v[48:51], v[190:193], v[212:215], v[48:51]
	v_mfma_f32_16x16x32_bf16 v[68:71], v[186:189], v[208:211], v[68:71]
	v_mfma_f32_16x16x32_bf16 v[64:67], v[194:197], v[208:211], v[64:67]
	v_mfma_f32_16x16x32_bf16 v[52:55], v[186:189], v[216:219], v[52:55]
	v_mfma_f32_16x16x32_bf16 v[48:51], v[194:197], v[216:219], v[48:51]
	v_mfma_f32_16x16x32_bf16 v[44:47], v[182:185], v[220:223], v[44:47]
	v_mfma_f32_16x16x32_bf16 v[40:43], v[190:193], v[220:223], v[40:43]
	v_mfma_f32_16x16x32_bf16 v[36:39], v[182:185], v[228:231], v[36:39]
	v_mfma_f32_16x16x32_bf16 v[32:35], v[190:193], v[228:231], v[32:35]
	v_mfma_f32_16x16x32_bf16 v[44:47], v[186:189], v[224:227], v[44:47]
	v_mfma_f32_16x16x32_bf16 v[40:43], v[194:197], v[224:227], v[40:43]
	v_mfma_f32_16x16x32_bf16 v[36:39], v[186:189], v[232:235], v[36:39]
	v_mfma_f32_16x16x32_bf16 v[32:35], v[194:197], v[232:235], v[32:35]
	s_setprio 0
	s_barrier
; #define PG8_STAGE(bufoff, gbase, voff) do { _Pragma("unroll") for (int _i = 0; _i < 2; ++_i) \
;         __builtin_amdgcn_global_load_lds((const unsigned*)((const char*)(gbase) + (voff)[_i]), (PG8_LAS unsigned*)(lds + (bufoff) + ldsw + _i * 8192), 16, 0, 0); } while (0)
; #define PG8_LDA(dst, b, h) do { _Pragma("unroll") for (int m = 0; m < 4; ++m) _Pragma("unroll") for (int k = 0; k < 2; ++k) dst[m][k] = *(const PG8_LAS bf16x8*)(lds + PG8_SA(b, h) + aoff + m * 2048 + k * 1024); } while (0)
; #define PG8_LDB(dst, b, h) do { _Pragma("unroll") for (int n = 0; n < 2; ++n) _Pragma("unroll") for (int k = 0; k < 2; ++k) dst[n][k] = *(const PG8_LAS bf16x8*)(lds + PG8_SB(b, h) + boff + n * 2048 + k * 1024); } while (0)
; template <class Epi, class Sched, bool ALIGN_EPI = false, bool SP2 = false>
; __device__ __forceinline__ void gemm_phase(PG8_LAS unsigned char* lds, const Gemm g, const Sched& S, const Epi& E) {
;     ...
;         for (int t = 0; t < nt; t += 2) {
;             const bool last = (t == nt - 2);
;             const char* a1 = cA + (size_t)(t + 1) * kstep;
;             const char* a2 = last ? nA : cA + (size_t)(t + 2) * kstep; const char* b2 = last ? nB : cB + (size_t)(t + 2) * kstep;
;             const char* a3 = a2 + kstep; const char* b3 = b2 + kstep;
;             if (last && has_next) S.a_ready(nxt);
;             if constexpr (SP2) {
;             PG8_LDB(B0, 0, 0); PG8_LDB(B1, 0, 1); PG8_SCHED; PG8_LDA(At, 0, 0); PG8_STAGE(PG8_SA(1, 1), a1 + hstep, voffA);
;             PG8_WAIT_V(8); PG8_WAIT_L(0); PG8_BAR; PG8_MMA(0, 0, At, B0); PG8_MMA(0, 1, At, B1); PG8_BAR; PG8_SCHED;
;             PG8_LDA(At, 0, 1); PG8_STAGE(PG8_SB(0, 0), b2, voffB); PG8_STAGE(PG8_SB(0, 1), b2 + hstep, voffB); PG8_STAGE(PG8_SA(0, 0), a2, voffA);
;             PG8_WAIT_V(8); PG8_WAIT_L(0); PG8_BAR; PG8_MMA(1, 0, At, B0); PG8_MMA(1, 1, At, B1); PG8_BAR; PG8_SCHED;
;             PG8_LDB(B0, 1, 0); PG8_LDB(B1, 1, 1); PG8_SCHED; PG8_LDA(At, 1, 0); PG8_STAGE(PG8_SA(0, 1), a2 + hstep, voffA);
;             PG8_WAIT_V(8); PG8_WAIT_L(0); PG8_BAR; PG8_MMA(0, 0, At, B0); PG8_MMA(0, 1, At, B1); PG8_BAR; PG8_SCHED;
;             PG8_LDA(At, 1, 1); PG8_STAGE(PG8_SB(1, 0), b3, voffB); PG8_STAGE(PG8_SB(1, 1), b3 + hstep, voffB); PG8_STAGE(PG8_SA(1, 0), a3, voffA);
;             PG8_WAIT_V(8); PG8_WAIT_L(0); PG8_BAR; PG8_MMA(1, 0, At, B0); PG8_MMA(1, 1, At, B1); PG8_BAR; PG8_SCHED;
	s_add_i32 s3, s3, s34
	v_lshl_add_u64 v[178:179], v[178:179], 0, s[8:9]
	s_mov_b32 m0, s3
	ds_read_b128 v[198:201], v171 offset:49152
	ds_read_b128 v[208:211], v171 offset:50176
	ds_read_b128 v[212:215], v171 offset:51200
	ds_read_b128 v[216:219], v171 offset:52224
	ds_read_b128 v[220:223], v171 offset:53248
	ds_read_b128 v[224:227], v171 offset:54272
	ds_read_b128 v[228:231], v171 offset:55296
	ds_read_b128 v[232:235], v171 offset:56320
	global_load_lds_dwordx4 v[178:179], off
	s_add_i32 m0, s3, 0x2000
	s_add_u32 s14, s56, 0x40080
	v_lshl_add_u64 v[178:179], v[202:203], 0, s[8:9]
	s_addc_u32 s15, s57, 0
	s_add_i32 s3, s33, s34
	global_load_lds_dwordx4 v[178:179], off
	v_lshl_add_u64 v[178:179], s[14:15], 0, v[132:133]
	s_mov_b32 m0, s3
	s_nop 0
	global_load_lds_dwordx4 v[178:179], off
	v_lshl_add_u64 v[178:179], s[14:15], 0, v[128:129]
	s_add_i32 m0, s3, 0x2000
	s_nop 0
	global_load_lds_dwordx4 v[178:179], off
	s_waitcnt vmcnt(6)
	s_waitcnt lgkmcnt(0)
	s_barrier
	s_setprio 1
	s_waitcnt lgkmcnt(0)
	v_mfma_f32_16x16x32_bf16 v[92:95], v[154:157], v[198:201], v[92:95]
	v_mfma_f32_16x16x32_bf16 v[88:91], v[162:165], v[198:201], v[88:91]
	v_mfma_f32_16x16x32_bf16 v[84:87], v[154:157], v[212:215], v[84:87]
	v_mfma_f32_16x16x32_bf16 v[80:83], v[162:165], v[212:215], v[80:83]
	v_mfma_f32_16x16x32_bf16 v[92:95], v[158:161], v[208:211], v[92:95]
	v_mfma_f32_16x16x32_bf16 v[88:91], v[174:177], v[208:211], v[88:91]
	v_mfma_f32_16x16x32_bf16 v[84:87], v[158:161], v[216:219], v[84:87]
	v_mfma_f32_16x16x32_bf16 v[80:83], v[174:177], v[216:219], v[80:83]
	v_mfma_f32_16x16x32_bf16 v[76:79], v[154:157], v[220:223], v[76:79]
	v_mfma_f32_16x16x32_bf16 v[72:75], v[162:165], v[220:223], v[72:75]
	v_mfma_f32_16x16x32_bf16 v[60:63], v[154:157], v[228:231], v[60:63]
	v_mfma_f32_16x16x32_bf16 v[56:59], v[162:165], v[228:231], v[56:59]
	v_mfma_f32_16x16x32_bf16 v[76:79], v[158:161], v[224:227], v[76:79]
	v_mfma_f32_16x16x32_bf16 v[72:75], v[174:177], v[224:227], v[72:75]
	v_lshl_add_u64 v[178:179], v[236:237], 0, s[8:9]
	s_mov_b32 m0, s66
	s_nop 0
	global_load_lds_dwordx4 v[178:179], off
	v_mfma_f32_16x16x32_bf16 v[60:63], v[158:161], v[232:235], v[60:63]
	v_mfma_f32_16x16x32_bf16 v[56:59], v[174:177], v[232:235], v[56:59]
	s_setprio 0
	s_setprio 1
	v_mfma_f32_16x16x32_bf16 v[28:31], v[182:185], v[198:201], v[28:31]
	v_mfma_f32_16x16x32_bf16 v[24:27], v[190:193], v[198:201], v[24:27]
	v_mfma_f32_16x16x32_bf16 v[20:23], v[182:185], v[212:215], v[20:23]
	v_mfma_f32_16x16x32_bf16 v[16:19], v[190:193], v[212:215], v[16:19]
	v_mfma_f32_16x16x32_bf16 v[28:31], v[186:189], v[208:211], v[28:31]
	v_mfma_f32_16x16x32_bf16 v[24:27], v[194:197], v[208:211], v[24:27]
	v_mfma_f32_16x16x32_bf16 v[20:23], v[186:189], v[216:219], v[20:23]
	v_mfma_f32_16x16x32_bf16 v[16:19], v[194:197], v[216:219], v[16:19]
	v_mfma_f32_16x16x32_bf16 v[12:15], v[182:185], v[220:223], v[12:15]
	v_mfma_f32_16x16x32_bf16 v[8:11], v[190:193], v[220:223], v[8:11]
	v_mfma_f32_16x16x32_bf16 v[4:7], v[182:185], v[228:231], v[4:7]
	v_mfma_f32_16x16x32_bf16 v[0:3], v[190:193], v[228:231], v[0:3]
	v_mfma_f32_16x16x32_bf16 v[12:15], v[186:189], v[224:227], v[12:15]
	v_mfma_f32_16x16x32_bf16 v[8:11], v[194:197], v[224:227], v[8:11]
	v_lshl_add_u64 v[178:179], v[238:239], 0, s[8:9]
	s_mov_b32 m0, s67
	s_nop 0
	global_load_lds_dwordx4 v[178:179], off
	v_mfma_f32_16x16x32_bf16 v[4:7], v[186:189], v[232:235], v[4:7]
	v_mfma_f32_16x16x32_bf16 v[0:3], v[194:197], v[232:235], v[0:3]
	s_setprio 0
	s_barrier
	s_add_i32 s93, s93, 2
	s_add_u32 s54, s54, 0x100
	s_addc_u32 s55, s55, 0
	s_add_u32 s91, s91, 0x100
	s_addc_u32 s92, s92, 0
.LBB0_417:
	ds_read_b128 v[154:157], v169
	ds_read_b128 v[158:161], v169 offset:1024
	ds_read_b128 v[162:165], v169 offset:2048
	ds_read_b128 v[174:177], v169 offset:3072
	ds_read_b128 v[182:185], v170
	ds_read_b128 v[186:189], v170 offset:1024
	ds_read_b128 v[190:193], v170 offset:2048
	ds_read_b128 v[194:197], v170 offset:3072
	s_add_u32 s3, s54, 0xfffc0080
	s_addc_u32 s14, s55, -1
	s_cmp_eq_u32 s93, 12
	s_cselect_b32 s59, s45, s14
	s_cselect_b32 s58, s89, s3
	s_cselect_b32 s57, s41, s92
	s_cselect_b32 s56, s90, s91
	v_lshl_add_u64 v[178:179], s[54:55], 0, v[146:147]
	s_add_i32 m0, s60, 0xc000
	ds_read_b128 v[198:201], v171
	ds_read_b128 v[208:211], v171 offset:1024
	ds_read_b128 v[212:215], v171 offset:2048
	ds_read_b128 v[216:219], v171 offset:3072
	ds_read_b128 v[220:223], v171 offset:4096
	ds_read_b128 v[224:227], v171 offset:5120
	ds_read_b128 v[228:231], v171 offset:6144
	ds_read_b128 v[232:235], v171 offset:7168
	global_load_lds_dwordx4 v[178:179], off
	v_lshl_add_u64 v[178:179], s[54:55], 0, v[148:149]
	s_add_i32 m0, s60, 0xe000
	s_nop 0
	global_load_lds_dwordx4 v[178:179], off
	s_waitcnt vmcnt(8)
	s_waitcnt lgkmcnt(0)
	s_barrier
; #define PG8_STAGE(bufoff, gbase, voff) do { _Pragma("unroll") for (int _i = 0; _i < 2; ++_i) \
;         __builtin_amdgcn_global_load_lds((const unsigned*)((const char*)(gbase) + (voff)[_i]), (PG8_LAS unsigned*)(lds + (bufoff) + ldsw + _i * 8192), 16, 0, 0); } while (0)
; #define PG8_LDA(dst, b, h) do { _Pragma("unroll") for (int m = 0; m < 4; ++m) _Pragma("unroll") for (int k = 0; k < 2; ++k) dst[m][k] = *(const PG8_LAS bf16x8*)(lds + PG8_SA(b, h) + aoff + m * 2048 + k * 1024); } while (0)
; #define PG8_LDB(dst, b, h) do { _Pragma("unroll") for (int n = 0; n < 2; ++n) _Pragma("unroll") for (int k = 0; k < 2; ++k) dst[n][k] = *(const PG8_LAS bf16x8*)(lds + PG8_SB(b, h) + boff + n * 2048 + k * 1024); } while (0)
; #define PG8_MMA(ai, bj, At, Bt) do { __builtin_amdgcn_s_setprio(1); _Pragma("unroll") for (int m = 0; m < 4; ++m) _Pragma("unroll") for (int n = 0; n < 2; ++n) _Pragma("unroll") for (int k = 0; k < 2; ++k) \
;         acc[ai][bj][m][n] = __builtin_amdgcn_mfma_f32_16x16x32_bf16(Bt[n][k], At[m][k], acc[ai][bj][m][n], 0, 0, 0); __builtin_amdgcn_s_setprio(0); } while (0)
; #define PG8_WAIT_V(n) asm volatile("s_waitcnt vmcnt(" #n ")" ::: "memory")
; #define PG8_WAIT_L(n) asm volatile("s_waitcnt lgkmcnt(" #n ")" ::: "memory")
; #define PG8_BAR __builtin_amdgcn_s_barrier()
; #define PG8_SCHED __builtin_amdgcn_sched_barrier(0)
; template <class Epi, class Sched, bool ALIGN_EPI = false, bool SP2 = false>
; __device__ __forceinline__ void gemm_phase(PG8_LAS unsigned char* lds, const Gemm g, const Sched& S, const Epi& E) {
;     ...
;             PG8_LDB(B0, 0, 0); PG8_LDB(B1, 0, 1); PG8_SCHED; PG8_LDA(At, 0, 0); PG8_STAGE(PG8_SA(1, 1), a1 + hstep, voffA);
;             PG8_WAIT_V(8); PG8_WAIT_L(0); PG8_BAR; PG8_MMA(0, 0, At, B0); PG8_MMA(0, 1, At, B1); PG8_BAR; PG8_SCHED;
;             PG8_LDA(At, 0, 1); PG8_STAGE(PG8_SB(0, 0), b2, voffB); PG8_STAGE(PG8_SB(0, 1), b2 + hstep, voffB); PG8_STAGE(PG8_SA(0, 0), a2, voffA);
;             PG8_WAIT_V(8); PG8_WAIT_L(0); PG8_BAR; PG8_MMA(1, 0, At, B0); PG8_MMA(1, 1, At, B1); PG8_BAR; PG8_SCHED;
	s_setprio 1
	s_waitcnt lgkmcnt(0)
	v_mfma_f32_16x16x32_bf16 v[124:127], v[154:157], v[198:201], v[124:127]
	v_mfma_f32_16x16x32_bf16 v[120:123], v[162:165], v[198:201], v[120:123]
	v_mfma_f32_16x16x32_bf16 v[116:119], v[154:157], v[212:215], v[116:119]
	v_mfma_f32_16x16x32_bf16 v[112:115], v[162:165], v[212:215], v[112:115]
	v_mfma_f32_16x16x32_bf16 v[124:127], v[158:161], v[208:211], v[124:127]
	v_mfma_f32_16x16x32_bf16 v[120:123], v[174:177], v[208:211], v[120:123]
	v_mfma_f32_16x16x32_bf16 v[116:119], v[158:161], v[216:219], v[116:119]
	v_mfma_f32_16x16x32_bf16 v[112:115], v[174:177], v[216:219], v[112:115]
	v_mfma_f32_16x16x32_bf16 v[108:111], v[154:157], v[220:223], v[108:111]
	v_mfma_f32_16x16x32_bf16 v[104:107], v[162:165], v[220:223], v[104:107]
	v_mfma_f32_16x16x32_bf16 v[100:103], v[154:157], v[228:231], v[100:103]
	v_mfma_f32_16x16x32_bf16 v[96:99], v[162:165], v[228:231], v[96:99]
	v_mfma_f32_16x16x32_bf16 v[108:111], v[158:161], v[224:227], v[108:111]
	v_mfma_f32_16x16x32_bf16 v[104:107], v[174:177], v[224:227], v[104:107]
	v_mfma_f32_16x16x32_bf16 v[100:103], v[158:161], v[232:235], v[100:103]
	v_mfma_f32_16x16x32_bf16 v[96:99], v[174:177], v[232:235], v[96:99]
	s_setprio 0
	s_setprio 1
	v_mfma_f32_16x16x32_bf16 v[68:71], v[182:185], v[198:201], v[68:71]
	v_mfma_f32_16x16x32_bf16 v[64:67], v[190:193], v[198:201], v[64:67]
	v_mfma_f32_16x16x32_bf16 v[52:55], v[182:185], v[212:215], v[52:55]
	v_mfma_f32_16x16x32_bf16 v[48:51], v[190:193], v[212:215], v[48:51]
	v_mfma_f32_16x16x32_bf16 v[68:71], v[186:189], v[208:211], v[68:71]
	v_mfma_f32_16x16x32_bf16 v[64:67], v[194:197], v[208:211], v[64:67]
	v_mfma_f32_16x16x32_bf16 v[52:55], v[186:189], v[216:219], v[52:55]
	v_mfma_f32_16x16x32_bf16 v[48:51], v[194:197], v[216:219], v[48:51]
	v_mfma_f32_16x16x32_bf16 v[44:47], v[182:185], v[220:223], v[44:47]
	v_mfma_f32_16x16x32_bf16 v[40:43], v[190:193], v[220:223], v[40:43]
	v_mfma_f32_16x16x32_bf16 v[36:39], v[182:185], v[228:231], v[36:39]
	v_mfma_f32_16x16x32_bf16 v[32:35], v[190:193], v[228:231], v[32:35]
	v_mfma_f32_16x16x32_bf16 v[44:47], v[186:189], v[224:227], v[44:47]
	v_mfma_f32_16x16x32_bf16 v[40:43], v[194:197], v[224:227], v[40:43]
	v_mfma_f32_16x16x32_bf16 v[36:39], v[186:189], v[232:235], v[36:39]
	v_mfma_f32_16x16x32_bf16 v[32:35], v[194:197], v[232:235], v[32:35]
	s_setprio 0
	s_barrier
	s_add_i32 s3, s86, s34
	v_lshl_add_u64 v[178:179], s[56:57], 0, v[132:133]
	s_mov_b32 m0, s3
	ds_read_b128 v[198:201], v171 offset:16384
	ds_read_b128 v[208:211], v171 offset:17408
	ds_read_b128 v[212:215], v171 offset:18432
	ds_read_b128 v[216:219], v171 offset:19456
	ds_read_b128 v[220:223], v171 offset:20480
	ds_read_b128 v[224:227], v171 offset:21504
	ds_read_b128 v[228:231], v171 offset:22528
	ds_read_b128 v[232:235], v171 offset:23552
	global_load_lds_dwordx4 v[178:179], off
	s_add_i32 m0, s3, 0x2000
	s_add_u32 s14, s56, 0x40000
	v_lshl_add_u64 v[202:203], s[56:57], 0, v[128:129]
	s_addc_u32 s15, s57, 0
	s_add_i32 s3, s87, s34
	global_load_lds_dwordx4 v[202:203], off
	v_lshl_add_u64 v[236:237], s[14:15], 0, v[132:133]
	s_mov_b32 m0, s3
	global_load_lds_dwordx4 v[236:237], off
	v_lshl_add_u64 v[236:237], s[14:15], 0, v[128:129]
	s_add_i32 m0, s3, 0x2000
	s_nop 0
	global_load_lds_dwordx4 v[236:237], off
	s_waitcnt vmcnt(6)
	s_waitcnt lgkmcnt(0)
	s_barrier
	s_setprio 1
	s_waitcnt lgkmcnt(0)
	v_mfma_f32_16x16x32_bf16 v[92:95], v[154:157], v[198:201], v[92:95]
	v_mfma_f32_16x16x32_bf16 v[88:91], v[162:165], v[198:201], v[88:91]
	v_mfma_f32_16x16x32_bf16 v[84:87], v[154:157], v[212:215], v[84:87]
	v_mfma_f32_16x16x32_bf16 v[80:83], v[162:165], v[212:215], v[80:83]
	v_mfma_f32_16x16x32_bf16 v[92:95], v[158:161], v[208:211], v[92:95]
	v_mfma_f32_16x16x32_bf16 v[88:91], v[174:177], v[208:211], v[88:91]
	v_mfma_f32_16x16x32_bf16 v[84:87], v[158:161], v[216:219], v[84:87]
	v_mfma_f32_16x16x32_bf16 v[80:83], v[174:177], v[216:219], v[80:83]
	v_mfma_f32_16x16x32_bf16 v[76:79], v[154:157], v[220:223], v[76:79]
	v_mfma_f32_16x16x32_bf16 v[72:75], v[162:165], v[220:223], v[72:75]
	v_mfma_f32_16x16x32_bf16 v[60:63], v[154:157], v[228:231], v[60:63]
	v_mfma_f32_16x16x32_bf16 v[56:59], v[162:165], v[228:231], v[56:59]
	v_mfma_f32_16x16x32_bf16 v[76:79], v[158:161], v[224:227], v[76:79]
	v_mfma_f32_16x16x32_bf16 v[72:75], v[174:177], v[224:227], v[72:75]
	v_lshl_add_u64 v[236:237], s[58:59], 0, v[134:135]
	s_mov_b32 m0, s60
	s_nop 0
	global_load_lds_dwordx4 v[236:237], off
	v_mfma_f32_16x16x32_bf16 v[60:63], v[158:161], v[232:235], v[60:63]
	v_mfma_f32_16x16x32_bf16 v[56:59], v[174:177], v[232:235], v[56:59]
	s_setprio 0
	s_setprio 1
	v_mfma_f32_16x16x32_bf16 v[28:31], v[182:185], v[198:201], v[28:31]
	v_mfma_f32_16x16x32_bf16 v[24:27], v[190:193], v[198:201], v[24:27]
	v_mfma_f32_16x16x32_bf16 v[20:23], v[182:185], v[212:215], v[20:23]
	v_mfma_f32_16x16x32_bf16 v[16:19], v[190:193], v[212:215], v[16:19]
	v_mfma_f32_16x16x32_bf16 v[28:31], v[186:189], v[208:211], v[28:31]
	v_mfma_f32_16x16x32_bf16 v[24:27], v[194:197], v[208:211], v[24:27]
	v_mfma_f32_16x16x32_bf16 v[20:23], v[186:189], v[216:219], v[20:23]
	v_mfma_f32_16x16x32_bf16 v[16:19], v[194:197], v[216:219], v[16:19]
	v_mfma_f32_16x16x32_bf16 v[12:15], v[182:185], v[220:223], v[12:15]
	v_mfma_f32_16x16x32_bf16 v[8:11], v[190:193], v[220:223], v[8:11]
	v_mfma_f32_16x16x32_bf16 v[4:7], v[182:185], v[228:231], v[4:7]
	v_mfma_f32_16x16x32_bf16 v[0:3], v[190:193], v[228:231], v[0:3]
	v_mfma_f32_16x16x32_bf16 v[12:15], v[186:189], v[224:227], v[12:15]
	v_mfma_f32_16x16x32_bf16 v[8:11], v[194:197], v[224:227], v[8:11]
	v_lshl_add_u64 v[238:239], s[58:59], 0, v[130:131]
	s_mov_b32 m0, s61
	s_nop 0
	global_load_lds_dwordx4 v[238:239], off
	v_mfma_f32_16x16x32_bf16 v[4:7], v[186:189], v[232:235], v[4:7]
	v_mfma_f32_16x16x32_bf16 v[0:3], v[194:197], v[232:235], v[0:3]
	s_setprio 0
	s_barrier
; #define PG8_STAGE(bufoff, gbase, voff) do { _Pragma("unroll") for (int _i = 0; _i < 2; ++_i) \
;         __builtin_amdgcn_global_load_lds((const unsigned*)((const char*)(gbase) + (voff)[_i]), (PG8_LAS unsigned*)(lds + (bufoff) + ldsw + _i * 8192), 16, 0, 0); } while (0)
; #define PG8_LDA(dst, b, h) do { _Pragma("unroll") for (int m = 0; m < 4; ++m) _Pragma("unroll") for (int k = 0; k < 2; ++k) dst[m][k] = *(const PG8_LAS bf16x8*)(lds + PG8_SA(b, h) + aoff + m * 2048 + k * 1024); } while (0)
; #define PG8_LDB(dst, b, h) do { _Pragma("unroll") for (int n = 0; n < 2; ++n) _Pragma("unroll") for (int k = 0; k < 2; ++k) dst[n][k] = *(const PG8_LAS bf16x8*)(lds + PG8_SB(b, h) + boff + n * 2048 + k * 1024); } while (0)
; #define PG8_MMA(ai, bj, At, Bt) do { __builtin_amdgcn_s_setprio(1); _Pragma("unroll") for (int m = 0; m < 4; ++m) _Pragma("unroll") for (int n = 0; n < 2; ++n) _Pragma("unroll") for (int k = 0; k < 2; ++k) \
;         acc[ai][bj][m][n] = __builtin_amdgcn_mfma_f32_16x16x32_bf16(Bt[n][k], At[m][k], acc[ai][bj][m][n], 0, 0, 0); __builtin_amdgcn_s_setprio(0); } while (0)
; #define PG8_WAIT_V(n) asm volatile("s_waitcnt vmcnt(" #n ")" ::: "memory")
; #define PG8_WAIT_L(n) asm volatile("s_waitcnt lgkmcnt(" #n ")" ::: "memory")
; #define PG8_BAR __builtin_amdgcn_s_barrier()
; #define PG8_SCHED __builtin_amdgcn_sched_barrier(0)
; template <class Epi, class Sched, bool ALIGN_EPI = false, bool SP2 = false>
; __device__ __forceinline__ void gemm_phase(PG8_LAS unsigned char* lds, const Gemm g, const Sched& S, const Epi& E) {
;     ...
;             PG8_LDB(B0, 1, 0); PG8_LDB(B1, 1, 1); PG8_SCHED; PG8_LDA(At, 1, 0); PG8_STAGE(PG8_SA(0, 1), a2 + hstep, voffA);
;             PG8_WAIT_V(8); PG8_WAIT_L(0); PG8_BAR; PG8_MMA(0, 0, At, B0); PG8_MMA(0, 1, At, B1); PG8_BAR; PG8_SCHED;
	s_add_i32 s3, 0, 0x18000
	v_add_u32_e32 v136, s3, v143
	s_add_i32 s33, 0, 0x1c000
	ds_read_b128 v[154:157], v136
	ds_read_b128 v[158:161], v136 offset:1024
	ds_read_b128 v[162:165], v136 offset:2048
	ds_read_b128 v[174:177], v136 offset:3072
	v_add_u32_e32 v136, s33, v143
	ds_read_b128 v[182:185], v136
	ds_read_b128 v[186:189], v136 offset:1024
	ds_read_b128 v[190:193], v136 offset:2048
	ds_read_b128 v[194:197], v136 offset:3072
	s_add_u32 s14, s58, 0x40000
	s_addc_u32 s15, s59, 0
	s_mov_b32 m0, s62
	v_lshl_add_u64 v[240:241], s[14:15], 0, v[134:135]
	ds_read_b128 v[198:201], v171 offset:32768
	ds_read_b128 v[208:211], v171 offset:33792
	ds_read_b128 v[212:215], v171 offset:34816
	ds_read_b128 v[216:219], v171 offset:35840
	ds_read_b128 v[220:223], v171 offset:36864
	ds_read_b128 v[224:227], v171 offset:37888
	ds_read_b128 v[228:231], v171 offset:38912
	ds_read_b128 v[232:235], v171 offset:39936
	global_load_lds_dwordx4 v[240:241], off
	v_lshl_add_u64 v[240:241], s[14:15], 0, v[130:131]
	s_mov_b32 m0, s63
	s_nop 0
	global_load_lds_dwordx4 v[240:241], off
	s_waitcnt vmcnt(8)
	s_waitcnt lgkmcnt(0)
	s_barrier
	s_setprio 1
	s_waitcnt lgkmcnt(0)
	v_mfma_f32_16x16x32_bf16 v[124:127], v[154:157], v[198:201], v[124:127]
	v_mfma_f32_16x16x32_bf16 v[120:123], v[162:165], v[198:201], v[120:123]
	v_mfma_f32_16x16x32_bf16 v[116:119], v[154:157], v[212:215], v[116:119]
	v_mfma_f32_16x16x32_bf16 v[112:115], v[162:165], v[212:215], v[112:115]
	v_mfma_f32_16x16x32_bf16 v[124:127], v[158:161], v[208:211], v[124:127]
	v_mfma_f32_16x16x32_bf16 v[120:123], v[174:177], v[208:211], v[120:123]
	v_mfma_f32_16x16x32_bf16 v[116:119], v[158:161], v[216:219], v[116:119]
	v_mfma_f32_16x16x32_bf16 v[112:115], v[174:177], v[216:219], v[112:115]
	v_mfma_f32_16x16x32_bf16 v[108:111], v[154:157], v[220:223], v[108:111]
	v_mfma_f32_16x16x32_bf16 v[104:107], v[162:165], v[220:223], v[104:107]
	v_mfma_f32_16x16x32_bf16 v[100:103], v[154:157], v[228:231], v[100:103]
	v_mfma_f32_16x16x32_bf16 v[96:99], v[162:165], v[228:231], v[96:99]
	v_mfma_f32_16x16x32_bf16 v[108:111], v[158:161], v[224:227], v[108:111]
	v_mfma_f32_16x16x32_bf16 v[104:107], v[174:177], v[224:227], v[104:107]
	v_mfma_f32_16x16x32_bf16 v[100:103], v[158:161], v[232:235], v[100:103]
	v_mfma_f32_16x16x32_bf16 v[96:99], v[174:177], v[232:235], v[96:99]
	s_setprio 0
	s_setprio 1
	v_mfma_f32_16x16x32_bf16 v[68:71], v[182:185], v[198:201], v[68:71]
	v_mfma_f32_16x16x32_bf16 v[64:67], v[190:193], v[198:201], v[64:67]
	v_mfma_f32_16x16x32_bf16 v[52:55], v[182:185], v[212:215], v[52:55]
	v_mfma_f32_16x16x32_bf16 v[48:51], v[190:193], v[212:215], v[48:51]
	v_mfma_f32_16x16x32_bf16 v[68:71], v[186:189], v[208:211], v[68:71]
	v_mfma_f32_16x16x32_bf16 v[64:67], v[194:197], v[208:211], v[64:67]
	v_mfma_f32_16x16x32_bf16 v[52:55], v[186:189], v[216:219], v[52:55]
	v_mfma_f32_16x16x32_bf16 v[48:51], v[194:197], v[216:219], v[48:51]
	v_mfma_f32_16x16x32_bf16 v[44:47], v[182:185], v[220:223], v[44:47]
	v_mfma_f32_16x16x32_bf16 v[40:43], v[190:193], v[220:223], v[40:43]
	v_mfma_f32_16x16x32_bf16 v[36:39], v[182:185], v[228:231], v[36:39]
	v_mfma_f32_16x16x32_bf16 v[32:35], v[190:193], v[228:231], v[32:35]
	v_mfma_f32_16x16x32_bf16 v[44:47], v[186:189], v[224:227], v[44:47]
	v_mfma_f32_16x16x32_bf16 v[40:43], v[194:197], v[224:227], v[40:43]
	v_mfma_f32_16x16x32_bf16 v[36:39], v[186:189], v[232:235], v[36:39]
	v_mfma_f32_16x16x32_bf16 v[32:35], v[194:197], v[232:235], v[32:35]
	s_setprio 0
	s_barrier
; #define PG8_STAGE(bufoff, gbase, voff) do { _Pragma("unroll") for (int _i = 0; _i < 2; ++_i) \
;         __builtin_amdgcn_global_load_lds((const unsigned*)((const char*)(gbase) + (voff)[_i]), (PG8_LAS unsigned*)(lds + (bufoff) + ldsw + _i * 8192), 16, 0, 0); } while (0)
; #define PG8_LDA(dst, b, h) do { _Pragma("unroll") for (int m = 0; m < 4; ++m) _Pragma("unroll") for (int k = 0; k < 2; ++k) dst[m][k] = *(const PG8_LAS bf16x8*)(lds + PG8_SA(b, h) + aoff + m * 2048 + k * 1024); } while (0)
; #define PG8_MMA(ai, bj, At, Bt) do { __builtin_amdgcn_s_setprio(1); _Pragma("unroll") for (int m = 0; m < 4; ++m) _Pragma("unroll") for (int n = 0; n < 2; ++n) _Pragma("unroll") for (int k = 0; k < 2; ++k) \
;         acc[ai][bj][m][n] = __builtin_amdgcn_mfma_f32_16x16x32_bf16(Bt[n][k], At[m][k], acc[ai][bj][m][n], 0, 0, 0); __builtin_amdgcn_s_setprio(0); } while (0)
; #define PG8_WAIT_V(n) asm volatile("s_waitcnt vmcnt(" #n ")" ::: "memory")
; #define PG8_WAIT_L(n) asm volatile("s_waitcnt lgkmcnt(" #n ")" ::: "memory")
; #define PG8_BAR __builtin_amdgcn_s_barrier()
; #define PG8_SCHED __builtin_amdgcn_sched_barrier(0)
; template <class Epi, class Sched, bool ALIGN_EPI = false, bool SP2 = false>
; __device__ __forceinline__ void gemm_phase(PG8_LAS unsigned char* lds, const Gemm g, const Sched& S, const Epi& E) {
;     ...
;             PG8_LDA(At, 1, 1); PG8_STAGE(PG8_SB(1, 0), b3, voffB); PG8_STAGE(PG8_SB(1, 1), b3 + hstep, voffB); PG8_STAGE(PG8_SA(1, 0), a3, voffA);
;             PG8_WAIT_V(8); PG8_WAIT_L(0); PG8_BAR; PG8_MMA(1, 0, At, B0); PG8_MMA(1, 1, At, B1); PG8_BAR; PG8_SCHED;
	s_add_i32 s3, s3, s34
	v_lshl_add_u64 v[178:179], v[178:179], 0, s[8:9]
	s_mov_b32 m0, s3
	ds_read_b128 v[198:201], v171 offset:49152
	ds_read_b128 v[208:211], v171 offset:50176
	ds_read_b128 v[212:215], v171 offset:51200
	ds_read_b128 v[216:219], v171 offset:52224
	ds_read_b128 v[220:223], v171 offset:53248
	ds_read_b128 v[224:227], v171 offset:54272
	ds_read_b128 v[228:231], v171 offset:55296
	ds_read_b128 v[232:235], v171 offset:56320
	global_load_lds_dwordx4 v[178:179], off
	s_add_i32 m0, s3, 0x2000
	s_add_u32 s14, s56, 0x40080
	v_lshl_add_u64 v[178:179], v[202:203], 0, s[8:9]
	s_addc_u32 s15, s57, 0
	s_add_i32 s3, s33, s34
	global_load_lds_dwordx4 v[178:179], off
	v_lshl_add_u64 v[178:179], s[14:15], 0, v[132:133]
	s_mov_b32 m0, s3
	s_nop 0
	global_load_lds_dwordx4 v[178:179], off
	v_lshl_add_u64 v[178:179], s[14:15], 0, v[128:129]
	s_add_i32 m0, s3, 0x2000
	s_nop 0
	global_load_lds_dwordx4 v[178:179], off
	s_waitcnt vmcnt(6)
	s_waitcnt lgkmcnt(0)
	s_barrier
	s_setprio 1
	s_waitcnt lgkmcnt(0)
	v_mfma_f32_16x16x32_bf16 v[92:95], v[154:157], v[198:201], v[92:95]
	v_mfma_f32_16x16x32_bf16 v[88:91], v[162:165], v[198:201], v[88:91]
	v_mfma_f32_16x16x32_bf16 v[84:87], v[154:157], v[212:215], v[84:87]
	v_mfma_f32_16x16x32_bf16 v[80:83], v[162:165], v[212:215], v[80:83]
	v_mfma_f32_16x16x32_bf16 v[92:95], v[158:161], v[208:211], v[92:95]
	v_mfma_f32_16x16x32_bf16 v[88:91], v[174:177], v[208:211], v[88:91]
	v_mfma_f32_16x16x32_bf16 v[84:87], v[158:161], v[216:219], v[84:87]
	v_mfma_f32_16x16x32_bf16 v[80:83], v[174:177], v[216:219], v[80:83]
	v_mfma_f32_16x16x32_bf16 v[76:79], v[154:157], v[220:223], v[76:79]
	v_mfma_f32_16x16x32_bf16 v[72:75], v[162:165], v[220:223], v[72:75]
	v_mfma_f32_16x16x32_bf16 v[60:63], v[154:157], v[228:231], v[60:63]
	v_mfma_f32_16x16x32_bf16 v[56:59], v[162:165], v[228:231], v[56:59]
	v_mfma_f32_16x16x32_bf16 v[76:79], v[158:161], v[224:227], v[76:79]
	v_mfma_f32_16x16x32_bf16 v[72:75], v[174:177], v[224:227], v[72:75]
	v_lshl_add_u64 v[178:179], v[236:237], 0, s[8:9]
	s_mov_b32 m0, s66
	s_nop 0
	global_load_lds_dwordx4 v[178:179], off
	v_mfma_f32_16x16x32_bf16 v[60:63], v[158:161], v[232:235], v[60:63]
	v_mfma_f32_16x16x32_bf16 v[56:59], v[174:177], v[232:235], v[56:59]
	s_setprio 0
	s_setprio 1
	v_mfma_f32_16x16x32_bf16 v[28:31], v[182:185], v[198:201], v[28:31]
	v_mfma_f32_16x16x32_bf16 v[24:27], v[190:193], v[198:201], v[24:27]
	v_mfma_f32_16x16x32_bf16 v[20:23], v[182:185], v[212:215], v[20:23]
	v_mfma_f32_16x16x32_bf16 v[16:19], v[190:193], v[212:215], v[16:19]
	v_mfma_f32_16x16x32_bf16 v[28:31], v[186:189], v[208:211], v[28:31]
	v_mfma_f32_16x16x32_bf16 v[24:27], v[194:197], v[208:211], v[24:27]
	v_mfma_f32_16x16x32_bf16 v[20:23], v[186:189], v[216:219], v[20:23]
	v_mfma_f32_16x16x32_bf16 v[16:19], v[194:197], v[216:219], v[16:19]
	v_mfma_f32_16x16x32_bf16 v[12:15], v[182:185], v[220:223], v[12:15]
	v_mfma_f32_16x16x32_bf16 v[8:11], v[190:193], v[220:223], v[8:11]
	v_mfma_f32_16x16x32_bf16 v[4:7], v[182:185], v[228:231], v[4:7]
	v_mfma_f32_16x16x32_bf16 v[0:3], v[190:193], v[228:231], v[0:3]
	v_mfma_f32_16x16x32_bf16 v[12:15], v[186:189], v[224:227], v[12:15]
	v_mfma_f32_16x16x32_bf16 v[8:11], v[194:197], v[224:227], v[8:11]
	v_lshl_add_u64 v[178:179], v[238:239], 0, s[8:9]
	s_mov_b32 m0, s67
	s_nop 0
	global_load_lds_dwordx4 v[178:179], off
	v_mfma_f32_16x16x32_bf16 v[4:7], v[186:189], v[232:235], v[4:7]
	v_mfma_f32_16x16x32_bf16 v[0:3], v[194:197], v[232:235], v[0:3]
	s_setprio 0
	s_barrier
	s_add_i32 s93, s93, 2
	s_add_u32 s54, s54, 0x100
	s_addc_u32 s55, s55, 0
	s_add_u32 s91, s91, 0x100
	s_addc_u32 s92, s92, 0
	s_cmp_gt_u32 s93, 13
	s_cbranch_scc0 .LBB0_417
	s_and_b64 vcc, exec, s[10:11]
	s_cbranch_vccz .LBB0_420
	s_barrier

; #define PG8_STAGE(bufoff, gbase, voff) do { _Pragma("unroll") for (int _i = 0; _i < 2; ++_i) \
;         __builtin_amdgcn_global_load_lds((const unsigned*)((const char*)(gbase) + (voff)[_i]), (PG8_LAS unsigned*)(lds + (bufoff) + ldsw + _i * 8192), 16, 0, 0); } while (0)
; #define PG8_LDA(dst, b, h) do { _Pragma("unroll") for (int m = 0; m < 4; ++m) _Pragma("unroll") for (int k = 0; k < 2; ++k) dst[m][k] = *(const PG8_LAS bf16x8*)(lds + PG8_SA(b, h) + aoff + m * 2048 + k * 1024); } while (0)
; #define PG8_LDB(dst, b, h) do { _Pragma("unroll") for (int n = 0; n < 2; ++n) _Pragma("unroll") for (int k = 0; k < 2; ++k) dst[n][k] = *(const PG8_LAS bf16x8*)(lds + PG8_SB(b, h) + boff + n * 2048 + k * 1024); } while (0)
; #define PG8_WAIT_V(n) asm volatile("s_waitcnt vmcnt(" #n ")" ::: "memory")
; #define PG8_WAIT_L(n) asm volatile("s_waitcnt lgkmcnt(" #n ")" ::: "memory")
; #define PG8_BAR __builtin_amdgcn_s_barrier()
; #define PG8_SCHED __builtin_amdgcn_sched_barrier(0)
; template <class Epi, class Sched, bool ALIGN_EPI = false, bool SP2 = false>
; __device__ __forceinline__ void gemm_phase(PG8_LAS unsigned char* lds, const Gemm g, const Sched& S, const Epi& E) {
;     ...
;         const bool has_next = S.next(ui + 1, nxt);
;         const char* nA = has_next ? (const char*)g.A + (size_t)nxt.pm * tstep : cA; const char* nB = has_next ? (const char*)g.Bt + (size_t)nxt.pn * tstep : cB;
;         for (int t = 0; t < nt; t += 2) {
;             const bool last = (t == nt - 2);
;             const char* a1 = cA + (size_t)(t + 1) * kstep;
;             const char* a2 = last ? nA : cA + (size_t)(t + 2) * kstep; const char* b2 = last ? nB : cB + (size_t)(t + 2) * kstep;
;             const char* a3 = a2 + kstep; const char* b3 = b2 + kstep;
;             if (last && has_next) S.a_ready(nxt);
;             if constexpr (SP2) {
;             PG8_LDB(B0, 0, 0); PG8_LDB(B1, 0, 1); PG8_SCHED; PG8_LDA(At, 0, 0); PG8_STAGE(PG8_SA(1, 1), a1 + hstep, voffA);
;             PG8_WAIT_V(8); PG8_WAIT_L(0); PG8_BAR; PG8_MMA(0, 0, At, B0); PG8_MMA(0, 1, At, B1); PG8_BAR; PG8_SCHED;
;             PG8_LDA(At, 0, 1); PG8_STAGE(PG8_SB(0, 0), b2, voffB); PG8_STAGE(PG8_SB(0, 1), b2 + hstep, voffB); PG8_STAGE(PG8_SA(0, 0), a2, voffA);
;             PG8_WAIT_V(8); PG8_WAIT_L(0); PG8_BAR; PG8_MMA(1, 0, At, B0); PG8_MMA(1, 1, At, B1); PG8_BAR; PG8_SCHED;
.LBB0_458:
	s_ashr_i32 s49, s48, 31
	s_lshl_b64 s[14:15], s[48:49], 19
	s_add_u32 s50, s34, s14
	s_addc_u32 s51, s43, s15
	s_and_b64 s[14:15], s[40:41], exec
	s_cselect_b32 s49, s51, s59
	s_cselect_b32 s55, s50, s58
	s_ashr_i32 s45, s44, 31
	s_lshl_b64 s[14:15], s[44:45], 19
	v_readlane_b32 s3, v250, 13
	s_add_u32 s52, s3, s14
	v_readlane_b32 s3, v250, 14
	s_addc_u32 s53, s3, s15
	s_and_b64 s[14:15], s[40:41], exec
	s_cselect_b32 s45, s53, s61
	s_cselect_b32 s57, s52, s60
	s_add_u32 s58, s58, 0x40080
	s_addc_u32 s59, s59, 0
	s_add_u32 s96, s60, 0x100
	s_addc_u32 s97, s61, 0
	s_mov_b32 vcc_lo, -2
	ds_read_b128 v[170:173], v165
	ds_read_b128 v[174:177], v165 offset:1024
	ds_read_b128 v[182:185], v165 offset:2048
	ds_read_b128 v[186:189], v165 offset:3072
	ds_read_b128 v[190:193], v168
	ds_read_b128 v[194:197], v168 offset:1024
	ds_read_b128 v[198:201], v168 offset:2048
	ds_read_b128 v[208:211], v168 offset:3072
	s_add_u32 s3, s58, 0xfffc0080
	s_addc_u32 s14, s59, -1
	s_cmp_eq_u32 vcc_lo, 12
	s_cselect_b32 s63, s49, s14
	s_cselect_b32 s62, s55, s3
	s_cselect_b32 s61, s45, s97
	s_cselect_b32 s60, s57, s96
	v_lshl_add_u64 v[178:179], s[58:59], 0, v[160:161]
	s_add_i32 m0, s85, 0xc000
	ds_read_b128 v[212:215], v164
	ds_read_b128 v[216:219], v164 offset:1024
	ds_read_b128 v[220:223], v164 offset:2048
	ds_read_b128 v[224:227], v164 offset:3072
	ds_read_b128 v[228:231], v164 offset:4096
	ds_read_b128 v[232:235], v164 offset:5120
	ds_read_b128 v[236:239], v164 offset:6144
	ds_read_b128 v[240:243], v164 offset:7168
	global_load_lds_dwordx4 v[178:179], off
	v_lshl_add_u64 v[178:179], s[58:59], 0, v[162:163]
	s_add_i32 m0, s85, 0xe000
	s_nop 0
	global_load_lds_dwordx4 v[178:179], off
	s_waitcnt vmcnt(8)
	s_waitcnt lgkmcnt(0)
	s_barrier
	s_setprio 1
	s_waitcnt lgkmcnt(0)
	v_mfma_f32_16x16x32_bf16 v[124:127], v[170:173], v[212:215], 0
	v_mfma_f32_16x16x32_bf16 v[120:123], v[182:185], v[212:215], 0
	v_mfma_f32_16x16x32_bf16 v[116:119], v[170:173], v[220:223], 0
	v_mfma_f32_16x16x32_bf16 v[112:115], v[182:185], v[220:223], 0
	v_mfma_f32_16x16x32_bf16 v[124:127], v[174:177], v[216:219], v[124:127]
	v_mfma_f32_16x16x32_bf16 v[120:123], v[186:189], v[216:219], v[120:123]
	v_mfma_f32_16x16x32_bf16 v[116:119], v[174:177], v[224:227], v[116:119]
	v_mfma_f32_16x16x32_bf16 v[112:115], v[186:189], v[224:227], v[112:115]
	v_mfma_f32_16x16x32_bf16 v[108:111], v[170:173], v[228:231], 0
	v_mfma_f32_16x16x32_bf16 v[104:107], v[182:185], v[228:231], 0
	v_mfma_f32_16x16x32_bf16 v[100:103], v[170:173], v[236:239], 0
	v_mfma_f32_16x16x32_bf16 v[96:99], v[182:185], v[236:239], 0
	v_mfma_f32_16x16x32_bf16 v[108:111], v[174:177], v[232:235], v[108:111]
	v_mfma_f32_16x16x32_bf16 v[104:107], v[186:189], v[232:235], v[104:107]
	v_mfma_f32_16x16x32_bf16 v[100:103], v[174:177], v[240:243], v[100:103]
	v_mfma_f32_16x16x32_bf16 v[96:99], v[186:189], v[240:243], v[96:99]
	s_setprio 0
	s_setprio 1
	v_mfma_f32_16x16x32_bf16 v[60:63], v[190:193], v[212:215], 0
	v_mfma_f32_16x16x32_bf16 v[56:59], v[198:201], v[212:215], 0
	v_mfma_f32_16x16x32_bf16 v[52:55], v[190:193], v[220:223], 0
	v_mfma_f32_16x16x32_bf16 v[48:51], v[198:201], v[220:223], 0
	v_mfma_f32_16x16x32_bf16 v[60:63], v[194:197], v[216:219], v[60:63]
	v_mfma_f32_16x16x32_bf16 v[56:59], v[208:211], v[216:219], v[56:59]
	v_mfma_f32_16x16x32_bf16 v[52:55], v[194:197], v[224:227], v[52:55]
	v_mfma_f32_16x16x32_bf16 v[48:51], v[208:211], v[224:227], v[48:51]
	v_mfma_f32_16x16x32_bf16 v[44:47], v[190:193], v[228:231], 0
	v_mfma_f32_16x16x32_bf16 v[40:43], v[198:201], v[228:231], 0
	v_mfma_f32_16x16x32_bf16 v[36:39], v[190:193], v[236:239], 0
	v_mfma_f32_16x16x32_bf16 v[32:35], v[198:201], v[236:239], 0
	v_mfma_f32_16x16x32_bf16 v[44:47], v[194:197], v[232:235], v[44:47]
	v_mfma_f32_16x16x32_bf16 v[40:43], v[208:211], v[232:235], v[40:43]
	v_mfma_f32_16x16x32_bf16 v[36:39], v[194:197], v[240:243], v[36:39]
	v_mfma_f32_16x16x32_bf16 v[32:35], v[208:211], v[240:243], v[32:35]
	s_setprio 0
	s_barrier
	s_add_i32 s3, s94, s84
	v_lshl_add_u64 v[178:179], s[60:61], 0, v[130:131]
	s_mov_b32 m0, s3
	ds_read_b128 v[212:215], v164 offset:16384
	ds_read_b128 v[216:219], v164 offset:17408
	ds_read_b128 v[220:223], v164 offset:18432
	ds_read_b128 v[224:227], v164 offset:19456
	ds_read_b128 v[228:231], v164 offset:20480
	ds_read_b128 v[232:235], v164 offset:21504
	ds_read_b128 v[236:239], v164 offset:22528
	ds_read_b128 v[240:243], v164 offset:23552
	global_load_lds_dwordx4 v[178:179], off
	s_add_i32 m0, s3, 0x2000
	s_add_u32 s14, s60, 0x40000
	v_lshl_add_u64 v[202:203], s[60:61], 0, v[134:135]
	s_addc_u32 s15, s61, 0
	s_add_i32 s3, s95, s84
	global_load_lds_dwordx4 v[202:203], off
	v_lshl_add_u64 v[244:245], s[14:15], 0, v[130:131]
	s_mov_b32 m0, s3
	global_load_lds_dwordx4 v[244:245], off
	v_lshl_add_u64 v[244:245], s[14:15], 0, v[134:135]
	s_add_i32 m0, s3, 0x2000
	s_nop 0
	global_load_lds_dwordx4 v[244:245], off
	s_waitcnt vmcnt(6)
	s_waitcnt lgkmcnt(0)
	s_barrier
; #define PG8_STAGE(bufoff, gbase, voff) do { _Pragma("unroll") for (int _i = 0; _i < 2; ++_i) \
;         __builtin_amdgcn_global_load_lds((const unsigned*)((const char*)(gbase) + (voff)[_i]), (PG8_LAS unsigned*)(lds + (bufoff) + ldsw + _i * 8192), 16, 0, 0); } while (0)
; #define PG8_LDA(dst, b, h) do { _Pragma("unroll") for (int m = 0; m < 4; ++m) _Pragma("unroll") for (int k = 0; k < 2; ++k) dst[m][k] = *(const PG8_LAS bf16x8*)(lds + PG8_SA(b, h) + aoff + m * 2048 + k * 1024); } while (0)
; #define PG8_LDB(dst, b, h) do { _Pragma("unroll") for (int n = 0; n < 2; ++n) _Pragma("unroll") for (int k = 0; k < 2; ++k) dst[n][k] = *(const PG8_LAS bf16x8*)(lds + PG8_SB(b, h) + boff + n * 2048 + k * 1024); } while (0)
; #define PG8_MMA(ai, bj, At, Bt) do { __builtin_amdgcn_s_setprio(1); _Pragma("unroll") for (int m = 0; m < 4; ++m) _Pragma("unroll") for (int n = 0; n < 2; ++n) _Pragma("unroll") for (int k = 0; k < 2; ++k) \
;         acc[ai][bj][m][n] = __builtin_amdgcn_mfma_f32_16x16x32_bf16(Bt[n][k], At[m][k], acc[ai][bj][m][n], 0, 0, 0); __builtin_amdgcn_s_setprio(0); } while (0)
; #define PG8_WAIT_V(n) asm volatile("s_waitcnt vmcnt(" #n ")" ::: "memory")
; #define PG8_WAIT_L(n) asm volatile("s_waitcnt lgkmcnt(" #n ")" ::: "memory")
; #define PG8_BAR __builtin_amdgcn_s_barrier()
; #define PG8_SCHED __builtin_amdgcn_sched_barrier(0)
; template <class Epi, class Sched, bool ALIGN_EPI = false, bool SP2 = false>
; __device__ __forceinline__ void gemm_phase(PG8_LAS unsigned char* lds, const Gemm g, const Sched& S, const Epi& E) {
;     ...
;             PG8_WAIT_V(8); PG8_WAIT_L(0); PG8_BAR; PG8_MMA(1, 0, At, B0); PG8_MMA(1, 1, At, B1); PG8_BAR; PG8_SCHED;
;             PG8_LDB(B0, 1, 0); PG8_LDB(B1, 1, 1); PG8_SCHED; PG8_LDA(At, 1, 0); PG8_STAGE(PG8_SA(0, 1), a2 + hstep, voffA);
;             PG8_WAIT_V(8); PG8_WAIT_L(0); PG8_BAR; PG8_MMA(0, 0, At, B0); PG8_MMA(0, 1, At, B1); PG8_BAR; PG8_SCHED;
	s_setprio 1
	s_waitcnt lgkmcnt(0)
	v_mfma_f32_16x16x32_bf16 v[92:95], v[170:173], v[212:215], 0
	v_mfma_f32_16x16x32_bf16 v[88:91], v[182:185], v[212:215], 0
	v_mfma_f32_16x16x32_bf16 v[84:87], v[170:173], v[220:223], 0
	v_mfma_f32_16x16x32_bf16 v[80:83], v[182:185], v[220:223], 0
	v_mfma_f32_16x16x32_bf16 v[92:95], v[174:177], v[216:219], v[92:95]
	v_mfma_f32_16x16x32_bf16 v[88:91], v[186:189], v[216:219], v[88:91]
	v_mfma_f32_16x16x32_bf16 v[84:87], v[174:177], v[224:227], v[84:87]
	v_mfma_f32_16x16x32_bf16 v[80:83], v[186:189], v[224:227], v[80:83]
	v_mfma_f32_16x16x32_bf16 v[76:79], v[170:173], v[228:231], 0
	v_mfma_f32_16x16x32_bf16 v[72:75], v[182:185], v[228:231], 0
	v_mfma_f32_16x16x32_bf16 v[68:71], v[170:173], v[236:239], 0
	v_mfma_f32_16x16x32_bf16 v[64:67], v[182:185], v[236:239], 0
	v_mfma_f32_16x16x32_bf16 v[76:79], v[174:177], v[232:235], v[76:79]
	v_mfma_f32_16x16x32_bf16 v[72:75], v[186:189], v[232:235], v[72:75]
	v_lshl_add_u64 v[244:245], s[62:63], 0, v[128:129]
	s_mov_b32 m0, s85
	s_nop 0
	global_load_lds_dwordx4 v[244:245], off
	v_mfma_f32_16x16x32_bf16 v[68:71], v[174:177], v[240:243], v[68:71]
	v_mfma_f32_16x16x32_bf16 v[64:67], v[186:189], v[240:243], v[64:67]
	s_setprio 0
	s_setprio 1
	v_mfma_f32_16x16x32_bf16 v[28:31], v[190:193], v[212:215], 0
	v_mfma_f32_16x16x32_bf16 v[24:27], v[198:201], v[212:215], 0
	v_mfma_f32_16x16x32_bf16 v[20:23], v[190:193], v[220:223], 0
	v_mfma_f32_16x16x32_bf16 v[16:19], v[198:201], v[220:223], 0
	v_mfma_f32_16x16x32_bf16 v[28:31], v[194:197], v[216:219], v[28:31]
	v_mfma_f32_16x16x32_bf16 v[24:27], v[208:211], v[216:219], v[24:27]
	v_mfma_f32_16x16x32_bf16 v[20:23], v[194:197], v[224:227], v[20:23]
	v_mfma_f32_16x16x32_bf16 v[16:19], v[208:211], v[224:227], v[16:19]
	v_mfma_f32_16x16x32_bf16 v[12:15], v[190:193], v[228:231], 0
	v_mfma_f32_16x16x32_bf16 v[8:11], v[198:201], v[228:231], 0
	v_mfma_f32_16x16x32_bf16 v[4:7], v[190:193], v[236:239], 0
	v_mfma_f32_16x16x32_bf16 v[0:3], v[198:201], v[236:239], 0
	v_mfma_f32_16x16x32_bf16 v[12:15], v[194:197], v[232:235], v[12:15]
	v_mfma_f32_16x16x32_bf16 v[8:11], v[208:211], v[232:235], v[8:11]
	v_lshl_add_u64 v[246:247], s[62:63], 0, v[132:133]
	s_mov_b32 m0, s86
	s_nop 0
	global_load_lds_dwordx4 v[246:247], off
	v_mfma_f32_16x16x32_bf16 v[4:7], v[194:197], v[240:243], v[4:7]
	v_mfma_f32_16x16x32_bf16 v[0:3], v[208:211], v[240:243], v[0:3]
	s_setprio 0
	s_barrier
	s_add_i32 s3, 0, 0x18000
	v_add_u32_e32 v136, s3, v141
	s_add_i32 s33, 0, 0x1c000
	ds_read_b128 v[170:173], v136
	ds_read_b128 v[174:177], v136 offset:1024
	ds_read_b128 v[182:185], v136 offset:2048
	ds_read_b128 v[186:189], v136 offset:3072
	v_add_u32_e32 v136, s33, v141
	ds_read_b128 v[190:193], v136
	ds_read_b128 v[194:197], v136 offset:1024
	ds_read_b128 v[198:201], v136 offset:2048
	ds_read_b128 v[208:211], v136 offset:3072
	s_add_u32 s14, s62, 0x40000
	s_addc_u32 s15, s63, 0
	s_mov_b32 m0, s87
	v_lshl_add_u64 v[248:249], s[14:15], 0, v[128:129]
	ds_read_b128 v[212:215], v164 offset:32768
	ds_read_b128 v[216:219], v164 offset:33792
	ds_read_b128 v[220:223], v164 offset:34816
	ds_read_b128 v[224:227], v164 offset:35840
	ds_read_b128 v[228:231], v164 offset:36864
	ds_read_b128 v[232:235], v164 offset:37888
	ds_read_b128 v[236:239], v164 offset:38912
	ds_read_b128 v[240:243], v164 offset:39936
	global_load_lds_dwordx4 v[248:249], off
	v_lshl_add_u64 v[248:249], s[14:15], 0, v[132:133]
	s_mov_b32 m0, s88
	s_nop 0
	global_load_lds_dwordx4 v[248:249], off
	s_waitcnt vmcnt(8)
	s_waitcnt lgkmcnt(0)
	s_barrier
	s_setprio 1
	s_waitcnt lgkmcnt(0)
	v_mfma_f32_16x16x32_bf16 v[124:127], v[170:173], v[212:215], v[124:127]
	v_mfma_f32_16x16x32_bf16 v[120:123], v[182:185], v[212:215], v[120:123]
	v_mfma_f32_16x16x32_bf16 v[116:119], v[170:173], v[220:223], v[116:119]
	v_mfma_f32_16x16x32_bf16 v[112:115], v[182:185], v[220:223], v[112:115]
	v_mfma_f32_16x16x32_bf16 v[124:127], v[174:177], v[216:219], v[124:127]
	v_mfma_f32_16x16x32_bf16 v[120:123], v[186:189], v[216:219], v[120:123]
	v_mfma_f32_16x16x32_bf16 v[116:119], v[174:177], v[224:227], v[116:119]
	v_mfma_f32_16x16x32_bf16 v[112:115], v[186:189], v[224:227], v[112:115]
	v_mfma_f32_16x16x32_bf16 v[108:111], v[170:173], v[228:231], v[108:111]
	v_mfma_f32_16x16x32_bf16 v[104:107], v[182:185], v[228:231], v[104:107]
	v_mfma_f32_16x16x32_bf16 v[100:103], v[170:173], v[236:239], v[100:103]
	v_mfma_f32_16x16x32_bf16 v[96:99], v[182:185], v[236:239], v[96:99]
	v_mfma_f32_16x16x32_bf16 v[108:111], v[174:177], v[232:235], v[108:111]
	v_mfma_f32_16x16x32_bf16 v[104:107], v[186:189], v[232:235], v[104:107]
	v_mfma_f32_16x16x32_bf16 v[100:103], v[174:177], v[240:243], v[100:103]
	v_mfma_f32_16x16x32_bf16 v[96:99], v[186:189], v[240:243], v[96:99]
	s_setprio 0
	s_setprio 1
	v_mfma_f32_16x16x32_bf16 v[60:63], v[190:193], v[212:215], v[60:63]
	v_mfma_f32_16x16x32_bf16 v[56:59], v[198:201], v[212:215], v[56:59]
	v_mfma_f32_16x16x32_bf16 v[52:55], v[190:193], v[220:223], v[52:55]
	v_mfma_f32_16x16x32_bf16 v[48:51], v[198:201], v[220:223], v[48:51]
	v_mfma_f32_16x16x32_bf16 v[60:63], v[194:197], v[216:219], v[60:63]
	v_mfma_f32_16x16x32_bf16 v[56:59], v[208:211], v[216:219], v[56:59]
	v_mfma_f32_16x16x32_bf16 v[52:55], v[194:197], v[224:227], v[52:55]
	v_mfma_f32_16x16x32_bf16 v[48:51], v[208:211], v[224:227], v[48:51]
	v_mfma_f32_16x16x32_bf16 v[44:47], v[190:193], v[228:231], v[44:47]
	v_mfma_f32_16x16x32_bf16 v[40:43], v[198:201], v[228:231], v[40:43]
	v_mfma_f32_16x16x32_bf16 v[36:39], v[190:193], v[236:239], v[36:39]
	v_mfma_f32_16x16x32_bf16 v[32:35], v[198:201], v[236:239], v[32:35]
	v_mfma_f32_16x16x32_bf16 v[44:47], v[194:197], v[232:235], v[44:47]
	v_mfma_f32_16x16x32_bf16 v[40:43], v[208:211], v[232:235], v[40:43]
	v_mfma_f32_16x16x32_bf16 v[36:39], v[194:197], v[240:243], v[36:39]
	v_mfma_f32_16x16x32_bf16 v[32:35], v[208:211], v[240:243], v[32:35]
	s_setprio 0
	s_barrier
; #define PG8_STAGE(bufoff, gbase, voff) do { _Pragma("unroll") for (int _i = 0; _i < 2; ++_i) \
;         __builtin_amdgcn_global_load_lds((const unsigned*)((const char*)(gbase) + (voff)[_i]), (PG8_LAS unsigned*)(lds + (bufoff) + ldsw + _i * 8192), 16, 0, 0); } while (0)
; #define PG8_LDA(dst, b, h) do { _Pragma("unroll") for (int m = 0; m < 4; ++m) _Pragma("unroll") for (int k = 0; k < 2; ++k) dst[m][k] = *(const PG8_LAS bf16x8*)(lds + PG8_SA(b, h) + aoff + m * 2048 + k * 1024); } while (0)
; #define PG8_LDB(dst, b, h) do { _Pragma("unroll") for (int n = 0; n < 2; ++n) _Pragma("unroll") for (int k = 0; k < 2; ++k) dst[n][k] = *(const PG8_LAS bf16x8*)(lds + PG8_SB(b, h) + boff + n * 2048 + k * 1024); } while (0)
; #define PG8_MMA(ai, bj, At, Bt) do { __builtin_amdgcn_s_setprio(1); _Pragma("unroll") for (int m = 0; m < 4; ++m) _Pragma("unroll") for (int n = 0; n < 2; ++n) _Pragma("unroll") for (int k = 0; k < 2; ++k) \
;         acc[ai][bj][m][n] = __builtin_amdgcn_mfma_f32_16x16x32_bf16(Bt[n][k], At[m][k], acc[ai][bj][m][n], 0, 0, 0); __builtin_amdgcn_s_setprio(0); } while (0)
; #define PG8_WAIT_V(n) asm volatile("s_waitcnt vmcnt(" #n ")" ::: "memory")
; #define PG8_WAIT_L(n) asm volatile("s_waitcnt lgkmcnt(" #n ")" ::: "memory")
; #define PG8_BAR __builtin_amdgcn_s_barrier()
; #define PG8_SCHED __builtin_amdgcn_sched_barrier(0)
; template <class Epi, class Sched, bool ALIGN_EPI = false, bool SP2 = false>
; __device__ __forceinline__ void gemm_phase(PG8_LAS unsigned char* lds, const Gemm g, const Sched& S, const Epi& E) {
;     ...
;             PG8_LDB(B0, 0, 0); PG8_LDB(B1, 0, 1); PG8_SCHED; PG8_LDA(At, 0, 0); PG8_STAGE(PG8_SA(1, 1), a1 + hstep, voffA);
;     ...
;             PG8_LDA(At, 1, 1); PG8_STAGE(PG8_SB(1, 0), b3, voffB); PG8_STAGE(PG8_SB(1, 1), b3 + hstep, voffB); PG8_STAGE(PG8_SA(1, 0), a3, voffA);
;             PG8_WAIT_V(8); PG8_WAIT_L(0); PG8_BAR; PG8_MMA(1, 0, At, B0); PG8_MMA(1, 1, At, B1); PG8_BAR; PG8_SCHED;
	s_add_i32 s3, s3, s84
	v_lshl_add_u64 v[178:179], v[178:179], 0, s[8:9]
	s_mov_b32 m0, s3
	ds_read_b128 v[212:215], v164 offset:49152
	ds_read_b128 v[216:219], v164 offset:50176
	ds_read_b128 v[220:223], v164 offset:51200
	ds_read_b128 v[224:227], v164 offset:52224
	ds_read_b128 v[228:231], v164 offset:53248
	ds_read_b128 v[232:235], v164 offset:54272
	ds_read_b128 v[236:239], v164 offset:55296
	ds_read_b128 v[240:243], v164 offset:56320
	global_load_lds_dwordx4 v[178:179], off
	s_add_i32 m0, s3, 0x2000
	s_add_u32 s14, s60, 0x40080
	v_lshl_add_u64 v[178:179], v[202:203], 0, s[8:9]
	s_addc_u32 s15, s61, 0
	s_add_i32 s3, s33, s84
	global_load_lds_dwordx4 v[178:179], off
	v_lshl_add_u64 v[178:179], s[14:15], 0, v[130:131]
	s_mov_b32 m0, s3
	s_nop 0
	global_load_lds_dwordx4 v[178:179], off
	v_lshl_add_u64 v[178:179], s[14:15], 0, v[134:135]
	s_add_i32 m0, s3, 0x2000
	s_nop 0
	global_load_lds_dwordx4 v[178:179], off
	s_waitcnt vmcnt(6)
	s_waitcnt lgkmcnt(0)
	s_barrier
	s_setprio 1
	s_waitcnt lgkmcnt(0)
	v_mfma_f32_16x16x32_bf16 v[92:95], v[170:173], v[212:215], v[92:95]
	v_mfma_f32_16x16x32_bf16 v[88:91], v[182:185], v[212:215], v[88:91]
	v_mfma_f32_16x16x32_bf16 v[84:87], v[170:173], v[220:223], v[84:87]
	v_mfma_f32_16x16x32_bf16 v[80:83], v[182:185], v[220:223], v[80:83]
	v_mfma_f32_16x16x32_bf16 v[92:95], v[174:177], v[216:219], v[92:95]
	v_mfma_f32_16x16x32_bf16 v[88:91], v[186:189], v[216:219], v[88:91]
	v_mfma_f32_16x16x32_bf16 v[84:87], v[174:177], v[224:227], v[84:87]
	v_mfma_f32_16x16x32_bf16 v[80:83], v[186:189], v[224:227], v[80:83]
	v_mfma_f32_16x16x32_bf16 v[76:79], v[170:173], v[228:231], v[76:79]
	v_mfma_f32_16x16x32_bf16 v[72:75], v[182:185], v[228:231], v[72:75]
	v_mfma_f32_16x16x32_bf16 v[68:71], v[170:173], v[236:239], v[68:71]
	v_mfma_f32_16x16x32_bf16 v[64:67], v[182:185], v[236:239], v[64:67]
	v_mfma_f32_16x16x32_bf16 v[76:79], v[174:177], v[232:235], v[76:79]
	v_mfma_f32_16x16x32_bf16 v[72:75], v[186:189], v[232:235], v[72:75]
	v_lshl_add_u64 v[178:179], v[244:245], 0, s[8:9]
	s_mov_b32 m0, s90
	s_nop 0
	global_load_lds_dwordx4 v[178:179], off
	v_mfma_f32_16x16x32_bf16 v[68:71], v[174:177], v[240:243], v[68:71]
	v_mfma_f32_16x16x32_bf16 v[64:67], v[186:189], v[240:243], v[64:67]
	s_setprio 0
	s_setprio 1
	v_mfma_f32_16x16x32_bf16 v[28:31], v[190:193], v[212:215], v[28:31]
	v_mfma_f32_16x16x32_bf16 v[24:27], v[198:201], v[212:215], v[24:27]
	v_mfma_f32_16x16x32_bf16 v[20:23], v[190:193], v[220:223], v[20:23]
	v_mfma_f32_16x16x32_bf16 v[16:19], v[198:201], v[220:223], v[16:19]
	v_mfma_f32_16x16x32_bf16 v[28:31], v[194:197], v[216:219], v[28:31]
	v_mfma_f32_16x16x32_bf16 v[24:27], v[208:211], v[216:219], v[24:27]
	v_mfma_f32_16x16x32_bf16 v[20:23], v[194:197], v[224:227], v[20:23]
	v_mfma_f32_16x16x32_bf16 v[16:19], v[208:211], v[224:227], v[16:19]
	v_mfma_f32_16x16x32_bf16 v[12:15], v[190:193], v[228:231], v[12:15]
	v_mfma_f32_16x16x32_bf16 v[8:11], v[198:201], v[228:231], v[8:11]
	v_mfma_f32_16x16x32_bf16 v[4:7], v[190:193], v[236:239], v[4:7]
	v_mfma_f32_16x16x32_bf16 v[0:3], v[198:201], v[236:239], v[0:3]
	v_mfma_f32_16x16x32_bf16 v[12:15], v[194:197], v[232:235], v[12:15]
	v_mfma_f32_16x16x32_bf16 v[8:11], v[208:211], v[232:235], v[8:11]
	v_lshl_add_u64 v[178:179], v[246:247], 0, s[8:9]
	s_mov_b32 m0, s91
	s_nop 0
	global_load_lds_dwordx4 v[178:179], off
	v_mfma_f32_16x16x32_bf16 v[4:7], v[194:197], v[240:243], v[4:7]
	v_mfma_f32_16x16x32_bf16 v[0:3], v[208:211], v[240:243], v[0:3]
	s_setprio 0
	s_barrier
	s_add_i32 vcc_lo, vcc_lo, 2
	s_add_u32 s58, s58, 0x100
	s_addc_u32 s59, s59, 0
	s_add_u32 s96, s96, 0x100
	s_addc_u32 s97, s97, 0
.LBB0_459:
	ds_read_b128 v[170:173], v165
	ds_read_b128 v[174:177], v165 offset:1024
	ds_read_b128 v[182:185], v165 offset:2048
	ds_read_b128 v[186:189], v165 offset:3072
	ds_read_b128 v[190:193], v168
	ds_read_b128 v[194:197], v168 offset:1024
	ds_read_b128 v[198:201], v168 offset:2048
	ds_read_b128 v[208:211], v168 offset:3072
	s_add_u32 s3, s58, 0xfffc0080
	s_addc_u32 s14, s59, -1
	s_cmp_eq_u32 vcc_lo, 12
	s_cselect_b32 s63, s49, s14
	s_cselect_b32 s62, s55, s3
	s_cselect_b32 s61, s45, s97
	s_cselect_b32 s60, s57, s96
	v_lshl_add_u64 v[178:179], s[58:59], 0, v[160:161]
	s_add_i32 m0, s85, 0xc000
	ds_read_b128 v[212:215], v164
	ds_read_b128 v[216:219], v164 offset:1024
	ds_read_b128 v[220:223], v164 offset:2048
	ds_read_b128 v[224:227], v164 offset:3072
	ds_read_b128 v[228:231], v164 offset:4096
	ds_read_b128 v[232:235], v164 offset:5120
	ds_read_b128 v[236:239], v164 offset:6144
	ds_read_b128 v[240:243], v164 offset:7168
	global_load_lds_dwordx4 v[178:179], off
	v_lshl_add_u64 v[178:179], s[58:59], 0, v[162:163]
	s_add_i32 m0, s85, 0xe000
	s_nop 0
	global_load_lds_dwordx4 v[178:179], off
	s_waitcnt vmcnt(8)
	s_waitcnt lgkmcnt(0)
	s_barrier
; #define PG8_STAGE(bufoff, gbase, voff) do { _Pragma("unroll") for (int _i = 0; _i < 2; ++_i) \
;         __builtin_amdgcn_global_load_lds((const unsigned*)((const char*)(gbase) + (voff)[_i]), (PG8_LAS unsigned*)(lds + (bufoff) + ldsw + _i * 8192), 16, 0, 0); } while (0)
; #define PG8_LDA(dst, b, h) do { _Pragma("unroll") for (int m = 0; m < 4; ++m) _Pragma("unroll") for (int k = 0; k < 2; ++k) dst[m][k] = *(const PG8_LAS bf16x8*)(lds + PG8_SA(b, h) + aoff + m * 2048 + k * 1024); } while (0)
; #define PG8_MMA(ai, bj, At, Bt) do { __builtin_amdgcn_s_setprio(1); _Pragma("unroll") for (int m = 0; m < 4; ++m) _Pragma("unroll") for (int n = 0; n < 2; ++n) _Pragma("unroll") for (int k = 0; k < 2; ++k) \
;         acc[ai][bj][m][n] = __builtin_amdgcn_mfma_f32_16x16x32_bf16(Bt[n][k], At[m][k], acc[ai][bj][m][n], 0, 0, 0); __builtin_amdgcn_s_setprio(0); } while (0)
; #define PG8_WAIT_V(n) asm volatile("s_waitcnt vmcnt(" #n ")" ::: "memory")
; #define PG8_WAIT_L(n) asm volatile("s_waitcnt lgkmcnt(" #n ")" ::: "memory")
; #define PG8_BAR __builtin_amdgcn_s_barrier()
; #define PG8_SCHED __builtin_amdgcn_sched_barrier(0)
; template <class Epi, class Sched, bool ALIGN_EPI = false, bool SP2 = false>
; __device__ __forceinline__ void gemm_phase(PG8_LAS unsigned char* lds, const Gemm g, const Sched& S, const Epi& E) {
;     ...
;             PG8_WAIT_V(8); PG8_WAIT_L(0); PG8_BAR; PG8_MMA(0, 0, At, B0); PG8_MMA(0, 1, At, B1); PG8_BAR; PG8_SCHED;
;             PG8_LDA(At, 0, 1); PG8_STAGE(PG8_SB(0, 0), b2, voffB); PG8_STAGE(PG8_SB(0, 1), b2 + hstep, voffB); PG8_STAGE(PG8_SA(0, 0), a2, voffA);
;             PG8_WAIT_V(8); PG8_WAIT_L(0); PG8_BAR; PG8_MMA(1, 0, At, B0); PG8_MMA(1, 1, At, B1); PG8_BAR; PG8_SCHED;
	s_setprio 1
	s_waitcnt lgkmcnt(0)
	v_mfma_f32_16x16x32_bf16 v[124:127], v[170:173], v[212:215], v[124:127]
	v_mfma_f32_16x16x32_bf16 v[120:123], v[182:185], v[212:215], v[120:123]
	v_mfma_f32_16x16x32_bf16 v[116:119], v[170:173], v[220:223], v[116:119]
	v_mfma_f32_16x16x32_bf16 v[112:115], v[182:185], v[220:223], v[112:115]
	v_mfma_f32_16x16x32_bf16 v[124:127], v[174:177], v[216:219], v[124:127]
	v_mfma_f32_16x16x32_bf16 v[120:123], v[186:189], v[216:219], v[120:123]
	v_mfma_f32_16x16x32_bf16 v[116:119], v[174:177], v[224:227], v[116:119]
	v_mfma_f32_16x16x32_bf16 v[112:115], v[186:189], v[224:227], v[112:115]
	v_mfma_f32_16x16x32_bf16 v[108:111], v[170:173], v[228:231], v[108:111]
	v_mfma_f32_16x16x32_bf16 v[104:107], v[182:185], v[228:231], v[104:107]
	v_mfma_f32_16x16x32_bf16 v[100:103], v[170:173], v[236:239], v[100:103]
	v_mfma_f32_16x16x32_bf16 v[96:99], v[182:185], v[236:239], v[96:99]
	v_mfma_f32_16x16x32_bf16 v[108:111], v[174:177], v[232:235], v[108:111]
	v_mfma_f32_16x16x32_bf16 v[104:107], v[186:189], v[232:235], v[104:107]
	v_mfma_f32_16x16x32_bf16 v[100:103], v[174:177], v[240:243], v[100:103]
	v_mfma_f32_16x16x32_bf16 v[96:99], v[186:189], v[240:243], v[96:99]
	s_setprio 0
	s_setprio 1
	v_mfma_f32_16x16x32_bf16 v[60:63], v[190:193], v[212:215], v[60:63]
	v_mfma_f32_16x16x32_bf16 v[56:59], v[198:201], v[212:215], v[56:59]
	v_mfma_f32_16x16x32_bf16 v[52:55], v[190:193], v[220:223], v[52:55]
	v_mfma_f32_16x16x32_bf16 v[48:51], v[198:201], v[220:223], v[48:51]
	v_mfma_f32_16x16x32_bf16 v[60:63], v[194:197], v[216:219], v[60:63]
	v_mfma_f32_16x16x32_bf16 v[56:59], v[208:211], v[216:219], v[56:59]
	v_mfma_f32_16x16x32_bf16 v[52:55], v[194:197], v[224:227], v[52:55]
	v_mfma_f32_16x16x32_bf16 v[48:51], v[208:211], v[224:227], v[48:51]
	v_mfma_f32_16x16x32_bf16 v[44:47], v[190:193], v[228:231], v[44:47]
	v_mfma_f32_16x16x32_bf16 v[40:43], v[198:201], v[228:231], v[40:43]
	v_mfma_f32_16x16x32_bf16 v[36:39], v[190:193], v[236:239], v[36:39]
	v_mfma_f32_16x16x32_bf16 v[32:35], v[198:201], v[236:239], v[32:35]
	v_mfma_f32_16x16x32_bf16 v[44:47], v[194:197], v[232:235], v[44:47]
	v_mfma_f32_16x16x32_bf16 v[40:43], v[208:211], v[232:235], v[40:43]
	v_mfma_f32_16x16x32_bf16 v[36:39], v[194:197], v[240:243], v[36:39]
	v_mfma_f32_16x16x32_bf16 v[32:35], v[208:211], v[240:243], v[32:35]
	s_setprio 0
	s_barrier
	s_add_i32 s3, s94, s84
	v_lshl_add_u64 v[178:179], s[60:61], 0, v[130:131]
	s_mov_b32 m0, s3
	ds_read_b128 v[212:215], v164 offset:16384
	ds_read_b128 v[216:219], v164 offset:17408
	ds_read_b128 v[220:223], v164 offset:18432
	ds_read_b128 v[224:227], v164 offset:19456
	ds_read_b128 v[228:231], v164 offset:20480
	ds_read_b128 v[232:235], v164 offset:21504
	ds_read_b128 v[236:239], v164 offset:22528
	ds_read_b128 v[240:243], v164 offset:23552
	global_load_lds_dwordx4 v[178:179], off
	s_add_i32 m0, s3, 0x2000
	s_add_u32 s14, s60, 0x40000
	v_lshl_add_u64 v[202:203], s[60:61], 0, v[134:135]
	s_addc_u32 s15, s61, 0
	s_add_i32 s3, s95, s84
	global_load_lds_dwordx4 v[202:203], off
	v_lshl_add_u64 v[244:245], s[14:15], 0, v[130:131]
	s_mov_b32 m0, s3
	global_load_lds_dwordx4 v[244:245], off
	v_lshl_add_u64 v[244:245], s[14:15], 0, v[134:135]
	s_add_i32 m0, s3, 0x2000
	s_nop 0
	global_load_lds_dwordx4 v[244:245], off
	s_waitcnt vmcnt(6)
	s_waitcnt lgkmcnt(0)
	s_barrier
	s_setprio 1
	s_waitcnt lgkmcnt(0)
	v_mfma_f32_16x16x32_bf16 v[92:95], v[170:173], v[212:215], v[92:95]
	v_mfma_f32_16x16x32_bf16 v[88:91], v[182:185], v[212:215], v[88:91]
	v_mfma_f32_16x16x32_bf16 v[84:87], v[170:173], v[220:223], v[84:87]
	v_mfma_f32_16x16x32_bf16 v[80:83], v[182:185], v[220:223], v[80:83]
	v_mfma_f32_16x16x32_bf16 v[92:95], v[174:177], v[216:219], v[92:95]
	v_mfma_f32_16x16x32_bf16 v[88:91], v[186:189], v[216:219], v[88:91]
	v_mfma_f32_16x16x32_bf16 v[84:87], v[174:177], v[224:227], v[84:87]
	v_mfma_f32_16x16x32_bf16 v[80:83], v[186:189], v[224:227], v[80:83]
	v_mfma_f32_16x16x32_bf16 v[76:79], v[170:173], v[228:231], v[76:79]
	v_mfma_f32_16x16x32_bf16 v[72:75], v[182:185], v[228:231], v[72:75]
	v_mfma_f32_16x16x32_bf16 v[68:71], v[170:173], v[236:239], v[68:71]
	v_mfma_f32_16x16x32_bf16 v[64:67], v[182:185], v[236:239], v[64:67]
	v_mfma_f32_16x16x32_bf16 v[76:79], v[174:177], v[232:235], v[76:79]
	v_mfma_f32_16x16x32_bf16 v[72:75], v[186:189], v[232:235], v[72:75]
	v_lshl_add_u64 v[244:245], s[62:63], 0, v[128:129]
	s_mov_b32 m0, s85
	s_nop 0
	global_load_lds_dwordx4 v[244:245], off
	v_mfma_f32_16x16x32_bf16 v[68:71], v[174:177], v[240:243], v[68:71]
	v_mfma_f32_16x16x32_bf16 v[64:67], v[186:189], v[240:243], v[64:67]
	s_setprio 0
	s_setprio 1
	v_mfma_f32_16x16x32_bf16 v[28:31], v[190:193], v[212:215], v[28:31]
	v_mfma_f32_16x16x32_bf16 v[24:27], v[198:201], v[212:215], v[24:27]
	v_mfma_f32_16x16x32_bf16 v[20:23], v[190:193], v[220:223], v[20:23]
	v_mfma_f32_16x16x32_bf16 v[16:19], v[198:201], v[220:223], v[16:19]
	v_mfma_f32_16x16x32_bf16 v[28:31], v[194:197], v[216:219], v[28:31]
	v_mfma_f32_16x16x32_bf16 v[24:27], v[208:211], v[216:219], v[24:27]
	v_mfma_f32_16x16x32_bf16 v[20:23], v[194:197], v[224:227], v[20:23]
	v_mfma_f32_16x16x32_bf16 v[16:19], v[208:211], v[224:227], v[16:19]
	v_mfma_f32_16x16x32_bf16 v[12:15], v[190:193], v[228:231], v[12:15]
	v_mfma_f32_16x16x32_bf16 v[8:11], v[198:201], v[228:231], v[8:11]
	v_mfma_f32_16x16x32_bf16 v[4:7], v[190:193], v[236:239], v[4:7]
	v_mfma_f32_16x16x32_bf16 v[0:3], v[198:201], v[236:239], v[0:3]
	v_mfma_f32_16x16x32_bf16 v[12:15], v[194:197], v[232:235], v[12:15]
	v_mfma_f32_16x16x32_bf16 v[8:11], v[208:211], v[232:235], v[8:11]
	v_lshl_add_u64 v[246:247], s[62:63], 0, v[132:133]
	s_mov_b32 m0, s86
	s_nop 0
	global_load_lds_dwordx4 v[246:247], off
	v_mfma_f32_16x16x32_bf16 v[4:7], v[194:197], v[240:243], v[4:7]
	v_mfma_f32_16x16x32_bf16 v[0:3], v[208:211], v[240:243], v[0:3]
	s_setprio 0
	s_barrier
; #define PG8_STAGE(bufoff, gbase, voff) do { _Pragma("unroll") for (int _i = 0; _i < 2; ++_i) \
;         __builtin_amdgcn_global_load_lds((const unsigned*)((const char*)(gbase) + (voff)[_i]), (PG8_LAS unsigned*)(lds + (bufoff) + ldsw + _i * 8192), 16, 0, 0); } while (0)
; #define PG8_LDA(dst, b, h) do { _Pragma("unroll") for (int m = 0; m < 4; ++m) _Pragma("unroll") for (int k = 0; k < 2; ++k) dst[m][k] = *(const PG8_LAS bf16x8*)(lds + PG8_SA(b, h) + aoff + m * 2048 + k * 1024); } while (0)
; #define PG8_LDB(dst, b, h) do { _Pragma("unroll") for (int n = 0; n < 2; ++n) _Pragma("unroll") for (int k = 0; k < 2; ++k) dst[n][k] = *(const PG8_LAS bf16x8*)(lds + PG8_SB(b, h) + boff + n * 2048 + k * 1024); } while (0)
; #define PG8_MMA(ai, bj, At, Bt) do { __builtin_amdgcn_s_setprio(1); _Pragma("unroll") for (int m = 0; m < 4; ++m) _Pragma("unroll") for (int n = 0; n < 2; ++n) _Pragma("unroll") for (int k = 0; k < 2; ++k) \
;         acc[ai][bj][m][n] = __builtin_amdgcn_mfma_f32_16x16x32_bf16(Bt[n][k], At[m][k], acc[ai][bj][m][n], 0, 0, 0); __builtin_amdgcn_s_setprio(0); } while (0)
; #define PG8_WAIT_V(n) asm volatile("s_waitcnt vmcnt(" #n ")" ::: "memory")
; #define PG8_WAIT_L(n) asm volatile("s_waitcnt lgkmcnt(" #n ")" ::: "memory")
; #define PG8_BAR __builtin_amdgcn_s_barrier()
; #define PG8_SCHED __builtin_amdgcn_sched_barrier(0)
; template <class Epi, class Sched, bool ALIGN_EPI = false, bool SP2 = false>
; __device__ __forceinline__ void gemm_phase(PG8_LAS unsigned char* lds, const Gemm g, const Sched& S, const Epi& E) {
;     ...
;             PG8_LDB(B0, 1, 0); PG8_LDB(B1, 1, 1); PG8_SCHED; PG8_LDA(At, 1, 0); PG8_STAGE(PG8_SA(0, 1), a2 + hstep, voffA);
;             PG8_WAIT_V(8); PG8_WAIT_L(0); PG8_BAR; PG8_MMA(0, 0, At, B0); PG8_MMA(0, 1, At, B1); PG8_BAR; PG8_SCHED;
	s_add_i32 s3, 0, 0x18000
	v_add_u32_e32 v136, s3, v141
	s_add_i32 s33, 0, 0x1c000
	ds_read_b128 v[170:173], v136
	ds_read_b128 v[174:177], v136 offset:1024
	ds_read_b128 v[182:185], v136 offset:2048
	ds_read_b128 v[186:189], v136 offset:3072
	v_add_u32_e32 v136, s33, v141
	ds_read_b128 v[190:193], v136
	ds_read_b128 v[194:197], v136 offset:1024
	ds_read_b128 v[198:201], v136 offset:2048
	ds_read_b128 v[208:211], v136 offset:3072
	s_add_u32 s14, s62, 0x40000
	s_addc_u32 s15, s63, 0
	s_mov_b32 m0, s87
	v_lshl_add_u64 v[248:249], s[14:15], 0, v[128:129]
	ds_read_b128 v[212:215], v164 offset:32768
	ds_read_b128 v[216:219], v164 offset:33792
	ds_read_b128 v[220:223], v164 offset:34816
	ds_read_b128 v[224:227], v164 offset:35840
	ds_read_b128 v[228:231], v164 offset:36864
	ds_read_b128 v[232:235], v164 offset:37888
	ds_read_b128 v[236:239], v164 offset:38912
	ds_read_b128 v[240:243], v164 offset:39936
	global_load_lds_dwordx4 v[248:249], off
	v_lshl_add_u64 v[248:249], s[14:15], 0, v[132:133]
	s_mov_b32 m0, s88
	s_nop 0
	global_load_lds_dwordx4 v[248:249], off
	s_waitcnt vmcnt(8)
	s_waitcnt lgkmcnt(0)
	s_barrier
	s_setprio 1
	s_waitcnt lgkmcnt(0)
	v_mfma_f32_16x16x32_bf16 v[124:127], v[170:173], v[212:215], v[124:127]
	v_mfma_f32_16x16x32_bf16 v[120:123], v[182:185], v[212:215], v[120:123]
	v_mfma_f32_16x16x32_bf16 v[116:119], v[170:173], v[220:223], v[116:119]
	v_mfma_f32_16x16x32_bf16 v[112:115], v[182:185], v[220:223], v[112:115]
	v_mfma_f32_16x16x32_bf16 v[124:127], v[174:177], v[216:219], v[124:127]
	v_mfma_f32_16x16x32_bf16 v[120:123], v[186:189], v[216:219], v[120:123]
	v_mfma_f32_16x16x32_bf16 v[116:119], v[174:177], v[224:227], v[116:119]
	v_mfma_f32_16x16x32_bf16 v[112:115], v[186:189], v[224:227], v[112:115]
	v_mfma_f32_16x16x32_bf16 v[108:111], v[170:173], v[228:231], v[108:111]
	v_mfma_f32_16x16x32_bf16 v[104:107], v[182:185], v[228:231], v[104:107]
	v_mfma_f32_16x16x32_bf16 v[100:103], v[170:173], v[236:239], v[100:103]
	v_mfma_f32_16x16x32_bf16 v[96:99], v[182:185], v[236:239], v[96:99]
	v_mfma_f32_16x16x32_bf16 v[108:111], v[174:177], v[232:235], v[108:111]
	v_mfma_f32_16x16x32_bf16 v[104:107], v[186:189], v[232:235], v[104:107]
	v_mfma_f32_16x16x32_bf16 v[100:103], v[174:177], v[240:243], v[100:103]
	v_mfma_f32_16x16x32_bf16 v[96:99], v[186:189], v[240:243], v[96:99]
	s_setprio 0
	s_setprio 1
	v_mfma_f32_16x16x32_bf16 v[60:63], v[190:193], v[212:215], v[60:63]
	v_mfma_f32_16x16x32_bf16 v[56:59], v[198:201], v[212:215], v[56:59]
	v_mfma_f32_16x16x32_bf16 v[52:55], v[190:193], v[220:223], v[52:55]
	v_mfma_f32_16x16x32_bf16 v[48:51], v[198:201], v[220:223], v[48:51]
	v_mfma_f32_16x16x32_bf16 v[60:63], v[194:197], v[216:219], v[60:63]
	v_mfma_f32_16x16x32_bf16 v[56:59], v[208:211], v[216:219], v[56:59]
	v_mfma_f32_16x16x32_bf16 v[52:55], v[194:197], v[224:227], v[52:55]
	v_mfma_f32_16x16x32_bf16 v[48:51], v[208:211], v[224:227], v[48:51]
	v_mfma_f32_16x16x32_bf16 v[44:47], v[190:193], v[228:231], v[44:47]
	v_mfma_f32_16x16x32_bf16 v[40:43], v[198:201], v[228:231], v[40:43]
	v_mfma_f32_16x16x32_bf16 v[36:39], v[190:193], v[236:239], v[36:39]
	v_mfma_f32_16x16x32_bf16 v[32:35], v[198:201], v[236:239], v[32:35]
	v_mfma_f32_16x16x32_bf16 v[44:47], v[194:197], v[232:235], v[44:47]
	v_mfma_f32_16x16x32_bf16 v[40:43], v[208:211], v[232:235], v[40:43]
	v_mfma_f32_16x16x32_bf16 v[36:39], v[194:197], v[240:243], v[36:39]
	v_mfma_f32_16x16x32_bf16 v[32:35], v[208:211], v[240:243], v[32:35]
	s_setprio 0
	s_barrier
; #define PG8_STAGE(bufoff, gbase, voff) do { _Pragma("unroll") for (int _i = 0; _i < 2; ++_i) \
;         __builtin_amdgcn_global_load_lds((const unsigned*)((const char*)(gbase) + (voff)[_i]), (PG8_LAS unsigned*)(lds + (bufoff) + ldsw + _i * 8192), 16, 0, 0); } while (0)
; #define PG8_LDA(dst, b, h) do { _Pragma("unroll") for (int m = 0; m < 4; ++m) _Pragma("unroll") for (int k = 0; k < 2; ++k) dst[m][k] = *(const PG8_LAS bf16x8*)(lds + PG8_SA(b, h) + aoff + m * 2048 + k * 1024); } while (0)
; #define PG8_MMA(ai, bj, At, Bt) do { __builtin_amdgcn_s_setprio(1); _Pragma("unroll") for (int m = 0; m < 4; ++m) _Pragma("unroll") for (int n = 0; n < 2; ++n) _Pragma("unroll") for (int k = 0; k < 2; ++k) \
;         acc[ai][bj][m][n] = __builtin_amdgcn_mfma_f32_16x16x32_bf16(Bt[n][k], At[m][k], acc[ai][bj][m][n], 0, 0, 0); __builtin_amdgcn_s_setprio(0); } while (0)
; #define PG8_WAIT_V(n) asm volatile("s_waitcnt vmcnt(" #n ")" ::: "memory")
; #define PG8_WAIT_L(n) asm volatile("s_waitcnt lgkmcnt(" #n ")" ::: "memory")
; #define PG8_BAR __builtin_amdgcn_s_barrier()
; #define PG8_SCHED __builtin_amdgcn_sched_barrier(0)
; template <class Epi, class Sched, bool ALIGN_EPI = false, bool SP2 = false>
; __device__ __forceinline__ void gemm_phase(PG8_LAS unsigned char* lds, const Gemm g, const Sched& S, const Epi& E) {
;     ...
;             PG8_LDA(At, 1, 1); PG8_STAGE(PG8_SB(1, 0), b3, voffB); PG8_STAGE(PG8_SB(1, 1), b3 + hstep, voffB); PG8_STAGE(PG8_SA(1, 0), a3, voffA);
;             PG8_WAIT_V(8); PG8_WAIT_L(0); PG8_BAR; PG8_MMA(1, 0, At, B0); PG8_MMA(1, 1, At, B1); PG8_BAR; PG8_SCHED;
;     ...
;         if constexpr (ALIGN_EPI) { if (wr == 0) PG8_BAR; }
	s_add_i32 s3, s3, s84
	v_lshl_add_u64 v[178:179], v[178:179], 0, s[8:9]
	s_mov_b32 m0, s3
	ds_read_b128 v[212:215], v164 offset:49152
	ds_read_b128 v[216:219], v164 offset:50176
	ds_read_b128 v[220:223], v164 offset:51200
	ds_read_b128 v[224:227], v164 offset:52224
	ds_read_b128 v[228:231], v164 offset:53248
	ds_read_b128 v[232:235], v164 offset:54272
	ds_read_b128 v[236:239], v164 offset:55296
	ds_read_b128 v[240:243], v164 offset:56320
	global_load_lds_dwordx4 v[178:179], off
	s_add_i32 m0, s3, 0x2000
	s_add_u32 s14, s60, 0x40080
	v_lshl_add_u64 v[178:179], v[202:203], 0, s[8:9]
	s_addc_u32 s15, s61, 0
	s_add_i32 s3, s33, s84
	global_load_lds_dwordx4 v[178:179], off
	v_lshl_add_u64 v[178:179], s[14:15], 0, v[130:131]
	s_mov_b32 m0, s3
	s_nop 0
	global_load_lds_dwordx4 v[178:179], off
	v_lshl_add_u64 v[178:179], s[14:15], 0, v[134:135]
	s_add_i32 m0, s3, 0x2000
	s_nop 0
	global_load_lds_dwordx4 v[178:179], off
	s_waitcnt vmcnt(6)
	s_waitcnt lgkmcnt(0)
	s_barrier
	s_setprio 1
	s_waitcnt lgkmcnt(0)
	v_mfma_f32_16x16x32_bf16 v[92:95], v[170:173], v[212:215], v[92:95]
	v_mfma_f32_16x16x32_bf16 v[88:91], v[182:185], v[212:215], v[88:91]
	v_mfma_f32_16x16x32_bf16 v[84:87], v[170:173], v[220:223], v[84:87]
	v_mfma_f32_16x16x32_bf16 v[80:83], v[182:185], v[220:223], v[80:83]
	v_mfma_f32_16x16x32_bf16 v[92:95], v[174:177], v[216:219], v[92:95]
	v_mfma_f32_16x16x32_bf16 v[88:91], v[186:189], v[216:219], v[88:91]
	v_mfma_f32_16x16x32_bf16 v[84:87], v[174:177], v[224:227], v[84:87]
	v_mfma_f32_16x16x32_bf16 v[80:83], v[186:189], v[224:227], v[80:83]
	v_mfma_f32_16x16x32_bf16 v[76:79], v[170:173], v[228:231], v[76:79]
	v_mfma_f32_16x16x32_bf16 v[72:75], v[182:185], v[228:231], v[72:75]
	v_mfma_f32_16x16x32_bf16 v[68:71], v[170:173], v[236:239], v[68:71]
	v_mfma_f32_16x16x32_bf16 v[64:67], v[182:185], v[236:239], v[64:67]
	v_mfma_f32_16x16x32_bf16 v[76:79], v[174:177], v[232:235], v[76:79]
	v_mfma_f32_16x16x32_bf16 v[72:75], v[186:189], v[232:235], v[72:75]
	v_lshl_add_u64 v[178:179], v[244:245], 0, s[8:9]
	s_mov_b32 m0, s90
	s_nop 0
	global_load_lds_dwordx4 v[178:179], off
	v_mfma_f32_16x16x32_bf16 v[68:71], v[174:177], v[240:243], v[68:71]
	v_mfma_f32_16x16x32_bf16 v[64:67], v[186:189], v[240:243], v[64:67]
	s_setprio 0
	s_setprio 1
	v_mfma_f32_16x16x32_bf16 v[28:31], v[190:193], v[212:215], v[28:31]
	v_mfma_f32_16x16x32_bf16 v[24:27], v[198:201], v[212:215], v[24:27]
	v_mfma_f32_16x16x32_bf16 v[20:23], v[190:193], v[220:223], v[20:23]
	v_mfma_f32_16x16x32_bf16 v[16:19], v[198:201], v[220:223], v[16:19]
	v_mfma_f32_16x16x32_bf16 v[28:31], v[194:197], v[216:219], v[28:31]
	v_mfma_f32_16x16x32_bf16 v[24:27], v[208:211], v[216:219], v[24:27]
	v_mfma_f32_16x16x32_bf16 v[20:23], v[194:197], v[224:227], v[20:23]
	v_mfma_f32_16x16x32_bf16 v[16:19], v[208:211], v[224:227], v[16:19]
	v_mfma_f32_16x16x32_bf16 v[12:15], v[190:193], v[228:231], v[12:15]
	v_mfma_f32_16x16x32_bf16 v[8:11], v[198:201], v[228:231], v[8:11]
	v_mfma_f32_16x16x32_bf16 v[4:7], v[190:193], v[236:239], v[4:7]
	v_mfma_f32_16x16x32_bf16 v[0:3], v[198:201], v[236:239], v[0:3]
	v_mfma_f32_16x16x32_bf16 v[12:15], v[194:197], v[232:235], v[12:15]
	v_mfma_f32_16x16x32_bf16 v[8:11], v[208:211], v[232:235], v[8:11]
	v_lshl_add_u64 v[178:179], v[246:247], 0, s[8:9]
	s_mov_b32 m0, s91
	s_nop 0
	global_load_lds_dwordx4 v[178:179], off
	v_mfma_f32_16x16x32_bf16 v[4:7], v[194:197], v[240:243], v[4:7]
	v_mfma_f32_16x16x32_bf16 v[0:3], v[208:211], v[240:243], v[0:3]
	s_setprio 0
	s_barrier
	s_add_i32 vcc_lo, vcc_lo, 2
	s_add_u32 s58, s58, 0x100
	s_addc_u32 s59, s59, 0
	s_add_u32 s96, s96, 0x100
	s_addc_u32 s97, s97, 0
	s_cmp_gt_u32 vcc_lo, 13
	s_cbranch_scc0 .LBB0_459
	s_and_b64 vcc, exec, s[10:11]
	s_cbranch_vccz .LBB0_462
	s_barrier

; #define PG8_STAGE(bufoff, gbase, voff) do { _Pragma("unroll") for (int _i = 0; _i < 2; ++_i) \
;         __builtin_amdgcn_global_load_lds((const unsigned*)((const char*)(gbase) + (voff)[_i]), (PG8_LAS unsigned*)(lds + (bufoff) + ldsw + _i * 8192), 16, 0, 0); } while (0)
; #define PG8_LDA(dst, b, h) do { _Pragma("unroll") for (int m = 0; m < 4; ++m) _Pragma("unroll") for (int k = 0; k < 2; ++k) dst[m][k] = *(const PG8_LAS bf16x8*)(lds + PG8_SA(b, h) + aoff + m * 2048 + k * 1024); } while (0)
; #define PG8_LDB(dst, b, h) do { _Pragma("unroll") for (int n = 0; n < 2; ++n) _Pragma("unroll") for (int k = 0; k < 2; ++k) dst[n][k] = *(const PG8_LAS bf16x8*)(lds + PG8_SB(b, h) + boff + n * 2048 + k * 1024); } while (0)
; #define PG8_MMA(ai, bj, At, Bt) do { __builtin_amdgcn_s_setprio(1); _Pragma("unroll") for (int m = 0; m < 4; ++m) _Pragma("unroll") for (int n = 0; n < 2; ++n) _Pragma("unroll") for (int k = 0; k < 2; ++k) \
;         acc[ai][bj][m][n] = __builtin_amdgcn_mfma_f32_16x16x32_bf16(Bt[n][k], At[m][k], acc[ai][bj][m][n], 0, 0, 0); __builtin_amdgcn_s_setprio(0); } while (0)
; #define PG8_WAIT_V(n) asm volatile("s_waitcnt vmcnt(" #n ")" ::: "memory")
; #define PG8_WAIT_L(n) asm volatile("s_waitcnt lgkmcnt(" #n ")" ::: "memory")
; #define PG8_BAR __builtin_amdgcn_s_barrier()
; #define PG8_SCHED __builtin_amdgcn_sched_barrier(0)
; template <class Epi, class Sched, bool ALIGN_EPI = false, bool SP2 = false>
; __device__ __forceinline__ void gemm_phase(PG8_LAS unsigned char* lds, const Gemm g, const Sched& S, const Epi& E) {
;     ...
;             PG8_LDB(B0, 0, 0); PG8_LDB(B1, 0, 1); PG8_SCHED; PG8_LDA(At, 0, 0); PG8_STAGE(PG8_SA(1, 1), a1 + hstep, voffA);
;             PG8_WAIT_V(8); PG8_WAIT_L(0); PG8_BAR; PG8_MMA(0, 0, At, B0); PG8_MMA(0, 1, At, B1); PG8_BAR; PG8_SCHED;
;             PG8_LDA(At, 0, 1); PG8_STAGE(PG8_SB(0, 0), b2, voffB); PG8_STAGE(PG8_SB(0, 1), b2 + hstep, voffB); PG8_STAGE(PG8_SA(0, 0), a2, voffA);
;             PG8_WAIT_V(8); PG8_WAIT_L(0); PG8_BAR; PG8_MMA(1, 0, At, B0); PG8_MMA(1, 1, At, B1); PG8_BAR; PG8_SCHED;
.LBB0_495:
	ds_read_b128 v[170:173], v165
	ds_read_b128 v[174:177], v165 offset:1024
	ds_read_b128 v[182:185], v165 offset:2048
	ds_read_b128 v[186:189], v165 offset:3072
	ds_read_b128 v[190:193], v168
	ds_read_b128 v[194:197], v168 offset:1024
	ds_read_b128 v[198:201], v168 offset:2048
	ds_read_b128 v[208:211], v168 offset:3072
	s_add_u32 s3, s60, 0xfffc0080
	s_addc_u32 s14, s61, -1
	s_cmp_eq_u32 s97, 12
	s_cselect_b32 s65, s49, s14
	s_cselect_b32 s64, s57, s3
	s_cselect_b32 s63, s45, s96
	s_cselect_b32 s62, s94, s95
	v_lshl_add_u64 v[178:179], s[60:61], 0, v[160:161]
	s_add_i32 m0, s59, 0xc000
	ds_read_b128 v[212:215], v164
	ds_read_b128 v[216:219], v164 offset:1024
	ds_read_b128 v[220:223], v164 offset:2048
	ds_read_b128 v[224:227], v164 offset:3072
	ds_read_b128 v[228:231], v164 offset:4096
	ds_read_b128 v[232:235], v164 offset:5120
	ds_read_b128 v[236:239], v164 offset:6144
	ds_read_b128 v[240:243], v164 offset:7168
	global_load_lds_dwordx4 v[178:179], off
	v_lshl_add_u64 v[178:179], s[60:61], 0, v[162:163]
	s_add_i32 m0, s59, 0xe000
	s_nop 0
	global_load_lds_dwordx4 v[178:179], off
	s_waitcnt vmcnt(8)
	s_waitcnt lgkmcnt(0)
	s_barrier
	s_setprio 1
	s_waitcnt lgkmcnt(0)
	v_mfma_f32_16x16x32_bf16 v[124:127], v[170:173], v[212:215], v[124:127]
	v_mfma_f32_16x16x32_bf16 v[120:123], v[182:185], v[212:215], v[120:123]
	v_mfma_f32_16x16x32_bf16 v[116:119], v[170:173], v[220:223], v[116:119]
	v_mfma_f32_16x16x32_bf16 v[112:115], v[182:185], v[220:223], v[112:115]
	v_mfma_f32_16x16x32_bf16 v[124:127], v[174:177], v[216:219], v[124:127]
	v_mfma_f32_16x16x32_bf16 v[120:123], v[186:189], v[216:219], v[120:123]
	v_mfma_f32_16x16x32_bf16 v[116:119], v[174:177], v[224:227], v[116:119]
	v_mfma_f32_16x16x32_bf16 v[112:115], v[186:189], v[224:227], v[112:115]
	v_mfma_f32_16x16x32_bf16 v[108:111], v[170:173], v[228:231], v[108:111]
	v_mfma_f32_16x16x32_bf16 v[104:107], v[182:185], v[228:231], v[104:107]
	v_mfma_f32_16x16x32_bf16 v[100:103], v[170:173], v[236:239], v[100:103]
	v_mfma_f32_16x16x32_bf16 v[96:99], v[182:185], v[236:239], v[96:99]
	v_mfma_f32_16x16x32_bf16 v[108:111], v[174:177], v[232:235], v[108:111]
	v_mfma_f32_16x16x32_bf16 v[104:107], v[186:189], v[232:235], v[104:107]
	v_mfma_f32_16x16x32_bf16 v[100:103], v[174:177], v[240:243], v[100:103]
	v_mfma_f32_16x16x32_bf16 v[96:99], v[186:189], v[240:243], v[96:99]
	s_setprio 0
	s_setprio 1
	v_mfma_f32_16x16x32_bf16 v[60:63], v[190:193], v[212:215], v[60:63]
	v_mfma_f32_16x16x32_bf16 v[56:59], v[198:201], v[212:215], v[56:59]
	v_mfma_f32_16x16x32_bf16 v[52:55], v[190:193], v[220:223], v[52:55]
	v_mfma_f32_16x16x32_bf16 v[48:51], v[198:201], v[220:223], v[48:51]
	v_mfma_f32_16x16x32_bf16 v[60:63], v[194:197], v[216:219], v[60:63]
	v_mfma_f32_16x16x32_bf16 v[56:59], v[208:211], v[216:219], v[56:59]
	v_mfma_f32_16x16x32_bf16 v[52:55], v[194:197], v[224:227], v[52:55]
	v_mfma_f32_16x16x32_bf16 v[48:51], v[208:211], v[224:227], v[48:51]
	v_mfma_f32_16x16x32_bf16 v[44:47], v[190:193], v[228:231], v[44:47]
	v_mfma_f32_16x16x32_bf16 v[40:43], v[198:201], v[228:231], v[40:43]
	v_mfma_f32_16x16x32_bf16 v[36:39], v[190:193], v[236:239], v[36:39]
	v_mfma_f32_16x16x32_bf16 v[32:35], v[198:201], v[236:239], v[32:35]
	v_mfma_f32_16x16x32_bf16 v[44:47], v[194:197], v[232:235], v[44:47]
	v_mfma_f32_16x16x32_bf16 v[40:43], v[208:211], v[232:235], v[40:43]
	v_mfma_f32_16x16x32_bf16 v[36:39], v[194:197], v[240:243], v[36:39]
	v_mfma_f32_16x16x32_bf16 v[32:35], v[208:211], v[240:243], v[32:35]
	s_setprio 0
	s_barrier
	s_add_i32 s3, s92, s75
	v_lshl_add_u64 v[178:179], s[62:63], 0, v[130:131]
	s_mov_b32 m0, s3
	ds_read_b128 v[212:215], v164 offset:16384
	ds_read_b128 v[216:219], v164 offset:17408
	ds_read_b128 v[220:223], v164 offset:18432
	ds_read_b128 v[224:227], v164 offset:19456
	ds_read_b128 v[228:231], v164 offset:20480
	ds_read_b128 v[232:235], v164 offset:21504
	ds_read_b128 v[236:239], v164 offset:22528
	ds_read_b128 v[240:243], v164 offset:23552
	global_load_lds_dwordx4 v[178:179], off
	s_add_i32 m0, s3, 0x2000
	s_add_u32 s14, s62, 0x40000
	v_lshl_add_u64 v[202:203], s[62:63], 0, v[134:135]
	s_addc_u32 s15, s63, 0
	s_add_i32 s3, s93, s75
	global_load_lds_dwordx4 v[202:203], off
	v_lshl_add_u64 v[244:245], s[14:15], 0, v[130:131]
	s_mov_b32 m0, s3
	global_load_lds_dwordx4 v[244:245], off
	v_lshl_add_u64 v[244:245], s[14:15], 0, v[134:135]
	s_add_i32 m0, s3, 0x2000
	s_nop 0
	global_load_lds_dwordx4 v[244:245], off
	s_waitcnt vmcnt(6)
	s_waitcnt lgkmcnt(0)
	s_barrier
; #define PG8_STAGE(bufoff, gbase, voff) do { _Pragma("unroll") for (int _i = 0; _i < 2; ++_i) \
;         __builtin_amdgcn_global_load_lds((const unsigned*)((const char*)(gbase) + (voff)[_i]), (PG8_LAS unsigned*)(lds + (bufoff) + ldsw + _i * 8192), 16, 0, 0); } while (0)
; #define PG8_LDA(dst, b, h) do { _Pragma("unroll") for (int m = 0; m < 4; ++m) _Pragma("unroll") for (int k = 0; k < 2; ++k) dst[m][k] = *(const PG8_LAS bf16x8*)(lds + PG8_SA(b, h) + aoff + m * 2048 + k * 1024); } while (0)
; #define PG8_LDB(dst, b, h) do { _Pragma("unroll") for (int n = 0; n < 2; ++n) _Pragma("unroll") for (int k = 0; k < 2; ++k) dst[n][k] = *(const PG8_LAS bf16x8*)(lds + PG8_SB(b, h) + boff + n * 2048 + k * 1024); } while (0)
; #define PG8_MMA(ai, bj, At, Bt) do { __builtin_amdgcn_s_setprio(1); _Pragma("unroll") for (int m = 0; m < 4; ++m) _Pragma("unroll") for (int n = 0; n < 2; ++n) _Pragma("unroll") for (int k = 0; k < 2; ++k) \
;         acc[ai][bj][m][n] = __builtin_amdgcn_mfma_f32_16x16x32_bf16(Bt[n][k], At[m][k], acc[ai][bj][m][n], 0, 0, 0); __builtin_amdgcn_s_setprio(0); } while (0)
; #define PG8_WAIT_V(n) asm volatile("s_waitcnt vmcnt(" #n ")" ::: "memory")
; #define PG8_WAIT_L(n) asm volatile("s_waitcnt lgkmcnt(" #n ")" ::: "memory")
; #define PG8_BAR __builtin_amdgcn_s_barrier()
; #define PG8_SCHED __builtin_amdgcn_sched_barrier(0)
; template <class Epi, class Sched, bool ALIGN_EPI = false, bool SP2 = false>
; __device__ __forceinline__ void gemm_phase(PG8_LAS unsigned char* lds, const Gemm g, const Sched& S, const Epi& E) {
;     ...
;             PG8_WAIT_V(8); PG8_WAIT_L(0); PG8_BAR; PG8_MMA(1, 0, At, B0); PG8_MMA(1, 1, At, B1); PG8_BAR; PG8_SCHED;
;             PG8_LDB(B0, 1, 0); PG8_LDB(B1, 1, 1); PG8_SCHED; PG8_LDA(At, 1, 0); PG8_STAGE(PG8_SA(0, 1), a2 + hstep, voffA);
;             PG8_WAIT_V(8); PG8_WAIT_L(0); PG8_BAR; PG8_MMA(0, 0, At, B0); PG8_MMA(0, 1, At, B1); PG8_BAR; PG8_SCHED;
	s_setprio 1
	s_waitcnt lgkmcnt(0)
	v_mfma_f32_16x16x32_bf16 v[92:95], v[170:173], v[212:215], v[92:95]
	v_mfma_f32_16x16x32_bf16 v[88:91], v[182:185], v[212:215], v[88:91]
	v_mfma_f32_16x16x32_bf16 v[84:87], v[170:173], v[220:223], v[84:87]
	v_mfma_f32_16x16x32_bf16 v[80:83], v[182:185], v[220:223], v[80:83]
	v_mfma_f32_16x16x32_bf16 v[92:95], v[174:177], v[216:219], v[92:95]
	v_mfma_f32_16x16x32_bf16 v[88:91], v[186:189], v[216:219], v[88:91]
	v_mfma_f32_16x16x32_bf16 v[84:87], v[174:177], v[224:227], v[84:87]
	v_mfma_f32_16x16x32_bf16 v[80:83], v[186:189], v[224:227], v[80:83]
	v_mfma_f32_16x16x32_bf16 v[76:79], v[170:173], v[228:231], v[76:79]
	v_mfma_f32_16x16x32_bf16 v[72:75], v[182:185], v[228:231], v[72:75]
	v_mfma_f32_16x16x32_bf16 v[68:71], v[170:173], v[236:239], v[68:71]
	v_mfma_f32_16x16x32_bf16 v[64:67], v[182:185], v[236:239], v[64:67]
	v_mfma_f32_16x16x32_bf16 v[76:79], v[174:177], v[232:235], v[76:79]
	v_mfma_f32_16x16x32_bf16 v[72:75], v[186:189], v[232:235], v[72:75]
	v_lshl_add_u64 v[244:245], s[64:65], 0, v[128:129]
	s_mov_b32 m0, s59
	s_nop 0
	global_load_lds_dwordx4 v[244:245], off
	v_mfma_f32_16x16x32_bf16 v[68:71], v[174:177], v[240:243], v[68:71]
	v_mfma_f32_16x16x32_bf16 v[64:67], v[186:189], v[240:243], v[64:67]
	s_setprio 0
	s_setprio 1
	v_mfma_f32_16x16x32_bf16 v[28:31], v[190:193], v[212:215], v[28:31]
	v_mfma_f32_16x16x32_bf16 v[24:27], v[198:201], v[212:215], v[24:27]
	v_mfma_f32_16x16x32_bf16 v[20:23], v[190:193], v[220:223], v[20:23]
	v_mfma_f32_16x16x32_bf16 v[16:19], v[198:201], v[220:223], v[16:19]
	v_mfma_f32_16x16x32_bf16 v[28:31], v[194:197], v[216:219], v[28:31]
	v_mfma_f32_16x16x32_bf16 v[24:27], v[208:211], v[216:219], v[24:27]
	v_mfma_f32_16x16x32_bf16 v[20:23], v[194:197], v[224:227], v[20:23]
	v_mfma_f32_16x16x32_bf16 v[16:19], v[208:211], v[224:227], v[16:19]
	v_mfma_f32_16x16x32_bf16 v[12:15], v[190:193], v[228:231], v[12:15]
	v_mfma_f32_16x16x32_bf16 v[8:11], v[198:201], v[228:231], v[8:11]
	v_mfma_f32_16x16x32_bf16 v[4:7], v[190:193], v[236:239], v[4:7]
	v_mfma_f32_16x16x32_bf16 v[0:3], v[198:201], v[236:239], v[0:3]
	v_mfma_f32_16x16x32_bf16 v[12:15], v[194:197], v[232:235], v[12:15]
	v_mfma_f32_16x16x32_bf16 v[8:11], v[208:211], v[232:235], v[8:11]
	v_lshl_add_u64 v[246:247], s[64:65], 0, v[132:133]
	s_mov_b32 m0, s84
	s_nop 0
	global_load_lds_dwordx4 v[246:247], off
	v_mfma_f32_16x16x32_bf16 v[4:7], v[194:197], v[240:243], v[4:7]
	v_mfma_f32_16x16x32_bf16 v[0:3], v[208:211], v[240:243], v[0:3]
	s_setprio 0
	s_barrier
	s_add_i32 s3, 0, 0x18000
	v_add_u32_e32 v136, s3, v141
	s_add_i32 s33, 0, 0x1c000
	ds_read_b128 v[170:173], v136
	ds_read_b128 v[174:177], v136 offset:1024
	ds_read_b128 v[182:185], v136 offset:2048
	ds_read_b128 v[186:189], v136 offset:3072
	v_add_u32_e32 v136, s33, v141
	ds_read_b128 v[190:193], v136
	ds_read_b128 v[194:197], v136 offset:1024
	ds_read_b128 v[198:201], v136 offset:2048
	ds_read_b128 v[208:211], v136 offset:3072
	s_add_u32 s14, s64, 0x40000
	s_addc_u32 s15, s65, 0
	s_mov_b32 m0, s85
	v_lshl_add_u64 v[248:249], s[14:15], 0, v[128:129]
	ds_read_b128 v[212:215], v164 offset:32768
	ds_read_b128 v[216:219], v164 offset:33792
	ds_read_b128 v[220:223], v164 offset:34816
	ds_read_b128 v[224:227], v164 offset:35840
	ds_read_b128 v[228:231], v164 offset:36864
	ds_read_b128 v[232:235], v164 offset:37888
	ds_read_b128 v[236:239], v164 offset:38912
	ds_read_b128 v[240:243], v164 offset:39936
	global_load_lds_dwordx4 v[248:249], off
	v_lshl_add_u64 v[248:249], s[14:15], 0, v[132:133]
	s_mov_b32 m0, s86
	s_nop 0
	global_load_lds_dwordx4 v[248:249], off
	s_waitcnt vmcnt(8)
	s_waitcnt lgkmcnt(0)
	s_barrier
	s_setprio 1
	s_waitcnt lgkmcnt(0)
	v_mfma_f32_16x16x32_bf16 v[124:127], v[170:173], v[212:215], v[124:127]
	v_mfma_f32_16x16x32_bf16 v[120:123], v[182:185], v[212:215], v[120:123]
	v_mfma_f32_16x16x32_bf16 v[116:119], v[170:173], v[220:223], v[116:119]
	v_mfma_f32_16x16x32_bf16 v[112:115], v[182:185], v[220:223], v[112:115]
	v_mfma_f32_16x16x32_bf16 v[124:127], v[174:177], v[216:219], v[124:127]
	v_mfma_f32_16x16x32_bf16 v[120:123], v[186:189], v[216:219], v[120:123]
	v_mfma_f32_16x16x32_bf16 v[116:119], v[174:177], v[224:227], v[116:119]
	v_mfma_f32_16x16x32_bf16 v[112:115], v[186:189], v[224:227], v[112:115]
	v_mfma_f32_16x16x32_bf16 v[108:111], v[170:173], v[228:231], v[108:111]
	v_mfma_f32_16x16x32_bf16 v[104:107], v[182:185], v[228:231], v[104:107]
	v_mfma_f32_16x16x32_bf16 v[100:103], v[170:173], v[236:239], v[100:103]
	v_mfma_f32_16x16x32_bf16 v[96:99], v[182:185], v[236:239], v[96:99]
	v_mfma_f32_16x16x32_bf16 v[108:111], v[174:177], v[232:235], v[108:111]
	v_mfma_f32_16x16x32_bf16 v[104:107], v[186:189], v[232:235], v[104:107]
	v_mfma_f32_16x16x32_bf16 v[100:103], v[174:177], v[240:243], v[100:103]
	v_mfma_f32_16x16x32_bf16 v[96:99], v[186:189], v[240:243], v[96:99]
	s_setprio 0
	s_setprio 1
	v_mfma_f32_16x16x32_bf16 v[60:63], v[190:193], v[212:215], v[60:63]
	v_mfma_f32_16x16x32_bf16 v[56:59], v[198:201], v[212:215], v[56:59]
	v_mfma_f32_16x16x32_bf16 v[52:55], v[190:193], v[220:223], v[52:55]
	v_mfma_f32_16x16x32_bf16 v[48:51], v[198:201], v[220:223], v[48:51]
	v_mfma_f32_16x16x32_bf16 v[60:63], v[194:197], v[216:219], v[60:63]
	v_mfma_f32_16x16x32_bf16 v[56:59], v[208:211], v[216:219], v[56:59]
	v_mfma_f32_16x16x32_bf16 v[52:55], v[194:197], v[224:227], v[52:55]
	v_mfma_f32_16x16x32_bf16 v[48:51], v[208:211], v[224:227], v[48:51]
	v_mfma_f32_16x16x32_bf16 v[44:47], v[190:193], v[228:231], v[44:47]
	v_mfma_f32_16x16x32_bf16 v[40:43], v[198:201], v[228:231], v[40:43]
	v_mfma_f32_16x16x32_bf16 v[36:39], v[190:193], v[236:239], v[36:39]
	v_mfma_f32_16x16x32_bf16 v[32:35], v[198:201], v[236:239], v[32:35]
	v_mfma_f32_16x16x32_bf16 v[44:47], v[194:197], v[232:235], v[44:47]
	v_mfma_f32_16x16x32_bf16 v[40:43], v[208:211], v[232:235], v[40:43]
	v_mfma_f32_16x16x32_bf16 v[36:39], v[194:197], v[240:243], v[36:39]
	v_mfma_f32_16x16x32_bf16 v[32:35], v[208:211], v[240:243], v[32:35]
	s_setprio 0
	s_barrier
; #define PG8_STAGE(bufoff, gbase, voff) do { _Pragma("unroll") for (int _i = 0; _i < 2; ++_i) \
;         __builtin_amdgcn_global_load_lds((const unsigned*)((const char*)(gbase) + (voff)[_i]), (PG8_LAS unsigned*)(lds + (bufoff) + ldsw + _i * 8192), 16, 0, 0); } while (0)
; #define PG8_LDA(dst, b, h) do { _Pragma("unroll") for (int m = 0; m < 4; ++m) _Pragma("unroll") for (int k = 0; k < 2; ++k) dst[m][k] = *(const PG8_LAS bf16x8*)(lds + PG8_SA(b, h) + aoff + m * 2048 + k * 1024); } while (0)
; #define PG8_MMA(ai, bj, At, Bt) do { __builtin_amdgcn_s_setprio(1); _Pragma("unroll") for (int m = 0; m < 4; ++m) _Pragma("unroll") for (int n = 0; n < 2; ++n) _Pragma("unroll") for (int k = 0; k < 2; ++k) \
;         acc[ai][bj][m][n] = __builtin_amdgcn_mfma_f32_16x16x32_bf16(Bt[n][k], At[m][k], acc[ai][bj][m][n], 0, 0, 0); __builtin_amdgcn_s_setprio(0); } while (0)
; #define PG8_WAIT_V(n) asm volatile("s_waitcnt vmcnt(" #n ")" ::: "memory")
; #define PG8_WAIT_L(n) asm volatile("s_waitcnt lgkmcnt(" #n ")" ::: "memory")
; #define PG8_BAR __builtin_amdgcn_s_barrier()
; #define PG8_SCHED __builtin_amdgcn_sched_barrier(0)
; template <class Epi, class Sched, bool ALIGN_EPI = false, bool SP2 = false>
; __device__ __forceinline__ void gemm_phase(PG8_LAS unsigned char* lds, const Gemm g, const Sched& S, const Epi& E) {
;     ...
;             PG8_LDA(At, 1, 1); PG8_STAGE(PG8_SB(1, 0), b3, voffB); PG8_STAGE(PG8_SB(1, 1), b3 + hstep, voffB); PG8_STAGE(PG8_SA(1, 0), a3, voffA);
;             PG8_WAIT_V(8); PG8_WAIT_L(0); PG8_BAR; PG8_MMA(1, 0, At, B0); PG8_MMA(1, 1, At, B1); PG8_BAR; PG8_SCHED;
;     ...
;         if constexpr (ALIGN_EPI) { if (wr == 0) PG8_BAR; }
	s_add_i32 s3, s3, s75
	v_lshl_add_u64 v[178:179], v[178:179], 0, s[10:11]
	s_mov_b32 m0, s3
	ds_read_b128 v[212:215], v164 offset:49152
	ds_read_b128 v[216:219], v164 offset:50176
	ds_read_b128 v[220:223], v164 offset:51200
	ds_read_b128 v[224:227], v164 offset:52224
	ds_read_b128 v[228:231], v164 offset:53248
	ds_read_b128 v[232:235], v164 offset:54272
	ds_read_b128 v[236:239], v164 offset:55296
	ds_read_b128 v[240:243], v164 offset:56320
	global_load_lds_dwordx4 v[178:179], off
	s_add_i32 m0, s3, 0x2000
	s_add_u32 s14, s62, 0x40080
	v_lshl_add_u64 v[178:179], v[202:203], 0, s[10:11]
	s_addc_u32 s15, s63, 0
	s_add_i32 s3, s33, s75
	global_load_lds_dwordx4 v[178:179], off
	v_lshl_add_u64 v[178:179], s[14:15], 0, v[130:131]
	s_mov_b32 m0, s3
	s_nop 0
	global_load_lds_dwordx4 v[178:179], off
	v_lshl_add_u64 v[178:179], s[14:15], 0, v[134:135]
	s_add_i32 m0, s3, 0x2000
	s_nop 0
	global_load_lds_dwordx4 v[178:179], off
	s_waitcnt vmcnt(6)
	s_waitcnt lgkmcnt(0)
	s_barrier
	s_setprio 1
	s_waitcnt lgkmcnt(0)
	v_mfma_f32_16x16x32_bf16 v[92:95], v[170:173], v[212:215], v[92:95]
	v_mfma_f32_16x16x32_bf16 v[88:91], v[182:185], v[212:215], v[88:91]
	v_mfma_f32_16x16x32_bf16 v[84:87], v[170:173], v[220:223], v[84:87]
	v_mfma_f32_16x16x32_bf16 v[80:83], v[182:185], v[220:223], v[80:83]
	v_mfma_f32_16x16x32_bf16 v[92:95], v[174:177], v[216:219], v[92:95]
	v_mfma_f32_16x16x32_bf16 v[88:91], v[186:189], v[216:219], v[88:91]
	v_mfma_f32_16x16x32_bf16 v[84:87], v[174:177], v[224:227], v[84:87]
	v_mfma_f32_16x16x32_bf16 v[80:83], v[186:189], v[224:227], v[80:83]
	v_mfma_f32_16x16x32_bf16 v[76:79], v[170:173], v[228:231], v[76:79]
	v_mfma_f32_16x16x32_bf16 v[72:75], v[182:185], v[228:231], v[72:75]
	v_mfma_f32_16x16x32_bf16 v[68:71], v[170:173], v[236:239], v[68:71]
	v_mfma_f32_16x16x32_bf16 v[64:67], v[182:185], v[236:239], v[64:67]
	v_mfma_f32_16x16x32_bf16 v[76:79], v[174:177], v[232:235], v[76:79]
	v_mfma_f32_16x16x32_bf16 v[72:75], v[186:189], v[232:235], v[72:75]
	v_lshl_add_u64 v[178:179], v[244:245], 0, s[10:11]
	s_mov_b32 m0, s88
	s_nop 0
	global_load_lds_dwordx4 v[178:179], off
	v_mfma_f32_16x16x32_bf16 v[68:71], v[174:177], v[240:243], v[68:71]
	v_mfma_f32_16x16x32_bf16 v[64:67], v[186:189], v[240:243], v[64:67]
	s_setprio 0
	s_setprio 1
	v_mfma_f32_16x16x32_bf16 v[28:31], v[190:193], v[212:215], v[28:31]
	v_mfma_f32_16x16x32_bf16 v[24:27], v[198:201], v[212:215], v[24:27]
	v_mfma_f32_16x16x32_bf16 v[20:23], v[190:193], v[220:223], v[20:23]
	v_mfma_f32_16x16x32_bf16 v[16:19], v[198:201], v[220:223], v[16:19]
	v_mfma_f32_16x16x32_bf16 v[28:31], v[194:197], v[216:219], v[28:31]
	v_mfma_f32_16x16x32_bf16 v[24:27], v[208:211], v[216:219], v[24:27]
	v_mfma_f32_16x16x32_bf16 v[20:23], v[194:197], v[224:227], v[20:23]
	v_mfma_f32_16x16x32_bf16 v[16:19], v[208:211], v[224:227], v[16:19]
	v_mfma_f32_16x16x32_bf16 v[12:15], v[190:193], v[228:231], v[12:15]
	v_mfma_f32_16x16x32_bf16 v[8:11], v[198:201], v[228:231], v[8:11]
	v_mfma_f32_16x16x32_bf16 v[4:7], v[190:193], v[236:239], v[4:7]
	v_mfma_f32_16x16x32_bf16 v[0:3], v[198:201], v[236:239], v[0:3]
	v_mfma_f32_16x16x32_bf16 v[12:15], v[194:197], v[232:235], v[12:15]
	v_mfma_f32_16x16x32_bf16 v[8:11], v[208:211], v[232:235], v[8:11]
	v_lshl_add_u64 v[178:179], v[246:247], 0, s[10:11]
	s_mov_b32 m0, s89
	s_nop 0
	global_load_lds_dwordx4 v[178:179], off
	v_mfma_f32_16x16x32_bf16 v[4:7], v[194:197], v[240:243], v[4:7]
	v_mfma_f32_16x16x32_bf16 v[0:3], v[208:211], v[240:243], v[0:3]
	s_setprio 0
	s_barrier
	s_add_i32 s97, s97, 2
	s_add_u32 s60, s60, 0x100
	s_addc_u32 s61, s61, 0
	s_add_u32 s95, s95, 0x100
	s_addc_u32 s96, s96, 0
	s_cmp_lt_u32 s97, 14
	s_cbranch_scc1 .LBB0_495
	s_andn2_b64 vcc, exec, s[40:41]
	s_cbranch_vccnz .LBB0_498
	s_barrier

; #define PG8_STAGE(bufoff, gbase, voff) do { _Pragma("unroll") for (int _i = 0; _i < 2; ++_i) \
;         __builtin_amdgcn_global_load_lds((const unsigned*)((const char*)(gbase) + (voff)[_i]), (PG8_LAS unsigned*)(lds + (bufoff) + ldsw + _i * 8192), 16, 0, 0); } while (0)
; #define PG8_LDA(dst, b, h) do { _Pragma("unroll") for (int m = 0; m < 4; ++m) _Pragma("unroll") for (int k = 0; k < 2; ++k) dst[m][k] = *(const PG8_LAS bf16x8*)(lds + PG8_SA(b, h) + aoff + m * 2048 + k * 1024); } while (0)
; #define PG8_LDB(dst, b, h) do { _Pragma("unroll") for (int n = 0; n < 2; ++n) _Pragma("unroll") for (int k = 0; k < 2; ++k) dst[n][k] = *(const PG8_LAS bf16x8*)(lds + PG8_SB(b, h) + boff + n * 2048 + k * 1024); } while (0)
; #define PG8_WAIT_V(n) asm volatile("s_waitcnt vmcnt(" #n ")" ::: "memory")
; #define PG8_WAIT_L(n) asm volatile("s_waitcnt lgkmcnt(" #n ")" ::: "memory")
; #define PG8_BAR __builtin_amdgcn_s_barrier()
; #define PG8_SCHED __builtin_amdgcn_sched_barrier(0)
; template <class Epi, class Sched, bool ALIGN_EPI = false, bool SP2 = false>
; __device__ __forceinline__ void gemm_phase(PG8_LAS unsigned char* lds, const Gemm g, const Sched& S, const Epi& E) {
;     ...
;         const bool has_next = S.next(ui + 1, nxt);
;         const char* nA = has_next ? (const char*)g.A + (size_t)nxt.pm * tstep : cA; const char* nB = has_next ? (const char*)g.Bt + (size_t)nxt.pn * tstep : cB;
;         for (int t = 0; t < nt; t += 2) {
;             const bool last = (t == nt - 2);
;             const char* a1 = cA + (size_t)(t + 1) * kstep;
;             const char* a2 = last ? nA : cA + (size_t)(t + 2) * kstep; const char* b2 = last ? nB : cB + (size_t)(t + 2) * kstep;
;             const char* a3 = a2 + kstep; const char* b3 = b2 + kstep;
;             if (last && has_next) S.a_ready(nxt);
;             if constexpr (SP2) {
;             PG8_LDB(B0, 0, 0); PG8_LDB(B1, 0, 1); PG8_SCHED; PG8_LDA(At, 0, 0); PG8_STAGE(PG8_SA(1, 1), a1 + hstep, voffA);
;             PG8_WAIT_V(8); PG8_WAIT_L(0); PG8_BAR; PG8_MMA(0, 0, At, B0); PG8_MMA(0, 1, At, B1); PG8_BAR; PG8_SCHED;
;             PG8_LDA(At, 0, 1); PG8_STAGE(PG8_SB(0, 0), b2, voffB); PG8_STAGE(PG8_SB(0, 1), b2 + hstep, voffB); PG8_STAGE(PG8_SA(0, 0), a2, voffA);
;             PG8_WAIT_V(8); PG8_WAIT_L(0); PG8_BAR; PG8_MMA(1, 0, At, B0); PG8_MMA(1, 1, At, B1); PG8_BAR; PG8_SCHED;
.LBB0_649:
	s_ashr_i32 s51, s50, 31
	s_lshl_b64 s[14:15], s[50:51], 19
	s_add_u32 s52, s40, s14
	s_addc_u32 s53, s41, s15
	s_and_b64 s[14:15], s[8:9], exec
	s_cselect_b32 s51, s53, s61
	s_cselect_b32 s57, s52, s60
	s_ashr_i32 s49, s48, 31
	s_lshl_b64 s[14:15], s[48:49], 19
	s_add_u32 s54, s82, s14
	s_addc_u32 s55, s83, s15
	s_and_b64 s[14:15], s[8:9], exec
	s_cselect_b32 s49, s55, s63
	s_cselect_b32 s89, s54, s62
	s_add_u32 s60, s60, 0x40080
	s_addc_u32 s61, s61, 0
	s_add_u32 s90, s62, 0x100
	s_addc_u32 s91, s63, 0
	s_mov_b32 s92, -2
	s_waitcnt lgkmcnt(0)
	s_waitcnt vmcnt(0)
	ds_read_b128 v[148:151], v155
	ds_read_b128 v[160:163], v155 offset:1024
	ds_read_b128 v[164:167], v155 offset:2048
	ds_read_b128 v[168:171], v155 offset:3072
	ds_read_b128 v[172:175], v156
	ds_read_b128 v[176:179], v156 offset:1024
	ds_read_b128 v[182:185], v156 offset:2048
	ds_read_b128 v[186:189], v156 offset:3072
	s_add_u32 s3, s60, 0xfffc0080
	s_addc_u32 s14, s61, -1
	s_cmp_eq_u32 s92, 12
	s_cselect_b32 s65, s51, s14
	s_cselect_b32 s64, s57, s3
	s_cselect_b32 s63, s49, s91
	s_cselect_b32 s62, s89, s90
	v_lshl_add_u64 v[202:203], s[60:61], 0, v[140:141]
	s_add_i32 m0, s43, 0xc000
	ds_read_b128 v[190:193], v157
	ds_read_b128 v[194:197], v157 offset:1024
	ds_read_b128 v[198:201], v157 offset:2048
	ds_read_b128 v[208:211], v157 offset:3072
	ds_read_b128 v[212:215], v157 offset:4096
	ds_read_b128 v[216:219], v157 offset:5120
	ds_read_b128 v[220:223], v157 offset:6144
	ds_read_b128 v[224:227], v157 offset:7168
	global_load_lds_dwordx4 v[202:203], off
	v_lshl_add_u64 v[202:203], s[60:61], 0, v[142:143]
	s_add_i32 m0, s43, 0xe000
	s_nop 0
	global_load_lds_dwordx4 v[202:203], off
	s_waitcnt vmcnt(8)
	s_waitcnt lgkmcnt(0)
	s_barrier
	s_setprio 1
	s_waitcnt lgkmcnt(0)
	v_mfma_f32_16x16x32_bf16 v[124:127], v[148:151], v[190:193], 0
	v_mfma_f32_16x16x32_bf16 v[120:123], v[164:167], v[190:193], 0
	v_mfma_f32_16x16x32_bf16 v[108:111], v[148:151], v[198:201], 0
	v_mfma_f32_16x16x32_bf16 v[104:107], v[164:167], v[198:201], 0
	v_mfma_f32_16x16x32_bf16 v[124:127], v[160:163], v[194:197], v[124:127]
	v_mfma_f32_16x16x32_bf16 v[120:123], v[168:171], v[194:197], v[120:123]
	v_mfma_f32_16x16x32_bf16 v[108:111], v[160:163], v[208:211], v[108:111]
	v_mfma_f32_16x16x32_bf16 v[104:107], v[168:171], v[208:211], v[104:107]
	v_mfma_f32_16x16x32_bf16 v[92:95], v[148:151], v[212:215], 0
	v_mfma_f32_16x16x32_bf16 v[88:91], v[164:167], v[212:215], 0
	v_mfma_f32_16x16x32_bf16 v[76:79], v[148:151], v[220:223], 0
	v_mfma_f32_16x16x32_bf16 v[72:75], v[164:167], v[220:223], 0
	v_mfma_f32_16x16x32_bf16 v[92:95], v[160:163], v[216:219], v[92:95]
	v_mfma_f32_16x16x32_bf16 v[88:91], v[168:171], v[216:219], v[88:91]
	v_mfma_f32_16x16x32_bf16 v[76:79], v[160:163], v[224:227], v[76:79]
	v_mfma_f32_16x16x32_bf16 v[72:75], v[168:171], v[224:227], v[72:75]
	s_setprio 0
	s_setprio 1
	v_mfma_f32_16x16x32_bf16 v[116:119], v[172:175], v[190:193], 0
	v_mfma_f32_16x16x32_bf16 v[112:115], v[182:185], v[190:193], 0
	v_mfma_f32_16x16x32_bf16 v[100:103], v[172:175], v[198:201], 0
	v_mfma_f32_16x16x32_bf16 v[96:99], v[182:185], v[198:201], 0
	v_mfma_f32_16x16x32_bf16 v[116:119], v[176:179], v[194:197], v[116:119]
	v_mfma_f32_16x16x32_bf16 v[112:115], v[186:189], v[194:197], v[112:115]
	v_mfma_f32_16x16x32_bf16 v[100:103], v[176:179], v[208:211], v[100:103]
	v_mfma_f32_16x16x32_bf16 v[96:99], v[186:189], v[208:211], v[96:99]
	v_mfma_f32_16x16x32_bf16 v[84:87], v[172:175], v[212:215], 0
	v_mfma_f32_16x16x32_bf16 v[80:83], v[182:185], v[212:215], 0
	v_mfma_f32_16x16x32_bf16 v[68:71], v[172:175], v[220:223], 0
	v_mfma_f32_16x16x32_bf16 v[64:67], v[182:185], v[220:223], 0
	v_mfma_f32_16x16x32_bf16 v[84:87], v[176:179], v[216:219], v[84:87]
	v_mfma_f32_16x16x32_bf16 v[80:83], v[186:189], v[216:219], v[80:83]
	v_mfma_f32_16x16x32_bf16 v[68:71], v[176:179], v[224:227], v[68:71]
	v_mfma_f32_16x16x32_bf16 v[64:67], v[186:189], v[224:227], v[64:67]
	s_setprio 0
	s_barrier
	s_add_i32 s3, s85, s34
	v_lshl_add_u64 v[202:203], s[62:63], 0, v[134:135]
	s_mov_b32 m0, s3
	ds_read_b128 v[190:193], v157 offset:16384
	ds_read_b128 v[194:197], v157 offset:17408
	ds_read_b128 v[198:201], v157 offset:18432
	ds_read_b128 v[208:211], v157 offset:19456
	ds_read_b128 v[212:215], v157 offset:20480
	ds_read_b128 v[216:219], v157 offset:21504
	ds_read_b128 v[220:223], v157 offset:22528
	ds_read_b128 v[224:227], v157 offset:23552
	global_load_lds_dwordx4 v[202:203], off
	s_add_i32 m0, s3, 0x2000
	s_add_u32 s14, s62, 0x40000
	v_lshl_add_u64 v[228:229], s[62:63], 0, v[138:139]
	s_addc_u32 s15, s63, 0
	s_add_i32 s3, s86, s34
	global_load_lds_dwordx4 v[228:229], off
	v_lshl_add_u64 v[230:231], s[14:15], 0, v[134:135]
	s_mov_b32 m0, s3
	global_load_lds_dwordx4 v[230:231], off
	v_lshl_add_u64 v[230:231], s[14:15], 0, v[138:139]
	s_add_i32 m0, s3, 0x2000
	s_nop 0
	global_load_lds_dwordx4 v[230:231], off
	s_waitcnt vmcnt(6)
	s_waitcnt lgkmcnt(0)
	s_barrier
; #define PG8_STAGE(bufoff, gbase, voff) do { _Pragma("unroll") for (int _i = 0; _i < 2; ++_i) \
;         __builtin_amdgcn_global_load_lds((const unsigned*)((const char*)(gbase) + (voff)[_i]), (PG8_LAS unsigned*)(lds + (bufoff) + ldsw + _i * 8192), 16, 0, 0); } while (0)
; #define PG8_LDA(dst, b, h) do { _Pragma("unroll") for (int m = 0; m < 4; ++m) _Pragma("unroll") for (int k = 0; k < 2; ++k) dst[m][k] = *(const PG8_LAS bf16x8*)(lds + PG8_SA(b, h) + aoff + m * 2048 + k * 1024); } while (0)
; #define PG8_LDB(dst, b, h) do { _Pragma("unroll") for (int n = 0; n < 2; ++n) _Pragma("unroll") for (int k = 0; k < 2; ++k) dst[n][k] = *(const PG8_LAS bf16x8*)(lds + PG8_SB(b, h) + boff + n * 2048 + k * 1024); } while (0)
; #define PG8_MMA(ai, bj, At, Bt) do { __builtin_amdgcn_s_setprio(1); _Pragma("unroll") for (int m = 0; m < 4; ++m) _Pragma("unroll") for (int n = 0; n < 2; ++n) _Pragma("unroll") for (int k = 0; k < 2; ++k) \
;         acc[ai][bj][m][n] = __builtin_amdgcn_mfma_f32_16x16x32_bf16(Bt[n][k], At[m][k], acc[ai][bj][m][n], 0, 0, 0); __builtin_amdgcn_s_setprio(0); } while (0)
; #define PG8_WAIT_V(n) asm volatile("s_waitcnt vmcnt(" #n ")" ::: "memory")
; #define PG8_WAIT_L(n) asm volatile("s_waitcnt lgkmcnt(" #n ")" ::: "memory")
; #define PG8_BAR __builtin_amdgcn_s_barrier()
; #define PG8_SCHED __builtin_amdgcn_sched_barrier(0)
; template <class Epi, class Sched, bool ALIGN_EPI = false, bool SP2 = false>
; __device__ __forceinline__ void gemm_phase(PG8_LAS unsigned char* lds, const Gemm g, const Sched& S, const Epi& E) {
;     ...
;             PG8_WAIT_V(8); PG8_WAIT_L(0); PG8_BAR; PG8_MMA(1, 0, At, B0); PG8_MMA(1, 1, At, B1); PG8_BAR; PG8_SCHED;
;             PG8_LDB(B0, 1, 0); PG8_LDB(B1, 1, 1); PG8_SCHED; PG8_LDA(At, 1, 0); PG8_STAGE(PG8_SA(0, 1), a2 + hstep, voffA);
;             PG8_WAIT_V(8); PG8_WAIT_L(0); PG8_BAR; PG8_MMA(0, 0, At, B0); PG8_MMA(0, 1, At, B1); PG8_BAR; PG8_SCHED;
	s_setprio 1
	s_waitcnt lgkmcnt(0)
	v_mfma_f32_16x16x32_bf16 v[60:63], v[148:151], v[190:193], 0
	v_mfma_f32_16x16x32_bf16 v[56:59], v[164:167], v[190:193], 0
	v_mfma_f32_16x16x32_bf16 v[44:47], v[148:151], v[198:201], 0
	v_mfma_f32_16x16x32_bf16 v[40:43], v[164:167], v[198:201], 0
	v_mfma_f32_16x16x32_bf16 v[60:63], v[160:163], v[194:197], v[60:63]
	v_mfma_f32_16x16x32_bf16 v[56:59], v[168:171], v[194:197], v[56:59]
	v_mfma_f32_16x16x32_bf16 v[44:47], v[160:163], v[208:211], v[44:47]
	v_mfma_f32_16x16x32_bf16 v[40:43], v[168:171], v[208:211], v[40:43]
	v_mfma_f32_16x16x32_bf16 v[28:31], v[148:151], v[212:215], 0
	v_mfma_f32_16x16x32_bf16 v[24:27], v[164:167], v[212:215], 0
	v_mfma_f32_16x16x32_bf16 v[12:15], v[148:151], v[220:223], 0
	v_mfma_f32_16x16x32_bf16 v[8:11], v[164:167], v[220:223], 0
	v_mfma_f32_16x16x32_bf16 v[28:31], v[160:163], v[216:219], v[28:31]
	v_mfma_f32_16x16x32_bf16 v[24:27], v[168:171], v[216:219], v[24:27]
	v_lshl_add_u64 v[230:231], s[64:65], 0, v[132:133]
	s_mov_b32 m0, s43
	s_nop 0
	global_load_lds_dwordx4 v[230:231], off
	v_mfma_f32_16x16x32_bf16 v[12:15], v[160:163], v[224:227], v[12:15]
	v_mfma_f32_16x16x32_bf16 v[8:11], v[168:171], v[224:227], v[8:11]
	s_setprio 0
	s_setprio 1
	v_mfma_f32_16x16x32_bf16 v[52:55], v[172:175], v[190:193], 0
	v_mfma_f32_16x16x32_bf16 v[48:51], v[182:185], v[190:193], 0
	v_mfma_f32_16x16x32_bf16 v[36:39], v[172:175], v[198:201], 0
	v_mfma_f32_16x16x32_bf16 v[32:35], v[182:185], v[198:201], 0
	v_mfma_f32_16x16x32_bf16 v[52:55], v[176:179], v[194:197], v[52:55]
	v_mfma_f32_16x16x32_bf16 v[48:51], v[186:189], v[194:197], v[48:51]
	v_mfma_f32_16x16x32_bf16 v[36:39], v[176:179], v[208:211], v[36:39]
	v_mfma_f32_16x16x32_bf16 v[32:35], v[186:189], v[208:211], v[32:35]
	v_mfma_f32_16x16x32_bf16 v[20:23], v[172:175], v[212:215], 0
	v_mfma_f32_16x16x32_bf16 v[16:19], v[182:185], v[212:215], 0
	v_mfma_f32_16x16x32_bf16 v[4:7], v[172:175], v[220:223], 0
	v_mfma_f32_16x16x32_bf16 v[0:3], v[182:185], v[220:223], 0
	v_mfma_f32_16x16x32_bf16 v[20:23], v[176:179], v[216:219], v[20:23]
	v_mfma_f32_16x16x32_bf16 v[16:19], v[186:189], v[216:219], v[16:19]
	v_lshl_add_u64 v[232:233], s[64:65], 0, v[136:137]
	s_mov_b32 m0, s59
	s_nop 0
	global_load_lds_dwordx4 v[232:233], off
	v_mfma_f32_16x16x32_bf16 v[4:7], v[176:179], v[224:227], v[4:7]
	v_mfma_f32_16x16x32_bf16 v[0:3], v[186:189], v[224:227], v[0:3]
	s_setprio 0
	s_barrier
	s_add_i32 s3, 0, 0x18000
	v_add_u32_e32 v159, s3, v131
	s_add_i32 s33, 0, 0x1c000
	ds_read_b128 v[148:151], v159
	ds_read_b128 v[160:163], v159 offset:1024
	ds_read_b128 v[164:167], v159 offset:2048
	ds_read_b128 v[168:171], v159 offset:3072
	v_add_u32_e32 v159, s33, v131
	ds_read_b128 v[172:175], v159
	ds_read_b128 v[176:179], v159 offset:1024
	ds_read_b128 v[182:185], v159 offset:2048
	ds_read_b128 v[186:189], v159 offset:3072
	s_add_u32 s14, s64, 0x40000
	s_addc_u32 s15, s65, 0
	s_mov_b32 m0, s66
	v_lshl_add_u64 v[234:235], s[14:15], 0, v[132:133]
	ds_read_b128 v[190:193], v157 offset:32768
	ds_read_b128 v[194:197], v157 offset:33792
	ds_read_b128 v[198:201], v157 offset:34816
	ds_read_b128 v[208:211], v157 offset:35840
	ds_read_b128 v[212:215], v157 offset:36864
	ds_read_b128 v[216:219], v157 offset:37888
	ds_read_b128 v[220:223], v157 offset:38912
	ds_read_b128 v[224:227], v157 offset:39936
	global_load_lds_dwordx4 v[234:235], off
	v_lshl_add_u64 v[234:235], s[14:15], 0, v[136:137]
	s_mov_b32 m0, s67
	s_nop 0
	global_load_lds_dwordx4 v[234:235], off
	s_waitcnt vmcnt(8)
	s_waitcnt lgkmcnt(0)
	s_barrier
	s_setprio 1
	s_waitcnt lgkmcnt(0)
	v_mfma_f32_16x16x32_bf16 v[124:127], v[148:151], v[190:193], v[124:127]
	v_mfma_f32_16x16x32_bf16 v[120:123], v[164:167], v[190:193], v[120:123]
	v_mfma_f32_16x16x32_bf16 v[108:111], v[148:151], v[198:201], v[108:111]
	v_mfma_f32_16x16x32_bf16 v[104:107], v[164:167], v[198:201], v[104:107]
	v_mfma_f32_16x16x32_bf16 v[124:127], v[160:163], v[194:197], v[124:127]
	v_mfma_f32_16x16x32_bf16 v[120:123], v[168:171], v[194:197], v[120:123]
	v_mfma_f32_16x16x32_bf16 v[108:111], v[160:163], v[208:211], v[108:111]
	v_mfma_f32_16x16x32_bf16 v[104:107], v[168:171], v[208:211], v[104:107]
	v_mfma_f32_16x16x32_bf16 v[92:95], v[148:151], v[212:215], v[92:95]
	v_mfma_f32_16x16x32_bf16 v[88:91], v[164:167], v[212:215], v[88:91]
	v_mfma_f32_16x16x32_bf16 v[76:79], v[148:151], v[220:223], v[76:79]
	v_mfma_f32_16x16x32_bf16 v[72:75], v[164:167], v[220:223], v[72:75]
	v_mfma_f32_16x16x32_bf16 v[92:95], v[160:163], v[216:219], v[92:95]
	v_mfma_f32_16x16x32_bf16 v[88:91], v[168:171], v[216:219], v[88:91]
	v_mfma_f32_16x16x32_bf16 v[76:79], v[160:163], v[224:227], v[76:79]
	v_mfma_f32_16x16x32_bf16 v[72:75], v[168:171], v[224:227], v[72:75]
	s_setprio 0
	s_setprio 1
	v_mfma_f32_16x16x32_bf16 v[116:119], v[172:175], v[190:193], v[116:119]
	v_mfma_f32_16x16x32_bf16 v[112:115], v[182:185], v[190:193], v[112:115]
	v_mfma_f32_16x16x32_bf16 v[100:103], v[172:175], v[198:201], v[100:103]
	v_mfma_f32_16x16x32_bf16 v[96:99], v[182:185], v[198:201], v[96:99]
	v_mfma_f32_16x16x32_bf16 v[116:119], v[176:179], v[194:197], v[116:119]
	v_mfma_f32_16x16x32_bf16 v[112:115], v[186:189], v[194:197], v[112:115]
	v_mfma_f32_16x16x32_bf16 v[100:103], v[176:179], v[208:211], v[100:103]
	v_mfma_f32_16x16x32_bf16 v[96:99], v[186:189], v[208:211], v[96:99]
	v_mfma_f32_16x16x32_bf16 v[84:87], v[172:175], v[212:215], v[84:87]
	v_mfma_f32_16x16x32_bf16 v[80:83], v[182:185], v[212:215], v[80:83]
	v_mfma_f32_16x16x32_bf16 v[68:71], v[172:175], v[220:223], v[68:71]
	v_mfma_f32_16x16x32_bf16 v[64:67], v[182:185], v[220:223], v[64:67]
	v_mfma_f32_16x16x32_bf16 v[84:87], v[176:179], v[216:219], v[84:87]
	v_mfma_f32_16x16x32_bf16 v[80:83], v[186:189], v[216:219], v[80:83]
	v_mfma_f32_16x16x32_bf16 v[68:71], v[176:179], v[224:227], v[68:71]
	v_mfma_f32_16x16x32_bf16 v[64:67], v[186:189], v[224:227], v[64:67]
	s_setprio 0
	s_barrier
; #define PG8_STAGE(bufoff, gbase, voff) do { _Pragma("unroll") for (int _i = 0; _i < 2; ++_i) \
;         __builtin_amdgcn_global_load_lds((const unsigned*)((const char*)(gbase) + (voff)[_i]), (PG8_LAS unsigned*)(lds + (bufoff) + ldsw + _i * 8192), 16, 0, 0); } while (0)
; #define PG8_LDA(dst, b, h) do { _Pragma("unroll") for (int m = 0; m < 4; ++m) _Pragma("unroll") for (int k = 0; k < 2; ++k) dst[m][k] = *(const PG8_LAS bf16x8*)(lds + PG8_SA(b, h) + aoff + m * 2048 + k * 1024); } while (0)
; #define PG8_LDB(dst, b, h) do { _Pragma("unroll") for (int n = 0; n < 2; ++n) _Pragma("unroll") for (int k = 0; k < 2; ++k) dst[n][k] = *(const PG8_LAS bf16x8*)(lds + PG8_SB(b, h) + boff + n * 2048 + k * 1024); } while (0)
; #define PG8_MMA(ai, bj, At, Bt) do { __builtin_amdgcn_s_setprio(1); _Pragma("unroll") for (int m = 0; m < 4; ++m) _Pragma("unroll") for (int n = 0; n < 2; ++n) _Pragma("unroll") for (int k = 0; k < 2; ++k) \
;         acc[ai][bj][m][n] = __builtin_amdgcn_mfma_f32_16x16x32_bf16(Bt[n][k], At[m][k], acc[ai][bj][m][n], 0, 0, 0); __builtin_amdgcn_s_setprio(0); } while (0)
; #define PG8_WAIT_V(n) asm volatile("s_waitcnt vmcnt(" #n ")" ::: "memory")
; #define PG8_WAIT_L(n) asm volatile("s_waitcnt lgkmcnt(" #n ")" ::: "memory")
; #define PG8_BAR __builtin_amdgcn_s_barrier()
; #define PG8_SCHED __builtin_amdgcn_sched_barrier(0)
; template <class Epi, class Sched, bool ALIGN_EPI = false, bool SP2 = false>
; __device__ __forceinline__ void gemm_phase(PG8_LAS unsigned char* lds, const Gemm g, const Sched& S, const Epi& E) {
;     ...
;             PG8_LDB(B0, 0, 0); PG8_LDB(B1, 0, 1); PG8_SCHED; PG8_LDA(At, 0, 0); PG8_STAGE(PG8_SA(1, 1), a1 + hstep, voffA);
;     ...
;             PG8_LDA(At, 1, 1); PG8_STAGE(PG8_SB(1, 0), b3, voffB); PG8_STAGE(PG8_SB(1, 1), b3 + hstep, voffB); PG8_STAGE(PG8_SA(1, 0), a3, voffA);
;             PG8_WAIT_V(8); PG8_WAIT_L(0); PG8_BAR; PG8_MMA(1, 0, At, B0); PG8_MMA(1, 1, At, B1); PG8_BAR; PG8_SCHED;
	s_add_i32 s3, s3, s34
	v_lshl_add_u64 v[202:203], v[202:203], 0, s[38:39]
	s_mov_b32 m0, s3
	ds_read_b128 v[190:193], v157 offset:49152
	ds_read_b128 v[194:197], v157 offset:50176
	ds_read_b128 v[198:201], v157 offset:51200
	ds_read_b128 v[208:211], v157 offset:52224
	ds_read_b128 v[212:215], v157 offset:53248
	ds_read_b128 v[216:219], v157 offset:54272
	ds_read_b128 v[220:223], v157 offset:55296
	ds_read_b128 v[224:227], v157 offset:56320
	global_load_lds_dwordx4 v[202:203], off
	s_add_i32 m0, s3, 0x2000
	s_add_u32 s14, s62, 0x40080
	v_lshl_add_u64 v[202:203], v[228:229], 0, s[38:39]
	s_addc_u32 s15, s63, 0
	s_add_i32 s3, s33, s34
	global_load_lds_dwordx4 v[202:203], off
	v_lshl_add_u64 v[202:203], s[14:15], 0, v[134:135]
	s_mov_b32 m0, s3
	s_nop 0
	global_load_lds_dwordx4 v[202:203], off
	v_lshl_add_u64 v[202:203], s[14:15], 0, v[138:139]
	s_add_i32 m0, s3, 0x2000
	s_nop 0
	global_load_lds_dwordx4 v[202:203], off
	s_waitcnt vmcnt(6)
	s_waitcnt lgkmcnt(0)
	s_barrier
	s_setprio 1
	s_waitcnt lgkmcnt(0)
	v_mfma_f32_16x16x32_bf16 v[60:63], v[148:151], v[190:193], v[60:63]
	v_mfma_f32_16x16x32_bf16 v[56:59], v[164:167], v[190:193], v[56:59]
	v_mfma_f32_16x16x32_bf16 v[44:47], v[148:151], v[198:201], v[44:47]
	v_mfma_f32_16x16x32_bf16 v[40:43], v[164:167], v[198:201], v[40:43]
	v_mfma_f32_16x16x32_bf16 v[60:63], v[160:163], v[194:197], v[60:63]
	v_mfma_f32_16x16x32_bf16 v[56:59], v[168:171], v[194:197], v[56:59]
	v_mfma_f32_16x16x32_bf16 v[44:47], v[160:163], v[208:211], v[44:47]
	v_mfma_f32_16x16x32_bf16 v[40:43], v[168:171], v[208:211], v[40:43]
	v_mfma_f32_16x16x32_bf16 v[28:31], v[148:151], v[212:215], v[28:31]
	v_mfma_f32_16x16x32_bf16 v[24:27], v[164:167], v[212:215], v[24:27]
	v_mfma_f32_16x16x32_bf16 v[12:15], v[148:151], v[220:223], v[12:15]
	v_mfma_f32_16x16x32_bf16 v[8:11], v[164:167], v[220:223], v[8:11]
	v_mfma_f32_16x16x32_bf16 v[28:31], v[160:163], v[216:219], v[28:31]
	v_mfma_f32_16x16x32_bf16 v[24:27], v[168:171], v[216:219], v[24:27]
	v_lshl_add_u64 v[202:203], v[230:231], 0, s[38:39]
	s_mov_b32 m0, s75
	s_nop 0
	global_load_lds_dwordx4 v[202:203], off
	v_mfma_f32_16x16x32_bf16 v[12:15], v[160:163], v[224:227], v[12:15]
	v_mfma_f32_16x16x32_bf16 v[8:11], v[168:171], v[224:227], v[8:11]
	s_setprio 0
	s_setprio 1
	v_mfma_f32_16x16x32_bf16 v[52:55], v[172:175], v[190:193], v[52:55]
	v_mfma_f32_16x16x32_bf16 v[48:51], v[182:185], v[190:193], v[48:51]
	v_mfma_f32_16x16x32_bf16 v[36:39], v[172:175], v[198:201], v[36:39]
	v_mfma_f32_16x16x32_bf16 v[32:35], v[182:185], v[198:201], v[32:35]
	v_mfma_f32_16x16x32_bf16 v[52:55], v[176:179], v[194:197], v[52:55]
	v_mfma_f32_16x16x32_bf16 v[48:51], v[186:189], v[194:197], v[48:51]
	v_mfma_f32_16x16x32_bf16 v[36:39], v[176:179], v[208:211], v[36:39]
	v_mfma_f32_16x16x32_bf16 v[32:35], v[186:189], v[208:211], v[32:35]
	v_mfma_f32_16x16x32_bf16 v[20:23], v[172:175], v[212:215], v[20:23]
	v_mfma_f32_16x16x32_bf16 v[16:19], v[182:185], v[212:215], v[16:19]
	v_mfma_f32_16x16x32_bf16 v[4:7], v[172:175], v[220:223], v[4:7]
	v_mfma_f32_16x16x32_bf16 v[0:3], v[182:185], v[220:223], v[0:3]
	v_mfma_f32_16x16x32_bf16 v[20:23], v[176:179], v[216:219], v[20:23]
	v_mfma_f32_16x16x32_bf16 v[16:19], v[186:189], v[216:219], v[16:19]
	v_lshl_add_u64 v[202:203], v[232:233], 0, s[38:39]
	s_mov_b32 m0, s84
	s_nop 0
	global_load_lds_dwordx4 v[202:203], off
	v_mfma_f32_16x16x32_bf16 v[4:7], v[176:179], v[224:227], v[4:7]
	v_mfma_f32_16x16x32_bf16 v[0:3], v[186:189], v[224:227], v[0:3]
	s_setprio 0
	s_barrier
	s_add_i32 s92, s92, 2
	s_add_u32 s60, s60, 0x100
	s_addc_u32 s61, s61, 0
	s_add_u32 s90, s90, 0x100
	s_addc_u32 s91, s91, 0
.LBB0_650:
	ds_read_b128 v[148:151], v155
	ds_read_b128 v[160:163], v155 offset:1024
	ds_read_b128 v[164:167], v155 offset:2048
	ds_read_b128 v[168:171], v155 offset:3072
	ds_read_b128 v[172:175], v156
	ds_read_b128 v[176:179], v156 offset:1024
	ds_read_b128 v[182:185], v156 offset:2048
	ds_read_b128 v[186:189], v156 offset:3072
	s_add_u32 s3, s60, 0xfffc0080
	s_addc_u32 s14, s61, -1
	s_cmp_eq_u32 s92, 12
	s_cselect_b32 s65, s51, s14
	s_cselect_b32 s64, s57, s3
	s_cselect_b32 s63, s49, s91
	s_cselect_b32 s62, s89, s90
	v_lshl_add_u64 v[202:203], s[60:61], 0, v[140:141]
	s_add_i32 m0, s43, 0xc000
	ds_read_b128 v[190:193], v157
	ds_read_b128 v[194:197], v157 offset:1024
	ds_read_b128 v[198:201], v157 offset:2048
	ds_read_b128 v[208:211], v157 offset:3072
	ds_read_b128 v[212:215], v157 offset:4096
	ds_read_b128 v[216:219], v157 offset:5120
	ds_read_b128 v[220:223], v157 offset:6144
	ds_read_b128 v[224:227], v157 offset:7168
	global_load_lds_dwordx4 v[202:203], off
	v_lshl_add_u64 v[202:203], s[60:61], 0, v[142:143]
	s_add_i32 m0, s43, 0xe000
	s_nop 0
	global_load_lds_dwordx4 v[202:203], off
	s_waitcnt vmcnt(8)
	s_waitcnt lgkmcnt(0)
	s_barrier
; #define PG8_STAGE(bufoff, gbase, voff) do { _Pragma("unroll") for (int _i = 0; _i < 2; ++_i) \
;         __builtin_amdgcn_global_load_lds((const unsigned*)((const char*)(gbase) + (voff)[_i]), (PG8_LAS unsigned*)(lds + (bufoff) + ldsw + _i * 8192), 16, 0, 0); } while (0)
; #define PG8_LDA(dst, b, h) do { _Pragma("unroll") for (int m = 0; m < 4; ++m) _Pragma("unroll") for (int k = 0; k < 2; ++k) dst[m][k] = *(const PG8_LAS bf16x8*)(lds + PG8_SA(b, h) + aoff + m * 2048 + k * 1024); } while (0)
; #define PG8_MMA(ai, bj, At, Bt) do { __builtin_amdgcn_s_setprio(1); _Pragma("unroll") for (int m = 0; m < 4; ++m) _Pragma("unroll") for (int n = 0; n < 2; ++n) _Pragma("unroll") for (int k = 0; k < 2; ++k) \
;         acc[ai][bj][m][n] = __builtin_amdgcn_mfma_f32_16x16x32_bf16(Bt[n][k], At[m][k], acc[ai][bj][m][n], 0, 0, 0); __builtin_amdgcn_s_setprio(0); } while (0)
; #define PG8_WAIT_V(n) asm volatile("s_waitcnt vmcnt(" #n ")" ::: "memory")
; #define PG8_WAIT_L(n) asm volatile("s_waitcnt lgkmcnt(" #n ")" ::: "memory")
; #define PG8_BAR __builtin_amdgcn_s_barrier()
; #define PG8_SCHED __builtin_amdgcn_sched_barrier(0)
; template <class Epi, class Sched, bool ALIGN_EPI = false, bool SP2 = false>
; __device__ __forceinline__ void gemm_phase(PG8_LAS unsigned char* lds, const Gemm g, const Sched& S, const Epi& E) {
;     ...
;             PG8_WAIT_V(8); PG8_WAIT_L(0); PG8_BAR; PG8_MMA(0, 0, At, B0); PG8_MMA(0, 1, At, B1); PG8_BAR; PG8_SCHED;
;             PG8_LDA(At, 0, 1); PG8_STAGE(PG8_SB(0, 0), b2, voffB); PG8_STAGE(PG8_SB(0, 1), b2 + hstep, voffB); PG8_STAGE(PG8_SA(0, 0), a2, voffA);
;             PG8_WAIT_V(8); PG8_WAIT_L(0); PG8_BAR; PG8_MMA(1, 0, At, B0); PG8_MMA(1, 1, At, B1); PG8_BAR; PG8_SCHED;
	s_setprio 1
	s_waitcnt lgkmcnt(0)
	v_mfma_f32_16x16x32_bf16 v[124:127], v[148:151], v[190:193], v[124:127]
	v_mfma_f32_16x16x32_bf16 v[120:123], v[164:167], v[190:193], v[120:123]
	v_mfma_f32_16x16x32_bf16 v[108:111], v[148:151], v[198:201], v[108:111]
	v_mfma_f32_16x16x32_bf16 v[104:107], v[164:167], v[198:201], v[104:107]
	v_mfma_f32_16x16x32_bf16 v[124:127], v[160:163], v[194:197], v[124:127]
	v_mfma_f32_16x16x32_bf16 v[120:123], v[168:171], v[194:197], v[120:123]
	v_mfma_f32_16x16x32_bf16 v[108:111], v[160:163], v[208:211], v[108:111]
	v_mfma_f32_16x16x32_bf16 v[104:107], v[168:171], v[208:211], v[104:107]
	v_mfma_f32_16x16x32_bf16 v[92:95], v[148:151], v[212:215], v[92:95]
	v_mfma_f32_16x16x32_bf16 v[88:91], v[164:167], v[212:215], v[88:91]
	v_mfma_f32_16x16x32_bf16 v[76:79], v[148:151], v[220:223], v[76:79]
	v_mfma_f32_16x16x32_bf16 v[72:75], v[164:167], v[220:223], v[72:75]
	v_mfma_f32_16x16x32_bf16 v[92:95], v[160:163], v[216:219], v[92:95]
	v_mfma_f32_16x16x32_bf16 v[88:91], v[168:171], v[216:219], v[88:91]
	v_mfma_f32_16x16x32_bf16 v[76:79], v[160:163], v[224:227], v[76:79]
	v_mfma_f32_16x16x32_bf16 v[72:75], v[168:171], v[224:227], v[72:75]
	s_setprio 0
	s_setprio 1
	v_mfma_f32_16x16x32_bf16 v[116:119], v[172:175], v[190:193], v[116:119]
	v_mfma_f32_16x16x32_bf16 v[112:115], v[182:185], v[190:193], v[112:115]
	v_mfma_f32_16x16x32_bf16 v[100:103], v[172:175], v[198:201], v[100:103]
	v_mfma_f32_16x16x32_bf16 v[96:99], v[182:185], v[198:201], v[96:99]
	v_mfma_f32_16x16x32_bf16 v[116:119], v[176:179], v[194:197], v[116:119]
	v_mfma_f32_16x16x32_bf16 v[112:115], v[186:189], v[194:197], v[112:115]
	v_mfma_f32_16x16x32_bf16 v[100:103], v[176:179], v[208:211], v[100:103]
	v_mfma_f32_16x16x32_bf16 v[96:99], v[186:189], v[208:211], v[96:99]
	v_mfma_f32_16x16x32_bf16 v[84:87], v[172:175], v[212:215], v[84:87]
	v_mfma_f32_16x16x32_bf16 v[80:83], v[182:185], v[212:215], v[80:83]
	v_mfma_f32_16x16x32_bf16 v[68:71], v[172:175], v[220:223], v[68:71]
	v_mfma_f32_16x16x32_bf16 v[64:67], v[182:185], v[220:223], v[64:67]
	v_mfma_f32_16x16x32_bf16 v[84:87], v[176:179], v[216:219], v[84:87]
	v_mfma_f32_16x16x32_bf16 v[80:83], v[186:189], v[216:219], v[80:83]
	v_mfma_f32_16x16x32_bf16 v[68:71], v[176:179], v[224:227], v[68:71]
	v_mfma_f32_16x16x32_bf16 v[64:67], v[186:189], v[224:227], v[64:67]
	s_setprio 0
	s_barrier
	s_add_i32 s3, s85, s34
	v_lshl_add_u64 v[202:203], s[62:63], 0, v[134:135]
	s_mov_b32 m0, s3
	ds_read_b128 v[190:193], v157 offset:16384
	ds_read_b128 v[194:197], v157 offset:17408
	ds_read_b128 v[198:201], v157 offset:18432
	ds_read_b128 v[208:211], v157 offset:19456
	ds_read_b128 v[212:215], v157 offset:20480
	ds_read_b128 v[216:219], v157 offset:21504
	ds_read_b128 v[220:223], v157 offset:22528
	ds_read_b128 v[224:227], v157 offset:23552
	global_load_lds_dwordx4 v[202:203], off
	s_add_i32 m0, s3, 0x2000
	s_add_u32 s14, s62, 0x40000
	v_lshl_add_u64 v[228:229], s[62:63], 0, v[138:139]
	s_addc_u32 s15, s63, 0
	s_add_i32 s3, s86, s34
	global_load_lds_dwordx4 v[228:229], off
	v_lshl_add_u64 v[230:231], s[14:15], 0, v[134:135]
	s_mov_b32 m0, s3
	global_load_lds_dwordx4 v[230:231], off
	v_lshl_add_u64 v[230:231], s[14:15], 0, v[138:139]
	s_add_i32 m0, s3, 0x2000
	s_nop 0
	global_load_lds_dwordx4 v[230:231], off
	s_waitcnt vmcnt(6)
	s_waitcnt lgkmcnt(0)
	s_barrier
	s_setprio 1
	s_waitcnt lgkmcnt(0)
	v_mfma_f32_16x16x32_bf16 v[60:63], v[148:151], v[190:193], v[60:63]
	v_mfma_f32_16x16x32_bf16 v[56:59], v[164:167], v[190:193], v[56:59]
	v_mfma_f32_16x16x32_bf16 v[44:47], v[148:151], v[198:201], v[44:47]
	v_mfma_f32_16x16x32_bf16 v[40:43], v[164:167], v[198:201], v[40:43]
	v_mfma_f32_16x16x32_bf16 v[60:63], v[160:163], v[194:197], v[60:63]
	v_mfma_f32_16x16x32_bf16 v[56:59], v[168:171], v[194:197], v[56:59]
	v_mfma_f32_16x16x32_bf16 v[44:47], v[160:163], v[208:211], v[44:47]
	v_mfma_f32_16x16x32_bf16 v[40:43], v[168:171], v[208:211], v[40:43]
	v_mfma_f32_16x16x32_bf16 v[28:31], v[148:151], v[212:215], v[28:31]
	v_mfma_f32_16x16x32_bf16 v[24:27], v[164:167], v[212:215], v[24:27]
	v_mfma_f32_16x16x32_bf16 v[12:15], v[148:151], v[220:223], v[12:15]
	v_mfma_f32_16x16x32_bf16 v[8:11], v[164:167], v[220:223], v[8:11]
	v_mfma_f32_16x16x32_bf16 v[28:31], v[160:163], v[216:219], v[28:31]
	v_mfma_f32_16x16x32_bf16 v[24:27], v[168:171], v[216:219], v[24:27]
	v_lshl_add_u64 v[230:231], s[64:65], 0, v[132:133]
	s_mov_b32 m0, s43
	s_nop 0
	global_load_lds_dwordx4 v[230:231], off
	v_mfma_f32_16x16x32_bf16 v[12:15], v[160:163], v[224:227], v[12:15]
	v_mfma_f32_16x16x32_bf16 v[8:11], v[168:171], v[224:227], v[8:11]
	s_setprio 0
	s_setprio 1
	v_mfma_f32_16x16x32_bf16 v[52:55], v[172:175], v[190:193], v[52:55]
	v_mfma_f32_16x16x32_bf16 v[48:51], v[182:185], v[190:193], v[48:51]
	v_mfma_f32_16x16x32_bf16 v[36:39], v[172:175], v[198:201], v[36:39]
	v_mfma_f32_16x16x32_bf16 v[32:35], v[182:185], v[198:201], v[32:35]
	v_mfma_f32_16x16x32_bf16 v[52:55], v[176:179], v[194:197], v[52:55]
	v_mfma_f32_16x16x32_bf16 v[48:51], v[186:189], v[194:197], v[48:51]
	v_mfma_f32_16x16x32_bf16 v[36:39], v[176:179], v[208:211], v[36:39]
	v_mfma_f32_16x16x32_bf16 v[32:35], v[186:189], v[208:211], v[32:35]
	v_mfma_f32_16x16x32_bf16 v[20:23], v[172:175], v[212:215], v[20:23]
	v_mfma_f32_16x16x32_bf16 v[16:19], v[182:185], v[212:215], v[16:19]
	v_mfma_f32_16x16x32_bf16 v[4:7], v[172:175], v[220:223], v[4:7]
	v_mfma_f32_16x16x32_bf16 v[0:3], v[182:185], v[220:223], v[0:3]
	v_mfma_f32_16x16x32_bf16 v[20:23], v[176:179], v[216:219], v[20:23]
	v_mfma_f32_16x16x32_bf16 v[16:19], v[186:189], v[216:219], v[16:19]
	v_lshl_add_u64 v[232:233], s[64:65], 0, v[136:137]
	s_mov_b32 m0, s59
	s_nop 0
	global_load_lds_dwordx4 v[232:233], off
	v_mfma_f32_16x16x32_bf16 v[4:7], v[176:179], v[224:227], v[4:7]
	v_mfma_f32_16x16x32_bf16 v[0:3], v[186:189], v[224:227], v[0:3]
	s_setprio 0
	s_barrier
; #define PG8_STAGE(bufoff, gbase, voff) do { _Pragma("unroll") for (int _i = 0; _i < 2; ++_i) \
;         __builtin_amdgcn_global_load_lds((const unsigned*)((const char*)(gbase) + (voff)[_i]), (PG8_LAS unsigned*)(lds + (bufoff) + ldsw + _i * 8192), 16, 0, 0); } while (0)
; #define PG8_LDA(dst, b, h) do { _Pragma("unroll") for (int m = 0; m < 4; ++m) _Pragma("unroll") for (int k = 0; k < 2; ++k) dst[m][k] = *(const PG8_LAS bf16x8*)(lds + PG8_SA(b, h) + aoff + m * 2048 + k * 1024); } while (0)
; #define PG8_LDB(dst, b, h) do { _Pragma("unroll") for (int n = 0; n < 2; ++n) _Pragma("unroll") for (int k = 0; k < 2; ++k) dst[n][k] = *(const PG8_LAS bf16x8*)(lds + PG8_SB(b, h) + boff + n * 2048 + k * 1024); } while (0)
; #define PG8_MMA(ai, bj, At, Bt) do { __builtin_amdgcn_s_setprio(1); _Pragma("unroll") for (int m = 0; m < 4; ++m) _Pragma("unroll") for (int n = 0; n < 2; ++n) _Pragma("unroll") for (int k = 0; k < 2; ++k) \
;         acc[ai][bj][m][n] = __builtin_amdgcn_mfma_f32_16x16x32_bf16(Bt[n][k], At[m][k], acc[ai][bj][m][n], 0, 0, 0); __builtin_amdgcn_s_setprio(0); } while (0)
; #define PG8_WAIT_V(n) asm volatile("s_waitcnt vmcnt(" #n ")" ::: "memory")
; #define PG8_WAIT_L(n) asm volatile("s_waitcnt lgkmcnt(" #n ")" ::: "memory")
; #define PG8_BAR __builtin_amdgcn_s_barrier()
; #define PG8_SCHED __builtin_amdgcn_sched_barrier(0)
; template <class Epi, class Sched, bool ALIGN_EPI = false, bool SP2 = false>
; __device__ __forceinline__ void gemm_phase(PG8_LAS unsigned char* lds, const Gemm g, const Sched& S, const Epi& E) {
;     ...
;             PG8_LDB(B0, 1, 0); PG8_LDB(B1, 1, 1); PG8_SCHED; PG8_LDA(At, 1, 0); PG8_STAGE(PG8_SA(0, 1), a2 + hstep, voffA);
;             PG8_WAIT_V(8); PG8_WAIT_L(0); PG8_BAR; PG8_MMA(0, 0, At, B0); PG8_MMA(0, 1, At, B1); PG8_BAR; PG8_SCHED;
	s_add_i32 s3, 0, 0x18000
	v_add_u32_e32 v159, s3, v131
	s_add_i32 s33, 0, 0x1c000
	ds_read_b128 v[148:151], v159
	ds_read_b128 v[160:163], v159 offset:1024
	ds_read_b128 v[164:167], v159 offset:2048
	ds_read_b128 v[168:171], v159 offset:3072
	v_add_u32_e32 v159, s33, v131
	ds_read_b128 v[172:175], v159
	ds_read_b128 v[176:179], v159 offset:1024
	ds_read_b128 v[182:185], v159 offset:2048
	ds_read_b128 v[186:189], v159 offset:3072
	s_add_u32 s14, s64, 0x40000
	s_addc_u32 s15, s65, 0
	s_mov_b32 m0, s66
	v_lshl_add_u64 v[234:235], s[14:15], 0, v[132:133]
	ds_read_b128 v[190:193], v157 offset:32768
	ds_read_b128 v[194:197], v157 offset:33792
	ds_read_b128 v[198:201], v157 offset:34816
	ds_read_b128 v[208:211], v157 offset:35840
	ds_read_b128 v[212:215], v157 offset:36864
	ds_read_b128 v[216:219], v157 offset:37888
	ds_read_b128 v[220:223], v157 offset:38912
	ds_read_b128 v[224:227], v157 offset:39936
	global_load_lds_dwordx4 v[234:235], off
	v_lshl_add_u64 v[234:235], s[14:15], 0, v[136:137]
	s_mov_b32 m0, s67
	s_nop 0
	global_load_lds_dwordx4 v[234:235], off
	s_waitcnt vmcnt(8)
	s_waitcnt lgkmcnt(0)
	s_barrier
	s_setprio 1
	s_waitcnt lgkmcnt(0)
	v_mfma_f32_16x16x32_bf16 v[124:127], v[148:151], v[190:193], v[124:127]
	v_mfma_f32_16x16x32_bf16 v[120:123], v[164:167], v[190:193], v[120:123]
	v_mfma_f32_16x16x32_bf16 v[108:111], v[148:151], v[198:201], v[108:111]
	v_mfma_f32_16x16x32_bf16 v[104:107], v[164:167], v[198:201], v[104:107]
	v_mfma_f32_16x16x32_bf16 v[124:127], v[160:163], v[194:197], v[124:127]
	v_mfma_f32_16x16x32_bf16 v[120:123], v[168:171], v[194:197], v[120:123]
	v_mfma_f32_16x16x32_bf16 v[108:111], v[160:163], v[208:211], v[108:111]
	v_mfma_f32_16x16x32_bf16 v[104:107], v[168:171], v[208:211], v[104:107]
	v_mfma_f32_16x16x32_bf16 v[92:95], v[148:151], v[212:215], v[92:95]
	v_mfma_f32_16x16x32_bf16 v[88:91], v[164:167], v[212:215], v[88:91]
	v_mfma_f32_16x16x32_bf16 v[76:79], v[148:151], v[220:223], v[76:79]
	v_mfma_f32_16x16x32_bf16 v[72:75], v[164:167], v[220:223], v[72:75]
	v_mfma_f32_16x16x32_bf16 v[92:95], v[160:163], v[216:219], v[92:95]
	v_mfma_f32_16x16x32_bf16 v[88:91], v[168:171], v[216:219], v[88:91]
	v_mfma_f32_16x16x32_bf16 v[76:79], v[160:163], v[224:227], v[76:79]
	v_mfma_f32_16x16x32_bf16 v[72:75], v[168:171], v[224:227], v[72:75]
	s_setprio 0
	s_setprio 1
	v_mfma_f32_16x16x32_bf16 v[116:119], v[172:175], v[190:193], v[116:119]
	v_mfma_f32_16x16x32_bf16 v[112:115], v[182:185], v[190:193], v[112:115]
	v_mfma_f32_16x16x32_bf16 v[100:103], v[172:175], v[198:201], v[100:103]
	v_mfma_f32_16x16x32_bf16 v[96:99], v[182:185], v[198:201], v[96:99]
	v_mfma_f32_16x16x32_bf16 v[116:119], v[176:179], v[194:197], v[116:119]
	v_mfma_f32_16x16x32_bf16 v[112:115], v[186:189], v[194:197], v[112:115]
	v_mfma_f32_16x16x32_bf16 v[100:103], v[176:179], v[208:211], v[100:103]
	v_mfma_f32_16x16x32_bf16 v[96:99], v[186:189], v[208:211], v[96:99]
	v_mfma_f32_16x16x32_bf16 v[84:87], v[172:175], v[212:215], v[84:87]
	v_mfma_f32_16x16x32_bf16 v[80:83], v[182:185], v[212:215], v[80:83]
	v_mfma_f32_16x16x32_bf16 v[68:71], v[172:175], v[220:223], v[68:71]
	v_mfma_f32_16x16x32_bf16 v[64:67], v[182:185], v[220:223], v[64:67]
	v_mfma_f32_16x16x32_bf16 v[84:87], v[176:179], v[216:219], v[84:87]
	v_mfma_f32_16x16x32_bf16 v[80:83], v[186:189], v[216:219], v[80:83]
	v_mfma_f32_16x16x32_bf16 v[68:71], v[176:179], v[224:227], v[68:71]
	v_mfma_f32_16x16x32_bf16 v[64:67], v[186:189], v[224:227], v[64:67]
	s_setprio 0
	s_barrier
; #define PG8_STAGE(bufoff, gbase, voff) do { _Pragma("unroll") for (int _i = 0; _i < 2; ++_i) \
;         __builtin_amdgcn_global_load_lds((const unsigned*)((const char*)(gbase) + (voff)[_i]), (PG8_LAS unsigned*)(lds + (bufoff) + ldsw + _i * 8192), 16, 0, 0); } while (0)
; #define PG8_LDA(dst, b, h) do { _Pragma("unroll") for (int m = 0; m < 4; ++m) _Pragma("unroll") for (int k = 0; k < 2; ++k) dst[m][k] = *(const PG8_LAS bf16x8*)(lds + PG8_SA(b, h) + aoff + m * 2048 + k * 1024); } while (0)
; #define PG8_MMA(ai, bj, At, Bt) do { __builtin_amdgcn_s_setprio(1); _Pragma("unroll") for (int m = 0; m < 4; ++m) _Pragma("unroll") for (int n = 0; n < 2; ++n) _Pragma("unroll") for (int k = 0; k < 2; ++k) \
;         acc[ai][bj][m][n] = __builtin_amdgcn_mfma_f32_16x16x32_bf16(Bt[n][k], At[m][k], acc[ai][bj][m][n], 0, 0, 0); __builtin_amdgcn_s_setprio(0); } while (0)
; #define PG8_WAIT_V(n) asm volatile("s_waitcnt vmcnt(" #n ")" ::: "memory")
; #define PG8_WAIT_L(n) asm volatile("s_waitcnt lgkmcnt(" #n ")" ::: "memory")
; #define PG8_BAR __builtin_amdgcn_s_barrier()
; #define PG8_SCHED __builtin_amdgcn_sched_barrier(0)
; template <class Epi, class Sched, bool ALIGN_EPI = false, bool SP2 = false>
; __device__ __forceinline__ void gemm_phase(PG8_LAS unsigned char* lds, const Gemm g, const Sched& S, const Epi& E) {
;     ...
;             PG8_LDA(At, 1, 1); PG8_STAGE(PG8_SB(1, 0), b3, voffB); PG8_STAGE(PG8_SB(1, 1), b3 + hstep, voffB); PG8_STAGE(PG8_SA(1, 0), a3, voffA);
;             PG8_WAIT_V(8); PG8_WAIT_L(0); PG8_BAR; PG8_MMA(1, 0, At, B0); PG8_MMA(1, 1, At, B1); PG8_BAR; PG8_SCHED;
;     ...
;         if constexpr (ALIGN_EPI) { if (wr == 0) PG8_BAR; }
	s_add_i32 s3, s3, s34
	v_lshl_add_u64 v[202:203], v[202:203], 0, s[38:39]
	s_mov_b32 m0, s3
	ds_read_b128 v[190:193], v157 offset:49152
	ds_read_b128 v[194:197], v157 offset:50176
	ds_read_b128 v[198:201], v157 offset:51200
	ds_read_b128 v[208:211], v157 offset:52224
	ds_read_b128 v[212:215], v157 offset:53248
	ds_read_b128 v[216:219], v157 offset:54272
	ds_read_b128 v[220:223], v157 offset:55296
	ds_read_b128 v[224:227], v157 offset:56320
	global_load_lds_dwordx4 v[202:203], off
	s_add_i32 m0, s3, 0x2000
	s_add_u32 s14, s62, 0x40080
	v_lshl_add_u64 v[202:203], v[228:229], 0, s[38:39]
	s_addc_u32 s15, s63, 0
	s_add_i32 s3, s33, s34
	global_load_lds_dwordx4 v[202:203], off
	v_lshl_add_u64 v[202:203], s[14:15], 0, v[134:135]
	s_mov_b32 m0, s3
	s_nop 0
	global_load_lds_dwordx4 v[202:203], off
	v_lshl_add_u64 v[202:203], s[14:15], 0, v[138:139]
	s_add_i32 m0, s3, 0x2000
	s_nop 0
	global_load_lds_dwordx4 v[202:203], off
	s_waitcnt vmcnt(6)
	s_waitcnt lgkmcnt(0)
	s_barrier
	s_setprio 1
	s_waitcnt lgkmcnt(0)
	v_mfma_f32_16x16x32_bf16 v[60:63], v[148:151], v[190:193], v[60:63]
	v_mfma_f32_16x16x32_bf16 v[56:59], v[164:167], v[190:193], v[56:59]
	v_mfma_f32_16x16x32_bf16 v[44:47], v[148:151], v[198:201], v[44:47]
	v_mfma_f32_16x16x32_bf16 v[40:43], v[164:167], v[198:201], v[40:43]
	v_mfma_f32_16x16x32_bf16 v[60:63], v[160:163], v[194:197], v[60:63]
	v_mfma_f32_16x16x32_bf16 v[56:59], v[168:171], v[194:197], v[56:59]
	v_mfma_f32_16x16x32_bf16 v[44:47], v[160:163], v[208:211], v[44:47]
	v_mfma_f32_16x16x32_bf16 v[40:43], v[168:171], v[208:211], v[40:43]
	v_mfma_f32_16x16x32_bf16 v[28:31], v[148:151], v[212:215], v[28:31]
	v_mfma_f32_16x16x32_bf16 v[24:27], v[164:167], v[212:215], v[24:27]
	v_mfma_f32_16x16x32_bf16 v[12:15], v[148:151], v[220:223], v[12:15]
	v_mfma_f32_16x16x32_bf16 v[8:11], v[164:167], v[220:223], v[8:11]
	v_mfma_f32_16x16x32_bf16 v[28:31], v[160:163], v[216:219], v[28:31]
	v_mfma_f32_16x16x32_bf16 v[24:27], v[168:171], v[216:219], v[24:27]
	v_lshl_add_u64 v[202:203], v[230:231], 0, s[38:39]
	s_mov_b32 m0, s75
	s_nop 0
	global_load_lds_dwordx4 v[202:203], off
	v_mfma_f32_16x16x32_bf16 v[12:15], v[160:163], v[224:227], v[12:15]
	v_mfma_f32_16x16x32_bf16 v[8:11], v[168:171], v[224:227], v[8:11]
	s_setprio 0
	s_setprio 1
	v_mfma_f32_16x16x32_bf16 v[52:55], v[172:175], v[190:193], v[52:55]
	v_mfma_f32_16x16x32_bf16 v[48:51], v[182:185], v[190:193], v[48:51]
	v_mfma_f32_16x16x32_bf16 v[36:39], v[172:175], v[198:201], v[36:39]
	v_mfma_f32_16x16x32_bf16 v[32:35], v[182:185], v[198:201], v[32:35]
	v_mfma_f32_16x16x32_bf16 v[52:55], v[176:179], v[194:197], v[52:55]
	v_mfma_f32_16x16x32_bf16 v[48:51], v[186:189], v[194:197], v[48:51]
	v_mfma_f32_16x16x32_bf16 v[36:39], v[176:179], v[208:211], v[36:39]
	v_mfma_f32_16x16x32_bf16 v[32:35], v[186:189], v[208:211], v[32:35]
	v_mfma_f32_16x16x32_bf16 v[20:23], v[172:175], v[212:215], v[20:23]
	v_mfma_f32_16x16x32_bf16 v[16:19], v[182:185], v[212:215], v[16:19]
	v_mfma_f32_16x16x32_bf16 v[4:7], v[172:175], v[220:223], v[4:7]
	v_mfma_f32_16x16x32_bf16 v[0:3], v[182:185], v[220:223], v[0:3]
	v_mfma_f32_16x16x32_bf16 v[20:23], v[176:179], v[216:219], v[20:23]
	v_mfma_f32_16x16x32_bf16 v[16:19], v[186:189], v[216:219], v[16:19]
	v_lshl_add_u64 v[202:203], v[232:233], 0, s[38:39]
	s_mov_b32 m0, s84
	s_nop 0
	global_load_lds_dwordx4 v[202:203], off
	v_mfma_f32_16x16x32_bf16 v[4:7], v[176:179], v[224:227], v[4:7]
	v_mfma_f32_16x16x32_bf16 v[0:3], v[186:189], v[224:227], v[0:3]
	s_setprio 0
	s_barrier
	s_add_i32 s92, s92, 2
	s_add_u32 s60, s60, 0x100
	s_addc_u32 s61, s61, 0
	s_add_u32 s90, s90, 0x100
	s_addc_u32 s91, s91, 0
	s_cmp_gt_u32 s92, 13
	s_cbranch_scc0 .LBB0_650
	s_and_b64 vcc, exec, s[44:45]
	s_cbranch_vccz .LBB0_653
	s_barrier

; #define PG8_STAGE(bufoff, gbase, voff) do { _Pragma("unroll") for (int _i = 0; _i < 2; ++_i) \
;         __builtin_amdgcn_global_load_lds((const unsigned*)((const char*)(gbase) + (voff)[_i]), (PG8_LAS unsigned*)(lds + (bufoff) + ldsw + _i * 8192), 16, 0, 0); } while (0)
; #define PG8_LDA(dst, b, h) do { _Pragma("unroll") for (int m = 0; m < 4; ++m) _Pragma("unroll") for (int k = 0; k < 2; ++k) dst[m][k] = *(const PG8_LAS bf16x8*)(lds + PG8_SA(b, h) + aoff + m * 2048 + k * 1024); } while (0)
; #define PG8_LDB(dst, b, h) do { _Pragma("unroll") for (int n = 0; n < 2; ++n) _Pragma("unroll") for (int k = 0; k < 2; ++k) dst[n][k] = *(const PG8_LAS bf16x8*)(lds + PG8_SB(b, h) + boff + n * 2048 + k * 1024); } while (0)
; #define PG8_WAIT_V(n) asm volatile("s_waitcnt vmcnt(" #n ")" ::: "memory")
; #define PG8_WAIT_L(n) asm volatile("s_waitcnt lgkmcnt(" #n ")" ::: "memory")
; #define PG8_BAR __builtin_amdgcn_s_barrier()
; #define PG8_SCHED __builtin_amdgcn_sched_barrier(0)
; template <class Epi, class Sched, bool ALIGN_EPI = false, bool SP2 = false>
; __device__ __forceinline__ void gemm_phase(PG8_LAS unsigned char* lds, const Gemm g, const Sched& S, const Epi& E) {
;     ...
;         const bool has_next = S.next(ui + 1, nxt);
;         const char* nA = has_next ? (const char*)g.A + (size_t)nxt.pm * tstep : cA; const char* nB = has_next ? (const char*)g.Bt + (size_t)nxt.pn * tstep : cB;
;         for (int t = 0; t < nt; t += 2) {
;             const bool last = (t == nt - 2);
;             const char* a1 = cA + (size_t)(t + 1) * kstep;
;             const char* a2 = last ? nA : cA + (size_t)(t + 2) * kstep; const char* b2 = last ? nB : cB + (size_t)(t + 2) * kstep;
;             const char* a3 = a2 + kstep; const char* b3 = b2 + kstep;
;             if (last && has_next) S.a_ready(nxt);
;             if constexpr (SP2) {
;             PG8_LDB(B0, 0, 0); PG8_LDB(B1, 0, 1); PG8_SCHED; PG8_LDA(At, 0, 0); PG8_STAGE(PG8_SA(1, 1), a1 + hstep, voffA);
;             PG8_WAIT_V(8); PG8_WAIT_L(0); PG8_BAR; PG8_MMA(0, 0, At, B0); PG8_MMA(0, 1, At, B1); PG8_BAR; PG8_SCHED;
;             PG8_LDA(At, 0, 1); PG8_STAGE(PG8_SB(0, 0), b2, voffB); PG8_STAGE(PG8_SB(0, 1), b2 + hstep, voffB); PG8_STAGE(PG8_SA(0, 0), a2, voffA);
;             PG8_WAIT_V(8); PG8_WAIT_L(0); PG8_BAR; PG8_MMA(1, 0, At, B0); PG8_MMA(1, 1, At, B1); PG8_BAR; PG8_SCHED;
.LBB0_737:
	s_ashr_i32 s51, s50, 31
	s_lshl_b64 s[14:15], s[50:51], 19
	s_add_u32 s52, s22, s14
	s_addc_u32 s53, s23, s15
	s_and_b64 s[14:15], s[8:9], exec
	s_cselect_b32 s51, s53, s57
	s_cselect_b32 s82, s52, s56
	s_ashr_i32 s49, s48, 31
	s_lshl_b64 s[14:15], s[48:49], 19
	v_readlane_b32 s3, v250, 15
	s_add_u32 s54, s3, s14
	v_readlane_b32 s3, v250, 16
	s_addc_u32 s55, s3, s15
	s_and_b64 s[14:15], s[8:9], exec
	s_cselect_b32 s49, s55, s59
	s_cselect_b32 s83, s54, s58
	s_add_u32 s56, s56, 0x40080
	s_addc_u32 s57, s57, 0
	s_add_u32 s84, s58, 0x100
	s_addc_u32 s85, s59, 0
	s_mov_b32 s86, -2
	s_waitcnt vmcnt(0)
	ds_read_b128 v[148:151], v155
	ds_read_b128 v[160:163], v155 offset:1024
	ds_read_b128 v[164:167], v155 offset:2048
	ds_read_b128 v[168:171], v155 offset:3072
	ds_read_b128 v[172:175], v156
	ds_read_b128 v[176:179], v156 offset:1024
	ds_read_b128 v[182:185], v156 offset:2048
	ds_read_b128 v[186:189], v156 offset:3072
	s_add_u32 s3, s56, 0xfffc0080
	s_addc_u32 s14, s57, -1
	s_cmp_eq_u32 s86, 12
	s_cselect_b32 s61, s51, s14
	s_cselect_b32 s60, s82, s3
	s_cselect_b32 s59, s49, s85
	s_cselect_b32 s58, s83, s84
	v_lshl_add_u64 v[202:203], s[56:57], 0, v[140:141]
	s_add_i32 m0, s43, 0xc000
	ds_read_b128 v[190:193], v157
	ds_read_b128 v[194:197], v157 offset:1024
	ds_read_b128 v[198:201], v157 offset:2048
	ds_read_b128 v[208:211], v157 offset:3072
	ds_read_b128 v[212:215], v157 offset:4096
	ds_read_b128 v[216:219], v157 offset:5120
	ds_read_b128 v[220:223], v157 offset:6144
	ds_read_b128 v[224:227], v157 offset:7168
	global_load_lds_dwordx4 v[202:203], off
	v_lshl_add_u64 v[202:203], s[56:57], 0, v[142:143]
	s_add_i32 m0, s43, 0xe000
	s_nop 0
	global_load_lds_dwordx4 v[202:203], off
	s_waitcnt vmcnt(8)
	s_waitcnt lgkmcnt(0)
	s_barrier
	s_setprio 1
	s_waitcnt lgkmcnt(0)
	v_mfma_f32_16x16x32_bf16 v[124:127], v[148:151], v[190:193], 0
	v_mfma_f32_16x16x32_bf16 v[120:123], v[164:167], v[190:193], 0
	v_mfma_f32_16x16x32_bf16 v[108:111], v[148:151], v[198:201], 0
	v_mfma_f32_16x16x32_bf16 v[104:107], v[164:167], v[198:201], 0
	v_mfma_f32_16x16x32_bf16 v[124:127], v[160:163], v[194:197], v[124:127]
	v_mfma_f32_16x16x32_bf16 v[120:123], v[168:171], v[194:197], v[120:123]
	v_mfma_f32_16x16x32_bf16 v[108:111], v[160:163], v[208:211], v[108:111]
	v_mfma_f32_16x16x32_bf16 v[104:107], v[168:171], v[208:211], v[104:107]
	v_mfma_f32_16x16x32_bf16 v[92:95], v[148:151], v[212:215], 0
	v_mfma_f32_16x16x32_bf16 v[88:91], v[164:167], v[212:215], 0
	v_mfma_f32_16x16x32_bf16 v[76:79], v[148:151], v[220:223], 0
	v_mfma_f32_16x16x32_bf16 v[72:75], v[164:167], v[220:223], 0
	v_mfma_f32_16x16x32_bf16 v[92:95], v[160:163], v[216:219], v[92:95]
	v_mfma_f32_16x16x32_bf16 v[88:91], v[168:171], v[216:219], v[88:91]
	v_mfma_f32_16x16x32_bf16 v[76:79], v[160:163], v[224:227], v[76:79]
	v_mfma_f32_16x16x32_bf16 v[72:75], v[168:171], v[224:227], v[72:75]
	s_setprio 0
	s_setprio 1
	v_mfma_f32_16x16x32_bf16 v[116:119], v[172:175], v[190:193], 0
	v_mfma_f32_16x16x32_bf16 v[112:115], v[182:185], v[190:193], 0
	v_mfma_f32_16x16x32_bf16 v[100:103], v[172:175], v[198:201], 0
	v_mfma_f32_16x16x32_bf16 v[96:99], v[182:185], v[198:201], 0
	v_mfma_f32_16x16x32_bf16 v[116:119], v[176:179], v[194:197], v[116:119]
	v_mfma_f32_16x16x32_bf16 v[112:115], v[186:189], v[194:197], v[112:115]
	v_mfma_f32_16x16x32_bf16 v[100:103], v[176:179], v[208:211], v[100:103]
	v_mfma_f32_16x16x32_bf16 v[96:99], v[186:189], v[208:211], v[96:99]
	v_mfma_f32_16x16x32_bf16 v[84:87], v[172:175], v[212:215], 0
	v_mfma_f32_16x16x32_bf16 v[80:83], v[182:185], v[212:215], 0
	v_mfma_f32_16x16x32_bf16 v[68:71], v[172:175], v[220:223], 0
	v_mfma_f32_16x16x32_bf16 v[64:67], v[182:185], v[220:223], 0
	v_mfma_f32_16x16x32_bf16 v[84:87], v[176:179], v[216:219], v[84:87]
	v_mfma_f32_16x16x32_bf16 v[80:83], v[186:189], v[216:219], v[80:83]
	v_mfma_f32_16x16x32_bf16 v[68:71], v[176:179], v[224:227], v[68:71]
	v_mfma_f32_16x16x32_bf16 v[64:67], v[186:189], v[224:227], v[64:67]
	s_setprio 0
	s_barrier
	s_add_i32 s3, s74, s34
	v_lshl_add_u64 v[202:203], s[58:59], 0, v[136:137]
	s_mov_b32 m0, s3
	ds_read_b128 v[190:193], v157 offset:16384
	ds_read_b128 v[194:197], v157 offset:17408
	ds_read_b128 v[198:201], v157 offset:18432
	ds_read_b128 v[208:211], v157 offset:19456
	ds_read_b128 v[212:215], v157 offset:20480
	ds_read_b128 v[216:219], v157 offset:21504
	ds_read_b128 v[220:223], v157 offset:22528
	ds_read_b128 v[224:227], v157 offset:23552
	global_load_lds_dwordx4 v[202:203], off
	s_add_i32 m0, s3, 0x2000
	s_add_u32 s14, s58, 0x40000
	v_lshl_add_u64 v[228:229], s[58:59], 0, v[132:133]
	s_addc_u32 s15, s59, 0
	s_add_i32 s3, s75, s34
	global_load_lds_dwordx4 v[228:229], off
	v_lshl_add_u64 v[230:231], s[14:15], 0, v[136:137]
	s_mov_b32 m0, s3
	global_load_lds_dwordx4 v[230:231], off
	v_lshl_add_u64 v[230:231], s[14:15], 0, v[132:133]
	s_add_i32 m0, s3, 0x2000
	s_nop 0
	global_load_lds_dwordx4 v[230:231], off
	s_waitcnt vmcnt(6)
	s_waitcnt lgkmcnt(0)
	s_barrier
; #define PG8_STAGE(bufoff, gbase, voff) do { _Pragma("unroll") for (int _i = 0; _i < 2; ++_i) \
;         __builtin_amdgcn_global_load_lds((const unsigned*)((const char*)(gbase) + (voff)[_i]), (PG8_LAS unsigned*)(lds + (bufoff) + ldsw + _i * 8192), 16, 0, 0); } while (0)
; #define PG8_LDA(dst, b, h) do { _Pragma("unroll") for (int m = 0; m < 4; ++m) _Pragma("unroll") for (int k = 0; k < 2; ++k) dst[m][k] = *(const PG8_LAS bf16x8*)(lds + PG8_SA(b, h) + aoff + m * 2048 + k * 1024); } while (0)
; #define PG8_LDB(dst, b, h) do { _Pragma("unroll") for (int n = 0; n < 2; ++n) _Pragma("unroll") for (int k = 0; k < 2; ++k) dst[n][k] = *(const PG8_LAS bf16x8*)(lds + PG8_SB(b, h) + boff + n * 2048 + k * 1024); } while (0)
; #define PG8_MMA(ai, bj, At, Bt) do { __builtin_amdgcn_s_setprio(1); _Pragma("unroll") for (int m = 0; m < 4; ++m) _Pragma("unroll") for (int n = 0; n < 2; ++n) _Pragma("unroll") for (int k = 0; k < 2; ++k) \
;         acc[ai][bj][m][n] = __builtin_amdgcn_mfma_f32_16x16x32_bf16(Bt[n][k], At[m][k], acc[ai][bj][m][n], 0, 0, 0); __builtin_amdgcn_s_setprio(0); } while (0)
; #define PG8_WAIT_V(n) asm volatile("s_waitcnt vmcnt(" #n ")" ::: "memory")
; #define PG8_WAIT_L(n) asm volatile("s_waitcnt lgkmcnt(" #n ")" ::: "memory")
; #define PG8_BAR __builtin_amdgcn_s_barrier()
; #define PG8_SCHED __builtin_amdgcn_sched_barrier(0)
; template <class Epi, class Sched, bool ALIGN_EPI = false, bool SP2 = false>
; __device__ __forceinline__ void gemm_phase(PG8_LAS unsigned char* lds, const Gemm g, const Sched& S, const Epi& E) {
;     ...
;             PG8_WAIT_V(8); PG8_WAIT_L(0); PG8_BAR; PG8_MMA(1, 0, At, B0); PG8_MMA(1, 1, At, B1); PG8_BAR; PG8_SCHED;
;             PG8_LDB(B0, 1, 0); PG8_LDB(B1, 1, 1); PG8_SCHED; PG8_LDA(At, 1, 0); PG8_STAGE(PG8_SA(0, 1), a2 + hstep, voffA);
;             PG8_WAIT_V(8); PG8_WAIT_L(0); PG8_BAR; PG8_MMA(0, 0, At, B0); PG8_MMA(0, 1, At, B1); PG8_BAR; PG8_SCHED;
	s_setprio 1
	s_waitcnt lgkmcnt(0)
	v_mfma_f32_16x16x32_bf16 v[60:63], v[148:151], v[190:193], 0
	v_mfma_f32_16x16x32_bf16 v[56:59], v[164:167], v[190:193], 0
	v_mfma_f32_16x16x32_bf16 v[44:47], v[148:151], v[198:201], 0
	v_mfma_f32_16x16x32_bf16 v[40:43], v[164:167], v[198:201], 0
	v_mfma_f32_16x16x32_bf16 v[60:63], v[160:163], v[194:197], v[60:63]
	v_mfma_f32_16x16x32_bf16 v[56:59], v[168:171], v[194:197], v[56:59]
	v_mfma_f32_16x16x32_bf16 v[44:47], v[160:163], v[208:211], v[44:47]
	v_mfma_f32_16x16x32_bf16 v[40:43], v[168:171], v[208:211], v[40:43]
	v_mfma_f32_16x16x32_bf16 v[28:31], v[148:151], v[212:215], 0
	v_mfma_f32_16x16x32_bf16 v[24:27], v[164:167], v[212:215], 0
	v_mfma_f32_16x16x32_bf16 v[12:15], v[148:151], v[220:223], 0
	v_mfma_f32_16x16x32_bf16 v[8:11], v[164:167], v[220:223], 0
	v_mfma_f32_16x16x32_bf16 v[28:31], v[160:163], v[216:219], v[28:31]
	v_mfma_f32_16x16x32_bf16 v[24:27], v[168:171], v[216:219], v[24:27]
	v_lshl_add_u64 v[230:231], s[60:61], 0, v[138:139]
	s_mov_b32 m0, s43
	s_nop 0
	global_load_lds_dwordx4 v[230:231], off
	v_mfma_f32_16x16x32_bf16 v[12:15], v[160:163], v[224:227], v[12:15]
	v_mfma_f32_16x16x32_bf16 v[8:11], v[168:171], v[224:227], v[8:11]
	s_setprio 0
	s_setprio 1
	v_mfma_f32_16x16x32_bf16 v[52:55], v[172:175], v[190:193], 0
	v_mfma_f32_16x16x32_bf16 v[48:51], v[182:185], v[190:193], 0
	v_mfma_f32_16x16x32_bf16 v[36:39], v[172:175], v[198:201], 0
	v_mfma_f32_16x16x32_bf16 v[32:35], v[182:185], v[198:201], 0
	v_mfma_f32_16x16x32_bf16 v[52:55], v[176:179], v[194:197], v[52:55]
	v_mfma_f32_16x16x32_bf16 v[48:51], v[186:189], v[194:197], v[48:51]
	v_mfma_f32_16x16x32_bf16 v[36:39], v[176:179], v[208:211], v[36:39]
	v_mfma_f32_16x16x32_bf16 v[32:35], v[186:189], v[208:211], v[32:35]
	v_mfma_f32_16x16x32_bf16 v[20:23], v[172:175], v[212:215], 0
	v_mfma_f32_16x16x32_bf16 v[16:19], v[182:185], v[212:215], 0
	v_mfma_f32_16x16x32_bf16 v[4:7], v[172:175], v[220:223], 0
	v_mfma_f32_16x16x32_bf16 v[0:3], v[182:185], v[220:223], 0
	v_mfma_f32_16x16x32_bf16 v[20:23], v[176:179], v[216:219], v[20:23]
	v_mfma_f32_16x16x32_bf16 v[16:19], v[186:189], v[216:219], v[16:19]
	v_lshl_add_u64 v[232:233], s[60:61], 0, v[134:135]
	s_mov_b32 m0, s62
	s_nop 0
	global_load_lds_dwordx4 v[232:233], off
	v_mfma_f32_16x16x32_bf16 v[4:7], v[176:179], v[224:227], v[4:7]
	v_mfma_f32_16x16x32_bf16 v[0:3], v[186:189], v[224:227], v[0:3]
	s_setprio 0
	s_barrier
	s_add_i32 s3, 0, 0x18000
	v_add_u32_e32 v159, s3, v131
	s_add_i32 s33, 0, 0x1c000
	ds_read_b128 v[148:151], v159
	ds_read_b128 v[160:163], v159 offset:1024
	ds_read_b128 v[164:167], v159 offset:2048
	ds_read_b128 v[168:171], v159 offset:3072
	v_add_u32_e32 v159, s33, v131
	ds_read_b128 v[172:175], v159
	ds_read_b128 v[176:179], v159 offset:1024
	ds_read_b128 v[182:185], v159 offset:2048
	ds_read_b128 v[186:189], v159 offset:3072
	s_add_u32 s14, s60, 0x40000
	s_addc_u32 s15, s61, 0
	s_mov_b32 m0, s63
	v_lshl_add_u64 v[234:235], s[14:15], 0, v[138:139]
	ds_read_b128 v[190:193], v157 offset:32768
	ds_read_b128 v[194:197], v157 offset:33792
	ds_read_b128 v[198:201], v157 offset:34816
	ds_read_b128 v[208:211], v157 offset:35840
	ds_read_b128 v[212:215], v157 offset:36864
	ds_read_b128 v[216:219], v157 offset:37888
	ds_read_b128 v[220:223], v157 offset:38912
	ds_read_b128 v[224:227], v157 offset:39936
	global_load_lds_dwordx4 v[234:235], off
	v_lshl_add_u64 v[234:235], s[14:15], 0, v[134:135]
	s_mov_b32 m0, s64
	s_nop 0
	global_load_lds_dwordx4 v[234:235], off
	s_waitcnt vmcnt(8)
	s_waitcnt lgkmcnt(0)
	s_barrier
	s_setprio 1
	s_waitcnt lgkmcnt(0)
	v_mfma_f32_16x16x32_bf16 v[124:127], v[148:151], v[190:193], v[124:127]
	v_mfma_f32_16x16x32_bf16 v[120:123], v[164:167], v[190:193], v[120:123]
	v_mfma_f32_16x16x32_bf16 v[108:111], v[148:151], v[198:201], v[108:111]
	v_mfma_f32_16x16x32_bf16 v[104:107], v[164:167], v[198:201], v[104:107]
	v_mfma_f32_16x16x32_bf16 v[124:127], v[160:163], v[194:197], v[124:127]
	v_mfma_f32_16x16x32_bf16 v[120:123], v[168:171], v[194:197], v[120:123]
	v_mfma_f32_16x16x32_bf16 v[108:111], v[160:163], v[208:211], v[108:111]
	v_mfma_f32_16x16x32_bf16 v[104:107], v[168:171], v[208:211], v[104:107]
	v_mfma_f32_16x16x32_bf16 v[92:95], v[148:151], v[212:215], v[92:95]
	v_mfma_f32_16x16x32_bf16 v[88:91], v[164:167], v[212:215], v[88:91]
	v_mfma_f32_16x16x32_bf16 v[76:79], v[148:151], v[220:223], v[76:79]
	v_mfma_f32_16x16x32_bf16 v[72:75], v[164:167], v[220:223], v[72:75]
	v_mfma_f32_16x16x32_bf16 v[92:95], v[160:163], v[216:219], v[92:95]
	v_mfma_f32_16x16x32_bf16 v[88:91], v[168:171], v[216:219], v[88:91]
	v_mfma_f32_16x16x32_bf16 v[76:79], v[160:163], v[224:227], v[76:79]
	v_mfma_f32_16x16x32_bf16 v[72:75], v[168:171], v[224:227], v[72:75]
	s_setprio 0
	s_setprio 1
	v_mfma_f32_16x16x32_bf16 v[116:119], v[172:175], v[190:193], v[116:119]
	v_mfma_f32_16x16x32_bf16 v[112:115], v[182:185], v[190:193], v[112:115]
	v_mfma_f32_16x16x32_bf16 v[100:103], v[172:175], v[198:201], v[100:103]
	v_mfma_f32_16x16x32_bf16 v[96:99], v[182:185], v[198:201], v[96:99]
	v_mfma_f32_16x16x32_bf16 v[116:119], v[176:179], v[194:197], v[116:119]
	v_mfma_f32_16x16x32_bf16 v[112:115], v[186:189], v[194:197], v[112:115]
	v_mfma_f32_16x16x32_bf16 v[100:103], v[176:179], v[208:211], v[100:103]
	v_mfma_f32_16x16x32_bf16 v[96:99], v[186:189], v[208:211], v[96:99]
	v_mfma_f32_16x16x32_bf16 v[84:87], v[172:175], v[212:215], v[84:87]
	v_mfma_f32_16x16x32_bf16 v[80:83], v[182:185], v[212:215], v[80:83]
	v_mfma_f32_16x16x32_bf16 v[68:71], v[172:175], v[220:223], v[68:71]
	v_mfma_f32_16x16x32_bf16 v[64:67], v[182:185], v[220:223], v[64:67]
	v_mfma_f32_16x16x32_bf16 v[84:87], v[176:179], v[216:219], v[84:87]
	v_mfma_f32_16x16x32_bf16 v[80:83], v[186:189], v[216:219], v[80:83]
	v_mfma_f32_16x16x32_bf16 v[68:71], v[176:179], v[224:227], v[68:71]
	v_mfma_f32_16x16x32_bf16 v[64:67], v[186:189], v[224:227], v[64:67]
	s_setprio 0
	s_barrier
; #define PG8_STAGE(bufoff, gbase, voff) do { _Pragma("unroll") for (int _i = 0; _i < 2; ++_i) \
;         __builtin_amdgcn_global_load_lds((const unsigned*)((const char*)(gbase) + (voff)[_i]), (PG8_LAS unsigned*)(lds + (bufoff) + ldsw + _i * 8192), 16, 0, 0); } while (0)
; #define PG8_LDA(dst, b, h) do { _Pragma("unroll") for (int m = 0; m < 4; ++m) _Pragma("unroll") for (int k = 0; k < 2; ++k) dst[m][k] = *(const PG8_LAS bf16x8*)(lds + PG8_SA(b, h) + aoff + m * 2048 + k * 1024); } while (0)
; #define PG8_LDB(dst, b, h) do { _Pragma("unroll") for (int n = 0; n < 2; ++n) _Pragma("unroll") for (int k = 0; k < 2; ++k) dst[n][k] = *(const PG8_LAS bf16x8*)(lds + PG8_SB(b, h) + boff + n * 2048 + k * 1024); } while (0)
; #define PG8_MMA(ai, bj, At, Bt) do { __builtin_amdgcn_s_setprio(1); _Pragma("unroll") for (int m = 0; m < 4; ++m) _Pragma("unroll") for (int n = 0; n < 2; ++n) _Pragma("unroll") for (int k = 0; k < 2; ++k) \
;         acc[ai][bj][m][n] = __builtin_amdgcn_mfma_f32_16x16x32_bf16(Bt[n][k], At[m][k], acc[ai][bj][m][n], 0, 0, 0); __builtin_amdgcn_s_setprio(0); } while (0)
; #define PG8_WAIT_V(n) asm volatile("s_waitcnt vmcnt(" #n ")" ::: "memory")
; #define PG8_WAIT_L(n) asm volatile("s_waitcnt lgkmcnt(" #n ")" ::: "memory")
; #define PG8_BAR __builtin_amdgcn_s_barrier()
; #define PG8_SCHED __builtin_amdgcn_sched_barrier(0)
; template <class Epi, class Sched, bool ALIGN_EPI = false, bool SP2 = false>
; __device__ __forceinline__ void gemm_phase(PG8_LAS unsigned char* lds, const Gemm g, const Sched& S, const Epi& E) {
;     ...
;             PG8_LDB(B0, 0, 0); PG8_LDB(B1, 0, 1); PG8_SCHED; PG8_LDA(At, 0, 0); PG8_STAGE(PG8_SA(1, 1), a1 + hstep, voffA);
;     ...
;             PG8_LDA(At, 1, 1); PG8_STAGE(PG8_SB(1, 0), b3, voffB); PG8_STAGE(PG8_SB(1, 1), b3 + hstep, voffB); PG8_STAGE(PG8_SA(1, 0), a3, voffA);
;             PG8_WAIT_V(8); PG8_WAIT_L(0); PG8_BAR; PG8_MMA(1, 0, At, B0); PG8_MMA(1, 1, At, B1); PG8_BAR; PG8_SCHED;
	s_add_i32 s3, s3, s34
	v_lshl_add_u64 v[202:203], v[202:203], 0, s[38:39]
	s_mov_b32 m0, s3
	ds_read_b128 v[190:193], v157 offset:49152
	ds_read_b128 v[194:197], v157 offset:50176
	ds_read_b128 v[198:201], v157 offset:51200
	ds_read_b128 v[208:211], v157 offset:52224
	ds_read_b128 v[212:215], v157 offset:53248
	ds_read_b128 v[216:219], v157 offset:54272
	ds_read_b128 v[220:223], v157 offset:55296
	ds_read_b128 v[224:227], v157 offset:56320
	global_load_lds_dwordx4 v[202:203], off
	s_add_i32 m0, s3, 0x2000
	s_add_u32 s14, s58, 0x40080
	v_lshl_add_u64 v[202:203], v[228:229], 0, s[38:39]
	s_addc_u32 s15, s59, 0
	s_add_i32 s3, s33, s34
	global_load_lds_dwordx4 v[202:203], off
	v_lshl_add_u64 v[202:203], s[14:15], 0, v[136:137]
	s_mov_b32 m0, s3
	s_nop 0
	global_load_lds_dwordx4 v[202:203], off
	v_lshl_add_u64 v[202:203], s[14:15], 0, v[132:133]
	s_add_i32 m0, s3, 0x2000
	s_nop 0
	global_load_lds_dwordx4 v[202:203], off
	s_waitcnt vmcnt(6)
	s_waitcnt lgkmcnt(0)
	s_barrier
	s_setprio 1
	s_waitcnt lgkmcnt(0)
	v_mfma_f32_16x16x32_bf16 v[60:63], v[148:151], v[190:193], v[60:63]
	v_mfma_f32_16x16x32_bf16 v[56:59], v[164:167], v[190:193], v[56:59]
	v_mfma_f32_16x16x32_bf16 v[44:47], v[148:151], v[198:201], v[44:47]
	v_mfma_f32_16x16x32_bf16 v[40:43], v[164:167], v[198:201], v[40:43]
	v_mfma_f32_16x16x32_bf16 v[60:63], v[160:163], v[194:197], v[60:63]
	v_mfma_f32_16x16x32_bf16 v[56:59], v[168:171], v[194:197], v[56:59]
	v_mfma_f32_16x16x32_bf16 v[44:47], v[160:163], v[208:211], v[44:47]
	v_mfma_f32_16x16x32_bf16 v[40:43], v[168:171], v[208:211], v[40:43]
	v_mfma_f32_16x16x32_bf16 v[28:31], v[148:151], v[212:215], v[28:31]
	v_mfma_f32_16x16x32_bf16 v[24:27], v[164:167], v[212:215], v[24:27]
	v_mfma_f32_16x16x32_bf16 v[12:15], v[148:151], v[220:223], v[12:15]
	v_mfma_f32_16x16x32_bf16 v[8:11], v[164:167], v[220:223], v[8:11]
	v_mfma_f32_16x16x32_bf16 v[28:31], v[160:163], v[216:219], v[28:31]
	v_mfma_f32_16x16x32_bf16 v[24:27], v[168:171], v[216:219], v[24:27]
	v_lshl_add_u64 v[202:203], v[230:231], 0, s[38:39]
	s_mov_b32 m0, s66
	s_nop 0
	global_load_lds_dwordx4 v[202:203], off
	v_mfma_f32_16x16x32_bf16 v[12:15], v[160:163], v[224:227], v[12:15]
	v_mfma_f32_16x16x32_bf16 v[8:11], v[168:171], v[224:227], v[8:11]
	s_setprio 0
	s_setprio 1
	v_mfma_f32_16x16x32_bf16 v[52:55], v[172:175], v[190:193], v[52:55]
	v_mfma_f32_16x16x32_bf16 v[48:51], v[182:185], v[190:193], v[48:51]
	v_mfma_f32_16x16x32_bf16 v[36:39], v[172:175], v[198:201], v[36:39]
	v_mfma_f32_16x16x32_bf16 v[32:35], v[182:185], v[198:201], v[32:35]
	v_mfma_f32_16x16x32_bf16 v[52:55], v[176:179], v[194:197], v[52:55]
	v_mfma_f32_16x16x32_bf16 v[48:51], v[186:189], v[194:197], v[48:51]
	v_mfma_f32_16x16x32_bf16 v[36:39], v[176:179], v[208:211], v[36:39]
	v_mfma_f32_16x16x32_bf16 v[32:35], v[186:189], v[208:211], v[32:35]
	v_mfma_f32_16x16x32_bf16 v[20:23], v[172:175], v[212:215], v[20:23]
	v_mfma_f32_16x16x32_bf16 v[16:19], v[182:185], v[212:215], v[16:19]
	v_mfma_f32_16x16x32_bf16 v[4:7], v[172:175], v[220:223], v[4:7]
	v_mfma_f32_16x16x32_bf16 v[0:3], v[182:185], v[220:223], v[0:3]
	v_mfma_f32_16x16x32_bf16 v[20:23], v[176:179], v[216:219], v[20:23]
	v_mfma_f32_16x16x32_bf16 v[16:19], v[186:189], v[216:219], v[16:19]
	v_lshl_add_u64 v[202:203], v[232:233], 0, s[38:39]
	s_mov_b32 m0, s67
	s_nop 0
	global_load_lds_dwordx4 v[202:203], off
	v_mfma_f32_16x16x32_bf16 v[4:7], v[176:179], v[224:227], v[4:7]
	v_mfma_f32_16x16x32_bf16 v[0:3], v[186:189], v[224:227], v[0:3]
	s_setprio 0
	s_barrier
	s_add_i32 s86, s86, 2
	s_add_u32 s56, s56, 0x100
	s_addc_u32 s57, s57, 0
	s_add_u32 s84, s84, 0x100
	s_addc_u32 s85, s85, 0
.LBB0_738:
	ds_read_b128 v[148:151], v155
	ds_read_b128 v[160:163], v155 offset:1024
	ds_read_b128 v[164:167], v155 offset:2048
	ds_read_b128 v[168:171], v155 offset:3072
	ds_read_b128 v[172:175], v156
	ds_read_b128 v[176:179], v156 offset:1024
	ds_read_b128 v[182:185], v156 offset:2048
	ds_read_b128 v[186:189], v156 offset:3072
	s_add_u32 s3, s56, 0xfffc0080
	s_addc_u32 s14, s57, -1
	s_cmp_eq_u32 s86, 12
	s_cselect_b32 s61, s51, s14
	s_cselect_b32 s60, s82, s3
	s_cselect_b32 s59, s49, s85
	s_cselect_b32 s58, s83, s84
	v_lshl_add_u64 v[202:203], s[56:57], 0, v[140:141]
	s_add_i32 m0, s43, 0xc000
	ds_read_b128 v[190:193], v157
	ds_read_b128 v[194:197], v157 offset:1024
	ds_read_b128 v[198:201], v157 offset:2048
	ds_read_b128 v[208:211], v157 offset:3072
	ds_read_b128 v[212:215], v157 offset:4096
	ds_read_b128 v[216:219], v157 offset:5120
	ds_read_b128 v[220:223], v157 offset:6144
	ds_read_b128 v[224:227], v157 offset:7168
	global_load_lds_dwordx4 v[202:203], off
	v_lshl_add_u64 v[202:203], s[56:57], 0, v[142:143]
	s_add_i32 m0, s43, 0xe000
	s_nop 0
	global_load_lds_dwordx4 v[202:203], off
	s_waitcnt vmcnt(8)
	s_waitcnt lgkmcnt(0)
	s_barrier
; #define PG8_STAGE(bufoff, gbase, voff) do { _Pragma("unroll") for (int _i = 0; _i < 2; ++_i) \
;         __builtin_amdgcn_global_load_lds((const unsigned*)((const char*)(gbase) + (voff)[_i]), (PG8_LAS unsigned*)(lds + (bufoff) + ldsw + _i * 8192), 16, 0, 0); } while (0)
; #define PG8_LDA(dst, b, h) do { _Pragma("unroll") for (int m = 0; m < 4; ++m) _Pragma("unroll") for (int k = 0; k < 2; ++k) dst[m][k] = *(const PG8_LAS bf16x8*)(lds + PG8_SA(b, h) + aoff + m * 2048 + k * 1024); } while (0)
; #define PG8_LDB(dst, b, h) do { _Pragma("unroll") for (int n = 0; n < 2; ++n) _Pragma("unroll") for (int k = 0; k < 2; ++k) dst[n][k] = *(const PG8_LAS bf16x8*)(lds + PG8_SB(b, h) + boff + n * 2048 + k * 1024); } while (0)
; #define PG8_MMA(ai, bj, At, Bt) do { __builtin_amdgcn_s_setprio(1); _Pragma("unroll") for (int m = 0; m < 4; ++m) _Pragma("unroll") for (int n = 0; n < 2; ++n) _Pragma("unroll") for (int k = 0; k < 2; ++k) \
;         acc[ai][bj][m][n] = __builtin_amdgcn_mfma_f32_16x16x32_bf16(Bt[n][k], At[m][k], acc[ai][bj][m][n], 0, 0, 0); __builtin_amdgcn_s_setprio(0); } while (0)
; #define PG8_WAIT_V(n) asm volatile("s_waitcnt vmcnt(" #n ")" ::: "memory")
; #define PG8_WAIT_L(n) asm volatile("s_waitcnt lgkmcnt(" #n ")" ::: "memory")
; #define PG8_BAR __builtin_amdgcn_s_barrier()
; #define PG8_SCHED __builtin_amdgcn_sched_barrier(0)
; template <class Epi, class Sched, bool ALIGN_EPI = false, bool SP2 = false>
; __device__ __forceinline__ void gemm_phase(PG8_LAS unsigned char* lds, const Gemm g, const Sched& S, const Epi& E) {
;     ...
;             PG8_LDB(B0, 0, 0); PG8_LDB(B1, 0, 1); PG8_SCHED; PG8_LDA(At, 0, 0); PG8_STAGE(PG8_SA(1, 1), a1 + hstep, voffA);
;             PG8_WAIT_V(8); PG8_WAIT_L(0); PG8_BAR; PG8_MMA(0, 0, At, B0); PG8_MMA(0, 1, At, B1); PG8_BAR; PG8_SCHED;
;             PG8_LDA(At, 0, 1); PG8_STAGE(PG8_SB(0, 0), b2, voffB); PG8_STAGE(PG8_SB(0, 1), b2 + hstep, voffB); PG8_STAGE(PG8_SA(0, 0), a2, voffA);
;             PG8_WAIT_V(8); PG8_WAIT_L(0); PG8_BAR; PG8_MMA(1, 0, At, B0); PG8_MMA(1, 1, At, B1); PG8_BAR; PG8_SCHED;
	s_setprio 1
	s_waitcnt lgkmcnt(0)
	v_mfma_f32_16x16x32_bf16 v[124:127], v[148:151], v[190:193], v[124:127]
	v_mfma_f32_16x16x32_bf16 v[120:123], v[164:167], v[190:193], v[120:123]
	v_mfma_f32_16x16x32_bf16 v[108:111], v[148:151], v[198:201], v[108:111]
	v_mfma_f32_16x16x32_bf16 v[104:107], v[164:167], v[198:201], v[104:107]
	v_mfma_f32_16x16x32_bf16 v[124:127], v[160:163], v[194:197], v[124:127]
	v_mfma_f32_16x16x32_bf16 v[120:123], v[168:171], v[194:197], v[120:123]
	v_mfma_f32_16x16x32_bf16 v[108:111], v[160:163], v[208:211], v[108:111]
	v_mfma_f32_16x16x32_bf16 v[104:107], v[168:171], v[208:211], v[104:107]
	v_mfma_f32_16x16x32_bf16 v[92:95], v[148:151], v[212:215], v[92:95]
	v_mfma_f32_16x16x32_bf16 v[88:91], v[164:167], v[212:215], v[88:91]
	v_mfma_f32_16x16x32_bf16 v[76:79], v[148:151], v[220:223], v[76:79]
	v_mfma_f32_16x16x32_bf16 v[72:75], v[164:167], v[220:223], v[72:75]
	v_mfma_f32_16x16x32_bf16 v[92:95], v[160:163], v[216:219], v[92:95]
	v_mfma_f32_16x16x32_bf16 v[88:91], v[168:171], v[216:219], v[88:91]
	v_mfma_f32_16x16x32_bf16 v[76:79], v[160:163], v[224:227], v[76:79]
	v_mfma_f32_16x16x32_bf16 v[72:75], v[168:171], v[224:227], v[72:75]
	s_setprio 0
	s_setprio 1
	v_mfma_f32_16x16x32_bf16 v[116:119], v[172:175], v[190:193], v[116:119]
	v_mfma_f32_16x16x32_bf16 v[112:115], v[182:185], v[190:193], v[112:115]
	v_mfma_f32_16x16x32_bf16 v[100:103], v[172:175], v[198:201], v[100:103]
	v_mfma_f32_16x16x32_bf16 v[96:99], v[182:185], v[198:201], v[96:99]
	v_mfma_f32_16x16x32_bf16 v[116:119], v[176:179], v[194:197], v[116:119]
	v_mfma_f32_16x16x32_bf16 v[112:115], v[186:189], v[194:197], v[112:115]
	v_mfma_f32_16x16x32_bf16 v[100:103], v[176:179], v[208:211], v[100:103]
	v_mfma_f32_16x16x32_bf16 v[96:99], v[186:189], v[208:211], v[96:99]
	v_mfma_f32_16x16x32_bf16 v[84:87], v[172:175], v[212:215], v[84:87]
	v_mfma_f32_16x16x32_bf16 v[80:83], v[182:185], v[212:215], v[80:83]
	v_mfma_f32_16x16x32_bf16 v[68:71], v[172:175], v[220:223], v[68:71]
	v_mfma_f32_16x16x32_bf16 v[64:67], v[182:185], v[220:223], v[64:67]
	v_mfma_f32_16x16x32_bf16 v[84:87], v[176:179], v[216:219], v[84:87]
	v_mfma_f32_16x16x32_bf16 v[80:83], v[186:189], v[216:219], v[80:83]
	v_mfma_f32_16x16x32_bf16 v[68:71], v[176:179], v[224:227], v[68:71]
	v_mfma_f32_16x16x32_bf16 v[64:67], v[186:189], v[224:227], v[64:67]
	s_setprio 0
	s_barrier
	s_add_i32 s3, s74, s34
	v_lshl_add_u64 v[202:203], s[58:59], 0, v[136:137]
	s_mov_b32 m0, s3
	ds_read_b128 v[190:193], v157 offset:16384
	ds_read_b128 v[194:197], v157 offset:17408
	ds_read_b128 v[198:201], v157 offset:18432
	ds_read_b128 v[208:211], v157 offset:19456
	ds_read_b128 v[212:215], v157 offset:20480
	ds_read_b128 v[216:219], v157 offset:21504
	ds_read_b128 v[220:223], v157 offset:22528
	ds_read_b128 v[224:227], v157 offset:23552
	global_load_lds_dwordx4 v[202:203], off
	s_add_i32 m0, s3, 0x2000
	s_add_u32 s14, s58, 0x40000
	v_lshl_add_u64 v[228:229], s[58:59], 0, v[132:133]
	s_addc_u32 s15, s59, 0
	s_add_i32 s3, s75, s34
	global_load_lds_dwordx4 v[228:229], off
	v_lshl_add_u64 v[230:231], s[14:15], 0, v[136:137]
	s_mov_b32 m0, s3
	global_load_lds_dwordx4 v[230:231], off
	v_lshl_add_u64 v[230:231], s[14:15], 0, v[132:133]
	s_add_i32 m0, s3, 0x2000
	s_nop 0
	global_load_lds_dwordx4 v[230:231], off
	s_waitcnt vmcnt(6)
	s_waitcnt lgkmcnt(0)
	s_barrier
	s_setprio 1
	s_waitcnt lgkmcnt(0)
	v_mfma_f32_16x16x32_bf16 v[60:63], v[148:151], v[190:193], v[60:63]
	v_mfma_f32_16x16x32_bf16 v[56:59], v[164:167], v[190:193], v[56:59]
	v_mfma_f32_16x16x32_bf16 v[44:47], v[148:151], v[198:201], v[44:47]
	v_mfma_f32_16x16x32_bf16 v[40:43], v[164:167], v[198:201], v[40:43]
	v_mfma_f32_16x16x32_bf16 v[60:63], v[160:163], v[194:197], v[60:63]
	v_mfma_f32_16x16x32_bf16 v[56:59], v[168:171], v[194:197], v[56:59]
	v_mfma_f32_16x16x32_bf16 v[44:47], v[160:163], v[208:211], v[44:47]
	v_mfma_f32_16x16x32_bf16 v[40:43], v[168:171], v[208:211], v[40:43]
	v_mfma_f32_16x16x32_bf16 v[28:31], v[148:151], v[212:215], v[28:31]
	v_mfma_f32_16x16x32_bf16 v[24:27], v[164:167], v[212:215], v[24:27]
	v_mfma_f32_16x16x32_bf16 v[12:15], v[148:151], v[220:223], v[12:15]
	v_mfma_f32_16x16x32_bf16 v[8:11], v[164:167], v[220:223], v[8:11]
	v_mfma_f32_16x16x32_bf16 v[28:31], v[160:163], v[216:219], v[28:31]
	v_mfma_f32_16x16x32_bf16 v[24:27], v[168:171], v[216:219], v[24:27]
	v_lshl_add_u64 v[230:231], s[60:61], 0, v[138:139]
	s_mov_b32 m0, s43
	s_nop 0
	global_load_lds_dwordx4 v[230:231], off
	v_mfma_f32_16x16x32_bf16 v[12:15], v[160:163], v[224:227], v[12:15]
	v_mfma_f32_16x16x32_bf16 v[8:11], v[168:171], v[224:227], v[8:11]
	s_setprio 0
	s_setprio 1
	v_mfma_f32_16x16x32_bf16 v[52:55], v[172:175], v[190:193], v[52:55]
	v_mfma_f32_16x16x32_bf16 v[48:51], v[182:185], v[190:193], v[48:51]
	v_mfma_f32_16x16x32_bf16 v[36:39], v[172:175], v[198:201], v[36:39]
	v_mfma_f32_16x16x32_bf16 v[32:35], v[182:185], v[198:201], v[32:35]
	v_mfma_f32_16x16x32_bf16 v[52:55], v[176:179], v[194:197], v[52:55]
	v_mfma_f32_16x16x32_bf16 v[48:51], v[186:189], v[194:197], v[48:51]
	v_mfma_f32_16x16x32_bf16 v[36:39], v[176:179], v[208:211], v[36:39]
	v_mfma_f32_16x16x32_bf16 v[32:35], v[186:189], v[208:211], v[32:35]
	v_mfma_f32_16x16x32_bf16 v[20:23], v[172:175], v[212:215], v[20:23]
	v_mfma_f32_16x16x32_bf16 v[16:19], v[182:185], v[212:215], v[16:19]
	v_mfma_f32_16x16x32_bf16 v[4:7], v[172:175], v[220:223], v[4:7]
	v_mfma_f32_16x16x32_bf16 v[0:3], v[182:185], v[220:223], v[0:3]
	v_mfma_f32_16x16x32_bf16 v[20:23], v[176:179], v[216:219], v[20:23]
	v_mfma_f32_16x16x32_bf16 v[16:19], v[186:189], v[216:219], v[16:19]
	v_lshl_add_u64 v[232:233], s[60:61], 0, v[134:135]
	s_mov_b32 m0, s62
	s_nop 0
	global_load_lds_dwordx4 v[232:233], off
	v_mfma_f32_16x16x32_bf16 v[4:7], v[176:179], v[224:227], v[4:7]
	v_mfma_f32_16x16x32_bf16 v[0:3], v[186:189], v[224:227], v[0:3]
	s_setprio 0
	s_barrier
; #define PG8_STAGE(bufoff, gbase, voff) do { _Pragma("unroll") for (int _i = 0; _i < 2; ++_i) \
;         __builtin_amdgcn_global_load_lds((const unsigned*)((const char*)(gbase) + (voff)[_i]), (PG8_LAS unsigned*)(lds + (bufoff) + ldsw + _i * 8192), 16, 0, 0); } while (0)
; #define PG8_LDA(dst, b, h) do { _Pragma("unroll") for (int m = 0; m < 4; ++m) _Pragma("unroll") for (int k = 0; k < 2; ++k) dst[m][k] = *(const PG8_LAS bf16x8*)(lds + PG8_SA(b, h) + aoff + m * 2048 + k * 1024); } while (0)
; #define PG8_LDB(dst, b, h) do { _Pragma("unroll") for (int n = 0; n < 2; ++n) _Pragma("unroll") for (int k = 0; k < 2; ++k) dst[n][k] = *(const PG8_LAS bf16x8*)(lds + PG8_SB(b, h) + boff + n * 2048 + k * 1024); } while (0)
; #define PG8_MMA(ai, bj, At, Bt) do { __builtin_amdgcn_s_setprio(1); _Pragma("unroll") for (int m = 0; m < 4; ++m) _Pragma("unroll") for (int n = 0; n < 2; ++n) _Pragma("unroll") for (int k = 0; k < 2; ++k) \
;         acc[ai][bj][m][n] = __builtin_amdgcn_mfma_f32_16x16x32_bf16(Bt[n][k], At[m][k], acc[ai][bj][m][n], 0, 0, 0); __builtin_amdgcn_s_setprio(0); } while (0)
; #define PG8_WAIT_V(n) asm volatile("s_waitcnt vmcnt(" #n ")" ::: "memory")
; #define PG8_WAIT_L(n) asm volatile("s_waitcnt lgkmcnt(" #n ")" ::: "memory")
; #define PG8_BAR __builtin_amdgcn_s_barrier()
; #define PG8_SCHED __builtin_amdgcn_sched_barrier(0)
; template <class Epi, class Sched, bool ALIGN_EPI = false, bool SP2 = false>
; __device__ __forceinline__ void gemm_phase(PG8_LAS unsigned char* lds, const Gemm g, const Sched& S, const Epi& E) {
;     ...
;             PG8_LDB(B0, 1, 0); PG8_LDB(B1, 1, 1); PG8_SCHED; PG8_LDA(At, 1, 0); PG8_STAGE(PG8_SA(0, 1), a2 + hstep, voffA);
;             PG8_WAIT_V(8); PG8_WAIT_L(0); PG8_BAR; PG8_MMA(0, 0, At, B0); PG8_MMA(0, 1, At, B1); PG8_BAR; PG8_SCHED;
	s_add_i32 s3, 0, 0x18000
	v_add_u32_e32 v159, s3, v131
	s_add_i32 s33, 0, 0x1c000
	ds_read_b128 v[148:151], v159
	ds_read_b128 v[160:163], v159 offset:1024
	ds_read_b128 v[164:167], v159 offset:2048
	ds_read_b128 v[168:171], v159 offset:3072
	v_add_u32_e32 v159, s33, v131
	ds_read_b128 v[172:175], v159
	ds_read_b128 v[176:179], v159 offset:1024
	ds_read_b128 v[182:185], v159 offset:2048
	ds_read_b128 v[186:189], v159 offset:3072
	s_add_u32 s14, s60, 0x40000
	s_addc_u32 s15, s61, 0
	s_mov_b32 m0, s63
	v_lshl_add_u64 v[234:235], s[14:15], 0, v[138:139]
	ds_read_b128 v[190:193], v157 offset:32768
	ds_read_b128 v[194:197], v157 offset:33792
	ds_read_b128 v[198:201], v157 offset:34816
	ds_read_b128 v[208:211], v157 offset:35840
	ds_read_b128 v[212:215], v157 offset:36864
	ds_read_b128 v[216:219], v157 offset:37888
	ds_read_b128 v[220:223], v157 offset:38912
	ds_read_b128 v[224:227], v157 offset:39936
	global_load_lds_dwordx4 v[234:235], off
	v_lshl_add_u64 v[234:235], s[14:15], 0, v[134:135]
	s_mov_b32 m0, s64
	s_nop 0
	global_load_lds_dwordx4 v[234:235], off
	s_waitcnt vmcnt(8)
	s_waitcnt lgkmcnt(0)
	s_barrier
	s_setprio 1
	s_waitcnt lgkmcnt(0)
	v_mfma_f32_16x16x32_bf16 v[124:127], v[148:151], v[190:193], v[124:127]
	v_mfma_f32_16x16x32_bf16 v[120:123], v[164:167], v[190:193], v[120:123]
	v_mfma_f32_16x16x32_bf16 v[108:111], v[148:151], v[198:201], v[108:111]
	v_mfma_f32_16x16x32_bf16 v[104:107], v[164:167], v[198:201], v[104:107]
	v_mfma_f32_16x16x32_bf16 v[124:127], v[160:163], v[194:197], v[124:127]
	v_mfma_f32_16x16x32_bf16 v[120:123], v[168:171], v[194:197], v[120:123]
	v_mfma_f32_16x16x32_bf16 v[108:111], v[160:163], v[208:211], v[108:111]
	v_mfma_f32_16x16x32_bf16 v[104:107], v[168:171], v[208:211], v[104:107]
	v_mfma_f32_16x16x32_bf16 v[92:95], v[148:151], v[212:215], v[92:95]
	v_mfma_f32_16x16x32_bf16 v[88:91], v[164:167], v[212:215], v[88:91]
	v_mfma_f32_16x16x32_bf16 v[76:79], v[148:151], v[220:223], v[76:79]
	v_mfma_f32_16x16x32_bf16 v[72:75], v[164:167], v[220:223], v[72:75]
	v_mfma_f32_16x16x32_bf16 v[92:95], v[160:163], v[216:219], v[92:95]
	v_mfma_f32_16x16x32_bf16 v[88:91], v[168:171], v[216:219], v[88:91]
	v_mfma_f32_16x16x32_bf16 v[76:79], v[160:163], v[224:227], v[76:79]
	v_mfma_f32_16x16x32_bf16 v[72:75], v[168:171], v[224:227], v[72:75]
	s_setprio 0
	s_setprio 1
	v_mfma_f32_16x16x32_bf16 v[116:119], v[172:175], v[190:193], v[116:119]
	v_mfma_f32_16x16x32_bf16 v[112:115], v[182:185], v[190:193], v[112:115]
	v_mfma_f32_16x16x32_bf16 v[100:103], v[172:175], v[198:201], v[100:103]
	v_mfma_f32_16x16x32_bf16 v[96:99], v[182:185], v[198:201], v[96:99]
	v_mfma_f32_16x16x32_bf16 v[116:119], v[176:179], v[194:197], v[116:119]
	v_mfma_f32_16x16x32_bf16 v[112:115], v[186:189], v[194:197], v[112:115]
	v_mfma_f32_16x16x32_bf16 v[100:103], v[176:179], v[208:211], v[100:103]
	v_mfma_f32_16x16x32_bf16 v[96:99], v[186:189], v[208:211], v[96:99]
	v_mfma_f32_16x16x32_bf16 v[84:87], v[172:175], v[212:215], v[84:87]
	v_mfma_f32_16x16x32_bf16 v[80:83], v[182:185], v[212:215], v[80:83]
	v_mfma_f32_16x16x32_bf16 v[68:71], v[172:175], v[220:223], v[68:71]
	v_mfma_f32_16x16x32_bf16 v[64:67], v[182:185], v[220:223], v[64:67]
	v_mfma_f32_16x16x32_bf16 v[84:87], v[176:179], v[216:219], v[84:87]
	v_mfma_f32_16x16x32_bf16 v[80:83], v[186:189], v[216:219], v[80:83]
	v_mfma_f32_16x16x32_bf16 v[68:71], v[176:179], v[224:227], v[68:71]
	v_mfma_f32_16x16x32_bf16 v[64:67], v[186:189], v[224:227], v[64:67]
	s_setprio 0
	s_barrier
; #define PG8_STAGE(bufoff, gbase, voff) do { _Pragma("unroll") for (int _i = 0; _i < 2; ++_i) \
;         __builtin_amdgcn_global_load_lds((const unsigned*)((const char*)(gbase) + (voff)[_i]), (PG8_LAS unsigned*)(lds + (bufoff) + ldsw + _i * 8192), 16, 0, 0); } while (0)
; #define PG8_LDA(dst, b, h) do { _Pragma("unroll") for (int m = 0; m < 4; ++m) _Pragma("unroll") for (int k = 0; k < 2; ++k) dst[m][k] = *(const PG8_LAS bf16x8*)(lds + PG8_SA(b, h) + aoff + m * 2048 + k * 1024); } while (0)
; #define PG8_MMA(ai, bj, At, Bt) do { __builtin_amdgcn_s_setprio(1); _Pragma("unroll") for (int m = 0; m < 4; ++m) _Pragma("unroll") for (int n = 0; n < 2; ++n) _Pragma("unroll") for (int k = 0; k < 2; ++k) \
;         acc[ai][bj][m][n] = __builtin_amdgcn_mfma_f32_16x16x32_bf16(Bt[n][k], At[m][k], acc[ai][bj][m][n], 0, 0, 0); __builtin_amdgcn_s_setprio(0); } while (0)
; #define PG8_WAIT_V(n) asm volatile("s_waitcnt vmcnt(" #n ")" ::: "memory")
; #define PG8_WAIT_L(n) asm volatile("s_waitcnt lgkmcnt(" #n ")" ::: "memory")
; #define PG8_BAR __builtin_amdgcn_s_barrier()
; #define PG8_SCHED __builtin_amdgcn_sched_barrier(0)
; template <class Epi, class Sched, bool ALIGN_EPI = false, bool SP2 = false>
; __device__ __forceinline__ void gemm_phase(PG8_LAS unsigned char* lds, const Gemm g, const Sched& S, const Epi& E) {
;     ...
;             PG8_LDA(At, 1, 1); PG8_STAGE(PG8_SB(1, 0), b3, voffB); PG8_STAGE(PG8_SB(1, 1), b3 + hstep, voffB); PG8_STAGE(PG8_SA(1, 0), a3, voffA);
;             PG8_WAIT_V(8); PG8_WAIT_L(0); PG8_BAR; PG8_MMA(1, 0, At, B0); PG8_MMA(1, 1, At, B1); PG8_BAR; PG8_SCHED;
;     ...
;         if constexpr (ALIGN_EPI) { if (wr == 0) PG8_BAR; }
	s_add_i32 s3, s3, s34
	v_lshl_add_u64 v[202:203], v[202:203], 0, s[38:39]
	s_mov_b32 m0, s3
	ds_read_b128 v[190:193], v157 offset:49152
	ds_read_b128 v[194:197], v157 offset:50176
	ds_read_b128 v[198:201], v157 offset:51200
	ds_read_b128 v[208:211], v157 offset:52224
	ds_read_b128 v[212:215], v157 offset:53248
	ds_read_b128 v[216:219], v157 offset:54272
	ds_read_b128 v[220:223], v157 offset:55296
	ds_read_b128 v[224:227], v157 offset:56320
	global_load_lds_dwordx4 v[202:203], off
	s_add_i32 m0, s3, 0x2000
	s_add_u32 s14, s58, 0x40080
	v_lshl_add_u64 v[202:203], v[228:229], 0, s[38:39]
	s_addc_u32 s15, s59, 0
	s_add_i32 s3, s33, s34
	global_load_lds_dwordx4 v[202:203], off
	v_lshl_add_u64 v[202:203], s[14:15], 0, v[136:137]
	s_mov_b32 m0, s3
	s_nop 0
	global_load_lds_dwordx4 v[202:203], off
	v_lshl_add_u64 v[202:203], s[14:15], 0, v[132:133]
	s_add_i32 m0, s3, 0x2000
	s_nop 0
	global_load_lds_dwordx4 v[202:203], off
	s_waitcnt vmcnt(6)
	s_waitcnt lgkmcnt(0)
	s_barrier
	s_setprio 1
	s_waitcnt lgkmcnt(0)
	v_mfma_f32_16x16x32_bf16 v[60:63], v[148:151], v[190:193], v[60:63]
	v_mfma_f32_16x16x32_bf16 v[56:59], v[164:167], v[190:193], v[56:59]
	v_mfma_f32_16x16x32_bf16 v[44:47], v[148:151], v[198:201], v[44:47]
	v_mfma_f32_16x16x32_bf16 v[40:43], v[164:167], v[198:201], v[40:43]
	v_mfma_f32_16x16x32_bf16 v[60:63], v[160:163], v[194:197], v[60:63]
	v_mfma_f32_16x16x32_bf16 v[56:59], v[168:171], v[194:197], v[56:59]
	v_mfma_f32_16x16x32_bf16 v[44:47], v[160:163], v[208:211], v[44:47]
	v_mfma_f32_16x16x32_bf16 v[40:43], v[168:171], v[208:211], v[40:43]
	v_mfma_f32_16x16x32_bf16 v[28:31], v[148:151], v[212:215], v[28:31]
	v_mfma_f32_16x16x32_bf16 v[24:27], v[164:167], v[212:215], v[24:27]
	v_mfma_f32_16x16x32_bf16 v[12:15], v[148:151], v[220:223], v[12:15]
	v_mfma_f32_16x16x32_bf16 v[8:11], v[164:167], v[220:223], v[8:11]
	v_mfma_f32_16x16x32_bf16 v[28:31], v[160:163], v[216:219], v[28:31]
	v_mfma_f32_16x16x32_bf16 v[24:27], v[168:171], v[216:219], v[24:27]
	v_lshl_add_u64 v[202:203], v[230:231], 0, s[38:39]
	s_mov_b32 m0, s66
	s_nop 0
	global_load_lds_dwordx4 v[202:203], off
	v_mfma_f32_16x16x32_bf16 v[12:15], v[160:163], v[224:227], v[12:15]
	v_mfma_f32_16x16x32_bf16 v[8:11], v[168:171], v[224:227], v[8:11]
	s_setprio 0
	s_setprio 1
	v_mfma_f32_16x16x32_bf16 v[52:55], v[172:175], v[190:193], v[52:55]
	v_mfma_f32_16x16x32_bf16 v[48:51], v[182:185], v[190:193], v[48:51]
	v_mfma_f32_16x16x32_bf16 v[36:39], v[172:175], v[198:201], v[36:39]
	v_mfma_f32_16x16x32_bf16 v[32:35], v[182:185], v[198:201], v[32:35]
	v_mfma_f32_16x16x32_bf16 v[52:55], v[176:179], v[194:197], v[52:55]
	v_mfma_f32_16x16x32_bf16 v[48:51], v[186:189], v[194:197], v[48:51]
	v_mfma_f32_16x16x32_bf16 v[36:39], v[176:179], v[208:211], v[36:39]
	v_mfma_f32_16x16x32_bf16 v[32:35], v[186:189], v[208:211], v[32:35]
	v_mfma_f32_16x16x32_bf16 v[20:23], v[172:175], v[212:215], v[20:23]
	v_mfma_f32_16x16x32_bf16 v[16:19], v[182:185], v[212:215], v[16:19]
	v_mfma_f32_16x16x32_bf16 v[4:7], v[172:175], v[220:223], v[4:7]
	v_mfma_f32_16x16x32_bf16 v[0:3], v[182:185], v[220:223], v[0:3]
	v_mfma_f32_16x16x32_bf16 v[20:23], v[176:179], v[216:219], v[20:23]
	v_mfma_f32_16x16x32_bf16 v[16:19], v[186:189], v[216:219], v[16:19]
	v_lshl_add_u64 v[202:203], v[232:233], 0, s[38:39]
	s_mov_b32 m0, s67
	s_nop 0
	global_load_lds_dwordx4 v[202:203], off
	v_mfma_f32_16x16x32_bf16 v[4:7], v[176:179], v[224:227], v[4:7]
	v_mfma_f32_16x16x32_bf16 v[0:3], v[186:189], v[224:227], v[0:3]
	s_setprio 0
	s_barrier
	s_add_i32 s86, s86, 2
	s_add_u32 s56, s56, 0x100
	s_addc_u32 s57, s57, 0
	s_add_u32 s84, s84, 0x100
	s_addc_u32 s85, s85, 0
	s_cmp_gt_u32 s86, 13
	s_cbranch_scc0 .LBB0_738
	s_and_b64 vcc, exec, s[44:45]
	s_cbranch_vccz .LBB0_741
	s_barrier

; #define PG8_STAGE(bufoff, gbase, voff) do { _Pragma("unroll") for (int _i = 0; _i < 2; ++_i) \
;         __builtin_amdgcn_global_load_lds((const unsigned*)((const char*)(gbase) + (voff)[_i]), (PG8_LAS unsigned*)(lds + (bufoff) + ldsw + _i * 8192), 16, 0, 0); } while (0)
; #define PG8_LDA(dst, b, h) do { _Pragma("unroll") for (int m = 0; m < 4; ++m) _Pragma("unroll") for (int k = 0; k < 2; ++k) dst[m][k] = *(const PG8_LAS bf16x8*)(lds + PG8_SA(b, h) + aoff + m * 2048 + k * 1024); } while (0)
; #define PG8_LDB(dst, b, h) do { _Pragma("unroll") for (int n = 0; n < 2; ++n) _Pragma("unroll") for (int k = 0; k < 2; ++k) dst[n][k] = *(const PG8_LAS bf16x8*)(lds + PG8_SB(b, h) + boff + n * 2048 + k * 1024); } while (0)
; #define PG8_MMA(ai, bj, At, Bt) do { __builtin_amdgcn_s_setprio(1); _Pragma("unroll") for (int m = 0; m < 4; ++m) _Pragma("unroll") for (int n = 0; n < 2; ++n) _Pragma("unroll") for (int k = 0; k < 2; ++k) \
;         acc[ai][bj][m][n] = __builtin_amdgcn_mfma_f32_16x16x32_bf16(Bt[n][k], At[m][k], acc[ai][bj][m][n], 0, 0, 0); __builtin_amdgcn_s_setprio(0); } while (0)
; #define PG8_BAR __builtin_amdgcn_s_barrier()
; template <class Epi, class Sched, bool ALIGN_EPI = false, bool SP2 = false>
; __device__ __forceinline__ void gemm_phase(PG8_LAS unsigned char* lds, const Gemm g, const Sched& S, const Epi& E) {
;     ...
;         const bool has_next = S.next(ui + 1, nxt);
;         const char* nA = has_next ? (const char*)g.A + (size_t)nxt.pm * tstep : cA; const char* nB = has_next ? (const char*)g.Bt + (size_t)nxt.pn * tstep : cB;
;         for (int t = 0; t < nt; t += 2) {
;             const bool last = (t == nt - 2);
;             const char* a1 = cA + (size_t)(t + 1) * kstep;
;             const char* a2 = last ? nA : cA + (size_t)(t + 2) * kstep; const char* b2 = last ? nB : cB + (size_t)(t + 2) * kstep;
;             const char* a3 = a2 + kstep; const char* b3 = b2 + kstep;
;             if (last && has_next) S.a_ready(nxt);
;             if constexpr (SP2) {
;             PG8_LDB(B0, 0, 0); PG8_LDB(B1, 0, 1); PG8_SCHED; PG8_LDA(At, 0, 0); PG8_STAGE(PG8_SA(1, 1), a1 + hstep, voffA);
;             PG8_WAIT_V(8); PG8_WAIT_L(0); PG8_BAR; PG8_MMA(0, 0, At, B0); PG8_MMA(0, 1, At, B1); PG8_BAR; PG8_SCHED;
;             PG8_LDA(At, 0, 1); PG8_STAGE(PG8_SB(0, 0), b2, voffB); PG8_STAGE(PG8_SB(0, 1), b2 + hstep, voffB); PG8_STAGE(PG8_SA(0, 0), a2, voffA);
.LBB0_872:
	s_ashr_i32 s49, s48, 31
	s_lshl_b64 s[50:51], s[48:49], 18
	s_add_u32 s50, s92, s50
	s_addc_u32 s51, s93, s51
	s_and_b64 s[52:53], s[10:11], exec
	s_cselect_b32 s49, s51, s59
	s_cselect_b32 s55, s50, s58
	s_ashr_i32 s45, s44, 31
	s_lshl_b64 s[52:53], s[44:45], 18
	s_add_u32 s52, s76, s52
	s_addc_u32 s53, s77, s53
	s_and_b64 s[62:63], s[10:11], exec
	s_cselect_b32 s45, s53, s61
	s_cselect_b32 s84, s52, s60
	s_add_u32 s58, s58, 0x20080
	s_addc_u32 s59, s59, 0
	s_add_u32 s85, s60, 0x100
	s_addc_u32 s86, s61, 0
	s_mov_b32 s87, -2
	s_waitcnt lgkmcnt(0)
	ds_read_b128 v[144:147], v151
	ds_read_b128 v[156:159], v151 offset:1024
	ds_read_b128 v[160:163], v151 offset:2048
	ds_read_b128 v[164:167], v151 offset:3072
	ds_read_b128 v[168:171], v152
	ds_read_b128 v[172:175], v152 offset:1024
	ds_read_b128 v[176:179], v152 offset:2048
	ds_read_b128 v[182:185], v152 offset:3072
	s_add_u32 s3, s58, 0xfffe0080
	s_addc_u32 s33, s59, -1
	s_cmp_eq_u32 s87, 4
	s_cselect_b32 s63, s49, s33
	s_cselect_b32 s62, s55, s3
	s_cselect_b32 s61, s45, s86
	s_cselect_b32 s60, s84, s85
	v_lshl_add_u64 v[202:203], s[58:59], 0, v[136:137]
	s_add_i32 m0, s15, 0xc000
	ds_read_b128 v[186:189], v153
	ds_read_b128 v[190:193], v153 offset:1024
	ds_read_b128 v[194:197], v153 offset:2048
	ds_read_b128 v[198:201], v153 offset:3072
	ds_read_b128 v[208:211], v153 offset:4096
	ds_read_b128 v[212:215], v153 offset:5120
	ds_read_b128 v[216:219], v153 offset:6144
	ds_read_b128 v[220:223], v153 offset:7168
	global_load_lds_dwordx4 v[202:203], off
	v_lshl_add_u64 v[202:203], s[58:59], 0, v[138:139]
	s_add_i32 m0, s15, 0xe000
	s_nop 0
	global_load_lds_dwordx4 v[202:203], off
	s_waitcnt vmcnt(8)
	s_waitcnt lgkmcnt(0)
	s_barrier
	s_setprio 1
	s_waitcnt lgkmcnt(0)
	v_mfma_f32_16x16x32_bf16 v[124:127], v[144:147], v[186:189], 0
	v_mfma_f32_16x16x32_bf16 v[120:123], v[160:163], v[186:189], 0
	v_mfma_f32_16x16x32_bf16 v[108:111], v[144:147], v[194:197], 0
	v_mfma_f32_16x16x32_bf16 v[104:107], v[160:163], v[194:197], 0
	v_mfma_f32_16x16x32_bf16 v[124:127], v[156:159], v[190:193], v[124:127]
	v_mfma_f32_16x16x32_bf16 v[120:123], v[164:167], v[190:193], v[120:123]
	v_mfma_f32_16x16x32_bf16 v[108:111], v[156:159], v[198:201], v[108:111]
	v_mfma_f32_16x16x32_bf16 v[104:107], v[164:167], v[198:201], v[104:107]
	v_mfma_f32_16x16x32_bf16 v[92:95], v[144:147], v[208:211], 0
	v_mfma_f32_16x16x32_bf16 v[88:91], v[160:163], v[208:211], 0
	v_mfma_f32_16x16x32_bf16 v[76:79], v[144:147], v[216:219], 0
	v_mfma_f32_16x16x32_bf16 v[72:75], v[160:163], v[216:219], 0
	v_mfma_f32_16x16x32_bf16 v[92:95], v[156:159], v[212:215], v[92:95]
	v_mfma_f32_16x16x32_bf16 v[88:91], v[164:167], v[212:215], v[88:91]
	v_mfma_f32_16x16x32_bf16 v[76:79], v[156:159], v[220:223], v[76:79]
	v_mfma_f32_16x16x32_bf16 v[72:75], v[164:167], v[220:223], v[72:75]
	s_setprio 0
	s_setprio 1
	v_mfma_f32_16x16x32_bf16 v[116:119], v[168:171], v[186:189], 0
	v_mfma_f32_16x16x32_bf16 v[112:115], v[176:179], v[186:189], 0
	v_mfma_f32_16x16x32_bf16 v[100:103], v[168:171], v[194:197], 0
	v_mfma_f32_16x16x32_bf16 v[96:99], v[176:179], v[194:197], 0
	v_mfma_f32_16x16x32_bf16 v[116:119], v[172:175], v[190:193], v[116:119]
	v_mfma_f32_16x16x32_bf16 v[112:115], v[182:185], v[190:193], v[112:115]
	v_mfma_f32_16x16x32_bf16 v[100:103], v[172:175], v[198:201], v[100:103]
	v_mfma_f32_16x16x32_bf16 v[96:99], v[182:185], v[198:201], v[96:99]
	v_mfma_f32_16x16x32_bf16 v[84:87], v[168:171], v[208:211], 0
	v_mfma_f32_16x16x32_bf16 v[80:83], v[176:179], v[208:211], 0
	v_mfma_f32_16x16x32_bf16 v[68:71], v[168:171], v[216:219], 0
	v_mfma_f32_16x16x32_bf16 v[64:67], v[176:179], v[216:219], 0
	v_mfma_f32_16x16x32_bf16 v[84:87], v[172:175], v[212:215], v[84:87]
	v_mfma_f32_16x16x32_bf16 v[80:83], v[182:185], v[212:215], v[80:83]
	v_mfma_f32_16x16x32_bf16 v[68:71], v[172:175], v[220:223], v[68:71]
	v_mfma_f32_16x16x32_bf16 v[64:67], v[182:185], v[220:223], v[64:67]
	s_setprio 0
	s_barrier
	s_add_i32 s3, s74, s14
	v_lshl_add_u64 v[202:203], s[60:61], 0, v[130:131]
	s_mov_b32 m0, s3
	ds_read_b128 v[186:189], v153 offset:16384
	ds_read_b128 v[190:193], v153 offset:17408
	ds_read_b128 v[194:197], v153 offset:18432
	ds_read_b128 v[198:201], v153 offset:19456
	ds_read_b128 v[208:211], v153 offset:20480
	ds_read_b128 v[212:215], v153 offset:21504
	ds_read_b128 v[216:219], v153 offset:22528
	ds_read_b128 v[220:223], v153 offset:23552
	global_load_lds_dwordx4 v[202:203], off
	s_add_i32 m0, s3, 0x2000
	s_add_u32 s78, s60, 0x20000
	v_lshl_add_u64 v[224:225], s[60:61], 0, v[134:135]
	s_addc_u32 s79, s61, 0
	s_add_i32 s3, s75, s14
	global_load_lds_dwordx4 v[224:225], off
	v_lshl_add_u64 v[226:227], s[78:79], 0, v[130:131]
	s_mov_b32 m0, s3
	global_load_lds_dwordx4 v[226:227], off
	v_lshl_add_u64 v[226:227], s[78:79], 0, v[134:135]
	s_add_i32 m0, s3, 0x2000
	s_nop 0
	global_load_lds_dwordx4 v[226:227], off
	s_waitcnt vmcnt(6)
	s_waitcnt lgkmcnt(0)
	s_barrier
; #define PG8_STAGE(bufoff, gbase, voff) do { _Pragma("unroll") for (int _i = 0; _i < 2; ++_i) \
;         __builtin_amdgcn_global_load_lds((const unsigned*)((const char*)(gbase) + (voff)[_i]), (PG8_LAS unsigned*)(lds + (bufoff) + ldsw + _i * 8192), 16, 0, 0); } while (0)
; #define PG8_LDA(dst, b, h) do { _Pragma("unroll") for (int m = 0; m < 4; ++m) _Pragma("unroll") for (int k = 0; k < 2; ++k) dst[m][k] = *(const PG8_LAS bf16x8*)(lds + PG8_SA(b, h) + aoff + m * 2048 + k * 1024); } while (0)
; #define PG8_LDB(dst, b, h) do { _Pragma("unroll") for (int n = 0; n < 2; ++n) _Pragma("unroll") for (int k = 0; k < 2; ++k) dst[n][k] = *(const PG8_LAS bf16x8*)(lds + PG8_SB(b, h) + boff + n * 2048 + k * 1024); } while (0)
; #define PG8_MMA(ai, bj, At, Bt) do { __builtin_amdgcn_s_setprio(1); _Pragma("unroll") for (int m = 0; m < 4; ++m) _Pragma("unroll") for (int n = 0; n < 2; ++n) _Pragma("unroll") for (int k = 0; k < 2; ++k) \
;         acc[ai][bj][m][n] = __builtin_amdgcn_mfma_f32_16x16x32_bf16(Bt[n][k], At[m][k], acc[ai][bj][m][n], 0, 0, 0); __builtin_amdgcn_s_setprio(0); } while (0)
; #define PG8_WAIT_V(n) asm volatile("s_waitcnt vmcnt(" #n ")" ::: "memory")
; #define PG8_WAIT_L(n) asm volatile("s_waitcnt lgkmcnt(" #n ")" ::: "memory")
; #define PG8_BAR __builtin_amdgcn_s_barrier()
; #define PG8_SCHED __builtin_amdgcn_sched_barrier(0)
; template <class Epi, class Sched, bool ALIGN_EPI = false, bool SP2 = false>
; __device__ __forceinline__ void gemm_phase(PG8_LAS unsigned char* lds, const Gemm g, const Sched& S, const Epi& E) {
;     ...
;             PG8_WAIT_V(8); PG8_WAIT_L(0); PG8_BAR; PG8_MMA(1, 0, At, B0); PG8_MMA(1, 1, At, B1); PG8_BAR; PG8_SCHED;
;             PG8_LDB(B0, 1, 0); PG8_LDB(B1, 1, 1); PG8_SCHED; PG8_LDA(At, 1, 0); PG8_STAGE(PG8_SA(0, 1), a2 + hstep, voffA);
;             PG8_WAIT_V(8); PG8_WAIT_L(0); PG8_BAR; PG8_MMA(0, 0, At, B0); PG8_MMA(0, 1, At, B1); PG8_BAR; PG8_SCHED;
	s_setprio 1
	s_waitcnt lgkmcnt(0)
	v_mfma_f32_16x16x32_bf16 v[60:63], v[144:147], v[186:189], 0
	v_mfma_f32_16x16x32_bf16 v[56:59], v[160:163], v[186:189], 0
	v_mfma_f32_16x16x32_bf16 v[44:47], v[144:147], v[194:197], 0
	v_mfma_f32_16x16x32_bf16 v[40:43], v[160:163], v[194:197], 0
	v_mfma_f32_16x16x32_bf16 v[60:63], v[156:159], v[190:193], v[60:63]
	v_mfma_f32_16x16x32_bf16 v[56:59], v[164:167], v[190:193], v[56:59]
	v_mfma_f32_16x16x32_bf16 v[44:47], v[156:159], v[198:201], v[44:47]
	v_mfma_f32_16x16x32_bf16 v[40:43], v[164:167], v[198:201], v[40:43]
	v_mfma_f32_16x16x32_bf16 v[28:31], v[144:147], v[208:211], 0
	v_mfma_f32_16x16x32_bf16 v[24:27], v[160:163], v[208:211], 0
	v_mfma_f32_16x16x32_bf16 v[12:15], v[144:147], v[216:219], 0
	v_mfma_f32_16x16x32_bf16 v[8:11], v[160:163], v[216:219], 0
	v_mfma_f32_16x16x32_bf16 v[28:31], v[156:159], v[212:215], v[28:31]
	v_mfma_f32_16x16x32_bf16 v[24:27], v[164:167], v[212:215], v[24:27]
	v_lshl_add_u64 v[226:227], s[62:63], 0, v[128:129]
	s_mov_b32 m0, s15
	s_nop 0
	global_load_lds_dwordx4 v[226:227], off
	v_mfma_f32_16x16x32_bf16 v[12:15], v[156:159], v[220:223], v[12:15]
	v_mfma_f32_16x16x32_bf16 v[8:11], v[164:167], v[220:223], v[8:11]
	s_setprio 0
	s_setprio 1
	v_mfma_f32_16x16x32_bf16 v[52:55], v[168:171], v[186:189], 0
	v_mfma_f32_16x16x32_bf16 v[48:51], v[176:179], v[186:189], 0
	v_mfma_f32_16x16x32_bf16 v[36:39], v[168:171], v[194:197], 0
	v_mfma_f32_16x16x32_bf16 v[32:35], v[176:179], v[194:197], 0
	v_mfma_f32_16x16x32_bf16 v[52:55], v[172:175], v[190:193], v[52:55]
	v_mfma_f32_16x16x32_bf16 v[48:51], v[182:185], v[190:193], v[48:51]
	v_mfma_f32_16x16x32_bf16 v[36:39], v[172:175], v[198:201], v[36:39]
	v_mfma_f32_16x16x32_bf16 v[32:35], v[182:185], v[198:201], v[32:35]
	v_mfma_f32_16x16x32_bf16 v[20:23], v[168:171], v[208:211], 0
	v_mfma_f32_16x16x32_bf16 v[16:19], v[176:179], v[208:211], 0
	v_mfma_f32_16x16x32_bf16 v[4:7], v[168:171], v[216:219], 0
	v_mfma_f32_16x16x32_bf16 v[0:3], v[176:179], v[216:219], 0
	v_mfma_f32_16x16x32_bf16 v[20:23], v[172:175], v[212:215], v[20:23]
	v_mfma_f32_16x16x32_bf16 v[16:19], v[182:185], v[212:215], v[16:19]
	v_lshl_add_u64 v[228:229], s[62:63], 0, v[132:133]
	s_mov_b32 m0, s34
	s_nop 0
	global_load_lds_dwordx4 v[228:229], off
	v_mfma_f32_16x16x32_bf16 v[4:7], v[172:175], v[220:223], v[4:7]
	v_mfma_f32_16x16x32_bf16 v[0:3], v[182:185], v[220:223], v[0:3]
	s_setprio 0
	s_barrier
	s_add_i32 s3, 0, 0x18000
	v_add_u32_e32 v155, s3, v149
	s_add_i32 s33, 0, 0x1c000
	ds_read_b128 v[144:147], v155
	ds_read_b128 v[156:159], v155 offset:1024
	ds_read_b128 v[160:163], v155 offset:2048
	ds_read_b128 v[164:167], v155 offset:3072
	v_add_u32_e32 v155, s33, v149
	ds_read_b128 v[168:171], v155
	ds_read_b128 v[172:175], v155 offset:1024
	ds_read_b128 v[176:179], v155 offset:2048
	ds_read_b128 v[182:185], v155 offset:3072
	s_add_u32 s62, s62, 0x20000
	s_addc_u32 s63, s63, 0
	s_mov_b32 m0, s57
	v_lshl_add_u64 v[230:231], s[62:63], 0, v[128:129]
	ds_read_b128 v[186:189], v153 offset:32768
	ds_read_b128 v[190:193], v153 offset:33792
	ds_read_b128 v[194:197], v153 offset:34816
	ds_read_b128 v[198:201], v153 offset:35840
	ds_read_b128 v[208:211], v153 offset:36864
	ds_read_b128 v[212:215], v153 offset:37888
	ds_read_b128 v[216:219], v153 offset:38912
	ds_read_b128 v[220:223], v153 offset:39936
	global_load_lds_dwordx4 v[230:231], off
	v_lshl_add_u64 v[230:231], s[62:63], 0, v[132:133]
	s_mov_b32 m0, s64
	s_nop 0
	global_load_lds_dwordx4 v[230:231], off
	s_waitcnt vmcnt(8)
	s_waitcnt lgkmcnt(0)
	s_barrier
	s_setprio 1
	s_waitcnt lgkmcnt(0)
	v_mfma_f32_16x16x32_bf16 v[124:127], v[144:147], v[186:189], v[124:127]
	v_mfma_f32_16x16x32_bf16 v[120:123], v[160:163], v[186:189], v[120:123]
	v_mfma_f32_16x16x32_bf16 v[108:111], v[144:147], v[194:197], v[108:111]
	v_mfma_f32_16x16x32_bf16 v[104:107], v[160:163], v[194:197], v[104:107]
	v_mfma_f32_16x16x32_bf16 v[124:127], v[156:159], v[190:193], v[124:127]
	v_mfma_f32_16x16x32_bf16 v[120:123], v[164:167], v[190:193], v[120:123]
	v_mfma_f32_16x16x32_bf16 v[108:111], v[156:159], v[198:201], v[108:111]
	v_mfma_f32_16x16x32_bf16 v[104:107], v[164:167], v[198:201], v[104:107]
	v_mfma_f32_16x16x32_bf16 v[92:95], v[144:147], v[208:211], v[92:95]
	v_mfma_f32_16x16x32_bf16 v[88:91], v[160:163], v[208:211], v[88:91]
	v_mfma_f32_16x16x32_bf16 v[76:79], v[144:147], v[216:219], v[76:79]
	v_mfma_f32_16x16x32_bf16 v[72:75], v[160:163], v[216:219], v[72:75]
	v_mfma_f32_16x16x32_bf16 v[92:95], v[156:159], v[212:215], v[92:95]
	v_mfma_f32_16x16x32_bf16 v[88:91], v[164:167], v[212:215], v[88:91]
	v_mfma_f32_16x16x32_bf16 v[76:79], v[156:159], v[220:223], v[76:79]
	v_mfma_f32_16x16x32_bf16 v[72:75], v[164:167], v[220:223], v[72:75]
	s_setprio 0
	s_setprio 1
	v_mfma_f32_16x16x32_bf16 v[116:119], v[168:171], v[186:189], v[116:119]
	v_mfma_f32_16x16x32_bf16 v[112:115], v[176:179], v[186:189], v[112:115]
	v_mfma_f32_16x16x32_bf16 v[100:103], v[168:171], v[194:197], v[100:103]
	v_mfma_f32_16x16x32_bf16 v[96:99], v[176:179], v[194:197], v[96:99]
	v_mfma_f32_16x16x32_bf16 v[116:119], v[172:175], v[190:193], v[116:119]
	v_mfma_f32_16x16x32_bf16 v[112:115], v[182:185], v[190:193], v[112:115]
	v_mfma_f32_16x16x32_bf16 v[100:103], v[172:175], v[198:201], v[100:103]
	v_mfma_f32_16x16x32_bf16 v[96:99], v[182:185], v[198:201], v[96:99]
	v_mfma_f32_16x16x32_bf16 v[84:87], v[168:171], v[208:211], v[84:87]
	v_mfma_f32_16x16x32_bf16 v[80:83], v[176:179], v[208:211], v[80:83]
	v_mfma_f32_16x16x32_bf16 v[68:71], v[168:171], v[216:219], v[68:71]
	v_mfma_f32_16x16x32_bf16 v[64:67], v[176:179], v[216:219], v[64:67]
	v_mfma_f32_16x16x32_bf16 v[84:87], v[172:175], v[212:215], v[84:87]
	v_mfma_f32_16x16x32_bf16 v[80:83], v[182:185], v[212:215], v[80:83]
	v_mfma_f32_16x16x32_bf16 v[68:71], v[172:175], v[220:223], v[68:71]
	v_mfma_f32_16x16x32_bf16 v[64:67], v[182:185], v[220:223], v[64:67]
	s_setprio 0
	s_barrier
; #define PG8_STAGE(bufoff, gbase, voff) do { _Pragma("unroll") for (int _i = 0; _i < 2; ++_i) \
;         __builtin_amdgcn_global_load_lds((const unsigned*)((const char*)(gbase) + (voff)[_i]), (PG8_LAS unsigned*)(lds + (bufoff) + ldsw + _i * 8192), 16, 0, 0); } while (0)
; #define PG8_LDA(dst, b, h) do { _Pragma("unroll") for (int m = 0; m < 4; ++m) _Pragma("unroll") for (int k = 0; k < 2; ++k) dst[m][k] = *(const PG8_LAS bf16x8*)(lds + PG8_SA(b, h) + aoff + m * 2048 + k * 1024); } while (0)
; #define PG8_LDB(dst, b, h) do { _Pragma("unroll") for (int n = 0; n < 2; ++n) _Pragma("unroll") for (int k = 0; k < 2; ++k) dst[n][k] = *(const PG8_LAS bf16x8*)(lds + PG8_SB(b, h) + boff + n * 2048 + k * 1024); } while (0)
; #define PG8_MMA(ai, bj, At, Bt) do { __builtin_amdgcn_s_setprio(1); _Pragma("unroll") for (int m = 0; m < 4; ++m) _Pragma("unroll") for (int n = 0; n < 2; ++n) _Pragma("unroll") for (int k = 0; k < 2; ++k) \
;         acc[ai][bj][m][n] = __builtin_amdgcn_mfma_f32_16x16x32_bf16(Bt[n][k], At[m][k], acc[ai][bj][m][n], 0, 0, 0); __builtin_amdgcn_s_setprio(0); } while (0)
; #define PG8_WAIT_V(n) asm volatile("s_waitcnt vmcnt(" #n ")" ::: "memory")
; #define PG8_WAIT_L(n) asm volatile("s_waitcnt lgkmcnt(" #n ")" ::: "memory")
; #define PG8_BAR __builtin_amdgcn_s_barrier()
; #define PG8_SCHED __builtin_amdgcn_sched_barrier(0)
; template <class Epi, class Sched, bool ALIGN_EPI = false, bool SP2 = false>
; __device__ __forceinline__ void gemm_phase(PG8_LAS unsigned char* lds, const Gemm g, const Sched& S, const Epi& E) {
;     ...
;             PG8_LDA(At, 1, 1); PG8_STAGE(PG8_SB(1, 0), b3, voffB); PG8_STAGE(PG8_SB(1, 1), b3 + hstep, voffB); PG8_STAGE(PG8_SA(1, 0), a3, voffA);
;             PG8_WAIT_V(8); PG8_WAIT_L(0); PG8_BAR; PG8_MMA(1, 0, At, B0); PG8_MMA(1, 1, At, B1); PG8_BAR; PG8_SCHED;
;             } else {
;             PG8_LDB(B0, 0, 0); PG8_SCHED; PG8_LDA(At, 0, 0); PG8_STAGE(PG8_SA(1, 1), a1 + hstep, voffA);
	s_add_i32 s3, s3, s14
	v_lshl_add_u64 v[202:203], v[202:203], 0, s[38:39]
	s_mov_b32 m0, s3
	ds_read_b128 v[186:189], v153 offset:49152
	ds_read_b128 v[190:193], v153 offset:50176
	ds_read_b128 v[194:197], v153 offset:51200
	ds_read_b128 v[198:201], v153 offset:52224
	ds_read_b128 v[208:211], v153 offset:53248
	ds_read_b128 v[212:215], v153 offset:54272
	ds_read_b128 v[216:219], v153 offset:55296
	ds_read_b128 v[220:223], v153 offset:56320
	global_load_lds_dwordx4 v[202:203], off
	s_add_i32 m0, s3, 0x2000
	s_add_u32 s60, s60, 0x20080
	v_lshl_add_u64 v[202:203], v[224:225], 0, s[38:39]
	s_addc_u32 s61, s61, 0
	s_add_i32 s3, s33, s14
	global_load_lds_dwordx4 v[202:203], off
	v_lshl_add_u64 v[202:203], s[60:61], 0, v[130:131]
	s_mov_b32 m0, s3
	s_nop 0
	global_load_lds_dwordx4 v[202:203], off
	v_lshl_add_u64 v[202:203], s[60:61], 0, v[134:135]
	s_add_i32 m0, s3, 0x2000
	s_nop 0
	global_load_lds_dwordx4 v[202:203], off
	s_waitcnt vmcnt(6)
	s_waitcnt lgkmcnt(0)
	s_barrier
	s_setprio 1
	s_waitcnt lgkmcnt(0)
	v_mfma_f32_16x16x32_bf16 v[60:63], v[144:147], v[186:189], v[60:63]
	v_mfma_f32_16x16x32_bf16 v[56:59], v[160:163], v[186:189], v[56:59]
	v_mfma_f32_16x16x32_bf16 v[44:47], v[144:147], v[194:197], v[44:47]
	v_mfma_f32_16x16x32_bf16 v[40:43], v[160:163], v[194:197], v[40:43]
	v_mfma_f32_16x16x32_bf16 v[60:63], v[156:159], v[190:193], v[60:63]
	v_mfma_f32_16x16x32_bf16 v[56:59], v[164:167], v[190:193], v[56:59]
	v_mfma_f32_16x16x32_bf16 v[44:47], v[156:159], v[198:201], v[44:47]
	v_mfma_f32_16x16x32_bf16 v[40:43], v[164:167], v[198:201], v[40:43]
	v_mfma_f32_16x16x32_bf16 v[28:31], v[144:147], v[208:211], v[28:31]
	v_mfma_f32_16x16x32_bf16 v[24:27], v[160:163], v[208:211], v[24:27]
	v_mfma_f32_16x16x32_bf16 v[12:15], v[144:147], v[216:219], v[12:15]
	v_mfma_f32_16x16x32_bf16 v[8:11], v[160:163], v[216:219], v[8:11]
	v_mfma_f32_16x16x32_bf16 v[28:31], v[156:159], v[212:215], v[28:31]
	v_mfma_f32_16x16x32_bf16 v[24:27], v[164:167], v[212:215], v[24:27]
	v_lshl_add_u64 v[202:203], v[226:227], 0, s[38:39]
	s_mov_b32 m0, s66
	s_nop 0
	global_load_lds_dwordx4 v[202:203], off
	v_mfma_f32_16x16x32_bf16 v[12:15], v[156:159], v[220:223], v[12:15]
	v_mfma_f32_16x16x32_bf16 v[8:11], v[164:167], v[220:223], v[8:11]
	s_setprio 0
	s_setprio 1
	v_mfma_f32_16x16x32_bf16 v[52:55], v[168:171], v[186:189], v[52:55]
	v_mfma_f32_16x16x32_bf16 v[48:51], v[176:179], v[186:189], v[48:51]
	v_mfma_f32_16x16x32_bf16 v[36:39], v[168:171], v[194:197], v[36:39]
	v_mfma_f32_16x16x32_bf16 v[32:35], v[176:179], v[194:197], v[32:35]
	v_mfma_f32_16x16x32_bf16 v[52:55], v[172:175], v[190:193], v[52:55]
	v_mfma_f32_16x16x32_bf16 v[48:51], v[182:185], v[190:193], v[48:51]
	v_mfma_f32_16x16x32_bf16 v[36:39], v[172:175], v[198:201], v[36:39]
	v_mfma_f32_16x16x32_bf16 v[32:35], v[182:185], v[198:201], v[32:35]
	v_mfma_f32_16x16x32_bf16 v[20:23], v[168:171], v[208:211], v[20:23]
	v_mfma_f32_16x16x32_bf16 v[16:19], v[176:179], v[208:211], v[16:19]
	v_mfma_f32_16x16x32_bf16 v[4:7], v[168:171], v[216:219], v[4:7]
	v_mfma_f32_16x16x32_bf16 v[0:3], v[176:179], v[216:219], v[0:3]
	v_mfma_f32_16x16x32_bf16 v[20:23], v[172:175], v[212:215], v[20:23]
	v_mfma_f32_16x16x32_bf16 v[16:19], v[182:185], v[212:215], v[16:19]
	v_lshl_add_u64 v[202:203], v[228:229], 0, s[38:39]
	s_mov_b32 m0, s67
	s_nop 0
	global_load_lds_dwordx4 v[202:203], off
	v_mfma_f32_16x16x32_bf16 v[4:7], v[172:175], v[220:223], v[4:7]
	v_mfma_f32_16x16x32_bf16 v[0:3], v[182:185], v[220:223], v[0:3]
	s_setprio 0
	s_barrier
	s_add_i32 s87, s87, 2
	s_add_u32 s58, s58, 0x100
	s_addc_u32 s59, s59, 0
	s_add_u32 s85, s85, 0x100
	s_addc_u32 s86, s86, 0
.LBB0_873:
	ds_read_b128 v[144:147], v151
	ds_read_b128 v[156:159], v151 offset:1024
	ds_read_b128 v[160:163], v151 offset:2048
	ds_read_b128 v[164:167], v151 offset:3072
	ds_read_b128 v[168:171], v152
	ds_read_b128 v[172:175], v152 offset:1024
	ds_read_b128 v[176:179], v152 offset:2048
	ds_read_b128 v[182:185], v152 offset:3072
	s_add_u32 s3, s58, 0xfffe0080
	s_addc_u32 s33, s59, -1
	s_cmp_eq_u32 s87, 4
	s_cselect_b32 s63, s49, s33
	s_cselect_b32 s62, s55, s3
	s_cselect_b32 s61, s45, s86
	s_cselect_b32 s60, s84, s85
	v_lshl_add_u64 v[202:203], s[58:59], 0, v[136:137]
	s_add_i32 m0, s15, 0xc000
	ds_read_b128 v[186:189], v153
	ds_read_b128 v[190:193], v153 offset:1024
	ds_read_b128 v[194:197], v153 offset:2048
	ds_read_b128 v[198:201], v153 offset:3072
	ds_read_b128 v[208:211], v153 offset:4096
	ds_read_b128 v[212:215], v153 offset:5120
	ds_read_b128 v[216:219], v153 offset:6144
	ds_read_b128 v[220:223], v153 offset:7168
	global_load_lds_dwordx4 v[202:203], off
	v_lshl_add_u64 v[202:203], s[58:59], 0, v[138:139]
	s_add_i32 m0, s15, 0xe000
	s_nop 0
	global_load_lds_dwordx4 v[202:203], off
	s_waitcnt vmcnt(8)
	s_waitcnt lgkmcnt(0)
	s_barrier
; #define PG8_STAGE(bufoff, gbase, voff) do { _Pragma("unroll") for (int _i = 0; _i < 2; ++_i) \
;         __builtin_amdgcn_global_load_lds((const unsigned*)((const char*)(gbase) + (voff)[_i]), (PG8_LAS unsigned*)(lds + (bufoff) + ldsw + _i * 8192), 16, 0, 0); } while (0)
; #define PG8_LDA(dst, b, h) do { _Pragma("unroll") for (int m = 0; m < 4; ++m) _Pragma("unroll") for (int k = 0; k < 2; ++k) dst[m][k] = *(const PG8_LAS bf16x8*)(lds + PG8_SA(b, h) + aoff + m * 2048 + k * 1024); } while (0)
; #define PG8_LDB(dst, b, h) do { _Pragma("unroll") for (int n = 0; n < 2; ++n) _Pragma("unroll") for (int k = 0; k < 2; ++k) dst[n][k] = *(const PG8_LAS bf16x8*)(lds + PG8_SB(b, h) + boff + n * 2048 + k * 1024); } while (0)
; #define PG8_MMA(ai, bj, At, Bt) do { __builtin_amdgcn_s_setprio(1); _Pragma("unroll") for (int m = 0; m < 4; ++m) _Pragma("unroll") for (int n = 0; n < 2; ++n) _Pragma("unroll") for (int k = 0; k < 2; ++k) \
;         acc[ai][bj][m][n] = __builtin_amdgcn_mfma_f32_16x16x32_bf16(Bt[n][k], At[m][k], acc[ai][bj][m][n], 0, 0, 0); __builtin_amdgcn_s_setprio(0); } while (0)
; #define PG8_WAIT_V(n) asm volatile("s_waitcnt vmcnt(" #n ")" ::: "memory")
; #define PG8_WAIT_L(n) asm volatile("s_waitcnt lgkmcnt(" #n ")" ::: "memory")
; #define PG8_BAR __builtin_amdgcn_s_barrier()
; #define PG8_SCHED __builtin_amdgcn_sched_barrier(0)
; template <class Epi, class Sched, bool ALIGN_EPI = false, bool SP2 = false>
; __device__ __forceinline__ void gemm_phase(PG8_LAS unsigned char* lds, const Gemm g, const Sched& S, const Epi& E) {
;     ...
;             PG8_LDB(B0, 0, 0); PG8_LDB(B1, 0, 1); PG8_SCHED; PG8_LDA(At, 0, 0); PG8_STAGE(PG8_SA(1, 1), a1 + hstep, voffA);
;             PG8_WAIT_V(8); PG8_WAIT_L(0); PG8_BAR; PG8_MMA(0, 0, At, B0); PG8_MMA(0, 1, At, B1); PG8_BAR; PG8_SCHED;
;             PG8_LDA(At, 0, 1); PG8_STAGE(PG8_SB(0, 0), b2, voffB); PG8_STAGE(PG8_SB(0, 1), b2 + hstep, voffB); PG8_STAGE(PG8_SA(0, 0), a2, voffA);
;             PG8_WAIT_V(8); PG8_WAIT_L(0); PG8_BAR; PG8_MMA(1, 0, At, B0); PG8_MMA(1, 1, At, B1); PG8_BAR; PG8_SCHED;
	s_setprio 1
	s_waitcnt lgkmcnt(0)
	v_mfma_f32_16x16x32_bf16 v[124:127], v[144:147], v[186:189], v[124:127]
	v_mfma_f32_16x16x32_bf16 v[120:123], v[160:163], v[186:189], v[120:123]
	v_mfma_f32_16x16x32_bf16 v[108:111], v[144:147], v[194:197], v[108:111]
	v_mfma_f32_16x16x32_bf16 v[104:107], v[160:163], v[194:197], v[104:107]
	v_mfma_f32_16x16x32_bf16 v[124:127], v[156:159], v[190:193], v[124:127]
	v_mfma_f32_16x16x32_bf16 v[120:123], v[164:167], v[190:193], v[120:123]
	v_mfma_f32_16x16x32_bf16 v[108:111], v[156:159], v[198:201], v[108:111]
	v_mfma_f32_16x16x32_bf16 v[104:107], v[164:167], v[198:201], v[104:107]
	v_mfma_f32_16x16x32_bf16 v[92:95], v[144:147], v[208:211], v[92:95]
	v_mfma_f32_16x16x32_bf16 v[88:91], v[160:163], v[208:211], v[88:91]
	v_mfma_f32_16x16x32_bf16 v[76:79], v[144:147], v[216:219], v[76:79]
	v_mfma_f32_16x16x32_bf16 v[72:75], v[160:163], v[216:219], v[72:75]
	v_mfma_f32_16x16x32_bf16 v[92:95], v[156:159], v[212:215], v[92:95]
	v_mfma_f32_16x16x32_bf16 v[88:91], v[164:167], v[212:215], v[88:91]
	v_mfma_f32_16x16x32_bf16 v[76:79], v[156:159], v[220:223], v[76:79]
	v_mfma_f32_16x16x32_bf16 v[72:75], v[164:167], v[220:223], v[72:75]
	s_setprio 0
	s_setprio 1
	v_mfma_f32_16x16x32_bf16 v[116:119], v[168:171], v[186:189], v[116:119]
	v_mfma_f32_16x16x32_bf16 v[112:115], v[176:179], v[186:189], v[112:115]
	v_mfma_f32_16x16x32_bf16 v[100:103], v[168:171], v[194:197], v[100:103]
	v_mfma_f32_16x16x32_bf16 v[96:99], v[176:179], v[194:197], v[96:99]
	v_mfma_f32_16x16x32_bf16 v[116:119], v[172:175], v[190:193], v[116:119]
	v_mfma_f32_16x16x32_bf16 v[112:115], v[182:185], v[190:193], v[112:115]
	v_mfma_f32_16x16x32_bf16 v[100:103], v[172:175], v[198:201], v[100:103]
	v_mfma_f32_16x16x32_bf16 v[96:99], v[182:185], v[198:201], v[96:99]
	v_mfma_f32_16x16x32_bf16 v[84:87], v[168:171], v[208:211], v[84:87]
	v_mfma_f32_16x16x32_bf16 v[80:83], v[176:179], v[208:211], v[80:83]
	v_mfma_f32_16x16x32_bf16 v[68:71], v[168:171], v[216:219], v[68:71]
	v_mfma_f32_16x16x32_bf16 v[64:67], v[176:179], v[216:219], v[64:67]
	v_mfma_f32_16x16x32_bf16 v[84:87], v[172:175], v[212:215], v[84:87]
	v_mfma_f32_16x16x32_bf16 v[80:83], v[182:185], v[212:215], v[80:83]
	v_mfma_f32_16x16x32_bf16 v[68:71], v[172:175], v[220:223], v[68:71]
	v_mfma_f32_16x16x32_bf16 v[64:67], v[182:185], v[220:223], v[64:67]
	s_setprio 0
	s_barrier
	s_add_i32 s3, s74, s14
	v_lshl_add_u64 v[202:203], s[60:61], 0, v[130:131]
	s_mov_b32 m0, s3
	ds_read_b128 v[186:189], v153 offset:16384
	ds_read_b128 v[190:193], v153 offset:17408
	ds_read_b128 v[194:197], v153 offset:18432
	ds_read_b128 v[198:201], v153 offset:19456
	ds_read_b128 v[208:211], v153 offset:20480
	ds_read_b128 v[212:215], v153 offset:21504
	ds_read_b128 v[216:219], v153 offset:22528
	ds_read_b128 v[220:223], v153 offset:23552
	global_load_lds_dwordx4 v[202:203], off
	s_add_i32 m0, s3, 0x2000
	s_add_u32 s78, s60, 0x20000
	v_lshl_add_u64 v[224:225], s[60:61], 0, v[134:135]
	s_addc_u32 s79, s61, 0
	s_add_i32 s3, s75, s14
	global_load_lds_dwordx4 v[224:225], off
	v_lshl_add_u64 v[226:227], s[78:79], 0, v[130:131]
	s_mov_b32 m0, s3
	global_load_lds_dwordx4 v[226:227], off
	v_lshl_add_u64 v[226:227], s[78:79], 0, v[134:135]
	s_add_i32 m0, s3, 0x2000
	s_nop 0
	global_load_lds_dwordx4 v[226:227], off
	s_waitcnt vmcnt(6)
	s_waitcnt lgkmcnt(0)
	s_barrier
	s_setprio 1
	s_waitcnt lgkmcnt(0)
	v_mfma_f32_16x16x32_bf16 v[60:63], v[144:147], v[186:189], v[60:63]
	v_mfma_f32_16x16x32_bf16 v[56:59], v[160:163], v[186:189], v[56:59]
	v_mfma_f32_16x16x32_bf16 v[44:47], v[144:147], v[194:197], v[44:47]
	v_mfma_f32_16x16x32_bf16 v[40:43], v[160:163], v[194:197], v[40:43]
	v_mfma_f32_16x16x32_bf16 v[60:63], v[156:159], v[190:193], v[60:63]
	v_mfma_f32_16x16x32_bf16 v[56:59], v[164:167], v[190:193], v[56:59]
	v_mfma_f32_16x16x32_bf16 v[44:47], v[156:159], v[198:201], v[44:47]
	v_mfma_f32_16x16x32_bf16 v[40:43], v[164:167], v[198:201], v[40:43]
	v_mfma_f32_16x16x32_bf16 v[28:31], v[144:147], v[208:211], v[28:31]
	v_mfma_f32_16x16x32_bf16 v[24:27], v[160:163], v[208:211], v[24:27]
	v_mfma_f32_16x16x32_bf16 v[12:15], v[144:147], v[216:219], v[12:15]
	v_mfma_f32_16x16x32_bf16 v[8:11], v[160:163], v[216:219], v[8:11]
	v_mfma_f32_16x16x32_bf16 v[28:31], v[156:159], v[212:215], v[28:31]
	v_mfma_f32_16x16x32_bf16 v[24:27], v[164:167], v[212:215], v[24:27]
	v_lshl_add_u64 v[226:227], s[62:63], 0, v[128:129]
	s_mov_b32 m0, s15
	s_nop 0
	global_load_lds_dwordx4 v[226:227], off
	v_mfma_f32_16x16x32_bf16 v[12:15], v[156:159], v[220:223], v[12:15]
	v_mfma_f32_16x16x32_bf16 v[8:11], v[164:167], v[220:223], v[8:11]
	s_setprio 0
	s_setprio 1
	v_mfma_f32_16x16x32_bf16 v[52:55], v[168:171], v[186:189], v[52:55]
	v_mfma_f32_16x16x32_bf16 v[48:51], v[176:179], v[186:189], v[48:51]
	v_mfma_f32_16x16x32_bf16 v[36:39], v[168:171], v[194:197], v[36:39]
	v_mfma_f32_16x16x32_bf16 v[32:35], v[176:179], v[194:197], v[32:35]
	v_mfma_f32_16x16x32_bf16 v[52:55], v[172:175], v[190:193], v[52:55]
	v_mfma_f32_16x16x32_bf16 v[48:51], v[182:185], v[190:193], v[48:51]
	v_mfma_f32_16x16x32_bf16 v[36:39], v[172:175], v[198:201], v[36:39]
	v_mfma_f32_16x16x32_bf16 v[32:35], v[182:185], v[198:201], v[32:35]
	v_mfma_f32_16x16x32_bf16 v[20:23], v[168:171], v[208:211], v[20:23]
	v_mfma_f32_16x16x32_bf16 v[16:19], v[176:179], v[208:211], v[16:19]
	v_mfma_f32_16x16x32_bf16 v[4:7], v[168:171], v[216:219], v[4:7]
	v_mfma_f32_16x16x32_bf16 v[0:3], v[176:179], v[216:219], v[0:3]
	v_mfma_f32_16x16x32_bf16 v[20:23], v[172:175], v[212:215], v[20:23]
	v_mfma_f32_16x16x32_bf16 v[16:19], v[182:185], v[212:215], v[16:19]
	v_lshl_add_u64 v[228:229], s[62:63], 0, v[132:133]
	s_mov_b32 m0, s34
	s_nop 0
	global_load_lds_dwordx4 v[228:229], off
	v_mfma_f32_16x16x32_bf16 v[4:7], v[172:175], v[220:223], v[4:7]
	v_mfma_f32_16x16x32_bf16 v[0:3], v[182:185], v[220:223], v[0:3]
	s_setprio 0
	s_barrier
; #define PG8_STAGE(bufoff, gbase, voff) do { _Pragma("unroll") for (int _i = 0; _i < 2; ++_i) \
;         __builtin_amdgcn_global_load_lds((const unsigned*)((const char*)(gbase) + (voff)[_i]), (PG8_LAS unsigned*)(lds + (bufoff) + ldsw + _i * 8192), 16, 0, 0); } while (0)
; #define PG8_LDA(dst, b, h) do { _Pragma("unroll") for (int m = 0; m < 4; ++m) _Pragma("unroll") for (int k = 0; k < 2; ++k) dst[m][k] = *(const PG8_LAS bf16x8*)(lds + PG8_SA(b, h) + aoff + m * 2048 + k * 1024); } while (0)
; #define PG8_LDB(dst, b, h) do { _Pragma("unroll") for (int n = 0; n < 2; ++n) _Pragma("unroll") for (int k = 0; k < 2; ++k) dst[n][k] = *(const PG8_LAS bf16x8*)(lds + PG8_SB(b, h) + boff + n * 2048 + k * 1024); } while (0)
; #define PG8_MMA(ai, bj, At, Bt) do { __builtin_amdgcn_s_setprio(1); _Pragma("unroll") for (int m = 0; m < 4; ++m) _Pragma("unroll") for (int n = 0; n < 2; ++n) _Pragma("unroll") for (int k = 0; k < 2; ++k) \
;         acc[ai][bj][m][n] = __builtin_amdgcn_mfma_f32_16x16x32_bf16(Bt[n][k], At[m][k], acc[ai][bj][m][n], 0, 0, 0); __builtin_amdgcn_s_setprio(0); } while (0)
; #define PG8_WAIT_V(n) asm volatile("s_waitcnt vmcnt(" #n ")" ::: "memory")
; #define PG8_WAIT_L(n) asm volatile("s_waitcnt lgkmcnt(" #n ")" ::: "memory")
; #define PG8_BAR __builtin_amdgcn_s_barrier()
; #define PG8_SCHED __builtin_amdgcn_sched_barrier(0)
; template <class Epi, class Sched, bool ALIGN_EPI = false, bool SP2 = false>
; __device__ __forceinline__ void gemm_phase(PG8_LAS unsigned char* lds, const Gemm g, const Sched& S, const Epi& E) {
;     ...
;             PG8_LDB(B0, 1, 0); PG8_LDB(B1, 1, 1); PG8_SCHED; PG8_LDA(At, 1, 0); PG8_STAGE(PG8_SA(0, 1), a2 + hstep, voffA);
;             PG8_WAIT_V(8); PG8_WAIT_L(0); PG8_BAR; PG8_MMA(0, 0, At, B0); PG8_MMA(0, 1, At, B1); PG8_BAR; PG8_SCHED;
	s_add_i32 s3, 0, 0x18000
	v_add_u32_e32 v155, s3, v149
	s_add_i32 s33, 0, 0x1c000
	ds_read_b128 v[144:147], v155
	ds_read_b128 v[156:159], v155 offset:1024
	ds_read_b128 v[160:163], v155 offset:2048
	ds_read_b128 v[164:167], v155 offset:3072
	v_add_u32_e32 v155, s33, v149
	ds_read_b128 v[168:171], v155
	ds_read_b128 v[172:175], v155 offset:1024
	ds_read_b128 v[176:179], v155 offset:2048
	ds_read_b128 v[182:185], v155 offset:3072
	s_add_u32 s62, s62, 0x20000
	s_addc_u32 s63, s63, 0
	s_mov_b32 m0, s57
	v_lshl_add_u64 v[230:231], s[62:63], 0, v[128:129]
	ds_read_b128 v[186:189], v153 offset:32768
	ds_read_b128 v[190:193], v153 offset:33792
	ds_read_b128 v[194:197], v153 offset:34816
	ds_read_b128 v[198:201], v153 offset:35840
	ds_read_b128 v[208:211], v153 offset:36864
	ds_read_b128 v[212:215], v153 offset:37888
	ds_read_b128 v[216:219], v153 offset:38912
	ds_read_b128 v[220:223], v153 offset:39936
	global_load_lds_dwordx4 v[230:231], off
	v_lshl_add_u64 v[230:231], s[62:63], 0, v[132:133]
	s_mov_b32 m0, s64
	s_nop 0
	global_load_lds_dwordx4 v[230:231], off
	s_waitcnt vmcnt(8)
	s_waitcnt lgkmcnt(0)
	s_barrier
	s_setprio 1
	s_waitcnt lgkmcnt(0)
	v_mfma_f32_16x16x32_bf16 v[124:127], v[144:147], v[186:189], v[124:127]
	v_mfma_f32_16x16x32_bf16 v[120:123], v[160:163], v[186:189], v[120:123]
	v_mfma_f32_16x16x32_bf16 v[108:111], v[144:147], v[194:197], v[108:111]
	v_mfma_f32_16x16x32_bf16 v[104:107], v[160:163], v[194:197], v[104:107]
	v_mfma_f32_16x16x32_bf16 v[124:127], v[156:159], v[190:193], v[124:127]
	v_mfma_f32_16x16x32_bf16 v[120:123], v[164:167], v[190:193], v[120:123]
	v_mfma_f32_16x16x32_bf16 v[108:111], v[156:159], v[198:201], v[108:111]
	v_mfma_f32_16x16x32_bf16 v[104:107], v[164:167], v[198:201], v[104:107]
	v_mfma_f32_16x16x32_bf16 v[92:95], v[144:147], v[208:211], v[92:95]
	v_mfma_f32_16x16x32_bf16 v[88:91], v[160:163], v[208:211], v[88:91]
	v_mfma_f32_16x16x32_bf16 v[76:79], v[144:147], v[216:219], v[76:79]
	v_mfma_f32_16x16x32_bf16 v[72:75], v[160:163], v[216:219], v[72:75]
	v_mfma_f32_16x16x32_bf16 v[92:95], v[156:159], v[212:215], v[92:95]
	v_mfma_f32_16x16x32_bf16 v[88:91], v[164:167], v[212:215], v[88:91]
	v_mfma_f32_16x16x32_bf16 v[76:79], v[156:159], v[220:223], v[76:79]
	v_mfma_f32_16x16x32_bf16 v[72:75], v[164:167], v[220:223], v[72:75]
	s_setprio 0
	s_setprio 1
	v_mfma_f32_16x16x32_bf16 v[116:119], v[168:171], v[186:189], v[116:119]
	v_mfma_f32_16x16x32_bf16 v[112:115], v[176:179], v[186:189], v[112:115]
	v_mfma_f32_16x16x32_bf16 v[100:103], v[168:171], v[194:197], v[100:103]
	v_mfma_f32_16x16x32_bf16 v[96:99], v[176:179], v[194:197], v[96:99]
	v_mfma_f32_16x16x32_bf16 v[116:119], v[172:175], v[190:193], v[116:119]
	v_mfma_f32_16x16x32_bf16 v[112:115], v[182:185], v[190:193], v[112:115]
	v_mfma_f32_16x16x32_bf16 v[100:103], v[172:175], v[198:201], v[100:103]
	v_mfma_f32_16x16x32_bf16 v[96:99], v[182:185], v[198:201], v[96:99]
	v_mfma_f32_16x16x32_bf16 v[84:87], v[168:171], v[208:211], v[84:87]
	v_mfma_f32_16x16x32_bf16 v[80:83], v[176:179], v[208:211], v[80:83]
	v_mfma_f32_16x16x32_bf16 v[68:71], v[168:171], v[216:219], v[68:71]
	v_mfma_f32_16x16x32_bf16 v[64:67], v[176:179], v[216:219], v[64:67]
	v_mfma_f32_16x16x32_bf16 v[84:87], v[172:175], v[212:215], v[84:87]
	v_mfma_f32_16x16x32_bf16 v[80:83], v[182:185], v[212:215], v[80:83]
	v_mfma_f32_16x16x32_bf16 v[68:71], v[172:175], v[220:223], v[68:71]
	v_mfma_f32_16x16x32_bf16 v[64:67], v[182:185], v[220:223], v[64:67]
	s_setprio 0
	s_barrier
; #define PG8_STAGE(bufoff, gbase, voff) do { _Pragma("unroll") for (int _i = 0; _i < 2; ++_i) \
;         __builtin_amdgcn_global_load_lds((const unsigned*)((const char*)(gbase) + (voff)[_i]), (PG8_LAS unsigned*)(lds + (bufoff) + ldsw + _i * 8192), 16, 0, 0); } while (0)
; #define PG8_LDA(dst, b, h) do { _Pragma("unroll") for (int m = 0; m < 4; ++m) _Pragma("unroll") for (int k = 0; k < 2; ++k) dst[m][k] = *(const PG8_LAS bf16x8*)(lds + PG8_SA(b, h) + aoff + m * 2048 + k * 1024); } while (0)
; #define PG8_MMA(ai, bj, At, Bt) do { __builtin_amdgcn_s_setprio(1); _Pragma("unroll") for (int m = 0; m < 4; ++m) _Pragma("unroll") for (int n = 0; n < 2; ++n) _Pragma("unroll") for (int k = 0; k < 2; ++k) \
;         acc[ai][bj][m][n] = __builtin_amdgcn_mfma_f32_16x16x32_bf16(Bt[n][k], At[m][k], acc[ai][bj][m][n], 0, 0, 0); __builtin_amdgcn_s_setprio(0); } while (0)
; #define PG8_WAIT_V(n) asm volatile("s_waitcnt vmcnt(" #n ")" ::: "memory")
; #define PG8_WAIT_L(n) asm volatile("s_waitcnt lgkmcnt(" #n ")" ::: "memory")
; #define PG8_BAR __builtin_amdgcn_s_barrier()
; #define PG8_SCHED __builtin_amdgcn_sched_barrier(0)
; template <class Epi, class Sched, bool ALIGN_EPI = false, bool SP2 = false>
; __device__ __forceinline__ void gemm_phase(PG8_LAS unsigned char* lds, const Gemm g, const Sched& S, const Epi& E) {
;     ...
;             PG8_LDA(At, 1, 1); PG8_STAGE(PG8_SB(1, 0), b3, voffB); PG8_STAGE(PG8_SB(1, 1), b3 + hstep, voffB); PG8_STAGE(PG8_SA(1, 0), a3, voffA);
;             PG8_WAIT_V(8); PG8_WAIT_L(0); PG8_BAR; PG8_MMA(1, 0, At, B0); PG8_MMA(1, 1, At, B1); PG8_BAR; PG8_SCHED;
;     ...
;         if constexpr (ALIGN_EPI) { if (wr == 0) PG8_BAR; }
	s_add_i32 s3, s3, s14
	v_lshl_add_u64 v[202:203], v[202:203], 0, s[38:39]
	s_mov_b32 m0, s3
	ds_read_b128 v[186:189], v153 offset:49152
	ds_read_b128 v[190:193], v153 offset:50176
	ds_read_b128 v[194:197], v153 offset:51200
	ds_read_b128 v[198:201], v153 offset:52224
	ds_read_b128 v[208:211], v153 offset:53248
	ds_read_b128 v[212:215], v153 offset:54272
	ds_read_b128 v[216:219], v153 offset:55296
	ds_read_b128 v[220:223], v153 offset:56320
	global_load_lds_dwordx4 v[202:203], off
	s_add_i32 m0, s3, 0x2000
	s_add_u32 s60, s60, 0x20080
	v_lshl_add_u64 v[202:203], v[224:225], 0, s[38:39]
	s_addc_u32 s61, s61, 0
	s_add_i32 s3, s33, s14
	global_load_lds_dwordx4 v[202:203], off
	v_lshl_add_u64 v[202:203], s[60:61], 0, v[130:131]
	s_mov_b32 m0, s3
	s_nop 0
	global_load_lds_dwordx4 v[202:203], off
	v_lshl_add_u64 v[202:203], s[60:61], 0, v[134:135]
	s_add_i32 m0, s3, 0x2000
	s_nop 0
	global_load_lds_dwordx4 v[202:203], off
	s_waitcnt vmcnt(6)
	s_waitcnt lgkmcnt(0)
	s_barrier
	s_setprio 1
	s_waitcnt lgkmcnt(0)
	v_mfma_f32_16x16x32_bf16 v[60:63], v[144:147], v[186:189], v[60:63]
	v_mfma_f32_16x16x32_bf16 v[56:59], v[160:163], v[186:189], v[56:59]
	v_mfma_f32_16x16x32_bf16 v[44:47], v[144:147], v[194:197], v[44:47]
	v_mfma_f32_16x16x32_bf16 v[40:43], v[160:163], v[194:197], v[40:43]
	v_mfma_f32_16x16x32_bf16 v[60:63], v[156:159], v[190:193], v[60:63]
	v_mfma_f32_16x16x32_bf16 v[56:59], v[164:167], v[190:193], v[56:59]
	v_mfma_f32_16x16x32_bf16 v[44:47], v[156:159], v[198:201], v[44:47]
	v_mfma_f32_16x16x32_bf16 v[40:43], v[164:167], v[198:201], v[40:43]
	v_mfma_f32_16x16x32_bf16 v[28:31], v[144:147], v[208:211], v[28:31]
	v_mfma_f32_16x16x32_bf16 v[24:27], v[160:163], v[208:211], v[24:27]
	v_mfma_f32_16x16x32_bf16 v[12:15], v[144:147], v[216:219], v[12:15]
	v_mfma_f32_16x16x32_bf16 v[8:11], v[160:163], v[216:219], v[8:11]
	v_mfma_f32_16x16x32_bf16 v[28:31], v[156:159], v[212:215], v[28:31]
	v_mfma_f32_16x16x32_bf16 v[24:27], v[164:167], v[212:215], v[24:27]
	v_lshl_add_u64 v[202:203], v[226:227], 0, s[38:39]
	s_mov_b32 m0, s66
	s_nop 0
	global_load_lds_dwordx4 v[202:203], off
	v_mfma_f32_16x16x32_bf16 v[12:15], v[156:159], v[220:223], v[12:15]
	v_mfma_f32_16x16x32_bf16 v[8:11], v[164:167], v[220:223], v[8:11]
	s_setprio 0
	s_setprio 1
	v_mfma_f32_16x16x32_bf16 v[52:55], v[168:171], v[186:189], v[52:55]
	v_mfma_f32_16x16x32_bf16 v[48:51], v[176:179], v[186:189], v[48:51]
	v_mfma_f32_16x16x32_bf16 v[36:39], v[168:171], v[194:197], v[36:39]
	v_mfma_f32_16x16x32_bf16 v[32:35], v[176:179], v[194:197], v[32:35]
	v_mfma_f32_16x16x32_bf16 v[52:55], v[172:175], v[190:193], v[52:55]
	v_mfma_f32_16x16x32_bf16 v[48:51], v[182:185], v[190:193], v[48:51]
	v_mfma_f32_16x16x32_bf16 v[36:39], v[172:175], v[198:201], v[36:39]
	v_mfma_f32_16x16x32_bf16 v[32:35], v[182:185], v[198:201], v[32:35]
	v_mfma_f32_16x16x32_bf16 v[20:23], v[168:171], v[208:211], v[20:23]
	v_mfma_f32_16x16x32_bf16 v[16:19], v[176:179], v[208:211], v[16:19]
	v_mfma_f32_16x16x32_bf16 v[4:7], v[168:171], v[216:219], v[4:7]
	v_mfma_f32_16x16x32_bf16 v[0:3], v[176:179], v[216:219], v[0:3]
	v_mfma_f32_16x16x32_bf16 v[20:23], v[172:175], v[212:215], v[20:23]
	v_mfma_f32_16x16x32_bf16 v[16:19], v[182:185], v[212:215], v[16:19]
	v_lshl_add_u64 v[202:203], v[228:229], 0, s[38:39]
	s_mov_b32 m0, s67
	s_nop 0
	global_load_lds_dwordx4 v[202:203], off
	v_mfma_f32_16x16x32_bf16 v[4:7], v[172:175], v[220:223], v[4:7]
	v_mfma_f32_16x16x32_bf16 v[0:3], v[182:185], v[220:223], v[0:3]
	s_setprio 0
	s_barrier
	s_add_i32 s87, s87, 2
	s_add_u32 s58, s58, 0x100
	s_addc_u32 s59, s59, 0
	s_add_u32 s85, s85, 0x100
	s_addc_u32 s86, s86, 0
	s_cmp_gt_u32 s87, 5
	s_cbranch_scc0 .LBB0_873
	s_and_b64 vcc, exec, s[42:43]
	s_cbranch_vccz .LBB0_876
	s_barrier

; #define PG8_STAGE(bufoff, gbase, voff) do { _Pragma("unroll") for (int _i = 0; _i < 2; ++_i) \
;         __builtin_amdgcn_global_load_lds((const unsigned*)((const char*)(gbase) + (voff)[_i]), (PG8_LAS unsigned*)(lds + (bufoff) + ldsw + _i * 8192), 16, 0, 0); } while (0)
; #define PG8_LDA(dst, b, h) do { _Pragma("unroll") for (int m = 0; m < 4; ++m) _Pragma("unroll") for (int k = 0; k < 2; ++k) dst[m][k] = *(const PG8_LAS bf16x8*)(lds + PG8_SA(b, h) + aoff + m * 2048 + k * 1024); } while (0)
; #define PG8_LDB(dst, b, h) do { _Pragma("unroll") for (int n = 0; n < 2; ++n) _Pragma("unroll") for (int k = 0; k < 2; ++k) dst[n][k] = *(const PG8_LAS bf16x8*)(lds + PG8_SB(b, h) + boff + n * 2048 + k * 1024); } while (0)
; #define PG8_MMA(ai, bj, At, Bt) do { __builtin_amdgcn_s_setprio(1); _Pragma("unroll") for (int m = 0; m < 4; ++m) _Pragma("unroll") for (int n = 0; n < 2; ++n) _Pragma("unroll") for (int k = 0; k < 2; ++k) \
;         acc[ai][bj][m][n] = __builtin_amdgcn_mfma_f32_16x16x32_bf16(Bt[n][k], At[m][k], acc[ai][bj][m][n], 0, 0, 0); __builtin_amdgcn_s_setprio(0); } while (0)
; #define PG8_BAR __builtin_amdgcn_s_barrier()
; template <class Epi, class Sched, bool ALIGN_EPI = false, bool SP2 = false>
; __device__ __forceinline__ void gemm_phase(PG8_LAS unsigned char* lds, const Gemm g, const Sched& S, const Epi& E) {
;     ...
;         const bool has_next = S.next(ui + 1, nxt);
;         const char* nA = has_next ? (const char*)g.A + (size_t)nxt.pm * tstep : cA; const char* nB = has_next ? (const char*)g.Bt + (size_t)nxt.pn * tstep : cB;
;         for (int t = 0; t < nt; t += 2) {
;             const bool last = (t == nt - 2);
;             const char* a1 = cA + (size_t)(t + 1) * kstep;
;             const char* a2 = last ? nA : cA + (size_t)(t + 2) * kstep; const char* b2 = last ? nB : cB + (size_t)(t + 2) * kstep;
;             const char* a3 = a2 + kstep; const char* b3 = b2 + kstep;
;             if (last && has_next) S.a_ready(nxt);
;             if constexpr (SP2) {
;             PG8_LDB(B0, 0, 0); PG8_LDB(B1, 0, 1); PG8_SCHED; PG8_LDA(At, 0, 0); PG8_STAGE(PG8_SA(1, 1), a1 + hstep, voffA);
;             PG8_WAIT_V(8); PG8_WAIT_L(0); PG8_BAR; PG8_MMA(0, 0, At, B0); PG8_MMA(0, 1, At, B1); PG8_BAR; PG8_SCHED;
;             PG8_LDA(At, 0, 1); PG8_STAGE(PG8_SB(0, 0), b2, voffB); PG8_STAGE(PG8_SB(0, 1), b2 + hstep, voffB); PG8_STAGE(PG8_SA(0, 0), a2, voffA);
.LBB0_956:
	s_ashr_i32 s45, s44, 31
	s_lshl_b64 s[48:49], s[44:45], 19
	s_add_u32 s48, s22, s48
	s_addc_u32 s49, s23, s49
	s_and_b64 s[50:51], s[10:11], exec
	s_cselect_b32 s45, s49, s55
	s_cselect_b32 s75, s48, s54
	s_ashr_i32 s43, s42, 31
	s_lshl_b64 s[50:51], s[42:43], 19
	v_readlane_b32 s3, v250, 18
	s_add_u32 s50, s3, s50
	v_readlane_b32 s3, v250, 19
	s_addc_u32 s51, s3, s51
	s_and_b64 s[58:59], s[10:11], exec
	s_cselect_b32 s43, s51, s57
	s_cselect_b32 s76, s50, s56
	s_add_u32 s54, s54, 0x40080
	s_addc_u32 s55, s55, 0
	s_add_u32 s77, s56, 0x100
	s_addc_u32 s82, s57, 0
	s_mov_b32 s83, -2
	ds_read_b128 v[144:147], v155
	ds_read_b128 v[148:151], v155 offset:1024
	ds_read_b128 v[160:163], v155 offset:2048
	ds_read_b128 v[164:167], v155 offset:3072
	ds_read_b128 v[168:171], v156
	ds_read_b128 v[172:175], v156 offset:1024
	ds_read_b128 v[176:179], v156 offset:2048
	ds_read_b128 v[182:185], v156 offset:3072
	s_add_u32 s3, s54, 0xfffc0080
	s_addc_u32 s33, s55, -1
	s_cmp_eq_u32 s83, 12
	s_cselect_b32 s59, s45, s33
	s_cselect_b32 s58, s75, s3
	s_cselect_b32 s57, s43, s82
	s_cselect_b32 s56, s76, s77
	v_lshl_add_u64 v[202:203], s[54:55], 0, v[136:137]
	s_add_i32 m0, s34, 0xc000
	ds_read_b128 v[186:189], v157
	ds_read_b128 v[190:193], v157 offset:1024
	ds_read_b128 v[194:197], v157 offset:2048
	ds_read_b128 v[198:201], v157 offset:3072
	ds_read_b128 v[208:211], v157 offset:4096
	ds_read_b128 v[212:215], v157 offset:5120
	ds_read_b128 v[216:219], v157 offset:6144
	ds_read_b128 v[220:223], v157 offset:7168
	global_load_lds_dwordx4 v[202:203], off
	v_lshl_add_u64 v[202:203], s[54:55], 0, v[138:139]
	s_add_i32 m0, s34, 0xe000
	s_nop 0
	global_load_lds_dwordx4 v[202:203], off
	s_waitcnt vmcnt(8)
	s_waitcnt lgkmcnt(0)
	s_barrier
	s_setprio 1
	s_waitcnt lgkmcnt(0)
	v_mfma_f32_16x16x32_bf16 v[124:127], v[144:147], v[186:189], 0
	v_mfma_f32_16x16x32_bf16 v[120:123], v[160:163], v[186:189], 0
	v_mfma_f32_16x16x32_bf16 v[108:111], v[144:147], v[194:197], 0
	v_mfma_f32_16x16x32_bf16 v[104:107], v[160:163], v[194:197], 0
	v_mfma_f32_16x16x32_bf16 v[124:127], v[148:151], v[190:193], v[124:127]
	v_mfma_f32_16x16x32_bf16 v[120:123], v[164:167], v[190:193], v[120:123]
	v_mfma_f32_16x16x32_bf16 v[108:111], v[148:151], v[198:201], v[108:111]
	v_mfma_f32_16x16x32_bf16 v[104:107], v[164:167], v[198:201], v[104:107]
	v_mfma_f32_16x16x32_bf16 v[92:95], v[144:147], v[208:211], 0
	v_mfma_f32_16x16x32_bf16 v[88:91], v[160:163], v[208:211], 0
	v_mfma_f32_16x16x32_bf16 v[76:79], v[144:147], v[216:219], 0
	v_mfma_f32_16x16x32_bf16 v[72:75], v[160:163], v[216:219], 0
	v_mfma_f32_16x16x32_bf16 v[92:95], v[148:151], v[212:215], v[92:95]
	v_mfma_f32_16x16x32_bf16 v[88:91], v[164:167], v[212:215], v[88:91]
	v_mfma_f32_16x16x32_bf16 v[76:79], v[148:151], v[220:223], v[76:79]
	v_mfma_f32_16x16x32_bf16 v[72:75], v[164:167], v[220:223], v[72:75]
	s_setprio 0
	s_setprio 1
	v_mfma_f32_16x16x32_bf16 v[116:119], v[168:171], v[186:189], 0
	v_mfma_f32_16x16x32_bf16 v[112:115], v[176:179], v[186:189], 0
	v_mfma_f32_16x16x32_bf16 v[100:103], v[168:171], v[194:197], 0
	v_mfma_f32_16x16x32_bf16 v[96:99], v[176:179], v[194:197], 0
	v_mfma_f32_16x16x32_bf16 v[116:119], v[172:175], v[190:193], v[116:119]
	v_mfma_f32_16x16x32_bf16 v[112:115], v[182:185], v[190:193], v[112:115]
	v_mfma_f32_16x16x32_bf16 v[100:103], v[172:175], v[198:201], v[100:103]
	v_mfma_f32_16x16x32_bf16 v[96:99], v[182:185], v[198:201], v[96:99]
	v_mfma_f32_16x16x32_bf16 v[84:87], v[168:171], v[208:211], 0
	v_mfma_f32_16x16x32_bf16 v[80:83], v[176:179], v[208:211], 0
	v_mfma_f32_16x16x32_bf16 v[68:71], v[168:171], v[216:219], 0
	v_mfma_f32_16x16x32_bf16 v[64:67], v[176:179], v[216:219], 0
	v_mfma_f32_16x16x32_bf16 v[84:87], v[172:175], v[212:215], v[84:87]
	v_mfma_f32_16x16x32_bf16 v[80:83], v[182:185], v[212:215], v[80:83]
	v_mfma_f32_16x16x32_bf16 v[68:71], v[172:175], v[220:223], v[68:71]
	v_mfma_f32_16x16x32_bf16 v[64:67], v[182:185], v[220:223], v[64:67]
	s_setprio 0
	s_barrier
	s_add_i32 s3, s65, s14
	v_lshl_add_u64 v[202:203], s[56:57], 0, v[132:133]
	s_mov_b32 m0, s3
	ds_read_b128 v[186:189], v157 offset:16384
	ds_read_b128 v[190:193], v157 offset:17408
	ds_read_b128 v[194:197], v157 offset:18432
	ds_read_b128 v[198:201], v157 offset:19456
	ds_read_b128 v[208:211], v157 offset:20480
	ds_read_b128 v[212:215], v157 offset:21504
	ds_read_b128 v[216:219], v157 offset:22528
	ds_read_b128 v[220:223], v157 offset:23552
	global_load_lds_dwordx4 v[202:203], off
	s_add_i32 m0, s3, 0x2000
	s_add_u32 s78, s56, 0x40000
	v_lshl_add_u64 v[224:225], s[56:57], 0, v[128:129]
	s_addc_u32 s79, s57, 0
	s_add_i32 s3, s66, s14
	global_load_lds_dwordx4 v[224:225], off
	v_lshl_add_u64 v[226:227], s[78:79], 0, v[132:133]
	s_mov_b32 m0, s3
	global_load_lds_dwordx4 v[226:227], off
	v_lshl_add_u64 v[226:227], s[78:79], 0, v[128:129]
	s_add_i32 m0, s3, 0x2000
	s_nop 0
	global_load_lds_dwordx4 v[226:227], off
	s_waitcnt vmcnt(6)
	s_waitcnt lgkmcnt(0)
	s_barrier
; #define PG8_STAGE(bufoff, gbase, voff) do { _Pragma("unroll") for (int _i = 0; _i < 2; ++_i) \
;         __builtin_amdgcn_global_load_lds((const unsigned*)((const char*)(gbase) + (voff)[_i]), (PG8_LAS unsigned*)(lds + (bufoff) + ldsw + _i * 8192), 16, 0, 0); } while (0)
; #define PG8_LDA(dst, b, h) do { _Pragma("unroll") for (int m = 0; m < 4; ++m) _Pragma("unroll") for (int k = 0; k < 2; ++k) dst[m][k] = *(const PG8_LAS bf16x8*)(lds + PG8_SA(b, h) + aoff + m * 2048 + k * 1024); } while (0)
; #define PG8_LDB(dst, b, h) do { _Pragma("unroll") for (int n = 0; n < 2; ++n) _Pragma("unroll") for (int k = 0; k < 2; ++k) dst[n][k] = *(const PG8_LAS bf16x8*)(lds + PG8_SB(b, h) + boff + n * 2048 + k * 1024); } while (0)
; #define PG8_MMA(ai, bj, At, Bt) do { __builtin_amdgcn_s_setprio(1); _Pragma("unroll") for (int m = 0; m < 4; ++m) _Pragma("unroll") for (int n = 0; n < 2; ++n) _Pragma("unroll") for (int k = 0; k < 2; ++k) \
;         acc[ai][bj][m][n] = __builtin_amdgcn_mfma_f32_16x16x32_bf16(Bt[n][k], At[m][k], acc[ai][bj][m][n], 0, 0, 0); __builtin_amdgcn_s_setprio(0); } while (0)
; #define PG8_WAIT_V(n) asm volatile("s_waitcnt vmcnt(" #n ")" ::: "memory")
; #define PG8_WAIT_L(n) asm volatile("s_waitcnt lgkmcnt(" #n ")" ::: "memory")
; #define PG8_BAR __builtin_amdgcn_s_barrier()
; #define PG8_SCHED __builtin_amdgcn_sched_barrier(0)
; template <class Epi, class Sched, bool ALIGN_EPI = false, bool SP2 = false>
; __device__ __forceinline__ void gemm_phase(PG8_LAS unsigned char* lds, const Gemm g, const Sched& S, const Epi& E) {
;     ...
;             PG8_WAIT_V(8); PG8_WAIT_L(0); PG8_BAR; PG8_MMA(1, 0, At, B0); PG8_MMA(1, 1, At, B1); PG8_BAR; PG8_SCHED;
;             PG8_LDB(B0, 1, 0); PG8_LDB(B1, 1, 1); PG8_SCHED; PG8_LDA(At, 1, 0); PG8_STAGE(PG8_SA(0, 1), a2 + hstep, voffA);
;             PG8_WAIT_V(8); PG8_WAIT_L(0); PG8_BAR; PG8_MMA(0, 0, At, B0); PG8_MMA(0, 1, At, B1); PG8_BAR; PG8_SCHED;
	s_setprio 1
	s_waitcnt lgkmcnt(0)
	v_mfma_f32_16x16x32_bf16 v[60:63], v[144:147], v[186:189], 0
	v_mfma_f32_16x16x32_bf16 v[56:59], v[160:163], v[186:189], 0
	v_mfma_f32_16x16x32_bf16 v[44:47], v[144:147], v[194:197], 0
	v_mfma_f32_16x16x32_bf16 v[40:43], v[160:163], v[194:197], 0
	v_mfma_f32_16x16x32_bf16 v[60:63], v[148:151], v[190:193], v[60:63]
	v_mfma_f32_16x16x32_bf16 v[56:59], v[164:167], v[190:193], v[56:59]
	v_mfma_f32_16x16x32_bf16 v[44:47], v[148:151], v[198:201], v[44:47]
	v_mfma_f32_16x16x32_bf16 v[40:43], v[164:167], v[198:201], v[40:43]
	v_mfma_f32_16x16x32_bf16 v[28:31], v[144:147], v[208:211], 0
	v_mfma_f32_16x16x32_bf16 v[24:27], v[160:163], v[208:211], 0
	v_mfma_f32_16x16x32_bf16 v[12:15], v[144:147], v[216:219], 0
	v_mfma_f32_16x16x32_bf16 v[8:11], v[160:163], v[216:219], 0
	v_mfma_f32_16x16x32_bf16 v[28:31], v[148:151], v[212:215], v[28:31]
	v_mfma_f32_16x16x32_bf16 v[24:27], v[164:167], v[212:215], v[24:27]
	v_lshl_add_u64 v[226:227], s[58:59], 0, v[134:135]
	s_mov_b32 m0, s34
	s_nop 0
	global_load_lds_dwordx4 v[226:227], off
	v_mfma_f32_16x16x32_bf16 v[12:15], v[148:151], v[220:223], v[12:15]
	v_mfma_f32_16x16x32_bf16 v[8:11], v[164:167], v[220:223], v[8:11]
	s_setprio 0
	s_setprio 1
	v_mfma_f32_16x16x32_bf16 v[52:55], v[168:171], v[186:189], 0
	v_mfma_f32_16x16x32_bf16 v[48:51], v[176:179], v[186:189], 0
	v_mfma_f32_16x16x32_bf16 v[36:39], v[168:171], v[194:197], 0
	v_mfma_f32_16x16x32_bf16 v[32:35], v[176:179], v[194:197], 0
	v_mfma_f32_16x16x32_bf16 v[52:55], v[172:175], v[190:193], v[52:55]
	v_mfma_f32_16x16x32_bf16 v[48:51], v[182:185], v[190:193], v[48:51]
	v_mfma_f32_16x16x32_bf16 v[36:39], v[172:175], v[198:201], v[36:39]
	v_mfma_f32_16x16x32_bf16 v[32:35], v[182:185], v[198:201], v[32:35]
	v_mfma_f32_16x16x32_bf16 v[20:23], v[168:171], v[208:211], 0
	v_mfma_f32_16x16x32_bf16 v[16:19], v[176:179], v[208:211], 0
	v_mfma_f32_16x16x32_bf16 v[4:7], v[168:171], v[216:219], 0
	v_mfma_f32_16x16x32_bf16 v[0:3], v[176:179], v[216:219], 0
	v_mfma_f32_16x16x32_bf16 v[20:23], v[172:175], v[212:215], v[20:23]
	v_mfma_f32_16x16x32_bf16 v[16:19], v[182:185], v[212:215], v[16:19]
	v_lshl_add_u64 v[228:229], s[58:59], 0, v[130:131]
	s_mov_b32 m0, s53
	s_nop 0
	global_load_lds_dwordx4 v[228:229], off
	v_mfma_f32_16x16x32_bf16 v[4:7], v[172:175], v[220:223], v[4:7]
	v_mfma_f32_16x16x32_bf16 v[0:3], v[182:185], v[220:223], v[0:3]
	s_setprio 0
	s_barrier
	s_add_i32 s3, 0, 0x18000
	v_add_u32_e32 v159, s3, v153
	s_add_i32 s33, 0, 0x1c000
	ds_read_b128 v[144:147], v159
	ds_read_b128 v[148:151], v159 offset:1024
	ds_read_b128 v[160:163], v159 offset:2048
	ds_read_b128 v[164:167], v159 offset:3072
	v_add_u32_e32 v159, s33, v153
	ds_read_b128 v[168:171], v159
	ds_read_b128 v[172:175], v159 offset:1024
	ds_read_b128 v[176:179], v159 offset:2048
	ds_read_b128 v[182:185], v159 offset:3072
	s_add_u32 s58, s58, 0x40000
	s_addc_u32 s59, s59, 0
	s_mov_b32 m0, s60
	v_lshl_add_u64 v[230:231], s[58:59], 0, v[134:135]
	ds_read_b128 v[186:189], v157 offset:32768
	ds_read_b128 v[190:193], v157 offset:33792
	ds_read_b128 v[194:197], v157 offset:34816
	ds_read_b128 v[198:201], v157 offset:35840
	ds_read_b128 v[208:211], v157 offset:36864
	ds_read_b128 v[212:215], v157 offset:37888
	ds_read_b128 v[216:219], v157 offset:38912
	ds_read_b128 v[220:223], v157 offset:39936
	global_load_lds_dwordx4 v[230:231], off
	v_lshl_add_u64 v[230:231], s[58:59], 0, v[130:131]
	s_mov_b32 m0, s61
	s_nop 0
	global_load_lds_dwordx4 v[230:231], off
	s_waitcnt vmcnt(8)
	s_waitcnt lgkmcnt(0)
	s_barrier
	s_setprio 1
	s_waitcnt lgkmcnt(0)
	v_mfma_f32_16x16x32_bf16 v[124:127], v[144:147], v[186:189], v[124:127]
	v_mfma_f32_16x16x32_bf16 v[120:123], v[160:163], v[186:189], v[120:123]
	v_mfma_f32_16x16x32_bf16 v[108:111], v[144:147], v[194:197], v[108:111]
	v_mfma_f32_16x16x32_bf16 v[104:107], v[160:163], v[194:197], v[104:107]
	v_mfma_f32_16x16x32_bf16 v[124:127], v[148:151], v[190:193], v[124:127]
	v_mfma_f32_16x16x32_bf16 v[120:123], v[164:167], v[190:193], v[120:123]
	v_mfma_f32_16x16x32_bf16 v[108:111], v[148:151], v[198:201], v[108:111]
	v_mfma_f32_16x16x32_bf16 v[104:107], v[164:167], v[198:201], v[104:107]
	v_mfma_f32_16x16x32_bf16 v[92:95], v[144:147], v[208:211], v[92:95]
	v_mfma_f32_16x16x32_bf16 v[88:91], v[160:163], v[208:211], v[88:91]
	v_mfma_f32_16x16x32_bf16 v[76:79], v[144:147], v[216:219], v[76:79]
	v_mfma_f32_16x16x32_bf16 v[72:75], v[160:163], v[216:219], v[72:75]
	v_mfma_f32_16x16x32_bf16 v[92:95], v[148:151], v[212:215], v[92:95]
	v_mfma_f32_16x16x32_bf16 v[88:91], v[164:167], v[212:215], v[88:91]
	v_mfma_f32_16x16x32_bf16 v[76:79], v[148:151], v[220:223], v[76:79]
	v_mfma_f32_16x16x32_bf16 v[72:75], v[164:167], v[220:223], v[72:75]
	s_setprio 0
	s_setprio 1
	v_mfma_f32_16x16x32_bf16 v[116:119], v[168:171], v[186:189], v[116:119]
	v_mfma_f32_16x16x32_bf16 v[112:115], v[176:179], v[186:189], v[112:115]
	v_mfma_f32_16x16x32_bf16 v[100:103], v[168:171], v[194:197], v[100:103]
	v_mfma_f32_16x16x32_bf16 v[96:99], v[176:179], v[194:197], v[96:99]
	v_mfma_f32_16x16x32_bf16 v[116:119], v[172:175], v[190:193], v[116:119]
	v_mfma_f32_16x16x32_bf16 v[112:115], v[182:185], v[190:193], v[112:115]
	v_mfma_f32_16x16x32_bf16 v[100:103], v[172:175], v[198:201], v[100:103]
	v_mfma_f32_16x16x32_bf16 v[96:99], v[182:185], v[198:201], v[96:99]
	v_mfma_f32_16x16x32_bf16 v[84:87], v[168:171], v[208:211], v[84:87]
	v_mfma_f32_16x16x32_bf16 v[80:83], v[176:179], v[208:211], v[80:83]
	v_mfma_f32_16x16x32_bf16 v[68:71], v[168:171], v[216:219], v[68:71]
	v_mfma_f32_16x16x32_bf16 v[64:67], v[176:179], v[216:219], v[64:67]
	v_mfma_f32_16x16x32_bf16 v[84:87], v[172:175], v[212:215], v[84:87]
	v_mfma_f32_16x16x32_bf16 v[80:83], v[182:185], v[212:215], v[80:83]
	v_mfma_f32_16x16x32_bf16 v[68:71], v[172:175], v[220:223], v[68:71]
	v_mfma_f32_16x16x32_bf16 v[64:67], v[182:185], v[220:223], v[64:67]
	s_setprio 0
	s_barrier
; #define PG8_STAGE(bufoff, gbase, voff) do { _Pragma("unroll") for (int _i = 0; _i < 2; ++_i) \
;         __builtin_amdgcn_global_load_lds((const unsigned*)((const char*)(gbase) + (voff)[_i]), (PG8_LAS unsigned*)(lds + (bufoff) + ldsw + _i * 8192), 16, 0, 0); } while (0)
; #define PG8_LDA(dst, b, h) do { _Pragma("unroll") for (int m = 0; m < 4; ++m) _Pragma("unroll") for (int k = 0; k < 2; ++k) dst[m][k] = *(const PG8_LAS bf16x8*)(lds + PG8_SA(b, h) + aoff + m * 2048 + k * 1024); } while (0)
; #define PG8_LDB(dst, b, h) do { _Pragma("unroll") for (int n = 0; n < 2; ++n) _Pragma("unroll") for (int k = 0; k < 2; ++k) dst[n][k] = *(const PG8_LAS bf16x8*)(lds + PG8_SB(b, h) + boff + n * 2048 + k * 1024); } while (0)
; #define PG8_MMA(ai, bj, At, Bt) do { __builtin_amdgcn_s_setprio(1); _Pragma("unroll") for (int m = 0; m < 4; ++m) _Pragma("unroll") for (int n = 0; n < 2; ++n) _Pragma("unroll") for (int k = 0; k < 2; ++k) \
;         acc[ai][bj][m][n] = __builtin_amdgcn_mfma_f32_16x16x32_bf16(Bt[n][k], At[m][k], acc[ai][bj][m][n], 0, 0, 0); __builtin_amdgcn_s_setprio(0); } while (0)
; #define PG8_WAIT_V(n) asm volatile("s_waitcnt vmcnt(" #n ")" ::: "memory")
; #define PG8_WAIT_L(n) asm volatile("s_waitcnt lgkmcnt(" #n ")" ::: "memory")
; #define PG8_BAR __builtin_amdgcn_s_barrier()
; #define PG8_SCHED __builtin_amdgcn_sched_barrier(0)
; template <class Epi, class Sched, bool ALIGN_EPI = false, bool SP2 = false>
; __device__ __forceinline__ void gemm_phase(PG8_LAS unsigned char* lds, const Gemm g, const Sched& S, const Epi& E) {
;     ...
;             PG8_LDA(At, 1, 1); PG8_STAGE(PG8_SB(1, 0), b3, voffB); PG8_STAGE(PG8_SB(1, 1), b3 + hstep, voffB); PG8_STAGE(PG8_SA(1, 0), a3, voffA);
;             PG8_WAIT_V(8); PG8_WAIT_L(0); PG8_BAR; PG8_MMA(1, 0, At, B0); PG8_MMA(1, 1, At, B1); PG8_BAR; PG8_SCHED;
;             } else {
;             PG8_LDB(B0, 0, 0); PG8_SCHED; PG8_LDA(At, 0, 0); PG8_STAGE(PG8_SA(1, 1), a1 + hstep, voffA);
	s_add_i32 s3, s3, s14
	v_lshl_add_u64 v[202:203], v[202:203], 0, s[36:37]
	s_mov_b32 m0, s3
	ds_read_b128 v[186:189], v157 offset:49152
	ds_read_b128 v[190:193], v157 offset:50176
	ds_read_b128 v[194:197], v157 offset:51200
	ds_read_b128 v[198:201], v157 offset:52224
	ds_read_b128 v[208:211], v157 offset:53248
	ds_read_b128 v[212:215], v157 offset:54272
	ds_read_b128 v[216:219], v157 offset:55296
	ds_read_b128 v[220:223], v157 offset:56320
	global_load_lds_dwordx4 v[202:203], off
	s_add_i32 m0, s3, 0x2000
	s_add_u32 s56, s56, 0x40080
	v_lshl_add_u64 v[202:203], v[224:225], 0, s[36:37]
	s_addc_u32 s57, s57, 0
	s_add_i32 s3, s33, s14
	global_load_lds_dwordx4 v[202:203], off
	v_lshl_add_u64 v[202:203], s[56:57], 0, v[132:133]
	s_mov_b32 m0, s3
	s_nop 0
	global_load_lds_dwordx4 v[202:203], off
	v_lshl_add_u64 v[202:203], s[56:57], 0, v[128:129]
	s_add_i32 m0, s3, 0x2000
	s_nop 0
	global_load_lds_dwordx4 v[202:203], off
	s_waitcnt vmcnt(6)
	s_waitcnt lgkmcnt(0)
	s_barrier
	s_setprio 1
	s_waitcnt lgkmcnt(0)
	v_mfma_f32_16x16x32_bf16 v[60:63], v[144:147], v[186:189], v[60:63]
	v_mfma_f32_16x16x32_bf16 v[56:59], v[160:163], v[186:189], v[56:59]
	v_mfma_f32_16x16x32_bf16 v[44:47], v[144:147], v[194:197], v[44:47]
	v_mfma_f32_16x16x32_bf16 v[40:43], v[160:163], v[194:197], v[40:43]
	v_mfma_f32_16x16x32_bf16 v[60:63], v[148:151], v[190:193], v[60:63]
	v_mfma_f32_16x16x32_bf16 v[56:59], v[164:167], v[190:193], v[56:59]
	v_mfma_f32_16x16x32_bf16 v[44:47], v[148:151], v[198:201], v[44:47]
	v_mfma_f32_16x16x32_bf16 v[40:43], v[164:167], v[198:201], v[40:43]
	v_mfma_f32_16x16x32_bf16 v[28:31], v[144:147], v[208:211], v[28:31]
	v_mfma_f32_16x16x32_bf16 v[24:27], v[160:163], v[208:211], v[24:27]
	v_mfma_f32_16x16x32_bf16 v[12:15], v[144:147], v[216:219], v[12:15]
	v_mfma_f32_16x16x32_bf16 v[8:11], v[160:163], v[216:219], v[8:11]
	v_mfma_f32_16x16x32_bf16 v[28:31], v[148:151], v[212:215], v[28:31]
	v_mfma_f32_16x16x32_bf16 v[24:27], v[164:167], v[212:215], v[24:27]
	v_lshl_add_u64 v[202:203], v[226:227], 0, s[36:37]
	s_mov_b32 m0, s63
	s_nop 0
	global_load_lds_dwordx4 v[202:203], off
	v_mfma_f32_16x16x32_bf16 v[12:15], v[148:151], v[220:223], v[12:15]
	v_mfma_f32_16x16x32_bf16 v[8:11], v[164:167], v[220:223], v[8:11]
	s_setprio 0
	s_setprio 1
	v_mfma_f32_16x16x32_bf16 v[52:55], v[168:171], v[186:189], v[52:55]
	v_mfma_f32_16x16x32_bf16 v[48:51], v[176:179], v[186:189], v[48:51]
	v_mfma_f32_16x16x32_bf16 v[36:39], v[168:171], v[194:197], v[36:39]
	v_mfma_f32_16x16x32_bf16 v[32:35], v[176:179], v[194:197], v[32:35]
	v_mfma_f32_16x16x32_bf16 v[52:55], v[172:175], v[190:193], v[52:55]
	v_mfma_f32_16x16x32_bf16 v[48:51], v[182:185], v[190:193], v[48:51]
	v_mfma_f32_16x16x32_bf16 v[36:39], v[172:175], v[198:201], v[36:39]
	v_mfma_f32_16x16x32_bf16 v[32:35], v[182:185], v[198:201], v[32:35]
	v_mfma_f32_16x16x32_bf16 v[20:23], v[168:171], v[208:211], v[20:23]
	v_mfma_f32_16x16x32_bf16 v[16:19], v[176:179], v[208:211], v[16:19]
	v_mfma_f32_16x16x32_bf16 v[4:7], v[168:171], v[216:219], v[4:7]
	v_mfma_f32_16x16x32_bf16 v[0:3], v[176:179], v[216:219], v[0:3]
	v_mfma_f32_16x16x32_bf16 v[20:23], v[172:175], v[212:215], v[20:23]
	v_mfma_f32_16x16x32_bf16 v[16:19], v[182:185], v[212:215], v[16:19]
	v_lshl_add_u64 v[202:203], v[228:229], 0, s[36:37]
	s_mov_b32 m0, s64
	s_nop 0
	global_load_lds_dwordx4 v[202:203], off
	v_mfma_f32_16x16x32_bf16 v[4:7], v[172:175], v[220:223], v[4:7]
	v_mfma_f32_16x16x32_bf16 v[0:3], v[182:185], v[220:223], v[0:3]
	s_setprio 0
	s_barrier
	s_add_i32 s83, s83, 2
	s_add_u32 s54, s54, 0x100
	s_addc_u32 s55, s55, 0
	s_add_u32 s77, s77, 0x100
	s_addc_u32 s82, s82, 0
.LBB0_957:
	ds_read_b128 v[144:147], v155
	ds_read_b128 v[148:151], v155 offset:1024
	ds_read_b128 v[160:163], v155 offset:2048
	ds_read_b128 v[164:167], v155 offset:3072
	ds_read_b128 v[168:171], v156
	ds_read_b128 v[172:175], v156 offset:1024
	ds_read_b128 v[176:179], v156 offset:2048
	ds_read_b128 v[182:185], v156 offset:3072
	s_add_u32 s3, s54, 0xfffc0080
	s_addc_u32 s33, s55, -1
	s_cmp_eq_u32 s83, 12
	s_cselect_b32 s59, s45, s33
	s_cselect_b32 s58, s75, s3
	s_cselect_b32 s57, s43, s82
	s_cselect_b32 s56, s76, s77
	v_lshl_add_u64 v[202:203], s[54:55], 0, v[136:137]
	s_add_i32 m0, s34, 0xc000
	ds_read_b128 v[186:189], v157
	ds_read_b128 v[190:193], v157 offset:1024
	ds_read_b128 v[194:197], v157 offset:2048
	ds_read_b128 v[198:201], v157 offset:3072
	ds_read_b128 v[208:211], v157 offset:4096
	ds_read_b128 v[212:215], v157 offset:5120
	ds_read_b128 v[216:219], v157 offset:6144
	ds_read_b128 v[220:223], v157 offset:7168
	global_load_lds_dwordx4 v[202:203], off
	v_lshl_add_u64 v[202:203], s[54:55], 0, v[138:139]
	s_add_i32 m0, s34, 0xe000
	s_nop 0
	global_load_lds_dwordx4 v[202:203], off
	s_waitcnt vmcnt(8)
	s_waitcnt lgkmcnt(0)
	s_barrier
; #define PG8_STAGE(bufoff, gbase, voff) do { _Pragma("unroll") for (int _i = 0; _i < 2; ++_i) \
;         __builtin_amdgcn_global_load_lds((const unsigned*)((const char*)(gbase) + (voff)[_i]), (PG8_LAS unsigned*)(lds + (bufoff) + ldsw + _i * 8192), 16, 0, 0); } while (0)
; #define PG8_LDA(dst, b, h) do { _Pragma("unroll") for (int m = 0; m < 4; ++m) _Pragma("unroll") for (int k = 0; k < 2; ++k) dst[m][k] = *(const PG8_LAS bf16x8*)(lds + PG8_SA(b, h) + aoff + m * 2048 + k * 1024); } while (0)
; #define PG8_LDB(dst, b, h) do { _Pragma("unroll") for (int n = 0; n < 2; ++n) _Pragma("unroll") for (int k = 0; k < 2; ++k) dst[n][k] = *(const PG8_LAS bf16x8*)(lds + PG8_SB(b, h) + boff + n * 2048 + k * 1024); } while (0)
; #define PG8_MMA(ai, bj, At, Bt) do { __builtin_amdgcn_s_setprio(1); _Pragma("unroll") for (int m = 0; m < 4; ++m) _Pragma("unroll") for (int n = 0; n < 2; ++n) _Pragma("unroll") for (int k = 0; k < 2; ++k) \
;         acc[ai][bj][m][n] = __builtin_amdgcn_mfma_f32_16x16x32_bf16(Bt[n][k], At[m][k], acc[ai][bj][m][n], 0, 0, 0); __builtin_amdgcn_s_setprio(0); } while (0)
; #define PG8_WAIT_V(n) asm volatile("s_waitcnt vmcnt(" #n ")" ::: "memory")
; #define PG8_WAIT_L(n) asm volatile("s_waitcnt lgkmcnt(" #n ")" ::: "memory")
; #define PG8_BAR __builtin_amdgcn_s_barrier()
; #define PG8_SCHED __builtin_amdgcn_sched_barrier(0)
; template <class Epi, class Sched, bool ALIGN_EPI = false, bool SP2 = false>
; __device__ __forceinline__ void gemm_phase(PG8_LAS unsigned char* lds, const Gemm g, const Sched& S, const Epi& E) {
;     ...
;             PG8_LDB(B0, 0, 0); PG8_LDB(B1, 0, 1); PG8_SCHED; PG8_LDA(At, 0, 0); PG8_STAGE(PG8_SA(1, 1), a1 + hstep, voffA);
;             PG8_WAIT_V(8); PG8_WAIT_L(0); PG8_BAR; PG8_MMA(0, 0, At, B0); PG8_MMA(0, 1, At, B1); PG8_BAR; PG8_SCHED;
;             PG8_LDA(At, 0, 1); PG8_STAGE(PG8_SB(0, 0), b2, voffB); PG8_STAGE(PG8_SB(0, 1), b2 + hstep, voffB); PG8_STAGE(PG8_SA(0, 0), a2, voffA);
;             PG8_WAIT_V(8); PG8_WAIT_L(0); PG8_BAR; PG8_MMA(1, 0, At, B0); PG8_MMA(1, 1, At, B1); PG8_BAR; PG8_SCHED;
	s_setprio 1
	s_waitcnt lgkmcnt(0)
	v_mfma_f32_16x16x32_bf16 v[124:127], v[144:147], v[186:189], v[124:127]
	v_mfma_f32_16x16x32_bf16 v[120:123], v[160:163], v[186:189], v[120:123]
	v_mfma_f32_16x16x32_bf16 v[108:111], v[144:147], v[194:197], v[108:111]
	v_mfma_f32_16x16x32_bf16 v[104:107], v[160:163], v[194:197], v[104:107]
	v_mfma_f32_16x16x32_bf16 v[124:127], v[148:151], v[190:193], v[124:127]
	v_mfma_f32_16x16x32_bf16 v[120:123], v[164:167], v[190:193], v[120:123]
	v_mfma_f32_16x16x32_bf16 v[108:111], v[148:151], v[198:201], v[108:111]
	v_mfma_f32_16x16x32_bf16 v[104:107], v[164:167], v[198:201], v[104:107]
	v_mfma_f32_16x16x32_bf16 v[92:95], v[144:147], v[208:211], v[92:95]
	v_mfma_f32_16x16x32_bf16 v[88:91], v[160:163], v[208:211], v[88:91]
	v_mfma_f32_16x16x32_bf16 v[76:79], v[144:147], v[216:219], v[76:79]
	v_mfma_f32_16x16x32_bf16 v[72:75], v[160:163], v[216:219], v[72:75]
	v_mfma_f32_16x16x32_bf16 v[92:95], v[148:151], v[212:215], v[92:95]
	v_mfma_f32_16x16x32_bf16 v[88:91], v[164:167], v[212:215], v[88:91]
	v_mfma_f32_16x16x32_bf16 v[76:79], v[148:151], v[220:223], v[76:79]
	v_mfma_f32_16x16x32_bf16 v[72:75], v[164:167], v[220:223], v[72:75]
	s_setprio 0
	s_setprio 1
	v_mfma_f32_16x16x32_bf16 v[116:119], v[168:171], v[186:189], v[116:119]
	v_mfma_f32_16x16x32_bf16 v[112:115], v[176:179], v[186:189], v[112:115]
	v_mfma_f32_16x16x32_bf16 v[100:103], v[168:171], v[194:197], v[100:103]
	v_mfma_f32_16x16x32_bf16 v[96:99], v[176:179], v[194:197], v[96:99]
	v_mfma_f32_16x16x32_bf16 v[116:119], v[172:175], v[190:193], v[116:119]
	v_mfma_f32_16x16x32_bf16 v[112:115], v[182:185], v[190:193], v[112:115]
	v_mfma_f32_16x16x32_bf16 v[100:103], v[172:175], v[198:201], v[100:103]
	v_mfma_f32_16x16x32_bf16 v[96:99], v[182:185], v[198:201], v[96:99]
	v_mfma_f32_16x16x32_bf16 v[84:87], v[168:171], v[208:211], v[84:87]
	v_mfma_f32_16x16x32_bf16 v[80:83], v[176:179], v[208:211], v[80:83]
	v_mfma_f32_16x16x32_bf16 v[68:71], v[168:171], v[216:219], v[68:71]
	v_mfma_f32_16x16x32_bf16 v[64:67], v[176:179], v[216:219], v[64:67]
	v_mfma_f32_16x16x32_bf16 v[84:87], v[172:175], v[212:215], v[84:87]
	v_mfma_f32_16x16x32_bf16 v[80:83], v[182:185], v[212:215], v[80:83]
	v_mfma_f32_16x16x32_bf16 v[68:71], v[172:175], v[220:223], v[68:71]
	v_mfma_f32_16x16x32_bf16 v[64:67], v[182:185], v[220:223], v[64:67]
	s_setprio 0
	s_barrier
	s_add_i32 s3, s65, s14
	v_lshl_add_u64 v[202:203], s[56:57], 0, v[132:133]
	s_mov_b32 m0, s3
	ds_read_b128 v[186:189], v157 offset:16384
	ds_read_b128 v[190:193], v157 offset:17408
	ds_read_b128 v[194:197], v157 offset:18432
	ds_read_b128 v[198:201], v157 offset:19456
	ds_read_b128 v[208:211], v157 offset:20480
	ds_read_b128 v[212:215], v157 offset:21504
	ds_read_b128 v[216:219], v157 offset:22528
	ds_read_b128 v[220:223], v157 offset:23552
	global_load_lds_dwordx4 v[202:203], off
	s_add_i32 m0, s3, 0x2000
	s_add_u32 s78, s56, 0x40000
	v_lshl_add_u64 v[224:225], s[56:57], 0, v[128:129]
	s_addc_u32 s79, s57, 0
	s_add_i32 s3, s66, s14
	global_load_lds_dwordx4 v[224:225], off
	v_lshl_add_u64 v[226:227], s[78:79], 0, v[132:133]
	s_mov_b32 m0, s3
	global_load_lds_dwordx4 v[226:227], off
	v_lshl_add_u64 v[226:227], s[78:79], 0, v[128:129]
	s_add_i32 m0, s3, 0x2000
	s_nop 0
	global_load_lds_dwordx4 v[226:227], off
	s_waitcnt vmcnt(6)
	s_waitcnt lgkmcnt(0)
	s_barrier
	s_setprio 1
	s_waitcnt lgkmcnt(0)
	v_mfma_f32_16x16x32_bf16 v[60:63], v[144:147], v[186:189], v[60:63]
	v_mfma_f32_16x16x32_bf16 v[56:59], v[160:163], v[186:189], v[56:59]
	v_mfma_f32_16x16x32_bf16 v[44:47], v[144:147], v[194:197], v[44:47]
	v_mfma_f32_16x16x32_bf16 v[40:43], v[160:163], v[194:197], v[40:43]
	v_mfma_f32_16x16x32_bf16 v[60:63], v[148:151], v[190:193], v[60:63]
	v_mfma_f32_16x16x32_bf16 v[56:59], v[164:167], v[190:193], v[56:59]
	v_mfma_f32_16x16x32_bf16 v[44:47], v[148:151], v[198:201], v[44:47]
	v_mfma_f32_16x16x32_bf16 v[40:43], v[164:167], v[198:201], v[40:43]
	v_mfma_f32_16x16x32_bf16 v[28:31], v[144:147], v[208:211], v[28:31]
	v_mfma_f32_16x16x32_bf16 v[24:27], v[160:163], v[208:211], v[24:27]
	v_mfma_f32_16x16x32_bf16 v[12:15], v[144:147], v[216:219], v[12:15]
	v_mfma_f32_16x16x32_bf16 v[8:11], v[160:163], v[216:219], v[8:11]
	v_mfma_f32_16x16x32_bf16 v[28:31], v[148:151], v[212:215], v[28:31]
	v_mfma_f32_16x16x32_bf16 v[24:27], v[164:167], v[212:215], v[24:27]
	v_lshl_add_u64 v[226:227], s[58:59], 0, v[134:135]
	s_mov_b32 m0, s34
	s_nop 0
	global_load_lds_dwordx4 v[226:227], off
	v_mfma_f32_16x16x32_bf16 v[12:15], v[148:151], v[220:223], v[12:15]
	v_mfma_f32_16x16x32_bf16 v[8:11], v[164:167], v[220:223], v[8:11]
	s_setprio 0
	s_setprio 1
	v_mfma_f32_16x16x32_bf16 v[52:55], v[168:171], v[186:189], v[52:55]
	v_mfma_f32_16x16x32_bf16 v[48:51], v[176:179], v[186:189], v[48:51]
	v_mfma_f32_16x16x32_bf16 v[36:39], v[168:171], v[194:197], v[36:39]
	v_mfma_f32_16x16x32_bf16 v[32:35], v[176:179], v[194:197], v[32:35]
	v_mfma_f32_16x16x32_bf16 v[52:55], v[172:175], v[190:193], v[52:55]
	v_mfma_f32_16x16x32_bf16 v[48:51], v[182:185], v[190:193], v[48:51]
	v_mfma_f32_16x16x32_bf16 v[36:39], v[172:175], v[198:201], v[36:39]
	v_mfma_f32_16x16x32_bf16 v[32:35], v[182:185], v[198:201], v[32:35]
	v_mfma_f32_16x16x32_bf16 v[20:23], v[168:171], v[208:211], v[20:23]
	v_mfma_f32_16x16x32_bf16 v[16:19], v[176:179], v[208:211], v[16:19]
	v_mfma_f32_16x16x32_bf16 v[4:7], v[168:171], v[216:219], v[4:7]
	v_mfma_f32_16x16x32_bf16 v[0:3], v[176:179], v[216:219], v[0:3]
	v_mfma_f32_16x16x32_bf16 v[20:23], v[172:175], v[212:215], v[20:23]
	v_mfma_f32_16x16x32_bf16 v[16:19], v[182:185], v[212:215], v[16:19]
	v_lshl_add_u64 v[228:229], s[58:59], 0, v[130:131]
	s_mov_b32 m0, s53
	s_nop 0
	global_load_lds_dwordx4 v[228:229], off
	v_mfma_f32_16x16x32_bf16 v[4:7], v[172:175], v[220:223], v[4:7]
	v_mfma_f32_16x16x32_bf16 v[0:3], v[182:185], v[220:223], v[0:3]
	s_setprio 0
	s_barrier
; #define PG8_STAGE(bufoff, gbase, voff) do { _Pragma("unroll") for (int _i = 0; _i < 2; ++_i) \
;         __builtin_amdgcn_global_load_lds((const unsigned*)((const char*)(gbase) + (voff)[_i]), (PG8_LAS unsigned*)(lds + (bufoff) + ldsw + _i * 8192), 16, 0, 0); } while (0)
; #define PG8_LDA(dst, b, h) do { _Pragma("unroll") for (int m = 0; m < 4; ++m) _Pragma("unroll") for (int k = 0; k < 2; ++k) dst[m][k] = *(const PG8_LAS bf16x8*)(lds + PG8_SA(b, h) + aoff + m * 2048 + k * 1024); } while (0)
; #define PG8_LDB(dst, b, h) do { _Pragma("unroll") for (int n = 0; n < 2; ++n) _Pragma("unroll") for (int k = 0; k < 2; ++k) dst[n][k] = *(const PG8_LAS bf16x8*)(lds + PG8_SB(b, h) + boff + n * 2048 + k * 1024); } while (0)
; #define PG8_MMA(ai, bj, At, Bt) do { __builtin_amdgcn_s_setprio(1); _Pragma("unroll") for (int m = 0; m < 4; ++m) _Pragma("unroll") for (int n = 0; n < 2; ++n) _Pragma("unroll") for (int k = 0; k < 2; ++k) \
;         acc[ai][bj][m][n] = __builtin_amdgcn_mfma_f32_16x16x32_bf16(Bt[n][k], At[m][k], acc[ai][bj][m][n], 0, 0, 0); __builtin_amdgcn_s_setprio(0); } while (0)
; #define PG8_WAIT_V(n) asm volatile("s_waitcnt vmcnt(" #n ")" ::: "memory")
; #define PG8_WAIT_L(n) asm volatile("s_waitcnt lgkmcnt(" #n ")" ::: "memory")
; #define PG8_BAR __builtin_amdgcn_s_barrier()
; #define PG8_SCHED __builtin_amdgcn_sched_barrier(0)
; template <class Epi, class Sched, bool ALIGN_EPI = false, bool SP2 = false>
; __device__ __forceinline__ void gemm_phase(PG8_LAS unsigned char* lds, const Gemm g, const Sched& S, const Epi& E) {
;     ...
;             PG8_LDB(B0, 1, 0); PG8_LDB(B1, 1, 1); PG8_SCHED; PG8_LDA(At, 1, 0); PG8_STAGE(PG8_SA(0, 1), a2 + hstep, voffA);
;             PG8_WAIT_V(8); PG8_WAIT_L(0); PG8_BAR; PG8_MMA(0, 0, At, B0); PG8_MMA(0, 1, At, B1); PG8_BAR; PG8_SCHED;
	s_add_i32 s3, 0, 0x18000
	v_add_u32_e32 v159, s3, v153
	s_add_i32 s33, 0, 0x1c000
	ds_read_b128 v[144:147], v159
	ds_read_b128 v[148:151], v159 offset:1024
	ds_read_b128 v[160:163], v159 offset:2048
	ds_read_b128 v[164:167], v159 offset:3072
	v_add_u32_e32 v159, s33, v153
	ds_read_b128 v[168:171], v159
	ds_read_b128 v[172:175], v159 offset:1024
	ds_read_b128 v[176:179], v159 offset:2048
	ds_read_b128 v[182:185], v159 offset:3072
	s_add_u32 s58, s58, 0x40000
	s_addc_u32 s59, s59, 0
	s_mov_b32 m0, s60
	v_lshl_add_u64 v[230:231], s[58:59], 0, v[134:135]
	ds_read_b128 v[186:189], v157 offset:32768
	ds_read_b128 v[190:193], v157 offset:33792
	ds_read_b128 v[194:197], v157 offset:34816
	ds_read_b128 v[198:201], v157 offset:35840
	ds_read_b128 v[208:211], v157 offset:36864
	ds_read_b128 v[212:215], v157 offset:37888
	ds_read_b128 v[216:219], v157 offset:38912
	ds_read_b128 v[220:223], v157 offset:39936
	global_load_lds_dwordx4 v[230:231], off
	v_lshl_add_u64 v[230:231], s[58:59], 0, v[130:131]
	s_mov_b32 m0, s61
	s_nop 0
	global_load_lds_dwordx4 v[230:231], off
	s_waitcnt vmcnt(8)
	s_waitcnt lgkmcnt(0)
	s_barrier
	s_setprio 1
	s_waitcnt lgkmcnt(0)
	v_mfma_f32_16x16x32_bf16 v[124:127], v[144:147], v[186:189], v[124:127]
	v_mfma_f32_16x16x32_bf16 v[120:123], v[160:163], v[186:189], v[120:123]
	v_mfma_f32_16x16x32_bf16 v[108:111], v[144:147], v[194:197], v[108:111]
	v_mfma_f32_16x16x32_bf16 v[104:107], v[160:163], v[194:197], v[104:107]
	v_mfma_f32_16x16x32_bf16 v[124:127], v[148:151], v[190:193], v[124:127]
	v_mfma_f32_16x16x32_bf16 v[120:123], v[164:167], v[190:193], v[120:123]
	v_mfma_f32_16x16x32_bf16 v[108:111], v[148:151], v[198:201], v[108:111]
	v_mfma_f32_16x16x32_bf16 v[104:107], v[164:167], v[198:201], v[104:107]
	v_mfma_f32_16x16x32_bf16 v[92:95], v[144:147], v[208:211], v[92:95]
	v_mfma_f32_16x16x32_bf16 v[88:91], v[160:163], v[208:211], v[88:91]
	v_mfma_f32_16x16x32_bf16 v[76:79], v[144:147], v[216:219], v[76:79]
	v_mfma_f32_16x16x32_bf16 v[72:75], v[160:163], v[216:219], v[72:75]
	v_mfma_f32_16x16x32_bf16 v[92:95], v[148:151], v[212:215], v[92:95]
	v_mfma_f32_16x16x32_bf16 v[88:91], v[164:167], v[212:215], v[88:91]
	v_mfma_f32_16x16x32_bf16 v[76:79], v[148:151], v[220:223], v[76:79]
	v_mfma_f32_16x16x32_bf16 v[72:75], v[164:167], v[220:223], v[72:75]
	s_setprio 0
	s_setprio 1
	v_mfma_f32_16x16x32_bf16 v[116:119], v[168:171], v[186:189], v[116:119]
	v_mfma_f32_16x16x32_bf16 v[112:115], v[176:179], v[186:189], v[112:115]
	v_mfma_f32_16x16x32_bf16 v[100:103], v[168:171], v[194:197], v[100:103]
	v_mfma_f32_16x16x32_bf16 v[96:99], v[176:179], v[194:197], v[96:99]
	v_mfma_f32_16x16x32_bf16 v[116:119], v[172:175], v[190:193], v[116:119]
	v_mfma_f32_16x16x32_bf16 v[112:115], v[182:185], v[190:193], v[112:115]
	v_mfma_f32_16x16x32_bf16 v[100:103], v[172:175], v[198:201], v[100:103]
	v_mfma_f32_16x16x32_bf16 v[96:99], v[182:185], v[198:201], v[96:99]
	v_mfma_f32_16x16x32_bf16 v[84:87], v[168:171], v[208:211], v[84:87]
	v_mfma_f32_16x16x32_bf16 v[80:83], v[176:179], v[208:211], v[80:83]
	v_mfma_f32_16x16x32_bf16 v[68:71], v[168:171], v[216:219], v[68:71]
	v_mfma_f32_16x16x32_bf16 v[64:67], v[176:179], v[216:219], v[64:67]
	v_mfma_f32_16x16x32_bf16 v[84:87], v[172:175], v[212:215], v[84:87]
	v_mfma_f32_16x16x32_bf16 v[80:83], v[182:185], v[212:215], v[80:83]
	v_mfma_f32_16x16x32_bf16 v[68:71], v[172:175], v[220:223], v[68:71]
	v_mfma_f32_16x16x32_bf16 v[64:67], v[182:185], v[220:223], v[64:67]
	s_setprio 0
	s_barrier
; #define PG8_STAGE(bufoff, gbase, voff) do { _Pragma("unroll") for (int _i = 0; _i < 2; ++_i) \
;         __builtin_amdgcn_global_load_lds((const unsigned*)((const char*)(gbase) + (voff)[_i]), (PG8_LAS unsigned*)(lds + (bufoff) + ldsw + _i * 8192), 16, 0, 0); } while (0)
; #define PG8_LDA(dst, b, h) do { _Pragma("unroll") for (int m = 0; m < 4; ++m) _Pragma("unroll") for (int k = 0; k < 2; ++k) dst[m][k] = *(const PG8_LAS bf16x8*)(lds + PG8_SA(b, h) + aoff + m * 2048 + k * 1024); } while (0)
; #define PG8_MMA(ai, bj, At, Bt) do { __builtin_amdgcn_s_setprio(1); _Pragma("unroll") for (int m = 0; m < 4; ++m) _Pragma("unroll") for (int n = 0; n < 2; ++n) _Pragma("unroll") for (int k = 0; k < 2; ++k) \
;         acc[ai][bj][m][n] = __builtin_amdgcn_mfma_f32_16x16x32_bf16(Bt[n][k], At[m][k], acc[ai][bj][m][n], 0, 0, 0); __builtin_amdgcn_s_setprio(0); } while (0)
; #define PG8_WAIT_V(n) asm volatile("s_waitcnt vmcnt(" #n ")" ::: "memory")
; #define PG8_WAIT_L(n) asm volatile("s_waitcnt lgkmcnt(" #n ")" ::: "memory")
; #define PG8_BAR __builtin_amdgcn_s_barrier()
; #define PG8_SCHED __builtin_amdgcn_sched_barrier(0)
; __device__ __forceinline__ float row_rs(const float* ssp, int row) { const unsigned long long v = ((const unsigned long long*)ssp)[row];
;     return __builtin_amdgcn_rsqf((float)v * (1.0f / 4294967296.0f) * (1.0f / 1024.0f) + RMS_EPS); }
; template <class Epi, class Sched, bool ALIGN_EPI = false, bool SP2 = false>
; __device__ __forceinline__ void gemm_phase(PG8_LAS unsigned char* lds, const Gemm g, const Sched& S, const Epi& E) {
;     ...
;             PG8_LDA(At, 1, 1); PG8_STAGE(PG8_SB(1, 0), b3, voffB); PG8_STAGE(PG8_SB(1, 1), b3 + hstep, voffB); PG8_STAGE(PG8_SA(1, 0), a3, voffA);
;             PG8_WAIT_V(8); PG8_WAIT_L(0); PG8_BAR; PG8_MMA(1, 0, At, B0); PG8_MMA(1, 1, At, B1); PG8_BAR; PG8_SCHED;
	s_add_i32 s3, s3, s14
	v_lshl_add_u64 v[202:203], v[202:203], 0, s[36:37]
	s_mov_b32 m0, s3
	ds_read_b128 v[186:189], v157 offset:49152
	ds_read_b128 v[190:193], v157 offset:50176
	ds_read_b128 v[194:197], v157 offset:51200
	ds_read_b128 v[198:201], v157 offset:52224
	ds_read_b128 v[208:211], v157 offset:53248
	ds_read_b128 v[212:215], v157 offset:54272
	ds_read_b128 v[216:219], v157 offset:55296
	ds_read_b128 v[220:223], v157 offset:56320
	global_load_lds_dwordx4 v[202:203], off
	s_add_i32 m0, s3, 0x2000
	s_add_u32 s56, s56, 0x40080
	v_lshl_add_u64 v[202:203], v[224:225], 0, s[36:37]
	s_addc_u32 s57, s57, 0
	s_add_i32 s3, s33, s14
	global_load_lds_dwordx4 v[202:203], off
	v_lshl_add_u64 v[202:203], s[56:57], 0, v[132:133]
	s_mov_b32 m0, s3
	s_nop 0
	global_load_lds_dwordx4 v[202:203], off
	v_lshl_add_u64 v[202:203], s[56:57], 0, v[128:129]
	s_add_i32 m0, s3, 0x2000
	s_nop 0
	global_load_lds_dwordx4 v[202:203], off
	s_waitcnt vmcnt(6)
	s_waitcnt lgkmcnt(0)
	s_barrier
	s_setprio 1
	s_waitcnt lgkmcnt(0)
	v_mfma_f32_16x16x32_bf16 v[60:63], v[144:147], v[186:189], v[60:63]
	v_mfma_f32_16x16x32_bf16 v[56:59], v[160:163], v[186:189], v[56:59]
	v_mfma_f32_16x16x32_bf16 v[44:47], v[144:147], v[194:197], v[44:47]
	v_mfma_f32_16x16x32_bf16 v[40:43], v[160:163], v[194:197], v[40:43]
	v_mfma_f32_16x16x32_bf16 v[60:63], v[148:151], v[190:193], v[60:63]
	v_mfma_f32_16x16x32_bf16 v[56:59], v[164:167], v[190:193], v[56:59]
	v_mfma_f32_16x16x32_bf16 v[44:47], v[148:151], v[198:201], v[44:47]
	v_mfma_f32_16x16x32_bf16 v[40:43], v[164:167], v[198:201], v[40:43]
	v_mfma_f32_16x16x32_bf16 v[28:31], v[144:147], v[208:211], v[28:31]
	v_mfma_f32_16x16x32_bf16 v[24:27], v[160:163], v[208:211], v[24:27]
	v_mfma_f32_16x16x32_bf16 v[12:15], v[144:147], v[216:219], v[12:15]
	v_mfma_f32_16x16x32_bf16 v[8:11], v[160:163], v[216:219], v[8:11]
	v_mfma_f32_16x16x32_bf16 v[28:31], v[148:151], v[212:215], v[28:31]
	v_mfma_f32_16x16x32_bf16 v[24:27], v[164:167], v[212:215], v[24:27]
	v_lshl_add_u64 v[202:203], v[226:227], 0, s[36:37]
	s_mov_b32 m0, s63
	s_nop 0
	global_load_lds_dwordx4 v[202:203], off
	v_mfma_f32_16x16x32_bf16 v[12:15], v[148:151], v[220:223], v[12:15]
	v_mfma_f32_16x16x32_bf16 v[8:11], v[164:167], v[220:223], v[8:11]
	s_setprio 0
	s_setprio 1
	v_mfma_f32_16x16x32_bf16 v[52:55], v[168:171], v[186:189], v[52:55]
	v_mfma_f32_16x16x32_bf16 v[48:51], v[176:179], v[186:189], v[48:51]
	v_mfma_f32_16x16x32_bf16 v[36:39], v[168:171], v[194:197], v[36:39]
	v_mfma_f32_16x16x32_bf16 v[32:35], v[176:179], v[194:197], v[32:35]
	v_mfma_f32_16x16x32_bf16 v[52:55], v[172:175], v[190:193], v[52:55]
	v_mfma_f32_16x16x32_bf16 v[48:51], v[182:185], v[190:193], v[48:51]
	v_mfma_f32_16x16x32_bf16 v[36:39], v[172:175], v[198:201], v[36:39]
	v_mfma_f32_16x16x32_bf16 v[32:35], v[182:185], v[198:201], v[32:35]
	v_mfma_f32_16x16x32_bf16 v[20:23], v[168:171], v[208:211], v[20:23]
	v_mfma_f32_16x16x32_bf16 v[16:19], v[176:179], v[208:211], v[16:19]
	v_mfma_f32_16x16x32_bf16 v[4:7], v[168:171], v[216:219], v[4:7]
	v_mfma_f32_16x16x32_bf16 v[0:3], v[176:179], v[216:219], v[0:3]
	v_mfma_f32_16x16x32_bf16 v[20:23], v[172:175], v[212:215], v[20:23]
	v_mfma_f32_16x16x32_bf16 v[16:19], v[182:185], v[212:215], v[16:19]
	v_lshl_add_u64 v[202:203], v[228:229], 0, s[36:37]
	s_mov_b32 m0, s64
	s_nop 0
	global_load_lds_dwordx4 v[202:203], off
	v_mfma_f32_16x16x32_bf16 v[4:7], v[172:175], v[220:223], v[4:7]
	v_mfma_f32_16x16x32_bf16 v[0:3], v[182:185], v[220:223], v[0:3]
	s_setprio 0
	s_barrier
	s_add_i32 s83, s83, 2
	s_add_u32 s54, s54, 0x100
	s_addc_u32 s55, s55, 0
	s_add_u32 s77, s77, 0x100
	s_addc_u32 s82, s82, 0
	s_cmp_gt_u32 s83, 13
	s_cbranch_scc0 .LBB0_957
	v_lshl_add_u32 v144, s52, 8, v152
	v_ashrrev_i32_e32 v145, 31, v144
	v_lshl_add_u64 v[150:151], v[144:145], 3, s[0:1]
	global_load_dwordx2 v[182:183], v[150:151], off
	global_load_dwordx2 v[184:185], v[150:151], off offset:128
	global_load_dwordx2 v[186:187], v[150:151], off offset:256
	global_load_dwordx2 v[188:189], v[150:151], off offset:384
	global_load_dwordx2 v[190:191], v[150:151], off offset:1024
	global_load_dwordx2 v[192:193], v[150:151], off offset:1152
	global_load_dwordx2 v[194:195], v[150:151], off offset:1280
	global_load_dwordx2 v[196:197], v[150:151], off offset:1408
	s_and_b64 vcc, exec, s[38:39]
	s_cbranch_vccz .LBB0_960
	s_barrier

; #define PG8_STAGE(bufoff, gbase, voff) do { _Pragma("unroll") for (int _i = 0; _i < 2; ++_i) \
;         __builtin_amdgcn_global_load_lds((const unsigned*)((const char*)(gbase) + (voff)[_i]), (PG8_LAS unsigned*)(lds + (bufoff) + ldsw + _i * 8192), 16, 0, 0); } while (0)
; #define PG8_LDA(dst, b, h) do { _Pragma("unroll") for (int m = 0; m < 4; ++m) _Pragma("unroll") for (int k = 0; k < 2; ++k) dst[m][k] = *(const PG8_LAS bf16x8*)(lds + PG8_SA(b, h) + aoff + m * 2048 + k * 1024); } while (0)
; #define PG8_LDB(dst, b, h) do { _Pragma("unroll") for (int n = 0; n < 2; ++n) _Pragma("unroll") for (int k = 0; k < 2; ++k) dst[n][k] = *(const PG8_LAS bf16x8*)(lds + PG8_SB(b, h) + boff + n * 2048 + k * 1024); } while (0)
; #define PG8_MMA(ai, bj, At, Bt) do { __builtin_amdgcn_s_setprio(1); _Pragma("unroll") for (int m = 0; m < 4; ++m) _Pragma("unroll") for (int n = 0; n < 2; ++n) _Pragma("unroll") for (int k = 0; k < 2; ++k) \
;         acc[ai][bj][m][n] = __builtin_amdgcn_mfma_f32_16x16x32_bf16(Bt[n][k], At[m][k], acc[ai][bj][m][n], 0, 0, 0); __builtin_amdgcn_s_setprio(0); } while (0)
; #define PG8_BAR __builtin_amdgcn_s_barrier()
; template <class Epi, class Sched, bool ALIGN_EPI = false, bool SP2 = false>
; __device__ __forceinline__ void gemm_phase(PG8_LAS unsigned char* lds, const Gemm g, const Sched& S, const Epi& E) {
;     ...
;         const bool has_next = S.next(ui + 1, nxt);
;         const char* nA = has_next ? (const char*)g.A + (size_t)nxt.pm * tstep : cA; const char* nB = has_next ? (const char*)g.Bt + (size_t)nxt.pn * tstep : cB;
;         for (int t = 0; t < nt; t += 2) {
;             const bool last = (t == nt - 2);
;             const char* a1 = cA + (size_t)(t + 1) * kstep;
;             const char* a2 = last ? nA : cA + (size_t)(t + 2) * kstep; const char* b2 = last ? nB : cB + (size_t)(t + 2) * kstep;
;             const char* a3 = a2 + kstep; const char* b3 = b2 + kstep;
;             if (last && has_next) S.a_ready(nxt);
;             if constexpr (SP2) {
;             PG8_LDB(B0, 0, 0); PG8_LDB(B1, 0, 1); PG8_SCHED; PG8_LDA(At, 0, 0); PG8_STAGE(PG8_SA(1, 1), a1 + hstep, voffA);
;             PG8_WAIT_V(8); PG8_WAIT_L(0); PG8_BAR; PG8_MMA(0, 0, At, B0); PG8_MMA(0, 1, At, B1); PG8_BAR; PG8_SCHED;
;             PG8_LDA(At, 0, 1); PG8_STAGE(PG8_SB(0, 0), b2, voffB); PG8_STAGE(PG8_SB(0, 1), b2 + hstep, voffB); PG8_STAGE(PG8_SA(0, 0), a2, voffA);
.LBB0_1034:
	s_add_u32 s75, s52, 0x100
	s_addc_u32 s76, s53, 0
	s_mov_b32 s77, -2
	s_waitcnt lgkmcnt(0)
	ds_read_b128 v[144:147], v151
	ds_read_b128 v[156:159], v151 offset:1024
	ds_read_b128 v[160:163], v151 offset:2048
	ds_read_b128 v[164:167], v151 offset:3072
	ds_read_b128 v[168:171], v152
	ds_read_b128 v[172:175], v152 offset:1024
	ds_read_b128 v[176:179], v152 offset:2048
	ds_read_b128 v[182:185], v152 offset:3072
	s_add_u32 s52, s50, 0x100
	s_addc_u32 s53, s51, 0
	s_cmp_eq_u32 s77, 40
	s_cselect_b32 s57, s1, s53
	s_cselect_b32 s56, s0, s52
	s_cselect_b32 s55, s49, s76
	s_cselect_b32 s54, s48, s75
	v_lshl_add_u64 v[202:203], s[50:51], 0, v[136:137]
	s_add_i32 m0, s14, 0xc000
	ds_read_b128 v[186:189], v153
	ds_read_b128 v[190:193], v153 offset:1024
	ds_read_b128 v[194:197], v153 offset:2048
	ds_read_b128 v[198:201], v153 offset:3072
	ds_read_b128 v[208:211], v153 offset:4096
	ds_read_b128 v[212:215], v153 offset:5120
	ds_read_b128 v[216:219], v153 offset:6144
	ds_read_b128 v[220:223], v153 offset:7168
	global_load_lds_dwordx4 v[202:203], off
	v_lshl_add_u64 v[202:203], s[50:51], 0, v[138:139]
	s_add_i32 m0, s14, 0xe000
	s_nop 0
	global_load_lds_dwordx4 v[202:203], off
	s_waitcnt vmcnt(8)
	s_waitcnt lgkmcnt(0)
	s_barrier
	s_setprio 1
	s_waitcnt lgkmcnt(0)
	v_mfma_f32_16x16x32_bf16 v[124:127], v[144:147], v[186:189], 0
	v_mfma_f32_16x16x32_bf16 v[120:123], v[160:163], v[186:189], 0
	v_mfma_f32_16x16x32_bf16 v[108:111], v[144:147], v[194:197], 0
	v_mfma_f32_16x16x32_bf16 v[104:107], v[160:163], v[194:197], 0
	v_mfma_f32_16x16x32_bf16 v[124:127], v[156:159], v[190:193], v[124:127]
	v_mfma_f32_16x16x32_bf16 v[120:123], v[164:167], v[190:193], v[120:123]
	v_mfma_f32_16x16x32_bf16 v[108:111], v[156:159], v[198:201], v[108:111]
	v_mfma_f32_16x16x32_bf16 v[104:107], v[164:167], v[198:201], v[104:107]
	v_mfma_f32_16x16x32_bf16 v[92:95], v[144:147], v[208:211], 0
	v_mfma_f32_16x16x32_bf16 v[88:91], v[160:163], v[208:211], 0
	v_mfma_f32_16x16x32_bf16 v[76:79], v[144:147], v[216:219], 0
	v_mfma_f32_16x16x32_bf16 v[72:75], v[160:163], v[216:219], 0
	v_mfma_f32_16x16x32_bf16 v[92:95], v[156:159], v[212:215], v[92:95]
	v_mfma_f32_16x16x32_bf16 v[88:91], v[164:167], v[212:215], v[88:91]
	v_mfma_f32_16x16x32_bf16 v[76:79], v[156:159], v[220:223], v[76:79]
	v_mfma_f32_16x16x32_bf16 v[72:75], v[164:167], v[220:223], v[72:75]
	s_setprio 0
	s_setprio 1
	v_mfma_f32_16x16x32_bf16 v[116:119], v[168:171], v[186:189], 0
	v_mfma_f32_16x16x32_bf16 v[112:115], v[176:179], v[186:189], 0
	v_mfma_f32_16x16x32_bf16 v[100:103], v[168:171], v[194:197], 0
	v_mfma_f32_16x16x32_bf16 v[96:99], v[176:179], v[194:197], 0
	v_mfma_f32_16x16x32_bf16 v[116:119], v[172:175], v[190:193], v[116:119]
	v_mfma_f32_16x16x32_bf16 v[112:115], v[182:185], v[190:193], v[112:115]
	v_mfma_f32_16x16x32_bf16 v[100:103], v[172:175], v[198:201], v[100:103]
	v_mfma_f32_16x16x32_bf16 v[96:99], v[182:185], v[198:201], v[96:99]
	v_mfma_f32_16x16x32_bf16 v[84:87], v[168:171], v[208:211], 0
	v_mfma_f32_16x16x32_bf16 v[80:83], v[176:179], v[208:211], 0
	v_mfma_f32_16x16x32_bf16 v[68:71], v[168:171], v[216:219], 0
	v_mfma_f32_16x16x32_bf16 v[64:67], v[176:179], v[216:219], 0
	v_mfma_f32_16x16x32_bf16 v[84:87], v[172:175], v[212:215], v[84:87]
	v_mfma_f32_16x16x32_bf16 v[80:83], v[182:185], v[212:215], v[80:83]
	v_mfma_f32_16x16x32_bf16 v[68:71], v[172:175], v[220:223], v[68:71]
	v_mfma_f32_16x16x32_bf16 v[64:67], v[182:185], v[220:223], v[64:67]
	s_setprio 0
	s_barrier
	s_add_i32 s50, s61, s3
	v_lshl_add_u64 v[202:203], s[54:55], 0, v[130:131]
	s_mov_b32 m0, s50
	ds_read_b128 v[186:189], v153 offset:16384
	ds_read_b128 v[190:193], v153 offset:17408
	ds_read_b128 v[194:197], v153 offset:18432
	ds_read_b128 v[198:201], v153 offset:19456
	ds_read_b128 v[208:211], v153 offset:20480
	ds_read_b128 v[212:215], v153 offset:21504
	ds_read_b128 v[216:219], v153 offset:22528
	ds_read_b128 v[220:223], v153 offset:23552
	global_load_lds_dwordx4 v[202:203], off
	s_add_i32 m0, s50, 0x2000
	s_add_u32 s50, s54, 0xb0000
	v_lshl_add_u64 v[224:225], s[54:55], 0, v[134:135]
	s_addc_u32 s51, s55, 0
	s_add_i32 s78, s62, s3
	global_load_lds_dwordx4 v[224:225], off
	v_lshl_add_u64 v[226:227], s[50:51], 0, v[130:131]
	s_mov_b32 m0, s78
	global_load_lds_dwordx4 v[226:227], off
	v_lshl_add_u64 v[226:227], s[50:51], 0, v[134:135]
	s_add_i32 m0, s78, 0x2000
	s_nop 0
	global_load_lds_dwordx4 v[226:227], off
	s_waitcnt vmcnt(6)
	s_waitcnt lgkmcnt(0)
	s_barrier
; #define PG8_STAGE(bufoff, gbase, voff) do { _Pragma("unroll") for (int _i = 0; _i < 2; ++_i) \
;         __builtin_amdgcn_global_load_lds((const unsigned*)((const char*)(gbase) + (voff)[_i]), (PG8_LAS unsigned*)(lds + (bufoff) + ldsw + _i * 8192), 16, 0, 0); } while (0)
; #define PG8_LDA(dst, b, h) do { _Pragma("unroll") for (int m = 0; m < 4; ++m) _Pragma("unroll") for (int k = 0; k < 2; ++k) dst[m][k] = *(const PG8_LAS bf16x8*)(lds + PG8_SA(b, h) + aoff + m * 2048 + k * 1024); } while (0)
; #define PG8_LDB(dst, b, h) do { _Pragma("unroll") for (int n = 0; n < 2; ++n) _Pragma("unroll") for (int k = 0; k < 2; ++k) dst[n][k] = *(const PG8_LAS bf16x8*)(lds + PG8_SB(b, h) + boff + n * 2048 + k * 1024); } while (0)
; #define PG8_MMA(ai, bj, At, Bt) do { __builtin_amdgcn_s_setprio(1); _Pragma("unroll") for (int m = 0; m < 4; ++m) _Pragma("unroll") for (int n = 0; n < 2; ++n) _Pragma("unroll") for (int k = 0; k < 2; ++k) \
;         acc[ai][bj][m][n] = __builtin_amdgcn_mfma_f32_16x16x32_bf16(Bt[n][k], At[m][k], acc[ai][bj][m][n], 0, 0, 0); __builtin_amdgcn_s_setprio(0); } while (0)
; #define PG8_WAIT_V(n) asm volatile("s_waitcnt vmcnt(" #n ")" ::: "memory")
; #define PG8_WAIT_L(n) asm volatile("s_waitcnt lgkmcnt(" #n ")" ::: "memory")
; #define PG8_BAR __builtin_amdgcn_s_barrier()
; #define PG8_SCHED __builtin_amdgcn_sched_barrier(0)
; template <class Epi, class Sched, bool ALIGN_EPI = false, bool SP2 = false>
; __device__ __forceinline__ void gemm_phase(PG8_LAS unsigned char* lds, const Gemm g, const Sched& S, const Epi& E) {
;     ...
;             PG8_WAIT_V(8); PG8_WAIT_L(0); PG8_BAR; PG8_MMA(1, 0, At, B0); PG8_MMA(1, 1, At, B1); PG8_BAR; PG8_SCHED;
;             PG8_LDB(B0, 1, 0); PG8_LDB(B1, 1, 1); PG8_SCHED; PG8_LDA(At, 1, 0); PG8_STAGE(PG8_SA(0, 1), a2 + hstep, voffA);
;             PG8_WAIT_V(8); PG8_WAIT_L(0); PG8_BAR; PG8_MMA(0, 0, At, B0); PG8_MMA(0, 1, At, B1); PG8_BAR; PG8_SCHED;
	s_setprio 1
	s_waitcnt lgkmcnt(0)
	v_mfma_f32_16x16x32_bf16 v[60:63], v[144:147], v[186:189], 0
	v_mfma_f32_16x16x32_bf16 v[56:59], v[160:163], v[186:189], 0
	v_mfma_f32_16x16x32_bf16 v[44:47], v[144:147], v[194:197], 0
	v_mfma_f32_16x16x32_bf16 v[40:43], v[160:163], v[194:197], 0
	v_mfma_f32_16x16x32_bf16 v[60:63], v[156:159], v[190:193], v[60:63]
	v_mfma_f32_16x16x32_bf16 v[56:59], v[164:167], v[190:193], v[56:59]
	v_mfma_f32_16x16x32_bf16 v[44:47], v[156:159], v[198:201], v[44:47]
	v_mfma_f32_16x16x32_bf16 v[40:43], v[164:167], v[198:201], v[40:43]
	v_mfma_f32_16x16x32_bf16 v[28:31], v[144:147], v[208:211], 0
	v_mfma_f32_16x16x32_bf16 v[24:27], v[160:163], v[208:211], 0
	v_mfma_f32_16x16x32_bf16 v[12:15], v[144:147], v[216:219], 0
	v_mfma_f32_16x16x32_bf16 v[8:11], v[160:163], v[216:219], 0
	v_mfma_f32_16x16x32_bf16 v[28:31], v[156:159], v[212:215], v[28:31]
	v_mfma_f32_16x16x32_bf16 v[24:27], v[164:167], v[212:215], v[24:27]
	v_lshl_add_u64 v[226:227], s[56:57], 0, v[128:129]
	s_mov_b32 m0, s14
	s_nop 0
	global_load_lds_dwordx4 v[226:227], off
	v_mfma_f32_16x16x32_bf16 v[12:15], v[156:159], v[220:223], v[12:15]
	v_mfma_f32_16x16x32_bf16 v[8:11], v[164:167], v[220:223], v[8:11]
	s_setprio 0
	s_setprio 1
	v_mfma_f32_16x16x32_bf16 v[52:55], v[168:171], v[186:189], 0
	v_mfma_f32_16x16x32_bf16 v[48:51], v[176:179], v[186:189], 0
	v_mfma_f32_16x16x32_bf16 v[36:39], v[168:171], v[194:197], 0
	v_mfma_f32_16x16x32_bf16 v[32:35], v[176:179], v[194:197], 0
	v_mfma_f32_16x16x32_bf16 v[52:55], v[172:175], v[190:193], v[52:55]
	v_mfma_f32_16x16x32_bf16 v[48:51], v[182:185], v[190:193], v[48:51]
	v_mfma_f32_16x16x32_bf16 v[36:39], v[172:175], v[198:201], v[36:39]
	v_mfma_f32_16x16x32_bf16 v[32:35], v[182:185], v[198:201], v[32:35]
	v_mfma_f32_16x16x32_bf16 v[20:23], v[168:171], v[208:211], 0
	v_mfma_f32_16x16x32_bf16 v[16:19], v[176:179], v[208:211], 0
	v_mfma_f32_16x16x32_bf16 v[4:7], v[168:171], v[216:219], 0
	v_mfma_f32_16x16x32_bf16 v[0:3], v[176:179], v[216:219], 0
	v_mfma_f32_16x16x32_bf16 v[20:23], v[172:175], v[212:215], v[20:23]
	v_mfma_f32_16x16x32_bf16 v[16:19], v[182:185], v[212:215], v[16:19]
	v_lshl_add_u64 v[228:229], s[56:57], 0, v[132:133]
	s_mov_b32 m0, s15
	s_nop 0
	global_load_lds_dwordx4 v[228:229], off
	v_mfma_f32_16x16x32_bf16 v[4:7], v[172:175], v[220:223], v[4:7]
	v_mfma_f32_16x16x32_bf16 v[0:3], v[182:185], v[220:223], v[0:3]
	s_setprio 0
	s_barrier
	s_add_i32 s78, 0, 0x18000
	v_add_u32_e32 v155, s78, v149
	s_add_i32 s79, 0, 0x1c000
	ds_read_b128 v[144:147], v155
	ds_read_b128 v[156:159], v155 offset:1024
	ds_read_b128 v[160:163], v155 offset:2048
	ds_read_b128 v[164:167], v155 offset:3072
	v_add_u32_e32 v155, s79, v149
	ds_read_b128 v[168:171], v155
	ds_read_b128 v[172:175], v155 offset:1024
	ds_read_b128 v[176:179], v155 offset:2048
	ds_read_b128 v[182:185], v155 offset:3072
	s_add_u32 s50, s56, 0xb0000
	s_addc_u32 s51, s57, 0
	s_mov_b32 m0, s33
	v_lshl_add_u64 v[230:231], s[50:51], 0, v[128:129]
	ds_read_b128 v[186:189], v153 offset:32768
	ds_read_b128 v[190:193], v153 offset:33792
	ds_read_b128 v[194:197], v153 offset:34816
	ds_read_b128 v[198:201], v153 offset:35840
	ds_read_b128 v[208:211], v153 offset:36864
	ds_read_b128 v[212:215], v153 offset:37888
	ds_read_b128 v[216:219], v153 offset:38912
	ds_read_b128 v[220:223], v153 offset:39936
	global_load_lds_dwordx4 v[230:231], off
	v_lshl_add_u64 v[230:231], s[50:51], 0, v[132:133]
	s_mov_b32 m0, s34
	s_nop 0
	global_load_lds_dwordx4 v[230:231], off
	s_waitcnt vmcnt(8)
	s_waitcnt lgkmcnt(0)
	s_barrier
	s_setprio 1
	s_waitcnt lgkmcnt(0)
	v_mfma_f32_16x16x32_bf16 v[124:127], v[144:147], v[186:189], v[124:127]
	v_mfma_f32_16x16x32_bf16 v[120:123], v[160:163], v[186:189], v[120:123]
	v_mfma_f32_16x16x32_bf16 v[108:111], v[144:147], v[194:197], v[108:111]
	v_mfma_f32_16x16x32_bf16 v[104:107], v[160:163], v[194:197], v[104:107]
	v_mfma_f32_16x16x32_bf16 v[124:127], v[156:159], v[190:193], v[124:127]
	v_mfma_f32_16x16x32_bf16 v[120:123], v[164:167], v[190:193], v[120:123]
	v_mfma_f32_16x16x32_bf16 v[108:111], v[156:159], v[198:201], v[108:111]
	v_mfma_f32_16x16x32_bf16 v[104:107], v[164:167], v[198:201], v[104:107]
	v_mfma_f32_16x16x32_bf16 v[92:95], v[144:147], v[208:211], v[92:95]
	v_mfma_f32_16x16x32_bf16 v[88:91], v[160:163], v[208:211], v[88:91]
	v_mfma_f32_16x16x32_bf16 v[76:79], v[144:147], v[216:219], v[76:79]
	v_mfma_f32_16x16x32_bf16 v[72:75], v[160:163], v[216:219], v[72:75]
	v_mfma_f32_16x16x32_bf16 v[92:95], v[156:159], v[212:215], v[92:95]
	v_mfma_f32_16x16x32_bf16 v[88:91], v[164:167], v[212:215], v[88:91]
	v_mfma_f32_16x16x32_bf16 v[76:79], v[156:159], v[220:223], v[76:79]
	v_mfma_f32_16x16x32_bf16 v[72:75], v[164:167], v[220:223], v[72:75]
	s_setprio 0
	s_setprio 1
	v_mfma_f32_16x16x32_bf16 v[116:119], v[168:171], v[186:189], v[116:119]
	v_mfma_f32_16x16x32_bf16 v[112:115], v[176:179], v[186:189], v[112:115]
	v_mfma_f32_16x16x32_bf16 v[100:103], v[168:171], v[194:197], v[100:103]
	v_mfma_f32_16x16x32_bf16 v[96:99], v[176:179], v[194:197], v[96:99]
	v_mfma_f32_16x16x32_bf16 v[116:119], v[172:175], v[190:193], v[116:119]
	v_mfma_f32_16x16x32_bf16 v[112:115], v[182:185], v[190:193], v[112:115]
	v_mfma_f32_16x16x32_bf16 v[100:103], v[172:175], v[198:201], v[100:103]
	v_mfma_f32_16x16x32_bf16 v[96:99], v[182:185], v[198:201], v[96:99]
	v_mfma_f32_16x16x32_bf16 v[84:87], v[168:171], v[208:211], v[84:87]
	v_mfma_f32_16x16x32_bf16 v[80:83], v[176:179], v[208:211], v[80:83]
	v_mfma_f32_16x16x32_bf16 v[68:71], v[168:171], v[216:219], v[68:71]
	v_mfma_f32_16x16x32_bf16 v[64:67], v[176:179], v[216:219], v[64:67]
	v_mfma_f32_16x16x32_bf16 v[84:87], v[172:175], v[212:215], v[84:87]
	v_mfma_f32_16x16x32_bf16 v[80:83], v[182:185], v[212:215], v[80:83]
	v_mfma_f32_16x16x32_bf16 v[68:71], v[172:175], v[220:223], v[68:71]
	v_mfma_f32_16x16x32_bf16 v[64:67], v[182:185], v[220:223], v[64:67]
	s_setprio 0
	s_barrier
; #define PG8_STAGE(bufoff, gbase, voff) do { _Pragma("unroll") for (int _i = 0; _i < 2; ++_i) \
;         __builtin_amdgcn_global_load_lds((const unsigned*)((const char*)(gbase) + (voff)[_i]), (PG8_LAS unsigned*)(lds + (bufoff) + ldsw + _i * 8192), 16, 0, 0); } while (0)
; #define PG8_LDA(dst, b, h) do { _Pragma("unroll") for (int m = 0; m < 4; ++m) _Pragma("unroll") for (int k = 0; k < 2; ++k) dst[m][k] = *(const PG8_LAS bf16x8*)(lds + PG8_SA(b, h) + aoff + m * 2048 + k * 1024); } while (0)
; #define PG8_LDB(dst, b, h) do { _Pragma("unroll") for (int n = 0; n < 2; ++n) _Pragma("unroll") for (int k = 0; k < 2; ++k) dst[n][k] = *(const PG8_LAS bf16x8*)(lds + PG8_SB(b, h) + boff + n * 2048 + k * 1024); } while (0)
; #define PG8_MMA(ai, bj, At, Bt) do { __builtin_amdgcn_s_setprio(1); _Pragma("unroll") for (int m = 0; m < 4; ++m) _Pragma("unroll") for (int n = 0; n < 2; ++n) _Pragma("unroll") for (int k = 0; k < 2; ++k) \
;         acc[ai][bj][m][n] = __builtin_amdgcn_mfma_f32_16x16x32_bf16(Bt[n][k], At[m][k], acc[ai][bj][m][n], 0, 0, 0); __builtin_amdgcn_s_setprio(0); } while (0)
; #define PG8_WAIT_V(n) asm volatile("s_waitcnt vmcnt(" #n ")" ::: "memory")
; #define PG8_WAIT_L(n) asm volatile("s_waitcnt lgkmcnt(" #n ")" ::: "memory")
; #define PG8_BAR __builtin_amdgcn_s_barrier()
; #define PG8_SCHED __builtin_amdgcn_sched_barrier(0)
; template <class Epi, class Sched, bool ALIGN_EPI = false, bool SP2 = false>
; __device__ __forceinline__ void gemm_phase(PG8_LAS unsigned char* lds, const Gemm g, const Sched& S, const Epi& E) {
;     ...
;             PG8_LDA(At, 1, 1); PG8_STAGE(PG8_SB(1, 0), b3, voffB); PG8_STAGE(PG8_SB(1, 1), b3 + hstep, voffB); PG8_STAGE(PG8_SA(1, 0), a3, voffA);
;             PG8_WAIT_V(8); PG8_WAIT_L(0); PG8_BAR; PG8_MMA(1, 0, At, B0); PG8_MMA(1, 1, At, B1); PG8_BAR; PG8_SCHED;
;             } else {
;             PG8_LDB(B0, 0, 0); PG8_SCHED; PG8_LDA(At, 0, 0); PG8_STAGE(PG8_SA(1, 1), a1 + hstep, voffA);
	s_add_i32 s50, s78, s3
	v_lshl_add_u64 v[202:203], v[202:203], 0, s[42:43]
	s_mov_b32 m0, s50
	ds_read_b128 v[186:189], v153 offset:49152
	ds_read_b128 v[190:193], v153 offset:50176
	ds_read_b128 v[194:197], v153 offset:51200
	ds_read_b128 v[198:201], v153 offset:52224
	ds_read_b128 v[208:211], v153 offset:53248
	ds_read_b128 v[212:215], v153 offset:54272
	ds_read_b128 v[216:219], v153 offset:55296
	ds_read_b128 v[220:223], v153 offset:56320
	global_load_lds_dwordx4 v[202:203], off
	s_add_i32 m0, s50, 0x2000
	s_add_u32 s50, s54, 0xb0080
	v_lshl_add_u64 v[202:203], v[224:225], 0, s[42:43]
	s_addc_u32 s51, s55, 0
	s_add_i32 s54, s79, s3
	global_load_lds_dwordx4 v[202:203], off
	v_lshl_add_u64 v[202:203], s[50:51], 0, v[130:131]
	s_mov_b32 m0, s54
	s_nop 0
	global_load_lds_dwordx4 v[202:203], off
	v_lshl_add_u64 v[202:203], s[50:51], 0, v[134:135]
	s_add_i32 m0, s54, 0x2000
	s_nop 0
	global_load_lds_dwordx4 v[202:203], off
	s_waitcnt vmcnt(6)
	s_waitcnt lgkmcnt(0)
	s_barrier
	s_setprio 1
	s_waitcnt lgkmcnt(0)
	v_mfma_f32_16x16x32_bf16 v[60:63], v[144:147], v[186:189], v[60:63]
	v_mfma_f32_16x16x32_bf16 v[56:59], v[160:163], v[186:189], v[56:59]
	v_mfma_f32_16x16x32_bf16 v[44:47], v[144:147], v[194:197], v[44:47]
	v_mfma_f32_16x16x32_bf16 v[40:43], v[160:163], v[194:197], v[40:43]
	v_mfma_f32_16x16x32_bf16 v[60:63], v[156:159], v[190:193], v[60:63]
	v_mfma_f32_16x16x32_bf16 v[56:59], v[164:167], v[190:193], v[56:59]
	v_mfma_f32_16x16x32_bf16 v[44:47], v[156:159], v[198:201], v[44:47]
	v_mfma_f32_16x16x32_bf16 v[40:43], v[164:167], v[198:201], v[40:43]
	v_mfma_f32_16x16x32_bf16 v[28:31], v[144:147], v[208:211], v[28:31]
	v_mfma_f32_16x16x32_bf16 v[24:27], v[160:163], v[208:211], v[24:27]
	v_mfma_f32_16x16x32_bf16 v[12:15], v[144:147], v[216:219], v[12:15]
	v_mfma_f32_16x16x32_bf16 v[8:11], v[160:163], v[216:219], v[8:11]
	v_mfma_f32_16x16x32_bf16 v[28:31], v[156:159], v[212:215], v[28:31]
	v_mfma_f32_16x16x32_bf16 v[24:27], v[164:167], v[212:215], v[24:27]
	v_lshl_add_u64 v[202:203], v[226:227], 0, s[42:43]
	s_mov_b32 m0, s59
	s_nop 0
	global_load_lds_dwordx4 v[202:203], off
	v_mfma_f32_16x16x32_bf16 v[12:15], v[156:159], v[220:223], v[12:15]
	v_mfma_f32_16x16x32_bf16 v[8:11], v[164:167], v[220:223], v[8:11]
	s_setprio 0
	s_setprio 1
	v_mfma_f32_16x16x32_bf16 v[52:55], v[168:171], v[186:189], v[52:55]
	v_mfma_f32_16x16x32_bf16 v[48:51], v[176:179], v[186:189], v[48:51]
	v_mfma_f32_16x16x32_bf16 v[36:39], v[168:171], v[194:197], v[36:39]
	v_mfma_f32_16x16x32_bf16 v[32:35], v[176:179], v[194:197], v[32:35]
	v_mfma_f32_16x16x32_bf16 v[52:55], v[172:175], v[190:193], v[52:55]
	v_mfma_f32_16x16x32_bf16 v[48:51], v[182:185], v[190:193], v[48:51]
	v_mfma_f32_16x16x32_bf16 v[36:39], v[172:175], v[198:201], v[36:39]
	v_mfma_f32_16x16x32_bf16 v[32:35], v[182:185], v[198:201], v[32:35]
	v_mfma_f32_16x16x32_bf16 v[20:23], v[168:171], v[208:211], v[20:23]
	v_mfma_f32_16x16x32_bf16 v[16:19], v[176:179], v[208:211], v[16:19]
	v_mfma_f32_16x16x32_bf16 v[4:7], v[168:171], v[216:219], v[4:7]
	v_mfma_f32_16x16x32_bf16 v[0:3], v[176:179], v[216:219], v[0:3]
	v_mfma_f32_16x16x32_bf16 v[20:23], v[172:175], v[212:215], v[20:23]
	v_mfma_f32_16x16x32_bf16 v[16:19], v[182:185], v[212:215], v[16:19]
	v_lshl_add_u64 v[202:203], v[228:229], 0, s[42:43]
	s_mov_b32 m0, s60
	s_nop 0
	global_load_lds_dwordx4 v[202:203], off
	v_mfma_f32_16x16x32_bf16 v[4:7], v[172:175], v[220:223], v[4:7]
	v_mfma_f32_16x16x32_bf16 v[0:3], v[182:185], v[220:223], v[0:3]
	s_setprio 0
	s_barrier
	s_add_i32 s77, s77, 2
	s_add_u32 s75, s75, 0x100
	s_addc_u32 s76, s76, 0
	s_mov_b64 s[50:51], s[52:53]
.LBB0_1035:
	ds_read_b128 v[144:147], v151
	ds_read_b128 v[156:159], v151 offset:1024
	ds_read_b128 v[160:163], v151 offset:2048
	ds_read_b128 v[164:167], v151 offset:3072
	ds_read_b128 v[168:171], v152
	ds_read_b128 v[172:175], v152 offset:1024
	ds_read_b128 v[176:179], v152 offset:2048
	ds_read_b128 v[182:185], v152 offset:3072
	s_add_u32 s52, s50, 0x100
	s_addc_u32 s53, s51, 0
	s_cmp_eq_u32 s77, 40
	s_cselect_b32 s57, s1, s53
	s_cselect_b32 s56, s0, s52
	s_cselect_b32 s55, s49, s76
	s_cselect_b32 s54, s48, s75
	v_lshl_add_u64 v[202:203], s[50:51], 0, v[136:137]
	s_add_i32 m0, s14, 0xc000
	ds_read_b128 v[186:189], v153
	ds_read_b128 v[190:193], v153 offset:1024
	ds_read_b128 v[194:197], v153 offset:2048
	ds_read_b128 v[198:201], v153 offset:3072
	ds_read_b128 v[208:211], v153 offset:4096
	ds_read_b128 v[212:215], v153 offset:5120
	ds_read_b128 v[216:219], v153 offset:6144
	ds_read_b128 v[220:223], v153 offset:7168
	global_load_lds_dwordx4 v[202:203], off
	v_lshl_add_u64 v[202:203], s[50:51], 0, v[138:139]
	s_add_i32 m0, s14, 0xe000
	s_nop 0
	global_load_lds_dwordx4 v[202:203], off
	s_waitcnt vmcnt(8)
	s_waitcnt lgkmcnt(0)
	s_barrier
; #define PG8_STAGE(bufoff, gbase, voff) do { _Pragma("unroll") for (int _i = 0; _i < 2; ++_i) \
;         __builtin_amdgcn_global_load_lds((const unsigned*)((const char*)(gbase) + (voff)[_i]), (PG8_LAS unsigned*)(lds + (bufoff) + ldsw + _i * 8192), 16, 0, 0); } while (0)
; #define PG8_LDA(dst, b, h) do { _Pragma("unroll") for (int m = 0; m < 4; ++m) _Pragma("unroll") for (int k = 0; k < 2; ++k) dst[m][k] = *(const PG8_LAS bf16x8*)(lds + PG8_SA(b, h) + aoff + m * 2048 + k * 1024); } while (0)
; #define PG8_LDB(dst, b, h) do { _Pragma("unroll") for (int n = 0; n < 2; ++n) _Pragma("unroll") for (int k = 0; k < 2; ++k) dst[n][k] = *(const PG8_LAS bf16x8*)(lds + PG8_SB(b, h) + boff + n * 2048 + k * 1024); } while (0)
; #define PG8_MMA(ai, bj, At, Bt) do { __builtin_amdgcn_s_setprio(1); _Pragma("unroll") for (int m = 0; m < 4; ++m) _Pragma("unroll") for (int n = 0; n < 2; ++n) _Pragma("unroll") for (int k = 0; k < 2; ++k) \
;         acc[ai][bj][m][n] = __builtin_amdgcn_mfma_f32_16x16x32_bf16(Bt[n][k], At[m][k], acc[ai][bj][m][n], 0, 0, 0); __builtin_amdgcn_s_setprio(0); } while (0)
; #define PG8_WAIT_V(n) asm volatile("s_waitcnt vmcnt(" #n ")" ::: "memory")
; #define PG8_WAIT_L(n) asm volatile("s_waitcnt lgkmcnt(" #n ")" ::: "memory")
; #define PG8_BAR __builtin_amdgcn_s_barrier()
; #define PG8_SCHED __builtin_amdgcn_sched_barrier(0)
; template <class Epi, class Sched, bool ALIGN_EPI = false, bool SP2 = false>
; __device__ __forceinline__ void gemm_phase(PG8_LAS unsigned char* lds, const Gemm g, const Sched& S, const Epi& E) {
;     ...
;             PG8_LDB(B0, 0, 0); PG8_LDB(B1, 0, 1); PG8_SCHED; PG8_LDA(At, 0, 0); PG8_STAGE(PG8_SA(1, 1), a1 + hstep, voffA);
;             PG8_WAIT_V(8); PG8_WAIT_L(0); PG8_BAR; PG8_MMA(0, 0, At, B0); PG8_MMA(0, 1, At, B1); PG8_BAR; PG8_SCHED;
;             PG8_LDA(At, 0, 1); PG8_STAGE(PG8_SB(0, 0), b2, voffB); PG8_STAGE(PG8_SB(0, 1), b2 + hstep, voffB); PG8_STAGE(PG8_SA(0, 0), a2, voffA);
;             PG8_WAIT_V(8); PG8_WAIT_L(0); PG8_BAR; PG8_MMA(1, 0, At, B0); PG8_MMA(1, 1, At, B1); PG8_BAR; PG8_SCHED;
	s_setprio 1
	s_waitcnt lgkmcnt(0)
	v_mfma_f32_16x16x32_bf16 v[124:127], v[144:147], v[186:189], v[124:127]
	v_mfma_f32_16x16x32_bf16 v[120:123], v[160:163], v[186:189], v[120:123]
	v_mfma_f32_16x16x32_bf16 v[108:111], v[144:147], v[194:197], v[108:111]
	v_mfma_f32_16x16x32_bf16 v[104:107], v[160:163], v[194:197], v[104:107]
	v_mfma_f32_16x16x32_bf16 v[124:127], v[156:159], v[190:193], v[124:127]
	v_mfma_f32_16x16x32_bf16 v[120:123], v[164:167], v[190:193], v[120:123]
	v_mfma_f32_16x16x32_bf16 v[108:111], v[156:159], v[198:201], v[108:111]
	v_mfma_f32_16x16x32_bf16 v[104:107], v[164:167], v[198:201], v[104:107]
	v_mfma_f32_16x16x32_bf16 v[92:95], v[144:147], v[208:211], v[92:95]
	v_mfma_f32_16x16x32_bf16 v[88:91], v[160:163], v[208:211], v[88:91]
	v_mfma_f32_16x16x32_bf16 v[76:79], v[144:147], v[216:219], v[76:79]
	v_mfma_f32_16x16x32_bf16 v[72:75], v[160:163], v[216:219], v[72:75]
	v_mfma_f32_16x16x32_bf16 v[92:95], v[156:159], v[212:215], v[92:95]
	v_mfma_f32_16x16x32_bf16 v[88:91], v[164:167], v[212:215], v[88:91]
	v_mfma_f32_16x16x32_bf16 v[76:79], v[156:159], v[220:223], v[76:79]
	v_mfma_f32_16x16x32_bf16 v[72:75], v[164:167], v[220:223], v[72:75]
	s_setprio 0
	s_setprio 1
	v_mfma_f32_16x16x32_bf16 v[116:119], v[168:171], v[186:189], v[116:119]
	v_mfma_f32_16x16x32_bf16 v[112:115], v[176:179], v[186:189], v[112:115]
	v_mfma_f32_16x16x32_bf16 v[100:103], v[168:171], v[194:197], v[100:103]
	v_mfma_f32_16x16x32_bf16 v[96:99], v[176:179], v[194:197], v[96:99]
	v_mfma_f32_16x16x32_bf16 v[116:119], v[172:175], v[190:193], v[116:119]
	v_mfma_f32_16x16x32_bf16 v[112:115], v[182:185], v[190:193], v[112:115]
	v_mfma_f32_16x16x32_bf16 v[100:103], v[172:175], v[198:201], v[100:103]
	v_mfma_f32_16x16x32_bf16 v[96:99], v[182:185], v[198:201], v[96:99]
	v_mfma_f32_16x16x32_bf16 v[84:87], v[168:171], v[208:211], v[84:87]
	v_mfma_f32_16x16x32_bf16 v[80:83], v[176:179], v[208:211], v[80:83]
	v_mfma_f32_16x16x32_bf16 v[68:71], v[168:171], v[216:219], v[68:71]
	v_mfma_f32_16x16x32_bf16 v[64:67], v[176:179], v[216:219], v[64:67]
	v_mfma_f32_16x16x32_bf16 v[84:87], v[172:175], v[212:215], v[84:87]
	v_mfma_f32_16x16x32_bf16 v[80:83], v[182:185], v[212:215], v[80:83]
	v_mfma_f32_16x16x32_bf16 v[68:71], v[172:175], v[220:223], v[68:71]
	v_mfma_f32_16x16x32_bf16 v[64:67], v[182:185], v[220:223], v[64:67]
	s_setprio 0
	s_barrier
	s_add_i32 s50, s61, s3
	v_lshl_add_u64 v[202:203], s[54:55], 0, v[130:131]
	s_mov_b32 m0, s50
	ds_read_b128 v[186:189], v153 offset:16384
	ds_read_b128 v[190:193], v153 offset:17408
	ds_read_b128 v[194:197], v153 offset:18432
	ds_read_b128 v[198:201], v153 offset:19456
	ds_read_b128 v[208:211], v153 offset:20480
	ds_read_b128 v[212:215], v153 offset:21504
	ds_read_b128 v[216:219], v153 offset:22528
	ds_read_b128 v[220:223], v153 offset:23552
	global_load_lds_dwordx4 v[202:203], off
	s_add_i32 m0, s50, 0x2000
	s_add_u32 s50, s54, 0xb0000
	v_lshl_add_u64 v[224:225], s[54:55], 0, v[134:135]
	s_addc_u32 s51, s55, 0
	s_add_i32 s78, s62, s3
	global_load_lds_dwordx4 v[224:225], off
	v_lshl_add_u64 v[226:227], s[50:51], 0, v[130:131]
	s_mov_b32 m0, s78
	global_load_lds_dwordx4 v[226:227], off
	v_lshl_add_u64 v[226:227], s[50:51], 0, v[134:135]
	s_add_i32 m0, s78, 0x2000
	s_nop 0
	global_load_lds_dwordx4 v[226:227], off
	s_waitcnt vmcnt(6)
	s_waitcnt lgkmcnt(0)
	s_barrier
	s_setprio 1
	s_waitcnt lgkmcnt(0)
	v_mfma_f32_16x16x32_bf16 v[60:63], v[144:147], v[186:189], v[60:63]
	v_mfma_f32_16x16x32_bf16 v[56:59], v[160:163], v[186:189], v[56:59]
	v_mfma_f32_16x16x32_bf16 v[44:47], v[144:147], v[194:197], v[44:47]
	v_mfma_f32_16x16x32_bf16 v[40:43], v[160:163], v[194:197], v[40:43]
	v_mfma_f32_16x16x32_bf16 v[60:63], v[156:159], v[190:193], v[60:63]
	v_mfma_f32_16x16x32_bf16 v[56:59], v[164:167], v[190:193], v[56:59]
	v_mfma_f32_16x16x32_bf16 v[44:47], v[156:159], v[198:201], v[44:47]
	v_mfma_f32_16x16x32_bf16 v[40:43], v[164:167], v[198:201], v[40:43]
	v_mfma_f32_16x16x32_bf16 v[28:31], v[144:147], v[208:211], v[28:31]
	v_mfma_f32_16x16x32_bf16 v[24:27], v[160:163], v[208:211], v[24:27]
	v_mfma_f32_16x16x32_bf16 v[12:15], v[144:147], v[216:219], v[12:15]
	v_mfma_f32_16x16x32_bf16 v[8:11], v[160:163], v[216:219], v[8:11]
	v_mfma_f32_16x16x32_bf16 v[28:31], v[156:159], v[212:215], v[28:31]
	v_mfma_f32_16x16x32_bf16 v[24:27], v[164:167], v[212:215], v[24:27]
	v_lshl_add_u64 v[226:227], s[56:57], 0, v[128:129]
	s_mov_b32 m0, s14
	s_nop 0
	global_load_lds_dwordx4 v[226:227], off
	v_mfma_f32_16x16x32_bf16 v[12:15], v[156:159], v[220:223], v[12:15]
	v_mfma_f32_16x16x32_bf16 v[8:11], v[164:167], v[220:223], v[8:11]
	s_setprio 0
	s_setprio 1
	v_mfma_f32_16x16x32_bf16 v[52:55], v[168:171], v[186:189], v[52:55]
	v_mfma_f32_16x16x32_bf16 v[48:51], v[176:179], v[186:189], v[48:51]
	v_mfma_f32_16x16x32_bf16 v[36:39], v[168:171], v[194:197], v[36:39]
	v_mfma_f32_16x16x32_bf16 v[32:35], v[176:179], v[194:197], v[32:35]
	v_mfma_f32_16x16x32_bf16 v[52:55], v[172:175], v[190:193], v[52:55]
	v_mfma_f32_16x16x32_bf16 v[48:51], v[182:185], v[190:193], v[48:51]
	v_mfma_f32_16x16x32_bf16 v[36:39], v[172:175], v[198:201], v[36:39]
	v_mfma_f32_16x16x32_bf16 v[32:35], v[182:185], v[198:201], v[32:35]
	v_mfma_f32_16x16x32_bf16 v[20:23], v[168:171], v[208:211], v[20:23]
	v_mfma_f32_16x16x32_bf16 v[16:19], v[176:179], v[208:211], v[16:19]
	v_mfma_f32_16x16x32_bf16 v[4:7], v[168:171], v[216:219], v[4:7]
	v_mfma_f32_16x16x32_bf16 v[0:3], v[176:179], v[216:219], v[0:3]
	v_mfma_f32_16x16x32_bf16 v[20:23], v[172:175], v[212:215], v[20:23]
	v_mfma_f32_16x16x32_bf16 v[16:19], v[182:185], v[212:215], v[16:19]
	v_lshl_add_u64 v[228:229], s[56:57], 0, v[132:133]
	s_mov_b32 m0, s15
	s_nop 0
	global_load_lds_dwordx4 v[228:229], off
	v_mfma_f32_16x16x32_bf16 v[4:7], v[172:175], v[220:223], v[4:7]
	v_mfma_f32_16x16x32_bf16 v[0:3], v[182:185], v[220:223], v[0:3]
	s_setprio 0
	s_barrier
; #define PG8_STAGE(bufoff, gbase, voff) do { _Pragma("unroll") for (int _i = 0; _i < 2; ++_i) \
;         __builtin_amdgcn_global_load_lds((const unsigned*)((const char*)(gbase) + (voff)[_i]), (PG8_LAS unsigned*)(lds + (bufoff) + ldsw + _i * 8192), 16, 0, 0); } while (0)
; #define PG8_LDA(dst, b, h) do { _Pragma("unroll") for (int m = 0; m < 4; ++m) _Pragma("unroll") for (int k = 0; k < 2; ++k) dst[m][k] = *(const PG8_LAS bf16x8*)(lds + PG8_SA(b, h) + aoff + m * 2048 + k * 1024); } while (0)
; #define PG8_LDB(dst, b, h) do { _Pragma("unroll") for (int n = 0; n < 2; ++n) _Pragma("unroll") for (int k = 0; k < 2; ++k) dst[n][k] = *(const PG8_LAS bf16x8*)(lds + PG8_SB(b, h) + boff + n * 2048 + k * 1024); } while (0)
; #define PG8_MMA(ai, bj, At, Bt) do { __builtin_amdgcn_s_setprio(1); _Pragma("unroll") for (int m = 0; m < 4; ++m) _Pragma("unroll") for (int n = 0; n < 2; ++n) _Pragma("unroll") for (int k = 0; k < 2; ++k) \
;         acc[ai][bj][m][n] = __builtin_amdgcn_mfma_f32_16x16x32_bf16(Bt[n][k], At[m][k], acc[ai][bj][m][n], 0, 0, 0); __builtin_amdgcn_s_setprio(0); } while (0)
; #define PG8_WAIT_V(n) asm volatile("s_waitcnt vmcnt(" #n ")" ::: "memory")
; #define PG8_WAIT_L(n) asm volatile("s_waitcnt lgkmcnt(" #n ")" ::: "memory")
; #define PG8_BAR __builtin_amdgcn_s_barrier()
; #define PG8_SCHED __builtin_amdgcn_sched_barrier(0)
; template <class Epi, class Sched, bool ALIGN_EPI = false, bool SP2 = false>
; __device__ __forceinline__ void gemm_phase(PG8_LAS unsigned char* lds, const Gemm g, const Sched& S, const Epi& E) {
;     ...
;             PG8_LDB(B0, 1, 0); PG8_LDB(B1, 1, 1); PG8_SCHED; PG8_LDA(At, 1, 0); PG8_STAGE(PG8_SA(0, 1), a2 + hstep, voffA);
;             PG8_WAIT_V(8); PG8_WAIT_L(0); PG8_BAR; PG8_MMA(0, 0, At, B0); PG8_MMA(0, 1, At, B1); PG8_BAR; PG8_SCHED;
	s_add_i32 s78, 0, 0x18000
	v_add_u32_e32 v155, s78, v149
	s_add_i32 s79, 0, 0x1c000
	ds_read_b128 v[144:147], v155
	ds_read_b128 v[156:159], v155 offset:1024
	ds_read_b128 v[160:163], v155 offset:2048
	ds_read_b128 v[164:167], v155 offset:3072
	v_add_u32_e32 v155, s79, v149
	ds_read_b128 v[168:171], v155
	ds_read_b128 v[172:175], v155 offset:1024
	ds_read_b128 v[176:179], v155 offset:2048
	ds_read_b128 v[182:185], v155 offset:3072
	s_add_u32 s50, s56, 0xb0000
	s_addc_u32 s51, s57, 0
	s_mov_b32 m0, s33
	v_lshl_add_u64 v[230:231], s[50:51], 0, v[128:129]
	ds_read_b128 v[186:189], v153 offset:32768
	ds_read_b128 v[190:193], v153 offset:33792
	ds_read_b128 v[194:197], v153 offset:34816
	ds_read_b128 v[198:201], v153 offset:35840
	ds_read_b128 v[208:211], v153 offset:36864
	ds_read_b128 v[212:215], v153 offset:37888
	ds_read_b128 v[216:219], v153 offset:38912
	ds_read_b128 v[220:223], v153 offset:39936
	global_load_lds_dwordx4 v[230:231], off
	v_lshl_add_u64 v[230:231], s[50:51], 0, v[132:133]
	s_mov_b32 m0, s34
	s_nop 0
	global_load_lds_dwordx4 v[230:231], off
	s_waitcnt vmcnt(8)
	s_waitcnt lgkmcnt(0)
	s_barrier
	s_setprio 1
	s_waitcnt lgkmcnt(0)
	v_mfma_f32_16x16x32_bf16 v[124:127], v[144:147], v[186:189], v[124:127]
	v_mfma_f32_16x16x32_bf16 v[120:123], v[160:163], v[186:189], v[120:123]
	v_mfma_f32_16x16x32_bf16 v[108:111], v[144:147], v[194:197], v[108:111]
	v_mfma_f32_16x16x32_bf16 v[104:107], v[160:163], v[194:197], v[104:107]
	v_mfma_f32_16x16x32_bf16 v[124:127], v[156:159], v[190:193], v[124:127]
	v_mfma_f32_16x16x32_bf16 v[120:123], v[164:167], v[190:193], v[120:123]
	v_mfma_f32_16x16x32_bf16 v[108:111], v[156:159], v[198:201], v[108:111]
	v_mfma_f32_16x16x32_bf16 v[104:107], v[164:167], v[198:201], v[104:107]
	v_mfma_f32_16x16x32_bf16 v[92:95], v[144:147], v[208:211], v[92:95]
	v_mfma_f32_16x16x32_bf16 v[88:91], v[160:163], v[208:211], v[88:91]
	v_mfma_f32_16x16x32_bf16 v[76:79], v[144:147], v[216:219], v[76:79]
	v_mfma_f32_16x16x32_bf16 v[72:75], v[160:163], v[216:219], v[72:75]
	v_mfma_f32_16x16x32_bf16 v[92:95], v[156:159], v[212:215], v[92:95]
	v_mfma_f32_16x16x32_bf16 v[88:91], v[164:167], v[212:215], v[88:91]
	v_mfma_f32_16x16x32_bf16 v[76:79], v[156:159], v[220:223], v[76:79]
	v_mfma_f32_16x16x32_bf16 v[72:75], v[164:167], v[220:223], v[72:75]
	s_setprio 0
	s_setprio 1
	v_mfma_f32_16x16x32_bf16 v[116:119], v[168:171], v[186:189], v[116:119]
	v_mfma_f32_16x16x32_bf16 v[112:115], v[176:179], v[186:189], v[112:115]
	v_mfma_f32_16x16x32_bf16 v[100:103], v[168:171], v[194:197], v[100:103]
	v_mfma_f32_16x16x32_bf16 v[96:99], v[176:179], v[194:197], v[96:99]
	v_mfma_f32_16x16x32_bf16 v[116:119], v[172:175], v[190:193], v[116:119]
	v_mfma_f32_16x16x32_bf16 v[112:115], v[182:185], v[190:193], v[112:115]
	v_mfma_f32_16x16x32_bf16 v[100:103], v[172:175], v[198:201], v[100:103]
	v_mfma_f32_16x16x32_bf16 v[96:99], v[182:185], v[198:201], v[96:99]
	v_mfma_f32_16x16x32_bf16 v[84:87], v[168:171], v[208:211], v[84:87]
	v_mfma_f32_16x16x32_bf16 v[80:83], v[176:179], v[208:211], v[80:83]
	v_mfma_f32_16x16x32_bf16 v[68:71], v[168:171], v[216:219], v[68:71]
	v_mfma_f32_16x16x32_bf16 v[64:67], v[176:179], v[216:219], v[64:67]
	v_mfma_f32_16x16x32_bf16 v[84:87], v[172:175], v[212:215], v[84:87]
	v_mfma_f32_16x16x32_bf16 v[80:83], v[182:185], v[212:215], v[80:83]
	v_mfma_f32_16x16x32_bf16 v[68:71], v[172:175], v[220:223], v[68:71]
	v_mfma_f32_16x16x32_bf16 v[64:67], v[182:185], v[220:223], v[64:67]
	s_setprio 0
	s_barrier
; #define PG8_STAGE(bufoff, gbase, voff) do { _Pragma("unroll") for (int _i = 0; _i < 2; ++_i) \
;         __builtin_amdgcn_global_load_lds((const unsigned*)((const char*)(gbase) + (voff)[_i]), (PG8_LAS unsigned*)(lds + (bufoff) + ldsw + _i * 8192), 16, 0, 0); } while (0)
; #define PG8_LDA(dst, b, h) do { _Pragma("unroll") for (int m = 0; m < 4; ++m) _Pragma("unroll") for (int k = 0; k < 2; ++k) dst[m][k] = *(const PG8_LAS bf16x8*)(lds + PG8_SA(b, h) + aoff + m * 2048 + k * 1024); } while (0)
; #define PG8_MMA(ai, bj, At, Bt) do { __builtin_amdgcn_s_setprio(1); _Pragma("unroll") for (int m = 0; m < 4; ++m) _Pragma("unroll") for (int n = 0; n < 2; ++n) _Pragma("unroll") for (int k = 0; k < 2; ++k) \
;         acc[ai][bj][m][n] = __builtin_amdgcn_mfma_f32_16x16x32_bf16(Bt[n][k], At[m][k], acc[ai][bj][m][n], 0, 0, 0); __builtin_amdgcn_s_setprio(0); } while (0)
; #define PG8_WAIT_V(n) asm volatile("s_waitcnt vmcnt(" #n ")" ::: "memory")
; #define PG8_WAIT_L(n) asm volatile("s_waitcnt lgkmcnt(" #n ")" ::: "memory")
; #define PG8_BAR __builtin_amdgcn_s_barrier()
; #define PG8_SCHED __builtin_amdgcn_sched_barrier(0)
; template <class Epi, class Sched, bool ALIGN_EPI = false, bool SP2 = false>
; __device__ __forceinline__ void gemm_phase(PG8_LAS unsigned char* lds, const Gemm g, const Sched& S, const Epi& E) {
;     ...
;         for (int t = 0; t < nt; t += 2) {
;     ...
;             PG8_LDA(At, 1, 1); PG8_STAGE(PG8_SB(1, 0), b3, voffB); PG8_STAGE(PG8_SB(1, 1), b3 + hstep, voffB); PG8_STAGE(PG8_SA(1, 0), a3, voffA);
;             PG8_WAIT_V(8); PG8_WAIT_L(0); PG8_BAR; PG8_MMA(1, 0, At, B0); PG8_MMA(1, 1, At, B1); PG8_BAR; PG8_SCHED;
	s_add_i32 s50, s78, s3
	v_lshl_add_u64 v[202:203], v[202:203], 0, s[42:43]
	s_mov_b32 m0, s50
	ds_read_b128 v[186:189], v153 offset:49152
	ds_read_b128 v[190:193], v153 offset:50176
	ds_read_b128 v[194:197], v153 offset:51200
	ds_read_b128 v[198:201], v153 offset:52224
	ds_read_b128 v[208:211], v153 offset:53248
	ds_read_b128 v[212:215], v153 offset:54272
	ds_read_b128 v[216:219], v153 offset:55296
	ds_read_b128 v[220:223], v153 offset:56320
	global_load_lds_dwordx4 v[202:203], off
	s_add_i32 m0, s50, 0x2000
	s_add_u32 s50, s54, 0xb0080
	v_lshl_add_u64 v[202:203], v[224:225], 0, s[42:43]
	s_addc_u32 s51, s55, 0
	s_add_i32 s54, s79, s3
	global_load_lds_dwordx4 v[202:203], off
	v_lshl_add_u64 v[202:203], s[50:51], 0, v[130:131]
	s_mov_b32 m0, s54
	s_nop 0
	global_load_lds_dwordx4 v[202:203], off
	v_lshl_add_u64 v[202:203], s[50:51], 0, v[134:135]
	s_add_i32 m0, s54, 0x2000
	s_nop 0
	global_load_lds_dwordx4 v[202:203], off
	s_waitcnt vmcnt(6)
	s_waitcnt lgkmcnt(0)
	s_barrier
	s_setprio 1
	s_waitcnt lgkmcnt(0)
	v_mfma_f32_16x16x32_bf16 v[60:63], v[144:147], v[186:189], v[60:63]
	v_mfma_f32_16x16x32_bf16 v[56:59], v[160:163], v[186:189], v[56:59]
	v_mfma_f32_16x16x32_bf16 v[44:47], v[144:147], v[194:197], v[44:47]
	v_mfma_f32_16x16x32_bf16 v[40:43], v[160:163], v[194:197], v[40:43]
	v_mfma_f32_16x16x32_bf16 v[60:63], v[156:159], v[190:193], v[60:63]
	v_mfma_f32_16x16x32_bf16 v[56:59], v[164:167], v[190:193], v[56:59]
	v_mfma_f32_16x16x32_bf16 v[44:47], v[156:159], v[198:201], v[44:47]
	v_mfma_f32_16x16x32_bf16 v[40:43], v[164:167], v[198:201], v[40:43]
	v_mfma_f32_16x16x32_bf16 v[28:31], v[144:147], v[208:211], v[28:31]
	v_mfma_f32_16x16x32_bf16 v[24:27], v[160:163], v[208:211], v[24:27]
	v_mfma_f32_16x16x32_bf16 v[12:15], v[144:147], v[216:219], v[12:15]
	v_mfma_f32_16x16x32_bf16 v[8:11], v[160:163], v[216:219], v[8:11]
	v_mfma_f32_16x16x32_bf16 v[28:31], v[156:159], v[212:215], v[28:31]
	v_mfma_f32_16x16x32_bf16 v[24:27], v[164:167], v[212:215], v[24:27]
	v_lshl_add_u64 v[202:203], v[226:227], 0, s[42:43]
	s_mov_b32 m0, s59
	s_nop 0
	global_load_lds_dwordx4 v[202:203], off
	v_mfma_f32_16x16x32_bf16 v[12:15], v[156:159], v[220:223], v[12:15]
	v_mfma_f32_16x16x32_bf16 v[8:11], v[164:167], v[220:223], v[8:11]
	s_setprio 0
	s_setprio 1
	v_mfma_f32_16x16x32_bf16 v[52:55], v[168:171], v[186:189], v[52:55]
	v_mfma_f32_16x16x32_bf16 v[48:51], v[176:179], v[186:189], v[48:51]
	v_mfma_f32_16x16x32_bf16 v[36:39], v[168:171], v[194:197], v[36:39]
	v_mfma_f32_16x16x32_bf16 v[32:35], v[176:179], v[194:197], v[32:35]
	v_mfma_f32_16x16x32_bf16 v[52:55], v[172:175], v[190:193], v[52:55]
	v_mfma_f32_16x16x32_bf16 v[48:51], v[182:185], v[190:193], v[48:51]
	v_mfma_f32_16x16x32_bf16 v[36:39], v[172:175], v[198:201], v[36:39]
	v_mfma_f32_16x16x32_bf16 v[32:35], v[182:185], v[198:201], v[32:35]
	v_mfma_f32_16x16x32_bf16 v[20:23], v[168:171], v[208:211], v[20:23]
	v_mfma_f32_16x16x32_bf16 v[16:19], v[176:179], v[208:211], v[16:19]
	v_mfma_f32_16x16x32_bf16 v[4:7], v[168:171], v[216:219], v[4:7]
	v_mfma_f32_16x16x32_bf16 v[0:3], v[176:179], v[216:219], v[0:3]
	v_mfma_f32_16x16x32_bf16 v[20:23], v[172:175], v[212:215], v[20:23]
	v_mfma_f32_16x16x32_bf16 v[16:19], v[182:185], v[212:215], v[16:19]
	v_lshl_add_u64 v[202:203], v[228:229], 0, s[42:43]
	s_mov_b32 m0, s60
	s_nop 0
	global_load_lds_dwordx4 v[202:203], off
	v_mfma_f32_16x16x32_bf16 v[4:7], v[172:175], v[220:223], v[4:7]
	v_mfma_f32_16x16x32_bf16 v[0:3], v[182:185], v[220:223], v[0:3]
	s_setprio 0
	s_barrier
	s_add_i32 s77, s77, 2
	s_add_u32 s75, s75, 0x100
	s_addc_u32 s76, s76, 0
	s_cmp_gt_u32 s77, 41
	s_mov_b64 s[50:51], s[52:53]
	s_cbranch_scc0 .LBB0_1035
	s_and_b64 vcc, exec, s[44:45]
	s_cbranch_vccz .LBB0_1038
	s_barrier

; #define PG8_STAGE(bufoff, gbase, voff) do { _Pragma("unroll") for (int _i = 0; _i < 2; ++_i) \
;         __builtin_amdgcn_global_load_lds((const unsigned*)((const char*)(gbase) + (voff)[_i]), (PG8_LAS unsigned*)(lds + (bufoff) + ldsw + _i * 8192), 16, 0, 0); } while (0)
; #define PG8_LDA(dst, b, h) do { _Pragma("unroll") for (int m = 0; m < 4; ++m) _Pragma("unroll") for (int k = 0; k < 2; ++k) dst[m][k] = *(const PG8_LAS bf16x8*)(lds + PG8_SA(b, h) + aoff + m * 2048 + k * 1024); } while (0)
; #define PG8_LDB(dst, b, h) do { _Pragma("unroll") for (int n = 0; n < 2; ++n) _Pragma("unroll") for (int k = 0; k < 2; ++k) dst[n][k] = *(const PG8_LAS bf16x8*)(lds + PG8_SB(b, h) + boff + n * 2048 + k * 1024); } while (0)
; #define PG8_WAIT_V(n) asm volatile("s_waitcnt vmcnt(" #n ")" ::: "memory")
; #define PG8_WAIT_L(n) asm volatile("s_waitcnt lgkmcnt(" #n ")" ::: "memory")
; #define PG8_BAR __builtin_amdgcn_s_barrier()
; #define PG8_SCHED __builtin_amdgcn_sched_barrier(0)
; template <class Epi, class Sched, bool ALIGN_EPI = false, bool SP2 = false>
; __device__ __forceinline__ void gemm_phase(PG8_LAS unsigned char* lds, const Gemm g, const Sched& S, const Epi& E) {
;     ...
;         const bool has_next = S.next(ui + 1, nxt);
;         const char* nA = has_next ? (const char*)g.A + (size_t)nxt.pm * tstep : cA; const char* nB = has_next ? (const char*)g.Bt + (size_t)nxt.pn * tstep : cB;
;         for (int t = 0; t < nt; t += 2) {
;             const bool last = (t == nt - 2);
;             const char* a1 = cA + (size_t)(t + 1) * kstep;
;             const char* a2 = last ? nA : cA + (size_t)(t + 2) * kstep; const char* b2 = last ? nB : cB + (size_t)(t + 2) * kstep;
;             const char* a3 = a2 + kstep; const char* b3 = b2 + kstep;
;             if (last && has_next) S.a_ready(nxt);
;             if constexpr (SP2) {
;             PG8_LDB(B0, 0, 0); PG8_LDB(B1, 0, 1); PG8_SCHED; PG8_LDA(At, 0, 0); PG8_STAGE(PG8_SA(1, 1), a1 + hstep, voffA);
;             PG8_WAIT_V(8); PG8_WAIT_L(0); PG8_BAR; PG8_MMA(0, 0, At, B0); PG8_MMA(0, 1, At, B1); PG8_BAR; PG8_SCHED;
;             PG8_LDA(At, 0, 1); PG8_STAGE(PG8_SB(0, 0), b2, voffB); PG8_STAGE(PG8_SB(0, 1), b2 + hstep, voffB); PG8_STAGE(PG8_SA(0, 0), a2, voffA);
;             PG8_WAIT_V(8); PG8_WAIT_L(0); PG8_BAR; PG8_MMA(1, 0, At, B0); PG8_MMA(1, 1, At, B1); PG8_BAR; PG8_SCHED;
.LBB0_1118:
	s_ashr_i32 s45, s44, 31
	s_lshl_b64 s[48:49], s[44:45], 19
	s_add_u32 s48, s22, s48
	s_addc_u32 s49, s23, s49
	s_and_b64 s[50:51], s[10:11], exec
	s_cselect_b32 s45, s49, s55
	s_cselect_b32 s76, s48, s54
	s_ashr_i32 s43, s42, 31
	s_lshl_b64 s[50:51], s[42:43], 19
	s_add_u32 s50, s14, s50
	s_addc_u32 s51, s15, s51
	s_and_b64 s[58:59], s[10:11], exec
	s_cselect_b32 s43, s51, s57
	s_cselect_b32 s77, s50, s56
	s_add_u32 s54, s54, 0x40080
	s_addc_u32 s55, s55, 0
	s_add_u32 s82, s56, 0x100
	s_addc_u32 s83, s57, 0
	s_mov_b32 s84, -2
	ds_read_b128 v[144:147], v155
	ds_read_b128 v[148:151], v155 offset:1024
	ds_read_b128 v[160:163], v155 offset:2048
	ds_read_b128 v[164:167], v155 offset:3072
	ds_read_b128 v[168:171], v156
	ds_read_b128 v[172:175], v156 offset:1024
	ds_read_b128 v[176:179], v156 offset:2048
	ds_read_b128 v[182:185], v156 offset:3072
	s_add_u32 s56, s54, 0xfffc0080
	s_addc_u32 s57, s55, -1
	s_cmp_eq_u32 s84, 12
	s_cselect_b32 s59, s45, s57
	s_cselect_b32 s58, s76, s56
	s_cselect_b32 s57, s43, s83
	s_cselect_b32 s56, s77, s82
	v_lshl_add_u64 v[224:225], s[54:55], 0, v[136:137]
	s_add_i32 m0, s53, 0xc000
	ds_read_b128 v[186:189], v157
	ds_read_b128 v[190:193], v157 offset:1024
	ds_read_b128 v[194:197], v157 offset:2048
	ds_read_b128 v[198:201], v157 offset:3072
	ds_read_b128 v[208:211], v157 offset:4096
	ds_read_b128 v[212:215], v157 offset:5120
	ds_read_b128 v[216:219], v157 offset:6144
	ds_read_b128 v[220:223], v157 offset:7168
	global_load_lds_dwordx4 v[224:225], off
	v_lshl_add_u64 v[224:225], s[54:55], 0, v[138:139]
	s_add_i32 m0, s53, 0xe000
	s_nop 0
	global_load_lds_dwordx4 v[224:225], off
	s_waitcnt vmcnt(8)
	s_waitcnt lgkmcnt(0)
	s_barrier
	s_setprio 1
	s_waitcnt lgkmcnt(0)
	v_mfma_f32_16x16x32_bf16 v[124:127], v[144:147], v[186:189], 0
	v_mfma_f32_16x16x32_bf16 v[120:123], v[160:163], v[186:189], 0
	v_mfma_f32_16x16x32_bf16 v[108:111], v[144:147], v[194:197], 0
	v_mfma_f32_16x16x32_bf16 v[104:107], v[160:163], v[194:197], 0
	v_mfma_f32_16x16x32_bf16 v[124:127], v[148:151], v[190:193], v[124:127]
	v_mfma_f32_16x16x32_bf16 v[120:123], v[164:167], v[190:193], v[120:123]
	v_mfma_f32_16x16x32_bf16 v[108:111], v[148:151], v[198:201], v[108:111]
	v_mfma_f32_16x16x32_bf16 v[104:107], v[164:167], v[198:201], v[104:107]
	v_mfma_f32_16x16x32_bf16 v[92:95], v[144:147], v[208:211], 0
	v_mfma_f32_16x16x32_bf16 v[88:91], v[160:163], v[208:211], 0
	v_mfma_f32_16x16x32_bf16 v[76:79], v[144:147], v[216:219], 0
	v_mfma_f32_16x16x32_bf16 v[72:75], v[160:163], v[216:219], 0
	v_mfma_f32_16x16x32_bf16 v[92:95], v[148:151], v[212:215], v[92:95]
	v_mfma_f32_16x16x32_bf16 v[88:91], v[164:167], v[212:215], v[88:91]
	v_mfma_f32_16x16x32_bf16 v[76:79], v[148:151], v[220:223], v[76:79]
	v_mfma_f32_16x16x32_bf16 v[72:75], v[164:167], v[220:223], v[72:75]
	s_setprio 0
	s_setprio 1
	v_mfma_f32_16x16x32_bf16 v[116:119], v[168:171], v[186:189], 0
	v_mfma_f32_16x16x32_bf16 v[112:115], v[176:179], v[186:189], 0
	v_mfma_f32_16x16x32_bf16 v[100:103], v[168:171], v[194:197], 0
	v_mfma_f32_16x16x32_bf16 v[96:99], v[176:179], v[194:197], 0
	v_mfma_f32_16x16x32_bf16 v[116:119], v[172:175], v[190:193], v[116:119]
	v_mfma_f32_16x16x32_bf16 v[112:115], v[182:185], v[190:193], v[112:115]
	v_mfma_f32_16x16x32_bf16 v[100:103], v[172:175], v[198:201], v[100:103]
	v_mfma_f32_16x16x32_bf16 v[96:99], v[182:185], v[198:201], v[96:99]
	v_mfma_f32_16x16x32_bf16 v[84:87], v[168:171], v[208:211], 0
	v_mfma_f32_16x16x32_bf16 v[80:83], v[176:179], v[208:211], 0
	v_mfma_f32_16x16x32_bf16 v[68:71], v[168:171], v[216:219], 0
	v_mfma_f32_16x16x32_bf16 v[64:67], v[176:179], v[216:219], 0
	v_mfma_f32_16x16x32_bf16 v[84:87], v[172:175], v[212:215], v[84:87]
	v_mfma_f32_16x16x32_bf16 v[80:83], v[182:185], v[212:215], v[80:83]
	v_mfma_f32_16x16x32_bf16 v[68:71], v[172:175], v[220:223], v[68:71]
	v_mfma_f32_16x16x32_bf16 v[64:67], v[182:185], v[220:223], v[64:67]
	s_setprio 0
	s_barrier
	s_add_i32 s78, s66, s33
	v_lshl_add_u64 v[224:225], s[56:57], 0, v[132:133]
	s_mov_b32 m0, s78
	ds_read_b128 v[186:189], v157 offset:16384
	ds_read_b128 v[190:193], v157 offset:17408
	ds_read_b128 v[194:197], v157 offset:18432
	ds_read_b128 v[198:201], v157 offset:19456
	ds_read_b128 v[208:211], v157 offset:20480
	ds_read_b128 v[212:215], v157 offset:21504
	ds_read_b128 v[216:219], v157 offset:22528
	ds_read_b128 v[220:223], v157 offset:23552
	global_load_lds_dwordx4 v[224:225], off
	s_add_i32 m0, s78, 0x2000
	s_add_u32 s78, s56, 0x40000
	v_lshl_add_u64 v[226:227], s[56:57], 0, v[128:129]
	s_addc_u32 s79, s57, 0
	s_add_i32 s85, s67, s33
	global_load_lds_dwordx4 v[226:227], off
	v_lshl_add_u64 v[228:229], s[78:79], 0, v[132:133]
	s_mov_b32 m0, s85
	global_load_lds_dwordx4 v[228:229], off
	v_lshl_add_u64 v[228:229], s[78:79], 0, v[128:129]
	s_add_i32 m0, s85, 0x2000
	s_nop 0
	global_load_lds_dwordx4 v[228:229], off
	s_waitcnt vmcnt(6)
	s_waitcnt lgkmcnt(0)
	s_barrier
; #define PG8_STAGE(bufoff, gbase, voff) do { _Pragma("unroll") for (int _i = 0; _i < 2; ++_i) \
;         __builtin_amdgcn_global_load_lds((const unsigned*)((const char*)(gbase) + (voff)[_i]), (PG8_LAS unsigned*)(lds + (bufoff) + ldsw + _i * 8192), 16, 0, 0); } while (0)
; #define PG8_LDA(dst, b, h) do { _Pragma("unroll") for (int m = 0; m < 4; ++m) _Pragma("unroll") for (int k = 0; k < 2; ++k) dst[m][k] = *(const PG8_LAS bf16x8*)(lds + PG8_SA(b, h) + aoff + m * 2048 + k * 1024); } while (0)
; #define PG8_LDB(dst, b, h) do { _Pragma("unroll") for (int n = 0; n < 2; ++n) _Pragma("unroll") for (int k = 0; k < 2; ++k) dst[n][k] = *(const PG8_LAS bf16x8*)(lds + PG8_SB(b, h) + boff + n * 2048 + k * 1024); } while (0)
; #define PG8_MMA(ai, bj, At, Bt) do { __builtin_amdgcn_s_setprio(1); _Pragma("unroll") for (int m = 0; m < 4; ++m) _Pragma("unroll") for (int n = 0; n < 2; ++n) _Pragma("unroll") for (int k = 0; k < 2; ++k) \
;         acc[ai][bj][m][n] = __builtin_amdgcn_mfma_f32_16x16x32_bf16(Bt[n][k], At[m][k], acc[ai][bj][m][n], 0, 0, 0); __builtin_amdgcn_s_setprio(0); } while (0)
; #define PG8_WAIT_V(n) asm volatile("s_waitcnt vmcnt(" #n ")" ::: "memory")
; #define PG8_WAIT_L(n) asm volatile("s_waitcnt lgkmcnt(" #n ")" ::: "memory")
; #define PG8_BAR __builtin_amdgcn_s_barrier()
; #define PG8_SCHED __builtin_amdgcn_sched_barrier(0)
; template <class Epi, class Sched, bool ALIGN_EPI = false, bool SP2 = false>
; __device__ __forceinline__ void gemm_phase(PG8_LAS unsigned char* lds, const Gemm g, const Sched& S, const Epi& E) {
;     ...
;             PG8_LDA(At, 0, 1); PG8_STAGE(PG8_SB(0, 0), b2, voffB); PG8_STAGE(PG8_SB(0, 1), b2 + hstep, voffB); PG8_STAGE(PG8_SA(0, 0), a2, voffA);
;             PG8_WAIT_V(8); PG8_WAIT_L(0); PG8_BAR; PG8_MMA(1, 0, At, B0); PG8_MMA(1, 1, At, B1); PG8_BAR; PG8_SCHED;
;             PG8_LDB(B0, 1, 0); PG8_LDB(B1, 1, 1); PG8_SCHED; PG8_LDA(At, 1, 0); PG8_STAGE(PG8_SA(0, 1), a2 + hstep, voffA);
;             PG8_WAIT_V(8); PG8_WAIT_L(0); PG8_BAR; PG8_MMA(0, 0, At, B0); PG8_MMA(0, 1, At, B1); PG8_BAR; PG8_SCHED;
	s_setprio 1
	s_waitcnt lgkmcnt(0)
	v_mfma_f32_16x16x32_bf16 v[60:63], v[144:147], v[186:189], 0
	v_mfma_f32_16x16x32_bf16 v[56:59], v[160:163], v[186:189], 0
	v_mfma_f32_16x16x32_bf16 v[44:47], v[144:147], v[194:197], 0
	v_mfma_f32_16x16x32_bf16 v[40:43], v[160:163], v[194:197], 0
	v_mfma_f32_16x16x32_bf16 v[60:63], v[148:151], v[190:193], v[60:63]
	v_mfma_f32_16x16x32_bf16 v[56:59], v[164:167], v[190:193], v[56:59]
	v_mfma_f32_16x16x32_bf16 v[44:47], v[148:151], v[198:201], v[44:47]
	v_mfma_f32_16x16x32_bf16 v[40:43], v[164:167], v[198:201], v[40:43]
	v_mfma_f32_16x16x32_bf16 v[28:31], v[144:147], v[208:211], 0
	v_mfma_f32_16x16x32_bf16 v[24:27], v[160:163], v[208:211], 0
	v_mfma_f32_16x16x32_bf16 v[12:15], v[144:147], v[216:219], 0
	v_mfma_f32_16x16x32_bf16 v[8:11], v[160:163], v[216:219], 0
	v_mfma_f32_16x16x32_bf16 v[28:31], v[148:151], v[212:215], v[28:31]
	v_mfma_f32_16x16x32_bf16 v[24:27], v[164:167], v[212:215], v[24:27]
	v_lshl_add_u64 v[228:229], s[58:59], 0, v[134:135]
	s_mov_b32 m0, s53
	s_nop 0
	global_load_lds_dwordx4 v[228:229], off
	v_mfma_f32_16x16x32_bf16 v[12:15], v[148:151], v[220:223], v[12:15]
	v_mfma_f32_16x16x32_bf16 v[8:11], v[164:167], v[220:223], v[8:11]
	s_setprio 0
	s_setprio 1
	v_mfma_f32_16x16x32_bf16 v[52:55], v[168:171], v[186:189], 0
	v_mfma_f32_16x16x32_bf16 v[48:51], v[176:179], v[186:189], 0
	v_mfma_f32_16x16x32_bf16 v[36:39], v[168:171], v[194:197], 0
	v_mfma_f32_16x16x32_bf16 v[32:35], v[176:179], v[194:197], 0
	v_mfma_f32_16x16x32_bf16 v[52:55], v[172:175], v[190:193], v[52:55]
	v_mfma_f32_16x16x32_bf16 v[48:51], v[182:185], v[190:193], v[48:51]
	v_mfma_f32_16x16x32_bf16 v[36:39], v[172:175], v[198:201], v[36:39]
	v_mfma_f32_16x16x32_bf16 v[32:35], v[182:185], v[198:201], v[32:35]
	v_mfma_f32_16x16x32_bf16 v[20:23], v[168:171], v[208:211], 0
	v_mfma_f32_16x16x32_bf16 v[16:19], v[176:179], v[208:211], 0
	v_mfma_f32_16x16x32_bf16 v[4:7], v[168:171], v[216:219], 0
	v_mfma_f32_16x16x32_bf16 v[0:3], v[176:179], v[216:219], 0
	v_mfma_f32_16x16x32_bf16 v[20:23], v[172:175], v[212:215], v[20:23]
	v_mfma_f32_16x16x32_bf16 v[16:19], v[182:185], v[212:215], v[16:19]
	v_lshl_add_u64 v[230:231], s[58:59], 0, v[130:131]
	s_mov_b32 m0, s60
	s_nop 0
	global_load_lds_dwordx4 v[230:231], off
	v_mfma_f32_16x16x32_bf16 v[4:7], v[172:175], v[220:223], v[4:7]
	v_mfma_f32_16x16x32_bf16 v[0:3], v[182:185], v[220:223], v[0:3]
	s_setprio 0
	s_barrier
	s_add_i32 s78, 0, 0x18000
	v_add_u32_e32 v159, s78, v153
	s_add_i32 s79, 0, 0x1c000
	ds_read_b128 v[144:147], v159
	ds_read_b128 v[148:151], v159 offset:1024
	ds_read_b128 v[160:163], v159 offset:2048
	ds_read_b128 v[164:167], v159 offset:3072
	v_add_u32_e32 v159, s79, v153
	ds_read_b128 v[168:171], v159
	ds_read_b128 v[172:175], v159 offset:1024
	ds_read_b128 v[176:179], v159 offset:2048
	ds_read_b128 v[182:185], v159 offset:3072
	s_add_u32 s58, s58, 0x40000
	s_addc_u32 s59, s59, 0
	s_mov_b32 m0, s61
	v_lshl_add_u64 v[232:233], s[58:59], 0, v[134:135]
	ds_read_b128 v[186:189], v157 offset:32768
	ds_read_b128 v[190:193], v157 offset:33792
	ds_read_b128 v[194:197], v157 offset:34816
	ds_read_b128 v[198:201], v157 offset:35840
	ds_read_b128 v[208:211], v157 offset:36864
	ds_read_b128 v[212:215], v157 offset:37888
	ds_read_b128 v[216:219], v157 offset:38912
	ds_read_b128 v[220:223], v157 offset:39936
	global_load_lds_dwordx4 v[232:233], off
	v_lshl_add_u64 v[232:233], s[58:59], 0, v[130:131]
	s_mov_b32 m0, s62
	s_nop 0
	global_load_lds_dwordx4 v[232:233], off
	s_waitcnt vmcnt(8)
	s_waitcnt lgkmcnt(0)
	s_barrier
	s_setprio 1
	s_waitcnt lgkmcnt(0)
	v_mfma_f32_16x16x32_bf16 v[124:127], v[144:147], v[186:189], v[124:127]
	v_mfma_f32_16x16x32_bf16 v[120:123], v[160:163], v[186:189], v[120:123]
	v_mfma_f32_16x16x32_bf16 v[108:111], v[144:147], v[194:197], v[108:111]
	v_mfma_f32_16x16x32_bf16 v[104:107], v[160:163], v[194:197], v[104:107]
	v_mfma_f32_16x16x32_bf16 v[124:127], v[148:151], v[190:193], v[124:127]
	v_mfma_f32_16x16x32_bf16 v[120:123], v[164:167], v[190:193], v[120:123]
	v_mfma_f32_16x16x32_bf16 v[108:111], v[148:151], v[198:201], v[108:111]
	v_mfma_f32_16x16x32_bf16 v[104:107], v[164:167], v[198:201], v[104:107]
	v_mfma_f32_16x16x32_bf16 v[92:95], v[144:147], v[208:211], v[92:95]
	v_mfma_f32_16x16x32_bf16 v[88:91], v[160:163], v[208:211], v[88:91]
	v_mfma_f32_16x16x32_bf16 v[76:79], v[144:147], v[216:219], v[76:79]
	v_mfma_f32_16x16x32_bf16 v[72:75], v[160:163], v[216:219], v[72:75]
	v_mfma_f32_16x16x32_bf16 v[92:95], v[148:151], v[212:215], v[92:95]
	v_mfma_f32_16x16x32_bf16 v[88:91], v[164:167], v[212:215], v[88:91]
	v_mfma_f32_16x16x32_bf16 v[76:79], v[148:151], v[220:223], v[76:79]
	v_mfma_f32_16x16x32_bf16 v[72:75], v[164:167], v[220:223], v[72:75]
	s_setprio 0
	s_setprio 1
	v_mfma_f32_16x16x32_bf16 v[116:119], v[168:171], v[186:189], v[116:119]
	v_mfma_f32_16x16x32_bf16 v[112:115], v[176:179], v[186:189], v[112:115]
	v_mfma_f32_16x16x32_bf16 v[100:103], v[168:171], v[194:197], v[100:103]
	v_mfma_f32_16x16x32_bf16 v[96:99], v[176:179], v[194:197], v[96:99]
	v_mfma_f32_16x16x32_bf16 v[116:119], v[172:175], v[190:193], v[116:119]
	v_mfma_f32_16x16x32_bf16 v[112:115], v[182:185], v[190:193], v[112:115]
	v_mfma_f32_16x16x32_bf16 v[100:103], v[172:175], v[198:201], v[100:103]
	v_mfma_f32_16x16x32_bf16 v[96:99], v[182:185], v[198:201], v[96:99]
	v_mfma_f32_16x16x32_bf16 v[84:87], v[168:171], v[208:211], v[84:87]
	v_mfma_f32_16x16x32_bf16 v[80:83], v[176:179], v[208:211], v[80:83]
	v_mfma_f32_16x16x32_bf16 v[68:71], v[168:171], v[216:219], v[68:71]
	v_mfma_f32_16x16x32_bf16 v[64:67], v[176:179], v[216:219], v[64:67]
	v_mfma_f32_16x16x32_bf16 v[84:87], v[172:175], v[212:215], v[84:87]
	v_mfma_f32_16x16x32_bf16 v[80:83], v[182:185], v[212:215], v[80:83]
	v_mfma_f32_16x16x32_bf16 v[68:71], v[172:175], v[220:223], v[68:71]
	v_mfma_f32_16x16x32_bf16 v[64:67], v[182:185], v[220:223], v[64:67]
	s_setprio 0
	s_barrier
; #define PG8_STAGE(bufoff, gbase, voff) do { _Pragma("unroll") for (int _i = 0; _i < 2; ++_i) \
;         __builtin_amdgcn_global_load_lds((const unsigned*)((const char*)(gbase) + (voff)[_i]), (PG8_LAS unsigned*)(lds + (bufoff) + ldsw + _i * 8192), 16, 0, 0); } while (0)
; #define PG8_LDA(dst, b, h) do { _Pragma("unroll") for (int m = 0; m < 4; ++m) _Pragma("unroll") for (int k = 0; k < 2; ++k) dst[m][k] = *(const PG8_LAS bf16x8*)(lds + PG8_SA(b, h) + aoff + m * 2048 + k * 1024); } while (0)
; #define PG8_LDB(dst, b, h) do { _Pragma("unroll") for (int n = 0; n < 2; ++n) _Pragma("unroll") for (int k = 0; k < 2; ++k) dst[n][k] = *(const PG8_LAS bf16x8*)(lds + PG8_SB(b, h) + boff + n * 2048 + k * 1024); } while (0)
; #define PG8_WAIT_V(n) asm volatile("s_waitcnt vmcnt(" #n ")" ::: "memory")
; #define PG8_WAIT_L(n) asm volatile("s_waitcnt lgkmcnt(" #n ")" ::: "memory")
; #define PG8_BAR __builtin_amdgcn_s_barrier()
; template <class Epi, class Sched, bool ALIGN_EPI = false, bool SP2 = false>
; __device__ __forceinline__ void gemm_phase(PG8_LAS unsigned char* lds, const Gemm g, const Sched& S, const Epi& E) {
;     ...
;         for (int t = 0; t < nt; t += 2) {
;             const bool last = (t == nt - 2);
;             const char* a1 = cA + (size_t)(t + 1) * kstep;
;             const char* a2 = last ? nA : cA + (size_t)(t + 2) * kstep; const char* b2 = last ? nB : cB + (size_t)(t + 2) * kstep;
;             const char* a3 = a2 + kstep; const char* b3 = b2 + kstep;
;             if (last && has_next) S.a_ready(nxt);
;             if constexpr (SP2) {
;             PG8_LDB(B0, 0, 0); PG8_LDB(B1, 0, 1); PG8_SCHED; PG8_LDA(At, 0, 0); PG8_STAGE(PG8_SA(1, 1), a1 + hstep, voffA);
;             PG8_WAIT_V(8); PG8_WAIT_L(0); PG8_BAR; PG8_MMA(0, 0, At, B0); PG8_MMA(0, 1, At, B1); PG8_BAR; PG8_SCHED;
;             PG8_LDA(At, 0, 1); PG8_STAGE(PG8_SB(0, 0), b2, voffB); PG8_STAGE(PG8_SB(0, 1), b2 + hstep, voffB); PG8_STAGE(PG8_SA(0, 0), a2, voffA);
;             PG8_WAIT_V(8); PG8_WAIT_L(0); PG8_BAR; PG8_MMA(1, 0, At, B0); PG8_MMA(1, 1, At, B1); PG8_BAR; PG8_SCHED;
;     ...
;             PG8_LDA(At, 1, 1); PG8_STAGE(PG8_SB(1, 0), b3, voffB); PG8_STAGE(PG8_SB(1, 1), b3 + hstep, voffB); PG8_STAGE(PG8_SA(1, 0), a3, voffA);
;             PG8_WAIT_V(8); PG8_WAIT_L(0); PG8_BAR; PG8_MMA(1, 0, At, B0); PG8_MMA(1, 1, At, B1); PG8_BAR; PG8_SCHED;
	s_add_i32 s58, s78, s33
	v_lshl_add_u64 v[224:225], v[224:225], 0, s[12:13]
	s_mov_b32 m0, s58
	ds_read_b128 v[186:189], v157 offset:49152
	ds_read_b128 v[190:193], v157 offset:50176
	ds_read_b128 v[194:197], v157 offset:51200
	ds_read_b128 v[198:201], v157 offset:52224
	ds_read_b128 v[208:211], v157 offset:53248
	ds_read_b128 v[212:215], v157 offset:54272
	ds_read_b128 v[216:219], v157 offset:55296
	ds_read_b128 v[220:223], v157 offset:56320
	global_load_lds_dwordx4 v[224:225], off
	s_add_i32 m0, s58, 0x2000
	s_add_u32 s56, s56, 0x40080
	v_lshl_add_u64 v[224:225], v[226:227], 0, s[12:13]
	s_addc_u32 s57, s57, 0
	s_add_i32 s58, s79, s33
	global_load_lds_dwordx4 v[224:225], off
	v_lshl_add_u64 v[224:225], s[56:57], 0, v[132:133]
	s_mov_b32 m0, s58
	s_nop 0
	global_load_lds_dwordx4 v[224:225], off
	v_lshl_add_u64 v[224:225], s[56:57], 0, v[128:129]
	s_add_i32 m0, s58, 0x2000
	s_nop 0
	global_load_lds_dwordx4 v[224:225], off
	s_waitcnt vmcnt(6)
	s_waitcnt lgkmcnt(0)
	s_barrier
	s_setprio 1
	s_waitcnt lgkmcnt(0)
	v_mfma_f32_16x16x32_bf16 v[60:63], v[144:147], v[186:189], v[60:63]
	v_mfma_f32_16x16x32_bf16 v[56:59], v[160:163], v[186:189], v[56:59]
	v_mfma_f32_16x16x32_bf16 v[44:47], v[144:147], v[194:197], v[44:47]
	v_mfma_f32_16x16x32_bf16 v[40:43], v[160:163], v[194:197], v[40:43]
	v_mfma_f32_16x16x32_bf16 v[60:63], v[148:151], v[190:193], v[60:63]
	v_mfma_f32_16x16x32_bf16 v[56:59], v[164:167], v[190:193], v[56:59]
	v_mfma_f32_16x16x32_bf16 v[44:47], v[148:151], v[198:201], v[44:47]
	v_mfma_f32_16x16x32_bf16 v[40:43], v[164:167], v[198:201], v[40:43]
	v_mfma_f32_16x16x32_bf16 v[28:31], v[144:147], v[208:211], v[28:31]
	v_mfma_f32_16x16x32_bf16 v[24:27], v[160:163], v[208:211], v[24:27]
	v_mfma_f32_16x16x32_bf16 v[12:15], v[144:147], v[216:219], v[12:15]
	v_mfma_f32_16x16x32_bf16 v[8:11], v[160:163], v[216:219], v[8:11]
	v_mfma_f32_16x16x32_bf16 v[28:31], v[148:151], v[212:215], v[28:31]
	v_mfma_f32_16x16x32_bf16 v[24:27], v[164:167], v[212:215], v[24:27]
	v_lshl_add_u64 v[224:225], v[228:229], 0, s[12:13]
	s_mov_b32 m0, s64
	s_nop 0
	global_load_lds_dwordx4 v[224:225], off
	v_mfma_f32_16x16x32_bf16 v[12:15], v[148:151], v[220:223], v[12:15]
	v_mfma_f32_16x16x32_bf16 v[8:11], v[164:167], v[220:223], v[8:11]
	s_setprio 0
	s_setprio 1
	v_mfma_f32_16x16x32_bf16 v[52:55], v[168:171], v[186:189], v[52:55]
	v_mfma_f32_16x16x32_bf16 v[48:51], v[176:179], v[186:189], v[48:51]
	v_mfma_f32_16x16x32_bf16 v[36:39], v[168:171], v[194:197], v[36:39]
	v_mfma_f32_16x16x32_bf16 v[32:35], v[176:179], v[194:197], v[32:35]
	v_mfma_f32_16x16x32_bf16 v[52:55], v[172:175], v[190:193], v[52:55]
	v_mfma_f32_16x16x32_bf16 v[48:51], v[182:185], v[190:193], v[48:51]
	v_mfma_f32_16x16x32_bf16 v[36:39], v[172:175], v[198:201], v[36:39]
	v_mfma_f32_16x16x32_bf16 v[32:35], v[182:185], v[198:201], v[32:35]
	v_mfma_f32_16x16x32_bf16 v[20:23], v[168:171], v[208:211], v[20:23]
	v_mfma_f32_16x16x32_bf16 v[16:19], v[176:179], v[208:211], v[16:19]
	v_mfma_f32_16x16x32_bf16 v[4:7], v[168:171], v[216:219], v[4:7]
	v_mfma_f32_16x16x32_bf16 v[0:3], v[176:179], v[216:219], v[0:3]
	v_mfma_f32_16x16x32_bf16 v[20:23], v[172:175], v[212:215], v[20:23]
	v_mfma_f32_16x16x32_bf16 v[16:19], v[182:185], v[212:215], v[16:19]
	v_lshl_add_u64 v[224:225], v[230:231], 0, s[12:13]
	s_mov_b32 m0, s65
	s_nop 0
	global_load_lds_dwordx4 v[224:225], off
	v_mfma_f32_16x16x32_bf16 v[4:7], v[172:175], v[220:223], v[4:7]
	v_mfma_f32_16x16x32_bf16 v[0:3], v[182:185], v[220:223], v[0:3]
	s_setprio 0
	s_barrier
	s_add_i32 s84, s84, 2
	s_add_u32 s54, s54, 0x100
	s_addc_u32 s55, s55, 0
	s_add_u32 s82, s82, 0x100
	s_addc_u32 s83, s83, 0
.LBB0_1119:
	ds_read_b128 v[144:147], v155
	ds_read_b128 v[148:151], v155 offset:1024
	ds_read_b128 v[160:163], v155 offset:2048
	ds_read_b128 v[164:167], v155 offset:3072
	ds_read_b128 v[168:171], v156
	ds_read_b128 v[172:175], v156 offset:1024
	ds_read_b128 v[176:179], v156 offset:2048
	ds_read_b128 v[182:185], v156 offset:3072
	s_add_u32 s56, s54, 0xfffc0080
	s_addc_u32 s57, s55, -1
	s_cmp_eq_u32 s84, 12
	s_cselect_b32 s59, s45, s57
	s_cselect_b32 s58, s76, s56
	s_cselect_b32 s57, s43, s83
	s_cselect_b32 s56, s77, s82
	v_lshl_add_u64 v[224:225], s[54:55], 0, v[136:137]
	s_add_i32 m0, s53, 0xc000
	ds_read_b128 v[186:189], v157
	ds_read_b128 v[190:193], v157 offset:1024
	ds_read_b128 v[194:197], v157 offset:2048
	ds_read_b128 v[198:201], v157 offset:3072
	ds_read_b128 v[208:211], v157 offset:4096
	ds_read_b128 v[212:215], v157 offset:5120
	ds_read_b128 v[216:219], v157 offset:6144
	ds_read_b128 v[220:223], v157 offset:7168
	global_load_lds_dwordx4 v[224:225], off
	v_lshl_add_u64 v[224:225], s[54:55], 0, v[138:139]
	s_add_i32 m0, s53, 0xe000
	s_nop 0
	global_load_lds_dwordx4 v[224:225], off
	s_waitcnt vmcnt(8)
	s_waitcnt lgkmcnt(0)
	s_barrier
; #define PG8_STAGE(bufoff, gbase, voff) do { _Pragma("unroll") for (int _i = 0; _i < 2; ++_i) \
;         __builtin_amdgcn_global_load_lds((const unsigned*)((const char*)(gbase) + (voff)[_i]), (PG8_LAS unsigned*)(lds + (bufoff) + ldsw + _i * 8192), 16, 0, 0); } while (0)
; #define PG8_LDA(dst, b, h) do { _Pragma("unroll") for (int m = 0; m < 4; ++m) _Pragma("unroll") for (int k = 0; k < 2; ++k) dst[m][k] = *(const PG8_LAS bf16x8*)(lds + PG8_SA(b, h) + aoff + m * 2048 + k * 1024); } while (0)
; #define PG8_LDB(dst, b, h) do { _Pragma("unroll") for (int n = 0; n < 2; ++n) _Pragma("unroll") for (int k = 0; k < 2; ++k) dst[n][k] = *(const PG8_LAS bf16x8*)(lds + PG8_SB(b, h) + boff + n * 2048 + k * 1024); } while (0)
; #define PG8_MMA(ai, bj, At, Bt) do { __builtin_amdgcn_s_setprio(1); _Pragma("unroll") for (int m = 0; m < 4; ++m) _Pragma("unroll") for (int n = 0; n < 2; ++n) _Pragma("unroll") for (int k = 0; k < 2; ++k) \
;         acc[ai][bj][m][n] = __builtin_amdgcn_mfma_f32_16x16x32_bf16(Bt[n][k], At[m][k], acc[ai][bj][m][n], 0, 0, 0); __builtin_amdgcn_s_setprio(0); } while (0)
; #define PG8_WAIT_V(n) asm volatile("s_waitcnt vmcnt(" #n ")" ::: "memory")
; #define PG8_WAIT_L(n) asm volatile("s_waitcnt lgkmcnt(" #n ")" ::: "memory")
; #define PG8_BAR __builtin_amdgcn_s_barrier()
; #define PG8_SCHED __builtin_amdgcn_sched_barrier(0)
; template <class Epi, class Sched, bool ALIGN_EPI = false, bool SP2 = false>
; __device__ __forceinline__ void gemm_phase(PG8_LAS unsigned char* lds, const Gemm g, const Sched& S, const Epi& E) {
;     ...
;             PG8_LDB(B0, 0, 0); PG8_LDB(B1, 0, 1); PG8_SCHED; PG8_LDA(At, 0, 0); PG8_STAGE(PG8_SA(1, 1), a1 + hstep, voffA);
;             PG8_WAIT_V(8); PG8_WAIT_L(0); PG8_BAR; PG8_MMA(0, 0, At, B0); PG8_MMA(0, 1, At, B1); PG8_BAR; PG8_SCHED;
;             PG8_LDA(At, 0, 1); PG8_STAGE(PG8_SB(0, 0), b2, voffB); PG8_STAGE(PG8_SB(0, 1), b2 + hstep, voffB); PG8_STAGE(PG8_SA(0, 0), a2, voffA);
;             PG8_WAIT_V(8); PG8_WAIT_L(0); PG8_BAR; PG8_MMA(1, 0, At, B0); PG8_MMA(1, 1, At, B1); PG8_BAR; PG8_SCHED;
	s_setprio 1
	s_waitcnt lgkmcnt(0)
	v_mfma_f32_16x16x32_bf16 v[124:127], v[144:147], v[186:189], v[124:127]
	v_mfma_f32_16x16x32_bf16 v[120:123], v[160:163], v[186:189], v[120:123]
	v_mfma_f32_16x16x32_bf16 v[108:111], v[144:147], v[194:197], v[108:111]
	v_mfma_f32_16x16x32_bf16 v[104:107], v[160:163], v[194:197], v[104:107]
	v_mfma_f32_16x16x32_bf16 v[124:127], v[148:151], v[190:193], v[124:127]
	v_mfma_f32_16x16x32_bf16 v[120:123], v[164:167], v[190:193], v[120:123]
	v_mfma_f32_16x16x32_bf16 v[108:111], v[148:151], v[198:201], v[108:111]
	v_mfma_f32_16x16x32_bf16 v[104:107], v[164:167], v[198:201], v[104:107]
	v_mfma_f32_16x16x32_bf16 v[92:95], v[144:147], v[208:211], v[92:95]
	v_mfma_f32_16x16x32_bf16 v[88:91], v[160:163], v[208:211], v[88:91]
	v_mfma_f32_16x16x32_bf16 v[76:79], v[144:147], v[216:219], v[76:79]
	v_mfma_f32_16x16x32_bf16 v[72:75], v[160:163], v[216:219], v[72:75]
	v_mfma_f32_16x16x32_bf16 v[92:95], v[148:151], v[212:215], v[92:95]
	v_mfma_f32_16x16x32_bf16 v[88:91], v[164:167], v[212:215], v[88:91]
	v_mfma_f32_16x16x32_bf16 v[76:79], v[148:151], v[220:223], v[76:79]
	v_mfma_f32_16x16x32_bf16 v[72:75], v[164:167], v[220:223], v[72:75]
	s_setprio 0
	s_setprio 1
	v_mfma_f32_16x16x32_bf16 v[116:119], v[168:171], v[186:189], v[116:119]
	v_mfma_f32_16x16x32_bf16 v[112:115], v[176:179], v[186:189], v[112:115]
	v_mfma_f32_16x16x32_bf16 v[100:103], v[168:171], v[194:197], v[100:103]
	v_mfma_f32_16x16x32_bf16 v[96:99], v[176:179], v[194:197], v[96:99]
	v_mfma_f32_16x16x32_bf16 v[116:119], v[172:175], v[190:193], v[116:119]
	v_mfma_f32_16x16x32_bf16 v[112:115], v[182:185], v[190:193], v[112:115]
	v_mfma_f32_16x16x32_bf16 v[100:103], v[172:175], v[198:201], v[100:103]
	v_mfma_f32_16x16x32_bf16 v[96:99], v[182:185], v[198:201], v[96:99]
	v_mfma_f32_16x16x32_bf16 v[84:87], v[168:171], v[208:211], v[84:87]
	v_mfma_f32_16x16x32_bf16 v[80:83], v[176:179], v[208:211], v[80:83]
	v_mfma_f32_16x16x32_bf16 v[68:71], v[168:171], v[216:219], v[68:71]
	v_mfma_f32_16x16x32_bf16 v[64:67], v[176:179], v[216:219], v[64:67]
	v_mfma_f32_16x16x32_bf16 v[84:87], v[172:175], v[212:215], v[84:87]
	v_mfma_f32_16x16x32_bf16 v[80:83], v[182:185], v[212:215], v[80:83]
	v_mfma_f32_16x16x32_bf16 v[68:71], v[172:175], v[220:223], v[68:71]
	v_mfma_f32_16x16x32_bf16 v[64:67], v[182:185], v[220:223], v[64:67]
	s_setprio 0
	s_barrier
	s_add_i32 s78, s66, s33
	v_lshl_add_u64 v[224:225], s[56:57], 0, v[132:133]
	s_mov_b32 m0, s78
	ds_read_b128 v[186:189], v157 offset:16384
	ds_read_b128 v[190:193], v157 offset:17408
	ds_read_b128 v[194:197], v157 offset:18432
	ds_read_b128 v[198:201], v157 offset:19456
	ds_read_b128 v[208:211], v157 offset:20480
	ds_read_b128 v[212:215], v157 offset:21504
	ds_read_b128 v[216:219], v157 offset:22528
	ds_read_b128 v[220:223], v157 offset:23552
	global_load_lds_dwordx4 v[224:225], off
	s_add_i32 m0, s78, 0x2000
	s_add_u32 s78, s56, 0x40000
	v_lshl_add_u64 v[226:227], s[56:57], 0, v[128:129]
	s_addc_u32 s79, s57, 0
	s_add_i32 s85, s67, s33
	global_load_lds_dwordx4 v[226:227], off
	v_lshl_add_u64 v[228:229], s[78:79], 0, v[132:133]
	s_mov_b32 m0, s85
	global_load_lds_dwordx4 v[228:229], off
	v_lshl_add_u64 v[228:229], s[78:79], 0, v[128:129]
	s_add_i32 m0, s85, 0x2000
	s_nop 0
	global_load_lds_dwordx4 v[228:229], off
	s_waitcnt vmcnt(6)
	s_waitcnt lgkmcnt(0)
	s_barrier
	s_setprio 1
	s_waitcnt lgkmcnt(0)
	v_mfma_f32_16x16x32_bf16 v[60:63], v[144:147], v[186:189], v[60:63]
	v_mfma_f32_16x16x32_bf16 v[56:59], v[160:163], v[186:189], v[56:59]
	v_mfma_f32_16x16x32_bf16 v[44:47], v[144:147], v[194:197], v[44:47]
	v_mfma_f32_16x16x32_bf16 v[40:43], v[160:163], v[194:197], v[40:43]
	v_mfma_f32_16x16x32_bf16 v[60:63], v[148:151], v[190:193], v[60:63]
	v_mfma_f32_16x16x32_bf16 v[56:59], v[164:167], v[190:193], v[56:59]
	v_mfma_f32_16x16x32_bf16 v[44:47], v[148:151], v[198:201], v[44:47]
	v_mfma_f32_16x16x32_bf16 v[40:43], v[164:167], v[198:201], v[40:43]
	v_mfma_f32_16x16x32_bf16 v[28:31], v[144:147], v[208:211], v[28:31]
	v_mfma_f32_16x16x32_bf16 v[24:27], v[160:163], v[208:211], v[24:27]
	v_mfma_f32_16x16x32_bf16 v[12:15], v[144:147], v[216:219], v[12:15]
	v_mfma_f32_16x16x32_bf16 v[8:11], v[160:163], v[216:219], v[8:11]
	v_mfma_f32_16x16x32_bf16 v[28:31], v[148:151], v[212:215], v[28:31]
	v_mfma_f32_16x16x32_bf16 v[24:27], v[164:167], v[212:215], v[24:27]
	v_lshl_add_u64 v[228:229], s[58:59], 0, v[134:135]
	s_mov_b32 m0, s53
	s_nop 0
	global_load_lds_dwordx4 v[228:229], off
	v_mfma_f32_16x16x32_bf16 v[12:15], v[148:151], v[220:223], v[12:15]
	v_mfma_f32_16x16x32_bf16 v[8:11], v[164:167], v[220:223], v[8:11]
	s_setprio 0
	s_setprio 1
	v_mfma_f32_16x16x32_bf16 v[52:55], v[168:171], v[186:189], v[52:55]
	v_mfma_f32_16x16x32_bf16 v[48:51], v[176:179], v[186:189], v[48:51]
	v_mfma_f32_16x16x32_bf16 v[36:39], v[168:171], v[194:197], v[36:39]
	v_mfma_f32_16x16x32_bf16 v[32:35], v[176:179], v[194:197], v[32:35]
	v_mfma_f32_16x16x32_bf16 v[52:55], v[172:175], v[190:193], v[52:55]
	v_mfma_f32_16x16x32_bf16 v[48:51], v[182:185], v[190:193], v[48:51]
	v_mfma_f32_16x16x32_bf16 v[36:39], v[172:175], v[198:201], v[36:39]
	v_mfma_f32_16x16x32_bf16 v[32:35], v[182:185], v[198:201], v[32:35]
	v_mfma_f32_16x16x32_bf16 v[20:23], v[168:171], v[208:211], v[20:23]
	v_mfma_f32_16x16x32_bf16 v[16:19], v[176:179], v[208:211], v[16:19]
	v_mfma_f32_16x16x32_bf16 v[4:7], v[168:171], v[216:219], v[4:7]
	v_mfma_f32_16x16x32_bf16 v[0:3], v[176:179], v[216:219], v[0:3]
	v_mfma_f32_16x16x32_bf16 v[20:23], v[172:175], v[212:215], v[20:23]
	v_mfma_f32_16x16x32_bf16 v[16:19], v[182:185], v[212:215], v[16:19]
	v_lshl_add_u64 v[230:231], s[58:59], 0, v[130:131]
	s_mov_b32 m0, s60
	s_nop 0
	global_load_lds_dwordx4 v[230:231], off
	v_mfma_f32_16x16x32_bf16 v[4:7], v[172:175], v[220:223], v[4:7]
	v_mfma_f32_16x16x32_bf16 v[0:3], v[182:185], v[220:223], v[0:3]
	s_setprio 0
	s_barrier
; #define PG8_STAGE(bufoff, gbase, voff) do { _Pragma("unroll") for (int _i = 0; _i < 2; ++_i) \
;         __builtin_amdgcn_global_load_lds((const unsigned*)((const char*)(gbase) + (voff)[_i]), (PG8_LAS unsigned*)(lds + (bufoff) + ldsw + _i * 8192), 16, 0, 0); } while (0)
; #define PG8_LDA(dst, b, h) do { _Pragma("unroll") for (int m = 0; m < 4; ++m) _Pragma("unroll") for (int k = 0; k < 2; ++k) dst[m][k] = *(const PG8_LAS bf16x8*)(lds + PG8_SA(b, h) + aoff + m * 2048 + k * 1024); } while (0)
; #define PG8_LDB(dst, b, h) do { _Pragma("unroll") for (int n = 0; n < 2; ++n) _Pragma("unroll") for (int k = 0; k < 2; ++k) dst[n][k] = *(const PG8_LAS bf16x8*)(lds + PG8_SB(b, h) + boff + n * 2048 + k * 1024); } while (0)
; #define PG8_MMA(ai, bj, At, Bt) do { __builtin_amdgcn_s_setprio(1); _Pragma("unroll") for (int m = 0; m < 4; ++m) _Pragma("unroll") for (int n = 0; n < 2; ++n) _Pragma("unroll") for (int k = 0; k < 2; ++k) \
;         acc[ai][bj][m][n] = __builtin_amdgcn_mfma_f32_16x16x32_bf16(Bt[n][k], At[m][k], acc[ai][bj][m][n], 0, 0, 0); __builtin_amdgcn_s_setprio(0); } while (0)
; #define PG8_WAIT_V(n) asm volatile("s_waitcnt vmcnt(" #n ")" ::: "memory")
; #define PG8_WAIT_L(n) asm volatile("s_waitcnt lgkmcnt(" #n ")" ::: "memory")
; #define PG8_BAR __builtin_amdgcn_s_barrier()
; #define PG8_SCHED __builtin_amdgcn_sched_barrier(0)
; template <class Epi, class Sched, bool ALIGN_EPI = false, bool SP2 = false>
; __device__ __forceinline__ void gemm_phase(PG8_LAS unsigned char* lds, const Gemm g, const Sched& S, const Epi& E) {
;     ...
;             PG8_LDB(B0, 1, 0); PG8_LDB(B1, 1, 1); PG8_SCHED; PG8_LDA(At, 1, 0); PG8_STAGE(PG8_SA(0, 1), a2 + hstep, voffA);
;             PG8_WAIT_V(8); PG8_WAIT_L(0); PG8_BAR; PG8_MMA(0, 0, At, B0); PG8_MMA(0, 1, At, B1); PG8_BAR; PG8_SCHED;
	s_add_i32 s78, 0, 0x18000
	v_add_u32_e32 v159, s78, v153
	s_add_i32 s79, 0, 0x1c000
	ds_read_b128 v[144:147], v159
	ds_read_b128 v[148:151], v159 offset:1024
	ds_read_b128 v[160:163], v159 offset:2048
	ds_read_b128 v[164:167], v159 offset:3072
	v_add_u32_e32 v159, s79, v153
	ds_read_b128 v[168:171], v159
	ds_read_b128 v[172:175], v159 offset:1024
	ds_read_b128 v[176:179], v159 offset:2048
	ds_read_b128 v[182:185], v159 offset:3072
	s_add_u32 s58, s58, 0x40000
	s_addc_u32 s59, s59, 0
	s_mov_b32 m0, s61
	v_lshl_add_u64 v[232:233], s[58:59], 0, v[134:135]
	ds_read_b128 v[186:189], v157 offset:32768
	ds_read_b128 v[190:193], v157 offset:33792
	ds_read_b128 v[194:197], v157 offset:34816
	ds_read_b128 v[198:201], v157 offset:35840
	ds_read_b128 v[208:211], v157 offset:36864
	ds_read_b128 v[212:215], v157 offset:37888
	ds_read_b128 v[216:219], v157 offset:38912
	ds_read_b128 v[220:223], v157 offset:39936
	global_load_lds_dwordx4 v[232:233], off
	v_lshl_add_u64 v[232:233], s[58:59], 0, v[130:131]
	s_mov_b32 m0, s62
	s_nop 0
	global_load_lds_dwordx4 v[232:233], off
	s_waitcnt vmcnt(8)
	s_waitcnt lgkmcnt(0)
	s_barrier
	s_setprio 1
	s_waitcnt lgkmcnt(0)
	v_mfma_f32_16x16x32_bf16 v[124:127], v[144:147], v[186:189], v[124:127]
	v_mfma_f32_16x16x32_bf16 v[120:123], v[160:163], v[186:189], v[120:123]
	v_mfma_f32_16x16x32_bf16 v[108:111], v[144:147], v[194:197], v[108:111]
	v_mfma_f32_16x16x32_bf16 v[104:107], v[160:163], v[194:197], v[104:107]
	v_mfma_f32_16x16x32_bf16 v[124:127], v[148:151], v[190:193], v[124:127]
	v_mfma_f32_16x16x32_bf16 v[120:123], v[164:167], v[190:193], v[120:123]
	v_mfma_f32_16x16x32_bf16 v[108:111], v[148:151], v[198:201], v[108:111]
	v_mfma_f32_16x16x32_bf16 v[104:107], v[164:167], v[198:201], v[104:107]
	v_mfma_f32_16x16x32_bf16 v[92:95], v[144:147], v[208:211], v[92:95]
	v_mfma_f32_16x16x32_bf16 v[88:91], v[160:163], v[208:211], v[88:91]
	v_mfma_f32_16x16x32_bf16 v[76:79], v[144:147], v[216:219], v[76:79]
	v_mfma_f32_16x16x32_bf16 v[72:75], v[160:163], v[216:219], v[72:75]
	v_mfma_f32_16x16x32_bf16 v[92:95], v[148:151], v[212:215], v[92:95]
	v_mfma_f32_16x16x32_bf16 v[88:91], v[164:167], v[212:215], v[88:91]
	v_mfma_f32_16x16x32_bf16 v[76:79], v[148:151], v[220:223], v[76:79]
	v_mfma_f32_16x16x32_bf16 v[72:75], v[164:167], v[220:223], v[72:75]
	s_setprio 0
	s_setprio 1
	v_mfma_f32_16x16x32_bf16 v[116:119], v[168:171], v[186:189], v[116:119]
	v_mfma_f32_16x16x32_bf16 v[112:115], v[176:179], v[186:189], v[112:115]
	v_mfma_f32_16x16x32_bf16 v[100:103], v[168:171], v[194:197], v[100:103]
	v_mfma_f32_16x16x32_bf16 v[96:99], v[176:179], v[194:197], v[96:99]
	v_mfma_f32_16x16x32_bf16 v[116:119], v[172:175], v[190:193], v[116:119]
	v_mfma_f32_16x16x32_bf16 v[112:115], v[182:185], v[190:193], v[112:115]
	v_mfma_f32_16x16x32_bf16 v[100:103], v[172:175], v[198:201], v[100:103]
	v_mfma_f32_16x16x32_bf16 v[96:99], v[182:185], v[198:201], v[96:99]
	v_mfma_f32_16x16x32_bf16 v[84:87], v[168:171], v[208:211], v[84:87]
	v_mfma_f32_16x16x32_bf16 v[80:83], v[176:179], v[208:211], v[80:83]
	v_mfma_f32_16x16x32_bf16 v[68:71], v[168:171], v[216:219], v[68:71]
	v_mfma_f32_16x16x32_bf16 v[64:67], v[176:179], v[216:219], v[64:67]
	v_mfma_f32_16x16x32_bf16 v[84:87], v[172:175], v[212:215], v[84:87]
	v_mfma_f32_16x16x32_bf16 v[80:83], v[182:185], v[212:215], v[80:83]
	v_mfma_f32_16x16x32_bf16 v[68:71], v[172:175], v[220:223], v[68:71]
	v_mfma_f32_16x16x32_bf16 v[64:67], v[182:185], v[220:223], v[64:67]
	s_setprio 0
	s_barrier
; #define PG8_STAGE(bufoff, gbase, voff) do { _Pragma("unroll") for (int _i = 0; _i < 2; ++_i) \
;         __builtin_amdgcn_global_load_lds((const unsigned*)((const char*)(gbase) + (voff)[_i]), (PG8_LAS unsigned*)(lds + (bufoff) + ldsw + _i * 8192), 16, 0, 0); } while (0)
; #define PG8_LDA(dst, b, h) do { _Pragma("unroll") for (int m = 0; m < 4; ++m) _Pragma("unroll") for (int k = 0; k < 2; ++k) dst[m][k] = *(const PG8_LAS bf16x8*)(lds + PG8_SA(b, h) + aoff + m * 2048 + k * 1024); } while (0)
; #define PG8_MMA(ai, bj, At, Bt) do { __builtin_amdgcn_s_setprio(1); _Pragma("unroll") for (int m = 0; m < 4; ++m) _Pragma("unroll") for (int n = 0; n < 2; ++n) _Pragma("unroll") for (int k = 0; k < 2; ++k) \
;         acc[ai][bj][m][n] = __builtin_amdgcn_mfma_f32_16x16x32_bf16(Bt[n][k], At[m][k], acc[ai][bj][m][n], 0, 0, 0); __builtin_amdgcn_s_setprio(0); } while (0)
; #define PG8_WAIT_V(n) asm volatile("s_waitcnt vmcnt(" #n ")" ::: "memory")
; #define PG8_WAIT_L(n) asm volatile("s_waitcnt lgkmcnt(" #n ")" ::: "memory")
; #define PG8_BAR __builtin_amdgcn_s_barrier()
; #define PG8_SCHED __builtin_amdgcn_sched_barrier(0)
; __device__ __forceinline__ float row_rs(const float* ssp, int row) { const unsigned long long v = ((const unsigned long long*)ssp)[row];
;     return __builtin_amdgcn_rsqf((float)v * (1.0f / 4294967296.0f) * (1.0f / 1024.0f) + RMS_EPS); }
; template <class Epi, class Sched, bool ALIGN_EPI = false, bool SP2 = false>
; __device__ __forceinline__ void gemm_phase(PG8_LAS unsigned char* lds, const Gemm g, const Sched& S, const Epi& E) {
;     ...
;             PG8_LDA(At, 1, 1); PG8_STAGE(PG8_SB(1, 0), b3, voffB); PG8_STAGE(PG8_SB(1, 1), b3 + hstep, voffB); PG8_STAGE(PG8_SA(1, 0), a3, voffA);
;             PG8_WAIT_V(8); PG8_WAIT_L(0); PG8_BAR; PG8_MMA(1, 0, At, B0); PG8_MMA(1, 1, At, B1); PG8_BAR; PG8_SCHED;
	s_add_i32 s58, s78, s33
	v_lshl_add_u64 v[224:225], v[224:225], 0, s[12:13]
	s_mov_b32 m0, s58
	ds_read_b128 v[186:189], v157 offset:49152
	ds_read_b128 v[190:193], v157 offset:50176
	ds_read_b128 v[194:197], v157 offset:51200
	ds_read_b128 v[198:201], v157 offset:52224
	ds_read_b128 v[208:211], v157 offset:53248
	ds_read_b128 v[212:215], v157 offset:54272
	ds_read_b128 v[216:219], v157 offset:55296
	ds_read_b128 v[220:223], v157 offset:56320
	global_load_lds_dwordx4 v[224:225], off
	s_add_i32 m0, s58, 0x2000
	s_add_u32 s56, s56, 0x40080
	v_lshl_add_u64 v[224:225], v[226:227], 0, s[12:13]
	s_addc_u32 s57, s57, 0
	s_add_i32 s58, s79, s33
	global_load_lds_dwordx4 v[224:225], off
	v_lshl_add_u64 v[224:225], s[56:57], 0, v[132:133]
	s_mov_b32 m0, s58
	s_nop 0
	global_load_lds_dwordx4 v[224:225], off
	v_lshl_add_u64 v[224:225], s[56:57], 0, v[128:129]
	s_add_i32 m0, s58, 0x2000
	s_nop 0
	global_load_lds_dwordx4 v[224:225], off
	s_waitcnt vmcnt(6)
	s_waitcnt lgkmcnt(0)
	s_barrier
	s_setprio 1
	s_waitcnt lgkmcnt(0)
	v_mfma_f32_16x16x32_bf16 v[60:63], v[144:147], v[186:189], v[60:63]
	v_mfma_f32_16x16x32_bf16 v[56:59], v[160:163], v[186:189], v[56:59]
	v_mfma_f32_16x16x32_bf16 v[44:47], v[144:147], v[194:197], v[44:47]
	v_mfma_f32_16x16x32_bf16 v[40:43], v[160:163], v[194:197], v[40:43]
	v_mfma_f32_16x16x32_bf16 v[60:63], v[148:151], v[190:193], v[60:63]
	v_mfma_f32_16x16x32_bf16 v[56:59], v[164:167], v[190:193], v[56:59]
	v_mfma_f32_16x16x32_bf16 v[44:47], v[148:151], v[198:201], v[44:47]
	v_mfma_f32_16x16x32_bf16 v[40:43], v[164:167], v[198:201], v[40:43]
	v_mfma_f32_16x16x32_bf16 v[28:31], v[144:147], v[208:211], v[28:31]
	v_mfma_f32_16x16x32_bf16 v[24:27], v[160:163], v[208:211], v[24:27]
	v_mfma_f32_16x16x32_bf16 v[12:15], v[144:147], v[216:219], v[12:15]
	v_mfma_f32_16x16x32_bf16 v[8:11], v[160:163], v[216:219], v[8:11]
	v_mfma_f32_16x16x32_bf16 v[28:31], v[148:151], v[212:215], v[28:31]
	v_mfma_f32_16x16x32_bf16 v[24:27], v[164:167], v[212:215], v[24:27]
	v_lshl_add_u64 v[224:225], v[228:229], 0, s[12:13]
	s_mov_b32 m0, s64
	s_nop 0
	global_load_lds_dwordx4 v[224:225], off
	v_mfma_f32_16x16x32_bf16 v[12:15], v[148:151], v[220:223], v[12:15]
	v_mfma_f32_16x16x32_bf16 v[8:11], v[164:167], v[220:223], v[8:11]
	s_setprio 0
	s_setprio 1
	v_mfma_f32_16x16x32_bf16 v[52:55], v[168:171], v[186:189], v[52:55]
	v_mfma_f32_16x16x32_bf16 v[48:51], v[176:179], v[186:189], v[48:51]
	v_mfma_f32_16x16x32_bf16 v[36:39], v[168:171], v[194:197], v[36:39]
	v_mfma_f32_16x16x32_bf16 v[32:35], v[176:179], v[194:197], v[32:35]
	v_mfma_f32_16x16x32_bf16 v[52:55], v[172:175], v[190:193], v[52:55]
	v_mfma_f32_16x16x32_bf16 v[48:51], v[182:185], v[190:193], v[48:51]
	v_mfma_f32_16x16x32_bf16 v[36:39], v[172:175], v[198:201], v[36:39]
	v_mfma_f32_16x16x32_bf16 v[32:35], v[182:185], v[198:201], v[32:35]
	v_mfma_f32_16x16x32_bf16 v[20:23], v[168:171], v[208:211], v[20:23]
	v_mfma_f32_16x16x32_bf16 v[16:19], v[176:179], v[208:211], v[16:19]
	v_mfma_f32_16x16x32_bf16 v[4:7], v[168:171], v[216:219], v[4:7]
	v_mfma_f32_16x16x32_bf16 v[0:3], v[176:179], v[216:219], v[0:3]
	v_mfma_f32_16x16x32_bf16 v[20:23], v[172:175], v[212:215], v[20:23]
	v_mfma_f32_16x16x32_bf16 v[16:19], v[182:185], v[212:215], v[16:19]
	v_lshl_add_u64 v[224:225], v[230:231], 0, s[12:13]
	s_mov_b32 m0, s65
	s_nop 0
	global_load_lds_dwordx4 v[224:225], off
	v_mfma_f32_16x16x32_bf16 v[4:7], v[172:175], v[220:223], v[4:7]
	v_mfma_f32_16x16x32_bf16 v[0:3], v[182:185], v[220:223], v[0:3]
	s_setprio 0
	s_barrier
	s_add_i32 s84, s84, 2
	s_add_u32 s54, s54, 0x100
	s_addc_u32 s55, s55, 0
	s_add_u32 s82, s82, 0x100
	s_addc_u32 s83, s83, 0
	s_cmp_gt_u32 s84, 13
	s_cbranch_scc0 .LBB0_1119
	v_lshl_add_u32 v144, s52, 8, v152
	v_ashrrev_i32_e32 v145, 31, v144
	v_lshl_add_u64 v[150:151], v[144:145], 3, s[36:37]
	global_load_dwordx2 v[182:183], v[150:151], off
	global_load_dwordx2 v[184:185], v[150:151], off offset:128
	global_load_dwordx2 v[186:187], v[150:151], off offset:256
	global_load_dwordx2 v[188:189], v[150:151], off offset:384
	global_load_dwordx2 v[190:191], v[150:151], off offset:1024
	global_load_dwordx2 v[192:193], v[150:151], off offset:1152
	global_load_dwordx2 v[194:195], v[150:151], off offset:1280
	global_load_dwordx2 v[196:197], v[150:151], off offset:1408
	s_and_b64 vcc, exec, s[38:39]
	s_cbranch_vccz .LBB0_1122
	s_barrier

; #define PG8_STAGE(bufoff, gbase, voff) do { _Pragma("unroll") for (int _i = 0; _i < 2; ++_i) \
;         __builtin_amdgcn_global_load_lds((const unsigned*)((const char*)(gbase) + (voff)[_i]), (PG8_LAS unsigned*)(lds + (bufoff) + ldsw + _i * 8192), 16, 0, 0); } while (0)
; #define PG8_LDA(dst, b, h) do { _Pragma("unroll") for (int m = 0; m < 4; ++m) _Pragma("unroll") for (int k = 0; k < 2; ++k) dst[m][k] = *(const PG8_LAS bf16x8*)(lds + PG8_SA(b, h) + aoff + m * 2048 + k * 1024); } while (0)
; #define PG8_LDB(dst, b, h) do { _Pragma("unroll") for (int n = 0; n < 2; ++n) _Pragma("unroll") for (int k = 0; k < 2; ++k) dst[n][k] = *(const PG8_LAS bf16x8*)(lds + PG8_SB(b, h) + boff + n * 2048 + k * 1024); } while (0)
; #define PG8_WAIT_V(n) asm volatile("s_waitcnt vmcnt(" #n ")" ::: "memory")
; #define PG8_WAIT_L(n) asm volatile("s_waitcnt lgkmcnt(" #n ")" ::: "memory")
; #define PG8_BAR __builtin_amdgcn_s_barrier()
; #define PG8_SCHED __builtin_amdgcn_sched_barrier(0)
; template <class Epi, class Sched, bool ALIGN_EPI = false, bool SP2 = false>
; __device__ __forceinline__ void gemm_phase(PG8_LAS unsigned char* lds, const Gemm g, const Sched& S, const Epi& E) {
;     ...
;         const bool has_next = S.next(ui + 1, nxt);
;         const char* nA = has_next ? (const char*)g.A + (size_t)nxt.pm * tstep : cA; const char* nB = has_next ? (const char*)g.Bt + (size_t)nxt.pn * tstep : cB;
;         for (int t = 0; t < nt; t += 2) {
;             const bool last = (t == nt - 2);
;             const char* a1 = cA + (size_t)(t + 1) * kstep;
;             const char* a2 = last ? nA : cA + (size_t)(t + 2) * kstep; const char* b2 = last ? nB : cB + (size_t)(t + 2) * kstep;
;             const char* a3 = a2 + kstep; const char* b3 = b2 + kstep;
;             if (last && has_next) S.a_ready(nxt);
;             if constexpr (SP2) {
;             PG8_LDB(B0, 0, 0); PG8_LDB(B1, 0, 1); PG8_SCHED; PG8_LDA(At, 0, 0); PG8_STAGE(PG8_SA(1, 1), a1 + hstep, voffA);
;             PG8_WAIT_V(8); PG8_WAIT_L(0); PG8_BAR; PG8_MMA(0, 0, At, B0); PG8_MMA(0, 1, At, B1); PG8_BAR; PG8_SCHED;
;             PG8_LDA(At, 0, 1); PG8_STAGE(PG8_SB(0, 0), b2, voffB); PG8_STAGE(PG8_SB(0, 1), b2 + hstep, voffB); PG8_STAGE(PG8_SA(0, 0), a2, voffA);
;             PG8_WAIT_V(8); PG8_WAIT_L(0); PG8_BAR; PG8_MMA(1, 0, At, B0); PG8_MMA(1, 1, At, B1); PG8_BAR; PG8_SCHED;
.LBB0_1196:
	s_add_u32 s82, s52, 0x100
	s_addc_u32 s83, s53, 0
	s_mov_b32 s84, -2
	s_waitcnt lgkmcnt(0)
	ds_read_b128 v[144:147], v151
	ds_read_b128 v[156:159], v151 offset:1024
	ds_read_b128 v[160:163], v151 offset:2048
	ds_read_b128 v[164:167], v151 offset:3072
	ds_read_b128 v[168:171], v152
	ds_read_b128 v[172:175], v152 offset:1024
	ds_read_b128 v[176:179], v152 offset:2048
	ds_read_b128 v[182:185], v152 offset:3072
	s_add_u32 s52, s50, 0x100
	s_addc_u32 s53, s51, 0
	s_cmp_eq_u32 s84, 40
	s_cselect_b32 s57, s1, s53
	s_cselect_b32 s56, s0, s52
	s_cselect_b32 s55, s49, s83
	s_cselect_b32 s54, s48, s82
	v_lshl_add_u64 v[224:225], s[50:51], 0, v[136:137]
	s_add_i32 m0, s34, 0xc000
	ds_read_b128 v[186:189], v153
	ds_read_b128 v[190:193], v153 offset:1024
	ds_read_b128 v[194:197], v153 offset:2048
	ds_read_b128 v[198:201], v153 offset:3072
	ds_read_b128 v[208:211], v153 offset:4096
	ds_read_b128 v[212:215], v153 offset:5120
	ds_read_b128 v[216:219], v153 offset:6144
	ds_read_b128 v[220:223], v153 offset:7168
	global_load_lds_dwordx4 v[224:225], off
	v_lshl_add_u64 v[224:225], s[50:51], 0, v[138:139]
	s_add_i32 m0, s34, 0xe000
	s_nop 0
	global_load_lds_dwordx4 v[224:225], off
	s_waitcnt vmcnt(8)
	s_waitcnt lgkmcnt(0)
	s_barrier
	s_setprio 1
	s_waitcnt lgkmcnt(0)
	v_mfma_f32_16x16x32_bf16 v[124:127], v[144:147], v[186:189], 0
	v_mfma_f32_16x16x32_bf16 v[120:123], v[160:163], v[186:189], 0
	v_mfma_f32_16x16x32_bf16 v[108:111], v[144:147], v[194:197], 0
	v_mfma_f32_16x16x32_bf16 v[104:107], v[160:163], v[194:197], 0
	v_mfma_f32_16x16x32_bf16 v[124:127], v[156:159], v[190:193], v[124:127]
	v_mfma_f32_16x16x32_bf16 v[120:123], v[164:167], v[190:193], v[120:123]
	v_mfma_f32_16x16x32_bf16 v[108:111], v[156:159], v[198:201], v[108:111]
	v_mfma_f32_16x16x32_bf16 v[104:107], v[164:167], v[198:201], v[104:107]
	v_mfma_f32_16x16x32_bf16 v[92:95], v[144:147], v[208:211], 0
	v_mfma_f32_16x16x32_bf16 v[88:91], v[160:163], v[208:211], 0
	v_mfma_f32_16x16x32_bf16 v[76:79], v[144:147], v[216:219], 0
	v_mfma_f32_16x16x32_bf16 v[72:75], v[160:163], v[216:219], 0
	v_mfma_f32_16x16x32_bf16 v[92:95], v[156:159], v[212:215], v[92:95]
	v_mfma_f32_16x16x32_bf16 v[88:91], v[164:167], v[212:215], v[88:91]
	v_mfma_f32_16x16x32_bf16 v[76:79], v[156:159], v[220:223], v[76:79]
	v_mfma_f32_16x16x32_bf16 v[72:75], v[164:167], v[220:223], v[72:75]
	s_setprio 0
	s_setprio 1
	v_mfma_f32_16x16x32_bf16 v[116:119], v[168:171], v[186:189], 0
	v_mfma_f32_16x16x32_bf16 v[112:115], v[176:179], v[186:189], 0
	v_mfma_f32_16x16x32_bf16 v[100:103], v[168:171], v[194:197], 0
	v_mfma_f32_16x16x32_bf16 v[96:99], v[176:179], v[194:197], 0
	v_mfma_f32_16x16x32_bf16 v[116:119], v[172:175], v[190:193], v[116:119]
	v_mfma_f32_16x16x32_bf16 v[112:115], v[182:185], v[190:193], v[112:115]
	v_mfma_f32_16x16x32_bf16 v[100:103], v[172:175], v[198:201], v[100:103]
	v_mfma_f32_16x16x32_bf16 v[96:99], v[182:185], v[198:201], v[96:99]
	v_mfma_f32_16x16x32_bf16 v[84:87], v[168:171], v[208:211], 0
	v_mfma_f32_16x16x32_bf16 v[80:83], v[176:179], v[208:211], 0
	v_mfma_f32_16x16x32_bf16 v[68:71], v[168:171], v[216:219], 0
	v_mfma_f32_16x16x32_bf16 v[64:67], v[176:179], v[216:219], 0
	v_mfma_f32_16x16x32_bf16 v[84:87], v[172:175], v[212:215], v[84:87]
	v_mfma_f32_16x16x32_bf16 v[80:83], v[182:185], v[212:215], v[80:83]
	v_mfma_f32_16x16x32_bf16 v[68:71], v[172:175], v[220:223], v[68:71]
	v_mfma_f32_16x16x32_bf16 v[64:67], v[182:185], v[220:223], v[64:67]
	s_setprio 0
	s_barrier
	s_add_i32 s50, s64, s33
	v_lshl_add_u64 v[224:225], s[54:55], 0, v[130:131]
	s_mov_b32 m0, s50
	ds_read_b128 v[186:189], v153 offset:16384
	ds_read_b128 v[190:193], v153 offset:17408
	ds_read_b128 v[194:197], v153 offset:18432
	ds_read_b128 v[198:201], v153 offset:19456
	ds_read_b128 v[208:211], v153 offset:20480
	ds_read_b128 v[212:215], v153 offset:21504
	ds_read_b128 v[216:219], v153 offset:22528
	ds_read_b128 v[220:223], v153 offset:23552
	global_load_lds_dwordx4 v[224:225], off
	s_add_i32 m0, s50, 0x2000
	s_add_u32 s50, s54, 0xb0000
	v_lshl_add_u64 v[226:227], s[54:55], 0, v[134:135]
	s_addc_u32 s51, s55, 0
	s_add_i32 s78, s65, s33
	global_load_lds_dwordx4 v[226:227], off
	v_lshl_add_u64 v[228:229], s[50:51], 0, v[130:131]
	s_mov_b32 m0, s78
	global_load_lds_dwordx4 v[228:229], off
	v_lshl_add_u64 v[228:229], s[50:51], 0, v[134:135]
	s_add_i32 m0, s78, 0x2000
	s_nop 0
	global_load_lds_dwordx4 v[228:229], off
	s_waitcnt vmcnt(6)
	s_waitcnt lgkmcnt(0)
	s_barrier
; #define PG8_STAGE(bufoff, gbase, voff) do { _Pragma("unroll") for (int _i = 0; _i < 2; ++_i) \
;         __builtin_amdgcn_global_load_lds((const unsigned*)((const char*)(gbase) + (voff)[_i]), (PG8_LAS unsigned*)(lds + (bufoff) + ldsw + _i * 8192), 16, 0, 0); } while (0)
; #define PG8_LDA(dst, b, h) do { _Pragma("unroll") for (int m = 0; m < 4; ++m) _Pragma("unroll") for (int k = 0; k < 2; ++k) dst[m][k] = *(const PG8_LAS bf16x8*)(lds + PG8_SA(b, h) + aoff + m * 2048 + k * 1024); } while (0)
; #define PG8_LDB(dst, b, h) do { _Pragma("unroll") for (int n = 0; n < 2; ++n) _Pragma("unroll") for (int k = 0; k < 2; ++k) dst[n][k] = *(const PG8_LAS bf16x8*)(lds + PG8_SB(b, h) + boff + n * 2048 + k * 1024); } while (0)
; #define PG8_MMA(ai, bj, At, Bt) do { __builtin_amdgcn_s_setprio(1); _Pragma("unroll") for (int m = 0; m < 4; ++m) _Pragma("unroll") for (int n = 0; n < 2; ++n) _Pragma("unroll") for (int k = 0; k < 2; ++k) \
;         acc[ai][bj][m][n] = __builtin_amdgcn_mfma_f32_16x16x32_bf16(Bt[n][k], At[m][k], acc[ai][bj][m][n], 0, 0, 0); __builtin_amdgcn_s_setprio(0); } while (0)
; #define PG8_WAIT_V(n) asm volatile("s_waitcnt vmcnt(" #n ")" ::: "memory")
; #define PG8_WAIT_L(n) asm volatile("s_waitcnt lgkmcnt(" #n ")" ::: "memory")
; #define PG8_BAR __builtin_amdgcn_s_barrier()
; #define PG8_SCHED __builtin_amdgcn_sched_barrier(0)
; template <class Epi, class Sched, bool ALIGN_EPI = false, bool SP2 = false>
; __device__ __forceinline__ void gemm_phase(PG8_LAS unsigned char* lds, const Gemm g, const Sched& S, const Epi& E) {
;     ...
;             PG8_LDA(At, 0, 1); PG8_STAGE(PG8_SB(0, 0), b2, voffB); PG8_STAGE(PG8_SB(0, 1), b2 + hstep, voffB); PG8_STAGE(PG8_SA(0, 0), a2, voffA);
;             PG8_WAIT_V(8); PG8_WAIT_L(0); PG8_BAR; PG8_MMA(1, 0, At, B0); PG8_MMA(1, 1, At, B1); PG8_BAR; PG8_SCHED;
;             PG8_LDB(B0, 1, 0); PG8_LDB(B1, 1, 1); PG8_SCHED; PG8_LDA(At, 1, 0); PG8_STAGE(PG8_SA(0, 1), a2 + hstep, voffA);
;             PG8_WAIT_V(8); PG8_WAIT_L(0); PG8_BAR; PG8_MMA(0, 0, At, B0); PG8_MMA(0, 1, At, B1); PG8_BAR; PG8_SCHED;
	s_setprio 1
	s_waitcnt lgkmcnt(0)
	v_mfma_f32_16x16x32_bf16 v[60:63], v[144:147], v[186:189], 0
	v_mfma_f32_16x16x32_bf16 v[56:59], v[160:163], v[186:189], 0
	v_mfma_f32_16x16x32_bf16 v[44:47], v[144:147], v[194:197], 0
	v_mfma_f32_16x16x32_bf16 v[40:43], v[160:163], v[194:197], 0
	v_mfma_f32_16x16x32_bf16 v[60:63], v[156:159], v[190:193], v[60:63]
	v_mfma_f32_16x16x32_bf16 v[56:59], v[164:167], v[190:193], v[56:59]
	v_mfma_f32_16x16x32_bf16 v[44:47], v[156:159], v[198:201], v[44:47]
	v_mfma_f32_16x16x32_bf16 v[40:43], v[164:167], v[198:201], v[40:43]
	v_mfma_f32_16x16x32_bf16 v[28:31], v[144:147], v[208:211], 0
	v_mfma_f32_16x16x32_bf16 v[24:27], v[160:163], v[208:211], 0
	v_mfma_f32_16x16x32_bf16 v[12:15], v[144:147], v[216:219], 0
	v_mfma_f32_16x16x32_bf16 v[8:11], v[160:163], v[216:219], 0
	v_mfma_f32_16x16x32_bf16 v[28:31], v[156:159], v[212:215], v[28:31]
	v_mfma_f32_16x16x32_bf16 v[24:27], v[164:167], v[212:215], v[24:27]
	v_lshl_add_u64 v[228:229], s[56:57], 0, v[128:129]
	s_mov_b32 m0, s34
	s_nop 0
	global_load_lds_dwordx4 v[228:229], off
	v_mfma_f32_16x16x32_bf16 v[12:15], v[156:159], v[220:223], v[12:15]
	v_mfma_f32_16x16x32_bf16 v[8:11], v[164:167], v[220:223], v[8:11]
	s_setprio 0
	s_setprio 1
	v_mfma_f32_16x16x32_bf16 v[52:55], v[168:171], v[186:189], 0
	v_mfma_f32_16x16x32_bf16 v[48:51], v[176:179], v[186:189], 0
	v_mfma_f32_16x16x32_bf16 v[36:39], v[168:171], v[194:197], 0
	v_mfma_f32_16x16x32_bf16 v[32:35], v[176:179], v[194:197], 0
	v_mfma_f32_16x16x32_bf16 v[52:55], v[172:175], v[190:193], v[52:55]
	v_mfma_f32_16x16x32_bf16 v[48:51], v[182:185], v[190:193], v[48:51]
	v_mfma_f32_16x16x32_bf16 v[36:39], v[172:175], v[198:201], v[36:39]
	v_mfma_f32_16x16x32_bf16 v[32:35], v[182:185], v[198:201], v[32:35]
	v_mfma_f32_16x16x32_bf16 v[20:23], v[168:171], v[208:211], 0
	v_mfma_f32_16x16x32_bf16 v[16:19], v[176:179], v[208:211], 0
	v_mfma_f32_16x16x32_bf16 v[4:7], v[168:171], v[216:219], 0
	v_mfma_f32_16x16x32_bf16 v[0:3], v[176:179], v[216:219], 0
	v_mfma_f32_16x16x32_bf16 v[20:23], v[172:175], v[212:215], v[20:23]
	v_mfma_f32_16x16x32_bf16 v[16:19], v[182:185], v[212:215], v[16:19]
	v_lshl_add_u64 v[230:231], s[56:57], 0, v[132:133]
	s_mov_b32 m0, s58
	s_nop 0
	global_load_lds_dwordx4 v[230:231], off
	v_mfma_f32_16x16x32_bf16 v[4:7], v[172:175], v[220:223], v[4:7]
	v_mfma_f32_16x16x32_bf16 v[0:3], v[182:185], v[220:223], v[0:3]
	s_setprio 0
	s_barrier
	s_add_i32 s78, 0, 0x18000
	v_add_u32_e32 v155, s78, v149
	s_add_i32 s79, 0, 0x1c000
	ds_read_b128 v[144:147], v155
	ds_read_b128 v[156:159], v155 offset:1024
	ds_read_b128 v[160:163], v155 offset:2048
	ds_read_b128 v[164:167], v155 offset:3072
	v_add_u32_e32 v155, s79, v149
	ds_read_b128 v[168:171], v155
	ds_read_b128 v[172:175], v155 offset:1024
	ds_read_b128 v[176:179], v155 offset:2048
	ds_read_b128 v[182:185], v155 offset:3072
	s_add_u32 s50, s56, 0xb0000
	s_addc_u32 s51, s57, 0
	s_mov_b32 m0, s59
	v_lshl_add_u64 v[232:233], s[50:51], 0, v[128:129]
	ds_read_b128 v[186:189], v153 offset:32768
	ds_read_b128 v[190:193], v153 offset:33792
	ds_read_b128 v[194:197], v153 offset:34816
	ds_read_b128 v[198:201], v153 offset:35840
	ds_read_b128 v[208:211], v153 offset:36864
	ds_read_b128 v[212:215], v153 offset:37888
	ds_read_b128 v[216:219], v153 offset:38912
	ds_read_b128 v[220:223], v153 offset:39936
	global_load_lds_dwordx4 v[232:233], off
	v_lshl_add_u64 v[232:233], s[50:51], 0, v[132:133]
	s_mov_b32 m0, s60
	s_nop 0
	global_load_lds_dwordx4 v[232:233], off
	s_waitcnt vmcnt(8)
	s_waitcnt lgkmcnt(0)
	s_barrier
	s_setprio 1
	s_waitcnt lgkmcnt(0)
	v_mfma_f32_16x16x32_bf16 v[124:127], v[144:147], v[186:189], v[124:127]
	v_mfma_f32_16x16x32_bf16 v[120:123], v[160:163], v[186:189], v[120:123]
	v_mfma_f32_16x16x32_bf16 v[108:111], v[144:147], v[194:197], v[108:111]
	v_mfma_f32_16x16x32_bf16 v[104:107], v[160:163], v[194:197], v[104:107]
	v_mfma_f32_16x16x32_bf16 v[124:127], v[156:159], v[190:193], v[124:127]
	v_mfma_f32_16x16x32_bf16 v[120:123], v[164:167], v[190:193], v[120:123]
	v_mfma_f32_16x16x32_bf16 v[108:111], v[156:159], v[198:201], v[108:111]
	v_mfma_f32_16x16x32_bf16 v[104:107], v[164:167], v[198:201], v[104:107]
	v_mfma_f32_16x16x32_bf16 v[92:95], v[144:147], v[208:211], v[92:95]
	v_mfma_f32_16x16x32_bf16 v[88:91], v[160:163], v[208:211], v[88:91]
	v_mfma_f32_16x16x32_bf16 v[76:79], v[144:147], v[216:219], v[76:79]
	v_mfma_f32_16x16x32_bf16 v[72:75], v[160:163], v[216:219], v[72:75]
	v_mfma_f32_16x16x32_bf16 v[92:95], v[156:159], v[212:215], v[92:95]
	v_mfma_f32_16x16x32_bf16 v[88:91], v[164:167], v[212:215], v[88:91]
	v_mfma_f32_16x16x32_bf16 v[76:79], v[156:159], v[220:223], v[76:79]
	v_mfma_f32_16x16x32_bf16 v[72:75], v[164:167], v[220:223], v[72:75]
	s_setprio 0
	s_setprio 1
	v_mfma_f32_16x16x32_bf16 v[116:119], v[168:171], v[186:189], v[116:119]
	v_mfma_f32_16x16x32_bf16 v[112:115], v[176:179], v[186:189], v[112:115]
	v_mfma_f32_16x16x32_bf16 v[100:103], v[168:171], v[194:197], v[100:103]
	v_mfma_f32_16x16x32_bf16 v[96:99], v[176:179], v[194:197], v[96:99]
	v_mfma_f32_16x16x32_bf16 v[116:119], v[172:175], v[190:193], v[116:119]
	v_mfma_f32_16x16x32_bf16 v[112:115], v[182:185], v[190:193], v[112:115]
	v_mfma_f32_16x16x32_bf16 v[100:103], v[172:175], v[198:201], v[100:103]
	v_mfma_f32_16x16x32_bf16 v[96:99], v[182:185], v[198:201], v[96:99]
	v_mfma_f32_16x16x32_bf16 v[84:87], v[168:171], v[208:211], v[84:87]
	v_mfma_f32_16x16x32_bf16 v[80:83], v[176:179], v[208:211], v[80:83]
	v_mfma_f32_16x16x32_bf16 v[68:71], v[168:171], v[216:219], v[68:71]
	v_mfma_f32_16x16x32_bf16 v[64:67], v[176:179], v[216:219], v[64:67]
	v_mfma_f32_16x16x32_bf16 v[84:87], v[172:175], v[212:215], v[84:87]
	v_mfma_f32_16x16x32_bf16 v[80:83], v[182:185], v[212:215], v[80:83]
	v_mfma_f32_16x16x32_bf16 v[68:71], v[172:175], v[220:223], v[68:71]
	v_mfma_f32_16x16x32_bf16 v[64:67], v[182:185], v[220:223], v[64:67]
	s_setprio 0
	s_barrier
; #define PG8_STAGE(bufoff, gbase, voff) do { _Pragma("unroll") for (int _i = 0; _i < 2; ++_i) \
;         __builtin_amdgcn_global_load_lds((const unsigned*)((const char*)(gbase) + (voff)[_i]), (PG8_LAS unsigned*)(lds + (bufoff) + ldsw + _i * 8192), 16, 0, 0); } while (0)
; #define PG8_LDA(dst, b, h) do { _Pragma("unroll") for (int m = 0; m < 4; ++m) _Pragma("unroll") for (int k = 0; k < 2; ++k) dst[m][k] = *(const PG8_LAS bf16x8*)(lds + PG8_SA(b, h) + aoff + m * 2048 + k * 1024); } while (0)
; #define PG8_LDB(dst, b, h) do { _Pragma("unroll") for (int n = 0; n < 2; ++n) _Pragma("unroll") for (int k = 0; k < 2; ++k) dst[n][k] = *(const PG8_LAS bf16x8*)(lds + PG8_SB(b, h) + boff + n * 2048 + k * 1024); } while (0)
; #define PG8_WAIT_V(n) asm volatile("s_waitcnt vmcnt(" #n ")" ::: "memory")
; #define PG8_WAIT_L(n) asm volatile("s_waitcnt lgkmcnt(" #n ")" ::: "memory")
; #define PG8_BAR __builtin_amdgcn_s_barrier()
; template <class Epi, class Sched, bool ALIGN_EPI = false, bool SP2 = false>
; __device__ __forceinline__ void gemm_phase(PG8_LAS unsigned char* lds, const Gemm g, const Sched& S, const Epi& E) {
;     ...
;         for (int t = 0; t < nt; t += 2) {
;             const bool last = (t == nt - 2);
;             const char* a1 = cA + (size_t)(t + 1) * kstep;
;             const char* a2 = last ? nA : cA + (size_t)(t + 2) * kstep; const char* b2 = last ? nB : cB + (size_t)(t + 2) * kstep;
;             const char* a3 = a2 + kstep; const char* b3 = b2 + kstep;
;             if (last && has_next) S.a_ready(nxt);
;             if constexpr (SP2) {
;             PG8_LDB(B0, 0, 0); PG8_LDB(B1, 0, 1); PG8_SCHED; PG8_LDA(At, 0, 0); PG8_STAGE(PG8_SA(1, 1), a1 + hstep, voffA);
;             PG8_WAIT_V(8); PG8_WAIT_L(0); PG8_BAR; PG8_MMA(0, 0, At, B0); PG8_MMA(0, 1, At, B1); PG8_BAR; PG8_SCHED;
;             PG8_LDA(At, 0, 1); PG8_STAGE(PG8_SB(0, 0), b2, voffB); PG8_STAGE(PG8_SB(0, 1), b2 + hstep, voffB); PG8_STAGE(PG8_SA(0, 0), a2, voffA);
;             PG8_WAIT_V(8); PG8_WAIT_L(0); PG8_BAR; PG8_MMA(1, 0, At, B0); PG8_MMA(1, 1, At, B1); PG8_BAR; PG8_SCHED;
;     ...
;             PG8_LDA(At, 1, 1); PG8_STAGE(PG8_SB(1, 0), b3, voffB); PG8_STAGE(PG8_SB(1, 1), b3 + hstep, voffB); PG8_STAGE(PG8_SA(1, 0), a3, voffA);
;             PG8_WAIT_V(8); PG8_WAIT_L(0); PG8_BAR; PG8_MMA(1, 0, At, B0); PG8_MMA(1, 1, At, B1); PG8_BAR; PG8_SCHED;
	s_add_i32 s50, s78, s33
	v_lshl_add_u64 v[224:225], v[224:225], 0, s[42:43]
	s_mov_b32 m0, s50
	ds_read_b128 v[186:189], v153 offset:49152
	ds_read_b128 v[190:193], v153 offset:50176
	ds_read_b128 v[194:197], v153 offset:51200
	ds_read_b128 v[198:201], v153 offset:52224
	ds_read_b128 v[208:211], v153 offset:53248
	ds_read_b128 v[212:215], v153 offset:54272
	ds_read_b128 v[216:219], v153 offset:55296
	ds_read_b128 v[220:223], v153 offset:56320
	global_load_lds_dwordx4 v[224:225], off
	s_add_i32 m0, s50, 0x2000
	s_add_u32 s50, s54, 0xb0080
	v_lshl_add_u64 v[224:225], v[226:227], 0, s[42:43]
	s_addc_u32 s51, s55, 0
	s_add_i32 s54, s79, s33
	global_load_lds_dwordx4 v[224:225], off
	v_lshl_add_u64 v[224:225], s[50:51], 0, v[130:131]
	s_mov_b32 m0, s54
	s_nop 0
	global_load_lds_dwordx4 v[224:225], off
	v_lshl_add_u64 v[224:225], s[50:51], 0, v[134:135]
	s_add_i32 m0, s54, 0x2000
	s_nop 0
	global_load_lds_dwordx4 v[224:225], off
	s_waitcnt vmcnt(6)
	s_waitcnt lgkmcnt(0)
	s_barrier
	s_setprio 1
	s_waitcnt lgkmcnt(0)
	v_mfma_f32_16x16x32_bf16 v[60:63], v[144:147], v[186:189], v[60:63]
	v_mfma_f32_16x16x32_bf16 v[56:59], v[160:163], v[186:189], v[56:59]
	v_mfma_f32_16x16x32_bf16 v[44:47], v[144:147], v[194:197], v[44:47]
	v_mfma_f32_16x16x32_bf16 v[40:43], v[160:163], v[194:197], v[40:43]
	v_mfma_f32_16x16x32_bf16 v[60:63], v[156:159], v[190:193], v[60:63]
	v_mfma_f32_16x16x32_bf16 v[56:59], v[164:167], v[190:193], v[56:59]
	v_mfma_f32_16x16x32_bf16 v[44:47], v[156:159], v[198:201], v[44:47]
	v_mfma_f32_16x16x32_bf16 v[40:43], v[164:167], v[198:201], v[40:43]
	v_mfma_f32_16x16x32_bf16 v[28:31], v[144:147], v[208:211], v[28:31]
	v_mfma_f32_16x16x32_bf16 v[24:27], v[160:163], v[208:211], v[24:27]
	v_mfma_f32_16x16x32_bf16 v[12:15], v[144:147], v[216:219], v[12:15]
	v_mfma_f32_16x16x32_bf16 v[8:11], v[160:163], v[216:219], v[8:11]
	v_mfma_f32_16x16x32_bf16 v[28:31], v[156:159], v[212:215], v[28:31]
	v_mfma_f32_16x16x32_bf16 v[24:27], v[164:167], v[212:215], v[24:27]
	v_lshl_add_u64 v[224:225], v[228:229], 0, s[42:43]
	s_mov_b32 m0, s62
	s_nop 0
	global_load_lds_dwordx4 v[224:225], off
	v_mfma_f32_16x16x32_bf16 v[12:15], v[156:159], v[220:223], v[12:15]
	v_mfma_f32_16x16x32_bf16 v[8:11], v[164:167], v[220:223], v[8:11]
	s_setprio 0
	s_setprio 1
	v_mfma_f32_16x16x32_bf16 v[52:55], v[168:171], v[186:189], v[52:55]
	v_mfma_f32_16x16x32_bf16 v[48:51], v[176:179], v[186:189], v[48:51]
	v_mfma_f32_16x16x32_bf16 v[36:39], v[168:171], v[194:197], v[36:39]
	v_mfma_f32_16x16x32_bf16 v[32:35], v[176:179], v[194:197], v[32:35]
	v_mfma_f32_16x16x32_bf16 v[52:55], v[172:175], v[190:193], v[52:55]
	v_mfma_f32_16x16x32_bf16 v[48:51], v[182:185], v[190:193], v[48:51]
	v_mfma_f32_16x16x32_bf16 v[36:39], v[172:175], v[198:201], v[36:39]
	v_mfma_f32_16x16x32_bf16 v[32:35], v[182:185], v[198:201], v[32:35]
	v_mfma_f32_16x16x32_bf16 v[20:23], v[168:171], v[208:211], v[20:23]
	v_mfma_f32_16x16x32_bf16 v[16:19], v[176:179], v[208:211], v[16:19]
	v_mfma_f32_16x16x32_bf16 v[4:7], v[168:171], v[216:219], v[4:7]
	v_mfma_f32_16x16x32_bf16 v[0:3], v[176:179], v[216:219], v[0:3]
	v_mfma_f32_16x16x32_bf16 v[20:23], v[172:175], v[212:215], v[20:23]
	v_mfma_f32_16x16x32_bf16 v[16:19], v[182:185], v[212:215], v[16:19]
	v_lshl_add_u64 v[224:225], v[230:231], 0, s[42:43]
	s_mov_b32 m0, s63
	s_nop 0
	global_load_lds_dwordx4 v[224:225], off
	v_mfma_f32_16x16x32_bf16 v[4:7], v[172:175], v[220:223], v[4:7]
	v_mfma_f32_16x16x32_bf16 v[0:3], v[182:185], v[220:223], v[0:3]
	s_setprio 0
	s_barrier
	s_add_i32 s84, s84, 2
	s_add_u32 s82, s82, 0x100
	s_addc_u32 s83, s83, 0
	s_mov_b64 s[50:51], s[52:53]
.LBB0_1197:
	ds_read_b128 v[144:147], v151
	ds_read_b128 v[156:159], v151 offset:1024
	ds_read_b128 v[160:163], v151 offset:2048
	ds_read_b128 v[164:167], v151 offset:3072
	ds_read_b128 v[168:171], v152
	ds_read_b128 v[172:175], v152 offset:1024
	ds_read_b128 v[176:179], v152 offset:2048
	ds_read_b128 v[182:185], v152 offset:3072
	s_add_u32 s52, s50, 0x100
	s_addc_u32 s53, s51, 0
	s_cmp_eq_u32 s84, 40
	s_cselect_b32 s57, s1, s53
	s_cselect_b32 s56, s0, s52
	s_cselect_b32 s55, s49, s83
	s_cselect_b32 s54, s48, s82
	v_lshl_add_u64 v[224:225], s[50:51], 0, v[136:137]
	s_add_i32 m0, s34, 0xc000
	ds_read_b128 v[186:189], v153
	ds_read_b128 v[190:193], v153 offset:1024
	ds_read_b128 v[194:197], v153 offset:2048
	ds_read_b128 v[198:201], v153 offset:3072
	ds_read_b128 v[208:211], v153 offset:4096
	ds_read_b128 v[212:215], v153 offset:5120
	ds_read_b128 v[216:219], v153 offset:6144
	ds_read_b128 v[220:223], v153 offset:7168
	global_load_lds_dwordx4 v[224:225], off
	v_lshl_add_u64 v[224:225], s[50:51], 0, v[138:139]
	s_add_i32 m0, s34, 0xe000
	s_nop 0
	global_load_lds_dwordx4 v[224:225], off
	s_waitcnt vmcnt(8)
	s_waitcnt lgkmcnt(0)
	s_barrier
; #define PG8_STAGE(bufoff, gbase, voff) do { _Pragma("unroll") for (int _i = 0; _i < 2; ++_i) \
;         __builtin_amdgcn_global_load_lds((const unsigned*)((const char*)(gbase) + (voff)[_i]), (PG8_LAS unsigned*)(lds + (bufoff) + ldsw + _i * 8192), 16, 0, 0); } while (0)
; #define PG8_LDA(dst, b, h) do { _Pragma("unroll") for (int m = 0; m < 4; ++m) _Pragma("unroll") for (int k = 0; k < 2; ++k) dst[m][k] = *(const PG8_LAS bf16x8*)(lds + PG8_SA(b, h) + aoff + m * 2048 + k * 1024); } while (0)
; #define PG8_LDB(dst, b, h) do { _Pragma("unroll") for (int n = 0; n < 2; ++n) _Pragma("unroll") for (int k = 0; k < 2; ++k) dst[n][k] = *(const PG8_LAS bf16x8*)(lds + PG8_SB(b, h) + boff + n * 2048 + k * 1024); } while (0)
; #define PG8_MMA(ai, bj, At, Bt) do { __builtin_amdgcn_s_setprio(1); _Pragma("unroll") for (int m = 0; m < 4; ++m) _Pragma("unroll") for (int n = 0; n < 2; ++n) _Pragma("unroll") for (int k = 0; k < 2; ++k) \
;         acc[ai][bj][m][n] = __builtin_amdgcn_mfma_f32_16x16x32_bf16(Bt[n][k], At[m][k], acc[ai][bj][m][n], 0, 0, 0); __builtin_amdgcn_s_setprio(0); } while (0)
; #define PG8_WAIT_V(n) asm volatile("s_waitcnt vmcnt(" #n ")" ::: "memory")
; #define PG8_WAIT_L(n) asm volatile("s_waitcnt lgkmcnt(" #n ")" ::: "memory")
; #define PG8_BAR __builtin_amdgcn_s_barrier()
; #define PG8_SCHED __builtin_amdgcn_sched_barrier(0)
; template <class Epi, class Sched, bool ALIGN_EPI = false, bool SP2 = false>
; __device__ __forceinline__ void gemm_phase(PG8_LAS unsigned char* lds, const Gemm g, const Sched& S, const Epi& E) {
;     ...
;             PG8_LDB(B0, 0, 0); PG8_LDB(B1, 0, 1); PG8_SCHED; PG8_LDA(At, 0, 0); PG8_STAGE(PG8_SA(1, 1), a1 + hstep, voffA);
;             PG8_WAIT_V(8); PG8_WAIT_L(0); PG8_BAR; PG8_MMA(0, 0, At, B0); PG8_MMA(0, 1, At, B1); PG8_BAR; PG8_SCHED;
;             PG8_LDA(At, 0, 1); PG8_STAGE(PG8_SB(0, 0), b2, voffB); PG8_STAGE(PG8_SB(0, 1), b2 + hstep, voffB); PG8_STAGE(PG8_SA(0, 0), a2, voffA);
;             PG8_WAIT_V(8); PG8_WAIT_L(0); PG8_BAR; PG8_MMA(1, 0, At, B0); PG8_MMA(1, 1, At, B1); PG8_BAR; PG8_SCHED;
	s_setprio 1
	s_waitcnt lgkmcnt(0)
	v_mfma_f32_16x16x32_bf16 v[124:127], v[144:147], v[186:189], v[124:127]
	v_mfma_f32_16x16x32_bf16 v[120:123], v[160:163], v[186:189], v[120:123]
	v_mfma_f32_16x16x32_bf16 v[108:111], v[144:147], v[194:197], v[108:111]
	v_mfma_f32_16x16x32_bf16 v[104:107], v[160:163], v[194:197], v[104:107]
	v_mfma_f32_16x16x32_bf16 v[124:127], v[156:159], v[190:193], v[124:127]
	v_mfma_f32_16x16x32_bf16 v[120:123], v[164:167], v[190:193], v[120:123]
	v_mfma_f32_16x16x32_bf16 v[108:111], v[156:159], v[198:201], v[108:111]
	v_mfma_f32_16x16x32_bf16 v[104:107], v[164:167], v[198:201], v[104:107]
	v_mfma_f32_16x16x32_bf16 v[92:95], v[144:147], v[208:211], v[92:95]
	v_mfma_f32_16x16x32_bf16 v[88:91], v[160:163], v[208:211], v[88:91]
	v_mfma_f32_16x16x32_bf16 v[76:79], v[144:147], v[216:219], v[76:79]
	v_mfma_f32_16x16x32_bf16 v[72:75], v[160:163], v[216:219], v[72:75]
	v_mfma_f32_16x16x32_bf16 v[92:95], v[156:159], v[212:215], v[92:95]
	v_mfma_f32_16x16x32_bf16 v[88:91], v[164:167], v[212:215], v[88:91]
	v_mfma_f32_16x16x32_bf16 v[76:79], v[156:159], v[220:223], v[76:79]
	v_mfma_f32_16x16x32_bf16 v[72:75], v[164:167], v[220:223], v[72:75]
	s_setprio 0
	s_setprio 1
	v_mfma_f32_16x16x32_bf16 v[116:119], v[168:171], v[186:189], v[116:119]
	v_mfma_f32_16x16x32_bf16 v[112:115], v[176:179], v[186:189], v[112:115]
	v_mfma_f32_16x16x32_bf16 v[100:103], v[168:171], v[194:197], v[100:103]
	v_mfma_f32_16x16x32_bf16 v[96:99], v[176:179], v[194:197], v[96:99]
	v_mfma_f32_16x16x32_bf16 v[116:119], v[172:175], v[190:193], v[116:119]
	v_mfma_f32_16x16x32_bf16 v[112:115], v[182:185], v[190:193], v[112:115]
	v_mfma_f32_16x16x32_bf16 v[100:103], v[172:175], v[198:201], v[100:103]
	v_mfma_f32_16x16x32_bf16 v[96:99], v[182:185], v[198:201], v[96:99]
	v_mfma_f32_16x16x32_bf16 v[84:87], v[168:171], v[208:211], v[84:87]
	v_mfma_f32_16x16x32_bf16 v[80:83], v[176:179], v[208:211], v[80:83]
	v_mfma_f32_16x16x32_bf16 v[68:71], v[168:171], v[216:219], v[68:71]
	v_mfma_f32_16x16x32_bf16 v[64:67], v[176:179], v[216:219], v[64:67]
	v_mfma_f32_16x16x32_bf16 v[84:87], v[172:175], v[212:215], v[84:87]
	v_mfma_f32_16x16x32_bf16 v[80:83], v[182:185], v[212:215], v[80:83]
	v_mfma_f32_16x16x32_bf16 v[68:71], v[172:175], v[220:223], v[68:71]
	v_mfma_f32_16x16x32_bf16 v[64:67], v[182:185], v[220:223], v[64:67]
	s_setprio 0
	s_barrier
	s_add_i32 s50, s64, s33
	v_lshl_add_u64 v[224:225], s[54:55], 0, v[130:131]
	s_mov_b32 m0, s50
	ds_read_b128 v[186:189], v153 offset:16384
	ds_read_b128 v[190:193], v153 offset:17408
	ds_read_b128 v[194:197], v153 offset:18432
	ds_read_b128 v[198:201], v153 offset:19456
	ds_read_b128 v[208:211], v153 offset:20480
	ds_read_b128 v[212:215], v153 offset:21504
	ds_read_b128 v[216:219], v153 offset:22528
	ds_read_b128 v[220:223], v153 offset:23552
	global_load_lds_dwordx4 v[224:225], off
	s_add_i32 m0, s50, 0x2000
	s_add_u32 s50, s54, 0xb0000
	v_lshl_add_u64 v[226:227], s[54:55], 0, v[134:135]
	s_addc_u32 s51, s55, 0
	s_add_i32 s78, s65, s33
	global_load_lds_dwordx4 v[226:227], off
	v_lshl_add_u64 v[228:229], s[50:51], 0, v[130:131]
	s_mov_b32 m0, s78
	global_load_lds_dwordx4 v[228:229], off
	v_lshl_add_u64 v[228:229], s[50:51], 0, v[134:135]
	s_add_i32 m0, s78, 0x2000
	s_nop 0
	global_load_lds_dwordx4 v[228:229], off
	s_waitcnt vmcnt(6)
	s_waitcnt lgkmcnt(0)
	s_barrier
	s_setprio 1
	s_waitcnt lgkmcnt(0)
	v_mfma_f32_16x16x32_bf16 v[60:63], v[144:147], v[186:189], v[60:63]
	v_mfma_f32_16x16x32_bf16 v[56:59], v[160:163], v[186:189], v[56:59]
	v_mfma_f32_16x16x32_bf16 v[44:47], v[144:147], v[194:197], v[44:47]
	v_mfma_f32_16x16x32_bf16 v[40:43], v[160:163], v[194:197], v[40:43]
	v_mfma_f32_16x16x32_bf16 v[60:63], v[156:159], v[190:193], v[60:63]
	v_mfma_f32_16x16x32_bf16 v[56:59], v[164:167], v[190:193], v[56:59]
	v_mfma_f32_16x16x32_bf16 v[44:47], v[156:159], v[198:201], v[44:47]
	v_mfma_f32_16x16x32_bf16 v[40:43], v[164:167], v[198:201], v[40:43]
	v_mfma_f32_16x16x32_bf16 v[28:31], v[144:147], v[208:211], v[28:31]
	v_mfma_f32_16x16x32_bf16 v[24:27], v[160:163], v[208:211], v[24:27]
	v_mfma_f32_16x16x32_bf16 v[12:15], v[144:147], v[216:219], v[12:15]
	v_mfma_f32_16x16x32_bf16 v[8:11], v[160:163], v[216:219], v[8:11]
	v_mfma_f32_16x16x32_bf16 v[28:31], v[156:159], v[212:215], v[28:31]
	v_mfma_f32_16x16x32_bf16 v[24:27], v[164:167], v[212:215], v[24:27]
	v_lshl_add_u64 v[228:229], s[56:57], 0, v[128:129]
	s_mov_b32 m0, s34
	s_nop 0
	global_load_lds_dwordx4 v[228:229], off
	v_mfma_f32_16x16x32_bf16 v[12:15], v[156:159], v[220:223], v[12:15]
	v_mfma_f32_16x16x32_bf16 v[8:11], v[164:167], v[220:223], v[8:11]
	s_setprio 0
	s_setprio 1
	v_mfma_f32_16x16x32_bf16 v[52:55], v[168:171], v[186:189], v[52:55]
	v_mfma_f32_16x16x32_bf16 v[48:51], v[176:179], v[186:189], v[48:51]
	v_mfma_f32_16x16x32_bf16 v[36:39], v[168:171], v[194:197], v[36:39]
	v_mfma_f32_16x16x32_bf16 v[32:35], v[176:179], v[194:197], v[32:35]
	v_mfma_f32_16x16x32_bf16 v[52:55], v[172:175], v[190:193], v[52:55]
	v_mfma_f32_16x16x32_bf16 v[48:51], v[182:185], v[190:193], v[48:51]
	v_mfma_f32_16x16x32_bf16 v[36:39], v[172:175], v[198:201], v[36:39]
	v_mfma_f32_16x16x32_bf16 v[32:35], v[182:185], v[198:201], v[32:35]
	v_mfma_f32_16x16x32_bf16 v[20:23], v[168:171], v[208:211], v[20:23]
	v_mfma_f32_16x16x32_bf16 v[16:19], v[176:179], v[208:211], v[16:19]
	v_mfma_f32_16x16x32_bf16 v[4:7], v[168:171], v[216:219], v[4:7]
	v_mfma_f32_16x16x32_bf16 v[0:3], v[176:179], v[216:219], v[0:3]
	v_mfma_f32_16x16x32_bf16 v[20:23], v[172:175], v[212:215], v[20:23]
	v_mfma_f32_16x16x32_bf16 v[16:19], v[182:185], v[212:215], v[16:19]
	v_lshl_add_u64 v[230:231], s[56:57], 0, v[132:133]
	s_mov_b32 m0, s58
	s_nop 0
	global_load_lds_dwordx4 v[230:231], off
	v_mfma_f32_16x16x32_bf16 v[4:7], v[172:175], v[220:223], v[4:7]
	v_mfma_f32_16x16x32_bf16 v[0:3], v[182:185], v[220:223], v[0:3]
	s_setprio 0
	s_barrier
; #define PG8_STAGE(bufoff, gbase, voff) do { _Pragma("unroll") for (int _i = 0; _i < 2; ++_i) \
;         __builtin_amdgcn_global_load_lds((const unsigned*)((const char*)(gbase) + (voff)[_i]), (PG8_LAS unsigned*)(lds + (bufoff) + ldsw + _i * 8192), 16, 0, 0); } while (0)
; #define PG8_LDA(dst, b, h) do { _Pragma("unroll") for (int m = 0; m < 4; ++m) _Pragma("unroll") for (int k = 0; k < 2; ++k) dst[m][k] = *(const PG8_LAS bf16x8*)(lds + PG8_SA(b, h) + aoff + m * 2048 + k * 1024); } while (0)
; #define PG8_LDB(dst, b, h) do { _Pragma("unroll") for (int n = 0; n < 2; ++n) _Pragma("unroll") for (int k = 0; k < 2; ++k) dst[n][k] = *(const PG8_LAS bf16x8*)(lds + PG8_SB(b, h) + boff + n * 2048 + k * 1024); } while (0)
; #define PG8_MMA(ai, bj, At, Bt) do { __builtin_amdgcn_s_setprio(1); _Pragma("unroll") for (int m = 0; m < 4; ++m) _Pragma("unroll") for (int n = 0; n < 2; ++n) _Pragma("unroll") for (int k = 0; k < 2; ++k) \
;         acc[ai][bj][m][n] = __builtin_amdgcn_mfma_f32_16x16x32_bf16(Bt[n][k], At[m][k], acc[ai][bj][m][n], 0, 0, 0); __builtin_amdgcn_s_setprio(0); } while (0)
; #define PG8_WAIT_V(n) asm volatile("s_waitcnt vmcnt(" #n ")" ::: "memory")
; #define PG8_WAIT_L(n) asm volatile("s_waitcnt lgkmcnt(" #n ")" ::: "memory")
; #define PG8_BAR __builtin_amdgcn_s_barrier()
; #define PG8_SCHED __builtin_amdgcn_sched_barrier(0)
; template <class Epi, class Sched, bool ALIGN_EPI = false, bool SP2 = false>
; __device__ __forceinline__ void gemm_phase(PG8_LAS unsigned char* lds, const Gemm g, const Sched& S, const Epi& E) {
;     ...
;             PG8_LDB(B0, 1, 0); PG8_LDB(B1, 1, 1); PG8_SCHED; PG8_LDA(At, 1, 0); PG8_STAGE(PG8_SA(0, 1), a2 + hstep, voffA);
;             PG8_WAIT_V(8); PG8_WAIT_L(0); PG8_BAR; PG8_MMA(0, 0, At, B0); PG8_MMA(0, 1, At, B1); PG8_BAR; PG8_SCHED;
	s_add_i32 s78, 0, 0x18000
	v_add_u32_e32 v155, s78, v149
	s_add_i32 s79, 0, 0x1c000
	ds_read_b128 v[144:147], v155
	ds_read_b128 v[156:159], v155 offset:1024
	ds_read_b128 v[160:163], v155 offset:2048
	ds_read_b128 v[164:167], v155 offset:3072
	v_add_u32_e32 v155, s79, v149
	ds_read_b128 v[168:171], v155
	ds_read_b128 v[172:175], v155 offset:1024
	ds_read_b128 v[176:179], v155 offset:2048
	ds_read_b128 v[182:185], v155 offset:3072
	s_add_u32 s50, s56, 0xb0000
	s_addc_u32 s51, s57, 0
	s_mov_b32 m0, s59
	v_lshl_add_u64 v[232:233], s[50:51], 0, v[128:129]
	ds_read_b128 v[186:189], v153 offset:32768
	ds_read_b128 v[190:193], v153 offset:33792
	ds_read_b128 v[194:197], v153 offset:34816
	ds_read_b128 v[198:201], v153 offset:35840
	ds_read_b128 v[208:211], v153 offset:36864
	ds_read_b128 v[212:215], v153 offset:37888
	ds_read_b128 v[216:219], v153 offset:38912
	ds_read_b128 v[220:223], v153 offset:39936
	global_load_lds_dwordx4 v[232:233], off
	v_lshl_add_u64 v[232:233], s[50:51], 0, v[132:133]
	s_mov_b32 m0, s60
	s_nop 0
	global_load_lds_dwordx4 v[232:233], off
	s_waitcnt vmcnt(8)
	s_waitcnt lgkmcnt(0)
	s_barrier
	s_setprio 1
	s_waitcnt lgkmcnt(0)
	v_mfma_f32_16x16x32_bf16 v[124:127], v[144:147], v[186:189], v[124:127]
	v_mfma_f32_16x16x32_bf16 v[120:123], v[160:163], v[186:189], v[120:123]
	v_mfma_f32_16x16x32_bf16 v[108:111], v[144:147], v[194:197], v[108:111]
	v_mfma_f32_16x16x32_bf16 v[104:107], v[160:163], v[194:197], v[104:107]
	v_mfma_f32_16x16x32_bf16 v[124:127], v[156:159], v[190:193], v[124:127]
	v_mfma_f32_16x16x32_bf16 v[120:123], v[164:167], v[190:193], v[120:123]
	v_mfma_f32_16x16x32_bf16 v[108:111], v[156:159], v[198:201], v[108:111]
	v_mfma_f32_16x16x32_bf16 v[104:107], v[164:167], v[198:201], v[104:107]
	v_mfma_f32_16x16x32_bf16 v[92:95], v[144:147], v[208:211], v[92:95]
	v_mfma_f32_16x16x32_bf16 v[88:91], v[160:163], v[208:211], v[88:91]
	v_mfma_f32_16x16x32_bf16 v[76:79], v[144:147], v[216:219], v[76:79]
	v_mfma_f32_16x16x32_bf16 v[72:75], v[160:163], v[216:219], v[72:75]
	v_mfma_f32_16x16x32_bf16 v[92:95], v[156:159], v[212:215], v[92:95]
	v_mfma_f32_16x16x32_bf16 v[88:91], v[164:167], v[212:215], v[88:91]
	v_mfma_f32_16x16x32_bf16 v[76:79], v[156:159], v[220:223], v[76:79]
	v_mfma_f32_16x16x32_bf16 v[72:75], v[164:167], v[220:223], v[72:75]
	s_setprio 0
	s_setprio 1
	v_mfma_f32_16x16x32_bf16 v[116:119], v[168:171], v[186:189], v[116:119]
	v_mfma_f32_16x16x32_bf16 v[112:115], v[176:179], v[186:189], v[112:115]
	v_mfma_f32_16x16x32_bf16 v[100:103], v[168:171], v[194:197], v[100:103]
	v_mfma_f32_16x16x32_bf16 v[96:99], v[176:179], v[194:197], v[96:99]
	v_mfma_f32_16x16x32_bf16 v[116:119], v[172:175], v[190:193], v[116:119]
	v_mfma_f32_16x16x32_bf16 v[112:115], v[182:185], v[190:193], v[112:115]
	v_mfma_f32_16x16x32_bf16 v[100:103], v[172:175], v[198:201], v[100:103]
	v_mfma_f32_16x16x32_bf16 v[96:99], v[182:185], v[198:201], v[96:99]
	v_mfma_f32_16x16x32_bf16 v[84:87], v[168:171], v[208:211], v[84:87]
	v_mfma_f32_16x16x32_bf16 v[80:83], v[176:179], v[208:211], v[80:83]
	v_mfma_f32_16x16x32_bf16 v[68:71], v[168:171], v[216:219], v[68:71]
	v_mfma_f32_16x16x32_bf16 v[64:67], v[176:179], v[216:219], v[64:67]
	v_mfma_f32_16x16x32_bf16 v[84:87], v[172:175], v[212:215], v[84:87]
	v_mfma_f32_16x16x32_bf16 v[80:83], v[182:185], v[212:215], v[80:83]
	v_mfma_f32_16x16x32_bf16 v[68:71], v[172:175], v[220:223], v[68:71]
	v_mfma_f32_16x16x32_bf16 v[64:67], v[182:185], v[220:223], v[64:67]
	s_setprio 0
	s_barrier
; #define PG8_STAGE(bufoff, gbase, voff) do { _Pragma("unroll") for (int _i = 0; _i < 2; ++_i) \
;         __builtin_amdgcn_global_load_lds((const unsigned*)((const char*)(gbase) + (voff)[_i]), (PG8_LAS unsigned*)(lds + (bufoff) + ldsw + _i * 8192), 16, 0, 0); } while (0)
; #define PG8_LDA(dst, b, h) do { _Pragma("unroll") for (int m = 0; m < 4; ++m) _Pragma("unroll") for (int k = 0; k < 2; ++k) dst[m][k] = *(const PG8_LAS bf16x8*)(lds + PG8_SA(b, h) + aoff + m * 2048 + k * 1024); } while (0)
; #define PG8_MMA(ai, bj, At, Bt) do { __builtin_amdgcn_s_setprio(1); _Pragma("unroll") for (int m = 0; m < 4; ++m) _Pragma("unroll") for (int n = 0; n < 2; ++n) _Pragma("unroll") for (int k = 0; k < 2; ++k) \
;         acc[ai][bj][m][n] = __builtin_amdgcn_mfma_f32_16x16x32_bf16(Bt[n][k], At[m][k], acc[ai][bj][m][n], 0, 0, 0); __builtin_amdgcn_s_setprio(0); } while (0)
; #define PG8_WAIT_V(n) asm volatile("s_waitcnt vmcnt(" #n ")" ::: "memory")
; #define PG8_WAIT_L(n) asm volatile("s_waitcnt lgkmcnt(" #n ")" ::: "memory")
; #define PG8_BAR __builtin_amdgcn_s_barrier()
; #define PG8_SCHED __builtin_amdgcn_sched_barrier(0)
; template <class Epi, class Sched, bool ALIGN_EPI = false, bool SP2 = false>
; __device__ __forceinline__ void gemm_phase(PG8_LAS unsigned char* lds, const Gemm g, const Sched& S, const Epi& E) {
;     ...
;         for (int t = 0; t < nt; t += 2) {
;     ...
;             PG8_LDA(At, 1, 1); PG8_STAGE(PG8_SB(1, 0), b3, voffB); PG8_STAGE(PG8_SB(1, 1), b3 + hstep, voffB); PG8_STAGE(PG8_SA(1, 0), a3, voffA);
;             PG8_WAIT_V(8); PG8_WAIT_L(0); PG8_BAR; PG8_MMA(1, 0, At, B0); PG8_MMA(1, 1, At, B1); PG8_BAR; PG8_SCHED;
	s_add_i32 s50, s78, s33
	v_lshl_add_u64 v[224:225], v[224:225], 0, s[42:43]
	s_mov_b32 m0, s50
	ds_read_b128 v[186:189], v153 offset:49152
	ds_read_b128 v[190:193], v153 offset:50176
	ds_read_b128 v[194:197], v153 offset:51200
	ds_read_b128 v[198:201], v153 offset:52224
	ds_read_b128 v[208:211], v153 offset:53248
	ds_read_b128 v[212:215], v153 offset:54272
	ds_read_b128 v[216:219], v153 offset:55296
	ds_read_b128 v[220:223], v153 offset:56320
	global_load_lds_dwordx4 v[224:225], off
	s_add_i32 m0, s50, 0x2000
	s_add_u32 s50, s54, 0xb0080
	v_lshl_add_u64 v[224:225], v[226:227], 0, s[42:43]
	s_addc_u32 s51, s55, 0
	s_add_i32 s54, s79, s33
	global_load_lds_dwordx4 v[224:225], off
	v_lshl_add_u64 v[224:225], s[50:51], 0, v[130:131]
	s_mov_b32 m0, s54
	s_nop 0
	global_load_lds_dwordx4 v[224:225], off
	v_lshl_add_u64 v[224:225], s[50:51], 0, v[134:135]
	s_add_i32 m0, s54, 0x2000
	s_nop 0
	global_load_lds_dwordx4 v[224:225], off
	s_waitcnt vmcnt(6)
	s_waitcnt lgkmcnt(0)
	s_barrier
	s_setprio 1
	s_waitcnt lgkmcnt(0)
	v_mfma_f32_16x16x32_bf16 v[60:63], v[144:147], v[186:189], v[60:63]
	v_mfma_f32_16x16x32_bf16 v[56:59], v[160:163], v[186:189], v[56:59]
	v_mfma_f32_16x16x32_bf16 v[44:47], v[144:147], v[194:197], v[44:47]
	v_mfma_f32_16x16x32_bf16 v[40:43], v[160:163], v[194:197], v[40:43]
	v_mfma_f32_16x16x32_bf16 v[60:63], v[156:159], v[190:193], v[60:63]
	v_mfma_f32_16x16x32_bf16 v[56:59], v[164:167], v[190:193], v[56:59]
	v_mfma_f32_16x16x32_bf16 v[44:47], v[156:159], v[198:201], v[44:47]
	v_mfma_f32_16x16x32_bf16 v[40:43], v[164:167], v[198:201], v[40:43]
	v_mfma_f32_16x16x32_bf16 v[28:31], v[144:147], v[208:211], v[28:31]
	v_mfma_f32_16x16x32_bf16 v[24:27], v[160:163], v[208:211], v[24:27]
	v_mfma_f32_16x16x32_bf16 v[12:15], v[144:147], v[216:219], v[12:15]
	v_mfma_f32_16x16x32_bf16 v[8:11], v[160:163], v[216:219], v[8:11]
	v_mfma_f32_16x16x32_bf16 v[28:31], v[156:159], v[212:215], v[28:31]
	v_mfma_f32_16x16x32_bf16 v[24:27], v[164:167], v[212:215], v[24:27]
	v_lshl_add_u64 v[224:225], v[228:229], 0, s[42:43]
	s_mov_b32 m0, s62
	s_nop 0
	global_load_lds_dwordx4 v[224:225], off
	v_mfma_f32_16x16x32_bf16 v[12:15], v[156:159], v[220:223], v[12:15]
	v_mfma_f32_16x16x32_bf16 v[8:11], v[164:167], v[220:223], v[8:11]
	s_setprio 0
	s_setprio 1
	v_mfma_f32_16x16x32_bf16 v[52:55], v[168:171], v[186:189], v[52:55]
	v_mfma_f32_16x16x32_bf16 v[48:51], v[176:179], v[186:189], v[48:51]
	v_mfma_f32_16x16x32_bf16 v[36:39], v[168:171], v[194:197], v[36:39]
	v_mfma_f32_16x16x32_bf16 v[32:35], v[176:179], v[194:197], v[32:35]
	v_mfma_f32_16x16x32_bf16 v[52:55], v[172:175], v[190:193], v[52:55]
	v_mfma_f32_16x16x32_bf16 v[48:51], v[182:185], v[190:193], v[48:51]
	v_mfma_f32_16x16x32_bf16 v[36:39], v[172:175], v[198:201], v[36:39]
	v_mfma_f32_16x16x32_bf16 v[32:35], v[182:185], v[198:201], v[32:35]
	v_mfma_f32_16x16x32_bf16 v[20:23], v[168:171], v[208:211], v[20:23]
	v_mfma_f32_16x16x32_bf16 v[16:19], v[176:179], v[208:211], v[16:19]
	v_mfma_f32_16x16x32_bf16 v[4:7], v[168:171], v[216:219], v[4:7]
	v_mfma_f32_16x16x32_bf16 v[0:3], v[176:179], v[216:219], v[0:3]
	v_mfma_f32_16x16x32_bf16 v[20:23], v[172:175], v[212:215], v[20:23]
	v_mfma_f32_16x16x32_bf16 v[16:19], v[182:185], v[212:215], v[16:19]
	v_lshl_add_u64 v[224:225], v[230:231], 0, s[42:43]
	s_mov_b32 m0, s63
	s_nop 0
	global_load_lds_dwordx4 v[224:225], off
	v_mfma_f32_16x16x32_bf16 v[4:7], v[172:175], v[220:223], v[4:7]
	v_mfma_f32_16x16x32_bf16 v[0:3], v[182:185], v[220:223], v[0:3]
	s_setprio 0
	s_barrier
	s_add_i32 s84, s84, 2
	s_add_u32 s82, s82, 0x100
	s_addc_u32 s83, s83, 0
	s_cmp_gt_u32 s84, 41
	s_mov_b64 s[50:51], s[52:53]
	s_cbranch_scc0 .LBB0_1197
	s_and_b64 vcc, exec, s[44:45]
	s_cbranch_vccz .LBB0_1200
	s_barrier

; #define PG8_STAGE(bufoff, gbase, voff) do { _Pragma("unroll") for (int _i = 0; _i < 2; ++_i) \
;         __builtin_amdgcn_global_load_lds((const unsigned*)((const char*)(gbase) + (voff)[_i]), (PG8_LAS unsigned*)(lds + (bufoff) + ldsw + _i * 8192), 16, 0, 0); } while (0)
; #define PG8_LDA(dst, b, h) do { _Pragma("unroll") for (int m = 0; m < 4; ++m) _Pragma("unroll") for (int k = 0; k < 2; ++k) dst[m][k] = *(const PG8_LAS bf16x8*)(lds + PG8_SA(b, h) + aoff + m * 2048 + k * 1024); } while (0)
; #define PG8_LDB(dst, b, h) do { _Pragma("unroll") for (int n = 0; n < 2; ++n) _Pragma("unroll") for (int k = 0; k < 2; ++k) dst[n][k] = *(const PG8_LAS bf16x8*)(lds + PG8_SB(b, h) + boff + n * 2048 + k * 1024); } while (0)
; #define PG8_WAIT_V(n) asm volatile("s_waitcnt vmcnt(" #n ")" ::: "memory")
; #define PG8_WAIT_L(n) asm volatile("s_waitcnt lgkmcnt(" #n ")" ::: "memory")
; #define PG8_BAR __builtin_amdgcn_s_barrier()
; #define PG8_SCHED __builtin_amdgcn_sched_barrier(0)
; template <class Epi, class Sched, bool ALIGN_EPI = false, bool SP2 = false>
; __device__ __forceinline__ void gemm_phase(PG8_LAS unsigned char* lds, const Gemm g, const Sched& S, const Epi& E) {
;     ...
;         const bool has_next = S.next(ui + 1, nxt);
;         const char* nA = has_next ? (const char*)g.A + (size_t)nxt.pm * tstep : cA; const char* nB = has_next ? (const char*)g.Bt + (size_t)nxt.pn * tstep : cB;
;         for (int t = 0; t < nt; t += 2) {
;             const bool last = (t == nt - 2);
;             const char* a1 = cA + (size_t)(t + 1) * kstep;
;             const char* a2 = last ? nA : cA + (size_t)(t + 2) * kstep; const char* b2 = last ? nB : cB + (size_t)(t + 2) * kstep;
;             const char* a3 = a2 + kstep; const char* b3 = b2 + kstep;
;             if (last && has_next) S.a_ready(nxt);
;             if constexpr (SP2) {
;             PG8_LDB(B0, 0, 0); PG8_LDB(B1, 0, 1); PG8_SCHED; PG8_LDA(At, 0, 0); PG8_STAGE(PG8_SA(1, 1), a1 + hstep, voffA);
;             PG8_WAIT_V(8); PG8_WAIT_L(0); PG8_BAR; PG8_MMA(0, 0, At, B0); PG8_MMA(0, 1, At, B1); PG8_BAR; PG8_SCHED;
;             PG8_LDA(At, 0, 1); PG8_STAGE(PG8_SB(0, 0), b2, voffB); PG8_STAGE(PG8_SB(0, 1), b2 + hstep, voffB); PG8_STAGE(PG8_SA(0, 0), a2, voffA);
;             PG8_WAIT_V(8); PG8_WAIT_L(0); PG8_BAR; PG8_MMA(1, 0, At, B0); PG8_MMA(1, 1, At, B1); PG8_BAR; PG8_SCHED;
.LBB0_1286:
	s_ashr_i32 s51, s50, 31
	s_lshl_b64 s[52:53], s[50:51], 19
	s_add_u32 s52, s22, s52
	s_addc_u32 s53, s23, s53
	s_and_b64 s[54:55], s[12:13], exec
	s_cselect_b32 s51, s53, s59
	s_cselect_b32 s61, s52, s58
	s_ashr_i32 s49, s48, 31
	s_lshl_b64 s[54:55], s[48:49], 19
	v_readlane_b32 s64, v250, 9
	v_readlane_b32 s65, v250, 10
	s_add_u32 s54, s64, s54
	s_addc_u32 s55, s65, s55
	s_and_b64 s[64:65], s[12:13], exec
	s_cselect_b32 s49, s55, s63
	s_cselect_b32 s87, s54, s62
	s_add_u32 s58, s58, 0x40080
	s_addc_u32 s59, s59, 0
	s_add_u32 s88, s62, 0x100
	s_addc_u32 s89, s63, 0
	s_mov_b32 s90, -2
	s_waitcnt lgkmcnt(0)
	ds_read_b128 v[128:131], v181
	ds_read_b128 v[160:163], v181 offset:1024
	ds_read_b128 v[164:167], v181 offset:2048
	ds_read_b128 v[168:171], v181 offset:3072
	ds_read_b128 v[172:175], v203
	ds_read_b128 v[176:179], v203 offset:1024
	ds_read_b128 v[182:185], v203 offset:2048
	ds_read_b128 v[186:189], v203 offset:3072
	s_add_u32 s62, s58, 0xfffc0080
	s_addc_u32 s63, s59, -1
	s_cmp_eq_u32 s90, 12
	s_cselect_b32 s65, s51, s63
	s_cselect_b32 s64, s61, s62
	s_cselect_b32 s63, s49, s89
	s_cselect_b32 s62, s87, s88
	v_lshl_add_u64 v[232:233], s[58:59], 0, v[152:153]
	s_add_i32 m0, s15, 0xc000
	ds_read_b128 v[190:193], v208
	ds_read_b128 v[194:197], v208 offset:1024
	ds_read_b128 v[198:201], v208 offset:2048
	ds_read_b128 v[212:215], v208 offset:3072
	ds_read_b128 v[216:219], v208 offset:4096
	ds_read_b128 v[220:223], v208 offset:5120
	ds_read_b128 v[224:227], v208 offset:6144
	ds_read_b128 v[228:231], v208 offset:7168
	global_load_lds_dwordx4 v[232:233], off
	v_lshl_add_u64 v[232:233], s[58:59], 0, v[154:155]
	s_add_i32 m0, s15, 0xe000
	s_nop 0
	global_load_lds_dwordx4 v[232:233], off
	s_waitcnt vmcnt(8)
	s_waitcnt lgkmcnt(0)
	s_barrier
	s_setprio 1
	s_waitcnt lgkmcnt(0)
	v_mfma_f32_16x16x32_bf16 v[124:127], v[128:131], v[190:193], 0
	v_mfma_f32_16x16x32_bf16 v[120:123], v[164:167], v[190:193], 0
	v_mfma_f32_16x16x32_bf16 v[116:119], v[128:131], v[198:201], 0
	v_mfma_f32_16x16x32_bf16 v[112:115], v[164:167], v[198:201], 0
	v_mfma_f32_16x16x32_bf16 v[124:127], v[160:163], v[194:197], v[124:127]
	v_mfma_f32_16x16x32_bf16 v[120:123], v[168:171], v[194:197], v[120:123]
	v_mfma_f32_16x16x32_bf16 v[116:119], v[160:163], v[212:215], v[116:119]
	v_mfma_f32_16x16x32_bf16 v[112:115], v[168:171], v[212:215], v[112:115]
	v_mfma_f32_16x16x32_bf16 v[108:111], v[128:131], v[216:219], 0
	v_mfma_f32_16x16x32_bf16 v[104:107], v[164:167], v[216:219], 0
	v_mfma_f32_16x16x32_bf16 v[100:103], v[128:131], v[224:227], 0
	v_mfma_f32_16x16x32_bf16 v[96:99], v[164:167], v[224:227], 0
	v_mfma_f32_16x16x32_bf16 v[108:111], v[160:163], v[220:223], v[108:111]
	v_mfma_f32_16x16x32_bf16 v[104:107], v[168:171], v[220:223], v[104:107]
	v_mfma_f32_16x16x32_bf16 v[100:103], v[160:163], v[228:231], v[100:103]
	v_mfma_f32_16x16x32_bf16 v[96:99], v[168:171], v[228:231], v[96:99]
	s_setprio 0
	s_setprio 1
	v_mfma_f32_16x16x32_bf16 v[60:63], v[172:175], v[190:193], 0
	v_mfma_f32_16x16x32_bf16 v[56:59], v[182:185], v[190:193], 0
	v_mfma_f32_16x16x32_bf16 v[52:55], v[172:175], v[198:201], 0
	v_mfma_f32_16x16x32_bf16 v[48:51], v[182:185], v[198:201], 0
	v_mfma_f32_16x16x32_bf16 v[60:63], v[176:179], v[194:197], v[60:63]
	v_mfma_f32_16x16x32_bf16 v[56:59], v[186:189], v[194:197], v[56:59]
	v_mfma_f32_16x16x32_bf16 v[52:55], v[176:179], v[212:215], v[52:55]
	v_mfma_f32_16x16x32_bf16 v[48:51], v[186:189], v[212:215], v[48:51]
	v_mfma_f32_16x16x32_bf16 v[44:47], v[172:175], v[216:219], 0
	v_mfma_f32_16x16x32_bf16 v[40:43], v[182:185], v[216:219], 0
	v_mfma_f32_16x16x32_bf16 v[36:39], v[172:175], v[224:227], 0
	v_mfma_f32_16x16x32_bf16 v[32:35], v[182:185], v[224:227], 0
	v_mfma_f32_16x16x32_bf16 v[44:47], v[176:179], v[220:223], v[44:47]
	v_mfma_f32_16x16x32_bf16 v[40:43], v[186:189], v[220:223], v[40:43]
	v_mfma_f32_16x16x32_bf16 v[36:39], v[176:179], v[228:231], v[36:39]
	v_mfma_f32_16x16x32_bf16 v[32:35], v[186:189], v[228:231], v[32:35]
	s_setprio 0
	s_barrier
	s_add_i32 s78, s75, s14
	v_lshl_add_u64 v[232:233], s[62:63], 0, v[134:135]
	s_mov_b32 m0, s78
	ds_read_b128 v[190:193], v208 offset:16384
	ds_read_b128 v[194:197], v208 offset:17408
	ds_read_b128 v[198:201], v208 offset:18432
	ds_read_b128 v[212:215], v208 offset:19456
	ds_read_b128 v[216:219], v208 offset:20480
	ds_read_b128 v[220:223], v208 offset:21504
	ds_read_b128 v[224:227], v208 offset:22528
	ds_read_b128 v[228:231], v208 offset:23552
	global_load_lds_dwordx4 v[232:233], off
	s_add_i32 m0, s78, 0x2000
	s_add_u32 s78, s62, 0x40000
	v_lshl_add_u64 v[234:235], s[62:63], 0, v[138:139]
	s_addc_u32 s79, s63, 0
	s_add_i32 s91, s76, s14
	global_load_lds_dwordx4 v[234:235], off
	v_lshl_add_u64 v[236:237], s[78:79], 0, v[134:135]
	s_mov_b32 m0, s91
	global_load_lds_dwordx4 v[236:237], off
	v_lshl_add_u64 v[236:237], s[78:79], 0, v[138:139]
	s_add_i32 m0, s91, 0x2000
	s_nop 0
	global_load_lds_dwordx4 v[236:237], off
	s_waitcnt vmcnt(6)
	s_waitcnt lgkmcnt(0)
	s_barrier
; #define PG8_STAGE(bufoff, gbase, voff) do { _Pragma("unroll") for (int _i = 0; _i < 2; ++_i) \
;         __builtin_amdgcn_global_load_lds((const unsigned*)((const char*)(gbase) + (voff)[_i]), (PG8_LAS unsigned*)(lds + (bufoff) + ldsw + _i * 8192), 16, 0, 0); } while (0)
; #define PG8_LDA(dst, b, h) do { _Pragma("unroll") for (int m = 0; m < 4; ++m) _Pragma("unroll") for (int k = 0; k < 2; ++k) dst[m][k] = *(const PG8_LAS bf16x8*)(lds + PG8_SA(b, h) + aoff + m * 2048 + k * 1024); } while (0)
; #define PG8_LDB(dst, b, h) do { _Pragma("unroll") for (int n = 0; n < 2; ++n) _Pragma("unroll") for (int k = 0; k < 2; ++k) dst[n][k] = *(const PG8_LAS bf16x8*)(lds + PG8_SB(b, h) + boff + n * 2048 + k * 1024); } while (0)
; #define PG8_MMA(ai, bj, At, Bt) do { __builtin_amdgcn_s_setprio(1); _Pragma("unroll") for (int m = 0; m < 4; ++m) _Pragma("unroll") for (int n = 0; n < 2; ++n) _Pragma("unroll") for (int k = 0; k < 2; ++k) \
;         acc[ai][bj][m][n] = __builtin_amdgcn_mfma_f32_16x16x32_bf16(Bt[n][k], At[m][k], acc[ai][bj][m][n], 0, 0, 0); __builtin_amdgcn_s_setprio(0); } while (0)
; #define PG8_WAIT_V(n) asm volatile("s_waitcnt vmcnt(" #n ")" ::: "memory")
; #define PG8_WAIT_L(n) asm volatile("s_waitcnt lgkmcnt(" #n ")" ::: "memory")
; #define PG8_BAR __builtin_amdgcn_s_barrier()
; #define PG8_SCHED __builtin_amdgcn_sched_barrier(0)
; template <class Epi, class Sched, bool ALIGN_EPI = false, bool SP2 = false>
; __device__ __forceinline__ void gemm_phase(PG8_LAS unsigned char* lds, const Gemm g, const Sched& S, const Epi& E) {
;     ...
;             PG8_LDA(At, 0, 1); PG8_STAGE(PG8_SB(0, 0), b2, voffB); PG8_STAGE(PG8_SB(0, 1), b2 + hstep, voffB); PG8_STAGE(PG8_SA(0, 0), a2, voffA);
;             PG8_WAIT_V(8); PG8_WAIT_L(0); PG8_BAR; PG8_MMA(1, 0, At, B0); PG8_MMA(1, 1, At, B1); PG8_BAR; PG8_SCHED;
;             PG8_LDB(B0, 1, 0); PG8_LDB(B1, 1, 1); PG8_SCHED; PG8_LDA(At, 1, 0); PG8_STAGE(PG8_SA(0, 1), a2 + hstep, voffA);
;             PG8_WAIT_V(8); PG8_WAIT_L(0); PG8_BAR; PG8_MMA(0, 0, At, B0); PG8_MMA(0, 1, At, B1); PG8_BAR; PG8_SCHED;
	s_setprio 1
	s_waitcnt lgkmcnt(0)
	v_mfma_f32_16x16x32_bf16 v[92:95], v[128:131], v[190:193], 0
	v_mfma_f32_16x16x32_bf16 v[88:91], v[164:167], v[190:193], 0
	v_mfma_f32_16x16x32_bf16 v[84:87], v[128:131], v[198:201], 0
	v_mfma_f32_16x16x32_bf16 v[80:83], v[164:167], v[198:201], 0
	v_mfma_f32_16x16x32_bf16 v[92:95], v[160:163], v[194:197], v[92:95]
	v_mfma_f32_16x16x32_bf16 v[88:91], v[168:171], v[194:197], v[88:91]
	v_mfma_f32_16x16x32_bf16 v[84:87], v[160:163], v[212:215], v[84:87]
	v_mfma_f32_16x16x32_bf16 v[80:83], v[168:171], v[212:215], v[80:83]
	v_mfma_f32_16x16x32_bf16 v[76:79], v[128:131], v[216:219], 0
	v_mfma_f32_16x16x32_bf16 v[72:75], v[164:167], v[216:219], 0
	v_mfma_f32_16x16x32_bf16 v[68:71], v[128:131], v[224:227], 0
	v_mfma_f32_16x16x32_bf16 v[64:67], v[164:167], v[224:227], 0
	v_mfma_f32_16x16x32_bf16 v[76:79], v[160:163], v[220:223], v[76:79]
	v_mfma_f32_16x16x32_bf16 v[72:75], v[168:171], v[220:223], v[72:75]
	v_lshl_add_u64 v[236:237], s[64:65], 0, v[132:133]
	s_mov_b32 m0, s15
	s_nop 0
	global_load_lds_dwordx4 v[236:237], off
	v_mfma_f32_16x16x32_bf16 v[68:71], v[160:163], v[228:231], v[68:71]
	v_mfma_f32_16x16x32_bf16 v[64:67], v[168:171], v[228:231], v[64:67]
	s_setprio 0
	s_setprio 1
	v_mfma_f32_16x16x32_bf16 v[28:31], v[172:175], v[190:193], 0
	v_mfma_f32_16x16x32_bf16 v[24:27], v[182:185], v[190:193], 0
	v_mfma_f32_16x16x32_bf16 v[20:23], v[172:175], v[198:201], 0
	v_mfma_f32_16x16x32_bf16 v[16:19], v[182:185], v[198:201], 0
	v_mfma_f32_16x16x32_bf16 v[28:31], v[176:179], v[194:197], v[28:31]
	v_mfma_f32_16x16x32_bf16 v[24:27], v[186:189], v[194:197], v[24:27]
	v_mfma_f32_16x16x32_bf16 v[20:23], v[176:179], v[212:215], v[20:23]
	v_mfma_f32_16x16x32_bf16 v[16:19], v[186:189], v[212:215], v[16:19]
	v_mfma_f32_16x16x32_bf16 v[12:15], v[172:175], v[216:219], 0
	v_mfma_f32_16x16x32_bf16 v[8:11], v[182:185], v[216:219], 0
	v_mfma_f32_16x16x32_bf16 v[4:7], v[172:175], v[224:227], 0
	v_mfma_f32_16x16x32_bf16 v[0:3], v[182:185], v[224:227], 0
	v_mfma_f32_16x16x32_bf16 v[12:15], v[176:179], v[220:223], v[12:15]
	v_mfma_f32_16x16x32_bf16 v[8:11], v[186:189], v[220:223], v[8:11]
	v_lshl_add_u64 v[238:239], s[64:65], 0, v[136:137]
	s_mov_b32 m0, s33
	s_nop 0
	global_load_lds_dwordx4 v[238:239], off
	v_mfma_f32_16x16x32_bf16 v[4:7], v[176:179], v[228:231], v[4:7]
	v_mfma_f32_16x16x32_bf16 v[0:3], v[186:189], v[228:231], v[0:3]
	s_setprio 0
	s_barrier
	s_add_i32 s78, 0, 0x18000
	v_add_u32_e32 v140, s78, v147
	s_add_i32 s79, 0, 0x1c000
	ds_read_b128 v[128:131], v140
	ds_read_b128 v[160:163], v140 offset:1024
	ds_read_b128 v[164:167], v140 offset:2048
	ds_read_b128 v[168:171], v140 offset:3072
	v_add_u32_e32 v140, s79, v147
	ds_read_b128 v[172:175], v140
	ds_read_b128 v[176:179], v140 offset:1024
	ds_read_b128 v[182:185], v140 offset:2048
	ds_read_b128 v[186:189], v140 offset:3072
	s_add_u32 s64, s64, 0x40000
	s_addc_u32 s65, s65, 0
	s_mov_b32 m0, s34
	v_lshl_add_u64 v[240:241], s[64:65], 0, v[132:133]
	ds_read_b128 v[190:193], v208 offset:32768
	ds_read_b128 v[194:197], v208 offset:33792
	ds_read_b128 v[198:201], v208 offset:34816
	ds_read_b128 v[212:215], v208 offset:35840
	ds_read_b128 v[216:219], v208 offset:36864
	ds_read_b128 v[220:223], v208 offset:37888
	ds_read_b128 v[224:227], v208 offset:38912
	ds_read_b128 v[228:231], v208 offset:39936
	global_load_lds_dwordx4 v[240:241], off
	v_lshl_add_u64 v[240:241], s[64:65], 0, v[136:137]
	s_mov_b32 m0, s57
	s_nop 0
	global_load_lds_dwordx4 v[240:241], off
	s_waitcnt vmcnt(8)
	s_waitcnt lgkmcnt(0)
	s_barrier
	s_setprio 1
	s_waitcnt lgkmcnt(0)
	v_mfma_f32_16x16x32_bf16 v[124:127], v[128:131], v[190:193], v[124:127]
	v_mfma_f32_16x16x32_bf16 v[120:123], v[164:167], v[190:193], v[120:123]
	v_mfma_f32_16x16x32_bf16 v[116:119], v[128:131], v[198:201], v[116:119]
	v_mfma_f32_16x16x32_bf16 v[112:115], v[164:167], v[198:201], v[112:115]
	v_mfma_f32_16x16x32_bf16 v[124:127], v[160:163], v[194:197], v[124:127]
	v_mfma_f32_16x16x32_bf16 v[120:123], v[168:171], v[194:197], v[120:123]
	v_mfma_f32_16x16x32_bf16 v[116:119], v[160:163], v[212:215], v[116:119]
	v_mfma_f32_16x16x32_bf16 v[112:115], v[168:171], v[212:215], v[112:115]
	v_mfma_f32_16x16x32_bf16 v[108:111], v[128:131], v[216:219], v[108:111]
	v_mfma_f32_16x16x32_bf16 v[104:107], v[164:167], v[216:219], v[104:107]
	v_mfma_f32_16x16x32_bf16 v[100:103], v[128:131], v[224:227], v[100:103]
	v_mfma_f32_16x16x32_bf16 v[96:99], v[164:167], v[224:227], v[96:99]
	v_mfma_f32_16x16x32_bf16 v[108:111], v[160:163], v[220:223], v[108:111]
	v_mfma_f32_16x16x32_bf16 v[104:107], v[168:171], v[220:223], v[104:107]
	v_mfma_f32_16x16x32_bf16 v[100:103], v[160:163], v[228:231], v[100:103]
	v_mfma_f32_16x16x32_bf16 v[96:99], v[168:171], v[228:231], v[96:99]
	s_setprio 0
	s_setprio 1
	v_mfma_f32_16x16x32_bf16 v[60:63], v[172:175], v[190:193], v[60:63]
	v_mfma_f32_16x16x32_bf16 v[56:59], v[182:185], v[190:193], v[56:59]
	v_mfma_f32_16x16x32_bf16 v[52:55], v[172:175], v[198:201], v[52:55]
	v_mfma_f32_16x16x32_bf16 v[48:51], v[182:185], v[198:201], v[48:51]
	v_mfma_f32_16x16x32_bf16 v[60:63], v[176:179], v[194:197], v[60:63]
	v_mfma_f32_16x16x32_bf16 v[56:59], v[186:189], v[194:197], v[56:59]
	v_mfma_f32_16x16x32_bf16 v[52:55], v[176:179], v[212:215], v[52:55]
	v_mfma_f32_16x16x32_bf16 v[48:51], v[186:189], v[212:215], v[48:51]
	v_mfma_f32_16x16x32_bf16 v[44:47], v[172:175], v[216:219], v[44:47]
	v_mfma_f32_16x16x32_bf16 v[40:43], v[182:185], v[216:219], v[40:43]
	v_mfma_f32_16x16x32_bf16 v[36:39], v[172:175], v[224:227], v[36:39]
	v_mfma_f32_16x16x32_bf16 v[32:35], v[182:185], v[224:227], v[32:35]
	v_mfma_f32_16x16x32_bf16 v[44:47], v[176:179], v[220:223], v[44:47]
	v_mfma_f32_16x16x32_bf16 v[40:43], v[186:189], v[220:223], v[40:43]
	v_mfma_f32_16x16x32_bf16 v[36:39], v[176:179], v[228:231], v[36:39]
	v_mfma_f32_16x16x32_bf16 v[32:35], v[186:189], v[228:231], v[32:35]
	s_setprio 0
	s_barrier
; #define PG8_STAGE(bufoff, gbase, voff) do { _Pragma("unroll") for (int _i = 0; _i < 2; ++_i) \
;         __builtin_amdgcn_global_load_lds((const unsigned*)((const char*)(gbase) + (voff)[_i]), (PG8_LAS unsigned*)(lds + (bufoff) + ldsw + _i * 8192), 16, 0, 0); } while (0)
; #define PG8_LDA(dst, b, h) do { _Pragma("unroll") for (int m = 0; m < 4; ++m) _Pragma("unroll") for (int k = 0; k < 2; ++k) dst[m][k] = *(const PG8_LAS bf16x8*)(lds + PG8_SA(b, h) + aoff + m * 2048 + k * 1024); } while (0)
; #define PG8_LDB(dst, b, h) do { _Pragma("unroll") for (int n = 0; n < 2; ++n) _Pragma("unroll") for (int k = 0; k < 2; ++k) dst[n][k] = *(const PG8_LAS bf16x8*)(lds + PG8_SB(b, h) + boff + n * 2048 + k * 1024); } while (0)
; #define PG8_WAIT_V(n) asm volatile("s_waitcnt vmcnt(" #n ")" ::: "memory")
; #define PG8_WAIT_L(n) asm volatile("s_waitcnt lgkmcnt(" #n ")" ::: "memory")
; #define PG8_BAR __builtin_amdgcn_s_barrier()
; template <class Epi, class Sched, bool ALIGN_EPI = false, bool SP2 = false>
; __device__ __forceinline__ void gemm_phase(PG8_LAS unsigned char* lds, const Gemm g, const Sched& S, const Epi& E) {
;     ...
;         for (int t = 0; t < nt; t += 2) {
;             const bool last = (t == nt - 2);
;             const char* a1 = cA + (size_t)(t + 1) * kstep;
;             const char* a2 = last ? nA : cA + (size_t)(t + 2) * kstep; const char* b2 = last ? nB : cB + (size_t)(t + 2) * kstep;
;             const char* a3 = a2 + kstep; const char* b3 = b2 + kstep;
;             if (last && has_next) S.a_ready(nxt);
;             if constexpr (SP2) {
;             PG8_LDB(B0, 0, 0); PG8_LDB(B1, 0, 1); PG8_SCHED; PG8_LDA(At, 0, 0); PG8_STAGE(PG8_SA(1, 1), a1 + hstep, voffA);
;             PG8_WAIT_V(8); PG8_WAIT_L(0); PG8_BAR; PG8_MMA(0, 0, At, B0); PG8_MMA(0, 1, At, B1); PG8_BAR; PG8_SCHED;
;             PG8_LDA(At, 0, 1); PG8_STAGE(PG8_SB(0, 0), b2, voffB); PG8_STAGE(PG8_SB(0, 1), b2 + hstep, voffB); PG8_STAGE(PG8_SA(0, 0), a2, voffA);
;             PG8_WAIT_V(8); PG8_WAIT_L(0); PG8_BAR; PG8_MMA(1, 0, At, B0); PG8_MMA(1, 1, At, B1); PG8_BAR; PG8_SCHED;
;     ...
;             PG8_LDA(At, 1, 1); PG8_STAGE(PG8_SB(1, 0), b3, voffB); PG8_STAGE(PG8_SB(1, 1), b3 + hstep, voffB); PG8_STAGE(PG8_SA(1, 0), a3, voffA);
;             PG8_WAIT_V(8); PG8_WAIT_L(0); PG8_BAR; PG8_MMA(1, 0, At, B0); PG8_MMA(1, 1, At, B1); PG8_BAR; PG8_SCHED;
	s_add_i32 s64, s78, s14
	v_lshl_add_u64 v[232:233], v[232:233], 0, s[42:43]
	s_mov_b32 m0, s64
	ds_read_b128 v[190:193], v208 offset:49152
	ds_read_b128 v[194:197], v208 offset:50176
	ds_read_b128 v[198:201], v208 offset:51200
	ds_read_b128 v[212:215], v208 offset:52224
	ds_read_b128 v[216:219], v208 offset:53248
	ds_read_b128 v[220:223], v208 offset:54272
	ds_read_b128 v[224:227], v208 offset:55296
	ds_read_b128 v[228:231], v208 offset:56320
	global_load_lds_dwordx4 v[232:233], off
	s_add_i32 m0, s64, 0x2000
	s_add_u32 s62, s62, 0x40080
	v_lshl_add_u64 v[232:233], v[234:235], 0, s[42:43]
	s_addc_u32 s63, s63, 0
	s_add_i32 s64, s79, s14
	global_load_lds_dwordx4 v[232:233], off
	v_lshl_add_u64 v[232:233], s[62:63], 0, v[134:135]
	s_mov_b32 m0, s64
	s_nop 0
	global_load_lds_dwordx4 v[232:233], off
	v_lshl_add_u64 v[232:233], s[62:63], 0, v[138:139]
	s_add_i32 m0, s64, 0x2000
	s_nop 0
	global_load_lds_dwordx4 v[232:233], off
	s_waitcnt vmcnt(6)
	s_waitcnt lgkmcnt(0)
	s_barrier
	s_setprio 1
	s_waitcnt lgkmcnt(0)
	v_mfma_f32_16x16x32_bf16 v[92:95], v[128:131], v[190:193], v[92:95]
	v_mfma_f32_16x16x32_bf16 v[88:91], v[164:167], v[190:193], v[88:91]
	v_mfma_f32_16x16x32_bf16 v[84:87], v[128:131], v[198:201], v[84:87]
	v_mfma_f32_16x16x32_bf16 v[80:83], v[164:167], v[198:201], v[80:83]
	v_mfma_f32_16x16x32_bf16 v[92:95], v[160:163], v[194:197], v[92:95]
	v_mfma_f32_16x16x32_bf16 v[88:91], v[168:171], v[194:197], v[88:91]
	v_mfma_f32_16x16x32_bf16 v[84:87], v[160:163], v[212:215], v[84:87]
	v_mfma_f32_16x16x32_bf16 v[80:83], v[168:171], v[212:215], v[80:83]
	v_mfma_f32_16x16x32_bf16 v[76:79], v[128:131], v[216:219], v[76:79]
	v_mfma_f32_16x16x32_bf16 v[72:75], v[164:167], v[216:219], v[72:75]
	v_mfma_f32_16x16x32_bf16 v[68:71], v[128:131], v[224:227], v[68:71]
	v_mfma_f32_16x16x32_bf16 v[64:67], v[164:167], v[224:227], v[64:67]
	v_mfma_f32_16x16x32_bf16 v[76:79], v[160:163], v[220:223], v[76:79]
	v_mfma_f32_16x16x32_bf16 v[72:75], v[168:171], v[220:223], v[72:75]
	v_lshl_add_u64 v[232:233], v[236:237], 0, s[42:43]
	s_mov_b32 m0, s67
	s_nop 0
	global_load_lds_dwordx4 v[232:233], off
	v_mfma_f32_16x16x32_bf16 v[68:71], v[160:163], v[228:231], v[68:71]
	v_mfma_f32_16x16x32_bf16 v[64:67], v[168:171], v[228:231], v[64:67]
	s_setprio 0
	s_setprio 1
	v_mfma_f32_16x16x32_bf16 v[28:31], v[172:175], v[190:193], v[28:31]
	v_mfma_f32_16x16x32_bf16 v[24:27], v[182:185], v[190:193], v[24:27]
	v_mfma_f32_16x16x32_bf16 v[20:23], v[172:175], v[198:201], v[20:23]
	v_mfma_f32_16x16x32_bf16 v[16:19], v[182:185], v[198:201], v[16:19]
	v_mfma_f32_16x16x32_bf16 v[28:31], v[176:179], v[194:197], v[28:31]
	v_mfma_f32_16x16x32_bf16 v[24:27], v[186:189], v[194:197], v[24:27]
	v_mfma_f32_16x16x32_bf16 v[20:23], v[176:179], v[212:215], v[20:23]
	v_mfma_f32_16x16x32_bf16 v[16:19], v[186:189], v[212:215], v[16:19]
	v_mfma_f32_16x16x32_bf16 v[12:15], v[172:175], v[216:219], v[12:15]
	v_mfma_f32_16x16x32_bf16 v[8:11], v[182:185], v[216:219], v[8:11]
	v_mfma_f32_16x16x32_bf16 v[4:7], v[172:175], v[224:227], v[4:7]
	v_mfma_f32_16x16x32_bf16 v[0:3], v[182:185], v[224:227], v[0:3]
	v_mfma_f32_16x16x32_bf16 v[12:15], v[176:179], v[220:223], v[12:15]
	v_mfma_f32_16x16x32_bf16 v[8:11], v[186:189], v[220:223], v[8:11]
	v_lshl_add_u64 v[232:233], v[238:239], 0, s[42:43]
	s_mov_b32 m0, s74
	s_nop 0
	global_load_lds_dwordx4 v[232:233], off
	v_mfma_f32_16x16x32_bf16 v[4:7], v[176:179], v[228:231], v[4:7]
	v_mfma_f32_16x16x32_bf16 v[0:3], v[186:189], v[228:231], v[0:3]
	s_setprio 0
	s_barrier
	s_add_i32 s90, s90, 2
	s_add_u32 s58, s58, 0x100
	s_addc_u32 s59, s59, 0
	s_add_u32 s88, s88, 0x100
	s_addc_u32 s89, s89, 0
.LBB0_1287:
	ds_read_b128 v[128:131], v181
	ds_read_b128 v[160:163], v181 offset:1024
	ds_read_b128 v[164:167], v181 offset:2048
	ds_read_b128 v[168:171], v181 offset:3072
	ds_read_b128 v[172:175], v203
	ds_read_b128 v[176:179], v203 offset:1024
	ds_read_b128 v[182:185], v203 offset:2048
	ds_read_b128 v[186:189], v203 offset:3072
	s_add_u32 s62, s58, 0xfffc0080
	s_addc_u32 s63, s59, -1
	s_cmp_eq_u32 s90, 12
	s_cselect_b32 s65, s51, s63
	s_cselect_b32 s64, s61, s62
	s_cselect_b32 s63, s49, s89
	s_cselect_b32 s62, s87, s88
	v_lshl_add_u64 v[232:233], s[58:59], 0, v[152:153]
	s_add_i32 m0, s15, 0xc000
	ds_read_b128 v[190:193], v208
	ds_read_b128 v[194:197], v208 offset:1024
	ds_read_b128 v[198:201], v208 offset:2048
	ds_read_b128 v[212:215], v208 offset:3072
	ds_read_b128 v[216:219], v208 offset:4096
	ds_read_b128 v[220:223], v208 offset:5120
	ds_read_b128 v[224:227], v208 offset:6144
	ds_read_b128 v[228:231], v208 offset:7168
	global_load_lds_dwordx4 v[232:233], off
	v_lshl_add_u64 v[232:233], s[58:59], 0, v[154:155]
	s_add_i32 m0, s15, 0xe000
	s_nop 0
	global_load_lds_dwordx4 v[232:233], off
	s_waitcnt vmcnt(8)
	s_waitcnt lgkmcnt(0)
	s_barrier
; #define PG8_STAGE(bufoff, gbase, voff) do { _Pragma("unroll") for (int _i = 0; _i < 2; ++_i) \
;         __builtin_amdgcn_global_load_lds((const unsigned*)((const char*)(gbase) + (voff)[_i]), (PG8_LAS unsigned*)(lds + (bufoff) + ldsw + _i * 8192), 16, 0, 0); } while (0)
; #define PG8_LDA(dst, b, h) do { _Pragma("unroll") for (int m = 0; m < 4; ++m) _Pragma("unroll") for (int k = 0; k < 2; ++k) dst[m][k] = *(const PG8_LAS bf16x8*)(lds + PG8_SA(b, h) + aoff + m * 2048 + k * 1024); } while (0)
; #define PG8_LDB(dst, b, h) do { _Pragma("unroll") for (int n = 0; n < 2; ++n) _Pragma("unroll") for (int k = 0; k < 2; ++k) dst[n][k] = *(const PG8_LAS bf16x8*)(lds + PG8_SB(b, h) + boff + n * 2048 + k * 1024); } while (0)
; #define PG8_MMA(ai, bj, At, Bt) do { __builtin_amdgcn_s_setprio(1); _Pragma("unroll") for (int m = 0; m < 4; ++m) _Pragma("unroll") for (int n = 0; n < 2; ++n) _Pragma("unroll") for (int k = 0; k < 2; ++k) \
;         acc[ai][bj][m][n] = __builtin_amdgcn_mfma_f32_16x16x32_bf16(Bt[n][k], At[m][k], acc[ai][bj][m][n], 0, 0, 0); __builtin_amdgcn_s_setprio(0); } while (0)
; #define PG8_WAIT_V(n) asm volatile("s_waitcnt vmcnt(" #n ")" ::: "memory")
; #define PG8_WAIT_L(n) asm volatile("s_waitcnt lgkmcnt(" #n ")" ::: "memory")
; #define PG8_BAR __builtin_amdgcn_s_barrier()
; #define PG8_SCHED __builtin_amdgcn_sched_barrier(0)
; template <class Epi, class Sched, bool ALIGN_EPI = false, bool SP2 = false>
; __device__ __forceinline__ void gemm_phase(PG8_LAS unsigned char* lds, const Gemm g, const Sched& S, const Epi& E) {
;     ...
;             PG8_LDB(B0, 0, 0); PG8_LDB(B1, 0, 1); PG8_SCHED; PG8_LDA(At, 0, 0); PG8_STAGE(PG8_SA(1, 1), a1 + hstep, voffA);
;             PG8_WAIT_V(8); PG8_WAIT_L(0); PG8_BAR; PG8_MMA(0, 0, At, B0); PG8_MMA(0, 1, At, B1); PG8_BAR; PG8_SCHED;
;             PG8_LDA(At, 0, 1); PG8_STAGE(PG8_SB(0, 0), b2, voffB); PG8_STAGE(PG8_SB(0, 1), b2 + hstep, voffB); PG8_STAGE(PG8_SA(0, 0), a2, voffA);
;             PG8_WAIT_V(8); PG8_WAIT_L(0); PG8_BAR; PG8_MMA(1, 0, At, B0); PG8_MMA(1, 1, At, B1); PG8_BAR; PG8_SCHED;
	s_setprio 1
	s_waitcnt lgkmcnt(0)
	v_mfma_f32_16x16x32_bf16 v[124:127], v[128:131], v[190:193], v[124:127]
	v_mfma_f32_16x16x32_bf16 v[120:123], v[164:167], v[190:193], v[120:123]
	v_mfma_f32_16x16x32_bf16 v[116:119], v[128:131], v[198:201], v[116:119]
	v_mfma_f32_16x16x32_bf16 v[112:115], v[164:167], v[198:201], v[112:115]
	v_mfma_f32_16x16x32_bf16 v[124:127], v[160:163], v[194:197], v[124:127]
	v_mfma_f32_16x16x32_bf16 v[120:123], v[168:171], v[194:197], v[120:123]
	v_mfma_f32_16x16x32_bf16 v[116:119], v[160:163], v[212:215], v[116:119]
	v_mfma_f32_16x16x32_bf16 v[112:115], v[168:171], v[212:215], v[112:115]
	v_mfma_f32_16x16x32_bf16 v[108:111], v[128:131], v[216:219], v[108:111]
	v_mfma_f32_16x16x32_bf16 v[104:107], v[164:167], v[216:219], v[104:107]
	v_mfma_f32_16x16x32_bf16 v[100:103], v[128:131], v[224:227], v[100:103]
	v_mfma_f32_16x16x32_bf16 v[96:99], v[164:167], v[224:227], v[96:99]
	v_mfma_f32_16x16x32_bf16 v[108:111], v[160:163], v[220:223], v[108:111]
	v_mfma_f32_16x16x32_bf16 v[104:107], v[168:171], v[220:223], v[104:107]
	v_mfma_f32_16x16x32_bf16 v[100:103], v[160:163], v[228:231], v[100:103]
	v_mfma_f32_16x16x32_bf16 v[96:99], v[168:171], v[228:231], v[96:99]
	s_setprio 0
	s_setprio 1
	v_mfma_f32_16x16x32_bf16 v[60:63], v[172:175], v[190:193], v[60:63]
	v_mfma_f32_16x16x32_bf16 v[56:59], v[182:185], v[190:193], v[56:59]
	v_mfma_f32_16x16x32_bf16 v[52:55], v[172:175], v[198:201], v[52:55]
	v_mfma_f32_16x16x32_bf16 v[48:51], v[182:185], v[198:201], v[48:51]
	v_mfma_f32_16x16x32_bf16 v[60:63], v[176:179], v[194:197], v[60:63]
	v_mfma_f32_16x16x32_bf16 v[56:59], v[186:189], v[194:197], v[56:59]
	v_mfma_f32_16x16x32_bf16 v[52:55], v[176:179], v[212:215], v[52:55]
	v_mfma_f32_16x16x32_bf16 v[48:51], v[186:189], v[212:215], v[48:51]
	v_mfma_f32_16x16x32_bf16 v[44:47], v[172:175], v[216:219], v[44:47]
	v_mfma_f32_16x16x32_bf16 v[40:43], v[182:185], v[216:219], v[40:43]
	v_mfma_f32_16x16x32_bf16 v[36:39], v[172:175], v[224:227], v[36:39]
	v_mfma_f32_16x16x32_bf16 v[32:35], v[182:185], v[224:227], v[32:35]
	v_mfma_f32_16x16x32_bf16 v[44:47], v[176:179], v[220:223], v[44:47]
	v_mfma_f32_16x16x32_bf16 v[40:43], v[186:189], v[220:223], v[40:43]
	v_mfma_f32_16x16x32_bf16 v[36:39], v[176:179], v[228:231], v[36:39]
	v_mfma_f32_16x16x32_bf16 v[32:35], v[186:189], v[228:231], v[32:35]
	s_setprio 0
	s_barrier
	s_add_i32 s78, s75, s14
	v_lshl_add_u64 v[232:233], s[62:63], 0, v[134:135]
	s_mov_b32 m0, s78
	ds_read_b128 v[190:193], v208 offset:16384
	ds_read_b128 v[194:197], v208 offset:17408
	ds_read_b128 v[198:201], v208 offset:18432
	ds_read_b128 v[212:215], v208 offset:19456
	ds_read_b128 v[216:219], v208 offset:20480
	ds_read_b128 v[220:223], v208 offset:21504
	ds_read_b128 v[224:227], v208 offset:22528
	ds_read_b128 v[228:231], v208 offset:23552
	global_load_lds_dwordx4 v[232:233], off
	s_add_i32 m0, s78, 0x2000
	s_add_u32 s78, s62, 0x40000
	v_lshl_add_u64 v[234:235], s[62:63], 0, v[138:139]
	s_addc_u32 s79, s63, 0
	s_add_i32 s91, s76, s14
	global_load_lds_dwordx4 v[234:235], off
	v_lshl_add_u64 v[236:237], s[78:79], 0, v[134:135]
	s_mov_b32 m0, s91
	global_load_lds_dwordx4 v[236:237], off
	v_lshl_add_u64 v[236:237], s[78:79], 0, v[138:139]
	s_add_i32 m0, s91, 0x2000
	s_nop 0
	global_load_lds_dwordx4 v[236:237], off
	s_waitcnt vmcnt(6)
	s_waitcnt lgkmcnt(0)
	s_barrier
	s_setprio 1
	s_waitcnt lgkmcnt(0)
	v_mfma_f32_16x16x32_bf16 v[92:95], v[128:131], v[190:193], v[92:95]
	v_mfma_f32_16x16x32_bf16 v[88:91], v[164:167], v[190:193], v[88:91]
	v_mfma_f32_16x16x32_bf16 v[84:87], v[128:131], v[198:201], v[84:87]
	v_mfma_f32_16x16x32_bf16 v[80:83], v[164:167], v[198:201], v[80:83]
	v_mfma_f32_16x16x32_bf16 v[92:95], v[160:163], v[194:197], v[92:95]
	v_mfma_f32_16x16x32_bf16 v[88:91], v[168:171], v[194:197], v[88:91]
	v_mfma_f32_16x16x32_bf16 v[84:87], v[160:163], v[212:215], v[84:87]
	v_mfma_f32_16x16x32_bf16 v[80:83], v[168:171], v[212:215], v[80:83]
	v_mfma_f32_16x16x32_bf16 v[76:79], v[128:131], v[216:219], v[76:79]
	v_mfma_f32_16x16x32_bf16 v[72:75], v[164:167], v[216:219], v[72:75]
	v_mfma_f32_16x16x32_bf16 v[68:71], v[128:131], v[224:227], v[68:71]
	v_mfma_f32_16x16x32_bf16 v[64:67], v[164:167], v[224:227], v[64:67]
	v_mfma_f32_16x16x32_bf16 v[76:79], v[160:163], v[220:223], v[76:79]
	v_mfma_f32_16x16x32_bf16 v[72:75], v[168:171], v[220:223], v[72:75]
	v_lshl_add_u64 v[236:237], s[64:65], 0, v[132:133]
	s_mov_b32 m0, s15
	s_nop 0
	global_load_lds_dwordx4 v[236:237], off
	v_mfma_f32_16x16x32_bf16 v[68:71], v[160:163], v[228:231], v[68:71]
	v_mfma_f32_16x16x32_bf16 v[64:67], v[168:171], v[228:231], v[64:67]
	s_setprio 0
	s_setprio 1
	v_mfma_f32_16x16x32_bf16 v[28:31], v[172:175], v[190:193], v[28:31]
	v_mfma_f32_16x16x32_bf16 v[24:27], v[182:185], v[190:193], v[24:27]
	v_mfma_f32_16x16x32_bf16 v[20:23], v[172:175], v[198:201], v[20:23]
	v_mfma_f32_16x16x32_bf16 v[16:19], v[182:185], v[198:201], v[16:19]
	v_mfma_f32_16x16x32_bf16 v[28:31], v[176:179], v[194:197], v[28:31]
	v_mfma_f32_16x16x32_bf16 v[24:27], v[186:189], v[194:197], v[24:27]
	v_mfma_f32_16x16x32_bf16 v[20:23], v[176:179], v[212:215], v[20:23]
	v_mfma_f32_16x16x32_bf16 v[16:19], v[186:189], v[212:215], v[16:19]
	v_mfma_f32_16x16x32_bf16 v[12:15], v[172:175], v[216:219], v[12:15]
	v_mfma_f32_16x16x32_bf16 v[8:11], v[182:185], v[216:219], v[8:11]
	v_mfma_f32_16x16x32_bf16 v[4:7], v[172:175], v[224:227], v[4:7]
	v_mfma_f32_16x16x32_bf16 v[0:3], v[182:185], v[224:227], v[0:3]
	v_mfma_f32_16x16x32_bf16 v[12:15], v[176:179], v[220:223], v[12:15]
	v_mfma_f32_16x16x32_bf16 v[8:11], v[186:189], v[220:223], v[8:11]
	v_lshl_add_u64 v[238:239], s[64:65], 0, v[136:137]
	s_mov_b32 m0, s33
	s_nop 0
	global_load_lds_dwordx4 v[238:239], off
	v_mfma_f32_16x16x32_bf16 v[4:7], v[176:179], v[228:231], v[4:7]
	v_mfma_f32_16x16x32_bf16 v[0:3], v[186:189], v[228:231], v[0:3]
	s_setprio 0
	s_barrier
; #define PG8_STAGE(bufoff, gbase, voff) do { _Pragma("unroll") for (int _i = 0; _i < 2; ++_i) \
;         __builtin_amdgcn_global_load_lds((const unsigned*)((const char*)(gbase) + (voff)[_i]), (PG8_LAS unsigned*)(lds + (bufoff) + ldsw + _i * 8192), 16, 0, 0); } while (0)
; #define PG8_LDA(dst, b, h) do { _Pragma("unroll") for (int m = 0; m < 4; ++m) _Pragma("unroll") for (int k = 0; k < 2; ++k) dst[m][k] = *(const PG8_LAS bf16x8*)(lds + PG8_SA(b, h) + aoff + m * 2048 + k * 1024); } while (0)
; #define PG8_LDB(dst, b, h) do { _Pragma("unroll") for (int n = 0; n < 2; ++n) _Pragma("unroll") for (int k = 0; k < 2; ++k) dst[n][k] = *(const PG8_LAS bf16x8*)(lds + PG8_SB(b, h) + boff + n * 2048 + k * 1024); } while (0)
; #define PG8_MMA(ai, bj, At, Bt) do { __builtin_amdgcn_s_setprio(1); _Pragma("unroll") for (int m = 0; m < 4; ++m) _Pragma("unroll") for (int n = 0; n < 2; ++n) _Pragma("unroll") for (int k = 0; k < 2; ++k) \
;         acc[ai][bj][m][n] = __builtin_amdgcn_mfma_f32_16x16x32_bf16(Bt[n][k], At[m][k], acc[ai][bj][m][n], 0, 0, 0); __builtin_amdgcn_s_setprio(0); } while (0)
; #define PG8_WAIT_V(n) asm volatile("s_waitcnt vmcnt(" #n ")" ::: "memory")
; #define PG8_WAIT_L(n) asm volatile("s_waitcnt lgkmcnt(" #n ")" ::: "memory")
; #define PG8_BAR __builtin_amdgcn_s_barrier()
; #define PG8_SCHED __builtin_amdgcn_sched_barrier(0)
; template <class Epi, class Sched, bool ALIGN_EPI = false, bool SP2 = false>
; __device__ __forceinline__ void gemm_phase(PG8_LAS unsigned char* lds, const Gemm g, const Sched& S, const Epi& E) {
;     ...
;             PG8_LDB(B0, 1, 0); PG8_LDB(B1, 1, 1); PG8_SCHED; PG8_LDA(At, 1, 0); PG8_STAGE(PG8_SA(0, 1), a2 + hstep, voffA);
;             PG8_WAIT_V(8); PG8_WAIT_L(0); PG8_BAR; PG8_MMA(0, 0, At, B0); PG8_MMA(0, 1, At, B1); PG8_BAR; PG8_SCHED;
	s_add_i32 s78, 0, 0x18000
	v_add_u32_e32 v140, s78, v147
	s_add_i32 s79, 0, 0x1c000
	ds_read_b128 v[128:131], v140
	ds_read_b128 v[160:163], v140 offset:1024
	ds_read_b128 v[164:167], v140 offset:2048
	ds_read_b128 v[168:171], v140 offset:3072
	v_add_u32_e32 v140, s79, v147
	ds_read_b128 v[172:175], v140
	ds_read_b128 v[176:179], v140 offset:1024
	ds_read_b128 v[182:185], v140 offset:2048
	ds_read_b128 v[186:189], v140 offset:3072
	s_add_u32 s64, s64, 0x40000
	s_addc_u32 s65, s65, 0
	s_mov_b32 m0, s34
	v_lshl_add_u64 v[240:241], s[64:65], 0, v[132:133]
	ds_read_b128 v[190:193], v208 offset:32768
	ds_read_b128 v[194:197], v208 offset:33792
	ds_read_b128 v[198:201], v208 offset:34816
	ds_read_b128 v[212:215], v208 offset:35840
	ds_read_b128 v[216:219], v208 offset:36864
	ds_read_b128 v[220:223], v208 offset:37888
	ds_read_b128 v[224:227], v208 offset:38912
	ds_read_b128 v[228:231], v208 offset:39936
	global_load_lds_dwordx4 v[240:241], off
	v_lshl_add_u64 v[240:241], s[64:65], 0, v[136:137]
	s_mov_b32 m0, s57
	s_nop 0
	global_load_lds_dwordx4 v[240:241], off
	s_waitcnt vmcnt(8)
	s_waitcnt lgkmcnt(0)
	s_barrier
	s_setprio 1
	s_waitcnt lgkmcnt(0)
	v_mfma_f32_16x16x32_bf16 v[124:127], v[128:131], v[190:193], v[124:127]
	v_mfma_f32_16x16x32_bf16 v[120:123], v[164:167], v[190:193], v[120:123]
	v_mfma_f32_16x16x32_bf16 v[116:119], v[128:131], v[198:201], v[116:119]
	v_mfma_f32_16x16x32_bf16 v[112:115], v[164:167], v[198:201], v[112:115]
	v_mfma_f32_16x16x32_bf16 v[124:127], v[160:163], v[194:197], v[124:127]
	v_mfma_f32_16x16x32_bf16 v[120:123], v[168:171], v[194:197], v[120:123]
	v_mfma_f32_16x16x32_bf16 v[116:119], v[160:163], v[212:215], v[116:119]
	v_mfma_f32_16x16x32_bf16 v[112:115], v[168:171], v[212:215], v[112:115]
	v_mfma_f32_16x16x32_bf16 v[108:111], v[128:131], v[216:219], v[108:111]
	v_mfma_f32_16x16x32_bf16 v[104:107], v[164:167], v[216:219], v[104:107]
	v_mfma_f32_16x16x32_bf16 v[100:103], v[128:131], v[224:227], v[100:103]
	v_mfma_f32_16x16x32_bf16 v[96:99], v[164:167], v[224:227], v[96:99]
	v_mfma_f32_16x16x32_bf16 v[108:111], v[160:163], v[220:223], v[108:111]
	v_mfma_f32_16x16x32_bf16 v[104:107], v[168:171], v[220:223], v[104:107]
	v_mfma_f32_16x16x32_bf16 v[100:103], v[160:163], v[228:231], v[100:103]
	v_mfma_f32_16x16x32_bf16 v[96:99], v[168:171], v[228:231], v[96:99]
	s_setprio 0
	s_setprio 1
	v_mfma_f32_16x16x32_bf16 v[60:63], v[172:175], v[190:193], v[60:63]
	v_mfma_f32_16x16x32_bf16 v[56:59], v[182:185], v[190:193], v[56:59]
	v_mfma_f32_16x16x32_bf16 v[52:55], v[172:175], v[198:201], v[52:55]
	v_mfma_f32_16x16x32_bf16 v[48:51], v[182:185], v[198:201], v[48:51]
	v_mfma_f32_16x16x32_bf16 v[60:63], v[176:179], v[194:197], v[60:63]
	v_mfma_f32_16x16x32_bf16 v[56:59], v[186:189], v[194:197], v[56:59]
	v_mfma_f32_16x16x32_bf16 v[52:55], v[176:179], v[212:215], v[52:55]
	v_mfma_f32_16x16x32_bf16 v[48:51], v[186:189], v[212:215], v[48:51]
	v_mfma_f32_16x16x32_bf16 v[44:47], v[172:175], v[216:219], v[44:47]
	v_mfma_f32_16x16x32_bf16 v[40:43], v[182:185], v[216:219], v[40:43]
	v_mfma_f32_16x16x32_bf16 v[36:39], v[172:175], v[224:227], v[36:39]
	v_mfma_f32_16x16x32_bf16 v[32:35], v[182:185], v[224:227], v[32:35]
	v_mfma_f32_16x16x32_bf16 v[44:47], v[176:179], v[220:223], v[44:47]
	v_mfma_f32_16x16x32_bf16 v[40:43], v[186:189], v[220:223], v[40:43]
	v_mfma_f32_16x16x32_bf16 v[36:39], v[176:179], v[228:231], v[36:39]
	v_mfma_f32_16x16x32_bf16 v[32:35], v[186:189], v[228:231], v[32:35]
	s_setprio 0
	s_barrier
; #define PG8_STAGE(bufoff, gbase, voff) do { _Pragma("unroll") for (int _i = 0; _i < 2; ++_i) \
;         __builtin_amdgcn_global_load_lds((const unsigned*)((const char*)(gbase) + (voff)[_i]), (PG8_LAS unsigned*)(lds + (bufoff) + ldsw + _i * 8192), 16, 0, 0); } while (0)
; #define PG8_LDA(dst, b, h) do { _Pragma("unroll") for (int m = 0; m < 4; ++m) _Pragma("unroll") for (int k = 0; k < 2; ++k) dst[m][k] = *(const PG8_LAS bf16x8*)(lds + PG8_SA(b, h) + aoff + m * 2048 + k * 1024); } while (0)
; #define PG8_MMA(ai, bj, At, Bt) do { __builtin_amdgcn_s_setprio(1); _Pragma("unroll") for (int m = 0; m < 4; ++m) _Pragma("unroll") for (int n = 0; n < 2; ++n) _Pragma("unroll") for (int k = 0; k < 2; ++k) \
;         acc[ai][bj][m][n] = __builtin_amdgcn_mfma_f32_16x16x32_bf16(Bt[n][k], At[m][k], acc[ai][bj][m][n], 0, 0, 0); __builtin_amdgcn_s_setprio(0); } while (0)
; #define PG8_WAIT_V(n) asm volatile("s_waitcnt vmcnt(" #n ")" ::: "memory")
; #define PG8_WAIT_L(n) asm volatile("s_waitcnt lgkmcnt(" #n ")" ::: "memory")
; #define PG8_BAR __builtin_amdgcn_s_barrier()
; #define PG8_SCHED __builtin_amdgcn_sched_barrier(0)
; template <class Epi, class Sched, bool ALIGN_EPI = false, bool SP2 = false>
; __device__ __forceinline__ void gemm_phase(PG8_LAS unsigned char* lds, const Gemm g, const Sched& S, const Epi& E) {
;     ...
;             PG8_LDA(At, 1, 1); PG8_STAGE(PG8_SB(1, 0), b3, voffB); PG8_STAGE(PG8_SB(1, 1), b3 + hstep, voffB); PG8_STAGE(PG8_SA(1, 0), a3, voffA);
;             PG8_WAIT_V(8); PG8_WAIT_L(0); PG8_BAR; PG8_MMA(1, 0, At, B0); PG8_MMA(1, 1, At, B1); PG8_BAR; PG8_SCHED;
;     ...
;         if constexpr (ALIGN_EPI) { if (wr == 0) PG8_BAR; }
	s_add_i32 s64, s78, s14
	v_lshl_add_u64 v[232:233], v[232:233], 0, s[42:43]
	s_mov_b32 m0, s64
	ds_read_b128 v[190:193], v208 offset:49152
	ds_read_b128 v[194:197], v208 offset:50176
	ds_read_b128 v[198:201], v208 offset:51200
	ds_read_b128 v[212:215], v208 offset:52224
	ds_read_b128 v[216:219], v208 offset:53248
	ds_read_b128 v[220:223], v208 offset:54272
	ds_read_b128 v[224:227], v208 offset:55296
	ds_read_b128 v[228:231], v208 offset:56320
	global_load_lds_dwordx4 v[232:233], off
	s_add_i32 m0, s64, 0x2000
	s_add_u32 s62, s62, 0x40080
	v_lshl_add_u64 v[232:233], v[234:235], 0, s[42:43]
	s_addc_u32 s63, s63, 0
	s_add_i32 s64, s79, s14
	global_load_lds_dwordx4 v[232:233], off
	v_lshl_add_u64 v[232:233], s[62:63], 0, v[134:135]
	s_mov_b32 m0, s64
	s_nop 0
	global_load_lds_dwordx4 v[232:233], off
	v_lshl_add_u64 v[232:233], s[62:63], 0, v[138:139]
	s_add_i32 m0, s64, 0x2000
	s_nop 0
	global_load_lds_dwordx4 v[232:233], off
	s_waitcnt vmcnt(6)
	s_waitcnt lgkmcnt(0)
	s_barrier
	s_setprio 1
	s_waitcnt lgkmcnt(0)
	v_mfma_f32_16x16x32_bf16 v[92:95], v[128:131], v[190:193], v[92:95]
	v_mfma_f32_16x16x32_bf16 v[88:91], v[164:167], v[190:193], v[88:91]
	v_mfma_f32_16x16x32_bf16 v[84:87], v[128:131], v[198:201], v[84:87]
	v_mfma_f32_16x16x32_bf16 v[80:83], v[164:167], v[198:201], v[80:83]
	v_mfma_f32_16x16x32_bf16 v[92:95], v[160:163], v[194:197], v[92:95]
	v_mfma_f32_16x16x32_bf16 v[88:91], v[168:171], v[194:197], v[88:91]
	v_mfma_f32_16x16x32_bf16 v[84:87], v[160:163], v[212:215], v[84:87]
	v_mfma_f32_16x16x32_bf16 v[80:83], v[168:171], v[212:215], v[80:83]
	v_mfma_f32_16x16x32_bf16 v[76:79], v[128:131], v[216:219], v[76:79]
	v_mfma_f32_16x16x32_bf16 v[72:75], v[164:167], v[216:219], v[72:75]
	v_mfma_f32_16x16x32_bf16 v[68:71], v[128:131], v[224:227], v[68:71]
	v_mfma_f32_16x16x32_bf16 v[64:67], v[164:167], v[224:227], v[64:67]
	v_mfma_f32_16x16x32_bf16 v[76:79], v[160:163], v[220:223], v[76:79]
	v_mfma_f32_16x16x32_bf16 v[72:75], v[168:171], v[220:223], v[72:75]
	v_lshl_add_u64 v[232:233], v[236:237], 0, s[42:43]
	s_mov_b32 m0, s67
	s_nop 0
	global_load_lds_dwordx4 v[232:233], off
	v_mfma_f32_16x16x32_bf16 v[68:71], v[160:163], v[228:231], v[68:71]
	v_mfma_f32_16x16x32_bf16 v[64:67], v[168:171], v[228:231], v[64:67]
	s_setprio 0
	s_setprio 1
	v_mfma_f32_16x16x32_bf16 v[28:31], v[172:175], v[190:193], v[28:31]
	v_mfma_f32_16x16x32_bf16 v[24:27], v[182:185], v[190:193], v[24:27]
	v_mfma_f32_16x16x32_bf16 v[20:23], v[172:175], v[198:201], v[20:23]
	v_mfma_f32_16x16x32_bf16 v[16:19], v[182:185], v[198:201], v[16:19]
	v_mfma_f32_16x16x32_bf16 v[28:31], v[176:179], v[194:197], v[28:31]
	v_mfma_f32_16x16x32_bf16 v[24:27], v[186:189], v[194:197], v[24:27]
	v_mfma_f32_16x16x32_bf16 v[20:23], v[176:179], v[212:215], v[20:23]
	v_mfma_f32_16x16x32_bf16 v[16:19], v[186:189], v[212:215], v[16:19]
	v_mfma_f32_16x16x32_bf16 v[12:15], v[172:175], v[216:219], v[12:15]
	v_mfma_f32_16x16x32_bf16 v[8:11], v[182:185], v[216:219], v[8:11]
	v_mfma_f32_16x16x32_bf16 v[4:7], v[172:175], v[224:227], v[4:7]
	v_mfma_f32_16x16x32_bf16 v[0:3], v[182:185], v[224:227], v[0:3]
	v_mfma_f32_16x16x32_bf16 v[12:15], v[176:179], v[220:223], v[12:15]
	v_mfma_f32_16x16x32_bf16 v[8:11], v[186:189], v[220:223], v[8:11]
	v_lshl_add_u64 v[232:233], v[238:239], 0, s[42:43]
	s_mov_b32 m0, s74
	s_nop 0
	global_load_lds_dwordx4 v[232:233], off
	v_mfma_f32_16x16x32_bf16 v[4:7], v[176:179], v[228:231], v[4:7]
	v_mfma_f32_16x16x32_bf16 v[0:3], v[186:189], v[228:231], v[0:3]
	s_setprio 0
	s_barrier
	s_add_i32 s90, s90, 2
	s_add_u32 s58, s58, 0x100
	s_addc_u32 s59, s59, 0
	s_add_u32 s88, s88, 0x100
	s_addc_u32 s89, s89, 0
	s_cmp_gt_u32 s90, 13
	s_cbranch_scc0 .LBB0_1287
	s_and_b64 vcc, exec, s[44:45]
	s_cbranch_vccz .LBB0_1290
	s_barrier

; #define PG8_STAGE(bufoff, gbase, voff) do { _Pragma("unroll") for (int _i = 0; _i < 2; ++_i) \
;         __builtin_amdgcn_global_load_lds((const unsigned*)((const char*)(gbase) + (voff)[_i]), (PG8_LAS unsigned*)(lds + (bufoff) + ldsw + _i * 8192), 16, 0, 0); } while (0)
; #define PG8_LDA(dst, b, h) do { _Pragma("unroll") for (int m = 0; m < 4; ++m) _Pragma("unroll") for (int k = 0; k < 2; ++k) dst[m][k] = *(const PG8_LAS bf16x8*)(lds + PG8_SA(b, h) + aoff + m * 2048 + k * 1024); } while (0)
; #define PG8_LDB(dst, b, h) do { _Pragma("unroll") for (int n = 0; n < 2; ++n) _Pragma("unroll") for (int k = 0; k < 2; ++k) dst[n][k] = *(const PG8_LAS bf16x8*)(lds + PG8_SB(b, h) + boff + n * 2048 + k * 1024); } while (0)
; #define PG8_MMA(ai, bj, At, Bt) do { __builtin_amdgcn_s_setprio(1); _Pragma("unroll") for (int m = 0; m < 4; ++m) _Pragma("unroll") for (int n = 0; n < 2; ++n) _Pragma("unroll") for (int k = 0; k < 2; ++k) \
;         acc[ai][bj][m][n] = __builtin_amdgcn_mfma_f32_16x16x32_bf16(Bt[n][k], At[m][k], acc[ai][bj][m][n], 0, 0, 0); __builtin_amdgcn_s_setprio(0); } while (0)
; #define PG8_BAR __builtin_amdgcn_s_barrier()
; template <class Epi, class Sched, bool ALIGN_EPI = false, bool SP2 = false>
; __device__ __forceinline__ void gemm_phase(PG8_LAS unsigned char* lds, const Gemm g, const Sched& S, const Epi& E) {
;     ...
;         const bool has_next = S.next(ui + 1, nxt);
;         const char* nA = has_next ? (const char*)g.A + (size_t)nxt.pm * tstep : cA; const char* nB = has_next ? (const char*)g.Bt + (size_t)nxt.pn * tstep : cB;
;         for (int t = 0; t < nt; t += 2) {
;             const bool last = (t == nt - 2);
;             const char* a1 = cA + (size_t)(t + 1) * kstep;
;             const char* a2 = last ? nA : cA + (size_t)(t + 2) * kstep; const char* b2 = last ? nB : cB + (size_t)(t + 2) * kstep;
;             const char* a3 = a2 + kstep; const char* b3 = b2 + kstep;
;             if (last && has_next) S.a_ready(nxt);
;             if constexpr (SP2) {
;             PG8_LDB(B0, 0, 0); PG8_LDB(B1, 0, 1); PG8_SCHED; PG8_LDA(At, 0, 0); PG8_STAGE(PG8_SA(1, 1), a1 + hstep, voffA);
;             PG8_WAIT_V(8); PG8_WAIT_L(0); PG8_BAR; PG8_MMA(0, 0, At, B0); PG8_MMA(0, 1, At, B1); PG8_BAR; PG8_SCHED;
;             PG8_LDA(At, 0, 1); PG8_STAGE(PG8_SB(0, 0), b2, voffB); PG8_STAGE(PG8_SB(0, 1), b2 + hstep, voffB); PG8_STAGE(PG8_SA(0, 0), a2, voffA);
.LBB0_1592:
	s_ashr_i32 s39, s38, 31
	s_lshl_b64 s[42:43], s[38:39], 19
	s_add_u32 s42, s40, s42
	s_addc_u32 s43, s41, s43
	s_and_b64 s[44:45], s[10:11], exec
	s_cselect_b32 s39, s43, s51
	s_cselect_b32 s47, s42, s50
	s_ashr_i32 s37, s36, 31
	s_lshl_b64 s[44:45], s[36:37], 19
	v_readlane_b32 s54, v250, 11
	v_readlane_b32 s55, v250, 12
	s_add_u32 s44, s54, s44
	s_addc_u32 s45, s55, s45
	s_and_b64 s[54:55], s[10:11], exec
	s_cselect_b32 s37, s45, s53
	s_cselect_b32 s64, s44, s52
	s_add_u32 s50, s50, 0x40080
	s_addc_u32 s51, s51, 0
	s_add_u32 s65, s52, 0x100
	s_addc_u32 s66, s53, 0
	s_mov_b32 s67, -2
	s_waitcnt lgkmcnt(0)
	ds_read_b128 v[146:149], v152
	ds_read_b128 v[156:159], v152 offset:1024
	ds_read_b128 v[160:163], v152 offset:2048
	ds_read_b128 v[164:167], v152 offset:3072
	ds_read_b128 v[168:171], v153
	ds_read_b128 v[172:175], v153 offset:1024
	ds_read_b128 v[180:183], v153 offset:2048
	ds_read_b128 v[184:187], v153 offset:3072
	s_add_u32 s52, s50, 0xfffc0080
	s_addc_u32 s53, s51, -1
	s_cmp_eq_u32 s67, 12
	s_cselect_b32 s55, s39, s53
	s_cselect_b32 s54, s47, s52
	s_cselect_b32 s53, s37, s66
	s_cselect_b32 s52, s64, s65
	v_lshl_add_u64 v[200:201], s[50:51], 0, v[136:137]
	s_add_i32 m0, s33, 0xc000
	ds_read_b128 v[188:191], v154
	ds_read_b128 v[192:195], v154 offset:1024
	ds_read_b128 v[196:199], v154 offset:2048
	ds_read_b128 v[206:209], v154 offset:3072
	ds_read_b128 v[210:213], v154 offset:4096
	ds_read_b128 v[214:217], v154 offset:5120
	ds_read_b128 v[218:221], v154 offset:6144
	ds_read_b128 v[222:225], v154 offset:7168
	global_load_lds_dwordx4 v[200:201], off
	v_lshl_add_u64 v[200:201], s[50:51], 0, v[138:139]
	s_add_i32 m0, s33, 0xe000
	s_nop 0
	global_load_lds_dwordx4 v[200:201], off
	s_waitcnt vmcnt(8)
	s_waitcnt lgkmcnt(0)
	s_barrier
	s_setprio 1
	s_waitcnt lgkmcnt(0)
	v_mfma_f32_16x16x32_bf16 v[124:127], v[146:149], v[188:191], 0
	v_mfma_f32_16x16x32_bf16 v[120:123], v[160:163], v[188:191], 0
	v_mfma_f32_16x16x32_bf16 v[108:111], v[146:149], v[196:199], 0
	v_mfma_f32_16x16x32_bf16 v[104:107], v[160:163], v[196:199], 0
	v_mfma_f32_16x16x32_bf16 v[124:127], v[156:159], v[192:195], v[124:127]
	v_mfma_f32_16x16x32_bf16 v[120:123], v[164:167], v[192:195], v[120:123]
	v_mfma_f32_16x16x32_bf16 v[108:111], v[156:159], v[206:209], v[108:111]
	v_mfma_f32_16x16x32_bf16 v[104:107], v[164:167], v[206:209], v[104:107]
	v_mfma_f32_16x16x32_bf16 v[92:95], v[146:149], v[210:213], 0
	v_mfma_f32_16x16x32_bf16 v[88:91], v[160:163], v[210:213], 0
	v_mfma_f32_16x16x32_bf16 v[76:79], v[146:149], v[218:221], 0
	v_mfma_f32_16x16x32_bf16 v[72:75], v[160:163], v[218:221], 0
	v_mfma_f32_16x16x32_bf16 v[92:95], v[156:159], v[214:217], v[92:95]
	v_mfma_f32_16x16x32_bf16 v[88:91], v[164:167], v[214:217], v[88:91]
	v_mfma_f32_16x16x32_bf16 v[76:79], v[156:159], v[222:225], v[76:79]
	v_mfma_f32_16x16x32_bf16 v[72:75], v[164:167], v[222:225], v[72:75]
	s_setprio 0
	s_setprio 1
	v_mfma_f32_16x16x32_bf16 v[116:119], v[168:171], v[188:191], 0
	v_mfma_f32_16x16x32_bf16 v[112:115], v[180:183], v[188:191], 0
	v_mfma_f32_16x16x32_bf16 v[100:103], v[168:171], v[196:199], 0
	v_mfma_f32_16x16x32_bf16 v[96:99], v[180:183], v[196:199], 0
	v_mfma_f32_16x16x32_bf16 v[116:119], v[172:175], v[192:195], v[116:119]
	v_mfma_f32_16x16x32_bf16 v[112:115], v[184:187], v[192:195], v[112:115]
	v_mfma_f32_16x16x32_bf16 v[100:103], v[172:175], v[206:209], v[100:103]
	v_mfma_f32_16x16x32_bf16 v[96:99], v[184:187], v[206:209], v[96:99]
	v_mfma_f32_16x16x32_bf16 v[84:87], v[168:171], v[210:213], 0
	v_mfma_f32_16x16x32_bf16 v[80:83], v[180:183], v[210:213], 0
	v_mfma_f32_16x16x32_bf16 v[68:71], v[168:171], v[218:221], 0
	v_mfma_f32_16x16x32_bf16 v[64:67], v[180:183], v[218:221], 0
	v_mfma_f32_16x16x32_bf16 v[84:87], v[172:175], v[214:217], v[84:87]
	v_mfma_f32_16x16x32_bf16 v[80:83], v[184:187], v[214:217], v[80:83]
	v_mfma_f32_16x16x32_bf16 v[68:71], v[172:175], v[222:225], v[68:71]
	v_mfma_f32_16x16x32_bf16 v[64:67], v[184:187], v[222:225], v[64:67]
	s_setprio 0
	s_barrier
	s_add_i32 s74, s60, s15
	v_lshl_add_u64 v[200:201], s[52:53], 0, v[130:131]
	s_mov_b32 m0, s74
	ds_read_b128 v[188:191], v154 offset:16384
	ds_read_b128 v[192:195], v154 offset:17408
	ds_read_b128 v[196:199], v154 offset:18432
	ds_read_b128 v[206:209], v154 offset:19456
	ds_read_b128 v[210:213], v154 offset:20480
	ds_read_b128 v[214:217], v154 offset:21504
	ds_read_b128 v[218:221], v154 offset:22528
	ds_read_b128 v[222:225], v154 offset:23552
	global_load_lds_dwordx4 v[200:201], off
	s_add_i32 m0, s74, 0x2000
	s_add_u32 s74, s52, 0x40000
	v_lshl_add_u64 v[226:227], s[52:53], 0, v[134:135]
	s_addc_u32 s75, s53, 0
	s_add_i32 s76, s61, s15
	global_load_lds_dwordx4 v[226:227], off
	v_lshl_add_u64 v[228:229], s[74:75], 0, v[130:131]
	s_mov_b32 m0, s76
	global_load_lds_dwordx4 v[228:229], off
	v_lshl_add_u64 v[228:229], s[74:75], 0, v[134:135]
	s_add_i32 m0, s76, 0x2000
	s_nop 0
	global_load_lds_dwordx4 v[228:229], off
	s_waitcnt vmcnt(6)
	s_waitcnt lgkmcnt(0)
	s_barrier
; #define PG8_STAGE(bufoff, gbase, voff) do { _Pragma("unroll") for (int _i = 0; _i < 2; ++_i) \
;         __builtin_amdgcn_global_load_lds((const unsigned*)((const char*)(gbase) + (voff)[_i]), (PG8_LAS unsigned*)(lds + (bufoff) + ldsw + _i * 8192), 16, 0, 0); } while (0)
; #define PG8_LDA(dst, b, h) do { _Pragma("unroll") for (int m = 0; m < 4; ++m) _Pragma("unroll") for (int k = 0; k < 2; ++k) dst[m][k] = *(const PG8_LAS bf16x8*)(lds + PG8_SA(b, h) + aoff + m * 2048 + k * 1024); } while (0)
; #define PG8_LDB(dst, b, h) do { _Pragma("unroll") for (int n = 0; n < 2; ++n) _Pragma("unroll") for (int k = 0; k < 2; ++k) dst[n][k] = *(const PG8_LAS bf16x8*)(lds + PG8_SB(b, h) + boff + n * 2048 + k * 1024); } while (0)
; #define PG8_MMA(ai, bj, At, Bt) do { __builtin_amdgcn_s_setprio(1); _Pragma("unroll") for (int m = 0; m < 4; ++m) _Pragma("unroll") for (int n = 0; n < 2; ++n) _Pragma("unroll") for (int k = 0; k < 2; ++k) \
;         acc[ai][bj][m][n] = __builtin_amdgcn_mfma_f32_16x16x32_bf16(Bt[n][k], At[m][k], acc[ai][bj][m][n], 0, 0, 0); __builtin_amdgcn_s_setprio(0); } while (0)
; #define PG8_WAIT_V(n) asm volatile("s_waitcnt vmcnt(" #n ")" ::: "memory")
; #define PG8_WAIT_L(n) asm volatile("s_waitcnt lgkmcnt(" #n ")" ::: "memory")
; #define PG8_BAR __builtin_amdgcn_s_barrier()
; #define PG8_SCHED __builtin_amdgcn_sched_barrier(0)
; template <class Epi, class Sched, bool ALIGN_EPI = false, bool SP2 = false>
; __device__ __forceinline__ void gemm_phase(PG8_LAS unsigned char* lds, const Gemm g, const Sched& S, const Epi& E) {
;     ...
;             PG8_WAIT_V(8); PG8_WAIT_L(0); PG8_BAR; PG8_MMA(1, 0, At, B0); PG8_MMA(1, 1, At, B1); PG8_BAR; PG8_SCHED;
;             PG8_LDB(B0, 1, 0); PG8_LDB(B1, 1, 1); PG8_SCHED; PG8_LDA(At, 1, 0); PG8_STAGE(PG8_SA(0, 1), a2 + hstep, voffA);
;             PG8_WAIT_V(8); PG8_WAIT_L(0); PG8_BAR; PG8_MMA(0, 0, At, B0); PG8_MMA(0, 1, At, B1); PG8_BAR; PG8_SCHED;
	s_setprio 1
	s_waitcnt lgkmcnt(0)
	v_mfma_f32_16x16x32_bf16 v[60:63], v[146:149], v[188:191], 0
	v_mfma_f32_16x16x32_bf16 v[56:59], v[160:163], v[188:191], 0
	v_mfma_f32_16x16x32_bf16 v[44:47], v[146:149], v[196:199], 0
	v_mfma_f32_16x16x32_bf16 v[40:43], v[160:163], v[196:199], 0
	v_mfma_f32_16x16x32_bf16 v[60:63], v[156:159], v[192:195], v[60:63]
	v_mfma_f32_16x16x32_bf16 v[56:59], v[164:167], v[192:195], v[56:59]
	v_mfma_f32_16x16x32_bf16 v[44:47], v[156:159], v[206:209], v[44:47]
	v_mfma_f32_16x16x32_bf16 v[40:43], v[164:167], v[206:209], v[40:43]
	v_mfma_f32_16x16x32_bf16 v[28:31], v[146:149], v[210:213], 0
	v_mfma_f32_16x16x32_bf16 v[24:27], v[160:163], v[210:213], 0
	v_mfma_f32_16x16x32_bf16 v[12:15], v[146:149], v[218:221], 0
	v_mfma_f32_16x16x32_bf16 v[8:11], v[160:163], v[218:221], 0
	v_mfma_f32_16x16x32_bf16 v[28:31], v[156:159], v[214:217], v[28:31]
	v_mfma_f32_16x16x32_bf16 v[24:27], v[164:167], v[214:217], v[24:27]
	v_lshl_add_u64 v[228:229], s[54:55], 0, v[128:129]
	s_mov_b32 m0, s33
	s_nop 0
	global_load_lds_dwordx4 v[228:229], off
	v_mfma_f32_16x16x32_bf16 v[12:15], v[156:159], v[222:225], v[12:15]
	v_mfma_f32_16x16x32_bf16 v[8:11], v[164:167], v[222:225], v[8:11]
	s_setprio 0
	s_setprio 1
	v_mfma_f32_16x16x32_bf16 v[52:55], v[168:171], v[188:191], 0
	v_mfma_f32_16x16x32_bf16 v[48:51], v[180:183], v[188:191], 0
	v_mfma_f32_16x16x32_bf16 v[36:39], v[168:171], v[196:199], 0
	v_mfma_f32_16x16x32_bf16 v[32:35], v[180:183], v[196:199], 0
	v_mfma_f32_16x16x32_bf16 v[52:55], v[172:175], v[192:195], v[52:55]
	v_mfma_f32_16x16x32_bf16 v[48:51], v[184:187], v[192:195], v[48:51]
	v_mfma_f32_16x16x32_bf16 v[36:39], v[172:175], v[206:209], v[36:39]
	v_mfma_f32_16x16x32_bf16 v[32:35], v[184:187], v[206:209], v[32:35]
	v_mfma_f32_16x16x32_bf16 v[20:23], v[168:171], v[210:213], 0
	v_mfma_f32_16x16x32_bf16 v[16:19], v[180:183], v[210:213], 0
	v_mfma_f32_16x16x32_bf16 v[4:7], v[168:171], v[218:221], 0
	v_mfma_f32_16x16x32_bf16 v[0:3], v[180:183], v[218:221], 0
	v_mfma_f32_16x16x32_bf16 v[20:23], v[172:175], v[214:217], v[20:23]
	v_mfma_f32_16x16x32_bf16 v[16:19], v[184:187], v[214:217], v[16:19]
	v_lshl_add_u64 v[230:231], s[54:55], 0, v[132:133]
	s_mov_b32 m0, s34
	s_nop 0
	global_load_lds_dwordx4 v[230:231], off
	v_mfma_f32_16x16x32_bf16 v[4:7], v[172:175], v[222:225], v[4:7]
	v_mfma_f32_16x16x32_bf16 v[0:3], v[184:187], v[222:225], v[0:3]
	s_setprio 0
	s_barrier
	s_add_i32 s74, 0, 0x18000
	s_add_i32 s75, 0, 0x1c000
	v_add_u32_e32 v164, s74, v150
	v_add_u32_e32 v179, s75, v150
	ds_read_b128 v[146:149], v164
	ds_read_b128 v[156:159], v164 offset:1024
	ds_read_b128 v[160:163], v164 offset:2048
	ds_read_b128 v[164:167], v164 offset:3072
	ds_read_b128 v[168:171], v179
	ds_read_b128 v[172:175], v179 offset:1024
	ds_read_b128 v[180:183], v179 offset:2048
	ds_read_b128 v[184:187], v179 offset:3072
	s_add_u32 s54, s54, 0x40000
	s_addc_u32 s55, s55, 0
	s_mov_b32 m0, s49
	v_lshl_add_u64 v[232:233], s[54:55], 0, v[128:129]
	ds_read_b128 v[188:191], v154 offset:32768
	ds_read_b128 v[192:195], v154 offset:33792
	ds_read_b128 v[196:199], v154 offset:34816
	ds_read_b128 v[206:209], v154 offset:35840
	ds_read_b128 v[210:213], v154 offset:36864
	ds_read_b128 v[214:217], v154 offset:37888
	ds_read_b128 v[218:221], v154 offset:38912
	ds_read_b128 v[222:225], v154 offset:39936
	global_load_lds_dwordx4 v[232:233], off
	v_lshl_add_u64 v[232:233], s[54:55], 0, v[132:133]
	s_mov_b32 m0, s56
	s_nop 0
	global_load_lds_dwordx4 v[232:233], off
	s_waitcnt vmcnt(8)
	s_waitcnt lgkmcnt(0)
	s_barrier
	s_setprio 1
	s_waitcnt lgkmcnt(0)
	v_mfma_f32_16x16x32_bf16 v[124:127], v[146:149], v[188:191], v[124:127]
	v_mfma_f32_16x16x32_bf16 v[120:123], v[160:163], v[188:191], v[120:123]
	v_mfma_f32_16x16x32_bf16 v[108:111], v[146:149], v[196:199], v[108:111]
	v_mfma_f32_16x16x32_bf16 v[104:107], v[160:163], v[196:199], v[104:107]
	v_mfma_f32_16x16x32_bf16 v[124:127], v[156:159], v[192:195], v[124:127]
	v_mfma_f32_16x16x32_bf16 v[120:123], v[164:167], v[192:195], v[120:123]
	v_mfma_f32_16x16x32_bf16 v[108:111], v[156:159], v[206:209], v[108:111]
	v_mfma_f32_16x16x32_bf16 v[104:107], v[164:167], v[206:209], v[104:107]
	v_mfma_f32_16x16x32_bf16 v[92:95], v[146:149], v[210:213], v[92:95]
	v_mfma_f32_16x16x32_bf16 v[88:91], v[160:163], v[210:213], v[88:91]
	v_mfma_f32_16x16x32_bf16 v[76:79], v[146:149], v[218:221], v[76:79]
	v_mfma_f32_16x16x32_bf16 v[72:75], v[160:163], v[218:221], v[72:75]
	v_mfma_f32_16x16x32_bf16 v[92:95], v[156:159], v[214:217], v[92:95]
	v_mfma_f32_16x16x32_bf16 v[88:91], v[164:167], v[214:217], v[88:91]
	v_mfma_f32_16x16x32_bf16 v[76:79], v[156:159], v[222:225], v[76:79]
	v_mfma_f32_16x16x32_bf16 v[72:75], v[164:167], v[222:225], v[72:75]
	s_setprio 0
	s_setprio 1
	v_mfma_f32_16x16x32_bf16 v[116:119], v[168:171], v[188:191], v[116:119]
	v_mfma_f32_16x16x32_bf16 v[112:115], v[180:183], v[188:191], v[112:115]
	v_mfma_f32_16x16x32_bf16 v[100:103], v[168:171], v[196:199], v[100:103]
	v_mfma_f32_16x16x32_bf16 v[96:99], v[180:183], v[196:199], v[96:99]
	v_mfma_f32_16x16x32_bf16 v[116:119], v[172:175], v[192:195], v[116:119]
	v_mfma_f32_16x16x32_bf16 v[112:115], v[184:187], v[192:195], v[112:115]
	v_mfma_f32_16x16x32_bf16 v[100:103], v[172:175], v[206:209], v[100:103]
	v_mfma_f32_16x16x32_bf16 v[96:99], v[184:187], v[206:209], v[96:99]
	v_mfma_f32_16x16x32_bf16 v[84:87], v[168:171], v[210:213], v[84:87]
	v_mfma_f32_16x16x32_bf16 v[80:83], v[180:183], v[210:213], v[80:83]
	v_mfma_f32_16x16x32_bf16 v[68:71], v[168:171], v[218:221], v[68:71]
	v_mfma_f32_16x16x32_bf16 v[64:67], v[180:183], v[218:221], v[64:67]
	v_mfma_f32_16x16x32_bf16 v[84:87], v[172:175], v[214:217], v[84:87]
	v_mfma_f32_16x16x32_bf16 v[80:83], v[184:187], v[214:217], v[80:83]
	v_mfma_f32_16x16x32_bf16 v[68:71], v[172:175], v[222:225], v[68:71]
	v_mfma_f32_16x16x32_bf16 v[64:67], v[184:187], v[222:225], v[64:67]
	s_setprio 0
	s_barrier
; #define PG8_STAGE(bufoff, gbase, voff) do { _Pragma("unroll") for (int _i = 0; _i < 2; ++_i) \
;         __builtin_amdgcn_global_load_lds((const unsigned*)((const char*)(gbase) + (voff)[_i]), (PG8_LAS unsigned*)(lds + (bufoff) + ldsw + _i * 8192), 16, 0, 0); } while (0)
; #define PG8_LDA(dst, b, h) do { _Pragma("unroll") for (int m = 0; m < 4; ++m) _Pragma("unroll") for (int k = 0; k < 2; ++k) dst[m][k] = *(const PG8_LAS bf16x8*)(lds + PG8_SA(b, h) + aoff + m * 2048 + k * 1024); } while (0)
; #define PG8_LDB(dst, b, h) do { _Pragma("unroll") for (int n = 0; n < 2; ++n) _Pragma("unroll") for (int k = 0; k < 2; ++k) dst[n][k] = *(const PG8_LAS bf16x8*)(lds + PG8_SB(b, h) + boff + n * 2048 + k * 1024); } while (0)
; #define PG8_MMA(ai, bj, At, Bt) do { __builtin_amdgcn_s_setprio(1); _Pragma("unroll") for (int m = 0; m < 4; ++m) _Pragma("unroll") for (int n = 0; n < 2; ++n) _Pragma("unroll") for (int k = 0; k < 2; ++k) \
;         acc[ai][bj][m][n] = __builtin_amdgcn_mfma_f32_16x16x32_bf16(Bt[n][k], At[m][k], acc[ai][bj][m][n], 0, 0, 0); __builtin_amdgcn_s_setprio(0); } while (0)
; #define PG8_WAIT_V(n) asm volatile("s_waitcnt vmcnt(" #n ")" ::: "memory")
; template <class Epi, class Sched, bool ALIGN_EPI = false, bool SP2 = false>
; __device__ __forceinline__ void gemm_phase(PG8_LAS unsigned char* lds, const Gemm g, const Sched& S, const Epi& E) {
;     ...
;             PG8_LDB(B0, 0, 0); PG8_LDB(B1, 0, 1); PG8_SCHED; PG8_LDA(At, 0, 0); PG8_STAGE(PG8_SA(1, 1), a1 + hstep, voffA);
;             PG8_WAIT_V(8); PG8_WAIT_L(0); PG8_BAR; PG8_MMA(0, 0, At, B0); PG8_MMA(0, 1, At, B1); PG8_BAR; PG8_SCHED;
;             PG8_LDA(At, 0, 1); PG8_STAGE(PG8_SB(0, 0), b2, voffB); PG8_STAGE(PG8_SB(0, 1), b2 + hstep, voffB); PG8_STAGE(PG8_SA(0, 0), a2, voffA);
;             PG8_WAIT_V(8); PG8_WAIT_L(0); PG8_BAR; PG8_MMA(1, 0, At, B0); PG8_MMA(1, 1, At, B1); PG8_BAR; PG8_SCHED;
;             PG8_LDB(B0, 1, 0); PG8_LDB(B1, 1, 1); PG8_SCHED; PG8_LDA(At, 1, 0); PG8_STAGE(PG8_SA(0, 1), a2 + hstep, voffA);
;             PG8_WAIT_V(8); PG8_WAIT_L(0); PG8_BAR; PG8_MMA(0, 0, At, B0); PG8_MMA(0, 1, At, B1); PG8_BAR; PG8_SCHED;
;             PG8_LDA(At, 1, 1); PG8_STAGE(PG8_SB(1, 0), b3, voffB); PG8_STAGE(PG8_SB(1, 1), b3 + hstep, voffB); PG8_STAGE(PG8_SA(1, 0), a3, voffA);
;             PG8_WAIT_V(8); PG8_WAIT_L(0); PG8_BAR; PG8_MMA(1, 0, At, B0); PG8_MMA(1, 1, At, B1); PG8_BAR; PG8_SCHED;
	s_add_i32 s54, s74, s15
	v_lshl_add_u64 v[200:201], v[200:201], 0, s[26:27]
	s_mov_b32 m0, s54
	ds_read_b128 v[188:191], v154 offset:49152
	ds_read_b128 v[192:195], v154 offset:50176
	ds_read_b128 v[196:199], v154 offset:51200
	ds_read_b128 v[206:209], v154 offset:52224
	ds_read_b128 v[210:213], v154 offset:53248
	ds_read_b128 v[214:217], v154 offset:54272
	ds_read_b128 v[218:221], v154 offset:55296
	ds_read_b128 v[222:225], v154 offset:56320
	global_load_lds_dwordx4 v[200:201], off
	s_add_i32 m0, s54, 0x2000
	s_add_u32 s52, s52, 0x40080
	v_lshl_add_u64 v[200:201], v[226:227], 0, s[26:27]
	s_addc_u32 s53, s53, 0
	s_add_i32 s54, s75, s15
	global_load_lds_dwordx4 v[200:201], off
	v_lshl_add_u64 v[200:201], s[52:53], 0, v[130:131]
	s_mov_b32 m0, s54
	s_nop 0
	global_load_lds_dwordx4 v[200:201], off
	v_lshl_add_u64 v[200:201], s[52:53], 0, v[134:135]
	s_add_i32 m0, s54, 0x2000
	s_nop 0
	global_load_lds_dwordx4 v[200:201], off
	s_waitcnt vmcnt(6)
	s_waitcnt lgkmcnt(0)
	s_barrier
	s_setprio 1
	s_waitcnt lgkmcnt(0)
	v_mfma_f32_16x16x32_bf16 v[60:63], v[146:149], v[188:191], v[60:63]
	v_mfma_f32_16x16x32_bf16 v[56:59], v[160:163], v[188:191], v[56:59]
	v_mfma_f32_16x16x32_bf16 v[44:47], v[146:149], v[196:199], v[44:47]
	v_mfma_f32_16x16x32_bf16 v[40:43], v[160:163], v[196:199], v[40:43]
	v_mfma_f32_16x16x32_bf16 v[60:63], v[156:159], v[192:195], v[60:63]
	v_mfma_f32_16x16x32_bf16 v[56:59], v[164:167], v[192:195], v[56:59]
	v_mfma_f32_16x16x32_bf16 v[44:47], v[156:159], v[206:209], v[44:47]
	v_mfma_f32_16x16x32_bf16 v[40:43], v[164:167], v[206:209], v[40:43]
	v_mfma_f32_16x16x32_bf16 v[28:31], v[146:149], v[210:213], v[28:31]
	v_mfma_f32_16x16x32_bf16 v[24:27], v[160:163], v[210:213], v[24:27]
	v_mfma_f32_16x16x32_bf16 v[12:15], v[146:149], v[218:221], v[12:15]
	v_mfma_f32_16x16x32_bf16 v[8:11], v[160:163], v[218:221], v[8:11]
	v_mfma_f32_16x16x32_bf16 v[28:31], v[156:159], v[214:217], v[28:31]
	v_mfma_f32_16x16x32_bf16 v[24:27], v[164:167], v[214:217], v[24:27]
	v_lshl_add_u64 v[200:201], v[228:229], 0, s[26:27]
	s_mov_b32 m0, s58
	s_nop 0
	global_load_lds_dwordx4 v[200:201], off
	v_mfma_f32_16x16x32_bf16 v[12:15], v[156:159], v[222:225], v[12:15]
	v_mfma_f32_16x16x32_bf16 v[8:11], v[164:167], v[222:225], v[8:11]
	s_setprio 0
	s_setprio 1
	v_mfma_f32_16x16x32_bf16 v[52:55], v[168:171], v[188:191], v[52:55]
	v_mfma_f32_16x16x32_bf16 v[48:51], v[180:183], v[188:191], v[48:51]
	v_mfma_f32_16x16x32_bf16 v[36:39], v[168:171], v[196:199], v[36:39]
	v_mfma_f32_16x16x32_bf16 v[32:35], v[180:183], v[196:199], v[32:35]
	v_mfma_f32_16x16x32_bf16 v[52:55], v[172:175], v[192:195], v[52:55]
	v_mfma_f32_16x16x32_bf16 v[48:51], v[184:187], v[192:195], v[48:51]
	v_mfma_f32_16x16x32_bf16 v[36:39], v[172:175], v[206:209], v[36:39]
	v_mfma_f32_16x16x32_bf16 v[32:35], v[184:187], v[206:209], v[32:35]
	v_mfma_f32_16x16x32_bf16 v[20:23], v[168:171], v[210:213], v[20:23]
	v_mfma_f32_16x16x32_bf16 v[16:19], v[180:183], v[210:213], v[16:19]
	v_mfma_f32_16x16x32_bf16 v[4:7], v[168:171], v[218:221], v[4:7]
	v_mfma_f32_16x16x32_bf16 v[0:3], v[180:183], v[218:221], v[0:3]
	v_mfma_f32_16x16x32_bf16 v[20:23], v[172:175], v[214:217], v[20:23]
	v_mfma_f32_16x16x32_bf16 v[16:19], v[184:187], v[214:217], v[16:19]
	v_lshl_add_u64 v[200:201], v[230:231], 0, s[26:27]
	s_mov_b32 m0, s59
	s_nop 0
	global_load_lds_dwordx4 v[200:201], off
	v_mfma_f32_16x16x32_bf16 v[4:7], v[172:175], v[222:225], v[4:7]
	v_mfma_f32_16x16x32_bf16 v[0:3], v[184:187], v[222:225], v[0:3]
	s_setprio 0
	s_barrier
	s_add_i32 s67, s67, 2
	s_add_u32 s50, s50, 0x100
	s_addc_u32 s51, s51, 0
	s_add_u32 s65, s65, 0x100
	s_addc_u32 s66, s66, 0
.LBB0_1593:
	ds_read_b128 v[146:149], v152
	ds_read_b128 v[156:159], v152 offset:1024
	ds_read_b128 v[160:163], v152 offset:2048
	ds_read_b128 v[164:167], v152 offset:3072
	ds_read_b128 v[168:171], v153
	ds_read_b128 v[172:175], v153 offset:1024
	ds_read_b128 v[180:183], v153 offset:2048
	ds_read_b128 v[184:187], v153 offset:3072
	s_add_u32 s52, s50, 0xfffc0080
	s_addc_u32 s53, s51, -1
	s_cmp_eq_u32 s67, 12
	s_cselect_b32 s55, s39, s53
	s_cselect_b32 s54, s47, s52
	s_cselect_b32 s53, s37, s66
	s_cselect_b32 s52, s64, s65
	v_lshl_add_u64 v[200:201], s[50:51], 0, v[136:137]
	s_add_i32 m0, s33, 0xc000
	ds_read_b128 v[188:191], v154
	ds_read_b128 v[192:195], v154 offset:1024
	ds_read_b128 v[196:199], v154 offset:2048
	ds_read_b128 v[206:209], v154 offset:3072
	ds_read_b128 v[210:213], v154 offset:4096
	ds_read_b128 v[214:217], v154 offset:5120
	ds_read_b128 v[218:221], v154 offset:6144
	ds_read_b128 v[222:225], v154 offset:7168
	global_load_lds_dwordx4 v[200:201], off
	v_lshl_add_u64 v[200:201], s[50:51], 0, v[138:139]
	s_add_i32 m0, s33, 0xe000
	s_nop 0
	global_load_lds_dwordx4 v[200:201], off
	s_waitcnt vmcnt(8)
	s_waitcnt lgkmcnt(0)
	s_barrier
; #define PG8_STAGE(bufoff, gbase, voff) do { _Pragma("unroll") for (int _i = 0; _i < 2; ++_i) \
;         __builtin_amdgcn_global_load_lds((const unsigned*)((const char*)(gbase) + (voff)[_i]), (PG8_LAS unsigned*)(lds + (bufoff) + ldsw + _i * 8192), 16, 0, 0); } while (0)
; #define PG8_LDA(dst, b, h) do { _Pragma("unroll") for (int m = 0; m < 4; ++m) _Pragma("unroll") for (int k = 0; k < 2; ++k) dst[m][k] = *(const PG8_LAS bf16x8*)(lds + PG8_SA(b, h) + aoff + m * 2048 + k * 1024); } while (0)
; #define PG8_MMA(ai, bj, At, Bt) do { __builtin_amdgcn_s_setprio(1); _Pragma("unroll") for (int m = 0; m < 4; ++m) _Pragma("unroll") for (int n = 0; n < 2; ++n) _Pragma("unroll") for (int k = 0; k < 2; ++k) \
;         acc[ai][bj][m][n] = __builtin_amdgcn_mfma_f32_16x16x32_bf16(Bt[n][k], At[m][k], acc[ai][bj][m][n], 0, 0, 0); __builtin_amdgcn_s_setprio(0); } while (0)
; #define PG8_WAIT_V(n) asm volatile("s_waitcnt vmcnt(" #n ")" ::: "memory")
; #define PG8_WAIT_L(n) asm volatile("s_waitcnt lgkmcnt(" #n ")" ::: "memory")
; #define PG8_BAR __builtin_amdgcn_s_barrier()
; #define PG8_SCHED __builtin_amdgcn_sched_barrier(0)
; template <class Epi, class Sched, bool ALIGN_EPI = false, bool SP2 = false>
; __device__ __forceinline__ void gemm_phase(PG8_LAS unsigned char* lds, const Gemm g, const Sched& S, const Epi& E) {
;     ...
;             PG8_WAIT_V(8); PG8_WAIT_L(0); PG8_BAR; PG8_MMA(0, 0, At, B0); PG8_MMA(0, 1, At, B1); PG8_BAR; PG8_SCHED;
;             PG8_LDA(At, 0, 1); PG8_STAGE(PG8_SB(0, 0), b2, voffB); PG8_STAGE(PG8_SB(0, 1), b2 + hstep, voffB); PG8_STAGE(PG8_SA(0, 0), a2, voffA);
;             PG8_WAIT_V(8); PG8_WAIT_L(0); PG8_BAR; PG8_MMA(1, 0, At, B0); PG8_MMA(1, 1, At, B1); PG8_BAR; PG8_SCHED;
	s_setprio 1
	s_waitcnt lgkmcnt(0)
	v_mfma_f32_16x16x32_bf16 v[124:127], v[146:149], v[188:191], v[124:127]
	v_mfma_f32_16x16x32_bf16 v[120:123], v[160:163], v[188:191], v[120:123]
	v_mfma_f32_16x16x32_bf16 v[108:111], v[146:149], v[196:199], v[108:111]
	v_mfma_f32_16x16x32_bf16 v[104:107], v[160:163], v[196:199], v[104:107]
	v_mfma_f32_16x16x32_bf16 v[124:127], v[156:159], v[192:195], v[124:127]
	v_mfma_f32_16x16x32_bf16 v[120:123], v[164:167], v[192:195], v[120:123]
	v_mfma_f32_16x16x32_bf16 v[108:111], v[156:159], v[206:209], v[108:111]
	v_mfma_f32_16x16x32_bf16 v[104:107], v[164:167], v[206:209], v[104:107]
	v_mfma_f32_16x16x32_bf16 v[92:95], v[146:149], v[210:213], v[92:95]
	v_mfma_f32_16x16x32_bf16 v[88:91], v[160:163], v[210:213], v[88:91]
	v_mfma_f32_16x16x32_bf16 v[76:79], v[146:149], v[218:221], v[76:79]
	v_mfma_f32_16x16x32_bf16 v[72:75], v[160:163], v[218:221], v[72:75]
	v_mfma_f32_16x16x32_bf16 v[92:95], v[156:159], v[214:217], v[92:95]
	v_mfma_f32_16x16x32_bf16 v[88:91], v[164:167], v[214:217], v[88:91]
	v_mfma_f32_16x16x32_bf16 v[76:79], v[156:159], v[222:225], v[76:79]
	v_mfma_f32_16x16x32_bf16 v[72:75], v[164:167], v[222:225], v[72:75]
	s_setprio 0
	s_setprio 1
	v_mfma_f32_16x16x32_bf16 v[116:119], v[168:171], v[188:191], v[116:119]
	v_mfma_f32_16x16x32_bf16 v[112:115], v[180:183], v[188:191], v[112:115]
	v_mfma_f32_16x16x32_bf16 v[100:103], v[168:171], v[196:199], v[100:103]
	v_mfma_f32_16x16x32_bf16 v[96:99], v[180:183], v[196:199], v[96:99]
	v_mfma_f32_16x16x32_bf16 v[116:119], v[172:175], v[192:195], v[116:119]
	v_mfma_f32_16x16x32_bf16 v[112:115], v[184:187], v[192:195], v[112:115]
	v_mfma_f32_16x16x32_bf16 v[100:103], v[172:175], v[206:209], v[100:103]
	v_mfma_f32_16x16x32_bf16 v[96:99], v[184:187], v[206:209], v[96:99]
	v_mfma_f32_16x16x32_bf16 v[84:87], v[168:171], v[210:213], v[84:87]
	v_mfma_f32_16x16x32_bf16 v[80:83], v[180:183], v[210:213], v[80:83]
	v_mfma_f32_16x16x32_bf16 v[68:71], v[168:171], v[218:221], v[68:71]
	v_mfma_f32_16x16x32_bf16 v[64:67], v[180:183], v[218:221], v[64:67]
	v_mfma_f32_16x16x32_bf16 v[84:87], v[172:175], v[214:217], v[84:87]
	v_mfma_f32_16x16x32_bf16 v[80:83], v[184:187], v[214:217], v[80:83]
	v_mfma_f32_16x16x32_bf16 v[68:71], v[172:175], v[222:225], v[68:71]
	v_mfma_f32_16x16x32_bf16 v[64:67], v[184:187], v[222:225], v[64:67]
	s_setprio 0
	s_barrier
	s_add_i32 s74, s60, s15
	v_lshl_add_u64 v[200:201], s[52:53], 0, v[130:131]
	s_mov_b32 m0, s74
	ds_read_b128 v[188:191], v154 offset:16384
	ds_read_b128 v[192:195], v154 offset:17408
	ds_read_b128 v[196:199], v154 offset:18432
	ds_read_b128 v[206:209], v154 offset:19456
	ds_read_b128 v[210:213], v154 offset:20480
	ds_read_b128 v[214:217], v154 offset:21504
	ds_read_b128 v[218:221], v154 offset:22528
	ds_read_b128 v[222:225], v154 offset:23552
	global_load_lds_dwordx4 v[200:201], off
	s_add_i32 m0, s74, 0x2000
	s_add_u32 s74, s52, 0x40000
	v_lshl_add_u64 v[226:227], s[52:53], 0, v[134:135]
	s_addc_u32 s75, s53, 0
	s_add_i32 s76, s61, s15
	global_load_lds_dwordx4 v[226:227], off
	v_lshl_add_u64 v[228:229], s[74:75], 0, v[130:131]
	s_mov_b32 m0, s76
	global_load_lds_dwordx4 v[228:229], off
	v_lshl_add_u64 v[228:229], s[74:75], 0, v[134:135]
	s_add_i32 m0, s76, 0x2000
	s_nop 0
	global_load_lds_dwordx4 v[228:229], off
	s_waitcnt vmcnt(6)
	s_waitcnt lgkmcnt(0)
	s_barrier
	s_setprio 1
	s_waitcnt lgkmcnt(0)
	v_mfma_f32_16x16x32_bf16 v[60:63], v[146:149], v[188:191], v[60:63]
	v_mfma_f32_16x16x32_bf16 v[56:59], v[160:163], v[188:191], v[56:59]
	v_mfma_f32_16x16x32_bf16 v[44:47], v[146:149], v[196:199], v[44:47]
	v_mfma_f32_16x16x32_bf16 v[40:43], v[160:163], v[196:199], v[40:43]
	v_mfma_f32_16x16x32_bf16 v[60:63], v[156:159], v[192:195], v[60:63]
	v_mfma_f32_16x16x32_bf16 v[56:59], v[164:167], v[192:195], v[56:59]
	v_mfma_f32_16x16x32_bf16 v[44:47], v[156:159], v[206:209], v[44:47]
	v_mfma_f32_16x16x32_bf16 v[40:43], v[164:167], v[206:209], v[40:43]
	v_mfma_f32_16x16x32_bf16 v[28:31], v[146:149], v[210:213], v[28:31]
	v_mfma_f32_16x16x32_bf16 v[24:27], v[160:163], v[210:213], v[24:27]
	v_mfma_f32_16x16x32_bf16 v[12:15], v[146:149], v[218:221], v[12:15]
	v_mfma_f32_16x16x32_bf16 v[8:11], v[160:163], v[218:221], v[8:11]
	v_mfma_f32_16x16x32_bf16 v[28:31], v[156:159], v[214:217], v[28:31]
	v_mfma_f32_16x16x32_bf16 v[24:27], v[164:167], v[214:217], v[24:27]
	v_lshl_add_u64 v[228:229], s[54:55], 0, v[128:129]
	s_mov_b32 m0, s33
	s_nop 0
	global_load_lds_dwordx4 v[228:229], off
	v_mfma_f32_16x16x32_bf16 v[12:15], v[156:159], v[222:225], v[12:15]
	v_mfma_f32_16x16x32_bf16 v[8:11], v[164:167], v[222:225], v[8:11]
	s_setprio 0
	s_setprio 1
	v_mfma_f32_16x16x32_bf16 v[52:55], v[168:171], v[188:191], v[52:55]
	v_mfma_f32_16x16x32_bf16 v[48:51], v[180:183], v[188:191], v[48:51]
	v_mfma_f32_16x16x32_bf16 v[36:39], v[168:171], v[196:199], v[36:39]
	v_mfma_f32_16x16x32_bf16 v[32:35], v[180:183], v[196:199], v[32:35]
	v_mfma_f32_16x16x32_bf16 v[52:55], v[172:175], v[192:195], v[52:55]
	v_mfma_f32_16x16x32_bf16 v[48:51], v[184:187], v[192:195], v[48:51]
	v_mfma_f32_16x16x32_bf16 v[36:39], v[172:175], v[206:209], v[36:39]
	v_mfma_f32_16x16x32_bf16 v[32:35], v[184:187], v[206:209], v[32:35]
	v_mfma_f32_16x16x32_bf16 v[20:23], v[168:171], v[210:213], v[20:23]
	v_mfma_f32_16x16x32_bf16 v[16:19], v[180:183], v[210:213], v[16:19]
	v_mfma_f32_16x16x32_bf16 v[4:7], v[168:171], v[218:221], v[4:7]
	v_mfma_f32_16x16x32_bf16 v[0:3], v[180:183], v[218:221], v[0:3]
	v_mfma_f32_16x16x32_bf16 v[20:23], v[172:175], v[214:217], v[20:23]
	v_mfma_f32_16x16x32_bf16 v[16:19], v[184:187], v[214:217], v[16:19]
	v_lshl_add_u64 v[230:231], s[54:55], 0, v[132:133]
	s_mov_b32 m0, s34
	s_nop 0
	global_load_lds_dwordx4 v[230:231], off
	v_mfma_f32_16x16x32_bf16 v[4:7], v[172:175], v[222:225], v[4:7]
	v_mfma_f32_16x16x32_bf16 v[0:3], v[184:187], v[222:225], v[0:3]
	s_setprio 0
	s_barrier
; #define PG8_STAGE(bufoff, gbase, voff) do { _Pragma("unroll") for (int _i = 0; _i < 2; ++_i) \
;         __builtin_amdgcn_global_load_lds((const unsigned*)((const char*)(gbase) + (voff)[_i]), (PG8_LAS unsigned*)(lds + (bufoff) + ldsw + _i * 8192), 16, 0, 0); } while (0)
; #define PG8_LDA(dst, b, h) do { _Pragma("unroll") for (int m = 0; m < 4; ++m) _Pragma("unroll") for (int k = 0; k < 2; ++k) dst[m][k] = *(const PG8_LAS bf16x8*)(lds + PG8_SA(b, h) + aoff + m * 2048 + k * 1024); } while (0)
; #define PG8_LDB(dst, b, h) do { _Pragma("unroll") for (int n = 0; n < 2; ++n) _Pragma("unroll") for (int k = 0; k < 2; ++k) dst[n][k] = *(const PG8_LAS bf16x8*)(lds + PG8_SB(b, h) + boff + n * 2048 + k * 1024); } while (0)
; #define PG8_MMA(ai, bj, At, Bt) do { __builtin_amdgcn_s_setprio(1); _Pragma("unroll") for (int m = 0; m < 4; ++m) _Pragma("unroll") for (int n = 0; n < 2; ++n) _Pragma("unroll") for (int k = 0; k < 2; ++k) \
;         acc[ai][bj][m][n] = __builtin_amdgcn_mfma_f32_16x16x32_bf16(Bt[n][k], At[m][k], acc[ai][bj][m][n], 0, 0, 0); __builtin_amdgcn_s_setprio(0); } while (0)
; #define PG8_WAIT_V(n) asm volatile("s_waitcnt vmcnt(" #n ")" ::: "memory")
; #define PG8_WAIT_L(n) asm volatile("s_waitcnt lgkmcnt(" #n ")" ::: "memory")
; #define PG8_BAR __builtin_amdgcn_s_barrier()
; #define PG8_SCHED __builtin_amdgcn_sched_barrier(0)
; template <class Epi, class Sched, bool ALIGN_EPI = false, bool SP2 = false>
; __device__ __forceinline__ void gemm_phase(PG8_LAS unsigned char* lds, const Gemm g, const Sched& S, const Epi& E) {
;     ...
;             PG8_LDB(B0, 1, 0); PG8_LDB(B1, 1, 1); PG8_SCHED; PG8_LDA(At, 1, 0); PG8_STAGE(PG8_SA(0, 1), a2 + hstep, voffA);
;             PG8_WAIT_V(8); PG8_WAIT_L(0); PG8_BAR; PG8_MMA(0, 0, At, B0); PG8_MMA(0, 1, At, B1); PG8_BAR; PG8_SCHED;
	s_add_i32 s74, 0, 0x18000
	s_add_i32 s75, 0, 0x1c000
	v_add_u32_e32 v164, s74, v150
	v_add_u32_e32 v179, s75, v150
	ds_read_b128 v[146:149], v164
	ds_read_b128 v[156:159], v164 offset:1024
	ds_read_b128 v[160:163], v164 offset:2048
	ds_read_b128 v[164:167], v164 offset:3072
	ds_read_b128 v[168:171], v179
	ds_read_b128 v[172:175], v179 offset:1024
	ds_read_b128 v[180:183], v179 offset:2048
	ds_read_b128 v[184:187], v179 offset:3072
	s_add_u32 s54, s54, 0x40000
	s_addc_u32 s55, s55, 0
	s_mov_b32 m0, s49
	v_lshl_add_u64 v[232:233], s[54:55], 0, v[128:129]
	ds_read_b128 v[188:191], v154 offset:32768
	ds_read_b128 v[192:195], v154 offset:33792
	ds_read_b128 v[196:199], v154 offset:34816
	ds_read_b128 v[206:209], v154 offset:35840
	ds_read_b128 v[210:213], v154 offset:36864
	ds_read_b128 v[214:217], v154 offset:37888
	ds_read_b128 v[218:221], v154 offset:38912
	ds_read_b128 v[222:225], v154 offset:39936
	global_load_lds_dwordx4 v[232:233], off
	v_lshl_add_u64 v[232:233], s[54:55], 0, v[132:133]
	s_mov_b32 m0, s56
	s_nop 0
	global_load_lds_dwordx4 v[232:233], off
	s_waitcnt vmcnt(8)
	s_waitcnt lgkmcnt(0)
	s_barrier
	s_setprio 1
	s_waitcnt lgkmcnt(0)
	v_mfma_f32_16x16x32_bf16 v[124:127], v[146:149], v[188:191], v[124:127]
	v_mfma_f32_16x16x32_bf16 v[120:123], v[160:163], v[188:191], v[120:123]
	v_mfma_f32_16x16x32_bf16 v[108:111], v[146:149], v[196:199], v[108:111]
	v_mfma_f32_16x16x32_bf16 v[104:107], v[160:163], v[196:199], v[104:107]
	v_mfma_f32_16x16x32_bf16 v[124:127], v[156:159], v[192:195], v[124:127]
	v_mfma_f32_16x16x32_bf16 v[120:123], v[164:167], v[192:195], v[120:123]
	v_mfma_f32_16x16x32_bf16 v[108:111], v[156:159], v[206:209], v[108:111]
	v_mfma_f32_16x16x32_bf16 v[104:107], v[164:167], v[206:209], v[104:107]
	v_mfma_f32_16x16x32_bf16 v[92:95], v[146:149], v[210:213], v[92:95]
	v_mfma_f32_16x16x32_bf16 v[88:91], v[160:163], v[210:213], v[88:91]
	v_mfma_f32_16x16x32_bf16 v[76:79], v[146:149], v[218:221], v[76:79]
	v_mfma_f32_16x16x32_bf16 v[72:75], v[160:163], v[218:221], v[72:75]
	v_mfma_f32_16x16x32_bf16 v[92:95], v[156:159], v[214:217], v[92:95]
	v_mfma_f32_16x16x32_bf16 v[88:91], v[164:167], v[214:217], v[88:91]
	v_mfma_f32_16x16x32_bf16 v[76:79], v[156:159], v[222:225], v[76:79]
	v_mfma_f32_16x16x32_bf16 v[72:75], v[164:167], v[222:225], v[72:75]
	s_setprio 0
	s_setprio 1
	v_mfma_f32_16x16x32_bf16 v[116:119], v[168:171], v[188:191], v[116:119]
	v_mfma_f32_16x16x32_bf16 v[112:115], v[180:183], v[188:191], v[112:115]
	v_mfma_f32_16x16x32_bf16 v[100:103], v[168:171], v[196:199], v[100:103]
	v_mfma_f32_16x16x32_bf16 v[96:99], v[180:183], v[196:199], v[96:99]
	v_mfma_f32_16x16x32_bf16 v[116:119], v[172:175], v[192:195], v[116:119]
	v_mfma_f32_16x16x32_bf16 v[112:115], v[184:187], v[192:195], v[112:115]
	v_mfma_f32_16x16x32_bf16 v[100:103], v[172:175], v[206:209], v[100:103]
	v_mfma_f32_16x16x32_bf16 v[96:99], v[184:187], v[206:209], v[96:99]
	v_mfma_f32_16x16x32_bf16 v[84:87], v[168:171], v[210:213], v[84:87]
	v_mfma_f32_16x16x32_bf16 v[80:83], v[180:183], v[210:213], v[80:83]
	v_mfma_f32_16x16x32_bf16 v[68:71], v[168:171], v[218:221], v[68:71]
	v_mfma_f32_16x16x32_bf16 v[64:67], v[180:183], v[218:221], v[64:67]
	v_mfma_f32_16x16x32_bf16 v[84:87], v[172:175], v[214:217], v[84:87]
	v_mfma_f32_16x16x32_bf16 v[80:83], v[184:187], v[214:217], v[80:83]
	v_mfma_f32_16x16x32_bf16 v[68:71], v[172:175], v[222:225], v[68:71]
	v_mfma_f32_16x16x32_bf16 v[64:67], v[184:187], v[222:225], v[64:67]
	s_setprio 0
	s_barrier
; #define PG8_STAGE(bufoff, gbase, voff) do { _Pragma("unroll") for (int _i = 0; _i < 2; ++_i) \
;         __builtin_amdgcn_global_load_lds((const unsigned*)((const char*)(gbase) + (voff)[_i]), (PG8_LAS unsigned*)(lds + (bufoff) + ldsw + _i * 8192), 16, 0, 0); } while (0)
; #define PG8_LDA(dst, b, h) do { _Pragma("unroll") for (int m = 0; m < 4; ++m) _Pragma("unroll") for (int k = 0; k < 2; ++k) dst[m][k] = *(const PG8_LAS bf16x8*)(lds + PG8_SA(b, h) + aoff + m * 2048 + k * 1024); } while (0)
; #define PG8_MMA(ai, bj, At, Bt) do { __builtin_amdgcn_s_setprio(1); _Pragma("unroll") for (int m = 0; m < 4; ++m) _Pragma("unroll") for (int n = 0; n < 2; ++n) _Pragma("unroll") for (int k = 0; k < 2; ++k) \
;         acc[ai][bj][m][n] = __builtin_amdgcn_mfma_f32_16x16x32_bf16(Bt[n][k], At[m][k], acc[ai][bj][m][n], 0, 0, 0); __builtin_amdgcn_s_setprio(0); } while (0)
; #define PG8_WAIT_V(n) asm volatile("s_waitcnt vmcnt(" #n ")" ::: "memory")
; #define PG8_WAIT_L(n) asm volatile("s_waitcnt lgkmcnt(" #n ")" ::: "memory")
; #define PG8_BAR __builtin_amdgcn_s_barrier()
; #define PG8_SCHED __builtin_amdgcn_sched_barrier(0)
; template <class Epi, class Sched, bool ALIGN_EPI = false, bool SP2 = false>
; __device__ __forceinline__ void gemm_phase(PG8_LAS unsigned char* lds, const Gemm g, const Sched& S, const Epi& E) {
;     ...
;             PG8_LDA(At, 1, 1); PG8_STAGE(PG8_SB(1, 0), b3, voffB); PG8_STAGE(PG8_SB(1, 1), b3 + hstep, voffB); PG8_STAGE(PG8_SA(1, 0), a3, voffA);
;             PG8_WAIT_V(8); PG8_WAIT_L(0); PG8_BAR; PG8_MMA(1, 0, At, B0); PG8_MMA(1, 1, At, B1); PG8_BAR; PG8_SCHED;
;     ...
;         if constexpr (ALIGN_EPI) { if (wr == 0) PG8_BAR; }
	s_add_i32 s54, s74, s15
	v_lshl_add_u64 v[200:201], v[200:201], 0, s[26:27]
	s_mov_b32 m0, s54
	ds_read_b128 v[188:191], v154 offset:49152
	ds_read_b128 v[192:195], v154 offset:50176
	ds_read_b128 v[196:199], v154 offset:51200
	ds_read_b128 v[206:209], v154 offset:52224
	ds_read_b128 v[210:213], v154 offset:53248
	ds_read_b128 v[214:217], v154 offset:54272
	ds_read_b128 v[218:221], v154 offset:55296
	ds_read_b128 v[222:225], v154 offset:56320
	global_load_lds_dwordx4 v[200:201], off
	s_add_i32 m0, s54, 0x2000
	s_add_u32 s52, s52, 0x40080
	v_lshl_add_u64 v[200:201], v[226:227], 0, s[26:27]
	s_addc_u32 s53, s53, 0
	s_add_i32 s54, s75, s15
	global_load_lds_dwordx4 v[200:201], off
	v_lshl_add_u64 v[200:201], s[52:53], 0, v[130:131]
	s_mov_b32 m0, s54
	s_nop 0
	global_load_lds_dwordx4 v[200:201], off
	v_lshl_add_u64 v[200:201], s[52:53], 0, v[134:135]
	s_add_i32 m0, s54, 0x2000
	s_nop 0
	global_load_lds_dwordx4 v[200:201], off
	s_waitcnt vmcnt(6)
	s_waitcnt lgkmcnt(0)
	s_barrier
	s_setprio 1
	s_waitcnt lgkmcnt(0)
	v_mfma_f32_16x16x32_bf16 v[60:63], v[146:149], v[188:191], v[60:63]
	v_mfma_f32_16x16x32_bf16 v[56:59], v[160:163], v[188:191], v[56:59]
	v_mfma_f32_16x16x32_bf16 v[44:47], v[146:149], v[196:199], v[44:47]
	v_mfma_f32_16x16x32_bf16 v[40:43], v[160:163], v[196:199], v[40:43]
	v_mfma_f32_16x16x32_bf16 v[60:63], v[156:159], v[192:195], v[60:63]
	v_mfma_f32_16x16x32_bf16 v[56:59], v[164:167], v[192:195], v[56:59]
	v_mfma_f32_16x16x32_bf16 v[44:47], v[156:159], v[206:209], v[44:47]
	v_mfma_f32_16x16x32_bf16 v[40:43], v[164:167], v[206:209], v[40:43]
	v_mfma_f32_16x16x32_bf16 v[28:31], v[146:149], v[210:213], v[28:31]
	v_mfma_f32_16x16x32_bf16 v[24:27], v[160:163], v[210:213], v[24:27]
	v_mfma_f32_16x16x32_bf16 v[12:15], v[146:149], v[218:221], v[12:15]
	v_mfma_f32_16x16x32_bf16 v[8:11], v[160:163], v[218:221], v[8:11]
	v_mfma_f32_16x16x32_bf16 v[28:31], v[156:159], v[214:217], v[28:31]
	v_mfma_f32_16x16x32_bf16 v[24:27], v[164:167], v[214:217], v[24:27]
	v_lshl_add_u64 v[200:201], v[228:229], 0, s[26:27]
	s_mov_b32 m0, s58
	s_nop 0
	global_load_lds_dwordx4 v[200:201], off
	v_mfma_f32_16x16x32_bf16 v[12:15], v[156:159], v[222:225], v[12:15]
	v_mfma_f32_16x16x32_bf16 v[8:11], v[164:167], v[222:225], v[8:11]
	s_setprio 0
	s_setprio 1
	v_mfma_f32_16x16x32_bf16 v[52:55], v[168:171], v[188:191], v[52:55]
	v_mfma_f32_16x16x32_bf16 v[48:51], v[180:183], v[188:191], v[48:51]
	v_mfma_f32_16x16x32_bf16 v[36:39], v[168:171], v[196:199], v[36:39]
	v_mfma_f32_16x16x32_bf16 v[32:35], v[180:183], v[196:199], v[32:35]
	v_mfma_f32_16x16x32_bf16 v[52:55], v[172:175], v[192:195], v[52:55]
	v_mfma_f32_16x16x32_bf16 v[48:51], v[184:187], v[192:195], v[48:51]
	v_mfma_f32_16x16x32_bf16 v[36:39], v[172:175], v[206:209], v[36:39]
	v_mfma_f32_16x16x32_bf16 v[32:35], v[184:187], v[206:209], v[32:35]
	v_mfma_f32_16x16x32_bf16 v[20:23], v[168:171], v[210:213], v[20:23]
	v_mfma_f32_16x16x32_bf16 v[16:19], v[180:183], v[210:213], v[16:19]
	v_mfma_f32_16x16x32_bf16 v[4:7], v[168:171], v[218:221], v[4:7]
	v_mfma_f32_16x16x32_bf16 v[0:3], v[180:183], v[218:221], v[0:3]
	v_mfma_f32_16x16x32_bf16 v[20:23], v[172:175], v[214:217], v[20:23]
	v_mfma_f32_16x16x32_bf16 v[16:19], v[184:187], v[214:217], v[16:19]
	v_lshl_add_u64 v[200:201], v[230:231], 0, s[26:27]
	s_mov_b32 m0, s59
	s_nop 0
	global_load_lds_dwordx4 v[200:201], off
	v_mfma_f32_16x16x32_bf16 v[4:7], v[172:175], v[222:225], v[4:7]
	v_mfma_f32_16x16x32_bf16 v[0:3], v[184:187], v[222:225], v[0:3]
	s_setprio 0
	s_barrier
	s_add_i32 s67, s67, 2
	s_add_u32 s50, s50, 0x100
	s_addc_u32 s51, s51, 0
	s_add_u32 s65, s65, 0x100
	s_addc_u32 s66, s66, 0
	s_cmp_gt_u32 s67, 13
	s_cbranch_scc0 .LBB0_1593
	s_and_b64 vcc, exec, s[28:29]
	s_cbranch_vccz .LBB0_1596
	s_barrier

; #define PG8_STAGE(bufoff, gbase, voff) do { _Pragma("unroll") for (int _i = 0; _i < 2; ++_i) \
;         __builtin_amdgcn_global_load_lds((const unsigned*)((const char*)(gbase) + (voff)[_i]), (PG8_LAS unsigned*)(lds + (bufoff) + ldsw + _i * 8192), 16, 0, 0); } while (0)
; #define PG8_LDA(dst, b, h) do { _Pragma("unroll") for (int m = 0; m < 4; ++m) _Pragma("unroll") for (int k = 0; k < 2; ++k) dst[m][k] = *(const PG8_LAS bf16x8*)(lds + PG8_SA(b, h) + aoff + m * 2048 + k * 1024); } while (0)
; #define PG8_LDB(dst, b, h) do { _Pragma("unroll") for (int n = 0; n < 2; ++n) _Pragma("unroll") for (int k = 0; k < 2; ++k) dst[n][k] = *(const PG8_LAS bf16x8*)(lds + PG8_SB(b, h) + boff + n * 2048 + k * 1024); } while (0)
; #define PG8_MMA(ai, bj, At, Bt) do { __builtin_amdgcn_s_setprio(1); _Pragma("unroll") for (int m = 0; m < 4; ++m) _Pragma("unroll") for (int n = 0; n < 2; ++n) _Pragma("unroll") for (int k = 0; k < 2; ++k) \
;         acc[ai][bj][m][n] = __builtin_amdgcn_mfma_f32_16x16x32_bf16(Bt[n][k], At[m][k], acc[ai][bj][m][n], 0, 0, 0); __builtin_amdgcn_s_setprio(0); } while (0)
; #define PG8_BAR __builtin_amdgcn_s_barrier()
; template <class Epi, class Sched, bool ALIGN_EPI = false, bool SP2 = false>
; __device__ __forceinline__ void gemm_phase(PG8_LAS unsigned char* lds, const Gemm g, const Sched& S, const Epi& E) {
;     ...
;         const bool has_next = S.next(ui + 1, nxt);
;         const char* nA = has_next ? (const char*)g.A + (size_t)nxt.pm * tstep : cA; const char* nB = has_next ? (const char*)g.Bt + (size_t)nxt.pn * tstep : cB;
;         for (int t = 0; t < nt; t += 2) {
;             const bool last = (t == nt - 2);
;             const char* a1 = cA + (size_t)(t + 1) * kstep;
;             const char* a2 = last ? nA : cA + (size_t)(t + 2) * kstep; const char* b2 = last ? nB : cB + (size_t)(t + 2) * kstep;
;             const char* a3 = a2 + kstep; const char* b3 = b2 + kstep;
;             if (last && has_next) S.a_ready(nxt);
;             if constexpr (SP2) {
;             PG8_LDB(B0, 0, 0); PG8_LDB(B1, 0, 1); PG8_SCHED; PG8_LDA(At, 0, 0); PG8_STAGE(PG8_SA(1, 1), a1 + hstep, voffA);
;             PG8_WAIT_V(8); PG8_WAIT_L(0); PG8_BAR; PG8_MMA(0, 0, At, B0); PG8_MMA(0, 1, At, B1); PG8_BAR; PG8_SCHED;
;             PG8_LDA(At, 0, 1); PG8_STAGE(PG8_SB(0, 0), b2, voffB); PG8_STAGE(PG8_SB(0, 1), b2 + hstep, voffB); PG8_STAGE(PG8_SA(0, 0), a2, voffA);
.LBB0_1680:
	s_ashr_i32 s47, s46, 31
	s_lshl_b64 s[48:49], s[46:47], 19
	s_add_u32 s48, s22, s48
	s_addc_u32 s49, s23, s49
	s_and_b64 s[50:51], s[4:5], exec
	s_cselect_b32 s47, s49, s53
	s_cselect_b32 s77, s48, s52
	s_ashr_i32 s45, s44, 31
	s_lshl_b64 s[50:51], s[44:45], 19
	s_add_u32 s50, s15, s50
	s_addc_u32 s51, s33, s51
	s_and_b64 s[56:57], s[4:5], exec
	s_cselect_b32 s45, s51, s55
	s_cselect_b32 s78, s50, s54
	s_add_u32 s52, s52, 0x40080
	s_addc_u32 s53, s53, 0
	s_add_u32 s79, s54, 0x100
	s_addc_u32 s80, s55, 0
	s_mov_b32 s81, -2
	ds_read_b128 v[146:149], v152
	ds_read_b128 v[156:159], v152 offset:1024
	ds_read_b128 v[160:163], v152 offset:2048
	ds_read_b128 v[164:167], v152 offset:3072
	ds_read_b128 v[168:171], v153
	ds_read_b128 v[172:175], v153 offset:1024
	ds_read_b128 v[180:183], v153 offset:2048
	ds_read_b128 v[184:187], v153 offset:3072
	s_add_u32 s54, s52, 0xfffc0080
	s_addc_u32 s55, s53, -1
	s_cmp_eq_u32 s81, 12
	s_cselect_b32 s57, s47, s55
	s_cselect_b32 s56, s77, s54
	s_cselect_b32 s55, s45, s80
	s_cselect_b32 s54, s78, s79
	v_lshl_add_u64 v[200:201], s[52:53], 0, v[136:137]
	s_add_i32 m0, s58, 0xc000
	ds_read_b128 v[188:191], v154
	ds_read_b128 v[192:195], v154 offset:1024
	ds_read_b128 v[196:199], v154 offset:2048
	ds_read_b128 v[206:209], v154 offset:3072
	ds_read_b128 v[210:213], v154 offset:4096
	ds_read_b128 v[214:217], v154 offset:5120
	ds_read_b128 v[218:221], v154 offset:6144
	ds_read_b128 v[222:225], v154 offset:7168
	global_load_lds_dwordx4 v[200:201], off
	v_lshl_add_u64 v[200:201], s[52:53], 0, v[138:139]
	s_add_i32 m0, s58, 0xe000
	s_nop 0
	global_load_lds_dwordx4 v[200:201], off
	s_waitcnt vmcnt(8)
	s_waitcnt lgkmcnt(0)
	s_barrier
	s_setprio 1
	s_waitcnt lgkmcnt(0)
	v_mfma_f32_16x16x32_bf16 v[124:127], v[146:149], v[188:191], 0
	v_mfma_f32_16x16x32_bf16 v[120:123], v[160:163], v[188:191], 0
	v_mfma_f32_16x16x32_bf16 v[108:111], v[146:149], v[196:199], 0
	v_mfma_f32_16x16x32_bf16 v[104:107], v[160:163], v[196:199], 0
	v_mfma_f32_16x16x32_bf16 v[124:127], v[156:159], v[192:195], v[124:127]
	v_mfma_f32_16x16x32_bf16 v[120:123], v[164:167], v[192:195], v[120:123]
	v_mfma_f32_16x16x32_bf16 v[108:111], v[156:159], v[206:209], v[108:111]
	v_mfma_f32_16x16x32_bf16 v[104:107], v[164:167], v[206:209], v[104:107]
	v_mfma_f32_16x16x32_bf16 v[92:95], v[146:149], v[210:213], 0
	v_mfma_f32_16x16x32_bf16 v[88:91], v[160:163], v[210:213], 0
	v_mfma_f32_16x16x32_bf16 v[76:79], v[146:149], v[218:221], 0
	v_mfma_f32_16x16x32_bf16 v[72:75], v[160:163], v[218:221], 0
	v_mfma_f32_16x16x32_bf16 v[92:95], v[156:159], v[214:217], v[92:95]
	v_mfma_f32_16x16x32_bf16 v[88:91], v[164:167], v[214:217], v[88:91]
	v_mfma_f32_16x16x32_bf16 v[76:79], v[156:159], v[222:225], v[76:79]
	v_mfma_f32_16x16x32_bf16 v[72:75], v[164:167], v[222:225], v[72:75]
	s_setprio 0
	s_setprio 1
	v_mfma_f32_16x16x32_bf16 v[116:119], v[168:171], v[188:191], 0
	v_mfma_f32_16x16x32_bf16 v[112:115], v[180:183], v[188:191], 0
	v_mfma_f32_16x16x32_bf16 v[100:103], v[168:171], v[196:199], 0
	v_mfma_f32_16x16x32_bf16 v[96:99], v[180:183], v[196:199], 0
	v_mfma_f32_16x16x32_bf16 v[116:119], v[172:175], v[192:195], v[116:119]
	v_mfma_f32_16x16x32_bf16 v[112:115], v[184:187], v[192:195], v[112:115]
	v_mfma_f32_16x16x32_bf16 v[100:103], v[172:175], v[206:209], v[100:103]
	v_mfma_f32_16x16x32_bf16 v[96:99], v[184:187], v[206:209], v[96:99]
	v_mfma_f32_16x16x32_bf16 v[84:87], v[168:171], v[210:213], 0
	v_mfma_f32_16x16x32_bf16 v[80:83], v[180:183], v[210:213], 0
	v_mfma_f32_16x16x32_bf16 v[68:71], v[168:171], v[218:221], 0
	v_mfma_f32_16x16x32_bf16 v[64:67], v[180:183], v[218:221], 0
	v_mfma_f32_16x16x32_bf16 v[84:87], v[172:175], v[214:217], v[84:87]
	v_mfma_f32_16x16x32_bf16 v[80:83], v[184:187], v[214:217], v[80:83]
	v_mfma_f32_16x16x32_bf16 v[68:71], v[172:175], v[222:225], v[68:71]
	v_mfma_f32_16x16x32_bf16 v[64:67], v[184:187], v[222:225], v[64:67]
	s_setprio 0
	s_barrier
	s_add_i32 s82, s65, s34
	v_lshl_add_u64 v[200:201], s[54:55], 0, v[132:133]
	s_mov_b32 m0, s82
	ds_read_b128 v[188:191], v154 offset:16384
	ds_read_b128 v[192:195], v154 offset:17408
	ds_read_b128 v[196:199], v154 offset:18432
	ds_read_b128 v[206:209], v154 offset:19456
	ds_read_b128 v[210:213], v154 offset:20480
	ds_read_b128 v[214:217], v154 offset:21504
	ds_read_b128 v[218:221], v154 offset:22528
	ds_read_b128 v[222:225], v154 offset:23552
	global_load_lds_dwordx4 v[200:201], off
	s_add_i32 m0, s82, 0x2000
	s_add_u32 s82, s54, 0x40000
	v_lshl_add_u64 v[226:227], s[54:55], 0, v[128:129]
	s_addc_u32 s83, s55, 0
	s_add_i32 s84, s66, s34
	global_load_lds_dwordx4 v[226:227], off
	v_lshl_add_u64 v[228:229], s[82:83], 0, v[132:133]
	s_mov_b32 m0, s84
	global_load_lds_dwordx4 v[228:229], off
	v_lshl_add_u64 v[228:229], s[82:83], 0, v[128:129]
	s_add_i32 m0, s84, 0x2000
	s_nop 0
	global_load_lds_dwordx4 v[228:229], off
	s_waitcnt vmcnt(6)
	s_waitcnt lgkmcnt(0)
	s_barrier
; #define PG8_STAGE(bufoff, gbase, voff) do { _Pragma("unroll") for (int _i = 0; _i < 2; ++_i) \
;         __builtin_amdgcn_global_load_lds((const unsigned*)((const char*)(gbase) + (voff)[_i]), (PG8_LAS unsigned*)(lds + (bufoff) + ldsw + _i * 8192), 16, 0, 0); } while (0)
; #define PG8_LDA(dst, b, h) do { _Pragma("unroll") for (int m = 0; m < 4; ++m) _Pragma("unroll") for (int k = 0; k < 2; ++k) dst[m][k] = *(const PG8_LAS bf16x8*)(lds + PG8_SA(b, h) + aoff + m * 2048 + k * 1024); } while (0)
; #define PG8_LDB(dst, b, h) do { _Pragma("unroll") for (int n = 0; n < 2; ++n) _Pragma("unroll") for (int k = 0; k < 2; ++k) dst[n][k] = *(const PG8_LAS bf16x8*)(lds + PG8_SB(b, h) + boff + n * 2048 + k * 1024); } while (0)
; #define PG8_MMA(ai, bj, At, Bt) do { __builtin_amdgcn_s_setprio(1); _Pragma("unroll") for (int m = 0; m < 4; ++m) _Pragma("unroll") for (int n = 0; n < 2; ++n) _Pragma("unroll") for (int k = 0; k < 2; ++k) \
;         acc[ai][bj][m][n] = __builtin_amdgcn_mfma_f32_16x16x32_bf16(Bt[n][k], At[m][k], acc[ai][bj][m][n], 0, 0, 0); __builtin_amdgcn_s_setprio(0); } while (0)
; #define PG8_WAIT_V(n) asm volatile("s_waitcnt vmcnt(" #n ")" ::: "memory")
; #define PG8_WAIT_L(n) asm volatile("s_waitcnt lgkmcnt(" #n ")" ::: "memory")
; #define PG8_BAR __builtin_amdgcn_s_barrier()
; #define PG8_SCHED __builtin_amdgcn_sched_barrier(0)
; template <class Epi, class Sched, bool ALIGN_EPI = false, bool SP2 = false>
; __device__ __forceinline__ void gemm_phase(PG8_LAS unsigned char* lds, const Gemm g, const Sched& S, const Epi& E) {
;     ...
;             PG8_WAIT_V(8); PG8_WAIT_L(0); PG8_BAR; PG8_MMA(1, 0, At, B0); PG8_MMA(1, 1, At, B1); PG8_BAR; PG8_SCHED;
;             PG8_LDB(B0, 1, 0); PG8_LDB(B1, 1, 1); PG8_SCHED; PG8_LDA(At, 1, 0); PG8_STAGE(PG8_SA(0, 1), a2 + hstep, voffA);
;             PG8_WAIT_V(8); PG8_WAIT_L(0); PG8_BAR; PG8_MMA(0, 0, At, B0); PG8_MMA(0, 1, At, B1); PG8_BAR; PG8_SCHED;
	s_setprio 1
	s_waitcnt lgkmcnt(0)
	v_mfma_f32_16x16x32_bf16 v[60:63], v[146:149], v[188:191], 0
	v_mfma_f32_16x16x32_bf16 v[56:59], v[160:163], v[188:191], 0
	v_mfma_f32_16x16x32_bf16 v[44:47], v[146:149], v[196:199], 0
	v_mfma_f32_16x16x32_bf16 v[40:43], v[160:163], v[196:199], 0
	v_mfma_f32_16x16x32_bf16 v[60:63], v[156:159], v[192:195], v[60:63]
	v_mfma_f32_16x16x32_bf16 v[56:59], v[164:167], v[192:195], v[56:59]
	v_mfma_f32_16x16x32_bf16 v[44:47], v[156:159], v[206:209], v[44:47]
	v_mfma_f32_16x16x32_bf16 v[40:43], v[164:167], v[206:209], v[40:43]
	v_mfma_f32_16x16x32_bf16 v[28:31], v[146:149], v[210:213], 0
	v_mfma_f32_16x16x32_bf16 v[24:27], v[160:163], v[210:213], 0
	v_mfma_f32_16x16x32_bf16 v[12:15], v[146:149], v[218:221], 0
	v_mfma_f32_16x16x32_bf16 v[8:11], v[160:163], v[218:221], 0
	v_mfma_f32_16x16x32_bf16 v[28:31], v[156:159], v[214:217], v[28:31]
	v_mfma_f32_16x16x32_bf16 v[24:27], v[164:167], v[214:217], v[24:27]
	v_lshl_add_u64 v[228:229], s[56:57], 0, v[134:135]
	s_mov_b32 m0, s58
	s_nop 0
	global_load_lds_dwordx4 v[228:229], off
	v_mfma_f32_16x16x32_bf16 v[12:15], v[156:159], v[222:225], v[12:15]
	v_mfma_f32_16x16x32_bf16 v[8:11], v[164:167], v[222:225], v[8:11]
	s_setprio 0
	s_setprio 1
	v_mfma_f32_16x16x32_bf16 v[52:55], v[168:171], v[188:191], 0
	v_mfma_f32_16x16x32_bf16 v[48:51], v[180:183], v[188:191], 0
	v_mfma_f32_16x16x32_bf16 v[36:39], v[168:171], v[196:199], 0
	v_mfma_f32_16x16x32_bf16 v[32:35], v[180:183], v[196:199], 0
	v_mfma_f32_16x16x32_bf16 v[52:55], v[172:175], v[192:195], v[52:55]
	v_mfma_f32_16x16x32_bf16 v[48:51], v[184:187], v[192:195], v[48:51]
	v_mfma_f32_16x16x32_bf16 v[36:39], v[172:175], v[206:209], v[36:39]
	v_mfma_f32_16x16x32_bf16 v[32:35], v[184:187], v[206:209], v[32:35]
	v_mfma_f32_16x16x32_bf16 v[20:23], v[168:171], v[210:213], 0
	v_mfma_f32_16x16x32_bf16 v[16:19], v[180:183], v[210:213], 0
	v_mfma_f32_16x16x32_bf16 v[4:7], v[168:171], v[218:221], 0
	v_mfma_f32_16x16x32_bf16 v[0:3], v[180:183], v[218:221], 0
	v_mfma_f32_16x16x32_bf16 v[20:23], v[172:175], v[214:217], v[20:23]
	v_mfma_f32_16x16x32_bf16 v[16:19], v[184:187], v[214:217], v[16:19]
	v_lshl_add_u64 v[230:231], s[56:57], 0, v[130:131]
	s_mov_b32 m0, s59
	s_nop 0
	global_load_lds_dwordx4 v[230:231], off
	v_mfma_f32_16x16x32_bf16 v[4:7], v[172:175], v[222:225], v[4:7]
	v_mfma_f32_16x16x32_bf16 v[0:3], v[184:187], v[222:225], v[0:3]
	s_setprio 0
	s_barrier
	s_add_i32 s82, 0, 0x18000
	s_add_i32 s83, 0, 0x1c000
	v_add_u32_e32 v164, s82, v150
	v_add_u32_e32 v179, s83, v150
	ds_read_b128 v[146:149], v164
	ds_read_b128 v[156:159], v164 offset:1024
	ds_read_b128 v[160:163], v164 offset:2048
	ds_read_b128 v[164:167], v164 offset:3072
	ds_read_b128 v[168:171], v179
	ds_read_b128 v[172:175], v179 offset:1024
	ds_read_b128 v[180:183], v179 offset:2048
	ds_read_b128 v[184:187], v179 offset:3072
	s_add_u32 s56, s56, 0x40000
	s_addc_u32 s57, s57, 0
	s_mov_b32 m0, s60
	v_lshl_add_u64 v[232:233], s[56:57], 0, v[134:135]
	ds_read_b128 v[188:191], v154 offset:32768
	ds_read_b128 v[192:195], v154 offset:33792
	ds_read_b128 v[196:199], v154 offset:34816
	ds_read_b128 v[206:209], v154 offset:35840
	ds_read_b128 v[210:213], v154 offset:36864
	ds_read_b128 v[214:217], v154 offset:37888
	ds_read_b128 v[218:221], v154 offset:38912
	ds_read_b128 v[222:225], v154 offset:39936
	global_load_lds_dwordx4 v[232:233], off
	v_lshl_add_u64 v[232:233], s[56:57], 0, v[130:131]
	s_mov_b32 m0, s61
	s_nop 0
	global_load_lds_dwordx4 v[232:233], off
	s_waitcnt vmcnt(8)
	s_waitcnt lgkmcnt(0)
	s_barrier
	s_setprio 1
	s_waitcnt lgkmcnt(0)
	v_mfma_f32_16x16x32_bf16 v[124:127], v[146:149], v[188:191], v[124:127]
	v_mfma_f32_16x16x32_bf16 v[120:123], v[160:163], v[188:191], v[120:123]
	v_mfma_f32_16x16x32_bf16 v[108:111], v[146:149], v[196:199], v[108:111]
	v_mfma_f32_16x16x32_bf16 v[104:107], v[160:163], v[196:199], v[104:107]
	v_mfma_f32_16x16x32_bf16 v[124:127], v[156:159], v[192:195], v[124:127]
	v_mfma_f32_16x16x32_bf16 v[120:123], v[164:167], v[192:195], v[120:123]
	v_mfma_f32_16x16x32_bf16 v[108:111], v[156:159], v[206:209], v[108:111]
	v_mfma_f32_16x16x32_bf16 v[104:107], v[164:167], v[206:209], v[104:107]
	v_mfma_f32_16x16x32_bf16 v[92:95], v[146:149], v[210:213], v[92:95]
	v_mfma_f32_16x16x32_bf16 v[88:91], v[160:163], v[210:213], v[88:91]
	v_mfma_f32_16x16x32_bf16 v[76:79], v[146:149], v[218:221], v[76:79]
	v_mfma_f32_16x16x32_bf16 v[72:75], v[160:163], v[218:221], v[72:75]
	v_mfma_f32_16x16x32_bf16 v[92:95], v[156:159], v[214:217], v[92:95]
	v_mfma_f32_16x16x32_bf16 v[88:91], v[164:167], v[214:217], v[88:91]
	v_mfma_f32_16x16x32_bf16 v[76:79], v[156:159], v[222:225], v[76:79]
	v_mfma_f32_16x16x32_bf16 v[72:75], v[164:167], v[222:225], v[72:75]
	s_setprio 0
	s_setprio 1
	v_mfma_f32_16x16x32_bf16 v[116:119], v[168:171], v[188:191], v[116:119]
	v_mfma_f32_16x16x32_bf16 v[112:115], v[180:183], v[188:191], v[112:115]
	v_mfma_f32_16x16x32_bf16 v[100:103], v[168:171], v[196:199], v[100:103]
	v_mfma_f32_16x16x32_bf16 v[96:99], v[180:183], v[196:199], v[96:99]
	v_mfma_f32_16x16x32_bf16 v[116:119], v[172:175], v[192:195], v[116:119]
	v_mfma_f32_16x16x32_bf16 v[112:115], v[184:187], v[192:195], v[112:115]
	v_mfma_f32_16x16x32_bf16 v[100:103], v[172:175], v[206:209], v[100:103]
	v_mfma_f32_16x16x32_bf16 v[96:99], v[184:187], v[206:209], v[96:99]
	v_mfma_f32_16x16x32_bf16 v[84:87], v[168:171], v[210:213], v[84:87]
	v_mfma_f32_16x16x32_bf16 v[80:83], v[180:183], v[210:213], v[80:83]
	v_mfma_f32_16x16x32_bf16 v[68:71], v[168:171], v[218:221], v[68:71]
	v_mfma_f32_16x16x32_bf16 v[64:67], v[180:183], v[218:221], v[64:67]
	v_mfma_f32_16x16x32_bf16 v[84:87], v[172:175], v[214:217], v[84:87]
	v_mfma_f32_16x16x32_bf16 v[80:83], v[184:187], v[214:217], v[80:83]
	v_mfma_f32_16x16x32_bf16 v[68:71], v[172:175], v[222:225], v[68:71]
	v_mfma_f32_16x16x32_bf16 v[64:67], v[184:187], v[222:225], v[64:67]
	s_setprio 0
	s_barrier
; #define PG8_STAGE(bufoff, gbase, voff) do { _Pragma("unroll") for (int _i = 0; _i < 2; ++_i) \
;         __builtin_amdgcn_global_load_lds((const unsigned*)((const char*)(gbase) + (voff)[_i]), (PG8_LAS unsigned*)(lds + (bufoff) + ldsw + _i * 8192), 16, 0, 0); } while (0)
; #define PG8_LDA(dst, b, h) do { _Pragma("unroll") for (int m = 0; m < 4; ++m) _Pragma("unroll") for (int k = 0; k < 2; ++k) dst[m][k] = *(const PG8_LAS bf16x8*)(lds + PG8_SA(b, h) + aoff + m * 2048 + k * 1024); } while (0)
; #define PG8_LDB(dst, b, h) do { _Pragma("unroll") for (int n = 0; n < 2; ++n) _Pragma("unroll") for (int k = 0; k < 2; ++k) dst[n][k] = *(const PG8_LAS bf16x8*)(lds + PG8_SB(b, h) + boff + n * 2048 + k * 1024); } while (0)
; #define PG8_MMA(ai, bj, At, Bt) do { __builtin_amdgcn_s_setprio(1); _Pragma("unroll") for (int m = 0; m < 4; ++m) _Pragma("unroll") for (int n = 0; n < 2; ++n) _Pragma("unroll") for (int k = 0; k < 2; ++k) \
;         acc[ai][bj][m][n] = __builtin_amdgcn_mfma_f32_16x16x32_bf16(Bt[n][k], At[m][k], acc[ai][bj][m][n], 0, 0, 0); __builtin_amdgcn_s_setprio(0); } while (0)
; #define PG8_WAIT_V(n) asm volatile("s_waitcnt vmcnt(" #n ")" ::: "memory")
; template <class Epi, class Sched, bool ALIGN_EPI = false, bool SP2 = false>
; __device__ __forceinline__ void gemm_phase(PG8_LAS unsigned char* lds, const Gemm g, const Sched& S, const Epi& E) {
;     ...
;             PG8_LDB(B0, 0, 0); PG8_LDB(B1, 0, 1); PG8_SCHED; PG8_LDA(At, 0, 0); PG8_STAGE(PG8_SA(1, 1), a1 + hstep, voffA);
;             PG8_WAIT_V(8); PG8_WAIT_L(0); PG8_BAR; PG8_MMA(0, 0, At, B0); PG8_MMA(0, 1, At, B1); PG8_BAR; PG8_SCHED;
;             PG8_LDA(At, 0, 1); PG8_STAGE(PG8_SB(0, 0), b2, voffB); PG8_STAGE(PG8_SB(0, 1), b2 + hstep, voffB); PG8_STAGE(PG8_SA(0, 0), a2, voffA);
;             PG8_WAIT_V(8); PG8_WAIT_L(0); PG8_BAR; PG8_MMA(1, 0, At, B0); PG8_MMA(1, 1, At, B1); PG8_BAR; PG8_SCHED;
;             PG8_LDB(B0, 1, 0); PG8_LDB(B1, 1, 1); PG8_SCHED; PG8_LDA(At, 1, 0); PG8_STAGE(PG8_SA(0, 1), a2 + hstep, voffA);
;             PG8_WAIT_V(8); PG8_WAIT_L(0); PG8_BAR; PG8_MMA(0, 0, At, B0); PG8_MMA(0, 1, At, B1); PG8_BAR; PG8_SCHED;
;             PG8_LDA(At, 1, 1); PG8_STAGE(PG8_SB(1, 0), b3, voffB); PG8_STAGE(PG8_SB(1, 1), b3 + hstep, voffB); PG8_STAGE(PG8_SA(1, 0), a3, voffA);
;             PG8_WAIT_V(8); PG8_WAIT_L(0); PG8_BAR; PG8_MMA(1, 0, At, B0); PG8_MMA(1, 1, At, B1); PG8_BAR; PG8_SCHED;
	s_add_i32 s56, s82, s34
	v_lshl_add_u64 v[200:201], v[200:201], 0, s[26:27]
	s_mov_b32 m0, s56
	ds_read_b128 v[188:191], v154 offset:49152
	ds_read_b128 v[192:195], v154 offset:50176
	ds_read_b128 v[196:199], v154 offset:51200
	ds_read_b128 v[206:209], v154 offset:52224
	ds_read_b128 v[210:213], v154 offset:53248
	ds_read_b128 v[214:217], v154 offset:54272
	ds_read_b128 v[218:221], v154 offset:55296
	ds_read_b128 v[222:225], v154 offset:56320
	global_load_lds_dwordx4 v[200:201], off
	s_add_i32 m0, s56, 0x2000
	s_add_u32 s54, s54, 0x40080
	v_lshl_add_u64 v[200:201], v[226:227], 0, s[26:27]
	s_addc_u32 s55, s55, 0
	s_add_i32 s56, s83, s34
	global_load_lds_dwordx4 v[200:201], off
	v_lshl_add_u64 v[200:201], s[54:55], 0, v[132:133]
	s_mov_b32 m0, s56
	s_nop 0
	global_load_lds_dwordx4 v[200:201], off
	v_lshl_add_u64 v[200:201], s[54:55], 0, v[128:129]
	s_add_i32 m0, s56, 0x2000
	s_nop 0
	global_load_lds_dwordx4 v[200:201], off
	s_waitcnt vmcnt(6)
	s_waitcnt lgkmcnt(0)
	s_barrier
	s_setprio 1
	s_waitcnt lgkmcnt(0)
	v_mfma_f32_16x16x32_bf16 v[60:63], v[146:149], v[188:191], v[60:63]
	v_mfma_f32_16x16x32_bf16 v[56:59], v[160:163], v[188:191], v[56:59]
	v_mfma_f32_16x16x32_bf16 v[44:47], v[146:149], v[196:199], v[44:47]
	v_mfma_f32_16x16x32_bf16 v[40:43], v[160:163], v[196:199], v[40:43]
	v_mfma_f32_16x16x32_bf16 v[60:63], v[156:159], v[192:195], v[60:63]
	v_mfma_f32_16x16x32_bf16 v[56:59], v[164:167], v[192:195], v[56:59]
	v_mfma_f32_16x16x32_bf16 v[44:47], v[156:159], v[206:209], v[44:47]
	v_mfma_f32_16x16x32_bf16 v[40:43], v[164:167], v[206:209], v[40:43]
	v_mfma_f32_16x16x32_bf16 v[28:31], v[146:149], v[210:213], v[28:31]
	v_mfma_f32_16x16x32_bf16 v[24:27], v[160:163], v[210:213], v[24:27]
	v_mfma_f32_16x16x32_bf16 v[12:15], v[146:149], v[218:221], v[12:15]
	v_mfma_f32_16x16x32_bf16 v[8:11], v[160:163], v[218:221], v[8:11]
	v_mfma_f32_16x16x32_bf16 v[28:31], v[156:159], v[214:217], v[28:31]
	v_mfma_f32_16x16x32_bf16 v[24:27], v[164:167], v[214:217], v[24:27]
	v_lshl_add_u64 v[200:201], v[228:229], 0, s[26:27]
	s_mov_b32 m0, s63
	s_nop 0
	global_load_lds_dwordx4 v[200:201], off
	v_mfma_f32_16x16x32_bf16 v[12:15], v[156:159], v[222:225], v[12:15]
	v_mfma_f32_16x16x32_bf16 v[8:11], v[164:167], v[222:225], v[8:11]
	s_setprio 0
	s_setprio 1
	v_mfma_f32_16x16x32_bf16 v[52:55], v[168:171], v[188:191], v[52:55]
	v_mfma_f32_16x16x32_bf16 v[48:51], v[180:183], v[188:191], v[48:51]
	v_mfma_f32_16x16x32_bf16 v[36:39], v[168:171], v[196:199], v[36:39]
	v_mfma_f32_16x16x32_bf16 v[32:35], v[180:183], v[196:199], v[32:35]
	v_mfma_f32_16x16x32_bf16 v[52:55], v[172:175], v[192:195], v[52:55]
	v_mfma_f32_16x16x32_bf16 v[48:51], v[184:187], v[192:195], v[48:51]
	v_mfma_f32_16x16x32_bf16 v[36:39], v[172:175], v[206:209], v[36:39]
	v_mfma_f32_16x16x32_bf16 v[32:35], v[184:187], v[206:209], v[32:35]
	v_mfma_f32_16x16x32_bf16 v[20:23], v[168:171], v[210:213], v[20:23]
	v_mfma_f32_16x16x32_bf16 v[16:19], v[180:183], v[210:213], v[16:19]
	v_mfma_f32_16x16x32_bf16 v[4:7], v[168:171], v[218:221], v[4:7]
	v_mfma_f32_16x16x32_bf16 v[0:3], v[180:183], v[218:221], v[0:3]
	v_mfma_f32_16x16x32_bf16 v[20:23], v[172:175], v[214:217], v[20:23]
	v_mfma_f32_16x16x32_bf16 v[16:19], v[184:187], v[214:217], v[16:19]
	v_lshl_add_u64 v[200:201], v[230:231], 0, s[26:27]
	s_mov_b32 m0, s64
	s_nop 0
	global_load_lds_dwordx4 v[200:201], off
	v_mfma_f32_16x16x32_bf16 v[4:7], v[172:175], v[222:225], v[4:7]
	v_mfma_f32_16x16x32_bf16 v[0:3], v[184:187], v[222:225], v[0:3]
	s_setprio 0
	s_barrier
	s_add_i32 s81, s81, 2
	s_add_u32 s52, s52, 0x100
	s_addc_u32 s53, s53, 0
	s_add_u32 s79, s79, 0x100
	s_addc_u32 s80, s80, 0
.LBB0_1681:
	ds_read_b128 v[146:149], v152
	ds_read_b128 v[156:159], v152 offset:1024
	ds_read_b128 v[160:163], v152 offset:2048
	ds_read_b128 v[164:167], v152 offset:3072
	ds_read_b128 v[168:171], v153
	ds_read_b128 v[172:175], v153 offset:1024
	ds_read_b128 v[180:183], v153 offset:2048
	ds_read_b128 v[184:187], v153 offset:3072
	s_add_u32 s54, s52, 0xfffc0080
	s_addc_u32 s55, s53, -1
	s_cmp_eq_u32 s81, 12
	s_cselect_b32 s57, s47, s55
	s_cselect_b32 s56, s77, s54
	s_cselect_b32 s55, s45, s80
	s_cselect_b32 s54, s78, s79
	v_lshl_add_u64 v[200:201], s[52:53], 0, v[136:137]
	s_add_i32 m0, s58, 0xc000
	ds_read_b128 v[188:191], v154
	ds_read_b128 v[192:195], v154 offset:1024
	ds_read_b128 v[196:199], v154 offset:2048
	ds_read_b128 v[206:209], v154 offset:3072
	ds_read_b128 v[210:213], v154 offset:4096
	ds_read_b128 v[214:217], v154 offset:5120
	ds_read_b128 v[218:221], v154 offset:6144
	ds_read_b128 v[222:225], v154 offset:7168
	global_load_lds_dwordx4 v[200:201], off
	v_lshl_add_u64 v[200:201], s[52:53], 0, v[138:139]
	s_add_i32 m0, s58, 0xe000
	s_nop 0
	global_load_lds_dwordx4 v[200:201], off
	s_waitcnt vmcnt(8)
	s_waitcnt lgkmcnt(0)
	s_barrier
; #define PG8_STAGE(bufoff, gbase, voff) do { _Pragma("unroll") for (int _i = 0; _i < 2; ++_i) \
;         __builtin_amdgcn_global_load_lds((const unsigned*)((const char*)(gbase) + (voff)[_i]), (PG8_LAS unsigned*)(lds + (bufoff) + ldsw + _i * 8192), 16, 0, 0); } while (0)
; #define PG8_LDA(dst, b, h) do { _Pragma("unroll") for (int m = 0; m < 4; ++m) _Pragma("unroll") for (int k = 0; k < 2; ++k) dst[m][k] = *(const PG8_LAS bf16x8*)(lds + PG8_SA(b, h) + aoff + m * 2048 + k * 1024); } while (0)
; #define PG8_MMA(ai, bj, At, Bt) do { __builtin_amdgcn_s_setprio(1); _Pragma("unroll") for (int m = 0; m < 4; ++m) _Pragma("unroll") for (int n = 0; n < 2; ++n) _Pragma("unroll") for (int k = 0; k < 2; ++k) \
;         acc[ai][bj][m][n] = __builtin_amdgcn_mfma_f32_16x16x32_bf16(Bt[n][k], At[m][k], acc[ai][bj][m][n], 0, 0, 0); __builtin_amdgcn_s_setprio(0); } while (0)
; #define PG8_WAIT_V(n) asm volatile("s_waitcnt vmcnt(" #n ")" ::: "memory")
; #define PG8_WAIT_L(n) asm volatile("s_waitcnt lgkmcnt(" #n ")" ::: "memory")
; #define PG8_BAR __builtin_amdgcn_s_barrier()
; #define PG8_SCHED __builtin_amdgcn_sched_barrier(0)
; template <class Epi, class Sched, bool ALIGN_EPI = false, bool SP2 = false>
; __device__ __forceinline__ void gemm_phase(PG8_LAS unsigned char* lds, const Gemm g, const Sched& S, const Epi& E) {
;     ...
;             PG8_WAIT_V(8); PG8_WAIT_L(0); PG8_BAR; PG8_MMA(0, 0, At, B0); PG8_MMA(0, 1, At, B1); PG8_BAR; PG8_SCHED;
;             PG8_LDA(At, 0, 1); PG8_STAGE(PG8_SB(0, 0), b2, voffB); PG8_STAGE(PG8_SB(0, 1), b2 + hstep, voffB); PG8_STAGE(PG8_SA(0, 0), a2, voffA);
;             PG8_WAIT_V(8); PG8_WAIT_L(0); PG8_BAR; PG8_MMA(1, 0, At, B0); PG8_MMA(1, 1, At, B1); PG8_BAR; PG8_SCHED;
	s_setprio 1
	s_waitcnt lgkmcnt(0)
	v_mfma_f32_16x16x32_bf16 v[124:127], v[146:149], v[188:191], v[124:127]
	v_mfma_f32_16x16x32_bf16 v[120:123], v[160:163], v[188:191], v[120:123]
	v_mfma_f32_16x16x32_bf16 v[108:111], v[146:149], v[196:199], v[108:111]
	v_mfma_f32_16x16x32_bf16 v[104:107], v[160:163], v[196:199], v[104:107]
	v_mfma_f32_16x16x32_bf16 v[124:127], v[156:159], v[192:195], v[124:127]
	v_mfma_f32_16x16x32_bf16 v[120:123], v[164:167], v[192:195], v[120:123]
	v_mfma_f32_16x16x32_bf16 v[108:111], v[156:159], v[206:209], v[108:111]
	v_mfma_f32_16x16x32_bf16 v[104:107], v[164:167], v[206:209], v[104:107]
	v_mfma_f32_16x16x32_bf16 v[92:95], v[146:149], v[210:213], v[92:95]
	v_mfma_f32_16x16x32_bf16 v[88:91], v[160:163], v[210:213], v[88:91]
	v_mfma_f32_16x16x32_bf16 v[76:79], v[146:149], v[218:221], v[76:79]
	v_mfma_f32_16x16x32_bf16 v[72:75], v[160:163], v[218:221], v[72:75]
	v_mfma_f32_16x16x32_bf16 v[92:95], v[156:159], v[214:217], v[92:95]
	v_mfma_f32_16x16x32_bf16 v[88:91], v[164:167], v[214:217], v[88:91]
	v_mfma_f32_16x16x32_bf16 v[76:79], v[156:159], v[222:225], v[76:79]
	v_mfma_f32_16x16x32_bf16 v[72:75], v[164:167], v[222:225], v[72:75]
	s_setprio 0
	s_setprio 1
	v_mfma_f32_16x16x32_bf16 v[116:119], v[168:171], v[188:191], v[116:119]
	v_mfma_f32_16x16x32_bf16 v[112:115], v[180:183], v[188:191], v[112:115]
	v_mfma_f32_16x16x32_bf16 v[100:103], v[168:171], v[196:199], v[100:103]
	v_mfma_f32_16x16x32_bf16 v[96:99], v[180:183], v[196:199], v[96:99]
	v_mfma_f32_16x16x32_bf16 v[116:119], v[172:175], v[192:195], v[116:119]
	v_mfma_f32_16x16x32_bf16 v[112:115], v[184:187], v[192:195], v[112:115]
	v_mfma_f32_16x16x32_bf16 v[100:103], v[172:175], v[206:209], v[100:103]
	v_mfma_f32_16x16x32_bf16 v[96:99], v[184:187], v[206:209], v[96:99]
	v_mfma_f32_16x16x32_bf16 v[84:87], v[168:171], v[210:213], v[84:87]
	v_mfma_f32_16x16x32_bf16 v[80:83], v[180:183], v[210:213], v[80:83]
	v_mfma_f32_16x16x32_bf16 v[68:71], v[168:171], v[218:221], v[68:71]
	v_mfma_f32_16x16x32_bf16 v[64:67], v[180:183], v[218:221], v[64:67]
	v_mfma_f32_16x16x32_bf16 v[84:87], v[172:175], v[214:217], v[84:87]
	v_mfma_f32_16x16x32_bf16 v[80:83], v[184:187], v[214:217], v[80:83]
	v_mfma_f32_16x16x32_bf16 v[68:71], v[172:175], v[222:225], v[68:71]
	v_mfma_f32_16x16x32_bf16 v[64:67], v[184:187], v[222:225], v[64:67]
	s_setprio 0
	s_barrier
	s_add_i32 s82, s65, s34
	v_lshl_add_u64 v[200:201], s[54:55], 0, v[132:133]
	s_mov_b32 m0, s82
	ds_read_b128 v[188:191], v154 offset:16384
	ds_read_b128 v[192:195], v154 offset:17408
	ds_read_b128 v[196:199], v154 offset:18432
	ds_read_b128 v[206:209], v154 offset:19456
	ds_read_b128 v[210:213], v154 offset:20480
	ds_read_b128 v[214:217], v154 offset:21504
	ds_read_b128 v[218:221], v154 offset:22528
	ds_read_b128 v[222:225], v154 offset:23552
	global_load_lds_dwordx4 v[200:201], off
	s_add_i32 m0, s82, 0x2000
	s_add_u32 s82, s54, 0x40000
	v_lshl_add_u64 v[226:227], s[54:55], 0, v[128:129]
	s_addc_u32 s83, s55, 0
	s_add_i32 s84, s66, s34
	global_load_lds_dwordx4 v[226:227], off
	v_lshl_add_u64 v[228:229], s[82:83], 0, v[132:133]
	s_mov_b32 m0, s84
	global_load_lds_dwordx4 v[228:229], off
	v_lshl_add_u64 v[228:229], s[82:83], 0, v[128:129]
	s_add_i32 m0, s84, 0x2000
	s_nop 0
	global_load_lds_dwordx4 v[228:229], off
	s_waitcnt vmcnt(6)
	s_waitcnt lgkmcnt(0)
	s_barrier
	s_setprio 1
	s_waitcnt lgkmcnt(0)
	v_mfma_f32_16x16x32_bf16 v[60:63], v[146:149], v[188:191], v[60:63]
	v_mfma_f32_16x16x32_bf16 v[56:59], v[160:163], v[188:191], v[56:59]
	v_mfma_f32_16x16x32_bf16 v[44:47], v[146:149], v[196:199], v[44:47]
	v_mfma_f32_16x16x32_bf16 v[40:43], v[160:163], v[196:199], v[40:43]
	v_mfma_f32_16x16x32_bf16 v[60:63], v[156:159], v[192:195], v[60:63]
	v_mfma_f32_16x16x32_bf16 v[56:59], v[164:167], v[192:195], v[56:59]
	v_mfma_f32_16x16x32_bf16 v[44:47], v[156:159], v[206:209], v[44:47]
	v_mfma_f32_16x16x32_bf16 v[40:43], v[164:167], v[206:209], v[40:43]
	v_mfma_f32_16x16x32_bf16 v[28:31], v[146:149], v[210:213], v[28:31]
	v_mfma_f32_16x16x32_bf16 v[24:27], v[160:163], v[210:213], v[24:27]
	v_mfma_f32_16x16x32_bf16 v[12:15], v[146:149], v[218:221], v[12:15]
	v_mfma_f32_16x16x32_bf16 v[8:11], v[160:163], v[218:221], v[8:11]
	v_mfma_f32_16x16x32_bf16 v[28:31], v[156:159], v[214:217], v[28:31]
	v_mfma_f32_16x16x32_bf16 v[24:27], v[164:167], v[214:217], v[24:27]
	v_lshl_add_u64 v[228:229], s[56:57], 0, v[134:135]
	s_mov_b32 m0, s58
	s_nop 0
	global_load_lds_dwordx4 v[228:229], off
	v_mfma_f32_16x16x32_bf16 v[12:15], v[156:159], v[222:225], v[12:15]
	v_mfma_f32_16x16x32_bf16 v[8:11], v[164:167], v[222:225], v[8:11]
	s_setprio 0
	s_setprio 1
	v_mfma_f32_16x16x32_bf16 v[52:55], v[168:171], v[188:191], v[52:55]
	v_mfma_f32_16x16x32_bf16 v[48:51], v[180:183], v[188:191], v[48:51]
	v_mfma_f32_16x16x32_bf16 v[36:39], v[168:171], v[196:199], v[36:39]
	v_mfma_f32_16x16x32_bf16 v[32:35], v[180:183], v[196:199], v[32:35]
	v_mfma_f32_16x16x32_bf16 v[52:55], v[172:175], v[192:195], v[52:55]
	v_mfma_f32_16x16x32_bf16 v[48:51], v[184:187], v[192:195], v[48:51]
	v_mfma_f32_16x16x32_bf16 v[36:39], v[172:175], v[206:209], v[36:39]
	v_mfma_f32_16x16x32_bf16 v[32:35], v[184:187], v[206:209], v[32:35]
	v_mfma_f32_16x16x32_bf16 v[20:23], v[168:171], v[210:213], v[20:23]
	v_mfma_f32_16x16x32_bf16 v[16:19], v[180:183], v[210:213], v[16:19]
	v_mfma_f32_16x16x32_bf16 v[4:7], v[168:171], v[218:221], v[4:7]
	v_mfma_f32_16x16x32_bf16 v[0:3], v[180:183], v[218:221], v[0:3]
	v_mfma_f32_16x16x32_bf16 v[20:23], v[172:175], v[214:217], v[20:23]
	v_mfma_f32_16x16x32_bf16 v[16:19], v[184:187], v[214:217], v[16:19]
	v_lshl_add_u64 v[230:231], s[56:57], 0, v[130:131]
	s_mov_b32 m0, s59
	s_nop 0
	global_load_lds_dwordx4 v[230:231], off
	v_mfma_f32_16x16x32_bf16 v[4:7], v[172:175], v[222:225], v[4:7]
	v_mfma_f32_16x16x32_bf16 v[0:3], v[184:187], v[222:225], v[0:3]
	s_setprio 0
	s_barrier
; #define PG8_STAGE(bufoff, gbase, voff) do { _Pragma("unroll") for (int _i = 0; _i < 2; ++_i) \
;         __builtin_amdgcn_global_load_lds((const unsigned*)((const char*)(gbase) + (voff)[_i]), (PG8_LAS unsigned*)(lds + (bufoff) + ldsw + _i * 8192), 16, 0, 0); } while (0)
; #define PG8_LDA(dst, b, h) do { _Pragma("unroll") for (int m = 0; m < 4; ++m) _Pragma("unroll") for (int k = 0; k < 2; ++k) dst[m][k] = *(const PG8_LAS bf16x8*)(lds + PG8_SA(b, h) + aoff + m * 2048 + k * 1024); } while (0)
; #define PG8_LDB(dst, b, h) do { _Pragma("unroll") for (int n = 0; n < 2; ++n) _Pragma("unroll") for (int k = 0; k < 2; ++k) dst[n][k] = *(const PG8_LAS bf16x8*)(lds + PG8_SB(b, h) + boff + n * 2048 + k * 1024); } while (0)
; #define PG8_MMA(ai, bj, At, Bt) do { __builtin_amdgcn_s_setprio(1); _Pragma("unroll") for (int m = 0; m < 4; ++m) _Pragma("unroll") for (int n = 0; n < 2; ++n) _Pragma("unroll") for (int k = 0; k < 2; ++k) \
;         acc[ai][bj][m][n] = __builtin_amdgcn_mfma_f32_16x16x32_bf16(Bt[n][k], At[m][k], acc[ai][bj][m][n], 0, 0, 0); __builtin_amdgcn_s_setprio(0); } while (0)
; #define PG8_WAIT_V(n) asm volatile("s_waitcnt vmcnt(" #n ")" ::: "memory")
; #define PG8_WAIT_L(n) asm volatile("s_waitcnt lgkmcnt(" #n ")" ::: "memory")
; #define PG8_BAR __builtin_amdgcn_s_barrier()
; #define PG8_SCHED __builtin_amdgcn_sched_barrier(0)
; template <class Epi, class Sched, bool ALIGN_EPI = false, bool SP2 = false>
; __device__ __forceinline__ void gemm_phase(PG8_LAS unsigned char* lds, const Gemm g, const Sched& S, const Epi& E) {
;     ...
;             PG8_LDB(B0, 1, 0); PG8_LDB(B1, 1, 1); PG8_SCHED; PG8_LDA(At, 1, 0); PG8_STAGE(PG8_SA(0, 1), a2 + hstep, voffA);
;             PG8_WAIT_V(8); PG8_WAIT_L(0); PG8_BAR; PG8_MMA(0, 0, At, B0); PG8_MMA(0, 1, At, B1); PG8_BAR; PG8_SCHED;
	s_add_i32 s82, 0, 0x18000
	s_add_i32 s83, 0, 0x1c000
	v_add_u32_e32 v164, s82, v150
	v_add_u32_e32 v179, s83, v150
	ds_read_b128 v[146:149], v164
	ds_read_b128 v[156:159], v164 offset:1024
	ds_read_b128 v[160:163], v164 offset:2048
	ds_read_b128 v[164:167], v164 offset:3072
	ds_read_b128 v[168:171], v179
	ds_read_b128 v[172:175], v179 offset:1024
	ds_read_b128 v[180:183], v179 offset:2048
	ds_read_b128 v[184:187], v179 offset:3072
	s_add_u32 s56, s56, 0x40000
	s_addc_u32 s57, s57, 0
	s_mov_b32 m0, s60
	v_lshl_add_u64 v[232:233], s[56:57], 0, v[134:135]
	ds_read_b128 v[188:191], v154 offset:32768
	ds_read_b128 v[192:195], v154 offset:33792
	ds_read_b128 v[196:199], v154 offset:34816
	ds_read_b128 v[206:209], v154 offset:35840
	ds_read_b128 v[210:213], v154 offset:36864
	ds_read_b128 v[214:217], v154 offset:37888
	ds_read_b128 v[218:221], v154 offset:38912
	ds_read_b128 v[222:225], v154 offset:39936
	global_load_lds_dwordx4 v[232:233], off
	v_lshl_add_u64 v[232:233], s[56:57], 0, v[130:131]
	s_mov_b32 m0, s61
	s_nop 0
	global_load_lds_dwordx4 v[232:233], off
	s_waitcnt vmcnt(8)
	s_waitcnt lgkmcnt(0)
	s_barrier
	s_setprio 1
	s_waitcnt lgkmcnt(0)
	v_mfma_f32_16x16x32_bf16 v[124:127], v[146:149], v[188:191], v[124:127]
	v_mfma_f32_16x16x32_bf16 v[120:123], v[160:163], v[188:191], v[120:123]
	v_mfma_f32_16x16x32_bf16 v[108:111], v[146:149], v[196:199], v[108:111]
	v_mfma_f32_16x16x32_bf16 v[104:107], v[160:163], v[196:199], v[104:107]
	v_mfma_f32_16x16x32_bf16 v[124:127], v[156:159], v[192:195], v[124:127]
	v_mfma_f32_16x16x32_bf16 v[120:123], v[164:167], v[192:195], v[120:123]
	v_mfma_f32_16x16x32_bf16 v[108:111], v[156:159], v[206:209], v[108:111]
	v_mfma_f32_16x16x32_bf16 v[104:107], v[164:167], v[206:209], v[104:107]
	v_mfma_f32_16x16x32_bf16 v[92:95], v[146:149], v[210:213], v[92:95]
	v_mfma_f32_16x16x32_bf16 v[88:91], v[160:163], v[210:213], v[88:91]
	v_mfma_f32_16x16x32_bf16 v[76:79], v[146:149], v[218:221], v[76:79]
	v_mfma_f32_16x16x32_bf16 v[72:75], v[160:163], v[218:221], v[72:75]
	v_mfma_f32_16x16x32_bf16 v[92:95], v[156:159], v[214:217], v[92:95]
	v_mfma_f32_16x16x32_bf16 v[88:91], v[164:167], v[214:217], v[88:91]
	v_mfma_f32_16x16x32_bf16 v[76:79], v[156:159], v[222:225], v[76:79]
	v_mfma_f32_16x16x32_bf16 v[72:75], v[164:167], v[222:225], v[72:75]
	s_setprio 0
	s_setprio 1
	v_mfma_f32_16x16x32_bf16 v[116:119], v[168:171], v[188:191], v[116:119]
	v_mfma_f32_16x16x32_bf16 v[112:115], v[180:183], v[188:191], v[112:115]
	v_mfma_f32_16x16x32_bf16 v[100:103], v[168:171], v[196:199], v[100:103]
	v_mfma_f32_16x16x32_bf16 v[96:99], v[180:183], v[196:199], v[96:99]
	v_mfma_f32_16x16x32_bf16 v[116:119], v[172:175], v[192:195], v[116:119]
	v_mfma_f32_16x16x32_bf16 v[112:115], v[184:187], v[192:195], v[112:115]
	v_mfma_f32_16x16x32_bf16 v[100:103], v[172:175], v[206:209], v[100:103]
	v_mfma_f32_16x16x32_bf16 v[96:99], v[184:187], v[206:209], v[96:99]
	v_mfma_f32_16x16x32_bf16 v[84:87], v[168:171], v[210:213], v[84:87]
	v_mfma_f32_16x16x32_bf16 v[80:83], v[180:183], v[210:213], v[80:83]
	v_mfma_f32_16x16x32_bf16 v[68:71], v[168:171], v[218:221], v[68:71]
	v_mfma_f32_16x16x32_bf16 v[64:67], v[180:183], v[218:221], v[64:67]
	v_mfma_f32_16x16x32_bf16 v[84:87], v[172:175], v[214:217], v[84:87]
	v_mfma_f32_16x16x32_bf16 v[80:83], v[184:187], v[214:217], v[80:83]
	v_mfma_f32_16x16x32_bf16 v[68:71], v[172:175], v[222:225], v[68:71]
	v_mfma_f32_16x16x32_bf16 v[64:67], v[184:187], v[222:225], v[64:67]
	s_setprio 0
	s_barrier
; #define PG8_STAGE(bufoff, gbase, voff) do { _Pragma("unroll") for (int _i = 0; _i < 2; ++_i) \
;         __builtin_amdgcn_global_load_lds((const unsigned*)((const char*)(gbase) + (voff)[_i]), (PG8_LAS unsigned*)(lds + (bufoff) + ldsw + _i * 8192), 16, 0, 0); } while (0)
; #define PG8_LDA(dst, b, h) do { _Pragma("unroll") for (int m = 0; m < 4; ++m) _Pragma("unroll") for (int k = 0; k < 2; ++k) dst[m][k] = *(const PG8_LAS bf16x8*)(lds + PG8_SA(b, h) + aoff + m * 2048 + k * 1024); } while (0)
; #define PG8_MMA(ai, bj, At, Bt) do { __builtin_amdgcn_s_setprio(1); _Pragma("unroll") for (int m = 0; m < 4; ++m) _Pragma("unroll") for (int n = 0; n < 2; ++n) _Pragma("unroll") for (int k = 0; k < 2; ++k) \
;         acc[ai][bj][m][n] = __builtin_amdgcn_mfma_f32_16x16x32_bf16(Bt[n][k], At[m][k], acc[ai][bj][m][n], 0, 0, 0); __builtin_amdgcn_s_setprio(0); } while (0)
; #define PG8_WAIT_V(n) asm volatile("s_waitcnt vmcnt(" #n ")" ::: "memory")
; #define PG8_WAIT_L(n) asm volatile("s_waitcnt lgkmcnt(" #n ")" ::: "memory")
; #define PG8_BAR __builtin_amdgcn_s_barrier()
; #define PG8_SCHED __builtin_amdgcn_sched_barrier(0)
; template <class Epi, class Sched, bool ALIGN_EPI = false, bool SP2 = false>
; __device__ __forceinline__ void gemm_phase(PG8_LAS unsigned char* lds, const Gemm g, const Sched& S, const Epi& E) {
;     ...
;             PG8_LDA(At, 1, 1); PG8_STAGE(PG8_SB(1, 0), b3, voffB); PG8_STAGE(PG8_SB(1, 1), b3 + hstep, voffB); PG8_STAGE(PG8_SA(1, 0), a3, voffA);
;             PG8_WAIT_V(8); PG8_WAIT_L(0); PG8_BAR; PG8_MMA(1, 0, At, B0); PG8_MMA(1, 1, At, B1); PG8_BAR; PG8_SCHED;
;     ...
;         if constexpr (ALIGN_EPI) { if (wr == 0) PG8_BAR; }
	s_add_i32 s56, s82, s34
	v_lshl_add_u64 v[200:201], v[200:201], 0, s[26:27]
	s_mov_b32 m0, s56
	ds_read_b128 v[188:191], v154 offset:49152
	ds_read_b128 v[192:195], v154 offset:50176
	ds_read_b128 v[196:199], v154 offset:51200
	ds_read_b128 v[206:209], v154 offset:52224
	ds_read_b128 v[210:213], v154 offset:53248
	ds_read_b128 v[214:217], v154 offset:54272
	ds_read_b128 v[218:221], v154 offset:55296
	ds_read_b128 v[222:225], v154 offset:56320
	global_load_lds_dwordx4 v[200:201], off
	s_add_i32 m0, s56, 0x2000
	s_add_u32 s54, s54, 0x40080
	v_lshl_add_u64 v[200:201], v[226:227], 0, s[26:27]
	s_addc_u32 s55, s55, 0
	s_add_i32 s56, s83, s34
	global_load_lds_dwordx4 v[200:201], off
	v_lshl_add_u64 v[200:201], s[54:55], 0, v[132:133]
	s_mov_b32 m0, s56
	s_nop 0
	global_load_lds_dwordx4 v[200:201], off
	v_lshl_add_u64 v[200:201], s[54:55], 0, v[128:129]
	s_add_i32 m0, s56, 0x2000
	s_nop 0
	global_load_lds_dwordx4 v[200:201], off
	s_waitcnt vmcnt(6)
	s_waitcnt lgkmcnt(0)
	s_barrier
	s_setprio 1
	s_waitcnt lgkmcnt(0)
	v_mfma_f32_16x16x32_bf16 v[60:63], v[146:149], v[188:191], v[60:63]
	v_mfma_f32_16x16x32_bf16 v[56:59], v[160:163], v[188:191], v[56:59]
	v_mfma_f32_16x16x32_bf16 v[44:47], v[146:149], v[196:199], v[44:47]
	v_mfma_f32_16x16x32_bf16 v[40:43], v[160:163], v[196:199], v[40:43]
	v_mfma_f32_16x16x32_bf16 v[60:63], v[156:159], v[192:195], v[60:63]
	v_mfma_f32_16x16x32_bf16 v[56:59], v[164:167], v[192:195], v[56:59]
	v_mfma_f32_16x16x32_bf16 v[44:47], v[156:159], v[206:209], v[44:47]
	v_mfma_f32_16x16x32_bf16 v[40:43], v[164:167], v[206:209], v[40:43]
	v_mfma_f32_16x16x32_bf16 v[28:31], v[146:149], v[210:213], v[28:31]
	v_mfma_f32_16x16x32_bf16 v[24:27], v[160:163], v[210:213], v[24:27]
	v_mfma_f32_16x16x32_bf16 v[12:15], v[146:149], v[218:221], v[12:15]
	v_mfma_f32_16x16x32_bf16 v[8:11], v[160:163], v[218:221], v[8:11]
	v_mfma_f32_16x16x32_bf16 v[28:31], v[156:159], v[214:217], v[28:31]
	v_mfma_f32_16x16x32_bf16 v[24:27], v[164:167], v[214:217], v[24:27]
	v_lshl_add_u64 v[200:201], v[228:229], 0, s[26:27]
	s_mov_b32 m0, s63
	s_nop 0
	global_load_lds_dwordx4 v[200:201], off
	v_mfma_f32_16x16x32_bf16 v[12:15], v[156:159], v[222:225], v[12:15]
	v_mfma_f32_16x16x32_bf16 v[8:11], v[164:167], v[222:225], v[8:11]
	s_setprio 0
	s_setprio 1
	v_mfma_f32_16x16x32_bf16 v[52:55], v[168:171], v[188:191], v[52:55]
	v_mfma_f32_16x16x32_bf16 v[48:51], v[180:183], v[188:191], v[48:51]
	v_mfma_f32_16x16x32_bf16 v[36:39], v[168:171], v[196:199], v[36:39]
	v_mfma_f32_16x16x32_bf16 v[32:35], v[180:183], v[196:199], v[32:35]
	v_mfma_f32_16x16x32_bf16 v[52:55], v[172:175], v[192:195], v[52:55]
	v_mfma_f32_16x16x32_bf16 v[48:51], v[184:187], v[192:195], v[48:51]
	v_mfma_f32_16x16x32_bf16 v[36:39], v[172:175], v[206:209], v[36:39]
	v_mfma_f32_16x16x32_bf16 v[32:35], v[184:187], v[206:209], v[32:35]
	v_mfma_f32_16x16x32_bf16 v[20:23], v[168:171], v[210:213], v[20:23]
	v_mfma_f32_16x16x32_bf16 v[16:19], v[180:183], v[210:213], v[16:19]
	v_mfma_f32_16x16x32_bf16 v[4:7], v[168:171], v[218:221], v[4:7]
	v_mfma_f32_16x16x32_bf16 v[0:3], v[180:183], v[218:221], v[0:3]
	v_mfma_f32_16x16x32_bf16 v[20:23], v[172:175], v[214:217], v[20:23]
	v_mfma_f32_16x16x32_bf16 v[16:19], v[184:187], v[214:217], v[16:19]
	v_lshl_add_u64 v[200:201], v[230:231], 0, s[26:27]
	s_mov_b32 m0, s64
	s_nop 0
	global_load_lds_dwordx4 v[200:201], off
	v_mfma_f32_16x16x32_bf16 v[4:7], v[172:175], v[222:225], v[4:7]
	v_mfma_f32_16x16x32_bf16 v[0:3], v[184:187], v[222:225], v[0:3]
	s_setprio 0
	s_barrier
	s_add_i32 s81, s81, 2
	s_add_u32 s52, s52, 0x100
	s_addc_u32 s53, s53, 0
	s_add_u32 s79, s79, 0x100
	s_addc_u32 s80, s80, 0
	s_cmp_gt_u32 s81, 13
	s_cbranch_scc0 .LBB0_1681
	s_and_b64 vcc, exec, s[28:29]
	s_cbranch_vccz .LBB0_1684
	s_barrier

; #define PG8_STAGE(bufoff, gbase, voff) do { _Pragma("unroll") for (int _i = 0; _i < 2; ++_i) \
;         __builtin_amdgcn_global_load_lds((const unsigned*)((const char*)(gbase) + (voff)[_i]), (PG8_LAS unsigned*)(lds + (bufoff) + ldsw + _i * 8192), 16, 0, 0); } while (0)
; #define PG8_LDA(dst, b, h) do { _Pragma("unroll") for (int m = 0; m < 4; ++m) _Pragma("unroll") for (int k = 0; k < 2; ++k) dst[m][k] = *(const PG8_LAS bf16x8*)(lds + PG8_SA(b, h) + aoff + m * 2048 + k * 1024); } while (0)
; #define PG8_LDB(dst, b, h) do { _Pragma("unroll") for (int n = 0; n < 2; ++n) _Pragma("unroll") for (int k = 0; k < 2; ++k) dst[n][k] = *(const PG8_LAS bf16x8*)(lds + PG8_SB(b, h) + boff + n * 2048 + k * 1024); } while (0)
; #define PG8_MMA(ai, bj, At, Bt) do { __builtin_amdgcn_s_setprio(1); _Pragma("unroll") for (int m = 0; m < 4; ++m) _Pragma("unroll") for (int n = 0; n < 2; ++n) _Pragma("unroll") for (int k = 0; k < 2; ++k) \
;         acc[ai][bj][m][n] = __builtin_amdgcn_mfma_f32_16x16x32_bf16(Bt[n][k], At[m][k], acc[ai][bj][m][n], 0, 0, 0); __builtin_amdgcn_s_setprio(0); } while (0)
; #define PG8_BAR __builtin_amdgcn_s_barrier()
; template <class Epi, class Sched, bool ALIGN_EPI = false, bool SP2 = false>
; __device__ __forceinline__ void gemm_phase(PG8_LAS unsigned char* lds, const Gemm g, const Sched& S, const Epi& E) {
;     ...
;         const bool has_next = S.next(ui + 1, nxt);
;         const char* nA = has_next ? (const char*)g.A + (size_t)nxt.pm * tstep : cA; const char* nB = has_next ? (const char*)g.Bt + (size_t)nxt.pn * tstep : cB;
;         for (int t = 0; t < nt; t += 2) {
;             const bool last = (t == nt - 2);
;             const char* a1 = cA + (size_t)(t + 1) * kstep;
;             const char* a2 = last ? nA : cA + (size_t)(t + 2) * kstep; const char* b2 = last ? nB : cB + (size_t)(t + 2) * kstep;
;             const char* a3 = a2 + kstep; const char* b3 = b2 + kstep;
;             if (last && has_next) S.a_ready(nxt);
;             if constexpr (SP2) {
;             PG8_LDB(B0, 0, 0); PG8_LDB(B1, 0, 1); PG8_SCHED; PG8_LDA(At, 0, 0); PG8_STAGE(PG8_SA(1, 1), a1 + hstep, voffA);
;             PG8_WAIT_V(8); PG8_WAIT_L(0); PG8_BAR; PG8_MMA(0, 0, At, B0); PG8_MMA(0, 1, At, B1); PG8_BAR; PG8_SCHED;
;             PG8_LDA(At, 0, 1); PG8_STAGE(PG8_SB(0, 0), b2, voffB); PG8_STAGE(PG8_SB(0, 1), b2 + hstep, voffB); PG8_STAGE(PG8_SA(0, 0), a2, voffA);
.LBB0_1815:
	s_ashr_i32 s29, s28, 31
	s_lshl_b64 s[36:37], s[28:29], 18
	s_add_u32 s36, s92, s36
	s_addc_u32 s37, s93, s37
	s_and_b64 s[38:39], s[6:7], exec
	s_cselect_b32 s29, s37, s45
	s_cselect_b32 s41, s36, s44
	s_ashr_i32 s27, s26, 31
	s_lshl_b64 s[38:39], s[26:27], 18
	s_add_u32 s38, s3, s38
	s_addc_u32 s39, s14, s39
	s_and_b64 s[48:49], s[6:7], exec
	s_cselect_b32 s27, s39, s47
	s_cselect_b32 s58, s38, s46
	s_add_u32 s44, s44, 0x20080
	s_addc_u32 s45, s45, 0
	s_add_u32 s59, s46, 0x100
	s_addc_u32 s60, s47, 0
	s_mov_b32 s61, -2
	s_waitcnt lgkmcnt(0)
	ds_read_b128 v[144:147], v151
	ds_read_b128 v[156:159], v151 offset:1024
	ds_read_b128 v[160:163], v151 offset:2048
	ds_read_b128 v[164:167], v151 offset:3072
	ds_read_b128 v[168:171], v152
	ds_read_b128 v[172:175], v152 offset:1024
	ds_read_b128 v[176:179], v152 offset:2048
	ds_read_b128 v[180:183], v152 offset:3072
	s_add_u32 s46, s44, 0xfffe0080
	s_addc_u32 s47, s45, -1
	s_cmp_eq_u32 s61, 4
	s_cselect_b32 s49, s29, s47
	s_cselect_b32 s48, s41, s46
	s_cselect_b32 s47, s27, s60
	s_cselect_b32 s46, s58, s59
	v_lshl_add_u64 v[218:219], s[44:45], 0, v[136:137]
	s_add_i32 m0, s33, 0xc000
	ds_read_b128 v[184:187], v153
	ds_read_b128 v[188:191], v153 offset:1024
	ds_read_b128 v[192:195], v153 offset:2048
	ds_read_b128 v[196:199], v153 offset:3072
	ds_read_b128 v[200:203], v153 offset:4096
	ds_read_b128 v[206:209], v153 offset:5120
	ds_read_b128 v[210:213], v153 offset:6144
	ds_read_b128 v[214:217], v153 offset:7168
	global_load_lds_dwordx4 v[218:219], off
	v_lshl_add_u64 v[218:219], s[44:45], 0, v[138:139]
	s_add_i32 m0, s33, 0xe000
	s_nop 0
	global_load_lds_dwordx4 v[218:219], off
	s_waitcnt vmcnt(8)
	s_waitcnt lgkmcnt(0)
	s_barrier
	s_setprio 1
	s_waitcnt lgkmcnt(0)
	v_mfma_f32_16x16x32_bf16 v[124:127], v[144:147], v[184:187], 0
	v_mfma_f32_16x16x32_bf16 v[120:123], v[160:163], v[184:187], 0
	v_mfma_f32_16x16x32_bf16 v[108:111], v[144:147], v[192:195], 0
	v_mfma_f32_16x16x32_bf16 v[104:107], v[160:163], v[192:195], 0
	v_mfma_f32_16x16x32_bf16 v[124:127], v[156:159], v[188:191], v[124:127]
	v_mfma_f32_16x16x32_bf16 v[120:123], v[164:167], v[188:191], v[120:123]
	v_mfma_f32_16x16x32_bf16 v[108:111], v[156:159], v[196:199], v[108:111]
	v_mfma_f32_16x16x32_bf16 v[104:107], v[164:167], v[196:199], v[104:107]
	v_mfma_f32_16x16x32_bf16 v[92:95], v[144:147], v[200:203], 0
	v_mfma_f32_16x16x32_bf16 v[88:91], v[160:163], v[200:203], 0
	v_mfma_f32_16x16x32_bf16 v[76:79], v[144:147], v[210:213], 0
	v_mfma_f32_16x16x32_bf16 v[72:75], v[160:163], v[210:213], 0
	v_mfma_f32_16x16x32_bf16 v[92:95], v[156:159], v[206:209], v[92:95]
	v_mfma_f32_16x16x32_bf16 v[88:91], v[164:167], v[206:209], v[88:91]
	v_mfma_f32_16x16x32_bf16 v[76:79], v[156:159], v[214:217], v[76:79]
	v_mfma_f32_16x16x32_bf16 v[72:75], v[164:167], v[214:217], v[72:75]
	s_setprio 0
	s_setprio 1
	v_mfma_f32_16x16x32_bf16 v[116:119], v[168:171], v[184:187], 0
	v_mfma_f32_16x16x32_bf16 v[112:115], v[176:179], v[184:187], 0
	v_mfma_f32_16x16x32_bf16 v[100:103], v[168:171], v[192:195], 0
	v_mfma_f32_16x16x32_bf16 v[96:99], v[176:179], v[192:195], 0
	v_mfma_f32_16x16x32_bf16 v[116:119], v[172:175], v[188:191], v[116:119]
	v_mfma_f32_16x16x32_bf16 v[112:115], v[180:183], v[188:191], v[112:115]
	v_mfma_f32_16x16x32_bf16 v[100:103], v[172:175], v[196:199], v[100:103]
	v_mfma_f32_16x16x32_bf16 v[96:99], v[180:183], v[196:199], v[96:99]
	v_mfma_f32_16x16x32_bf16 v[84:87], v[168:171], v[200:203], 0
	v_mfma_f32_16x16x32_bf16 v[80:83], v[176:179], v[200:203], 0
	v_mfma_f32_16x16x32_bf16 v[68:71], v[168:171], v[210:213], 0
	v_mfma_f32_16x16x32_bf16 v[64:67], v[176:179], v[210:213], 0
	v_mfma_f32_16x16x32_bf16 v[84:87], v[172:175], v[206:209], v[84:87]
	v_mfma_f32_16x16x32_bf16 v[80:83], v[180:183], v[206:209], v[80:83]
	v_mfma_f32_16x16x32_bf16 v[68:71], v[172:175], v[214:217], v[68:71]
	v_mfma_f32_16x16x32_bf16 v[64:67], v[180:183], v[214:217], v[64:67]
	s_setprio 0
	s_barrier
	s_add_i32 s62, s54, s15
	v_lshl_add_u64 v[218:219], s[46:47], 0, v[130:131]
	s_mov_b32 m0, s62
	ds_read_b128 v[184:187], v153 offset:16384
	ds_read_b128 v[188:191], v153 offset:17408
	ds_read_b128 v[192:195], v153 offset:18432
	ds_read_b128 v[196:199], v153 offset:19456
	ds_read_b128 v[200:203], v153 offset:20480
	ds_read_b128 v[206:209], v153 offset:21504
	ds_read_b128 v[210:213], v153 offset:22528
	ds_read_b128 v[214:217], v153 offset:23552
	global_load_lds_dwordx4 v[218:219], off
	s_add_i32 m0, s62, 0x2000
	s_add_u32 s62, s46, 0x20000
	v_lshl_add_u64 v[220:221], s[46:47], 0, v[134:135]
	s_addc_u32 s63, s47, 0
	s_add_i32 s64, s55, s15
	global_load_lds_dwordx4 v[220:221], off
	v_lshl_add_u64 v[222:223], s[62:63], 0, v[130:131]
	s_mov_b32 m0, s64
	global_load_lds_dwordx4 v[222:223], off
	v_lshl_add_u64 v[222:223], s[62:63], 0, v[134:135]
	s_add_i32 m0, s64, 0x2000
	s_nop 0
	global_load_lds_dwordx4 v[222:223], off
	s_waitcnt vmcnt(6)
	s_waitcnt lgkmcnt(0)
	s_barrier
; #define PG8_STAGE(bufoff, gbase, voff) do { _Pragma("unroll") for (int _i = 0; _i < 2; ++_i) \
;         __builtin_amdgcn_global_load_lds((const unsigned*)((const char*)(gbase) + (voff)[_i]), (PG8_LAS unsigned*)(lds + (bufoff) + ldsw + _i * 8192), 16, 0, 0); } while (0)
; #define PG8_LDA(dst, b, h) do { _Pragma("unroll") for (int m = 0; m < 4; ++m) _Pragma("unroll") for (int k = 0; k < 2; ++k) dst[m][k] = *(const PG8_LAS bf16x8*)(lds + PG8_SA(b, h) + aoff + m * 2048 + k * 1024); } while (0)
; #define PG8_LDB(dst, b, h) do { _Pragma("unroll") for (int n = 0; n < 2; ++n) _Pragma("unroll") for (int k = 0; k < 2; ++k) dst[n][k] = *(const PG8_LAS bf16x8*)(lds + PG8_SB(b, h) + boff + n * 2048 + k * 1024); } while (0)
; #define PG8_MMA(ai, bj, At, Bt) do { __builtin_amdgcn_s_setprio(1); _Pragma("unroll") for (int m = 0; m < 4; ++m) _Pragma("unroll") for (int n = 0; n < 2; ++n) _Pragma("unroll") for (int k = 0; k < 2; ++k) \
;         acc[ai][bj][m][n] = __builtin_amdgcn_mfma_f32_16x16x32_bf16(Bt[n][k], At[m][k], acc[ai][bj][m][n], 0, 0, 0); __builtin_amdgcn_s_setprio(0); } while (0)
; #define PG8_WAIT_V(n) asm volatile("s_waitcnt vmcnt(" #n ")" ::: "memory")
; #define PG8_WAIT_L(n) asm volatile("s_waitcnt lgkmcnt(" #n ")" ::: "memory")
; #define PG8_BAR __builtin_amdgcn_s_barrier()
; #define PG8_SCHED __builtin_amdgcn_sched_barrier(0)
; template <class Epi, class Sched, bool ALIGN_EPI = false, bool SP2 = false>
; __device__ __forceinline__ void gemm_phase(PG8_LAS unsigned char* lds, const Gemm g, const Sched& S, const Epi& E) {
;     ...
;             PG8_WAIT_V(8); PG8_WAIT_L(0); PG8_BAR; PG8_MMA(1, 0, At, B0); PG8_MMA(1, 1, At, B1); PG8_BAR; PG8_SCHED;
;             PG8_LDB(B0, 1, 0); PG8_LDB(B1, 1, 1); PG8_SCHED; PG8_LDA(At, 1, 0); PG8_STAGE(PG8_SA(0, 1), a2 + hstep, voffA);
;             PG8_WAIT_V(8); PG8_WAIT_L(0); PG8_BAR; PG8_MMA(0, 0, At, B0); PG8_MMA(0, 1, At, B1); PG8_BAR; PG8_SCHED;
	s_setprio 1
	s_waitcnt lgkmcnt(0)
	v_mfma_f32_16x16x32_bf16 v[60:63], v[144:147], v[184:187], 0
	v_mfma_f32_16x16x32_bf16 v[56:59], v[160:163], v[184:187], 0
	v_mfma_f32_16x16x32_bf16 v[44:47], v[144:147], v[192:195], 0
	v_mfma_f32_16x16x32_bf16 v[40:43], v[160:163], v[192:195], 0
	v_mfma_f32_16x16x32_bf16 v[60:63], v[156:159], v[188:191], v[60:63]
	v_mfma_f32_16x16x32_bf16 v[56:59], v[164:167], v[188:191], v[56:59]
	v_mfma_f32_16x16x32_bf16 v[44:47], v[156:159], v[196:199], v[44:47]
	v_mfma_f32_16x16x32_bf16 v[40:43], v[164:167], v[196:199], v[40:43]
	v_mfma_f32_16x16x32_bf16 v[28:31], v[144:147], v[200:203], 0
	v_mfma_f32_16x16x32_bf16 v[24:27], v[160:163], v[200:203], 0
	v_mfma_f32_16x16x32_bf16 v[12:15], v[144:147], v[210:213], 0
	v_mfma_f32_16x16x32_bf16 v[8:11], v[160:163], v[210:213], 0
	v_mfma_f32_16x16x32_bf16 v[28:31], v[156:159], v[206:209], v[28:31]
	v_mfma_f32_16x16x32_bf16 v[24:27], v[164:167], v[206:209], v[24:27]
	v_lshl_add_u64 v[222:223], s[48:49], 0, v[128:129]
	s_mov_b32 m0, s33
	s_nop 0
	global_load_lds_dwordx4 v[222:223], off
	v_mfma_f32_16x16x32_bf16 v[12:15], v[156:159], v[214:217], v[12:15]
	v_mfma_f32_16x16x32_bf16 v[8:11], v[164:167], v[214:217], v[8:11]
	s_setprio 0
	s_setprio 1
	v_mfma_f32_16x16x32_bf16 v[52:55], v[168:171], v[184:187], 0
	v_mfma_f32_16x16x32_bf16 v[48:51], v[176:179], v[184:187], 0
	v_mfma_f32_16x16x32_bf16 v[36:39], v[168:171], v[192:195], 0
	v_mfma_f32_16x16x32_bf16 v[32:35], v[176:179], v[192:195], 0
	v_mfma_f32_16x16x32_bf16 v[52:55], v[172:175], v[188:191], v[52:55]
	v_mfma_f32_16x16x32_bf16 v[48:51], v[180:183], v[188:191], v[48:51]
	v_mfma_f32_16x16x32_bf16 v[36:39], v[172:175], v[196:199], v[36:39]
	v_mfma_f32_16x16x32_bf16 v[32:35], v[180:183], v[196:199], v[32:35]
	v_mfma_f32_16x16x32_bf16 v[20:23], v[168:171], v[200:203], 0
	v_mfma_f32_16x16x32_bf16 v[16:19], v[176:179], v[200:203], 0
	v_mfma_f32_16x16x32_bf16 v[4:7], v[168:171], v[210:213], 0
	v_mfma_f32_16x16x32_bf16 v[0:3], v[176:179], v[210:213], 0
	v_mfma_f32_16x16x32_bf16 v[20:23], v[172:175], v[206:209], v[20:23]
	v_mfma_f32_16x16x32_bf16 v[16:19], v[180:183], v[206:209], v[16:19]
	v_lshl_add_u64 v[224:225], s[48:49], 0, v[132:133]
	s_mov_b32 m0, s34
	s_nop 0
	global_load_lds_dwordx4 v[224:225], off
	v_mfma_f32_16x16x32_bf16 v[4:7], v[172:175], v[214:217], v[4:7]
	v_mfma_f32_16x16x32_bf16 v[0:3], v[180:183], v[214:217], v[0:3]
	s_setprio 0
	s_barrier
	s_add_i32 s62, 0, 0x18000
	v_add_u32_e32 v155, s62, v149
	s_add_i32 s63, 0, 0x1c000
	ds_read_b128 v[144:147], v155
	ds_read_b128 v[156:159], v155 offset:1024
	ds_read_b128 v[160:163], v155 offset:2048
	ds_read_b128 v[164:167], v155 offset:3072
	v_add_u32_e32 v155, s63, v149
	ds_read_b128 v[168:171], v155
	ds_read_b128 v[172:175], v155 offset:1024
	ds_read_b128 v[176:179], v155 offset:2048
	ds_read_b128 v[180:183], v155 offset:3072
	s_add_u32 s48, s48, 0x20000
	s_addc_u32 s49, s49, 0
	s_mov_b32 m0, s43
	v_lshl_add_u64 v[226:227], s[48:49], 0, v[128:129]
	ds_read_b128 v[184:187], v153 offset:32768
	ds_read_b128 v[188:191], v153 offset:33792
	ds_read_b128 v[192:195], v153 offset:34816
	ds_read_b128 v[196:199], v153 offset:35840
	ds_read_b128 v[200:203], v153 offset:36864
	ds_read_b128 v[206:209], v153 offset:37888
	ds_read_b128 v[210:213], v153 offset:38912
	ds_read_b128 v[214:217], v153 offset:39936
	global_load_lds_dwordx4 v[226:227], off
	v_lshl_add_u64 v[226:227], s[48:49], 0, v[132:133]
	s_mov_b32 m0, s50
	s_nop 0
	global_load_lds_dwordx4 v[226:227], off
	s_waitcnt vmcnt(8)
	s_waitcnt lgkmcnt(0)
	s_barrier
	s_setprio 1
	s_waitcnt lgkmcnt(0)
	v_mfma_f32_16x16x32_bf16 v[124:127], v[144:147], v[184:187], v[124:127]
	v_mfma_f32_16x16x32_bf16 v[120:123], v[160:163], v[184:187], v[120:123]
	v_mfma_f32_16x16x32_bf16 v[108:111], v[144:147], v[192:195], v[108:111]
	v_mfma_f32_16x16x32_bf16 v[104:107], v[160:163], v[192:195], v[104:107]
	v_mfma_f32_16x16x32_bf16 v[124:127], v[156:159], v[188:191], v[124:127]
	v_mfma_f32_16x16x32_bf16 v[120:123], v[164:167], v[188:191], v[120:123]
	v_mfma_f32_16x16x32_bf16 v[108:111], v[156:159], v[196:199], v[108:111]
	v_mfma_f32_16x16x32_bf16 v[104:107], v[164:167], v[196:199], v[104:107]
	v_mfma_f32_16x16x32_bf16 v[92:95], v[144:147], v[200:203], v[92:95]
	v_mfma_f32_16x16x32_bf16 v[88:91], v[160:163], v[200:203], v[88:91]
	v_mfma_f32_16x16x32_bf16 v[76:79], v[144:147], v[210:213], v[76:79]
	v_mfma_f32_16x16x32_bf16 v[72:75], v[160:163], v[210:213], v[72:75]
	v_mfma_f32_16x16x32_bf16 v[92:95], v[156:159], v[206:209], v[92:95]
	v_mfma_f32_16x16x32_bf16 v[88:91], v[164:167], v[206:209], v[88:91]
	v_mfma_f32_16x16x32_bf16 v[76:79], v[156:159], v[214:217], v[76:79]
	v_mfma_f32_16x16x32_bf16 v[72:75], v[164:167], v[214:217], v[72:75]
	s_setprio 0
	s_setprio 1
	v_mfma_f32_16x16x32_bf16 v[116:119], v[168:171], v[184:187], v[116:119]
	v_mfma_f32_16x16x32_bf16 v[112:115], v[176:179], v[184:187], v[112:115]
	v_mfma_f32_16x16x32_bf16 v[100:103], v[168:171], v[192:195], v[100:103]
	v_mfma_f32_16x16x32_bf16 v[96:99], v[176:179], v[192:195], v[96:99]
	v_mfma_f32_16x16x32_bf16 v[116:119], v[172:175], v[188:191], v[116:119]
	v_mfma_f32_16x16x32_bf16 v[112:115], v[180:183], v[188:191], v[112:115]
	v_mfma_f32_16x16x32_bf16 v[100:103], v[172:175], v[196:199], v[100:103]
	v_mfma_f32_16x16x32_bf16 v[96:99], v[180:183], v[196:199], v[96:99]
	v_mfma_f32_16x16x32_bf16 v[84:87], v[168:171], v[200:203], v[84:87]
	v_mfma_f32_16x16x32_bf16 v[80:83], v[176:179], v[200:203], v[80:83]
	v_mfma_f32_16x16x32_bf16 v[68:71], v[168:171], v[210:213], v[68:71]
	v_mfma_f32_16x16x32_bf16 v[64:67], v[176:179], v[210:213], v[64:67]
	v_mfma_f32_16x16x32_bf16 v[84:87], v[172:175], v[206:209], v[84:87]
	v_mfma_f32_16x16x32_bf16 v[80:83], v[180:183], v[206:209], v[80:83]
	v_mfma_f32_16x16x32_bf16 v[68:71], v[172:175], v[214:217], v[68:71]
	v_mfma_f32_16x16x32_bf16 v[64:67], v[180:183], v[214:217], v[64:67]
	s_setprio 0
	s_barrier
; #define PG8_STAGE(bufoff, gbase, voff) do { _Pragma("unroll") for (int _i = 0; _i < 2; ++_i) \
;         __builtin_amdgcn_global_load_lds((const unsigned*)((const char*)(gbase) + (voff)[_i]), (PG8_LAS unsigned*)(lds + (bufoff) + ldsw + _i * 8192), 16, 0, 0); } while (0)
; #define PG8_LDA(dst, b, h) do { _Pragma("unroll") for (int m = 0; m < 4; ++m) _Pragma("unroll") for (int k = 0; k < 2; ++k) dst[m][k] = *(const PG8_LAS bf16x8*)(lds + PG8_SA(b, h) + aoff + m * 2048 + k * 1024); } while (0)
; #define PG8_LDB(dst, b, h) do { _Pragma("unroll") for (int n = 0; n < 2; ++n) _Pragma("unroll") for (int k = 0; k < 2; ++k) dst[n][k] = *(const PG8_LAS bf16x8*)(lds + PG8_SB(b, h) + boff + n * 2048 + k * 1024); } while (0)
; #define PG8_MMA(ai, bj, At, Bt) do { __builtin_amdgcn_s_setprio(1); _Pragma("unroll") for (int m = 0; m < 4; ++m) _Pragma("unroll") for (int n = 0; n < 2; ++n) _Pragma("unroll") for (int k = 0; k < 2; ++k) \
;         acc[ai][bj][m][n] = __builtin_amdgcn_mfma_f32_16x16x32_bf16(Bt[n][k], At[m][k], acc[ai][bj][m][n], 0, 0, 0); __builtin_amdgcn_s_setprio(0); } while (0)
; #define PG8_WAIT_V(n) asm volatile("s_waitcnt vmcnt(" #n ")" ::: "memory")
; template <class Epi, class Sched, bool ALIGN_EPI = false, bool SP2 = false>
; __device__ __forceinline__ void gemm_phase(PG8_LAS unsigned char* lds, const Gemm g, const Sched& S, const Epi& E) {
;     ...
;             PG8_LDB(B0, 0, 0); PG8_LDB(B1, 0, 1); PG8_SCHED; PG8_LDA(At, 0, 0); PG8_STAGE(PG8_SA(1, 1), a1 + hstep, voffA);
;             PG8_WAIT_V(8); PG8_WAIT_L(0); PG8_BAR; PG8_MMA(0, 0, At, B0); PG8_MMA(0, 1, At, B1); PG8_BAR; PG8_SCHED;
;             PG8_LDA(At, 0, 1); PG8_STAGE(PG8_SB(0, 0), b2, voffB); PG8_STAGE(PG8_SB(0, 1), b2 + hstep, voffB); PG8_STAGE(PG8_SA(0, 0), a2, voffA);
;             PG8_WAIT_V(8); PG8_WAIT_L(0); PG8_BAR; PG8_MMA(1, 0, At, B0); PG8_MMA(1, 1, At, B1); PG8_BAR; PG8_SCHED;
;             PG8_LDB(B0, 1, 0); PG8_LDB(B1, 1, 1); PG8_SCHED; PG8_LDA(At, 1, 0); PG8_STAGE(PG8_SA(0, 1), a2 + hstep, voffA);
;             PG8_WAIT_V(8); PG8_WAIT_L(0); PG8_BAR; PG8_MMA(0, 0, At, B0); PG8_MMA(0, 1, At, B1); PG8_BAR; PG8_SCHED;
;             PG8_LDA(At, 1, 1); PG8_STAGE(PG8_SB(1, 0), b3, voffB); PG8_STAGE(PG8_SB(1, 1), b3 + hstep, voffB); PG8_STAGE(PG8_SA(1, 0), a3, voffA);
;             PG8_WAIT_V(8); PG8_WAIT_L(0); PG8_BAR; PG8_MMA(1, 0, At, B0); PG8_MMA(1, 1, At, B1); PG8_BAR; PG8_SCHED;
	s_add_i32 s48, s62, s15
	v_lshl_add_u64 v[218:219], v[218:219], 0, s[12:13]
	s_mov_b32 m0, s48
	ds_read_b128 v[184:187], v153 offset:49152
	ds_read_b128 v[188:191], v153 offset:50176
	ds_read_b128 v[192:195], v153 offset:51200
	ds_read_b128 v[196:199], v153 offset:52224
	ds_read_b128 v[200:203], v153 offset:53248
	ds_read_b128 v[206:209], v153 offset:54272
	ds_read_b128 v[210:213], v153 offset:55296
	ds_read_b128 v[214:217], v153 offset:56320
	global_load_lds_dwordx4 v[218:219], off
	s_add_i32 m0, s48, 0x2000
	s_add_u32 s46, s46, 0x20080
	v_lshl_add_u64 v[218:219], v[220:221], 0, s[12:13]
	s_addc_u32 s47, s47, 0
	s_add_i32 s48, s63, s15
	global_load_lds_dwordx4 v[218:219], off
	v_lshl_add_u64 v[218:219], s[46:47], 0, v[130:131]
	s_mov_b32 m0, s48
	s_nop 0
	global_load_lds_dwordx4 v[218:219], off
	v_lshl_add_u64 v[218:219], s[46:47], 0, v[134:135]
	s_add_i32 m0, s48, 0x2000
	s_nop 0
	global_load_lds_dwordx4 v[218:219], off
	s_waitcnt vmcnt(6)
	s_waitcnt lgkmcnt(0)
	s_barrier
	s_setprio 1
	s_waitcnt lgkmcnt(0)
	v_mfma_f32_16x16x32_bf16 v[60:63], v[144:147], v[184:187], v[60:63]
	v_mfma_f32_16x16x32_bf16 v[56:59], v[160:163], v[184:187], v[56:59]
	v_mfma_f32_16x16x32_bf16 v[44:47], v[144:147], v[192:195], v[44:47]
	v_mfma_f32_16x16x32_bf16 v[40:43], v[160:163], v[192:195], v[40:43]
	v_mfma_f32_16x16x32_bf16 v[60:63], v[156:159], v[188:191], v[60:63]
	v_mfma_f32_16x16x32_bf16 v[56:59], v[164:167], v[188:191], v[56:59]
	v_mfma_f32_16x16x32_bf16 v[44:47], v[156:159], v[196:199], v[44:47]
	v_mfma_f32_16x16x32_bf16 v[40:43], v[164:167], v[196:199], v[40:43]
	v_mfma_f32_16x16x32_bf16 v[28:31], v[144:147], v[200:203], v[28:31]
	v_mfma_f32_16x16x32_bf16 v[24:27], v[160:163], v[200:203], v[24:27]
	v_mfma_f32_16x16x32_bf16 v[12:15], v[144:147], v[210:213], v[12:15]
	v_mfma_f32_16x16x32_bf16 v[8:11], v[160:163], v[210:213], v[8:11]
	v_mfma_f32_16x16x32_bf16 v[28:31], v[156:159], v[206:209], v[28:31]
	v_mfma_f32_16x16x32_bf16 v[24:27], v[164:167], v[206:209], v[24:27]
	v_lshl_add_u64 v[218:219], v[222:223], 0, s[12:13]
	s_mov_b32 m0, s52
	s_nop 0
	global_load_lds_dwordx4 v[218:219], off
	v_mfma_f32_16x16x32_bf16 v[12:15], v[156:159], v[214:217], v[12:15]
	v_mfma_f32_16x16x32_bf16 v[8:11], v[164:167], v[214:217], v[8:11]
	s_setprio 0
	s_setprio 1
	v_mfma_f32_16x16x32_bf16 v[52:55], v[168:171], v[184:187], v[52:55]
	v_mfma_f32_16x16x32_bf16 v[48:51], v[176:179], v[184:187], v[48:51]
	v_mfma_f32_16x16x32_bf16 v[36:39], v[168:171], v[192:195], v[36:39]
	v_mfma_f32_16x16x32_bf16 v[32:35], v[176:179], v[192:195], v[32:35]
	v_mfma_f32_16x16x32_bf16 v[52:55], v[172:175], v[188:191], v[52:55]
	v_mfma_f32_16x16x32_bf16 v[48:51], v[180:183], v[188:191], v[48:51]
	v_mfma_f32_16x16x32_bf16 v[36:39], v[172:175], v[196:199], v[36:39]
	v_mfma_f32_16x16x32_bf16 v[32:35], v[180:183], v[196:199], v[32:35]
	v_mfma_f32_16x16x32_bf16 v[20:23], v[168:171], v[200:203], v[20:23]
	v_mfma_f32_16x16x32_bf16 v[16:19], v[176:179], v[200:203], v[16:19]
	v_mfma_f32_16x16x32_bf16 v[4:7], v[168:171], v[210:213], v[4:7]
	v_mfma_f32_16x16x32_bf16 v[0:3], v[176:179], v[210:213], v[0:3]
	v_mfma_f32_16x16x32_bf16 v[20:23], v[172:175], v[206:209], v[20:23]
	v_mfma_f32_16x16x32_bf16 v[16:19], v[180:183], v[206:209], v[16:19]
	v_lshl_add_u64 v[218:219], v[224:225], 0, s[12:13]
	s_mov_b32 m0, s53
	s_nop 0
	global_load_lds_dwordx4 v[218:219], off
	v_mfma_f32_16x16x32_bf16 v[4:7], v[172:175], v[214:217], v[4:7]
	v_mfma_f32_16x16x32_bf16 v[0:3], v[180:183], v[214:217], v[0:3]
	s_setprio 0
	s_barrier
	s_add_i32 s61, s61, 2
	s_add_u32 s44, s44, 0x100
	s_addc_u32 s45, s45, 0
	s_add_u32 s59, s59, 0x100
	s_addc_u32 s60, s60, 0
.LBB0_1816:
	ds_read_b128 v[144:147], v151
	ds_read_b128 v[156:159], v151 offset:1024
	ds_read_b128 v[160:163], v151 offset:2048
	ds_read_b128 v[164:167], v151 offset:3072
	ds_read_b128 v[168:171], v152
	ds_read_b128 v[172:175], v152 offset:1024
	ds_read_b128 v[176:179], v152 offset:2048
	ds_read_b128 v[180:183], v152 offset:3072
	s_add_u32 s46, s44, 0xfffe0080
	s_addc_u32 s47, s45, -1
	s_cmp_eq_u32 s61, 4
	s_cselect_b32 s49, s29, s47
	s_cselect_b32 s48, s41, s46
	s_cselect_b32 s47, s27, s60
	s_cselect_b32 s46, s58, s59
	v_lshl_add_u64 v[218:219], s[44:45], 0, v[136:137]
	s_add_i32 m0, s33, 0xc000
	ds_read_b128 v[184:187], v153
	ds_read_b128 v[188:191], v153 offset:1024
	ds_read_b128 v[192:195], v153 offset:2048
	ds_read_b128 v[196:199], v153 offset:3072
	ds_read_b128 v[200:203], v153 offset:4096
	ds_read_b128 v[206:209], v153 offset:5120
	ds_read_b128 v[210:213], v153 offset:6144
	ds_read_b128 v[214:217], v153 offset:7168
	global_load_lds_dwordx4 v[218:219], off
	v_lshl_add_u64 v[218:219], s[44:45], 0, v[138:139]
	s_add_i32 m0, s33, 0xe000
	s_nop 0
	global_load_lds_dwordx4 v[218:219], off
	s_waitcnt vmcnt(8)
	s_waitcnt lgkmcnt(0)
	s_barrier
; #define PG8_STAGE(bufoff, gbase, voff) do { _Pragma("unroll") for (int _i = 0; _i < 2; ++_i) \
;         __builtin_amdgcn_global_load_lds((const unsigned*)((const char*)(gbase) + (voff)[_i]), (PG8_LAS unsigned*)(lds + (bufoff) + ldsw + _i * 8192), 16, 0, 0); } while (0)
; #define PG8_LDA(dst, b, h) do { _Pragma("unroll") for (int m = 0; m < 4; ++m) _Pragma("unroll") for (int k = 0; k < 2; ++k) dst[m][k] = *(const PG8_LAS bf16x8*)(lds + PG8_SA(b, h) + aoff + m * 2048 + k * 1024); } while (0)
; #define PG8_MMA(ai, bj, At, Bt) do { __builtin_amdgcn_s_setprio(1); _Pragma("unroll") for (int m = 0; m < 4; ++m) _Pragma("unroll") for (int n = 0; n < 2; ++n) _Pragma("unroll") for (int k = 0; k < 2; ++k) \
;         acc[ai][bj][m][n] = __builtin_amdgcn_mfma_f32_16x16x32_bf16(Bt[n][k], At[m][k], acc[ai][bj][m][n], 0, 0, 0); __builtin_amdgcn_s_setprio(0); } while (0)
; #define PG8_WAIT_V(n) asm volatile("s_waitcnt vmcnt(" #n ")" ::: "memory")
; #define PG8_WAIT_L(n) asm volatile("s_waitcnt lgkmcnt(" #n ")" ::: "memory")
; #define PG8_BAR __builtin_amdgcn_s_barrier()
; #define PG8_SCHED __builtin_amdgcn_sched_barrier(0)
; template <class Epi, class Sched, bool ALIGN_EPI = false, bool SP2 = false>
; __device__ __forceinline__ void gemm_phase(PG8_LAS unsigned char* lds, const Gemm g, const Sched& S, const Epi& E) {
;     ...
;             PG8_WAIT_V(8); PG8_WAIT_L(0); PG8_BAR; PG8_MMA(0, 0, At, B0); PG8_MMA(0, 1, At, B1); PG8_BAR; PG8_SCHED;
;             PG8_LDA(At, 0, 1); PG8_STAGE(PG8_SB(0, 0), b2, voffB); PG8_STAGE(PG8_SB(0, 1), b2 + hstep, voffB); PG8_STAGE(PG8_SA(0, 0), a2, voffA);
;             PG8_WAIT_V(8); PG8_WAIT_L(0); PG8_BAR; PG8_MMA(1, 0, At, B0); PG8_MMA(1, 1, At, B1); PG8_BAR; PG8_SCHED;
	s_setprio 1
	s_waitcnt lgkmcnt(0)
	v_mfma_f32_16x16x32_bf16 v[124:127], v[144:147], v[184:187], v[124:127]
	v_mfma_f32_16x16x32_bf16 v[120:123], v[160:163], v[184:187], v[120:123]
	v_mfma_f32_16x16x32_bf16 v[108:111], v[144:147], v[192:195], v[108:111]
	v_mfma_f32_16x16x32_bf16 v[104:107], v[160:163], v[192:195], v[104:107]
	v_mfma_f32_16x16x32_bf16 v[124:127], v[156:159], v[188:191], v[124:127]
	v_mfma_f32_16x16x32_bf16 v[120:123], v[164:167], v[188:191], v[120:123]
	v_mfma_f32_16x16x32_bf16 v[108:111], v[156:159], v[196:199], v[108:111]
	v_mfma_f32_16x16x32_bf16 v[104:107], v[164:167], v[196:199], v[104:107]
	v_mfma_f32_16x16x32_bf16 v[92:95], v[144:147], v[200:203], v[92:95]
	v_mfma_f32_16x16x32_bf16 v[88:91], v[160:163], v[200:203], v[88:91]
	v_mfma_f32_16x16x32_bf16 v[76:79], v[144:147], v[210:213], v[76:79]
	v_mfma_f32_16x16x32_bf16 v[72:75], v[160:163], v[210:213], v[72:75]
	v_mfma_f32_16x16x32_bf16 v[92:95], v[156:159], v[206:209], v[92:95]
	v_mfma_f32_16x16x32_bf16 v[88:91], v[164:167], v[206:209], v[88:91]
	v_mfma_f32_16x16x32_bf16 v[76:79], v[156:159], v[214:217], v[76:79]
	v_mfma_f32_16x16x32_bf16 v[72:75], v[164:167], v[214:217], v[72:75]
	s_setprio 0
	s_setprio 1
	v_mfma_f32_16x16x32_bf16 v[116:119], v[168:171], v[184:187], v[116:119]
	v_mfma_f32_16x16x32_bf16 v[112:115], v[176:179], v[184:187], v[112:115]
	v_mfma_f32_16x16x32_bf16 v[100:103], v[168:171], v[192:195], v[100:103]
	v_mfma_f32_16x16x32_bf16 v[96:99], v[176:179], v[192:195], v[96:99]
	v_mfma_f32_16x16x32_bf16 v[116:119], v[172:175], v[188:191], v[116:119]
	v_mfma_f32_16x16x32_bf16 v[112:115], v[180:183], v[188:191], v[112:115]
	v_mfma_f32_16x16x32_bf16 v[100:103], v[172:175], v[196:199], v[100:103]
	v_mfma_f32_16x16x32_bf16 v[96:99], v[180:183], v[196:199], v[96:99]
	v_mfma_f32_16x16x32_bf16 v[84:87], v[168:171], v[200:203], v[84:87]
	v_mfma_f32_16x16x32_bf16 v[80:83], v[176:179], v[200:203], v[80:83]
	v_mfma_f32_16x16x32_bf16 v[68:71], v[168:171], v[210:213], v[68:71]
	v_mfma_f32_16x16x32_bf16 v[64:67], v[176:179], v[210:213], v[64:67]
	v_mfma_f32_16x16x32_bf16 v[84:87], v[172:175], v[206:209], v[84:87]
	v_mfma_f32_16x16x32_bf16 v[80:83], v[180:183], v[206:209], v[80:83]
	v_mfma_f32_16x16x32_bf16 v[68:71], v[172:175], v[214:217], v[68:71]
	v_mfma_f32_16x16x32_bf16 v[64:67], v[180:183], v[214:217], v[64:67]
	s_setprio 0
	s_barrier
	s_add_i32 s62, s54, s15
	v_lshl_add_u64 v[218:219], s[46:47], 0, v[130:131]
	s_mov_b32 m0, s62
	ds_read_b128 v[184:187], v153 offset:16384
	ds_read_b128 v[188:191], v153 offset:17408
	ds_read_b128 v[192:195], v153 offset:18432
	ds_read_b128 v[196:199], v153 offset:19456
	ds_read_b128 v[200:203], v153 offset:20480
	ds_read_b128 v[206:209], v153 offset:21504
	ds_read_b128 v[210:213], v153 offset:22528
	ds_read_b128 v[214:217], v153 offset:23552
	global_load_lds_dwordx4 v[218:219], off
	s_add_i32 m0, s62, 0x2000
	s_add_u32 s62, s46, 0x20000
	v_lshl_add_u64 v[220:221], s[46:47], 0, v[134:135]
	s_addc_u32 s63, s47, 0
	s_add_i32 s64, s55, s15
	global_load_lds_dwordx4 v[220:221], off
	v_lshl_add_u64 v[222:223], s[62:63], 0, v[130:131]
	s_mov_b32 m0, s64
	global_load_lds_dwordx4 v[222:223], off
	v_lshl_add_u64 v[222:223], s[62:63], 0, v[134:135]
	s_add_i32 m0, s64, 0x2000
	s_nop 0
	global_load_lds_dwordx4 v[222:223], off
	s_waitcnt vmcnt(6)
	s_waitcnt lgkmcnt(0)
	s_barrier
	s_setprio 1
	s_waitcnt lgkmcnt(0)
	v_mfma_f32_16x16x32_bf16 v[60:63], v[144:147], v[184:187], v[60:63]
	v_mfma_f32_16x16x32_bf16 v[56:59], v[160:163], v[184:187], v[56:59]
	v_mfma_f32_16x16x32_bf16 v[44:47], v[144:147], v[192:195], v[44:47]
	v_mfma_f32_16x16x32_bf16 v[40:43], v[160:163], v[192:195], v[40:43]
	v_mfma_f32_16x16x32_bf16 v[60:63], v[156:159], v[188:191], v[60:63]
	v_mfma_f32_16x16x32_bf16 v[56:59], v[164:167], v[188:191], v[56:59]
	v_mfma_f32_16x16x32_bf16 v[44:47], v[156:159], v[196:199], v[44:47]
	v_mfma_f32_16x16x32_bf16 v[40:43], v[164:167], v[196:199], v[40:43]
	v_mfma_f32_16x16x32_bf16 v[28:31], v[144:147], v[200:203], v[28:31]
	v_mfma_f32_16x16x32_bf16 v[24:27], v[160:163], v[200:203], v[24:27]
	v_mfma_f32_16x16x32_bf16 v[12:15], v[144:147], v[210:213], v[12:15]
	v_mfma_f32_16x16x32_bf16 v[8:11], v[160:163], v[210:213], v[8:11]
	v_mfma_f32_16x16x32_bf16 v[28:31], v[156:159], v[206:209], v[28:31]
	v_mfma_f32_16x16x32_bf16 v[24:27], v[164:167], v[206:209], v[24:27]
	v_lshl_add_u64 v[222:223], s[48:49], 0, v[128:129]
	s_mov_b32 m0, s33
	s_nop 0
	global_load_lds_dwordx4 v[222:223], off
	v_mfma_f32_16x16x32_bf16 v[12:15], v[156:159], v[214:217], v[12:15]
	v_mfma_f32_16x16x32_bf16 v[8:11], v[164:167], v[214:217], v[8:11]
	s_setprio 0
	s_setprio 1
	v_mfma_f32_16x16x32_bf16 v[52:55], v[168:171], v[184:187], v[52:55]
	v_mfma_f32_16x16x32_bf16 v[48:51], v[176:179], v[184:187], v[48:51]
	v_mfma_f32_16x16x32_bf16 v[36:39], v[168:171], v[192:195], v[36:39]
	v_mfma_f32_16x16x32_bf16 v[32:35], v[176:179], v[192:195], v[32:35]
	v_mfma_f32_16x16x32_bf16 v[52:55], v[172:175], v[188:191], v[52:55]
	v_mfma_f32_16x16x32_bf16 v[48:51], v[180:183], v[188:191], v[48:51]
	v_mfma_f32_16x16x32_bf16 v[36:39], v[172:175], v[196:199], v[36:39]
	v_mfma_f32_16x16x32_bf16 v[32:35], v[180:183], v[196:199], v[32:35]
	v_mfma_f32_16x16x32_bf16 v[20:23], v[168:171], v[200:203], v[20:23]
	v_mfma_f32_16x16x32_bf16 v[16:19], v[176:179], v[200:203], v[16:19]
	v_mfma_f32_16x16x32_bf16 v[4:7], v[168:171], v[210:213], v[4:7]
	v_mfma_f32_16x16x32_bf16 v[0:3], v[176:179], v[210:213], v[0:3]
	v_mfma_f32_16x16x32_bf16 v[20:23], v[172:175], v[206:209], v[20:23]
	v_mfma_f32_16x16x32_bf16 v[16:19], v[180:183], v[206:209], v[16:19]
	v_lshl_add_u64 v[224:225], s[48:49], 0, v[132:133]
	s_mov_b32 m0, s34
	s_nop 0
	global_load_lds_dwordx4 v[224:225], off
	v_mfma_f32_16x16x32_bf16 v[4:7], v[172:175], v[214:217], v[4:7]
	v_mfma_f32_16x16x32_bf16 v[0:3], v[180:183], v[214:217], v[0:3]
	s_setprio 0
	s_barrier
; #define PG8_STAGE(bufoff, gbase, voff) do { _Pragma("unroll") for (int _i = 0; _i < 2; ++_i) \
;         __builtin_amdgcn_global_load_lds((const unsigned*)((const char*)(gbase) + (voff)[_i]), (PG8_LAS unsigned*)(lds + (bufoff) + ldsw + _i * 8192), 16, 0, 0); } while (0)
; #define PG8_LDA(dst, b, h) do { _Pragma("unroll") for (int m = 0; m < 4; ++m) _Pragma("unroll") for (int k = 0; k < 2; ++k) dst[m][k] = *(const PG8_LAS bf16x8*)(lds + PG8_SA(b, h) + aoff + m * 2048 + k * 1024); } while (0)
; #define PG8_LDB(dst, b, h) do { _Pragma("unroll") for (int n = 0; n < 2; ++n) _Pragma("unroll") for (int k = 0; k < 2; ++k) dst[n][k] = *(const PG8_LAS bf16x8*)(lds + PG8_SB(b, h) + boff + n * 2048 + k * 1024); } while (0)
; #define PG8_MMA(ai, bj, At, Bt) do { __builtin_amdgcn_s_setprio(1); _Pragma("unroll") for (int m = 0; m < 4; ++m) _Pragma("unroll") for (int n = 0; n < 2; ++n) _Pragma("unroll") for (int k = 0; k < 2; ++k) \
;         acc[ai][bj][m][n] = __builtin_amdgcn_mfma_f32_16x16x32_bf16(Bt[n][k], At[m][k], acc[ai][bj][m][n], 0, 0, 0); __builtin_amdgcn_s_setprio(0); } while (0)
; #define PG8_WAIT_V(n) asm volatile("s_waitcnt vmcnt(" #n ")" ::: "memory")
; #define PG8_WAIT_L(n) asm volatile("s_waitcnt lgkmcnt(" #n ")" ::: "memory")
; #define PG8_BAR __builtin_amdgcn_s_barrier()
; #define PG8_SCHED __builtin_amdgcn_sched_barrier(0)
; template <class Epi, class Sched, bool ALIGN_EPI = false, bool SP2 = false>
; __device__ __forceinline__ void gemm_phase(PG8_LAS unsigned char* lds, const Gemm g, const Sched& S, const Epi& E) {
;     ...
;             PG8_LDB(B0, 1, 0); PG8_LDB(B1, 1, 1); PG8_SCHED; PG8_LDA(At, 1, 0); PG8_STAGE(PG8_SA(0, 1), a2 + hstep, voffA);
;             PG8_WAIT_V(8); PG8_WAIT_L(0); PG8_BAR; PG8_MMA(0, 0, At, B0); PG8_MMA(0, 1, At, B1); PG8_BAR; PG8_SCHED;
	s_add_i32 s62, 0, 0x18000
	v_add_u32_e32 v155, s62, v149
	s_add_i32 s63, 0, 0x1c000
	ds_read_b128 v[144:147], v155
	ds_read_b128 v[156:159], v155 offset:1024
	ds_read_b128 v[160:163], v155 offset:2048
	ds_read_b128 v[164:167], v155 offset:3072
	v_add_u32_e32 v155, s63, v149
	ds_read_b128 v[168:171], v155
	ds_read_b128 v[172:175], v155 offset:1024
	ds_read_b128 v[176:179], v155 offset:2048
	ds_read_b128 v[180:183], v155 offset:3072
	s_add_u32 s48, s48, 0x20000
	s_addc_u32 s49, s49, 0
	s_mov_b32 m0, s43
	v_lshl_add_u64 v[226:227], s[48:49], 0, v[128:129]
	ds_read_b128 v[184:187], v153 offset:32768
	ds_read_b128 v[188:191], v153 offset:33792
	ds_read_b128 v[192:195], v153 offset:34816
	ds_read_b128 v[196:199], v153 offset:35840
	ds_read_b128 v[200:203], v153 offset:36864
	ds_read_b128 v[206:209], v153 offset:37888
	ds_read_b128 v[210:213], v153 offset:38912
	ds_read_b128 v[214:217], v153 offset:39936
	global_load_lds_dwordx4 v[226:227], off
	v_lshl_add_u64 v[226:227], s[48:49], 0, v[132:133]
	s_mov_b32 m0, s50
	s_nop 0
	global_load_lds_dwordx4 v[226:227], off
	s_waitcnt vmcnt(8)
	s_waitcnt lgkmcnt(0)
	s_barrier
	s_setprio 1
	s_waitcnt lgkmcnt(0)
	v_mfma_f32_16x16x32_bf16 v[124:127], v[144:147], v[184:187], v[124:127]
	v_mfma_f32_16x16x32_bf16 v[120:123], v[160:163], v[184:187], v[120:123]
	v_mfma_f32_16x16x32_bf16 v[108:111], v[144:147], v[192:195], v[108:111]
	v_mfma_f32_16x16x32_bf16 v[104:107], v[160:163], v[192:195], v[104:107]
	v_mfma_f32_16x16x32_bf16 v[124:127], v[156:159], v[188:191], v[124:127]
	v_mfma_f32_16x16x32_bf16 v[120:123], v[164:167], v[188:191], v[120:123]
	v_mfma_f32_16x16x32_bf16 v[108:111], v[156:159], v[196:199], v[108:111]
	v_mfma_f32_16x16x32_bf16 v[104:107], v[164:167], v[196:199], v[104:107]
	v_mfma_f32_16x16x32_bf16 v[92:95], v[144:147], v[200:203], v[92:95]
	v_mfma_f32_16x16x32_bf16 v[88:91], v[160:163], v[200:203], v[88:91]
	v_mfma_f32_16x16x32_bf16 v[76:79], v[144:147], v[210:213], v[76:79]
	v_mfma_f32_16x16x32_bf16 v[72:75], v[160:163], v[210:213], v[72:75]
	v_mfma_f32_16x16x32_bf16 v[92:95], v[156:159], v[206:209], v[92:95]
	v_mfma_f32_16x16x32_bf16 v[88:91], v[164:167], v[206:209], v[88:91]
	v_mfma_f32_16x16x32_bf16 v[76:79], v[156:159], v[214:217], v[76:79]
	v_mfma_f32_16x16x32_bf16 v[72:75], v[164:167], v[214:217], v[72:75]
	s_setprio 0
	s_setprio 1
	v_mfma_f32_16x16x32_bf16 v[116:119], v[168:171], v[184:187], v[116:119]
	v_mfma_f32_16x16x32_bf16 v[112:115], v[176:179], v[184:187], v[112:115]
	v_mfma_f32_16x16x32_bf16 v[100:103], v[168:171], v[192:195], v[100:103]
	v_mfma_f32_16x16x32_bf16 v[96:99], v[176:179], v[192:195], v[96:99]
	v_mfma_f32_16x16x32_bf16 v[116:119], v[172:175], v[188:191], v[116:119]
	v_mfma_f32_16x16x32_bf16 v[112:115], v[180:183], v[188:191], v[112:115]
	v_mfma_f32_16x16x32_bf16 v[100:103], v[172:175], v[196:199], v[100:103]
	v_mfma_f32_16x16x32_bf16 v[96:99], v[180:183], v[196:199], v[96:99]
	v_mfma_f32_16x16x32_bf16 v[84:87], v[168:171], v[200:203], v[84:87]
	v_mfma_f32_16x16x32_bf16 v[80:83], v[176:179], v[200:203], v[80:83]
	v_mfma_f32_16x16x32_bf16 v[68:71], v[168:171], v[210:213], v[68:71]
	v_mfma_f32_16x16x32_bf16 v[64:67], v[176:179], v[210:213], v[64:67]
	v_mfma_f32_16x16x32_bf16 v[84:87], v[172:175], v[206:209], v[84:87]
	v_mfma_f32_16x16x32_bf16 v[80:83], v[180:183], v[206:209], v[80:83]
	v_mfma_f32_16x16x32_bf16 v[68:71], v[172:175], v[214:217], v[68:71]
	v_mfma_f32_16x16x32_bf16 v[64:67], v[180:183], v[214:217], v[64:67]
	s_setprio 0
	s_barrier
; #define PG8_STAGE(bufoff, gbase, voff) do { _Pragma("unroll") for (int _i = 0; _i < 2; ++_i) \
;         __builtin_amdgcn_global_load_lds((const unsigned*)((const char*)(gbase) + (voff)[_i]), (PG8_LAS unsigned*)(lds + (bufoff) + ldsw + _i * 8192), 16, 0, 0); } while (0)
; #define PG8_LDA(dst, b, h) do { _Pragma("unroll") for (int m = 0; m < 4; ++m) _Pragma("unroll") for (int k = 0; k < 2; ++k) dst[m][k] = *(const PG8_LAS bf16x8*)(lds + PG8_SA(b, h) + aoff + m * 2048 + k * 1024); } while (0)
; #define PG8_MMA(ai, bj, At, Bt) do { __builtin_amdgcn_s_setprio(1); _Pragma("unroll") for (int m = 0; m < 4; ++m) _Pragma("unroll") for (int n = 0; n < 2; ++n) _Pragma("unroll") for (int k = 0; k < 2; ++k) \
;         acc[ai][bj][m][n] = __builtin_amdgcn_mfma_f32_16x16x32_bf16(Bt[n][k], At[m][k], acc[ai][bj][m][n], 0, 0, 0); __builtin_amdgcn_s_setprio(0); } while (0)
; #define PG8_WAIT_V(n) asm volatile("s_waitcnt vmcnt(" #n ")" ::: "memory")
; #define PG8_WAIT_L(n) asm volatile("s_waitcnt lgkmcnt(" #n ")" ::: "memory")
; #define PG8_BAR __builtin_amdgcn_s_barrier()
; #define PG8_SCHED __builtin_amdgcn_sched_barrier(0)
; template <class Epi, class Sched, bool ALIGN_EPI = false, bool SP2 = false>
; __device__ __forceinline__ void gemm_phase(PG8_LAS unsigned char* lds, const Gemm g, const Sched& S, const Epi& E) {
;     ...
;             PG8_LDA(At, 1, 1); PG8_STAGE(PG8_SB(1, 0), b3, voffB); PG8_STAGE(PG8_SB(1, 1), b3 + hstep, voffB); PG8_STAGE(PG8_SA(1, 0), a3, voffA);
;             PG8_WAIT_V(8); PG8_WAIT_L(0); PG8_BAR; PG8_MMA(1, 0, At, B0); PG8_MMA(1, 1, At, B1); PG8_BAR; PG8_SCHED;
	s_add_i32 s48, s62, s15
	v_lshl_add_u64 v[218:219], v[218:219], 0, s[12:13]
	s_mov_b32 m0, s48
	ds_read_b128 v[184:187], v153 offset:49152
	ds_read_b128 v[188:191], v153 offset:50176
	ds_read_b128 v[192:195], v153 offset:51200
	ds_read_b128 v[196:199], v153 offset:52224
	ds_read_b128 v[200:203], v153 offset:53248
	ds_read_b128 v[206:209], v153 offset:54272
	ds_read_b128 v[210:213], v153 offset:55296
	ds_read_b128 v[214:217], v153 offset:56320
	global_load_lds_dwordx4 v[218:219], off
	s_add_i32 m0, s48, 0x2000
	s_add_u32 s46, s46, 0x20080
	v_lshl_add_u64 v[218:219], v[220:221], 0, s[12:13]
	s_addc_u32 s47, s47, 0
	s_add_i32 s48, s63, s15
	global_load_lds_dwordx4 v[218:219], off
	v_lshl_add_u64 v[218:219], s[46:47], 0, v[130:131]
	s_mov_b32 m0, s48
	s_nop 0
	global_load_lds_dwordx4 v[218:219], off
	v_lshl_add_u64 v[218:219], s[46:47], 0, v[134:135]
	s_add_i32 m0, s48, 0x2000
	s_nop 0
	global_load_lds_dwordx4 v[218:219], off
	s_waitcnt vmcnt(6)
	s_waitcnt lgkmcnt(0)
	s_barrier
	s_setprio 1
	s_waitcnt lgkmcnt(0)
	v_mfma_f32_16x16x32_bf16 v[60:63], v[144:147], v[184:187], v[60:63]
	v_mfma_f32_16x16x32_bf16 v[56:59], v[160:163], v[184:187], v[56:59]
	v_mfma_f32_16x16x32_bf16 v[44:47], v[144:147], v[192:195], v[44:47]
	v_mfma_f32_16x16x32_bf16 v[40:43], v[160:163], v[192:195], v[40:43]
	v_mfma_f32_16x16x32_bf16 v[60:63], v[156:159], v[188:191], v[60:63]
	v_mfma_f32_16x16x32_bf16 v[56:59], v[164:167], v[188:191], v[56:59]
	v_mfma_f32_16x16x32_bf16 v[44:47], v[156:159], v[196:199], v[44:47]
	v_mfma_f32_16x16x32_bf16 v[40:43], v[164:167], v[196:199], v[40:43]
	v_mfma_f32_16x16x32_bf16 v[28:31], v[144:147], v[200:203], v[28:31]
	v_mfma_f32_16x16x32_bf16 v[24:27], v[160:163], v[200:203], v[24:27]
	v_mfma_f32_16x16x32_bf16 v[12:15], v[144:147], v[210:213], v[12:15]
	v_mfma_f32_16x16x32_bf16 v[8:11], v[160:163], v[210:213], v[8:11]
	v_mfma_f32_16x16x32_bf16 v[28:31], v[156:159], v[206:209], v[28:31]
	v_mfma_f32_16x16x32_bf16 v[24:27], v[164:167], v[206:209], v[24:27]
	v_lshl_add_u64 v[218:219], v[222:223], 0, s[12:13]
	s_mov_b32 m0, s52
	s_nop 0
	global_load_lds_dwordx4 v[218:219], off
	v_mfma_f32_16x16x32_bf16 v[12:15], v[156:159], v[214:217], v[12:15]
	v_mfma_f32_16x16x32_bf16 v[8:11], v[164:167], v[214:217], v[8:11]
	s_setprio 0
	s_setprio 1
	v_mfma_f32_16x16x32_bf16 v[52:55], v[168:171], v[184:187], v[52:55]
	v_mfma_f32_16x16x32_bf16 v[48:51], v[176:179], v[184:187], v[48:51]
	v_mfma_f32_16x16x32_bf16 v[36:39], v[168:171], v[192:195], v[36:39]
	v_mfma_f32_16x16x32_bf16 v[32:35], v[176:179], v[192:195], v[32:35]
	v_mfma_f32_16x16x32_bf16 v[52:55], v[172:175], v[188:191], v[52:55]
	v_mfma_f32_16x16x32_bf16 v[48:51], v[180:183], v[188:191], v[48:51]
	v_mfma_f32_16x16x32_bf16 v[36:39], v[172:175], v[196:199], v[36:39]
	v_mfma_f32_16x16x32_bf16 v[32:35], v[180:183], v[196:199], v[32:35]
	v_mfma_f32_16x16x32_bf16 v[20:23], v[168:171], v[200:203], v[20:23]
	v_mfma_f32_16x16x32_bf16 v[16:19], v[176:179], v[200:203], v[16:19]
	v_mfma_f32_16x16x32_bf16 v[4:7], v[168:171], v[210:213], v[4:7]
	v_mfma_f32_16x16x32_bf16 v[0:3], v[176:179], v[210:213], v[0:3]
	v_mfma_f32_16x16x32_bf16 v[20:23], v[172:175], v[206:209], v[20:23]
	v_mfma_f32_16x16x32_bf16 v[16:19], v[180:183], v[206:209], v[16:19]
	v_lshl_add_u64 v[218:219], v[224:225], 0, s[12:13]
	s_mov_b32 m0, s53
	s_nop 0
	global_load_lds_dwordx4 v[218:219], off
	v_mfma_f32_16x16x32_bf16 v[4:7], v[172:175], v[214:217], v[4:7]
	v_mfma_f32_16x16x32_bf16 v[0:3], v[180:183], v[214:217], v[0:3]
	s_setprio 0
	s_barrier
	s_add_i32 s61, s61, 2
	s_add_u32 s44, s44, 0x100
	s_addc_u32 s45, s45, 0
	s_add_u32 s59, s59, 0x100
	s_addc_u32 s60, s60, 0
	s_cmp_gt_u32 s61, 5
	s_cbranch_scc0 .LBB0_1816
	s_and_b64 vcc, exec, s[24:25]
	s_cbranch_vccz .LBB0_1819
	s_barrier

; #define PG8_STAGE(bufoff, gbase, voff) do { _Pragma("unroll") for (int _i = 0; _i < 2; ++_i) \
;         __builtin_amdgcn_global_load_lds((const unsigned*)((const char*)(gbase) + (voff)[_i]), (PG8_LAS unsigned*)(lds + (bufoff) + ldsw + _i * 8192), 16, 0, 0); } while (0)
; #define PG8_LDA(dst, b, h) do { _Pragma("unroll") for (int m = 0; m < 4; ++m) _Pragma("unroll") for (int k = 0; k < 2; ++k) dst[m][k] = *(const PG8_LAS bf16x8*)(lds + PG8_SA(b, h) + aoff + m * 2048 + k * 1024); } while (0)
; #define PG8_LDB(dst, b, h) do { _Pragma("unroll") for (int n = 0; n < 2; ++n) _Pragma("unroll") for (int k = 0; k < 2; ++k) dst[n][k] = *(const PG8_LAS bf16x8*)(lds + PG8_SB(b, h) + boff + n * 2048 + k * 1024); } while (0)
; #define PG8_MMA(ai, bj, At, Bt) do { __builtin_amdgcn_s_setprio(1); _Pragma("unroll") for (int m = 0; m < 4; ++m) _Pragma("unroll") for (int n = 0; n < 2; ++n) _Pragma("unroll") for (int k = 0; k < 2; ++k) \
;         acc[ai][bj][m][n] = __builtin_amdgcn_mfma_f32_16x16x32_bf16(Bt[n][k], At[m][k], acc[ai][bj][m][n], 0, 0, 0); __builtin_amdgcn_s_setprio(0); } while (0)
; #define PG8_WAIT_V(n) asm volatile("s_waitcnt vmcnt(" #n ")" ::: "memory")
; #define PG8_WAIT_L(n) asm volatile("s_waitcnt lgkmcnt(" #n ")" ::: "memory")
; #define PG8_BAR __builtin_amdgcn_s_barrier()
; template <class Epi, class Sched, bool ALIGN_EPI = false, bool SP2 = false>
; __device__ __forceinline__ void gemm_phase(PG8_LAS unsigned char* lds, const Gemm g, const Sched& S, const Epi& E) {
;     ...
;         const bool has_next = S.next(ui + 1, nxt);
;         const char* nA = has_next ? (const char*)g.A + (size_t)nxt.pm * tstep : cA; const char* nB = has_next ? (const char*)g.Bt + (size_t)nxt.pn * tstep : cB;
;         for (int t = 0; t < nt; t += 2) {
;             const bool last = (t == nt - 2);
;             const char* a1 = cA + (size_t)(t + 1) * kstep;
;             const char* a2 = last ? nA : cA + (size_t)(t + 2) * kstep; const char* b2 = last ? nB : cB + (size_t)(t + 2) * kstep;
;             const char* a3 = a2 + kstep; const char* b3 = b2 + kstep;
;             if (last && has_next) S.a_ready(nxt);
;             if constexpr (SP2) {
;             PG8_LDB(B0, 0, 0); PG8_LDB(B1, 0, 1); PG8_SCHED; PG8_LDA(At, 0, 0); PG8_STAGE(PG8_SA(1, 1), a1 + hstep, voffA);
;             PG8_WAIT_V(8); PG8_WAIT_L(0); PG8_BAR; PG8_MMA(0, 0, At, B0); PG8_MMA(0, 1, At, B1); PG8_BAR; PG8_SCHED;
.LBB0_1899:
	s_ashr_i32 s25, s24, 31
	s_lshl_b64 s[26:27], s[24:25], 19
	s_add_u32 s26, s22, s26
	s_addc_u32 s27, s23, s27
	s_and_b64 s[28:29], s[4:5], exec
	s_cselect_b32 s25, s27, s39
	s_cselect_b32 s53, s26, s38
	s_ashr_i32 s13, s12, 31
	s_lshl_b64 s[28:29], s[12:13], 19
	s_add_u32 s28, s3, s28
	s_addc_u32 s29, s14, s29
	s_and_b64 s[42:43], s[4:5], exec
	s_cselect_b32 s13, s29, s41
	s_cselect_b32 s54, s28, s40
	s_add_u32 s38, s38, 0x40080
	s_addc_u32 s39, s39, 0
	s_add_u32 s55, s40, 0x100
	s_addc_u32 s56, s41, 0
	s_mov_b32 s57, -2
	ds_read_b128 v[144:147], v155
	ds_read_b128 v[148:151], v155 offset:1024
	ds_read_b128 v[160:163], v155 offset:2048
	ds_read_b128 v[164:167], v155 offset:3072
	ds_read_b128 v[168:171], v156
	ds_read_b128 v[172:175], v156 offset:1024
	ds_read_b128 v[176:179], v156 offset:2048
	ds_read_b128 v[180:183], v156 offset:3072
	s_add_u32 s40, s38, 0xfffc0080
	s_addc_u32 s41, s39, -1
	s_cmp_eq_u32 s57, 12
	s_cselect_b32 s43, s25, s41
	s_cselect_b32 s42, s53, s40
	s_cselect_b32 s41, s13, s56
	s_cselect_b32 s40, s54, s55
	v_lshl_add_u64 v[218:219], s[38:39], 0, v[136:137]
	s_add_i32 m0, s34, 0xc000
	ds_read_b128 v[184:187], v157
	ds_read_b128 v[188:191], v157 offset:1024
	ds_read_b128 v[192:195], v157 offset:2048
	ds_read_b128 v[196:199], v157 offset:3072
	ds_read_b128 v[200:203], v157 offset:4096
	ds_read_b128 v[206:209], v157 offset:5120
	ds_read_b128 v[210:213], v157 offset:6144
	ds_read_b128 v[214:217], v157 offset:7168
	global_load_lds_dwordx4 v[218:219], off
	v_lshl_add_u64 v[218:219], s[38:39], 0, v[138:139]
	s_add_i32 m0, s34, 0xe000
	s_nop 0
	global_load_lds_dwordx4 v[218:219], off
	s_waitcnt vmcnt(8)
	s_waitcnt lgkmcnt(0)
	s_barrier
	s_setprio 1
	s_waitcnt lgkmcnt(0)
	v_mfma_f32_16x16x32_bf16 v[124:127], v[144:147], v[184:187], 0
	v_mfma_f32_16x16x32_bf16 v[120:123], v[160:163], v[184:187], 0
	v_mfma_f32_16x16x32_bf16 v[108:111], v[144:147], v[192:195], 0
	v_mfma_f32_16x16x32_bf16 v[104:107], v[160:163], v[192:195], 0
	v_mfma_f32_16x16x32_bf16 v[124:127], v[148:151], v[188:191], v[124:127]
	v_mfma_f32_16x16x32_bf16 v[120:123], v[164:167], v[188:191], v[120:123]
	v_mfma_f32_16x16x32_bf16 v[108:111], v[148:151], v[196:199], v[108:111]
	v_mfma_f32_16x16x32_bf16 v[104:107], v[164:167], v[196:199], v[104:107]
	v_mfma_f32_16x16x32_bf16 v[92:95], v[144:147], v[200:203], 0
	v_mfma_f32_16x16x32_bf16 v[88:91], v[160:163], v[200:203], 0
	v_mfma_f32_16x16x32_bf16 v[76:79], v[144:147], v[210:213], 0
	v_mfma_f32_16x16x32_bf16 v[72:75], v[160:163], v[210:213], 0
	v_mfma_f32_16x16x32_bf16 v[92:95], v[148:151], v[206:209], v[92:95]
	v_mfma_f32_16x16x32_bf16 v[88:91], v[164:167], v[206:209], v[88:91]
	v_mfma_f32_16x16x32_bf16 v[76:79], v[148:151], v[214:217], v[76:79]
	v_mfma_f32_16x16x32_bf16 v[72:75], v[164:167], v[214:217], v[72:75]
	s_setprio 0
	s_setprio 1
	v_mfma_f32_16x16x32_bf16 v[116:119], v[168:171], v[184:187], 0
	v_mfma_f32_16x16x32_bf16 v[112:115], v[176:179], v[184:187], 0
	v_mfma_f32_16x16x32_bf16 v[100:103], v[168:171], v[192:195], 0
	v_mfma_f32_16x16x32_bf16 v[96:99], v[176:179], v[192:195], 0
	v_mfma_f32_16x16x32_bf16 v[116:119], v[172:175], v[188:191], v[116:119]
	v_mfma_f32_16x16x32_bf16 v[112:115], v[180:183], v[188:191], v[112:115]
	v_mfma_f32_16x16x32_bf16 v[100:103], v[172:175], v[196:199], v[100:103]
	v_mfma_f32_16x16x32_bf16 v[96:99], v[180:183], v[196:199], v[96:99]
	v_mfma_f32_16x16x32_bf16 v[84:87], v[168:171], v[200:203], 0
	v_mfma_f32_16x16x32_bf16 v[80:83], v[176:179], v[200:203], 0
	v_mfma_f32_16x16x32_bf16 v[68:71], v[168:171], v[210:213], 0
	v_mfma_f32_16x16x32_bf16 v[64:67], v[176:179], v[210:213], 0
	v_mfma_f32_16x16x32_bf16 v[84:87], v[172:175], v[206:209], v[84:87]
	v_mfma_f32_16x16x32_bf16 v[80:83], v[180:183], v[206:209], v[80:83]
	v_mfma_f32_16x16x32_bf16 v[68:71], v[172:175], v[214:217], v[68:71]
	v_mfma_f32_16x16x32_bf16 v[64:67], v[180:183], v[214:217], v[64:67]
	s_setprio 0
	s_barrier
	s_add_i32 s58, s49, s15
	v_lshl_add_u64 v[218:219], s[40:41], 0, v[132:133]
	s_mov_b32 m0, s58
	ds_read_b128 v[184:187], v157 offset:16384
	ds_read_b128 v[188:191], v157 offset:17408
	ds_read_b128 v[192:195], v157 offset:18432
	ds_read_b128 v[196:199], v157 offset:19456
	ds_read_b128 v[200:203], v157 offset:20480
	ds_read_b128 v[206:209], v157 offset:21504
	ds_read_b128 v[210:213], v157 offset:22528
	ds_read_b128 v[214:217], v157 offset:23552
	global_load_lds_dwordx4 v[218:219], off
	s_add_i32 m0, s58, 0x2000
	s_add_u32 s58, s40, 0x40000
	v_lshl_add_u64 v[220:221], s[40:41], 0, v[128:129]
	s_addc_u32 s59, s41, 0
	s_add_i32 s60, s50, s15
	global_load_lds_dwordx4 v[220:221], off
	v_lshl_add_u64 v[222:223], s[58:59], 0, v[132:133]
	s_mov_b32 m0, s60
	global_load_lds_dwordx4 v[222:223], off
	v_lshl_add_u64 v[222:223], s[58:59], 0, v[128:129]
	s_add_i32 m0, s60, 0x2000
	s_nop 0
	global_load_lds_dwordx4 v[222:223], off
	s_waitcnt vmcnt(6)
	s_waitcnt lgkmcnt(0)
	s_barrier
; #define PG8_STAGE(bufoff, gbase, voff) do { _Pragma("unroll") for (int _i = 0; _i < 2; ++_i) \
;         __builtin_amdgcn_global_load_lds((const unsigned*)((const char*)(gbase) + (voff)[_i]), (PG8_LAS unsigned*)(lds + (bufoff) + ldsw + _i * 8192), 16, 0, 0); } while (0)
; #define PG8_LDA(dst, b, h) do { _Pragma("unroll") for (int m = 0; m < 4; ++m) _Pragma("unroll") for (int k = 0; k < 2; ++k) dst[m][k] = *(const PG8_LAS bf16x8*)(lds + PG8_SA(b, h) + aoff + m * 2048 + k * 1024); } while (0)
; #define PG8_LDB(dst, b, h) do { _Pragma("unroll") for (int n = 0; n < 2; ++n) _Pragma("unroll") for (int k = 0; k < 2; ++k) dst[n][k] = *(const PG8_LAS bf16x8*)(lds + PG8_SB(b, h) + boff + n * 2048 + k * 1024); } while (0)
; #define PG8_MMA(ai, bj, At, Bt) do { __builtin_amdgcn_s_setprio(1); _Pragma("unroll") for (int m = 0; m < 4; ++m) _Pragma("unroll") for (int n = 0; n < 2; ++n) _Pragma("unroll") for (int k = 0; k < 2; ++k) \
;         acc[ai][bj][m][n] = __builtin_amdgcn_mfma_f32_16x16x32_bf16(Bt[n][k], At[m][k], acc[ai][bj][m][n], 0, 0, 0); __builtin_amdgcn_s_setprio(0); } while (0)
; #define PG8_WAIT_V(n) asm volatile("s_waitcnt vmcnt(" #n ")" ::: "memory")
; #define PG8_WAIT_L(n) asm volatile("s_waitcnt lgkmcnt(" #n ")" ::: "memory")
; #define PG8_BAR __builtin_amdgcn_s_barrier()
; #define PG8_SCHED __builtin_amdgcn_sched_barrier(0)
; template <class Epi, class Sched, bool ALIGN_EPI = false, bool SP2 = false>
; __device__ __forceinline__ void gemm_phase(PG8_LAS unsigned char* lds, const Gemm g, const Sched& S, const Epi& E) {
;     ...
;             PG8_WAIT_V(8); PG8_WAIT_L(0); PG8_BAR; PG8_MMA(1, 0, At, B0); PG8_MMA(1, 1, At, B1); PG8_BAR; PG8_SCHED;
;             PG8_LDB(B0, 1, 0); PG8_LDB(B1, 1, 1); PG8_SCHED; PG8_LDA(At, 1, 0); PG8_STAGE(PG8_SA(0, 1), a2 + hstep, voffA);
;             PG8_WAIT_V(8); PG8_WAIT_L(0); PG8_BAR; PG8_MMA(0, 0, At, B0); PG8_MMA(0, 1, At, B1); PG8_BAR; PG8_SCHED;
	s_setprio 1
	s_waitcnt lgkmcnt(0)
	v_mfma_f32_16x16x32_bf16 v[60:63], v[144:147], v[184:187], 0
	v_mfma_f32_16x16x32_bf16 v[56:59], v[160:163], v[184:187], 0
	v_mfma_f32_16x16x32_bf16 v[44:47], v[144:147], v[192:195], 0
	v_mfma_f32_16x16x32_bf16 v[40:43], v[160:163], v[192:195], 0
	v_mfma_f32_16x16x32_bf16 v[60:63], v[148:151], v[188:191], v[60:63]
	v_mfma_f32_16x16x32_bf16 v[56:59], v[164:167], v[188:191], v[56:59]
	v_mfma_f32_16x16x32_bf16 v[44:47], v[148:151], v[196:199], v[44:47]
	v_mfma_f32_16x16x32_bf16 v[40:43], v[164:167], v[196:199], v[40:43]
	v_mfma_f32_16x16x32_bf16 v[28:31], v[144:147], v[200:203], 0
	v_mfma_f32_16x16x32_bf16 v[24:27], v[160:163], v[200:203], 0
	v_mfma_f32_16x16x32_bf16 v[12:15], v[144:147], v[210:213], 0
	v_mfma_f32_16x16x32_bf16 v[8:11], v[160:163], v[210:213], 0
	v_mfma_f32_16x16x32_bf16 v[28:31], v[148:151], v[206:209], v[28:31]
	v_mfma_f32_16x16x32_bf16 v[24:27], v[164:167], v[206:209], v[24:27]
	v_lshl_add_u64 v[222:223], s[42:43], 0, v[134:135]
	s_mov_b32 m0, s34
	s_nop 0
	global_load_lds_dwordx4 v[222:223], off
	v_mfma_f32_16x16x32_bf16 v[12:15], v[148:151], v[214:217], v[12:15]
	v_mfma_f32_16x16x32_bf16 v[8:11], v[164:167], v[214:217], v[8:11]
	s_setprio 0
	s_setprio 1
	v_mfma_f32_16x16x32_bf16 v[52:55], v[168:171], v[184:187], 0
	v_mfma_f32_16x16x32_bf16 v[48:51], v[176:179], v[184:187], 0
	v_mfma_f32_16x16x32_bf16 v[36:39], v[168:171], v[192:195], 0
	v_mfma_f32_16x16x32_bf16 v[32:35], v[176:179], v[192:195], 0
	v_mfma_f32_16x16x32_bf16 v[52:55], v[172:175], v[188:191], v[52:55]
	v_mfma_f32_16x16x32_bf16 v[48:51], v[180:183], v[188:191], v[48:51]
	v_mfma_f32_16x16x32_bf16 v[36:39], v[172:175], v[196:199], v[36:39]
	v_mfma_f32_16x16x32_bf16 v[32:35], v[180:183], v[196:199], v[32:35]
	v_mfma_f32_16x16x32_bf16 v[20:23], v[168:171], v[200:203], 0
	v_mfma_f32_16x16x32_bf16 v[16:19], v[176:179], v[200:203], 0
	v_mfma_f32_16x16x32_bf16 v[4:7], v[168:171], v[210:213], 0
	v_mfma_f32_16x16x32_bf16 v[0:3], v[176:179], v[210:213], 0
	v_mfma_f32_16x16x32_bf16 v[20:23], v[172:175], v[206:209], v[20:23]
	v_mfma_f32_16x16x32_bf16 v[16:19], v[180:183], v[206:209], v[16:19]
	v_lshl_add_u64 v[224:225], s[42:43], 0, v[130:131]
	s_mov_b32 m0, s37
	s_nop 0
	global_load_lds_dwordx4 v[224:225], off
	v_mfma_f32_16x16x32_bf16 v[4:7], v[172:175], v[214:217], v[4:7]
	v_mfma_f32_16x16x32_bf16 v[0:3], v[180:183], v[214:217], v[0:3]
	s_setprio 0
	s_barrier
	s_add_i32 s58, 0, 0x18000
	v_add_u32_e32 v159, s58, v153
	s_add_i32 s59, 0, 0x1c000
	ds_read_b128 v[144:147], v159
	ds_read_b128 v[148:151], v159 offset:1024
	ds_read_b128 v[160:163], v159 offset:2048
	ds_read_b128 v[164:167], v159 offset:3072
	v_add_u32_e32 v159, s59, v153
	ds_read_b128 v[168:171], v159
	ds_read_b128 v[172:175], v159 offset:1024
	ds_read_b128 v[176:179], v159 offset:2048
	ds_read_b128 v[180:183], v159 offset:3072
	s_add_u32 s42, s42, 0x40000
	s_addc_u32 s43, s43, 0
	s_mov_b32 m0, s44
	v_lshl_add_u64 v[226:227], s[42:43], 0, v[134:135]
	ds_read_b128 v[184:187], v157 offset:32768
	ds_read_b128 v[188:191], v157 offset:33792
	ds_read_b128 v[192:195], v157 offset:34816
	ds_read_b128 v[196:199], v157 offset:35840
	ds_read_b128 v[200:203], v157 offset:36864
	ds_read_b128 v[206:209], v157 offset:37888
	ds_read_b128 v[210:213], v157 offset:38912
	ds_read_b128 v[214:217], v157 offset:39936
	global_load_lds_dwordx4 v[226:227], off
	v_lshl_add_u64 v[226:227], s[42:43], 0, v[130:131]
	s_mov_b32 m0, s45
	s_nop 0
	global_load_lds_dwordx4 v[226:227], off
	s_waitcnt vmcnt(8)
	s_waitcnt lgkmcnt(0)
	s_barrier
	s_setprio 1
	s_waitcnt lgkmcnt(0)
	v_mfma_f32_16x16x32_bf16 v[124:127], v[144:147], v[184:187], v[124:127]
	v_mfma_f32_16x16x32_bf16 v[120:123], v[160:163], v[184:187], v[120:123]
	v_mfma_f32_16x16x32_bf16 v[108:111], v[144:147], v[192:195], v[108:111]
	v_mfma_f32_16x16x32_bf16 v[104:107], v[160:163], v[192:195], v[104:107]
	v_mfma_f32_16x16x32_bf16 v[124:127], v[148:151], v[188:191], v[124:127]
	v_mfma_f32_16x16x32_bf16 v[120:123], v[164:167], v[188:191], v[120:123]
	v_mfma_f32_16x16x32_bf16 v[108:111], v[148:151], v[196:199], v[108:111]
	v_mfma_f32_16x16x32_bf16 v[104:107], v[164:167], v[196:199], v[104:107]
	v_mfma_f32_16x16x32_bf16 v[92:95], v[144:147], v[200:203], v[92:95]
	v_mfma_f32_16x16x32_bf16 v[88:91], v[160:163], v[200:203], v[88:91]
	v_mfma_f32_16x16x32_bf16 v[76:79], v[144:147], v[210:213], v[76:79]
	v_mfma_f32_16x16x32_bf16 v[72:75], v[160:163], v[210:213], v[72:75]
	v_mfma_f32_16x16x32_bf16 v[92:95], v[148:151], v[206:209], v[92:95]
	v_mfma_f32_16x16x32_bf16 v[88:91], v[164:167], v[206:209], v[88:91]
	v_mfma_f32_16x16x32_bf16 v[76:79], v[148:151], v[214:217], v[76:79]
	v_mfma_f32_16x16x32_bf16 v[72:75], v[164:167], v[214:217], v[72:75]
	s_setprio 0
	s_setprio 1
	v_mfma_f32_16x16x32_bf16 v[116:119], v[168:171], v[184:187], v[116:119]
	v_mfma_f32_16x16x32_bf16 v[112:115], v[176:179], v[184:187], v[112:115]
	v_mfma_f32_16x16x32_bf16 v[100:103], v[168:171], v[192:195], v[100:103]
	v_mfma_f32_16x16x32_bf16 v[96:99], v[176:179], v[192:195], v[96:99]
	v_mfma_f32_16x16x32_bf16 v[116:119], v[172:175], v[188:191], v[116:119]
	v_mfma_f32_16x16x32_bf16 v[112:115], v[180:183], v[188:191], v[112:115]
	v_mfma_f32_16x16x32_bf16 v[100:103], v[172:175], v[196:199], v[100:103]
	v_mfma_f32_16x16x32_bf16 v[96:99], v[180:183], v[196:199], v[96:99]
	v_mfma_f32_16x16x32_bf16 v[84:87], v[168:171], v[200:203], v[84:87]
	v_mfma_f32_16x16x32_bf16 v[80:83], v[176:179], v[200:203], v[80:83]
	v_mfma_f32_16x16x32_bf16 v[68:71], v[168:171], v[210:213], v[68:71]
	v_mfma_f32_16x16x32_bf16 v[64:67], v[176:179], v[210:213], v[64:67]
	v_mfma_f32_16x16x32_bf16 v[84:87], v[172:175], v[206:209], v[84:87]
	v_mfma_f32_16x16x32_bf16 v[80:83], v[180:183], v[206:209], v[80:83]
	v_mfma_f32_16x16x32_bf16 v[68:71], v[172:175], v[214:217], v[68:71]
	v_mfma_f32_16x16x32_bf16 v[64:67], v[180:183], v[214:217], v[64:67]
	s_setprio 0
	s_barrier
; #define PG8_STAGE(bufoff, gbase, voff) do { _Pragma("unroll") for (int _i = 0; _i < 2; ++_i) \
;         __builtin_amdgcn_global_load_lds((const unsigned*)((const char*)(gbase) + (voff)[_i]), (PG8_LAS unsigned*)(lds + (bufoff) + ldsw + _i * 8192), 16, 0, 0); } while (0)
; #define PG8_LDA(dst, b, h) do { _Pragma("unroll") for (int m = 0; m < 4; ++m) _Pragma("unroll") for (int k = 0; k < 2; ++k) dst[m][k] = *(const PG8_LAS bf16x8*)(lds + PG8_SA(b, h) + aoff + m * 2048 + k * 1024); } while (0)
; #define PG8_LDB(dst, b, h) do { _Pragma("unroll") for (int n = 0; n < 2; ++n) _Pragma("unroll") for (int k = 0; k < 2; ++k) dst[n][k] = *(const PG8_LAS bf16x8*)(lds + PG8_SB(b, h) + boff + n * 2048 + k * 1024); } while (0)
; #define PG8_MMA(ai, bj, At, Bt) do { __builtin_amdgcn_s_setprio(1); _Pragma("unroll") for (int m = 0; m < 4; ++m) _Pragma("unroll") for (int n = 0; n < 2; ++n) _Pragma("unroll") for (int k = 0; k < 2; ++k) \
;         acc[ai][bj][m][n] = __builtin_amdgcn_mfma_f32_16x16x32_bf16(Bt[n][k], At[m][k], acc[ai][bj][m][n], 0, 0, 0); __builtin_amdgcn_s_setprio(0); } while (0)
; #define PG8_WAIT_V(n) asm volatile("s_waitcnt vmcnt(" #n ")" ::: "memory")
; #define PG8_WAIT_L(n) asm volatile("s_waitcnt lgkmcnt(" #n ")" ::: "memory")
; #define PG8_BAR __builtin_amdgcn_s_barrier()
; #define PG8_SCHED __builtin_amdgcn_sched_barrier(0)
; template <class Epi, class Sched, bool ALIGN_EPI = false, bool SP2 = false>
; __device__ __forceinline__ void gemm_phase(PG8_LAS unsigned char* lds, const Gemm g, const Sched& S, const Epi& E) {
;     ...
;             PG8_LDB(B0, 0, 0); PG8_LDB(B1, 0, 1); PG8_SCHED; PG8_LDA(At, 0, 0); PG8_STAGE(PG8_SA(1, 1), a1 + hstep, voffA);
;             PG8_WAIT_V(8); PG8_WAIT_L(0); PG8_BAR; PG8_MMA(0, 0, At, B0); PG8_MMA(0, 1, At, B1); PG8_BAR; PG8_SCHED;
;     ...
;             PG8_LDA(At, 1, 1); PG8_STAGE(PG8_SB(1, 0), b3, voffB); PG8_STAGE(PG8_SB(1, 1), b3 + hstep, voffB); PG8_STAGE(PG8_SA(1, 0), a3, voffA);
;             PG8_WAIT_V(8); PG8_WAIT_L(0); PG8_BAR; PG8_MMA(1, 0, At, B0); PG8_MMA(1, 1, At, B1); PG8_BAR; PG8_SCHED;
	s_add_i32 s42, s58, s15
	v_lshl_add_u64 v[218:219], v[218:219], 0, s[8:9]
	s_mov_b32 m0, s42
	ds_read_b128 v[184:187], v157 offset:49152
	ds_read_b128 v[188:191], v157 offset:50176
	ds_read_b128 v[192:195], v157 offset:51200
	ds_read_b128 v[196:199], v157 offset:52224
	ds_read_b128 v[200:203], v157 offset:53248
	ds_read_b128 v[206:209], v157 offset:54272
	ds_read_b128 v[210:213], v157 offset:55296
	ds_read_b128 v[214:217], v157 offset:56320
	global_load_lds_dwordx4 v[218:219], off
	s_add_i32 m0, s42, 0x2000
	s_add_u32 s40, s40, 0x40080
	v_lshl_add_u64 v[218:219], v[220:221], 0, s[8:9]
	s_addc_u32 s41, s41, 0
	s_add_i32 s42, s59, s15
	global_load_lds_dwordx4 v[218:219], off
	v_lshl_add_u64 v[218:219], s[40:41], 0, v[132:133]
	s_mov_b32 m0, s42
	s_nop 0
	global_load_lds_dwordx4 v[218:219], off
	v_lshl_add_u64 v[218:219], s[40:41], 0, v[128:129]
	s_add_i32 m0, s42, 0x2000
	s_nop 0
	global_load_lds_dwordx4 v[218:219], off
	s_waitcnt vmcnt(6)
	s_waitcnt lgkmcnt(0)
	s_barrier
	s_setprio 1
	s_waitcnt lgkmcnt(0)
	v_mfma_f32_16x16x32_bf16 v[60:63], v[144:147], v[184:187], v[60:63]
	v_mfma_f32_16x16x32_bf16 v[56:59], v[160:163], v[184:187], v[56:59]
	v_mfma_f32_16x16x32_bf16 v[44:47], v[144:147], v[192:195], v[44:47]
	v_mfma_f32_16x16x32_bf16 v[40:43], v[160:163], v[192:195], v[40:43]
	v_mfma_f32_16x16x32_bf16 v[60:63], v[148:151], v[188:191], v[60:63]
	v_mfma_f32_16x16x32_bf16 v[56:59], v[164:167], v[188:191], v[56:59]
	v_mfma_f32_16x16x32_bf16 v[44:47], v[148:151], v[196:199], v[44:47]
	v_mfma_f32_16x16x32_bf16 v[40:43], v[164:167], v[196:199], v[40:43]
	v_mfma_f32_16x16x32_bf16 v[28:31], v[144:147], v[200:203], v[28:31]
	v_mfma_f32_16x16x32_bf16 v[24:27], v[160:163], v[200:203], v[24:27]
	v_mfma_f32_16x16x32_bf16 v[12:15], v[144:147], v[210:213], v[12:15]
	v_mfma_f32_16x16x32_bf16 v[8:11], v[160:163], v[210:213], v[8:11]
	v_mfma_f32_16x16x32_bf16 v[28:31], v[148:151], v[206:209], v[28:31]
	v_mfma_f32_16x16x32_bf16 v[24:27], v[164:167], v[206:209], v[24:27]
	v_lshl_add_u64 v[218:219], v[222:223], 0, s[8:9]
	s_mov_b32 m0, s47
	s_nop 0
	global_load_lds_dwordx4 v[218:219], off
	v_mfma_f32_16x16x32_bf16 v[12:15], v[148:151], v[214:217], v[12:15]
	v_mfma_f32_16x16x32_bf16 v[8:11], v[164:167], v[214:217], v[8:11]
	s_setprio 0
	s_setprio 1
	v_mfma_f32_16x16x32_bf16 v[52:55], v[168:171], v[184:187], v[52:55]
	v_mfma_f32_16x16x32_bf16 v[48:51], v[176:179], v[184:187], v[48:51]
	v_mfma_f32_16x16x32_bf16 v[36:39], v[168:171], v[192:195], v[36:39]
	v_mfma_f32_16x16x32_bf16 v[32:35], v[176:179], v[192:195], v[32:35]
	v_mfma_f32_16x16x32_bf16 v[52:55], v[172:175], v[188:191], v[52:55]
	v_mfma_f32_16x16x32_bf16 v[48:51], v[180:183], v[188:191], v[48:51]
	v_mfma_f32_16x16x32_bf16 v[36:39], v[172:175], v[196:199], v[36:39]
	v_mfma_f32_16x16x32_bf16 v[32:35], v[180:183], v[196:199], v[32:35]
	v_mfma_f32_16x16x32_bf16 v[20:23], v[168:171], v[200:203], v[20:23]
	v_mfma_f32_16x16x32_bf16 v[16:19], v[176:179], v[200:203], v[16:19]
	v_mfma_f32_16x16x32_bf16 v[4:7], v[168:171], v[210:213], v[4:7]
	v_mfma_f32_16x16x32_bf16 v[0:3], v[176:179], v[210:213], v[0:3]
	v_mfma_f32_16x16x32_bf16 v[20:23], v[172:175], v[206:209], v[20:23]
	v_mfma_f32_16x16x32_bf16 v[16:19], v[180:183], v[206:209], v[16:19]
	v_lshl_add_u64 v[218:219], v[224:225], 0, s[8:9]
	s_mov_b32 m0, s48
	s_nop 0
	global_load_lds_dwordx4 v[218:219], off
	v_mfma_f32_16x16x32_bf16 v[4:7], v[172:175], v[214:217], v[4:7]
	v_mfma_f32_16x16x32_bf16 v[0:3], v[180:183], v[214:217], v[0:3]
	s_setprio 0
	s_barrier
	s_add_i32 s57, s57, 2
	s_add_u32 s38, s38, 0x100
	s_addc_u32 s39, s39, 0
	s_add_u32 s55, s55, 0x100
	s_addc_u32 s56, s56, 0
.LBB0_1900:
	ds_read_b128 v[144:147], v155
	ds_read_b128 v[148:151], v155 offset:1024
	ds_read_b128 v[160:163], v155 offset:2048
	ds_read_b128 v[164:167], v155 offset:3072
	ds_read_b128 v[168:171], v156
	ds_read_b128 v[172:175], v156 offset:1024
	ds_read_b128 v[176:179], v156 offset:2048
	ds_read_b128 v[180:183], v156 offset:3072
	s_add_u32 s40, s38, 0xfffc0080
	s_addc_u32 s41, s39, -1
	s_cmp_eq_u32 s57, 12
	s_cselect_b32 s43, s25, s41
	s_cselect_b32 s42, s53, s40
	s_cselect_b32 s41, s13, s56
	s_cselect_b32 s40, s54, s55
	v_lshl_add_u64 v[218:219], s[38:39], 0, v[136:137]
	s_add_i32 m0, s34, 0xc000
	ds_read_b128 v[184:187], v157
	ds_read_b128 v[188:191], v157 offset:1024
	ds_read_b128 v[192:195], v157 offset:2048
	ds_read_b128 v[196:199], v157 offset:3072
	ds_read_b128 v[200:203], v157 offset:4096
	ds_read_b128 v[206:209], v157 offset:5120
	ds_read_b128 v[210:213], v157 offset:6144
	ds_read_b128 v[214:217], v157 offset:7168
	global_load_lds_dwordx4 v[218:219], off
	v_lshl_add_u64 v[218:219], s[38:39], 0, v[138:139]
	s_add_i32 m0, s34, 0xe000
	s_nop 0
	global_load_lds_dwordx4 v[218:219], off
	s_waitcnt vmcnt(8)
	s_waitcnt lgkmcnt(0)
	s_barrier
; #define PG8_STAGE(bufoff, gbase, voff) do { _Pragma("unroll") for (int _i = 0; _i < 2; ++_i) \
;         __builtin_amdgcn_global_load_lds((const unsigned*)((const char*)(gbase) + (voff)[_i]), (PG8_LAS unsigned*)(lds + (bufoff) + ldsw + _i * 8192), 16, 0, 0); } while (0)
; #define PG8_LDA(dst, b, h) do { _Pragma("unroll") for (int m = 0; m < 4; ++m) _Pragma("unroll") for (int k = 0; k < 2; ++k) dst[m][k] = *(const PG8_LAS bf16x8*)(lds + PG8_SA(b, h) + aoff + m * 2048 + k * 1024); } while (0)
; #define PG8_MMA(ai, bj, At, Bt) do { __builtin_amdgcn_s_setprio(1); _Pragma("unroll") for (int m = 0; m < 4; ++m) _Pragma("unroll") for (int n = 0; n < 2; ++n) _Pragma("unroll") for (int k = 0; k < 2; ++k) \
;         acc[ai][bj][m][n] = __builtin_amdgcn_mfma_f32_16x16x32_bf16(Bt[n][k], At[m][k], acc[ai][bj][m][n], 0, 0, 0); __builtin_amdgcn_s_setprio(0); } while (0)
; #define PG8_WAIT_V(n) asm volatile("s_waitcnt vmcnt(" #n ")" ::: "memory")
; #define PG8_WAIT_L(n) asm volatile("s_waitcnt lgkmcnt(" #n ")" ::: "memory")
; #define PG8_BAR __builtin_amdgcn_s_barrier()
; #define PG8_SCHED __builtin_amdgcn_sched_barrier(0)
; template <class Epi, class Sched, bool ALIGN_EPI = false, bool SP2 = false>
; __device__ __forceinline__ void gemm_phase(PG8_LAS unsigned char* lds, const Gemm g, const Sched& S, const Epi& E) {
;     ...
;             PG8_WAIT_V(8); PG8_WAIT_L(0); PG8_BAR; PG8_MMA(0, 0, At, B0); PG8_MMA(0, 1, At, B1); PG8_BAR; PG8_SCHED;
;             PG8_LDA(At, 0, 1); PG8_STAGE(PG8_SB(0, 0), b2, voffB); PG8_STAGE(PG8_SB(0, 1), b2 + hstep, voffB); PG8_STAGE(PG8_SA(0, 0), a2, voffA);
;             PG8_WAIT_V(8); PG8_WAIT_L(0); PG8_BAR; PG8_MMA(1, 0, At, B0); PG8_MMA(1, 1, At, B1); PG8_BAR; PG8_SCHED;
	s_setprio 1
	s_waitcnt lgkmcnt(0)
	v_mfma_f32_16x16x32_bf16 v[124:127], v[144:147], v[184:187], v[124:127]
	v_mfma_f32_16x16x32_bf16 v[120:123], v[160:163], v[184:187], v[120:123]
	v_mfma_f32_16x16x32_bf16 v[108:111], v[144:147], v[192:195], v[108:111]
	v_mfma_f32_16x16x32_bf16 v[104:107], v[160:163], v[192:195], v[104:107]
	v_mfma_f32_16x16x32_bf16 v[124:127], v[148:151], v[188:191], v[124:127]
	v_mfma_f32_16x16x32_bf16 v[120:123], v[164:167], v[188:191], v[120:123]
	v_mfma_f32_16x16x32_bf16 v[108:111], v[148:151], v[196:199], v[108:111]
	v_mfma_f32_16x16x32_bf16 v[104:107], v[164:167], v[196:199], v[104:107]
	v_mfma_f32_16x16x32_bf16 v[92:95], v[144:147], v[200:203], v[92:95]
	v_mfma_f32_16x16x32_bf16 v[88:91], v[160:163], v[200:203], v[88:91]
	v_mfma_f32_16x16x32_bf16 v[76:79], v[144:147], v[210:213], v[76:79]
	v_mfma_f32_16x16x32_bf16 v[72:75], v[160:163], v[210:213], v[72:75]
	v_mfma_f32_16x16x32_bf16 v[92:95], v[148:151], v[206:209], v[92:95]
	v_mfma_f32_16x16x32_bf16 v[88:91], v[164:167], v[206:209], v[88:91]
	v_mfma_f32_16x16x32_bf16 v[76:79], v[148:151], v[214:217], v[76:79]
	v_mfma_f32_16x16x32_bf16 v[72:75], v[164:167], v[214:217], v[72:75]
	s_setprio 0
	s_setprio 1
	v_mfma_f32_16x16x32_bf16 v[116:119], v[168:171], v[184:187], v[116:119]
	v_mfma_f32_16x16x32_bf16 v[112:115], v[176:179], v[184:187], v[112:115]
	v_mfma_f32_16x16x32_bf16 v[100:103], v[168:171], v[192:195], v[100:103]
	v_mfma_f32_16x16x32_bf16 v[96:99], v[176:179], v[192:195], v[96:99]
	v_mfma_f32_16x16x32_bf16 v[116:119], v[172:175], v[188:191], v[116:119]
	v_mfma_f32_16x16x32_bf16 v[112:115], v[180:183], v[188:191], v[112:115]
	v_mfma_f32_16x16x32_bf16 v[100:103], v[172:175], v[196:199], v[100:103]
	v_mfma_f32_16x16x32_bf16 v[96:99], v[180:183], v[196:199], v[96:99]
	v_mfma_f32_16x16x32_bf16 v[84:87], v[168:171], v[200:203], v[84:87]
	v_mfma_f32_16x16x32_bf16 v[80:83], v[176:179], v[200:203], v[80:83]
	v_mfma_f32_16x16x32_bf16 v[68:71], v[168:171], v[210:213], v[68:71]
	v_mfma_f32_16x16x32_bf16 v[64:67], v[176:179], v[210:213], v[64:67]
	v_mfma_f32_16x16x32_bf16 v[84:87], v[172:175], v[206:209], v[84:87]
	v_mfma_f32_16x16x32_bf16 v[80:83], v[180:183], v[206:209], v[80:83]
	v_mfma_f32_16x16x32_bf16 v[68:71], v[172:175], v[214:217], v[68:71]
	v_mfma_f32_16x16x32_bf16 v[64:67], v[180:183], v[214:217], v[64:67]
	s_setprio 0
	s_barrier
	s_add_i32 s58, s49, s15
	v_lshl_add_u64 v[218:219], s[40:41], 0, v[132:133]
	s_mov_b32 m0, s58
	ds_read_b128 v[184:187], v157 offset:16384
	ds_read_b128 v[188:191], v157 offset:17408
	ds_read_b128 v[192:195], v157 offset:18432
	ds_read_b128 v[196:199], v157 offset:19456
	ds_read_b128 v[200:203], v157 offset:20480
	ds_read_b128 v[206:209], v157 offset:21504
	ds_read_b128 v[210:213], v157 offset:22528
	ds_read_b128 v[214:217], v157 offset:23552
	global_load_lds_dwordx4 v[218:219], off
	s_add_i32 m0, s58, 0x2000
	s_add_u32 s58, s40, 0x40000
	v_lshl_add_u64 v[220:221], s[40:41], 0, v[128:129]
	s_addc_u32 s59, s41, 0
	s_add_i32 s60, s50, s15
	global_load_lds_dwordx4 v[220:221], off
	v_lshl_add_u64 v[222:223], s[58:59], 0, v[132:133]
	s_mov_b32 m0, s60
	global_load_lds_dwordx4 v[222:223], off
	v_lshl_add_u64 v[222:223], s[58:59], 0, v[128:129]
	s_add_i32 m0, s60, 0x2000
	s_nop 0
	global_load_lds_dwordx4 v[222:223], off
	s_waitcnt vmcnt(6)
	s_waitcnt lgkmcnt(0)
	s_barrier
	s_setprio 1
	s_waitcnt lgkmcnt(0)
	v_mfma_f32_16x16x32_bf16 v[60:63], v[144:147], v[184:187], v[60:63]
	v_mfma_f32_16x16x32_bf16 v[56:59], v[160:163], v[184:187], v[56:59]
	v_mfma_f32_16x16x32_bf16 v[44:47], v[144:147], v[192:195], v[44:47]
	v_mfma_f32_16x16x32_bf16 v[40:43], v[160:163], v[192:195], v[40:43]
	v_mfma_f32_16x16x32_bf16 v[60:63], v[148:151], v[188:191], v[60:63]
	v_mfma_f32_16x16x32_bf16 v[56:59], v[164:167], v[188:191], v[56:59]
	v_mfma_f32_16x16x32_bf16 v[44:47], v[148:151], v[196:199], v[44:47]
	v_mfma_f32_16x16x32_bf16 v[40:43], v[164:167], v[196:199], v[40:43]
	v_mfma_f32_16x16x32_bf16 v[28:31], v[144:147], v[200:203], v[28:31]
	v_mfma_f32_16x16x32_bf16 v[24:27], v[160:163], v[200:203], v[24:27]
	v_mfma_f32_16x16x32_bf16 v[12:15], v[144:147], v[210:213], v[12:15]
	v_mfma_f32_16x16x32_bf16 v[8:11], v[160:163], v[210:213], v[8:11]
	v_mfma_f32_16x16x32_bf16 v[28:31], v[148:151], v[206:209], v[28:31]
	v_mfma_f32_16x16x32_bf16 v[24:27], v[164:167], v[206:209], v[24:27]
	v_lshl_add_u64 v[222:223], s[42:43], 0, v[134:135]
	s_mov_b32 m0, s34
	s_nop 0
	global_load_lds_dwordx4 v[222:223], off
	v_mfma_f32_16x16x32_bf16 v[12:15], v[148:151], v[214:217], v[12:15]
	v_mfma_f32_16x16x32_bf16 v[8:11], v[164:167], v[214:217], v[8:11]
	s_setprio 0
	s_setprio 1
	v_mfma_f32_16x16x32_bf16 v[52:55], v[168:171], v[184:187], v[52:55]
	v_mfma_f32_16x16x32_bf16 v[48:51], v[176:179], v[184:187], v[48:51]
	v_mfma_f32_16x16x32_bf16 v[36:39], v[168:171], v[192:195], v[36:39]
	v_mfma_f32_16x16x32_bf16 v[32:35], v[176:179], v[192:195], v[32:35]
	v_mfma_f32_16x16x32_bf16 v[52:55], v[172:175], v[188:191], v[52:55]
	v_mfma_f32_16x16x32_bf16 v[48:51], v[180:183], v[188:191], v[48:51]
	v_mfma_f32_16x16x32_bf16 v[36:39], v[172:175], v[196:199], v[36:39]
	v_mfma_f32_16x16x32_bf16 v[32:35], v[180:183], v[196:199], v[32:35]
	v_mfma_f32_16x16x32_bf16 v[20:23], v[168:171], v[200:203], v[20:23]
	v_mfma_f32_16x16x32_bf16 v[16:19], v[176:179], v[200:203], v[16:19]
	v_mfma_f32_16x16x32_bf16 v[4:7], v[168:171], v[210:213], v[4:7]
	v_mfma_f32_16x16x32_bf16 v[0:3], v[176:179], v[210:213], v[0:3]
	v_mfma_f32_16x16x32_bf16 v[20:23], v[172:175], v[206:209], v[20:23]
	v_mfma_f32_16x16x32_bf16 v[16:19], v[180:183], v[206:209], v[16:19]
	v_lshl_add_u64 v[224:225], s[42:43], 0, v[130:131]
	s_mov_b32 m0, s37
	s_nop 0
	global_load_lds_dwordx4 v[224:225], off
	v_mfma_f32_16x16x32_bf16 v[4:7], v[172:175], v[214:217], v[4:7]
	v_mfma_f32_16x16x32_bf16 v[0:3], v[180:183], v[214:217], v[0:3]
	s_setprio 0
	s_barrier
; #define PG8_STAGE(bufoff, gbase, voff) do { _Pragma("unroll") for (int _i = 0; _i < 2; ++_i) \
;         __builtin_amdgcn_global_load_lds((const unsigned*)((const char*)(gbase) + (voff)[_i]), (PG8_LAS unsigned*)(lds + (bufoff) + ldsw + _i * 8192), 16, 0, 0); } while (0)
; #define PG8_LDA(dst, b, h) do { _Pragma("unroll") for (int m = 0; m < 4; ++m) _Pragma("unroll") for (int k = 0; k < 2; ++k) dst[m][k] = *(const PG8_LAS bf16x8*)(lds + PG8_SA(b, h) + aoff + m * 2048 + k * 1024); } while (0)
; #define PG8_LDB(dst, b, h) do { _Pragma("unroll") for (int n = 0; n < 2; ++n) _Pragma("unroll") for (int k = 0; k < 2; ++k) dst[n][k] = *(const PG8_LAS bf16x8*)(lds + PG8_SB(b, h) + boff + n * 2048 + k * 1024); } while (0)
; #define PG8_MMA(ai, bj, At, Bt) do { __builtin_amdgcn_s_setprio(1); _Pragma("unroll") for (int m = 0; m < 4; ++m) _Pragma("unroll") for (int n = 0; n < 2; ++n) _Pragma("unroll") for (int k = 0; k < 2; ++k) \
;         acc[ai][bj][m][n] = __builtin_amdgcn_mfma_f32_16x16x32_bf16(Bt[n][k], At[m][k], acc[ai][bj][m][n], 0, 0, 0); __builtin_amdgcn_s_setprio(0); } while (0)
; #define PG8_WAIT_V(n) asm volatile("s_waitcnt vmcnt(" #n ")" ::: "memory")
; #define PG8_WAIT_L(n) asm volatile("s_waitcnt lgkmcnt(" #n ")" ::: "memory")
; #define PG8_BAR __builtin_amdgcn_s_barrier()
; #define PG8_SCHED __builtin_amdgcn_sched_barrier(0)
; template <class Epi, class Sched, bool ALIGN_EPI = false, bool SP2 = false>
; __device__ __forceinline__ void gemm_phase(PG8_LAS unsigned char* lds, const Gemm g, const Sched& S, const Epi& E) {
;     ...
;             PG8_LDB(B0, 1, 0); PG8_LDB(B1, 1, 1); PG8_SCHED; PG8_LDA(At, 1, 0); PG8_STAGE(PG8_SA(0, 1), a2 + hstep, voffA);
;             PG8_WAIT_V(8); PG8_WAIT_L(0); PG8_BAR; PG8_MMA(0, 0, At, B0); PG8_MMA(0, 1, At, B1); PG8_BAR; PG8_SCHED;
	s_add_i32 s58, 0, 0x18000
	v_add_u32_e32 v159, s58, v153
	s_add_i32 s59, 0, 0x1c000
	ds_read_b128 v[144:147], v159
	ds_read_b128 v[148:151], v159 offset:1024
	ds_read_b128 v[160:163], v159 offset:2048
	ds_read_b128 v[164:167], v159 offset:3072
	v_add_u32_e32 v159, s59, v153
	ds_read_b128 v[168:171], v159
	ds_read_b128 v[172:175], v159 offset:1024
	ds_read_b128 v[176:179], v159 offset:2048
	ds_read_b128 v[180:183], v159 offset:3072
	s_add_u32 s42, s42, 0x40000
	s_addc_u32 s43, s43, 0
	s_mov_b32 m0, s44
	v_lshl_add_u64 v[226:227], s[42:43], 0, v[134:135]
	ds_read_b128 v[184:187], v157 offset:32768
	ds_read_b128 v[188:191], v157 offset:33792
	ds_read_b128 v[192:195], v157 offset:34816
	ds_read_b128 v[196:199], v157 offset:35840
	ds_read_b128 v[200:203], v157 offset:36864
	ds_read_b128 v[206:209], v157 offset:37888
	ds_read_b128 v[210:213], v157 offset:38912
	ds_read_b128 v[214:217], v157 offset:39936
	global_load_lds_dwordx4 v[226:227], off
	v_lshl_add_u64 v[226:227], s[42:43], 0, v[130:131]
	s_mov_b32 m0, s45
	s_nop 0
	global_load_lds_dwordx4 v[226:227], off
	s_waitcnt vmcnt(8)
	s_waitcnt lgkmcnt(0)
	s_barrier
	s_setprio 1
	s_waitcnt lgkmcnt(0)
	v_mfma_f32_16x16x32_bf16 v[124:127], v[144:147], v[184:187], v[124:127]
	v_mfma_f32_16x16x32_bf16 v[120:123], v[160:163], v[184:187], v[120:123]
	v_mfma_f32_16x16x32_bf16 v[108:111], v[144:147], v[192:195], v[108:111]
	v_mfma_f32_16x16x32_bf16 v[104:107], v[160:163], v[192:195], v[104:107]
	v_mfma_f32_16x16x32_bf16 v[124:127], v[148:151], v[188:191], v[124:127]
	v_mfma_f32_16x16x32_bf16 v[120:123], v[164:167], v[188:191], v[120:123]
	v_mfma_f32_16x16x32_bf16 v[108:111], v[148:151], v[196:199], v[108:111]
	v_mfma_f32_16x16x32_bf16 v[104:107], v[164:167], v[196:199], v[104:107]
	v_mfma_f32_16x16x32_bf16 v[92:95], v[144:147], v[200:203], v[92:95]
	v_mfma_f32_16x16x32_bf16 v[88:91], v[160:163], v[200:203], v[88:91]
	v_mfma_f32_16x16x32_bf16 v[76:79], v[144:147], v[210:213], v[76:79]
	v_mfma_f32_16x16x32_bf16 v[72:75], v[160:163], v[210:213], v[72:75]
	v_mfma_f32_16x16x32_bf16 v[92:95], v[148:151], v[206:209], v[92:95]
	v_mfma_f32_16x16x32_bf16 v[88:91], v[164:167], v[206:209], v[88:91]
	v_mfma_f32_16x16x32_bf16 v[76:79], v[148:151], v[214:217], v[76:79]
	v_mfma_f32_16x16x32_bf16 v[72:75], v[164:167], v[214:217], v[72:75]
	s_setprio 0
	s_setprio 1
	v_mfma_f32_16x16x32_bf16 v[116:119], v[168:171], v[184:187], v[116:119]
	v_mfma_f32_16x16x32_bf16 v[112:115], v[176:179], v[184:187], v[112:115]
	v_mfma_f32_16x16x32_bf16 v[100:103], v[168:171], v[192:195], v[100:103]
	v_mfma_f32_16x16x32_bf16 v[96:99], v[176:179], v[192:195], v[96:99]
	v_mfma_f32_16x16x32_bf16 v[116:119], v[172:175], v[188:191], v[116:119]
	v_mfma_f32_16x16x32_bf16 v[112:115], v[180:183], v[188:191], v[112:115]
	v_mfma_f32_16x16x32_bf16 v[100:103], v[172:175], v[196:199], v[100:103]
	v_mfma_f32_16x16x32_bf16 v[96:99], v[180:183], v[196:199], v[96:99]
	v_mfma_f32_16x16x32_bf16 v[84:87], v[168:171], v[200:203], v[84:87]
	v_mfma_f32_16x16x32_bf16 v[80:83], v[176:179], v[200:203], v[80:83]
	v_mfma_f32_16x16x32_bf16 v[68:71], v[168:171], v[210:213], v[68:71]
	v_mfma_f32_16x16x32_bf16 v[64:67], v[176:179], v[210:213], v[64:67]
	v_mfma_f32_16x16x32_bf16 v[84:87], v[172:175], v[206:209], v[84:87]
	v_mfma_f32_16x16x32_bf16 v[80:83], v[180:183], v[206:209], v[80:83]
	v_mfma_f32_16x16x32_bf16 v[68:71], v[172:175], v[214:217], v[68:71]
	v_mfma_f32_16x16x32_bf16 v[64:67], v[180:183], v[214:217], v[64:67]
	s_setprio 0
	s_barrier
; #define PG8_STAGE(bufoff, gbase, voff) do { _Pragma("unroll") for (int _i = 0; _i < 2; ++_i) \
;         __builtin_amdgcn_global_load_lds((const unsigned*)((const char*)(gbase) + (voff)[_i]), (PG8_LAS unsigned*)(lds + (bufoff) + ldsw + _i * 8192), 16, 0, 0); } while (0)
; #define PG8_LDA(dst, b, h) do { _Pragma("unroll") for (int m = 0; m < 4; ++m) _Pragma("unroll") for (int k = 0; k < 2; ++k) dst[m][k] = *(const PG8_LAS bf16x8*)(lds + PG8_SA(b, h) + aoff + m * 2048 + k * 1024); } while (0)
; #define PG8_MMA(ai, bj, At, Bt) do { __builtin_amdgcn_s_setprio(1); _Pragma("unroll") for (int m = 0; m < 4; ++m) _Pragma("unroll") for (int n = 0; n < 2; ++n) _Pragma("unroll") for (int k = 0; k < 2; ++k) \
;         acc[ai][bj][m][n] = __builtin_amdgcn_mfma_f32_16x16x32_bf16(Bt[n][k], At[m][k], acc[ai][bj][m][n], 0, 0, 0); __builtin_amdgcn_s_setprio(0); } while (0)
; #define PG8_WAIT_V(n) asm volatile("s_waitcnt vmcnt(" #n ")" ::: "memory")
; #define PG8_WAIT_L(n) asm volatile("s_waitcnt lgkmcnt(" #n ")" ::: "memory")
; #define PG8_BAR __builtin_amdgcn_s_barrier()
; #define PG8_SCHED __builtin_amdgcn_sched_barrier(0)
; __device__ __forceinline__ float row_rs(const float* ssp, int row) { const unsigned long long v = ((const unsigned long long*)ssp)[row];
;     return __builtin_amdgcn_rsqf((float)v * (1.0f / 4294967296.0f) * (1.0f / 1024.0f) + RMS_EPS); }
; template <class Epi, class Sched, bool ALIGN_EPI = false, bool SP2 = false>
; __device__ __forceinline__ void gemm_phase(PG8_LAS unsigned char* lds, const Gemm g, const Sched& S, const Epi& E) {
;     ...
;             PG8_LDA(At, 1, 1); PG8_STAGE(PG8_SB(1, 0), b3, voffB); PG8_STAGE(PG8_SB(1, 1), b3 + hstep, voffB); PG8_STAGE(PG8_SA(1, 0), a3, voffA);
;             PG8_WAIT_V(8); PG8_WAIT_L(0); PG8_BAR; PG8_MMA(1, 0, At, B0); PG8_MMA(1, 1, At, B1); PG8_BAR; PG8_SCHED;
	s_add_i32 s42, s58, s15
	v_lshl_add_u64 v[218:219], v[218:219], 0, s[8:9]
	s_mov_b32 m0, s42
	ds_read_b128 v[184:187], v157 offset:49152
	ds_read_b128 v[188:191], v157 offset:50176
	ds_read_b128 v[192:195], v157 offset:51200
	ds_read_b128 v[196:199], v157 offset:52224
	ds_read_b128 v[200:203], v157 offset:53248
	ds_read_b128 v[206:209], v157 offset:54272
	ds_read_b128 v[210:213], v157 offset:55296
	ds_read_b128 v[214:217], v157 offset:56320
	global_load_lds_dwordx4 v[218:219], off
	s_add_i32 m0, s42, 0x2000
	s_add_u32 s40, s40, 0x40080
	v_lshl_add_u64 v[218:219], v[220:221], 0, s[8:9]
	s_addc_u32 s41, s41, 0
	s_add_i32 s42, s59, s15
	global_load_lds_dwordx4 v[218:219], off
	v_lshl_add_u64 v[218:219], s[40:41], 0, v[132:133]
	s_mov_b32 m0, s42
	s_nop 0
	global_load_lds_dwordx4 v[218:219], off
	v_lshl_add_u64 v[218:219], s[40:41], 0, v[128:129]
	s_add_i32 m0, s42, 0x2000
	s_nop 0
	global_load_lds_dwordx4 v[218:219], off
	s_waitcnt vmcnt(6)
	s_waitcnt lgkmcnt(0)
	s_barrier
	s_setprio 1
	s_waitcnt lgkmcnt(0)
	v_mfma_f32_16x16x32_bf16 v[60:63], v[144:147], v[184:187], v[60:63]
	v_mfma_f32_16x16x32_bf16 v[56:59], v[160:163], v[184:187], v[56:59]
	v_mfma_f32_16x16x32_bf16 v[44:47], v[144:147], v[192:195], v[44:47]
	v_mfma_f32_16x16x32_bf16 v[40:43], v[160:163], v[192:195], v[40:43]
	v_mfma_f32_16x16x32_bf16 v[60:63], v[148:151], v[188:191], v[60:63]
	v_mfma_f32_16x16x32_bf16 v[56:59], v[164:167], v[188:191], v[56:59]
	v_mfma_f32_16x16x32_bf16 v[44:47], v[148:151], v[196:199], v[44:47]
	v_mfma_f32_16x16x32_bf16 v[40:43], v[164:167], v[196:199], v[40:43]
	v_mfma_f32_16x16x32_bf16 v[28:31], v[144:147], v[200:203], v[28:31]
	v_mfma_f32_16x16x32_bf16 v[24:27], v[160:163], v[200:203], v[24:27]
	v_mfma_f32_16x16x32_bf16 v[12:15], v[144:147], v[210:213], v[12:15]
	v_mfma_f32_16x16x32_bf16 v[8:11], v[160:163], v[210:213], v[8:11]
	v_mfma_f32_16x16x32_bf16 v[28:31], v[148:151], v[206:209], v[28:31]
	v_mfma_f32_16x16x32_bf16 v[24:27], v[164:167], v[206:209], v[24:27]
	v_lshl_add_u64 v[218:219], v[222:223], 0, s[8:9]
	s_mov_b32 m0, s47
	s_nop 0
	global_load_lds_dwordx4 v[218:219], off
	v_mfma_f32_16x16x32_bf16 v[12:15], v[148:151], v[214:217], v[12:15]
	v_mfma_f32_16x16x32_bf16 v[8:11], v[164:167], v[214:217], v[8:11]
	s_setprio 0
	s_setprio 1
	v_mfma_f32_16x16x32_bf16 v[52:55], v[168:171], v[184:187], v[52:55]
	v_mfma_f32_16x16x32_bf16 v[48:51], v[176:179], v[184:187], v[48:51]
	v_mfma_f32_16x16x32_bf16 v[36:39], v[168:171], v[192:195], v[36:39]
	v_mfma_f32_16x16x32_bf16 v[32:35], v[176:179], v[192:195], v[32:35]
	v_mfma_f32_16x16x32_bf16 v[52:55], v[172:175], v[188:191], v[52:55]
	v_mfma_f32_16x16x32_bf16 v[48:51], v[180:183], v[188:191], v[48:51]
	v_mfma_f32_16x16x32_bf16 v[36:39], v[172:175], v[196:199], v[36:39]
	v_mfma_f32_16x16x32_bf16 v[32:35], v[180:183], v[196:199], v[32:35]
	v_mfma_f32_16x16x32_bf16 v[20:23], v[168:171], v[200:203], v[20:23]
	v_mfma_f32_16x16x32_bf16 v[16:19], v[176:179], v[200:203], v[16:19]
	v_mfma_f32_16x16x32_bf16 v[4:7], v[168:171], v[210:213], v[4:7]
	v_mfma_f32_16x16x32_bf16 v[0:3], v[176:179], v[210:213], v[0:3]
	v_mfma_f32_16x16x32_bf16 v[20:23], v[172:175], v[206:209], v[20:23]
	v_mfma_f32_16x16x32_bf16 v[16:19], v[180:183], v[206:209], v[16:19]
	v_lshl_add_u64 v[218:219], v[224:225], 0, s[8:9]
	s_mov_b32 m0, s48
	s_nop 0
	global_load_lds_dwordx4 v[218:219], off
	v_mfma_f32_16x16x32_bf16 v[4:7], v[172:175], v[214:217], v[4:7]
	v_mfma_f32_16x16x32_bf16 v[0:3], v[180:183], v[214:217], v[0:3]
	s_setprio 0
	s_barrier
	s_add_i32 s57, s57, 2
	s_add_u32 s38, s38, 0x100
	s_addc_u32 s39, s39, 0
	s_add_u32 s55, s55, 0x100
	s_addc_u32 s56, s56, 0
	s_cmp_gt_u32 s57, 13
	s_cbranch_scc0 .LBB0_1900
	v_lshl_add_u32 v144, s36, 8, v152
	v_ashrrev_i32_e32 v145, 31, v144
	v_lshl_add_u64 v[150:151], v[144:145], 3, s[0:1]
	global_load_dwordx2 v[182:183], v[150:151], off
	global_load_dwordx2 v[184:185], v[150:151], off offset:128
	global_load_dwordx2 v[186:187], v[150:151], off offset:256
	global_load_dwordx2 v[188:189], v[150:151], off offset:384
	global_load_dwordx2 v[190:191], v[150:151], off offset:1024
	global_load_dwordx2 v[192:193], v[150:151], off offset:1152
	global_load_dwordx2 v[194:195], v[150:151], off offset:1280
	global_load_dwordx2 v[196:197], v[150:151], off offset:1408
	s_and_b64 vcc, exec, s[10:11]
	s_cbranch_vccz .LBB0_1903
	s_barrier

; #define PG8_STAGE(bufoff, gbase, voff) do { _Pragma("unroll") for (int _i = 0; _i < 2; ++_i) \
;         __builtin_amdgcn_global_load_lds((const unsigned*)((const char*)(gbase) + (voff)[_i]), (PG8_LAS unsigned*)(lds + (bufoff) + ldsw + _i * 8192), 16, 0, 0); } while (0)
; #define PG8_LDA(dst, b, h) do { _Pragma("unroll") for (int m = 0; m < 4; ++m) _Pragma("unroll") for (int k = 0; k < 2; ++k) dst[m][k] = *(const PG8_LAS bf16x8*)(lds + PG8_SA(b, h) + aoff + m * 2048 + k * 1024); } while (0)
; #define PG8_LDB(dst, b, h) do { _Pragma("unroll") for (int n = 0; n < 2; ++n) _Pragma("unroll") for (int k = 0; k < 2; ++k) dst[n][k] = *(const PG8_LAS bf16x8*)(lds + PG8_SB(b, h) + boff + n * 2048 + k * 1024); } while (0)
; #define PG8_MMA(ai, bj, At, Bt) do { __builtin_amdgcn_s_setprio(1); _Pragma("unroll") for (int m = 0; m < 4; ++m) _Pragma("unroll") for (int n = 0; n < 2; ++n) _Pragma("unroll") for (int k = 0; k < 2; ++k) \
;         acc[ai][bj][m][n] = __builtin_amdgcn_mfma_f32_16x16x32_bf16(Bt[n][k], At[m][k], acc[ai][bj][m][n], 0, 0, 0); __builtin_amdgcn_s_setprio(0); } while (0)
; #define PG8_WAIT_V(n) asm volatile("s_waitcnt vmcnt(" #n ")" ::: "memory")
; #define PG8_WAIT_L(n) asm volatile("s_waitcnt lgkmcnt(" #n ")" ::: "memory")
; #define PG8_BAR __builtin_amdgcn_s_barrier()
; #define PG8_SCHED __builtin_amdgcn_sched_barrier(0)
; template <class Epi, class Sched, bool ALIGN_EPI = false, bool SP2 = false>
; __device__ __forceinline__ void gemm_phase(PG8_LAS unsigned char* lds, const Gemm g, const Sched& S, const Epi& E) {
;     ...
;         const char* nA = has_next ? (const char*)g.A + (size_t)nxt.pm * tstep : cA; const char* nB = has_next ? (const char*)g.Bt + (size_t)nxt.pn * tstep : cB;
;         for (int t = 0; t < nt; t += 2) {
;             const bool last = (t == nt - 2);
;             const char* a1 = cA + (size_t)(t + 1) * kstep;
;             const char* a2 = last ? nA : cA + (size_t)(t + 2) * kstep; const char* b2 = last ? nB : cB + (size_t)(t + 2) * kstep;
;             const char* a3 = a2 + kstep; const char* b3 = b2 + kstep;
;             if (last && has_next) S.a_ready(nxt);
;             if constexpr (SP2) {
;             PG8_LDB(B0, 0, 0); PG8_LDB(B1, 0, 1); PG8_SCHED; PG8_LDA(At, 0, 0); PG8_STAGE(PG8_SA(1, 1), a1 + hstep, voffA);
;             PG8_WAIT_V(8); PG8_WAIT_L(0); PG8_BAR; PG8_MMA(0, 0, At, B0); PG8_MMA(0, 1, At, B1); PG8_BAR; PG8_SCHED;
.LBB0_1977:
	s_add_u32 s53, s28, 0x100
	s_addc_u32 s54, s29, 0
	s_mov_b32 s55, -2
	s_waitcnt lgkmcnt(0)
	ds_read_b128 v[144:147], v151
	ds_read_b128 v[156:159], v151 offset:1024
	ds_read_b128 v[160:163], v151 offset:2048
	ds_read_b128 v[164:167], v151 offset:3072
	ds_read_b128 v[168:171], v152
	ds_read_b128 v[172:175], v152 offset:1024
	ds_read_b128 v[176:179], v152 offset:2048
	ds_read_b128 v[180:183], v152 offset:3072
	s_add_u32 s28, s26, 0x100
	s_addc_u32 s29, s27, 0
	s_cmp_eq_u32 s55, 40
	s_cselect_b32 s39, s1, s29
	s_cselect_b32 s38, s0, s28
	s_cselect_b32 s37, s25, s54
	s_cselect_b32 s36, s24, s53
	v_lshl_add_u64 v[218:219], s[26:27], 0, v[136:137]
	s_add_i32 m0, s33, 0xc000
	ds_read_b128 v[184:187], v153
	ds_read_b128 v[188:191], v153 offset:1024
	ds_read_b128 v[192:195], v153 offset:2048
	ds_read_b128 v[196:199], v153 offset:3072
	ds_read_b128 v[200:203], v153 offset:4096
	ds_read_b128 v[206:209], v153 offset:5120
	ds_read_b128 v[210:213], v153 offset:6144
	ds_read_b128 v[214:217], v153 offset:7168
	global_load_lds_dwordx4 v[218:219], off
	v_lshl_add_u64 v[218:219], s[26:27], 0, v[138:139]
	s_add_i32 m0, s33, 0xe000
	s_nop 0
	global_load_lds_dwordx4 v[218:219], off
	s_waitcnt vmcnt(8)
	s_waitcnt lgkmcnt(0)
	s_barrier
	s_setprio 1
	s_waitcnt lgkmcnt(0)
	v_mfma_f32_16x16x32_bf16 v[124:127], v[144:147], v[184:187], 0
	v_mfma_f32_16x16x32_bf16 v[120:123], v[160:163], v[184:187], 0
	v_mfma_f32_16x16x32_bf16 v[108:111], v[144:147], v[192:195], 0
	v_mfma_f32_16x16x32_bf16 v[104:107], v[160:163], v[192:195], 0
	v_mfma_f32_16x16x32_bf16 v[124:127], v[156:159], v[188:191], v[124:127]
	v_mfma_f32_16x16x32_bf16 v[120:123], v[164:167], v[188:191], v[120:123]
	v_mfma_f32_16x16x32_bf16 v[108:111], v[156:159], v[196:199], v[108:111]
	v_mfma_f32_16x16x32_bf16 v[104:107], v[164:167], v[196:199], v[104:107]
	v_mfma_f32_16x16x32_bf16 v[92:95], v[144:147], v[200:203], 0
	v_mfma_f32_16x16x32_bf16 v[88:91], v[160:163], v[200:203], 0
	v_mfma_f32_16x16x32_bf16 v[76:79], v[144:147], v[210:213], 0
	v_mfma_f32_16x16x32_bf16 v[72:75], v[160:163], v[210:213], 0
	v_mfma_f32_16x16x32_bf16 v[92:95], v[156:159], v[206:209], v[92:95]
	v_mfma_f32_16x16x32_bf16 v[88:91], v[164:167], v[206:209], v[88:91]
	v_mfma_f32_16x16x32_bf16 v[76:79], v[156:159], v[214:217], v[76:79]
	v_mfma_f32_16x16x32_bf16 v[72:75], v[164:167], v[214:217], v[72:75]
	s_setprio 0
	s_setprio 1
	v_mfma_f32_16x16x32_bf16 v[116:119], v[168:171], v[184:187], 0
	v_mfma_f32_16x16x32_bf16 v[112:115], v[176:179], v[184:187], 0
	v_mfma_f32_16x16x32_bf16 v[100:103], v[168:171], v[192:195], 0
	v_mfma_f32_16x16x32_bf16 v[96:99], v[176:179], v[192:195], 0
	v_mfma_f32_16x16x32_bf16 v[116:119], v[172:175], v[188:191], v[116:119]
	v_mfma_f32_16x16x32_bf16 v[112:115], v[180:183], v[188:191], v[112:115]
	v_mfma_f32_16x16x32_bf16 v[100:103], v[172:175], v[196:199], v[100:103]
	v_mfma_f32_16x16x32_bf16 v[96:99], v[180:183], v[196:199], v[96:99]
	v_mfma_f32_16x16x32_bf16 v[84:87], v[168:171], v[200:203], 0
	v_mfma_f32_16x16x32_bf16 v[80:83], v[176:179], v[200:203], 0
	v_mfma_f32_16x16x32_bf16 v[68:71], v[168:171], v[210:213], 0
	v_mfma_f32_16x16x32_bf16 v[64:67], v[176:179], v[210:213], 0
	v_mfma_f32_16x16x32_bf16 v[84:87], v[172:175], v[206:209], v[84:87]
	v_mfma_f32_16x16x32_bf16 v[80:83], v[180:183], v[206:209], v[80:83]
	v_mfma_f32_16x16x32_bf16 v[68:71], v[172:175], v[214:217], v[68:71]
	v_mfma_f32_16x16x32_bf16 v[64:67], v[180:183], v[214:217], v[64:67]
	s_setprio 0
	s_barrier
	s_add_i32 s26, s45, s15
	v_lshl_add_u64 v[218:219], s[36:37], 0, v[130:131]
	s_mov_b32 m0, s26
	ds_read_b128 v[184:187], v153 offset:16384
	ds_read_b128 v[188:191], v153 offset:17408
	ds_read_b128 v[192:195], v153 offset:18432
	ds_read_b128 v[196:199], v153 offset:19456
	ds_read_b128 v[200:203], v153 offset:20480
	ds_read_b128 v[206:209], v153 offset:21504
	ds_read_b128 v[210:213], v153 offset:22528
	ds_read_b128 v[214:217], v153 offset:23552
	global_load_lds_dwordx4 v[218:219], off
	s_add_i32 m0, s26, 0x2000
	s_add_u32 s26, s36, 0xb0000
	v_lshl_add_u64 v[220:221], s[36:37], 0, v[134:135]
	s_addc_u32 s27, s37, 0
	s_add_i32 s56, s46, s15
	global_load_lds_dwordx4 v[220:221], off
	v_lshl_add_u64 v[222:223], s[26:27], 0, v[130:131]
	s_mov_b32 m0, s56
	global_load_lds_dwordx4 v[222:223], off
	v_lshl_add_u64 v[222:223], s[26:27], 0, v[134:135]
	s_add_i32 m0, s56, 0x2000
	s_nop 0
	global_load_lds_dwordx4 v[222:223], off
	s_waitcnt vmcnt(6)
	s_waitcnt lgkmcnt(0)
	s_barrier
; #define PG8_STAGE(bufoff, gbase, voff) do { _Pragma("unroll") for (int _i = 0; _i < 2; ++_i) \
;         __builtin_amdgcn_global_load_lds((const unsigned*)((const char*)(gbase) + (voff)[_i]), (PG8_LAS unsigned*)(lds + (bufoff) + ldsw + _i * 8192), 16, 0, 0); } while (0)
; #define PG8_LDA(dst, b, h) do { _Pragma("unroll") for (int m = 0; m < 4; ++m) _Pragma("unroll") for (int k = 0; k < 2; ++k) dst[m][k] = *(const PG8_LAS bf16x8*)(lds + PG8_SA(b, h) + aoff + m * 2048 + k * 1024); } while (0)
; #define PG8_LDB(dst, b, h) do { _Pragma("unroll") for (int n = 0; n < 2; ++n) _Pragma("unroll") for (int k = 0; k < 2; ++k) dst[n][k] = *(const PG8_LAS bf16x8*)(lds + PG8_SB(b, h) + boff + n * 2048 + k * 1024); } while (0)
; #define PG8_MMA(ai, bj, At, Bt) do { __builtin_amdgcn_s_setprio(1); _Pragma("unroll") for (int m = 0; m < 4; ++m) _Pragma("unroll") for (int n = 0; n < 2; ++n) _Pragma("unroll") for (int k = 0; k < 2; ++k) \
;         acc[ai][bj][m][n] = __builtin_amdgcn_mfma_f32_16x16x32_bf16(Bt[n][k], At[m][k], acc[ai][bj][m][n], 0, 0, 0); __builtin_amdgcn_s_setprio(0); } while (0)
; #define PG8_WAIT_V(n) asm volatile("s_waitcnt vmcnt(" #n ")" ::: "memory")
; #define PG8_WAIT_L(n) asm volatile("s_waitcnt lgkmcnt(" #n ")" ::: "memory")
; #define PG8_BAR __builtin_amdgcn_s_barrier()
; #define PG8_SCHED __builtin_amdgcn_sched_barrier(0)
; template <class Epi, class Sched, bool ALIGN_EPI = false, bool SP2 = false>
; __device__ __forceinline__ void gemm_phase(PG8_LAS unsigned char* lds, const Gemm g, const Sched& S, const Epi& E) {
;     ...
;             PG8_WAIT_V(8); PG8_WAIT_L(0); PG8_BAR; PG8_MMA(1, 0, At, B0); PG8_MMA(1, 1, At, B1); PG8_BAR; PG8_SCHED;
;             PG8_LDB(B0, 1, 0); PG8_LDB(B1, 1, 1); PG8_SCHED; PG8_LDA(At, 1, 0); PG8_STAGE(PG8_SA(0, 1), a2 + hstep, voffA);
;             PG8_WAIT_V(8); PG8_WAIT_L(0); PG8_BAR; PG8_MMA(0, 0, At, B0); PG8_MMA(0, 1, At, B1); PG8_BAR; PG8_SCHED;
	s_setprio 1
	s_waitcnt lgkmcnt(0)
	v_mfma_f32_16x16x32_bf16 v[60:63], v[144:147], v[184:187], 0
	v_mfma_f32_16x16x32_bf16 v[56:59], v[160:163], v[184:187], 0
	v_mfma_f32_16x16x32_bf16 v[44:47], v[144:147], v[192:195], 0
	v_mfma_f32_16x16x32_bf16 v[40:43], v[160:163], v[192:195], 0
	v_mfma_f32_16x16x32_bf16 v[60:63], v[156:159], v[188:191], v[60:63]
	v_mfma_f32_16x16x32_bf16 v[56:59], v[164:167], v[188:191], v[56:59]
	v_mfma_f32_16x16x32_bf16 v[44:47], v[156:159], v[196:199], v[44:47]
	v_mfma_f32_16x16x32_bf16 v[40:43], v[164:167], v[196:199], v[40:43]
	v_mfma_f32_16x16x32_bf16 v[28:31], v[144:147], v[200:203], 0
	v_mfma_f32_16x16x32_bf16 v[24:27], v[160:163], v[200:203], 0
	v_mfma_f32_16x16x32_bf16 v[12:15], v[144:147], v[210:213], 0
	v_mfma_f32_16x16x32_bf16 v[8:11], v[160:163], v[210:213], 0
	v_mfma_f32_16x16x32_bf16 v[28:31], v[156:159], v[206:209], v[28:31]
	v_mfma_f32_16x16x32_bf16 v[24:27], v[164:167], v[206:209], v[24:27]
	v_lshl_add_u64 v[222:223], s[38:39], 0, v[128:129]
	s_mov_b32 m0, s33
	s_nop 0
	global_load_lds_dwordx4 v[222:223], off
	v_mfma_f32_16x16x32_bf16 v[12:15], v[156:159], v[214:217], v[12:15]
	v_mfma_f32_16x16x32_bf16 v[8:11], v[164:167], v[214:217], v[8:11]
	s_setprio 0
	s_setprio 1
	v_mfma_f32_16x16x32_bf16 v[52:55], v[168:171], v[184:187], 0
	v_mfma_f32_16x16x32_bf16 v[48:51], v[176:179], v[184:187], 0
	v_mfma_f32_16x16x32_bf16 v[36:39], v[168:171], v[192:195], 0
	v_mfma_f32_16x16x32_bf16 v[32:35], v[176:179], v[192:195], 0
	v_mfma_f32_16x16x32_bf16 v[52:55], v[172:175], v[188:191], v[52:55]
	v_mfma_f32_16x16x32_bf16 v[48:51], v[180:183], v[188:191], v[48:51]
	v_mfma_f32_16x16x32_bf16 v[36:39], v[172:175], v[196:199], v[36:39]
	v_mfma_f32_16x16x32_bf16 v[32:35], v[180:183], v[196:199], v[32:35]
	v_mfma_f32_16x16x32_bf16 v[20:23], v[168:171], v[200:203], 0
	v_mfma_f32_16x16x32_bf16 v[16:19], v[176:179], v[200:203], 0
	v_mfma_f32_16x16x32_bf16 v[4:7], v[168:171], v[210:213], 0
	v_mfma_f32_16x16x32_bf16 v[0:3], v[176:179], v[210:213], 0
	v_mfma_f32_16x16x32_bf16 v[20:23], v[172:175], v[206:209], v[20:23]
	v_mfma_f32_16x16x32_bf16 v[16:19], v[180:183], v[206:209], v[16:19]
	v_lshl_add_u64 v[224:225], s[38:39], 0, v[132:133]
	s_mov_b32 m0, s34
	s_nop 0
	global_load_lds_dwordx4 v[224:225], off
	v_mfma_f32_16x16x32_bf16 v[4:7], v[172:175], v[214:217], v[4:7]
	v_mfma_f32_16x16x32_bf16 v[0:3], v[180:183], v[214:217], v[0:3]
	s_setprio 0
	s_barrier
	s_add_i32 s56, 0, 0x18000
	v_add_u32_e32 v155, s56, v149
	s_add_i32 s57, 0, 0x1c000
	ds_read_b128 v[144:147], v155
	ds_read_b128 v[156:159], v155 offset:1024
	ds_read_b128 v[160:163], v155 offset:2048
	ds_read_b128 v[164:167], v155 offset:3072
	v_add_u32_e32 v155, s57, v149
	ds_read_b128 v[168:171], v155
	ds_read_b128 v[172:175], v155 offset:1024
	ds_read_b128 v[176:179], v155 offset:2048
	ds_read_b128 v[180:183], v155 offset:3072
	s_add_u32 s26, s38, 0xb0000
	s_addc_u32 s27, s39, 0
	s_mov_b32 m0, s40
	v_lshl_add_u64 v[226:227], s[26:27], 0, v[128:129]
	ds_read_b128 v[184:187], v153 offset:32768
	ds_read_b128 v[188:191], v153 offset:33792
	ds_read_b128 v[192:195], v153 offset:34816
	ds_read_b128 v[196:199], v153 offset:35840
	ds_read_b128 v[200:203], v153 offset:36864
	ds_read_b128 v[206:209], v153 offset:37888
	ds_read_b128 v[210:213], v153 offset:38912
	ds_read_b128 v[214:217], v153 offset:39936
	global_load_lds_dwordx4 v[226:227], off
	v_lshl_add_u64 v[226:227], s[26:27], 0, v[132:133]
	s_mov_b32 m0, s41
	s_nop 0
	global_load_lds_dwordx4 v[226:227], off
	s_waitcnt vmcnt(8)
	s_waitcnt lgkmcnt(0)
	s_barrier
	s_setprio 1
	s_waitcnt lgkmcnt(0)
	v_mfma_f32_16x16x32_bf16 v[124:127], v[144:147], v[184:187], v[124:127]
	v_mfma_f32_16x16x32_bf16 v[120:123], v[160:163], v[184:187], v[120:123]
	v_mfma_f32_16x16x32_bf16 v[108:111], v[144:147], v[192:195], v[108:111]
	v_mfma_f32_16x16x32_bf16 v[104:107], v[160:163], v[192:195], v[104:107]
	v_mfma_f32_16x16x32_bf16 v[124:127], v[156:159], v[188:191], v[124:127]
	v_mfma_f32_16x16x32_bf16 v[120:123], v[164:167], v[188:191], v[120:123]
	v_mfma_f32_16x16x32_bf16 v[108:111], v[156:159], v[196:199], v[108:111]
	v_mfma_f32_16x16x32_bf16 v[104:107], v[164:167], v[196:199], v[104:107]
	v_mfma_f32_16x16x32_bf16 v[92:95], v[144:147], v[200:203], v[92:95]
	v_mfma_f32_16x16x32_bf16 v[88:91], v[160:163], v[200:203], v[88:91]
	v_mfma_f32_16x16x32_bf16 v[76:79], v[144:147], v[210:213], v[76:79]
	v_mfma_f32_16x16x32_bf16 v[72:75], v[160:163], v[210:213], v[72:75]
	v_mfma_f32_16x16x32_bf16 v[92:95], v[156:159], v[206:209], v[92:95]
	v_mfma_f32_16x16x32_bf16 v[88:91], v[164:167], v[206:209], v[88:91]
	v_mfma_f32_16x16x32_bf16 v[76:79], v[156:159], v[214:217], v[76:79]
	v_mfma_f32_16x16x32_bf16 v[72:75], v[164:167], v[214:217], v[72:75]
	s_setprio 0
	s_setprio 1
	v_mfma_f32_16x16x32_bf16 v[116:119], v[168:171], v[184:187], v[116:119]
	v_mfma_f32_16x16x32_bf16 v[112:115], v[176:179], v[184:187], v[112:115]
	v_mfma_f32_16x16x32_bf16 v[100:103], v[168:171], v[192:195], v[100:103]
	v_mfma_f32_16x16x32_bf16 v[96:99], v[176:179], v[192:195], v[96:99]
	v_mfma_f32_16x16x32_bf16 v[116:119], v[172:175], v[188:191], v[116:119]
	v_mfma_f32_16x16x32_bf16 v[112:115], v[180:183], v[188:191], v[112:115]
	v_mfma_f32_16x16x32_bf16 v[100:103], v[172:175], v[196:199], v[100:103]
	v_mfma_f32_16x16x32_bf16 v[96:99], v[180:183], v[196:199], v[96:99]
	v_mfma_f32_16x16x32_bf16 v[84:87], v[168:171], v[200:203], v[84:87]
	v_mfma_f32_16x16x32_bf16 v[80:83], v[176:179], v[200:203], v[80:83]
	v_mfma_f32_16x16x32_bf16 v[68:71], v[168:171], v[210:213], v[68:71]
	v_mfma_f32_16x16x32_bf16 v[64:67], v[176:179], v[210:213], v[64:67]
	v_mfma_f32_16x16x32_bf16 v[84:87], v[172:175], v[206:209], v[84:87]
	v_mfma_f32_16x16x32_bf16 v[80:83], v[180:183], v[206:209], v[80:83]
	v_mfma_f32_16x16x32_bf16 v[68:71], v[172:175], v[214:217], v[68:71]
	v_mfma_f32_16x16x32_bf16 v[64:67], v[180:183], v[214:217], v[64:67]
	s_setprio 0
	s_barrier
; #define PG8_STAGE(bufoff, gbase, voff) do { _Pragma("unroll") for (int _i = 0; _i < 2; ++_i) \
;         __builtin_amdgcn_global_load_lds((const unsigned*)((const char*)(gbase) + (voff)[_i]), (PG8_LAS unsigned*)(lds + (bufoff) + ldsw + _i * 8192), 16, 0, 0); } while (0)
; #define PG8_LDA(dst, b, h) do { _Pragma("unroll") for (int m = 0; m < 4; ++m) _Pragma("unroll") for (int k = 0; k < 2; ++k) dst[m][k] = *(const PG8_LAS bf16x8*)(lds + PG8_SA(b, h) + aoff + m * 2048 + k * 1024); } while (0)
; #define PG8_LDB(dst, b, h) do { _Pragma("unroll") for (int n = 0; n < 2; ++n) _Pragma("unroll") for (int k = 0; k < 2; ++k) dst[n][k] = *(const PG8_LAS bf16x8*)(lds + PG8_SB(b, h) + boff + n * 2048 + k * 1024); } while (0)
; #define PG8_MMA(ai, bj, At, Bt) do { __builtin_amdgcn_s_setprio(1); _Pragma("unroll") for (int m = 0; m < 4; ++m) _Pragma("unroll") for (int n = 0; n < 2; ++n) _Pragma("unroll") for (int k = 0; k < 2; ++k) \
;         acc[ai][bj][m][n] = __builtin_amdgcn_mfma_f32_16x16x32_bf16(Bt[n][k], At[m][k], acc[ai][bj][m][n], 0, 0, 0); __builtin_amdgcn_s_setprio(0); } while (0)
; #define PG8_WAIT_V(n) asm volatile("s_waitcnt vmcnt(" #n ")" ::: "memory")
; #define PG8_WAIT_L(n) asm volatile("s_waitcnt lgkmcnt(" #n ")" ::: "memory")
; #define PG8_BAR __builtin_amdgcn_s_barrier()
; #define PG8_SCHED __builtin_amdgcn_sched_barrier(0)
; template <class Epi, class Sched, bool ALIGN_EPI = false, bool SP2 = false>
; __device__ __forceinline__ void gemm_phase(PG8_LAS unsigned char* lds, const Gemm g, const Sched& S, const Epi& E) {
;     ...
;             PG8_LDB(B0, 0, 0); PG8_LDB(B1, 0, 1); PG8_SCHED; PG8_LDA(At, 0, 0); PG8_STAGE(PG8_SA(1, 1), a1 + hstep, voffA);
;             PG8_WAIT_V(8); PG8_WAIT_L(0); PG8_BAR; PG8_MMA(0, 0, At, B0); PG8_MMA(0, 1, At, B1); PG8_BAR; PG8_SCHED;
;     ...
;             PG8_LDA(At, 1, 1); PG8_STAGE(PG8_SB(1, 0), b3, voffB); PG8_STAGE(PG8_SB(1, 1), b3 + hstep, voffB); PG8_STAGE(PG8_SA(1, 0), a3, voffA);
;             PG8_WAIT_V(8); PG8_WAIT_L(0); PG8_BAR; PG8_MMA(1, 0, At, B0); PG8_MMA(1, 1, At, B1); PG8_BAR; PG8_SCHED;
	s_add_i32 s26, s56, s15
	v_lshl_add_u64 v[218:219], v[218:219], 0, s[12:13]
	s_mov_b32 m0, s26
	ds_read_b128 v[184:187], v153 offset:49152
	ds_read_b128 v[188:191], v153 offset:50176
	ds_read_b128 v[192:195], v153 offset:51200
	ds_read_b128 v[196:199], v153 offset:52224
	ds_read_b128 v[200:203], v153 offset:53248
	ds_read_b128 v[206:209], v153 offset:54272
	ds_read_b128 v[210:213], v153 offset:55296
	ds_read_b128 v[214:217], v153 offset:56320
	global_load_lds_dwordx4 v[218:219], off
	s_add_i32 m0, s26, 0x2000
	s_add_u32 s26, s36, 0xb0080
	v_lshl_add_u64 v[218:219], v[220:221], 0, s[12:13]
	s_addc_u32 s27, s37, 0
	s_add_i32 s36, s57, s15
	global_load_lds_dwordx4 v[218:219], off
	v_lshl_add_u64 v[218:219], s[26:27], 0, v[130:131]
	s_mov_b32 m0, s36
	s_nop 0
	global_load_lds_dwordx4 v[218:219], off
	v_lshl_add_u64 v[218:219], s[26:27], 0, v[134:135]
	s_add_i32 m0, s36, 0x2000
	s_nop 0
	global_load_lds_dwordx4 v[218:219], off
	s_waitcnt vmcnt(6)
	s_waitcnt lgkmcnt(0)
	s_barrier
	s_setprio 1
	s_waitcnt lgkmcnt(0)
	v_mfma_f32_16x16x32_bf16 v[60:63], v[144:147], v[184:187], v[60:63]
	v_mfma_f32_16x16x32_bf16 v[56:59], v[160:163], v[184:187], v[56:59]
	v_mfma_f32_16x16x32_bf16 v[44:47], v[144:147], v[192:195], v[44:47]
	v_mfma_f32_16x16x32_bf16 v[40:43], v[160:163], v[192:195], v[40:43]
	v_mfma_f32_16x16x32_bf16 v[60:63], v[156:159], v[188:191], v[60:63]
	v_mfma_f32_16x16x32_bf16 v[56:59], v[164:167], v[188:191], v[56:59]
	v_mfma_f32_16x16x32_bf16 v[44:47], v[156:159], v[196:199], v[44:47]
	v_mfma_f32_16x16x32_bf16 v[40:43], v[164:167], v[196:199], v[40:43]
	v_mfma_f32_16x16x32_bf16 v[28:31], v[144:147], v[200:203], v[28:31]
	v_mfma_f32_16x16x32_bf16 v[24:27], v[160:163], v[200:203], v[24:27]
	v_mfma_f32_16x16x32_bf16 v[12:15], v[144:147], v[210:213], v[12:15]
	v_mfma_f32_16x16x32_bf16 v[8:11], v[160:163], v[210:213], v[8:11]
	v_mfma_f32_16x16x32_bf16 v[28:31], v[156:159], v[206:209], v[28:31]
	v_mfma_f32_16x16x32_bf16 v[24:27], v[164:167], v[206:209], v[24:27]
	v_lshl_add_u64 v[218:219], v[222:223], 0, s[12:13]
	s_mov_b32 m0, s43
	s_nop 0
	global_load_lds_dwordx4 v[218:219], off
	v_mfma_f32_16x16x32_bf16 v[12:15], v[156:159], v[214:217], v[12:15]
	v_mfma_f32_16x16x32_bf16 v[8:11], v[164:167], v[214:217], v[8:11]
	s_setprio 0
	s_setprio 1
	v_mfma_f32_16x16x32_bf16 v[52:55], v[168:171], v[184:187], v[52:55]
	v_mfma_f32_16x16x32_bf16 v[48:51], v[176:179], v[184:187], v[48:51]
	v_mfma_f32_16x16x32_bf16 v[36:39], v[168:171], v[192:195], v[36:39]
	v_mfma_f32_16x16x32_bf16 v[32:35], v[176:179], v[192:195], v[32:35]
	v_mfma_f32_16x16x32_bf16 v[52:55], v[172:175], v[188:191], v[52:55]
	v_mfma_f32_16x16x32_bf16 v[48:51], v[180:183], v[188:191], v[48:51]
	v_mfma_f32_16x16x32_bf16 v[36:39], v[172:175], v[196:199], v[36:39]
	v_mfma_f32_16x16x32_bf16 v[32:35], v[180:183], v[196:199], v[32:35]
	v_mfma_f32_16x16x32_bf16 v[20:23], v[168:171], v[200:203], v[20:23]
	v_mfma_f32_16x16x32_bf16 v[16:19], v[176:179], v[200:203], v[16:19]
	v_mfma_f32_16x16x32_bf16 v[4:7], v[168:171], v[210:213], v[4:7]
	v_mfma_f32_16x16x32_bf16 v[0:3], v[176:179], v[210:213], v[0:3]
	v_mfma_f32_16x16x32_bf16 v[20:23], v[172:175], v[206:209], v[20:23]
	v_mfma_f32_16x16x32_bf16 v[16:19], v[180:183], v[206:209], v[16:19]
	v_lshl_add_u64 v[218:219], v[224:225], 0, s[12:13]
	s_mov_b32 m0, s44
	s_nop 0
	global_load_lds_dwordx4 v[218:219], off
	v_mfma_f32_16x16x32_bf16 v[4:7], v[172:175], v[214:217], v[4:7]
	v_mfma_f32_16x16x32_bf16 v[0:3], v[180:183], v[214:217], v[0:3]
	s_setprio 0
	s_barrier
	s_add_i32 s55, s55, 2
	s_add_u32 s53, s53, 0x100
	s_addc_u32 s54, s54, 0
	s_mov_b64 s[26:27], s[28:29]
.LBB0_1978:
	ds_read_b128 v[144:147], v151
	ds_read_b128 v[156:159], v151 offset:1024
	ds_read_b128 v[160:163], v151 offset:2048
	ds_read_b128 v[164:167], v151 offset:3072
	ds_read_b128 v[168:171], v152
	ds_read_b128 v[172:175], v152 offset:1024
	ds_read_b128 v[176:179], v152 offset:2048
	ds_read_b128 v[180:183], v152 offset:3072
	s_add_u32 s28, s26, 0x100
	s_addc_u32 s29, s27, 0
	s_cmp_eq_u32 s55, 40
	s_cselect_b32 s39, s1, s29
	s_cselect_b32 s38, s0, s28
	s_cselect_b32 s37, s25, s54
	s_cselect_b32 s36, s24, s53
	v_lshl_add_u64 v[218:219], s[26:27], 0, v[136:137]
	s_add_i32 m0, s33, 0xc000
	ds_read_b128 v[184:187], v153
	ds_read_b128 v[188:191], v153 offset:1024
	ds_read_b128 v[192:195], v153 offset:2048
	ds_read_b128 v[196:199], v153 offset:3072
	ds_read_b128 v[200:203], v153 offset:4096
	ds_read_b128 v[206:209], v153 offset:5120
	ds_read_b128 v[210:213], v153 offset:6144
	ds_read_b128 v[214:217], v153 offset:7168
	global_load_lds_dwordx4 v[218:219], off
	v_lshl_add_u64 v[218:219], s[26:27], 0, v[138:139]
	s_add_i32 m0, s33, 0xe000
	s_nop 0
	global_load_lds_dwordx4 v[218:219], off
	s_waitcnt vmcnt(8)
	s_waitcnt lgkmcnt(0)
	s_barrier
; #define PG8_STAGE(bufoff, gbase, voff) do { _Pragma("unroll") for (int _i = 0; _i < 2; ++_i) \
;         __builtin_amdgcn_global_load_lds((const unsigned*)((const char*)(gbase) + (voff)[_i]), (PG8_LAS unsigned*)(lds + (bufoff) + ldsw + _i * 8192), 16, 0, 0); } while (0)
; #define PG8_LDA(dst, b, h) do { _Pragma("unroll") for (int m = 0; m < 4; ++m) _Pragma("unroll") for (int k = 0; k < 2; ++k) dst[m][k] = *(const PG8_LAS bf16x8*)(lds + PG8_SA(b, h) + aoff + m * 2048 + k * 1024); } while (0)
; #define PG8_MMA(ai, bj, At, Bt) do { __builtin_amdgcn_s_setprio(1); _Pragma("unroll") for (int m = 0; m < 4; ++m) _Pragma("unroll") for (int n = 0; n < 2; ++n) _Pragma("unroll") for (int k = 0; k < 2; ++k) \
;         acc[ai][bj][m][n] = __builtin_amdgcn_mfma_f32_16x16x32_bf16(Bt[n][k], At[m][k], acc[ai][bj][m][n], 0, 0, 0); __builtin_amdgcn_s_setprio(0); } while (0)
; #define PG8_WAIT_V(n) asm volatile("s_waitcnt vmcnt(" #n ")" ::: "memory")
; #define PG8_WAIT_L(n) asm volatile("s_waitcnt lgkmcnt(" #n ")" ::: "memory")
; #define PG8_BAR __builtin_amdgcn_s_barrier()
; #define PG8_SCHED __builtin_amdgcn_sched_barrier(0)
; template <class Epi, class Sched, bool ALIGN_EPI = false, bool SP2 = false>
; __device__ __forceinline__ void gemm_phase(PG8_LAS unsigned char* lds, const Gemm g, const Sched& S, const Epi& E) {
;     ...
;             PG8_WAIT_V(8); PG8_WAIT_L(0); PG8_BAR; PG8_MMA(0, 0, At, B0); PG8_MMA(0, 1, At, B1); PG8_BAR; PG8_SCHED;
;             PG8_LDA(At, 0, 1); PG8_STAGE(PG8_SB(0, 0), b2, voffB); PG8_STAGE(PG8_SB(0, 1), b2 + hstep, voffB); PG8_STAGE(PG8_SA(0, 0), a2, voffA);
;             PG8_WAIT_V(8); PG8_WAIT_L(0); PG8_BAR; PG8_MMA(1, 0, At, B0); PG8_MMA(1, 1, At, B1); PG8_BAR; PG8_SCHED;
	s_setprio 1
	s_waitcnt lgkmcnt(0)
	v_mfma_f32_16x16x32_bf16 v[124:127], v[144:147], v[184:187], v[124:127]
	v_mfma_f32_16x16x32_bf16 v[120:123], v[160:163], v[184:187], v[120:123]
	v_mfma_f32_16x16x32_bf16 v[108:111], v[144:147], v[192:195], v[108:111]
	v_mfma_f32_16x16x32_bf16 v[104:107], v[160:163], v[192:195], v[104:107]
	v_mfma_f32_16x16x32_bf16 v[124:127], v[156:159], v[188:191], v[124:127]
	v_mfma_f32_16x16x32_bf16 v[120:123], v[164:167], v[188:191], v[120:123]
	v_mfma_f32_16x16x32_bf16 v[108:111], v[156:159], v[196:199], v[108:111]
	v_mfma_f32_16x16x32_bf16 v[104:107], v[164:167], v[196:199], v[104:107]
	v_mfma_f32_16x16x32_bf16 v[92:95], v[144:147], v[200:203], v[92:95]
	v_mfma_f32_16x16x32_bf16 v[88:91], v[160:163], v[200:203], v[88:91]
	v_mfma_f32_16x16x32_bf16 v[76:79], v[144:147], v[210:213], v[76:79]
	v_mfma_f32_16x16x32_bf16 v[72:75], v[160:163], v[210:213], v[72:75]
	v_mfma_f32_16x16x32_bf16 v[92:95], v[156:159], v[206:209], v[92:95]
	v_mfma_f32_16x16x32_bf16 v[88:91], v[164:167], v[206:209], v[88:91]
	v_mfma_f32_16x16x32_bf16 v[76:79], v[156:159], v[214:217], v[76:79]
	v_mfma_f32_16x16x32_bf16 v[72:75], v[164:167], v[214:217], v[72:75]
	s_setprio 0
	s_setprio 1
	v_mfma_f32_16x16x32_bf16 v[116:119], v[168:171], v[184:187], v[116:119]
	v_mfma_f32_16x16x32_bf16 v[112:115], v[176:179], v[184:187], v[112:115]
	v_mfma_f32_16x16x32_bf16 v[100:103], v[168:171], v[192:195], v[100:103]
	v_mfma_f32_16x16x32_bf16 v[96:99], v[176:179], v[192:195], v[96:99]
	v_mfma_f32_16x16x32_bf16 v[116:119], v[172:175], v[188:191], v[116:119]
	v_mfma_f32_16x16x32_bf16 v[112:115], v[180:183], v[188:191], v[112:115]
	v_mfma_f32_16x16x32_bf16 v[100:103], v[172:175], v[196:199], v[100:103]
	v_mfma_f32_16x16x32_bf16 v[96:99], v[180:183], v[196:199], v[96:99]
	v_mfma_f32_16x16x32_bf16 v[84:87], v[168:171], v[200:203], v[84:87]
	v_mfma_f32_16x16x32_bf16 v[80:83], v[176:179], v[200:203], v[80:83]
	v_mfma_f32_16x16x32_bf16 v[68:71], v[168:171], v[210:213], v[68:71]
	v_mfma_f32_16x16x32_bf16 v[64:67], v[176:179], v[210:213], v[64:67]
	v_mfma_f32_16x16x32_bf16 v[84:87], v[172:175], v[206:209], v[84:87]
	v_mfma_f32_16x16x32_bf16 v[80:83], v[180:183], v[206:209], v[80:83]
	v_mfma_f32_16x16x32_bf16 v[68:71], v[172:175], v[214:217], v[68:71]
	v_mfma_f32_16x16x32_bf16 v[64:67], v[180:183], v[214:217], v[64:67]
	s_setprio 0
	s_barrier
	s_add_i32 s26, s45, s15
	v_lshl_add_u64 v[218:219], s[36:37], 0, v[130:131]
	s_mov_b32 m0, s26
	ds_read_b128 v[184:187], v153 offset:16384
	ds_read_b128 v[188:191], v153 offset:17408
	ds_read_b128 v[192:195], v153 offset:18432
	ds_read_b128 v[196:199], v153 offset:19456
	ds_read_b128 v[200:203], v153 offset:20480
	ds_read_b128 v[206:209], v153 offset:21504
	ds_read_b128 v[210:213], v153 offset:22528
	ds_read_b128 v[214:217], v153 offset:23552
	global_load_lds_dwordx4 v[218:219], off
	s_add_i32 m0, s26, 0x2000
	s_add_u32 s26, s36, 0xb0000
	v_lshl_add_u64 v[220:221], s[36:37], 0, v[134:135]
	s_addc_u32 s27, s37, 0
	s_add_i32 s56, s46, s15
	global_load_lds_dwordx4 v[220:221], off
	v_lshl_add_u64 v[222:223], s[26:27], 0, v[130:131]
	s_mov_b32 m0, s56
	global_load_lds_dwordx4 v[222:223], off
	v_lshl_add_u64 v[222:223], s[26:27], 0, v[134:135]
	s_add_i32 m0, s56, 0x2000
	s_nop 0
	global_load_lds_dwordx4 v[222:223], off
	s_waitcnt vmcnt(6)
	s_waitcnt lgkmcnt(0)
	s_barrier
	s_setprio 1
	s_waitcnt lgkmcnt(0)
	v_mfma_f32_16x16x32_bf16 v[60:63], v[144:147], v[184:187], v[60:63]
	v_mfma_f32_16x16x32_bf16 v[56:59], v[160:163], v[184:187], v[56:59]
	v_mfma_f32_16x16x32_bf16 v[44:47], v[144:147], v[192:195], v[44:47]
	v_mfma_f32_16x16x32_bf16 v[40:43], v[160:163], v[192:195], v[40:43]
	v_mfma_f32_16x16x32_bf16 v[60:63], v[156:159], v[188:191], v[60:63]
	v_mfma_f32_16x16x32_bf16 v[56:59], v[164:167], v[188:191], v[56:59]
	v_mfma_f32_16x16x32_bf16 v[44:47], v[156:159], v[196:199], v[44:47]
	v_mfma_f32_16x16x32_bf16 v[40:43], v[164:167], v[196:199], v[40:43]
	v_mfma_f32_16x16x32_bf16 v[28:31], v[144:147], v[200:203], v[28:31]
	v_mfma_f32_16x16x32_bf16 v[24:27], v[160:163], v[200:203], v[24:27]
	v_mfma_f32_16x16x32_bf16 v[12:15], v[144:147], v[210:213], v[12:15]
	v_mfma_f32_16x16x32_bf16 v[8:11], v[160:163], v[210:213], v[8:11]
	v_mfma_f32_16x16x32_bf16 v[28:31], v[156:159], v[206:209], v[28:31]
	v_mfma_f32_16x16x32_bf16 v[24:27], v[164:167], v[206:209], v[24:27]
	v_lshl_add_u64 v[222:223], s[38:39], 0, v[128:129]
	s_mov_b32 m0, s33
	s_nop 0
	global_load_lds_dwordx4 v[222:223], off
	v_mfma_f32_16x16x32_bf16 v[12:15], v[156:159], v[214:217], v[12:15]
	v_mfma_f32_16x16x32_bf16 v[8:11], v[164:167], v[214:217], v[8:11]
	s_setprio 0
	s_setprio 1
	v_mfma_f32_16x16x32_bf16 v[52:55], v[168:171], v[184:187], v[52:55]
	v_mfma_f32_16x16x32_bf16 v[48:51], v[176:179], v[184:187], v[48:51]
	v_mfma_f32_16x16x32_bf16 v[36:39], v[168:171], v[192:195], v[36:39]
	v_mfma_f32_16x16x32_bf16 v[32:35], v[176:179], v[192:195], v[32:35]
	v_mfma_f32_16x16x32_bf16 v[52:55], v[172:175], v[188:191], v[52:55]
	v_mfma_f32_16x16x32_bf16 v[48:51], v[180:183], v[188:191], v[48:51]
	v_mfma_f32_16x16x32_bf16 v[36:39], v[172:175], v[196:199], v[36:39]
	v_mfma_f32_16x16x32_bf16 v[32:35], v[180:183], v[196:199], v[32:35]
	v_mfma_f32_16x16x32_bf16 v[20:23], v[168:171], v[200:203], v[20:23]
	v_mfma_f32_16x16x32_bf16 v[16:19], v[176:179], v[200:203], v[16:19]
	v_mfma_f32_16x16x32_bf16 v[4:7], v[168:171], v[210:213], v[4:7]
	v_mfma_f32_16x16x32_bf16 v[0:3], v[176:179], v[210:213], v[0:3]
	v_mfma_f32_16x16x32_bf16 v[20:23], v[172:175], v[206:209], v[20:23]
	v_mfma_f32_16x16x32_bf16 v[16:19], v[180:183], v[206:209], v[16:19]
	v_lshl_add_u64 v[224:225], s[38:39], 0, v[132:133]
	s_mov_b32 m0, s34
	s_nop 0
	global_load_lds_dwordx4 v[224:225], off
	v_mfma_f32_16x16x32_bf16 v[4:7], v[172:175], v[214:217], v[4:7]
	v_mfma_f32_16x16x32_bf16 v[0:3], v[180:183], v[214:217], v[0:3]
	s_setprio 0
	s_barrier
; #define PG8_STAGE(bufoff, gbase, voff) do { _Pragma("unroll") for (int _i = 0; _i < 2; ++_i) \
;         __builtin_amdgcn_global_load_lds((const unsigned*)((const char*)(gbase) + (voff)[_i]), (PG8_LAS unsigned*)(lds + (bufoff) + ldsw + _i * 8192), 16, 0, 0); } while (0)
; #define PG8_LDA(dst, b, h) do { _Pragma("unroll") for (int m = 0; m < 4; ++m) _Pragma("unroll") for (int k = 0; k < 2; ++k) dst[m][k] = *(const PG8_LAS bf16x8*)(lds + PG8_SA(b, h) + aoff + m * 2048 + k * 1024); } while (0)
; #define PG8_LDB(dst, b, h) do { _Pragma("unroll") for (int n = 0; n < 2; ++n) _Pragma("unroll") for (int k = 0; k < 2; ++k) dst[n][k] = *(const PG8_LAS bf16x8*)(lds + PG8_SB(b, h) + boff + n * 2048 + k * 1024); } while (0)
; #define PG8_MMA(ai, bj, At, Bt) do { __builtin_amdgcn_s_setprio(1); _Pragma("unroll") for (int m = 0; m < 4; ++m) _Pragma("unroll") for (int n = 0; n < 2; ++n) _Pragma("unroll") for (int k = 0; k < 2; ++k) \
;         acc[ai][bj][m][n] = __builtin_amdgcn_mfma_f32_16x16x32_bf16(Bt[n][k], At[m][k], acc[ai][bj][m][n], 0, 0, 0); __builtin_amdgcn_s_setprio(0); } while (0)
; #define PG8_WAIT_V(n) asm volatile("s_waitcnt vmcnt(" #n ")" ::: "memory")
; #define PG8_WAIT_L(n) asm volatile("s_waitcnt lgkmcnt(" #n ")" ::: "memory")
; #define PG8_BAR __builtin_amdgcn_s_barrier()
; #define PG8_SCHED __builtin_amdgcn_sched_barrier(0)
; template <class Epi, class Sched, bool ALIGN_EPI = false, bool SP2 = false>
; __device__ __forceinline__ void gemm_phase(PG8_LAS unsigned char* lds, const Gemm g, const Sched& S, const Epi& E) {
;     ...
;             PG8_LDB(B0, 1, 0); PG8_LDB(B1, 1, 1); PG8_SCHED; PG8_LDA(At, 1, 0); PG8_STAGE(PG8_SA(0, 1), a2 + hstep, voffA);
;             PG8_WAIT_V(8); PG8_WAIT_L(0); PG8_BAR; PG8_MMA(0, 0, At, B0); PG8_MMA(0, 1, At, B1); PG8_BAR; PG8_SCHED;
	s_add_i32 s56, 0, 0x18000
	v_add_u32_e32 v155, s56, v149
	s_add_i32 s57, 0, 0x1c000
	ds_read_b128 v[144:147], v155
	ds_read_b128 v[156:159], v155 offset:1024
	ds_read_b128 v[160:163], v155 offset:2048
	ds_read_b128 v[164:167], v155 offset:3072
	v_add_u32_e32 v155, s57, v149
	ds_read_b128 v[168:171], v155
	ds_read_b128 v[172:175], v155 offset:1024
	ds_read_b128 v[176:179], v155 offset:2048
	ds_read_b128 v[180:183], v155 offset:3072
	s_add_u32 s26, s38, 0xb0000
	s_addc_u32 s27, s39, 0
	s_mov_b32 m0, s40
	v_lshl_add_u64 v[226:227], s[26:27], 0, v[128:129]
	ds_read_b128 v[184:187], v153 offset:32768
	ds_read_b128 v[188:191], v153 offset:33792
	ds_read_b128 v[192:195], v153 offset:34816
	ds_read_b128 v[196:199], v153 offset:35840
	ds_read_b128 v[200:203], v153 offset:36864
	ds_read_b128 v[206:209], v153 offset:37888
	ds_read_b128 v[210:213], v153 offset:38912
	ds_read_b128 v[214:217], v153 offset:39936
	global_load_lds_dwordx4 v[226:227], off
	v_lshl_add_u64 v[226:227], s[26:27], 0, v[132:133]
	s_mov_b32 m0, s41
	s_nop 0
	global_load_lds_dwordx4 v[226:227], off
	s_waitcnt vmcnt(8)
	s_waitcnt lgkmcnt(0)
	s_barrier
	s_setprio 1
	s_waitcnt lgkmcnt(0)
	v_mfma_f32_16x16x32_bf16 v[124:127], v[144:147], v[184:187], v[124:127]
	v_mfma_f32_16x16x32_bf16 v[120:123], v[160:163], v[184:187], v[120:123]
	v_mfma_f32_16x16x32_bf16 v[108:111], v[144:147], v[192:195], v[108:111]
	v_mfma_f32_16x16x32_bf16 v[104:107], v[160:163], v[192:195], v[104:107]
	v_mfma_f32_16x16x32_bf16 v[124:127], v[156:159], v[188:191], v[124:127]
	v_mfma_f32_16x16x32_bf16 v[120:123], v[164:167], v[188:191], v[120:123]
	v_mfma_f32_16x16x32_bf16 v[108:111], v[156:159], v[196:199], v[108:111]
	v_mfma_f32_16x16x32_bf16 v[104:107], v[164:167], v[196:199], v[104:107]
	v_mfma_f32_16x16x32_bf16 v[92:95], v[144:147], v[200:203], v[92:95]
	v_mfma_f32_16x16x32_bf16 v[88:91], v[160:163], v[200:203], v[88:91]
	v_mfma_f32_16x16x32_bf16 v[76:79], v[144:147], v[210:213], v[76:79]
	v_mfma_f32_16x16x32_bf16 v[72:75], v[160:163], v[210:213], v[72:75]
	v_mfma_f32_16x16x32_bf16 v[92:95], v[156:159], v[206:209], v[92:95]
	v_mfma_f32_16x16x32_bf16 v[88:91], v[164:167], v[206:209], v[88:91]
	v_mfma_f32_16x16x32_bf16 v[76:79], v[156:159], v[214:217], v[76:79]
	v_mfma_f32_16x16x32_bf16 v[72:75], v[164:167], v[214:217], v[72:75]
	s_setprio 0
	s_setprio 1
	v_mfma_f32_16x16x32_bf16 v[116:119], v[168:171], v[184:187], v[116:119]
	v_mfma_f32_16x16x32_bf16 v[112:115], v[176:179], v[184:187], v[112:115]
	v_mfma_f32_16x16x32_bf16 v[100:103], v[168:171], v[192:195], v[100:103]
	v_mfma_f32_16x16x32_bf16 v[96:99], v[176:179], v[192:195], v[96:99]
	v_mfma_f32_16x16x32_bf16 v[116:119], v[172:175], v[188:191], v[116:119]
	v_mfma_f32_16x16x32_bf16 v[112:115], v[180:183], v[188:191], v[112:115]
	v_mfma_f32_16x16x32_bf16 v[100:103], v[172:175], v[196:199], v[100:103]
	v_mfma_f32_16x16x32_bf16 v[96:99], v[180:183], v[196:199], v[96:99]
	v_mfma_f32_16x16x32_bf16 v[84:87], v[168:171], v[200:203], v[84:87]
	v_mfma_f32_16x16x32_bf16 v[80:83], v[176:179], v[200:203], v[80:83]
	v_mfma_f32_16x16x32_bf16 v[68:71], v[168:171], v[210:213], v[68:71]
	v_mfma_f32_16x16x32_bf16 v[64:67], v[176:179], v[210:213], v[64:67]
	v_mfma_f32_16x16x32_bf16 v[84:87], v[172:175], v[206:209], v[84:87]
	v_mfma_f32_16x16x32_bf16 v[80:83], v[180:183], v[206:209], v[80:83]
	v_mfma_f32_16x16x32_bf16 v[68:71], v[172:175], v[214:217], v[68:71]
	v_mfma_f32_16x16x32_bf16 v[64:67], v[180:183], v[214:217], v[64:67]
	s_setprio 0
	s_barrier
; #define PG8_STAGE(bufoff, gbase, voff) do { _Pragma("unroll") for (int _i = 0; _i < 2; ++_i) \
;         __builtin_amdgcn_global_load_lds((const unsigned*)((const char*)(gbase) + (voff)[_i]), (PG8_LAS unsigned*)(lds + (bufoff) + ldsw + _i * 8192), 16, 0, 0); } while (0)
; #define PG8_LDA(dst, b, h) do { _Pragma("unroll") for (int m = 0; m < 4; ++m) _Pragma("unroll") for (int k = 0; k < 2; ++k) dst[m][k] = *(const PG8_LAS bf16x8*)(lds + PG8_SA(b, h) + aoff + m * 2048 + k * 1024); } while (0)
; #define PG8_MMA(ai, bj, At, Bt) do { __builtin_amdgcn_s_setprio(1); _Pragma("unroll") for (int m = 0; m < 4; ++m) _Pragma("unroll") for (int n = 0; n < 2; ++n) _Pragma("unroll") for (int k = 0; k < 2; ++k) \
;         acc[ai][bj][m][n] = __builtin_amdgcn_mfma_f32_16x16x32_bf16(Bt[n][k], At[m][k], acc[ai][bj][m][n], 0, 0, 0); __builtin_amdgcn_s_setprio(0); } while (0)
; #define PG8_WAIT_V(n) asm volatile("s_waitcnt vmcnt(" #n ")" ::: "memory")
; #define PG8_WAIT_L(n) asm volatile("s_waitcnt lgkmcnt(" #n ")" ::: "memory")
; #define PG8_BAR __builtin_amdgcn_s_barrier()
; #define PG8_SCHED __builtin_amdgcn_sched_barrier(0)
; template <class Epi, class Sched, bool ALIGN_EPI = false, bool SP2 = false>
; __device__ __forceinline__ void gemm_phase(PG8_LAS unsigned char* lds, const Gemm g, const Sched& S, const Epi& E) {
;     ...
;             PG8_LDA(At, 1, 1); PG8_STAGE(PG8_SB(1, 0), b3, voffB); PG8_STAGE(PG8_SB(1, 1), b3 + hstep, voffB); PG8_STAGE(PG8_SA(1, 0), a3, voffA);
;             PG8_WAIT_V(8); PG8_WAIT_L(0); PG8_BAR; PG8_MMA(1, 0, At, B0); PG8_MMA(1, 1, At, B1); PG8_BAR; PG8_SCHED;
;     ...
;         if constexpr (ALIGN_EPI) { if (wr == 0) PG8_BAR; }
	s_add_i32 s26, s56, s15
	v_lshl_add_u64 v[218:219], v[218:219], 0, s[12:13]
	s_mov_b32 m0, s26
	ds_read_b128 v[184:187], v153 offset:49152
	ds_read_b128 v[188:191], v153 offset:50176
	ds_read_b128 v[192:195], v153 offset:51200
	ds_read_b128 v[196:199], v153 offset:52224
	ds_read_b128 v[200:203], v153 offset:53248
	ds_read_b128 v[206:209], v153 offset:54272
	ds_read_b128 v[210:213], v153 offset:55296
	ds_read_b128 v[214:217], v153 offset:56320
	global_load_lds_dwordx4 v[218:219], off
	s_add_i32 m0, s26, 0x2000
	s_add_u32 s26, s36, 0xb0080
	v_lshl_add_u64 v[218:219], v[220:221], 0, s[12:13]
	s_addc_u32 s27, s37, 0
	s_add_i32 s36, s57, s15
	global_load_lds_dwordx4 v[218:219], off
	v_lshl_add_u64 v[218:219], s[26:27], 0, v[130:131]
	s_mov_b32 m0, s36
	s_nop 0
	global_load_lds_dwordx4 v[218:219], off
	v_lshl_add_u64 v[218:219], s[26:27], 0, v[134:135]
	s_add_i32 m0, s36, 0x2000
	s_nop 0
	global_load_lds_dwordx4 v[218:219], off
	s_waitcnt vmcnt(6)
	s_waitcnt lgkmcnt(0)
	s_barrier
	s_setprio 1
	s_waitcnt lgkmcnt(0)
	v_mfma_f32_16x16x32_bf16 v[60:63], v[144:147], v[184:187], v[60:63]
	v_mfma_f32_16x16x32_bf16 v[56:59], v[160:163], v[184:187], v[56:59]
	v_mfma_f32_16x16x32_bf16 v[44:47], v[144:147], v[192:195], v[44:47]
	v_mfma_f32_16x16x32_bf16 v[40:43], v[160:163], v[192:195], v[40:43]
	v_mfma_f32_16x16x32_bf16 v[60:63], v[156:159], v[188:191], v[60:63]
	v_mfma_f32_16x16x32_bf16 v[56:59], v[164:167], v[188:191], v[56:59]
	v_mfma_f32_16x16x32_bf16 v[44:47], v[156:159], v[196:199], v[44:47]
	v_mfma_f32_16x16x32_bf16 v[40:43], v[164:167], v[196:199], v[40:43]
	v_mfma_f32_16x16x32_bf16 v[28:31], v[144:147], v[200:203], v[28:31]
	v_mfma_f32_16x16x32_bf16 v[24:27], v[160:163], v[200:203], v[24:27]
	v_mfma_f32_16x16x32_bf16 v[12:15], v[144:147], v[210:213], v[12:15]
	v_mfma_f32_16x16x32_bf16 v[8:11], v[160:163], v[210:213], v[8:11]
	v_mfma_f32_16x16x32_bf16 v[28:31], v[156:159], v[206:209], v[28:31]
	v_mfma_f32_16x16x32_bf16 v[24:27], v[164:167], v[206:209], v[24:27]
	v_lshl_add_u64 v[218:219], v[222:223], 0, s[12:13]
	s_mov_b32 m0, s43
	s_nop 0
	global_load_lds_dwordx4 v[218:219], off
	v_mfma_f32_16x16x32_bf16 v[12:15], v[156:159], v[214:217], v[12:15]
	v_mfma_f32_16x16x32_bf16 v[8:11], v[164:167], v[214:217], v[8:11]
	s_setprio 0
	s_setprio 1
	v_mfma_f32_16x16x32_bf16 v[52:55], v[168:171], v[184:187], v[52:55]
	v_mfma_f32_16x16x32_bf16 v[48:51], v[176:179], v[184:187], v[48:51]
	v_mfma_f32_16x16x32_bf16 v[36:39], v[168:171], v[192:195], v[36:39]
	v_mfma_f32_16x16x32_bf16 v[32:35], v[176:179], v[192:195], v[32:35]
	v_mfma_f32_16x16x32_bf16 v[52:55], v[172:175], v[188:191], v[52:55]
	v_mfma_f32_16x16x32_bf16 v[48:51], v[180:183], v[188:191], v[48:51]
	v_mfma_f32_16x16x32_bf16 v[36:39], v[172:175], v[196:199], v[36:39]
	v_mfma_f32_16x16x32_bf16 v[32:35], v[180:183], v[196:199], v[32:35]
	v_mfma_f32_16x16x32_bf16 v[20:23], v[168:171], v[200:203], v[20:23]
	v_mfma_f32_16x16x32_bf16 v[16:19], v[176:179], v[200:203], v[16:19]
	v_mfma_f32_16x16x32_bf16 v[4:7], v[168:171], v[210:213], v[4:7]
	v_mfma_f32_16x16x32_bf16 v[0:3], v[176:179], v[210:213], v[0:3]
	v_mfma_f32_16x16x32_bf16 v[20:23], v[172:175], v[206:209], v[20:23]
	v_mfma_f32_16x16x32_bf16 v[16:19], v[180:183], v[206:209], v[16:19]
	v_lshl_add_u64 v[218:219], v[224:225], 0, s[12:13]
	s_mov_b32 m0, s44
	s_nop 0
	global_load_lds_dwordx4 v[218:219], off
	v_mfma_f32_16x16x32_bf16 v[4:7], v[172:175], v[214:217], v[4:7]
	v_mfma_f32_16x16x32_bf16 v[0:3], v[180:183], v[214:217], v[0:3]
	s_setprio 0
	s_barrier
	s_add_i32 s55, s55, 2
	s_add_u32 s53, s53, 0x100
	s_addc_u32 s54, s54, 0
	s_cmp_gt_u32 s55, 41
	s_mov_b64 s[26:27], s[28:29]
	s_cbranch_scc0 .LBB0_1978
	s_and_b64 vcc, exec, s[16:17]
	s_cbranch_vccz .LBB0_1981
	s_barrier
